# GEMM loops: phase-5 B-fragment ds_reads addressed off the persistent +0x14000 base with larger immediates (per-iteration v_add_u32 removed); on top of the tail-relocation version
# speedup vs baseline: 1.0089x; 1.0016x over previous
; #define PG8_STAGE(bufoff, gbase, voff) do { _Pragma("unroll") for (int _i = 0; _i < 2; ++_i) \
;         __builtin_amdgcn_global_load_lds((const unsigned*)((const char*)(gbase) + (voff)[_i]), (LAS unsigned*)(lds + (bufoff) + ldsw + _i * 8192), 16, 0, 0); } while (0)
; #define PG8_LDA(dst, b, h) do { _Pragma("unroll") for (int m = 0; m < 4; ++m) _Pragma("unroll") for (int k = 0; k < 2; ++k) dst[m][k] = *(const LAS bf16x8*)(lds + PG8_SA(b, h) + aoff + m * 2048 + k * 1024); } while (0)
; #define PG8_LDB(dst, b, h) do { _Pragma("unroll") for (int n = 0; n < 2; ++n) _Pragma("unroll") for (int k = 0; k < 2; ++k) dst[n][k] = *(const LAS bf16x8*)(lds + PG8_SB(b, h) + boff + n * 2048 + k * 1024); } while (0)
; #define PG8_MMA(ai, bj, At, Bt) do { __builtin_amdgcn_s_setprio(1); _Pragma("unroll") for (int m = 0; m < 4; ++m) _Pragma("unroll") for (int n = 0; n < 2; ++n) _Pragma("unroll") for (int k = 0; k < 2; ++k) \
;         acc[ai][bj][m][n] = __builtin_amdgcn_mfma_f32_16x16x32_bf16(Bt[n][k], At[m][k], acc[ai][bj][m][n], 0, 0, 0); __builtin_amdgcn_s_setprio(0); } while (0)
; #define PG8_WAIT_L(n) asm volatile("s_waitcnt lgkmcnt(" #n ")" ::: "memory")
; template <class Epi, class Sched>
; __device__ __forceinline__ void gemm_phase(LAS unsigned char* lds, const Gemm g, const Sched& S, const Epi& E) {
;     ...
;         const bool has_next = S.next(ui + 1, nxt);
;         const char* nA = has_next ? (const char*)g.A + (size_t)nxt.pm * tstep : cA; const char* nB = has_next ? (const char*)g.Bt + (size_t)nxt.pn * tstep : cB;
;         for (int t = 0; t < nt; t += 2) {
;             const bool last = (t == nt - 2);
;             const char* a1 = cA + (size_t)(t + 1) * kstep;
;             const char* a2 = last ? nA : cA + (size_t)(t + 2) * kstep; const char* b2 = last ? nB : cB + (size_t)(t + 2) * kstep;
;             const char* a3 = a2 + kstep; const char* b3 = b2 + kstep;
;             PG8_LDB(B0, 0, 0); PG8_SCHED; PG8_LDA(At, 0, 0); PG8_STAGE(PG8_SA(1, 1), a1 + hstep, voffA);
;             PG8_WAIT_L(8); PG8_BAR; PG8_WAIT_L(0); PG8_MMA(0, 0, At, B0); PG8_BAR; PG8_SCHED;
;             PG8_LDB(B1, 0, 1); PG8_STAGE(PG8_SB(0, 0), b2, voffB);
;             PG8_BAR; PG8_WAIT_L(0); PG8_MMA(0, 1, At, B1); PG8_BAR;
;             PG8_LDA(At, 0, 1); PG8_STAGE(PG8_SA(0, 0), a2, voffA);
;             PG8_BAR; PG8_WAIT_L(0); PG8_MMA(1, 0, At, B0); PG8_BAR; PG8_SCHED;
.LBB0_234:
	s_ashr_i32 s7, s6, 31
	v_cmp_lt_i64_e32 vcc, s[8:9], v[140:141]
	s_lshl_b64 s[8:9], s[6:7], 19
	s_add_u32 s8, s96, s8
	s_addc_u32 s9, s97, s9
	s_and_b64 s[10:11], vcc, exec
	s_cselect_b32 s7, s9, s15
	s_cselect_b32 s44, s8, s14
	s_ashr_i32 s5, s4, 31
	s_lshl_b64 s[10:11], s[4:5], 19
	s_add_u32 s10, s72, s10
	s_addc_u32 s11, s73, s11
	s_and_b64 s[16:17], vcc, exec
	s_cselect_b32 s5, s11, s19
	s_cselect_b32 s45, s10, s18
	s_add_u32 s14, s14, 0x40080
	s_addc_u32 s15, s15, 0
	s_add_u32 s46, s18, 0x100
	s_addc_u32 s47, s19, 0
	s_mov_b32 s48, -2
	ds_read_b128 v[150:153], v147
	ds_read_b128 v[154:157], v147 offset:1024
	ds_read_b128 v[158:161], v147 offset:2048
	ds_read_b128 v[162:165], v147 offset:3072
	s_add_u32 s16, s14, 0xfffc0080
	s_addc_u32 s17, s15, -1
	s_cmp_eq_u32 s48, 12
	s_cselect_b32 s23, s7, s17
	s_cselect_b32 s22, s44, s16
	s_cselect_b32 s19, s5, s47
	s_cselect_b32 s18, s45, s46
	s_add_i32 m0, s13, 0xc000
	ds_read_b128 v[166:169], v148
	ds_read_b128 v[170:173], v148 offset:1024
	ds_read_b128 v[174:177], v148 offset:2048
	ds_read_b128 v[178:181], v148 offset:3072
	ds_read_b128 v[182:185], v148 offset:4096
	ds_read_b128 v[186:189], v148 offset:5120
	ds_read_b128 v[190:193], v148 offset:6144
	ds_read_b128 v[194:197], v148 offset:7168
	global_load_lds_dwordx4 v136, s[14:15]
	s_add_i32 m0, s13, 0xe000
	s_nop 0
	global_load_lds_dwordx4 v138, s[14:15]
	s_waitcnt lgkmcnt(8)
	s_waitcnt vmcnt(8)
	s_setprio 1
	s_barrier
	s_waitcnt lgkmcnt(0)
	v_mfma_f32_16x16x32_bf16 v[124:127], v[150:153], v[166:169], 0
	v_mfma_f32_16x16x32_bf16 v[116:119], v[158:161], v[166:169], 0
	v_mfma_f32_16x16x32_bf16 v[108:111], v[150:153], v[174:177], 0
	v_mfma_f32_16x16x32_bf16 v[100:103], v[158:161], v[174:177], 0
	v_mfma_f32_16x16x32_bf16 v[92:95], v[150:153], v[182:185], 0
	v_mfma_f32_16x16x32_bf16 v[84:87], v[158:161], v[182:185], 0
	v_mfma_f32_16x16x32_bf16 v[76:79], v[150:153], v[190:193], 0
	v_mfma_f32_16x16x32_bf16 v[68:71], v[158:161], v[190:193], 0
	v_mfma_f32_16x16x32_bf16 v[124:127], v[154:157], v[170:173], v[124:127]
	v_mfma_f32_16x16x32_bf16 v[116:119], v[162:165], v[170:173], v[116:119]
	v_mfma_f32_16x16x32_bf16 v[108:111], v[154:157], v[178:181], v[108:111]
	v_mfma_f32_16x16x32_bf16 v[100:103], v[162:165], v[178:181], v[100:103]
	v_mfma_f32_16x16x32_bf16 v[92:95], v[154:157], v[186:189], v[92:95]
	v_mfma_f32_16x16x32_bf16 v[84:87], v[162:165], v[186:189], v[84:87]
	v_mfma_f32_16x16x32_bf16 v[76:79], v[154:157], v[194:197], v[76:79]
	v_mfma_f32_16x16x32_bf16 v[68:71], v[162:165], v[194:197], v[68:71]
	s_barrier
	s_setprio 0
	s_add_i32 s16, s40, s25
	s_mov_b32 m0, s16
	ds_read_b128 v[202:205], v149
	ds_read_b128 v[206:209], v149 offset:1024
	ds_read_b128 v[210:213], v149 offset:2048
	ds_read_b128 v[214:217], v149 offset:3072
	global_load_lds_dwordx4 v132, s[18:19]
	s_add_i32 m0, s16, 0x2000
	s_nop 0
	global_load_lds_dwordx4 v128, s[18:19]
	s_waitcnt vmcnt(8)
	s_setprio 1
	s_barrier
	s_waitcnt lgkmcnt(0)
	v_mfma_f32_16x16x32_bf16 v[120:123], v[202:205], v[166:169], 0
	v_mfma_f32_16x16x32_bf16 v[112:115], v[210:213], v[166:169], 0
	v_mfma_f32_16x16x32_bf16 v[104:107], v[202:205], v[174:177], 0
	v_mfma_f32_16x16x32_bf16 v[96:99], v[210:213], v[174:177], 0
	v_mfma_f32_16x16x32_bf16 v[88:91], v[202:205], v[182:185], 0
	v_mfma_f32_16x16x32_bf16 v[80:83], v[210:213], v[182:185], 0
	v_mfma_f32_16x16x32_bf16 v[72:75], v[202:205], v[190:193], 0
	v_mfma_f32_16x16x32_bf16 v[64:67], v[210:213], v[190:193], 0
	v_mfma_f32_16x16x32_bf16 v[120:123], v[206:209], v[170:173], v[120:123]
	v_mfma_f32_16x16x32_bf16 v[112:115], v[214:217], v[170:173], v[112:115]
	v_mfma_f32_16x16x32_bf16 v[104:107], v[206:209], v[178:181], v[104:107]
	v_mfma_f32_16x16x32_bf16 v[96:99], v[214:217], v[178:181], v[96:99]
	v_mfma_f32_16x16x32_bf16 v[88:91], v[206:209], v[186:189], v[88:91]
	v_mfma_f32_16x16x32_bf16 v[80:83], v[214:217], v[186:189], v[80:83]
	v_mfma_f32_16x16x32_bf16 v[72:75], v[206:209], v[194:197], v[72:75]
	v_mfma_f32_16x16x32_bf16 v[64:67], v[214:217], v[194:197], v[64:67]
	s_barrier
	s_setprio 0
	s_mov_b32 m0, s13
	ds_read_b128 v[166:169], v148 offset:16384
	ds_read_b128 v[170:173], v148 offset:17408
	ds_read_b128 v[174:177], v148 offset:18432
	ds_read_b128 v[178:181], v148 offset:19456
	ds_read_b128 v[182:185], v148 offset:20480
	ds_read_b128 v[186:189], v148 offset:21504
	ds_read_b128 v[190:193], v148 offset:22528
	ds_read_b128 v[194:197], v148 offset:23552
	global_load_lds_dwordx4 v134, s[22:23]
	s_mov_b32 m0, s28
	s_nop 0
	global_load_lds_dwordx4 v130, s[22:23]
	s_setprio 1
	s_barrier
	s_waitcnt lgkmcnt(0)
	v_mfma_f32_16x16x32_bf16 v[60:63], v[150:153], v[166:169], 0
	v_mfma_f32_16x16x32_bf16 v[56:59], v[158:161], v[166:169], 0
	v_mfma_f32_16x16x32_bf16 v[44:47], v[150:153], v[174:177], 0
	v_mfma_f32_16x16x32_bf16 v[40:43], v[158:161], v[174:177], 0
	v_mfma_f32_16x16x32_bf16 v[28:31], v[150:153], v[182:185], 0
	v_mfma_f32_16x16x32_bf16 v[24:27], v[158:161], v[182:185], 0
	v_mfma_f32_16x16x32_bf16 v[12:15], v[150:153], v[190:193], 0
	v_mfma_f32_16x16x32_bf16 v[8:11], v[158:161], v[190:193], 0
	v_mfma_f32_16x16x32_bf16 v[60:63], v[154:157], v[170:173], v[60:63]
	v_mfma_f32_16x16x32_bf16 v[56:59], v[162:165], v[170:173], v[56:59]
	v_mfma_f32_16x16x32_bf16 v[44:47], v[154:157], v[178:181], v[44:47]
	v_mfma_f32_16x16x32_bf16 v[40:43], v[162:165], v[178:181], v[40:43]
	v_mfma_f32_16x16x32_bf16 v[28:31], v[154:157], v[186:189], v[28:31]
	v_mfma_f32_16x16x32_bf16 v[24:27], v[162:165], v[186:189], v[24:27]
	v_mfma_f32_16x16x32_bf16 v[12:15], v[154:157], v[194:197], v[12:15]
	v_mfma_f32_16x16x32_bf16 v[8:11], v[162:165], v[194:197], v[8:11]
	s_barrier
; #define PG8_STAGE(bufoff, gbase, voff) do { _Pragma("unroll") for (int _i = 0; _i < 2; ++_i) \
;         __builtin_amdgcn_global_load_lds((const unsigned*)((const char*)(gbase) + (voff)[_i]), (LAS unsigned*)(lds + (bufoff) + ldsw + _i * 8192), 16, 0, 0); } while (0)
; #define PG8_LDA(dst, b, h) do { _Pragma("unroll") for (int m = 0; m < 4; ++m) _Pragma("unroll") for (int k = 0; k < 2; ++k) dst[m][k] = *(const LAS bf16x8*)(lds + PG8_SA(b, h) + aoff + m * 2048 + k * 1024); } while (0)
; #define PG8_LDB(dst, b, h) do { _Pragma("unroll") for (int n = 0; n < 2; ++n) _Pragma("unroll") for (int k = 0; k < 2; ++k) dst[n][k] = *(const LAS bf16x8*)(lds + PG8_SB(b, h) + boff + n * 2048 + k * 1024); } while (0)
; #define PG8_MMA(ai, bj, At, Bt) do { __builtin_amdgcn_s_setprio(1); _Pragma("unroll") for (int m = 0; m < 4; ++m) _Pragma("unroll") for (int n = 0; n < 2; ++n) _Pragma("unroll") for (int k = 0; k < 2; ++k) \
;         acc[ai][bj][m][n] = __builtin_amdgcn_mfma_f32_16x16x32_bf16(Bt[n][k], At[m][k], acc[ai][bj][m][n], 0, 0, 0); __builtin_amdgcn_s_setprio(0); } while (0)
; #define PG8_WAIT_V(n) asm volatile("s_waitcnt vmcnt(" #n ")" ::: "memory")
; #define PG8_WAIT_L(n) asm volatile("s_waitcnt lgkmcnt(" #n ")" ::: "memory")
; #define PG8_BAR __builtin_amdgcn_s_barrier()
; #define PG8_SCHED __builtin_amdgcn_sched_barrier(0)
; template <class Epi, class Sched>
; __device__ __forceinline__ void gemm_phase(LAS unsigned char* lds, const Gemm g, const Sched& S, const Epi& E) {
;     ...
;             PG8_STAGE(PG8_SB(0, 1), b2 + hstep, voffB);
;             PG8_WAIT_V(6); PG8_BAR; PG8_MMA(1, 1, At, B1); PG8_BAR;
;             PG8_LDB(B0, 1, 0); PG8_SCHED; PG8_LDA(At, 1, 0); PG8_STAGE(PG8_SA(0, 1), a2 + hstep, voffA);
;             PG8_WAIT_L(8); PG8_BAR; PG8_WAIT_L(0); PG8_MMA(0, 0, At, B0); PG8_BAR; PG8_SCHED;
;             PG8_LDB(B1, 1, 1); PG8_STAGE(PG8_SB(1, 0), b3, voffB);
;             PG8_BAR; PG8_WAIT_L(0); PG8_MMA(0, 1, At, B1); PG8_BAR;
;             PG8_LDA(At, 1, 1); PG8_STAGE(PG8_SA(1, 0), a3, voffA);
;             PG8_BAR; PG8_WAIT_L(0); PG8_MMA(1, 0, At, B0); PG8_BAR; PG8_SCHED;
	s_setprio 0
	s_add_u32 s16, s18, 0x40000
	s_addc_u32 s17, s19, 0
	s_add_i32 s20, s41, s25
	s_mov_b32 m0, s20
	s_nop 0
	global_load_lds_dwordx4 v132, s[16:17]
	s_add_i32 m0, s20, 0x2000
	s_nop 0
	global_load_lds_dwordx4 v128, s[16:17]
	s_add_u32 s16, s22, 0x40000
	s_addc_u32 s17, s23, 0
	s_mov_b32 m0, s29
	s_nop 0
	global_load_lds_dwordx4 v134, s[16:17]
	s_mov_b32 m0, s33
	s_nop 0
	global_load_lds_dwordx4 v130, s[16:17]
	s_waitcnt vmcnt(10)
	s_setprio 1
	s_barrier
	v_mfma_f32_16x16x32_bf16 v[52:55], v[202:205], v[166:169], 0
	v_mfma_f32_16x16x32_bf16 v[48:51], v[210:213], v[166:169], 0
	v_mfma_f32_16x16x32_bf16 v[36:39], v[202:205], v[174:177], 0
	v_mfma_f32_16x16x32_bf16 v[32:35], v[210:213], v[174:177], 0
	v_mfma_f32_16x16x32_bf16 v[20:23], v[202:205], v[182:185], 0
	v_mfma_f32_16x16x32_bf16 v[16:19], v[210:213], v[182:185], 0
	v_mfma_f32_16x16x32_bf16 v[4:7], v[202:205], v[190:193], 0
	v_mfma_f32_16x16x32_bf16 v[0:3], v[210:213], v[190:193], 0
	v_mfma_f32_16x16x32_bf16 v[52:55], v[206:209], v[170:173], v[52:55]
	v_mfma_f32_16x16x32_bf16 v[48:51], v[214:217], v[170:173], v[48:51]
	v_mfma_f32_16x16x32_bf16 v[36:39], v[206:209], v[178:181], v[36:39]
	v_mfma_f32_16x16x32_bf16 v[32:35], v[214:217], v[178:181], v[32:35]
	v_mfma_f32_16x16x32_bf16 v[20:23], v[206:209], v[186:189], v[20:23]
	v_mfma_f32_16x16x32_bf16 v[16:19], v[214:217], v[186:189], v[16:19]
	v_mfma_f32_16x16x32_bf16 v[4:7], v[206:209], v[194:197], v[4:7]
	v_mfma_f32_16x16x32_bf16 v[0:3], v[214:217], v[194:197], v[0:3]
	s_barrier
	s_setprio 0
	s_add_i32 s20, 0, 0x18000
	ds_read_b128 v[150:153], v149 offset:16384
	ds_read_b128 v[154:157], v149 offset:17408
	ds_read_b128 v[158:161], v149 offset:18432
	ds_read_b128 v[162:165], v149 offset:19456
	ds_read_b128 v[166:169], v148 offset:32768
	ds_read_b128 v[170:173], v148 offset:33792
	ds_read_b128 v[174:177], v148 offset:34816
	ds_read_b128 v[178:181], v148 offset:35840
	ds_read_b128 v[182:185], v148 offset:36864
	ds_read_b128 v[186:189], v148 offset:37888
	ds_read_b128 v[190:193], v148 offset:38912
	ds_read_b128 v[194:197], v148 offset:39936
	s_waitcnt lgkmcnt(8)
	s_waitcnt vmcnt(8)
	s_setprio 1
	s_barrier
	s_waitcnt lgkmcnt(0)
	v_mfma_f32_16x16x32_bf16 v[124:127], v[150:153], v[166:169], v[124:127]
	v_mfma_f32_16x16x32_bf16 v[116:119], v[158:161], v[166:169], v[116:119]
	v_mfma_f32_16x16x32_bf16 v[108:111], v[150:153], v[174:177], v[108:111]
	v_mfma_f32_16x16x32_bf16 v[100:103], v[158:161], v[174:177], v[100:103]
	v_mfma_f32_16x16x32_bf16 v[92:95], v[150:153], v[182:185], v[92:95]
	v_mfma_f32_16x16x32_bf16 v[84:87], v[158:161], v[182:185], v[84:87]
	v_mfma_f32_16x16x32_bf16 v[76:79], v[150:153], v[190:193], v[76:79]
	v_mfma_f32_16x16x32_bf16 v[68:71], v[158:161], v[190:193], v[68:71]
	v_mfma_f32_16x16x32_bf16 v[124:127], v[154:157], v[170:173], v[124:127]
	v_mfma_f32_16x16x32_bf16 v[116:119], v[162:165], v[170:173], v[116:119]
	v_mfma_f32_16x16x32_bf16 v[108:111], v[154:157], v[178:181], v[108:111]
	v_mfma_f32_16x16x32_bf16 v[100:103], v[162:165], v[178:181], v[100:103]
	v_mfma_f32_16x16x32_bf16 v[92:95], v[154:157], v[186:189], v[92:95]
	v_mfma_f32_16x16x32_bf16 v[84:87], v[162:165], v[186:189], v[84:87]
	v_mfma_f32_16x16x32_bf16 v[76:79], v[154:157], v[194:197], v[76:79]
	v_mfma_f32_16x16x32_bf16 v[68:71], v[162:165], v[194:197], v[68:71]
	s_barrier
	s_setprio 0
	s_add_i32 s21, 0, 0x1c000
	s_add_i32 s16, s20, s25
	v_add_u32_e32 v214, s21, v146
	s_add_u32 s0, s18, 0x80
	s_addc_u32 s1, s19, 0
	s_mov_b32 m0, s16
	ds_read_b128 v[202:205], v214
	ds_read_b128 v[206:209], v214 offset:1024
	ds_read_b128 v[210:213], v214 offset:2048
	ds_read_b128 v[214:217], v214 offset:3072
	global_load_lds_dwordx4 v132, s[0:1]
	s_add_i32 m0, s16, 0x2000
	s_nop 0
	global_load_lds_dwordx4 v128, s[0:1]
	s_waitcnt vmcnt(8)
	s_setprio 1
	s_barrier
	s_waitcnt lgkmcnt(0)
	v_mfma_f32_16x16x32_bf16 v[120:123], v[202:205], v[166:169], v[120:123]
	v_mfma_f32_16x16x32_bf16 v[112:115], v[210:213], v[166:169], v[112:115]
	v_mfma_f32_16x16x32_bf16 v[104:107], v[202:205], v[174:177], v[104:107]
	v_mfma_f32_16x16x32_bf16 v[96:99], v[210:213], v[174:177], v[96:99]
	v_mfma_f32_16x16x32_bf16 v[88:91], v[202:205], v[182:185], v[88:91]
	v_mfma_f32_16x16x32_bf16 v[80:83], v[210:213], v[182:185], v[80:83]
	v_mfma_f32_16x16x32_bf16 v[72:75], v[202:205], v[190:193], v[72:75]
	v_mfma_f32_16x16x32_bf16 v[64:67], v[210:213], v[190:193], v[64:67]
	v_mfma_f32_16x16x32_bf16 v[120:123], v[206:209], v[170:173], v[120:123]
	v_mfma_f32_16x16x32_bf16 v[112:115], v[214:217], v[170:173], v[112:115]
	v_mfma_f32_16x16x32_bf16 v[104:107], v[206:209], v[178:181], v[104:107]
	v_mfma_f32_16x16x32_bf16 v[96:99], v[214:217], v[178:181], v[96:99]
	v_mfma_f32_16x16x32_bf16 v[88:91], v[206:209], v[186:189], v[88:91]
	v_mfma_f32_16x16x32_bf16 v[80:83], v[214:217], v[186:189], v[80:83]
	v_mfma_f32_16x16x32_bf16 v[72:75], v[206:209], v[194:197], v[72:75]
	v_mfma_f32_16x16x32_bf16 v[64:67], v[214:217], v[194:197], v[64:67]
	s_barrier
	s_setprio 0
	s_mov_b32 m0, s36
	s_add_u32 s0, s22, 0x80
	s_addc_u32 s1, s23, 0
	ds_read_b128 v[166:169], v148 offset:49152
	ds_read_b128 v[170:173], v148 offset:50176
	ds_read_b128 v[174:177], v148 offset:51200
	ds_read_b128 v[178:181], v148 offset:52224
	ds_read_b128 v[182:185], v148 offset:53248
	ds_read_b128 v[186:189], v148 offset:54272
	ds_read_b128 v[190:193], v148 offset:55296
	ds_read_b128 v[194:197], v148 offset:56320
	global_load_lds_dwordx4 v134, s[0:1]
	s_mov_b32 m0, s37
	s_nop 0
	global_load_lds_dwordx4 v130, s[0:1]
	s_setprio 1
	s_barrier
; #define PG8_STAGE(bufoff, gbase, voff) do { _Pragma("unroll") for (int _i = 0; _i < 2; ++_i) \
;         __builtin_amdgcn_global_load_lds((const unsigned*)((const char*)(gbase) + (voff)[_i]), (LAS unsigned*)(lds + (bufoff) + ldsw + _i * 8192), 16, 0, 0); } while (0)
; #define PG8_LDA(dst, b, h) do { _Pragma("unroll") for (int m = 0; m < 4; ++m) _Pragma("unroll") for (int k = 0; k < 2; ++k) dst[m][k] = *(const LAS bf16x8*)(lds + PG8_SA(b, h) + aoff + m * 2048 + k * 1024); } while (0)
; #define PG8_LDB(dst, b, h) do { _Pragma("unroll") for (int n = 0; n < 2; ++n) _Pragma("unroll") for (int k = 0; k < 2; ++k) dst[n][k] = *(const LAS bf16x8*)(lds + PG8_SB(b, h) + boff + n * 2048 + k * 1024); } while (0)
; #define PG8_MMA(ai, bj, At, Bt) do { __builtin_amdgcn_s_setprio(1); _Pragma("unroll") for (int m = 0; m < 4; ++m) _Pragma("unroll") for (int n = 0; n < 2; ++n) _Pragma("unroll") for (int k = 0; k < 2; ++k) \
;         acc[ai][bj][m][n] = __builtin_amdgcn_mfma_f32_16x16x32_bf16(Bt[n][k], At[m][k], acc[ai][bj][m][n], 0, 0, 0); __builtin_amdgcn_s_setprio(0); } while (0)
; #define PG8_WAIT_V(n) asm volatile("s_waitcnt vmcnt(" #n ")" ::: "memory")
; #define PG8_WAIT_L(n) asm volatile("s_waitcnt lgkmcnt(" #n ")" ::: "memory")
; #define PG8_BAR __builtin_amdgcn_s_barrier()
; #define PG8_SCHED __builtin_amdgcn_sched_barrier(0)
; template <class Epi, class Sched>
; __device__ __forceinline__ void gemm_phase(LAS unsigned char* lds, const Gemm g, const Sched& S, const Epi& E) {
;     ...
;             PG8_LDB(B0, 0, 0); PG8_SCHED; PG8_LDA(At, 0, 0); PG8_STAGE(PG8_SA(1, 1), a1 + hstep, voffA);
;             PG8_WAIT_L(8); PG8_BAR; PG8_WAIT_L(0); PG8_MMA(0, 0, At, B0); PG8_BAR; PG8_SCHED;
;             PG8_LDB(B1, 0, 1); PG8_STAGE(PG8_SB(0, 0), b2, voffB);
;             PG8_BAR; PG8_WAIT_L(0); PG8_MMA(0, 1, At, B1); PG8_BAR;
;             PG8_LDA(At, 0, 1); PG8_STAGE(PG8_SA(0, 0), a2, voffA);
;             PG8_BAR; PG8_WAIT_L(0); PG8_MMA(1, 0, At, B0); PG8_BAR; PG8_SCHED;
;     ...
;             PG8_BAR; PG8_WAIT_L(0); PG8_MMA(1, 0, At, B0); PG8_BAR; PG8_SCHED;
;             PG8_STAGE(PG8_SB(1, 1), b3 + hstep, voffB);
;             PG8_WAIT_V(6); PG8_BAR; PG8_MMA(1, 1, At, B1); PG8_BAR;
;         }
	s_waitcnt lgkmcnt(0)
	v_mfma_f32_16x16x32_bf16 v[60:63], v[150:153], v[166:169], v[60:63]
	v_mfma_f32_16x16x32_bf16 v[56:59], v[158:161], v[166:169], v[56:59]
	v_mfma_f32_16x16x32_bf16 v[44:47], v[150:153], v[174:177], v[44:47]
	v_mfma_f32_16x16x32_bf16 v[40:43], v[158:161], v[174:177], v[40:43]
	v_mfma_f32_16x16x32_bf16 v[28:31], v[150:153], v[182:185], v[28:31]
	v_mfma_f32_16x16x32_bf16 v[24:27], v[158:161], v[182:185], v[24:27]
	v_mfma_f32_16x16x32_bf16 v[12:15], v[150:153], v[190:193], v[12:15]
	v_mfma_f32_16x16x32_bf16 v[8:11], v[158:161], v[190:193], v[8:11]
	v_mfma_f32_16x16x32_bf16 v[60:63], v[154:157], v[170:173], v[60:63]
	v_mfma_f32_16x16x32_bf16 v[56:59], v[162:165], v[170:173], v[56:59]
	v_mfma_f32_16x16x32_bf16 v[44:47], v[154:157], v[178:181], v[44:47]
	v_mfma_f32_16x16x32_bf16 v[40:43], v[162:165], v[178:181], v[40:43]
	v_mfma_f32_16x16x32_bf16 v[28:31], v[154:157], v[186:189], v[28:31]
	v_mfma_f32_16x16x32_bf16 v[24:27], v[162:165], v[186:189], v[24:27]
	v_mfma_f32_16x16x32_bf16 v[12:15], v[154:157], v[194:197], v[12:15]
	v_mfma_f32_16x16x32_bf16 v[8:11], v[162:165], v[194:197], v[8:11]
	s_barrier
	s_setprio 0
	s_add_u32 s16, s18, 0x40080
	s_addc_u32 s17, s19, 0
	s_add_i32 s18, s21, s25
	s_mov_b32 m0, s18
	s_nop 0
	global_load_lds_dwordx4 v132, s[16:17]
	s_add_i32 m0, s18, 0x2000
	s_nop 0
	global_load_lds_dwordx4 v128, s[16:17]
	s_waitcnt vmcnt(8)
	s_setprio 1
	s_barrier
	v_mfma_f32_16x16x32_bf16 v[52:55], v[202:205], v[166:169], v[52:55]
	v_mfma_f32_16x16x32_bf16 v[48:51], v[210:213], v[166:169], v[48:51]
	v_mfma_f32_16x16x32_bf16 v[36:39], v[202:205], v[174:177], v[36:39]
	v_mfma_f32_16x16x32_bf16 v[32:35], v[210:213], v[174:177], v[32:35]
	v_mfma_f32_16x16x32_bf16 v[20:23], v[202:205], v[182:185], v[20:23]
	v_mfma_f32_16x16x32_bf16 v[16:19], v[210:213], v[182:185], v[16:19]
	v_mfma_f32_16x16x32_bf16 v[4:7], v[202:205], v[190:193], v[4:7]
	v_mfma_f32_16x16x32_bf16 v[0:3], v[210:213], v[190:193], v[0:3]
	v_mfma_f32_16x16x32_bf16 v[52:55], v[206:209], v[170:173], v[52:55]
	v_mfma_f32_16x16x32_bf16 v[48:51], v[214:217], v[170:173], v[48:51]
	v_mfma_f32_16x16x32_bf16 v[36:39], v[206:209], v[178:181], v[36:39]
	v_mfma_f32_16x16x32_bf16 v[32:35], v[214:217], v[178:181], v[32:35]
	v_mfma_f32_16x16x32_bf16 v[20:23], v[206:209], v[186:189], v[20:23]
	v_mfma_f32_16x16x32_bf16 v[16:19], v[214:217], v[186:189], v[16:19]
	v_mfma_f32_16x16x32_bf16 v[4:7], v[206:209], v[194:197], v[4:7]
	v_mfma_f32_16x16x32_bf16 v[0:3], v[214:217], v[194:197], v[0:3]
	s_barrier
	s_setprio 0
	s_add_i32 s48, s48, 2
	s_add_u32 s14, s14, 0x100
	s_addc_u32 s15, s15, 0
	s_add_u32 s46, s46, 0x100
	s_addc_u32 s47, s47, 0
	s_cmp_gt_u32 s48, 13
.LBB0_235:
	ds_read_b128 v[150:153], v147
	ds_read_b128 v[154:157], v147 offset:1024
	ds_read_b128 v[158:161], v147 offset:2048
	ds_read_b128 v[162:165], v147 offset:3072
	s_add_u32 s16, s14, 0xfffc0080
	s_addc_u32 s17, s15, -1
	s_cmp_eq_u32 s48, 12
	s_cselect_b32 s23, s7, s17
	s_cselect_b32 s22, s44, s16
	s_cselect_b32 s19, s5, s47
	s_cselect_b32 s18, s45, s46
	s_add_i32 m0, s13, 0xc000
	ds_read_b128 v[166:169], v148
	ds_read_b128 v[170:173], v148 offset:1024
	ds_read_b128 v[174:177], v148 offset:2048
	ds_read_b128 v[178:181], v148 offset:3072
	ds_read_b128 v[182:185], v148 offset:4096
	ds_read_b128 v[186:189], v148 offset:5120
	ds_read_b128 v[190:193], v148 offset:6144
	ds_read_b128 v[194:197], v148 offset:7168
	global_load_lds_dwordx4 v136, s[14:15]
	s_add_i32 m0, s13, 0xe000
	s_nop 0
	global_load_lds_dwordx4 v138, s[14:15]
	s_waitcnt lgkmcnt(8)
	s_waitcnt vmcnt(8)
	s_setprio 1
	s_barrier
	s_waitcnt lgkmcnt(0)
	v_mfma_f32_16x16x32_bf16 v[124:127], v[150:153], v[166:169], v[124:127]
	v_mfma_f32_16x16x32_bf16 v[116:119], v[158:161], v[166:169], v[116:119]
	v_mfma_f32_16x16x32_bf16 v[108:111], v[150:153], v[174:177], v[108:111]
	v_mfma_f32_16x16x32_bf16 v[100:103], v[158:161], v[174:177], v[100:103]
	v_mfma_f32_16x16x32_bf16 v[92:95], v[150:153], v[182:185], v[92:95]
	v_mfma_f32_16x16x32_bf16 v[84:87], v[158:161], v[182:185], v[84:87]
	v_mfma_f32_16x16x32_bf16 v[76:79], v[150:153], v[190:193], v[76:79]
	v_mfma_f32_16x16x32_bf16 v[68:71], v[158:161], v[190:193], v[68:71]
	v_mfma_f32_16x16x32_bf16 v[124:127], v[154:157], v[170:173], v[124:127]
	v_mfma_f32_16x16x32_bf16 v[116:119], v[162:165], v[170:173], v[116:119]
	v_mfma_f32_16x16x32_bf16 v[108:111], v[154:157], v[178:181], v[108:111]
	v_mfma_f32_16x16x32_bf16 v[100:103], v[162:165], v[178:181], v[100:103]
	v_mfma_f32_16x16x32_bf16 v[92:95], v[154:157], v[186:189], v[92:95]
	v_mfma_f32_16x16x32_bf16 v[84:87], v[162:165], v[186:189], v[84:87]
	v_mfma_f32_16x16x32_bf16 v[76:79], v[154:157], v[194:197], v[76:79]
	v_mfma_f32_16x16x32_bf16 v[68:71], v[162:165], v[194:197], v[68:71]
	s_barrier
	s_setprio 0
	s_add_i32 s16, s40, s25
	s_mov_b32 m0, s16
	ds_read_b128 v[202:205], v149
	ds_read_b128 v[206:209], v149 offset:1024
	ds_read_b128 v[210:213], v149 offset:2048
	ds_read_b128 v[214:217], v149 offset:3072
	global_load_lds_dwordx4 v132, s[18:19]
	s_add_i32 m0, s16, 0x2000
	s_nop 0
	global_load_lds_dwordx4 v128, s[18:19]
	s_waitcnt vmcnt(8)
	s_setprio 1
	s_barrier
; #define PG8_STAGE(bufoff, gbase, voff) do { _Pragma("unroll") for (int _i = 0; _i < 2; ++_i) \
;         __builtin_amdgcn_global_load_lds((const unsigned*)((const char*)(gbase) + (voff)[_i]), (LAS unsigned*)(lds + (bufoff) + ldsw + _i * 8192), 16, 0, 0); } while (0)
; #define PG8_LDA(dst, b, h) do { _Pragma("unroll") for (int m = 0; m < 4; ++m) _Pragma("unroll") for (int k = 0; k < 2; ++k) dst[m][k] = *(const LAS bf16x8*)(lds + PG8_SA(b, h) + aoff + m * 2048 + k * 1024); } while (0)
; #define PG8_LDB(dst, b, h) do { _Pragma("unroll") for (int n = 0; n < 2; ++n) _Pragma("unroll") for (int k = 0; k < 2; ++k) dst[n][k] = *(const LAS bf16x8*)(lds + PG8_SB(b, h) + boff + n * 2048 + k * 1024); } while (0)
; #define PG8_MMA(ai, bj, At, Bt) do { __builtin_amdgcn_s_setprio(1); _Pragma("unroll") for (int m = 0; m < 4; ++m) _Pragma("unroll") for (int n = 0; n < 2; ++n) _Pragma("unroll") for (int k = 0; k < 2; ++k) \
;         acc[ai][bj][m][n] = __builtin_amdgcn_mfma_f32_16x16x32_bf16(Bt[n][k], At[m][k], acc[ai][bj][m][n], 0, 0, 0); __builtin_amdgcn_s_setprio(0); } while (0)
; #define PG8_WAIT_V(n) asm volatile("s_waitcnt vmcnt(" #n ")" ::: "memory")
; #define PG8_WAIT_L(n) asm volatile("s_waitcnt lgkmcnt(" #n ")" ::: "memory")
; #define PG8_BAR __builtin_amdgcn_s_barrier()
; #define PG8_SCHED __builtin_amdgcn_sched_barrier(0)
; template <class Epi, class Sched>
; __device__ __forceinline__ void gemm_phase(LAS unsigned char* lds, const Gemm g, const Sched& S, const Epi& E) {
;     ...
;             PG8_BAR; PG8_WAIT_L(0); PG8_MMA(1, 0, At, B0); PG8_BAR; PG8_SCHED;
;             PG8_STAGE(PG8_SB(0, 1), b2 + hstep, voffB);
;             PG8_WAIT_V(6); PG8_BAR; PG8_MMA(1, 1, At, B1); PG8_BAR;
;             PG8_LDB(B0, 1, 0); PG8_SCHED; PG8_LDA(At, 1, 0); PG8_STAGE(PG8_SA(0, 1), a2 + hstep, voffA);
;             PG8_WAIT_L(8); PG8_BAR; PG8_WAIT_L(0); PG8_MMA(0, 0, At, B0); PG8_BAR; PG8_SCHED;
	s_waitcnt lgkmcnt(0)
	v_mfma_f32_16x16x32_bf16 v[120:123], v[202:205], v[166:169], v[120:123]
	v_mfma_f32_16x16x32_bf16 v[112:115], v[210:213], v[166:169], v[112:115]
	v_mfma_f32_16x16x32_bf16 v[104:107], v[202:205], v[174:177], v[104:107]
	v_mfma_f32_16x16x32_bf16 v[96:99], v[210:213], v[174:177], v[96:99]
	v_mfma_f32_16x16x32_bf16 v[88:91], v[202:205], v[182:185], v[88:91]
	v_mfma_f32_16x16x32_bf16 v[80:83], v[210:213], v[182:185], v[80:83]
	v_mfma_f32_16x16x32_bf16 v[72:75], v[202:205], v[190:193], v[72:75]
	v_mfma_f32_16x16x32_bf16 v[64:67], v[210:213], v[190:193], v[64:67]
	v_mfma_f32_16x16x32_bf16 v[120:123], v[206:209], v[170:173], v[120:123]
	v_mfma_f32_16x16x32_bf16 v[112:115], v[214:217], v[170:173], v[112:115]
	v_mfma_f32_16x16x32_bf16 v[104:107], v[206:209], v[178:181], v[104:107]
	v_mfma_f32_16x16x32_bf16 v[96:99], v[214:217], v[178:181], v[96:99]
	v_mfma_f32_16x16x32_bf16 v[88:91], v[206:209], v[186:189], v[88:91]
	v_mfma_f32_16x16x32_bf16 v[80:83], v[214:217], v[186:189], v[80:83]
	v_mfma_f32_16x16x32_bf16 v[72:75], v[206:209], v[194:197], v[72:75]
	v_mfma_f32_16x16x32_bf16 v[64:67], v[214:217], v[194:197], v[64:67]
	s_barrier
	s_setprio 0
	s_mov_b32 m0, s13
	ds_read_b128 v[166:169], v148 offset:16384
	ds_read_b128 v[170:173], v148 offset:17408
	ds_read_b128 v[174:177], v148 offset:18432
	ds_read_b128 v[178:181], v148 offset:19456
	ds_read_b128 v[182:185], v148 offset:20480
	ds_read_b128 v[186:189], v148 offset:21504
	ds_read_b128 v[190:193], v148 offset:22528
	ds_read_b128 v[194:197], v148 offset:23552
	global_load_lds_dwordx4 v134, s[22:23]
	s_mov_b32 m0, s28
	s_nop 0
	global_load_lds_dwordx4 v130, s[22:23]
	s_setprio 1
	s_barrier
	s_waitcnt lgkmcnt(0)
	v_mfma_f32_16x16x32_bf16 v[60:63], v[150:153], v[166:169], v[60:63]
	v_mfma_f32_16x16x32_bf16 v[56:59], v[158:161], v[166:169], v[56:59]
	v_mfma_f32_16x16x32_bf16 v[44:47], v[150:153], v[174:177], v[44:47]
	v_mfma_f32_16x16x32_bf16 v[40:43], v[158:161], v[174:177], v[40:43]
	v_mfma_f32_16x16x32_bf16 v[28:31], v[150:153], v[182:185], v[28:31]
	v_mfma_f32_16x16x32_bf16 v[24:27], v[158:161], v[182:185], v[24:27]
	v_mfma_f32_16x16x32_bf16 v[12:15], v[150:153], v[190:193], v[12:15]
	v_mfma_f32_16x16x32_bf16 v[8:11], v[158:161], v[190:193], v[8:11]
	v_mfma_f32_16x16x32_bf16 v[60:63], v[154:157], v[170:173], v[60:63]
	v_mfma_f32_16x16x32_bf16 v[56:59], v[162:165], v[170:173], v[56:59]
	v_mfma_f32_16x16x32_bf16 v[44:47], v[154:157], v[178:181], v[44:47]
	v_mfma_f32_16x16x32_bf16 v[40:43], v[162:165], v[178:181], v[40:43]
	v_mfma_f32_16x16x32_bf16 v[28:31], v[154:157], v[186:189], v[28:31]
	v_mfma_f32_16x16x32_bf16 v[24:27], v[162:165], v[186:189], v[24:27]
	v_mfma_f32_16x16x32_bf16 v[12:15], v[154:157], v[194:197], v[12:15]
	v_mfma_f32_16x16x32_bf16 v[8:11], v[162:165], v[194:197], v[8:11]
	s_barrier
	s_setprio 0
	s_add_u32 s16, s18, 0x40000
	s_addc_u32 s17, s19, 0
	s_add_i32 s20, s41, s25
	s_mov_b32 m0, s20
	s_nop 0
	global_load_lds_dwordx4 v132, s[16:17]
	s_add_i32 m0, s20, 0x2000
	s_nop 0
	global_load_lds_dwordx4 v128, s[16:17]
	s_add_u32 s16, s22, 0x40000
	s_addc_u32 s17, s23, 0
	s_mov_b32 m0, s29
	s_nop 0
	global_load_lds_dwordx4 v134, s[16:17]
	s_mov_b32 m0, s33
	s_nop 0
	global_load_lds_dwordx4 v130, s[16:17]
	s_waitcnt vmcnt(10)
	s_setprio 1
	s_barrier
	v_mfma_f32_16x16x32_bf16 v[52:55], v[202:205], v[166:169], v[52:55]
	v_mfma_f32_16x16x32_bf16 v[48:51], v[210:213], v[166:169], v[48:51]
	v_mfma_f32_16x16x32_bf16 v[36:39], v[202:205], v[174:177], v[36:39]
	v_mfma_f32_16x16x32_bf16 v[32:35], v[210:213], v[174:177], v[32:35]
	v_mfma_f32_16x16x32_bf16 v[20:23], v[202:205], v[182:185], v[20:23]
	v_mfma_f32_16x16x32_bf16 v[16:19], v[210:213], v[182:185], v[16:19]
	v_mfma_f32_16x16x32_bf16 v[4:7], v[202:205], v[190:193], v[4:7]
	v_mfma_f32_16x16x32_bf16 v[0:3], v[210:213], v[190:193], v[0:3]
	v_mfma_f32_16x16x32_bf16 v[52:55], v[206:209], v[170:173], v[52:55]
	v_mfma_f32_16x16x32_bf16 v[48:51], v[214:217], v[170:173], v[48:51]
	v_mfma_f32_16x16x32_bf16 v[36:39], v[206:209], v[178:181], v[36:39]
	v_mfma_f32_16x16x32_bf16 v[32:35], v[214:217], v[178:181], v[32:35]
	v_mfma_f32_16x16x32_bf16 v[20:23], v[206:209], v[186:189], v[20:23]
	v_mfma_f32_16x16x32_bf16 v[16:19], v[214:217], v[186:189], v[16:19]
	v_mfma_f32_16x16x32_bf16 v[4:7], v[206:209], v[194:197], v[4:7]
	v_mfma_f32_16x16x32_bf16 v[0:3], v[214:217], v[194:197], v[0:3]
	s_barrier
	s_setprio 0
	s_add_i32 s20, 0, 0x18000
	ds_read_b128 v[150:153], v149 offset:16384
	ds_read_b128 v[154:157], v149 offset:17408
	ds_read_b128 v[158:161], v149 offset:18432
	ds_read_b128 v[162:165], v149 offset:19456
	ds_read_b128 v[166:169], v148 offset:32768
	ds_read_b128 v[170:173], v148 offset:33792
	ds_read_b128 v[174:177], v148 offset:34816
	ds_read_b128 v[178:181], v148 offset:35840
	ds_read_b128 v[182:185], v148 offset:36864
	ds_read_b128 v[186:189], v148 offset:37888
	ds_read_b128 v[190:193], v148 offset:38912
	ds_read_b128 v[194:197], v148 offset:39936
	s_waitcnt lgkmcnt(8)
	s_waitcnt vmcnt(8)
	s_setprio 1
	s_barrier
; #define PG8_STAGE(bufoff, gbase, voff) do { _Pragma("unroll") for (int _i = 0; _i < 2; ++_i) \
;         __builtin_amdgcn_global_load_lds((const unsigned*)((const char*)(gbase) + (voff)[_i]), (LAS unsigned*)(lds + (bufoff) + ldsw + _i * 8192), 16, 0, 0); } while (0)
; #define PG8_LDA(dst, b, h) do { _Pragma("unroll") for (int m = 0; m < 4; ++m) _Pragma("unroll") for (int k = 0; k < 2; ++k) dst[m][k] = *(const LAS bf16x8*)(lds + PG8_SA(b, h) + aoff + m * 2048 + k * 1024); } while (0)
; #define PG8_LDB(dst, b, h) do { _Pragma("unroll") for (int n = 0; n < 2; ++n) _Pragma("unroll") for (int k = 0; k < 2; ++k) dst[n][k] = *(const LAS bf16x8*)(lds + PG8_SB(b, h) + boff + n * 2048 + k * 1024); } while (0)
; #define PG8_MMA(ai, bj, At, Bt) do { __builtin_amdgcn_s_setprio(1); _Pragma("unroll") for (int m = 0; m < 4; ++m) _Pragma("unroll") for (int n = 0; n < 2; ++n) _Pragma("unroll") for (int k = 0; k < 2; ++k) \
;         acc[ai][bj][m][n] = __builtin_amdgcn_mfma_f32_16x16x32_bf16(Bt[n][k], At[m][k], acc[ai][bj][m][n], 0, 0, 0); __builtin_amdgcn_s_setprio(0); } while (0)
; #define PG8_WAIT_V(n) asm volatile("s_waitcnt vmcnt(" #n ")" ::: "memory")
; #define PG8_WAIT_L(n) asm volatile("s_waitcnt lgkmcnt(" #n ")" ::: "memory")
; #define PG8_BAR __builtin_amdgcn_s_barrier()
; #define PG8_SCHED __builtin_amdgcn_sched_barrier(0)
; template <class Epi, class Sched>
; __device__ __forceinline__ void gemm_phase(LAS unsigned char* lds, const Gemm g, const Sched& S, const Epi& E) {
;     ...
;             PG8_WAIT_L(8); PG8_BAR; PG8_WAIT_L(0); PG8_MMA(0, 0, At, B0); PG8_BAR; PG8_SCHED;
;             PG8_LDB(B1, 1, 1); PG8_STAGE(PG8_SB(1, 0), b3, voffB);
;             PG8_BAR; PG8_WAIT_L(0); PG8_MMA(0, 1, At, B1); PG8_BAR;
;             PG8_LDA(At, 1, 1); PG8_STAGE(PG8_SA(1, 0), a3, voffA);
;             PG8_BAR; PG8_WAIT_L(0); PG8_MMA(1, 0, At, B0); PG8_BAR; PG8_SCHED;
;             PG8_STAGE(PG8_SB(1, 1), b3 + hstep, voffB);
;             PG8_WAIT_V(6); PG8_BAR; PG8_MMA(1, 1, At, B1); PG8_BAR;
;         }
	s_waitcnt lgkmcnt(0)
	v_mfma_f32_16x16x32_bf16 v[124:127], v[150:153], v[166:169], v[124:127]
	v_mfma_f32_16x16x32_bf16 v[116:119], v[158:161], v[166:169], v[116:119]
	v_mfma_f32_16x16x32_bf16 v[108:111], v[150:153], v[174:177], v[108:111]
	v_mfma_f32_16x16x32_bf16 v[100:103], v[158:161], v[174:177], v[100:103]
	v_mfma_f32_16x16x32_bf16 v[92:95], v[150:153], v[182:185], v[92:95]
	v_mfma_f32_16x16x32_bf16 v[84:87], v[158:161], v[182:185], v[84:87]
	v_mfma_f32_16x16x32_bf16 v[76:79], v[150:153], v[190:193], v[76:79]
	v_mfma_f32_16x16x32_bf16 v[68:71], v[158:161], v[190:193], v[68:71]
	v_mfma_f32_16x16x32_bf16 v[124:127], v[154:157], v[170:173], v[124:127]
	v_mfma_f32_16x16x32_bf16 v[116:119], v[162:165], v[170:173], v[116:119]
	v_mfma_f32_16x16x32_bf16 v[108:111], v[154:157], v[178:181], v[108:111]
	v_mfma_f32_16x16x32_bf16 v[100:103], v[162:165], v[178:181], v[100:103]
	v_mfma_f32_16x16x32_bf16 v[92:95], v[154:157], v[186:189], v[92:95]
	v_mfma_f32_16x16x32_bf16 v[84:87], v[162:165], v[186:189], v[84:87]
	v_mfma_f32_16x16x32_bf16 v[76:79], v[154:157], v[194:197], v[76:79]
	v_mfma_f32_16x16x32_bf16 v[68:71], v[162:165], v[194:197], v[68:71]
	s_barrier
	s_setprio 0
	s_add_i32 s21, 0, 0x1c000
	s_add_i32 s16, s20, s25
	v_add_u32_e32 v214, s21, v146
	s_add_u32 s0, s18, 0x80
	s_addc_u32 s1, s19, 0
	s_mov_b32 m0, s16
	ds_read_b128 v[202:205], v214
	ds_read_b128 v[206:209], v214 offset:1024
	ds_read_b128 v[210:213], v214 offset:2048
	ds_read_b128 v[214:217], v214 offset:3072
	global_load_lds_dwordx4 v132, s[0:1]
	s_add_i32 m0, s16, 0x2000
	s_nop 0
	global_load_lds_dwordx4 v128, s[0:1]
	s_waitcnt vmcnt(8)
	s_setprio 1
	s_barrier
	s_waitcnt lgkmcnt(0)
	v_mfma_f32_16x16x32_bf16 v[120:123], v[202:205], v[166:169], v[120:123]
	v_mfma_f32_16x16x32_bf16 v[112:115], v[210:213], v[166:169], v[112:115]
	v_mfma_f32_16x16x32_bf16 v[104:107], v[202:205], v[174:177], v[104:107]
	v_mfma_f32_16x16x32_bf16 v[96:99], v[210:213], v[174:177], v[96:99]
	v_mfma_f32_16x16x32_bf16 v[88:91], v[202:205], v[182:185], v[88:91]
	v_mfma_f32_16x16x32_bf16 v[80:83], v[210:213], v[182:185], v[80:83]
	v_mfma_f32_16x16x32_bf16 v[72:75], v[202:205], v[190:193], v[72:75]
	v_mfma_f32_16x16x32_bf16 v[64:67], v[210:213], v[190:193], v[64:67]
	v_mfma_f32_16x16x32_bf16 v[120:123], v[206:209], v[170:173], v[120:123]
	v_mfma_f32_16x16x32_bf16 v[112:115], v[214:217], v[170:173], v[112:115]
	v_mfma_f32_16x16x32_bf16 v[104:107], v[206:209], v[178:181], v[104:107]
	v_mfma_f32_16x16x32_bf16 v[96:99], v[214:217], v[178:181], v[96:99]
	v_mfma_f32_16x16x32_bf16 v[88:91], v[206:209], v[186:189], v[88:91]
	v_mfma_f32_16x16x32_bf16 v[80:83], v[214:217], v[186:189], v[80:83]
	v_mfma_f32_16x16x32_bf16 v[72:75], v[206:209], v[194:197], v[72:75]
	v_mfma_f32_16x16x32_bf16 v[64:67], v[214:217], v[194:197], v[64:67]
	s_barrier
	s_setprio 0
	s_mov_b32 m0, s36
	s_add_u32 s0, s22, 0x80
	s_addc_u32 s1, s23, 0
	ds_read_b128 v[166:169], v148 offset:49152
	ds_read_b128 v[170:173], v148 offset:50176
	ds_read_b128 v[174:177], v148 offset:51200
	ds_read_b128 v[178:181], v148 offset:52224
	ds_read_b128 v[182:185], v148 offset:53248
	ds_read_b128 v[186:189], v148 offset:54272
	ds_read_b128 v[190:193], v148 offset:55296
	ds_read_b128 v[194:197], v148 offset:56320
	global_load_lds_dwordx4 v134, s[0:1]
	s_mov_b32 m0, s37
	s_nop 0
	global_load_lds_dwordx4 v130, s[0:1]
	s_setprio 1
	s_barrier
	s_waitcnt lgkmcnt(0)
	v_mfma_f32_16x16x32_bf16 v[60:63], v[150:153], v[166:169], v[60:63]
	v_mfma_f32_16x16x32_bf16 v[56:59], v[158:161], v[166:169], v[56:59]
	v_mfma_f32_16x16x32_bf16 v[44:47], v[150:153], v[174:177], v[44:47]
	v_mfma_f32_16x16x32_bf16 v[40:43], v[158:161], v[174:177], v[40:43]
	v_mfma_f32_16x16x32_bf16 v[28:31], v[150:153], v[182:185], v[28:31]
	v_mfma_f32_16x16x32_bf16 v[24:27], v[158:161], v[182:185], v[24:27]
	v_mfma_f32_16x16x32_bf16 v[12:15], v[150:153], v[190:193], v[12:15]
	v_mfma_f32_16x16x32_bf16 v[8:11], v[158:161], v[190:193], v[8:11]
	v_mfma_f32_16x16x32_bf16 v[60:63], v[154:157], v[170:173], v[60:63]
	v_mfma_f32_16x16x32_bf16 v[56:59], v[162:165], v[170:173], v[56:59]
	v_mfma_f32_16x16x32_bf16 v[44:47], v[154:157], v[178:181], v[44:47]
	v_mfma_f32_16x16x32_bf16 v[40:43], v[162:165], v[178:181], v[40:43]
	v_mfma_f32_16x16x32_bf16 v[28:31], v[154:157], v[186:189], v[28:31]
	v_mfma_f32_16x16x32_bf16 v[24:27], v[162:165], v[186:189], v[24:27]
	v_mfma_f32_16x16x32_bf16 v[12:15], v[154:157], v[194:197], v[12:15]
	v_mfma_f32_16x16x32_bf16 v[8:11], v[162:165], v[194:197], v[8:11]
	s_barrier
	s_setprio 0
	s_add_u32 s16, s18, 0x40080
	s_addc_u32 s17, s19, 0
	s_add_i32 s18, s21, s25
	s_mov_b32 m0, s18
	s_nop 0
	global_load_lds_dwordx4 v132, s[16:17]
	s_add_i32 m0, s18, 0x2000
	s_nop 0
	global_load_lds_dwordx4 v128, s[16:17]
	s_waitcnt vmcnt(8)
	s_setprio 1
	s_barrier
	v_mfma_f32_16x16x32_bf16 v[52:55], v[202:205], v[166:169], v[52:55]
	v_mfma_f32_16x16x32_bf16 v[48:51], v[210:213], v[166:169], v[48:51]
	v_mfma_f32_16x16x32_bf16 v[36:39], v[202:205], v[174:177], v[36:39]
	v_mfma_f32_16x16x32_bf16 v[32:35], v[210:213], v[174:177], v[32:35]
	v_mfma_f32_16x16x32_bf16 v[20:23], v[202:205], v[182:185], v[20:23]
	v_mfma_f32_16x16x32_bf16 v[16:19], v[210:213], v[182:185], v[16:19]
	v_mfma_f32_16x16x32_bf16 v[4:7], v[202:205], v[190:193], v[4:7]
	v_mfma_f32_16x16x32_bf16 v[0:3], v[210:213], v[190:193], v[0:3]
	v_mfma_f32_16x16x32_bf16 v[52:55], v[206:209], v[170:173], v[52:55]
	v_mfma_f32_16x16x32_bf16 v[48:51], v[214:217], v[170:173], v[48:51]
	v_mfma_f32_16x16x32_bf16 v[36:39], v[206:209], v[178:181], v[36:39]
	v_mfma_f32_16x16x32_bf16 v[32:35], v[214:217], v[178:181], v[32:35]
	v_mfma_f32_16x16x32_bf16 v[20:23], v[206:209], v[186:189], v[20:23]
	v_mfma_f32_16x16x32_bf16 v[16:19], v[214:217], v[186:189], v[16:19]
	v_mfma_f32_16x16x32_bf16 v[4:7], v[206:209], v[194:197], v[4:7]
	v_mfma_f32_16x16x32_bf16 v[0:3], v[214:217], v[194:197], v[0:3]
	s_setprio 0
	s_add_i32 s48, s48, 2
	s_add_u32 s14, s14, 0x100
	s_addc_u32 s15, s15, 0
	s_add_u32 s46, s46, 0x100
	s_addc_u32 s47, s47, 0
	s_cmp_gt_u32 s48, 13
	s_cbranch_scc1 .Lconc_last_g0
	s_barrier
	s_branch .LBB0_235

; #define PG8_STAGE(bufoff, gbase, voff) do { _Pragma("unroll") for (int _i = 0; _i < 2; ++_i) \
;         __builtin_amdgcn_global_load_lds((const unsigned*)((const char*)(gbase) + (voff)[_i]), (LAS unsigned*)(lds + (bufoff) + ldsw + _i * 8192), 16, 0, 0); } while (0)
; #define PG8_LDA(dst, b, h) do { _Pragma("unroll") for (int m = 0; m < 4; ++m) _Pragma("unroll") for (int k = 0; k < 2; ++k) dst[m][k] = *(const LAS bf16x8*)(lds + PG8_SA(b, h) + aoff + m * 2048 + k * 1024); } while (0)
; #define PG8_LDB(dst, b, h) do { _Pragma("unroll") for (int n = 0; n < 2; ++n) _Pragma("unroll") for (int k = 0; k < 2; ++k) dst[n][k] = *(const LAS bf16x8*)(lds + PG8_SB(b, h) + boff + n * 2048 + k * 1024); } while (0)
; #define PG8_MMA(ai, bj, At, Bt) do { __builtin_amdgcn_s_setprio(1); _Pragma("unroll") for (int m = 0; m < 4; ++m) _Pragma("unroll") for (int n = 0; n < 2; ++n) _Pragma("unroll") for (int k = 0; k < 2; ++k) \
;         acc[ai][bj][m][n] = __builtin_amdgcn_mfma_f32_16x16x32_bf16(Bt[n][k], At[m][k], acc[ai][bj][m][n], 0, 0, 0); __builtin_amdgcn_s_setprio(0); } while (0)
; #define PG8_WAIT_L(n) asm volatile("s_waitcnt lgkmcnt(" #n ")" ::: "memory")
; template <class Epi, class Sched>
; __device__ __forceinline__ void gemm_phase(LAS unsigned char* lds, const Gemm g, const Sched& S, const Epi& E) {
;     ...
;         const bool has_next = S.next(ui + 1, nxt);
;         const char* nA = has_next ? (const char*)g.A + (size_t)nxt.pm * tstep : cA; const char* nB = has_next ? (const char*)g.Bt + (size_t)nxt.pn * tstep : cB;
;         for (int t = 0; t < nt; t += 2) {
;             const bool last = (t == nt - 2);
;             const char* a1 = cA + (size_t)(t + 1) * kstep;
;             const char* a2 = last ? nA : cA + (size_t)(t + 2) * kstep; const char* b2 = last ? nB : cB + (size_t)(t + 2) * kstep;
;             const char* a3 = a2 + kstep; const char* b3 = b2 + kstep;
;             PG8_LDB(B0, 0, 0); PG8_SCHED; PG8_LDA(At, 0, 0); PG8_STAGE(PG8_SA(1, 1), a1 + hstep, voffA);
;             PG8_WAIT_L(8); PG8_BAR; PG8_WAIT_L(0); PG8_MMA(0, 0, At, B0); PG8_BAR; PG8_SCHED;
;             PG8_LDB(B1, 0, 1); PG8_STAGE(PG8_SB(0, 0), b2, voffB);
;             PG8_BAR; PG8_WAIT_L(0); PG8_MMA(0, 1, At, B1); PG8_BAR;
;             PG8_LDA(At, 0, 1); PG8_STAGE(PG8_SA(0, 0), a2, voffA);
;             PG8_BAR; PG8_WAIT_L(0); PG8_MMA(1, 0, At, B0); PG8_BAR; PG8_SCHED;
.LBB0_304:
	s_add_u32 s0, s28, 0x100
	s_addc_u32 s67, s29, 0
	s_mov_b32 s68, -2
	ds_read_b128 v[144:147], v165
	ds_read_b128 v[148:151], v165 offset:1024
	ds_read_b128 v[152:155], v165 offset:2048
	ds_read_b128 v[156:159], v165 offset:3072
	s_add_u32 s28, s26, 0x100
	s_addc_u32 s29, s27, 0
	s_cmp_eq_u32 s68, 40
	s_cselect_b32 s37, s5, s29
	s_cselect_b32 s36, s4, s28
	s_cselect_b32 s35, s7, s67
	s_cselect_b32 s34, s6, s0
	v_lshl_add_u64 v[160:161], s[26:27], 0, v[136:137]
	s_add_i32 m0, s42, 0xc000
	ds_read_b128 v[168:171], v166
	ds_read_b128 v[172:175], v166 offset:1024
	ds_read_b128 v[176:179], v166 offset:2048
	ds_read_b128 v[180:183], v166 offset:3072
	ds_read_b128 v[184:187], v166 offset:4096
	ds_read_b128 v[188:191], v166 offset:5120
	ds_read_b128 v[192:195], v166 offset:6144
	ds_read_b128 v[196:199], v166 offset:7168
	global_load_lds_dwordx4 v[160:161], off
	v_lshl_add_u64 v[160:161], s[26:27], 0, v[138:139]
	s_add_i32 m0, s42, 0xe000
	s_nop 0
	global_load_lds_dwordx4 v[160:161], off
	s_waitcnt lgkmcnt(8)
	s_waitcnt vmcnt(8)
	s_setprio 1
	s_barrier
	s_waitcnt lgkmcnt(0)
	v_mfma_f32_16x16x32_bf16 v[124:127], v[144:147], v[168:171], 0
	v_mfma_f32_16x16x32_bf16 v[120:123], v[152:155], v[168:171], 0
	v_mfma_f32_16x16x32_bf16 v[116:119], v[144:147], v[176:179], 0
	v_mfma_f32_16x16x32_bf16 v[104:107], v[152:155], v[176:179], 0
	v_mfma_f32_16x16x32_bf16 v[96:99], v[144:147], v[184:187], 0
	v_mfma_f32_16x16x32_bf16 v[88:91], v[152:155], v[184:187], 0
	v_mfma_f32_16x16x32_bf16 v[80:83], v[144:147], v[192:195], 0
	v_mfma_f32_16x16x32_bf16 v[72:75], v[152:155], v[192:195], 0
	v_mfma_f32_16x16x32_bf16 v[124:127], v[148:151], v[172:175], v[124:127]
	v_mfma_f32_16x16x32_bf16 v[120:123], v[156:159], v[172:175], v[120:123]
	v_mfma_f32_16x16x32_bf16 v[116:119], v[148:151], v[180:183], v[116:119]
	v_mfma_f32_16x16x32_bf16 v[104:107], v[156:159], v[180:183], v[104:107]
	v_mfma_f32_16x16x32_bf16 v[96:99], v[148:151], v[188:191], v[96:99]
	v_mfma_f32_16x16x32_bf16 v[88:91], v[156:159], v[188:191], v[88:91]
	v_mfma_f32_16x16x32_bf16 v[80:83], v[148:151], v[196:199], v[80:83]
	v_mfma_f32_16x16x32_bf16 v[72:75], v[156:159], v[196:199], v[72:75]
	s_barrier
	s_setprio 0
	s_add_i32 s16, s58, s40
	s_mov_b32 m0, s16
	ds_read_b128 v[202:205], v167
	ds_read_b128 v[206:209], v167 offset:1024
	ds_read_b128 v[210:213], v167 offset:2048
	ds_read_b128 v[214:217], v167 offset:3072
	global_load_lds_dwordx4 v132, s[34:35]
	s_add_i32 m0, s16, 0x2000
	s_nop 0
	global_load_lds_dwordx4 v128, s[34:35]
	s_waitcnt vmcnt(8)
	s_setprio 1
	s_barrier
	s_waitcnt lgkmcnt(0)
	v_mfma_f32_16x16x32_bf16 v[112:115], v[202:205], v[168:171], 0
	v_mfma_f32_16x16x32_bf16 v[108:111], v[210:213], v[168:171], 0
	v_mfma_f32_16x16x32_bf16 v[100:103], v[202:205], v[176:179], 0
	v_mfma_f32_16x16x32_bf16 v[92:95], v[210:213], v[176:179], 0
	v_mfma_f32_16x16x32_bf16 v[84:87], v[202:205], v[184:187], 0
	v_mfma_f32_16x16x32_bf16 v[76:79], v[210:213], v[184:187], 0
	v_mfma_f32_16x16x32_bf16 v[68:71], v[202:205], v[192:195], 0
	v_mfma_f32_16x16x32_bf16 v[64:67], v[210:213], v[192:195], 0
	v_mfma_f32_16x16x32_bf16 v[112:115], v[206:209], v[172:175], v[112:115]
	v_mfma_f32_16x16x32_bf16 v[108:111], v[214:217], v[172:175], v[108:111]
	v_mfma_f32_16x16x32_bf16 v[100:103], v[206:209], v[180:183], v[100:103]
	v_mfma_f32_16x16x32_bf16 v[92:95], v[214:217], v[180:183], v[92:95]
	v_mfma_f32_16x16x32_bf16 v[84:87], v[206:209], v[188:191], v[84:87]
	v_mfma_f32_16x16x32_bf16 v[76:79], v[214:217], v[188:191], v[76:79]
	v_mfma_f32_16x16x32_bf16 v[68:71], v[206:209], v[196:199], v[68:71]
	v_mfma_f32_16x16x32_bf16 v[64:67], v[214:217], v[196:199], v[64:67]
	s_barrier
	s_setprio 0
	s_mov_b32 m0, s42
	ds_read_b128 v[168:171], v166 offset:16384
	ds_read_b128 v[172:175], v166 offset:17408
	ds_read_b128 v[176:179], v166 offset:18432
	ds_read_b128 v[180:183], v166 offset:19456
	ds_read_b128 v[184:187], v166 offset:20480
	ds_read_b128 v[188:191], v166 offset:21504
	ds_read_b128 v[192:195], v166 offset:22528
	ds_read_b128 v[196:199], v166 offset:23552
	global_load_lds_dwordx4 v134, s[36:37]
	s_mov_b32 m0, s43
	s_nop 0
	global_load_lds_dwordx4 v130, s[36:37]
	s_setprio 1
	s_barrier
	s_waitcnt lgkmcnt(0)
	v_mfma_f32_16x16x32_bf16 v[60:63], v[144:147], v[168:171], 0
	v_mfma_f32_16x16x32_bf16 v[56:59], v[152:155], v[168:171], 0
	v_mfma_f32_16x16x32_bf16 v[48:51], v[144:147], v[176:179], 0
	v_mfma_f32_16x16x32_bf16 v[40:43], v[152:155], v[176:179], 0
	v_mfma_f32_16x16x32_bf16 v[32:35], v[144:147], v[184:187], 0
	v_mfma_f32_16x16x32_bf16 v[24:27], v[152:155], v[184:187], 0
	v_mfma_f32_16x16x32_bf16 v[16:19], v[144:147], v[192:195], 0
	v_mfma_f32_16x16x32_bf16 v[8:11], v[152:155], v[192:195], 0
	v_mfma_f32_16x16x32_bf16 v[60:63], v[148:151], v[172:175], v[60:63]
	v_mfma_f32_16x16x32_bf16 v[56:59], v[156:159], v[172:175], v[56:59]
	v_mfma_f32_16x16x32_bf16 v[48:51], v[148:151], v[180:183], v[48:51]
	v_mfma_f32_16x16x32_bf16 v[40:43], v[156:159], v[180:183], v[40:43]
	v_mfma_f32_16x16x32_bf16 v[32:35], v[148:151], v[188:191], v[32:35]
	v_mfma_f32_16x16x32_bf16 v[24:27], v[156:159], v[188:191], v[24:27]
	v_mfma_f32_16x16x32_bf16 v[16:19], v[148:151], v[196:199], v[16:19]
	v_mfma_f32_16x16x32_bf16 v[8:11], v[156:159], v[196:199], v[8:11]
	s_barrier
	s_setprio 0
	s_add_u32 s16, s34, 0xb0000
	s_addc_u32 s17, s35, 0
	s_add_i32 s20, s59, s40
	s_mov_b32 m0, s20
	s_nop 0
	global_load_lds_dwordx4 v132, s[16:17]
	s_add_i32 m0, s20, 0x2000
	s_nop 0
	global_load_lds_dwordx4 v128, s[16:17]
	s_add_u32 s16, s36, 0xb0000
	s_addc_u32 s17, s37, 0
	s_mov_b32 m0, s44
	s_nop 0
	global_load_lds_dwordx4 v134, s[16:17]
	s_mov_b32 m0, s45
	s_nop 0
	global_load_lds_dwordx4 v130, s[16:17]
	s_waitcnt vmcnt(10)
	s_setprio 1
	s_barrier
; #define PG8_STAGE(bufoff, gbase, voff) do { _Pragma("unroll") for (int _i = 0; _i < 2; ++_i) \
;         __builtin_amdgcn_global_load_lds((const unsigned*)((const char*)(gbase) + (voff)[_i]), (LAS unsigned*)(lds + (bufoff) + ldsw + _i * 8192), 16, 0, 0); } while (0)
; #define PG8_LDA(dst, b, h) do { _Pragma("unroll") for (int m = 0; m < 4; ++m) _Pragma("unroll") for (int k = 0; k < 2; ++k) dst[m][k] = *(const LAS bf16x8*)(lds + PG8_SA(b, h) + aoff + m * 2048 + k * 1024); } while (0)
; #define PG8_LDB(dst, b, h) do { _Pragma("unroll") for (int n = 0; n < 2; ++n) _Pragma("unroll") for (int k = 0; k < 2; ++k) dst[n][k] = *(const LAS bf16x8*)(lds + PG8_SB(b, h) + boff + n * 2048 + k * 1024); } while (0)
; #define PG8_MMA(ai, bj, At, Bt) do { __builtin_amdgcn_s_setprio(1); _Pragma("unroll") for (int m = 0; m < 4; ++m) _Pragma("unroll") for (int n = 0; n < 2; ++n) _Pragma("unroll") for (int k = 0; k < 2; ++k) \
;         acc[ai][bj][m][n] = __builtin_amdgcn_mfma_f32_16x16x32_bf16(Bt[n][k], At[m][k], acc[ai][bj][m][n], 0, 0, 0); __builtin_amdgcn_s_setprio(0); } while (0)
; #define PG8_WAIT_V(n) asm volatile("s_waitcnt vmcnt(" #n ")" ::: "memory")
; #define PG8_WAIT_L(n) asm volatile("s_waitcnt lgkmcnt(" #n ")" ::: "memory")
; #define PG8_BAR __builtin_amdgcn_s_barrier()
; #define PG8_SCHED __builtin_amdgcn_sched_barrier(0)
; template <class Epi, class Sched>
; __device__ __forceinline__ void gemm_phase(LAS unsigned char* lds, const Gemm g, const Sched& S, const Epi& E) {
;     ...
;             PG8_WAIT_V(6); PG8_BAR; PG8_MMA(1, 1, At, B1); PG8_BAR;
;             PG8_LDB(B0, 1, 0); PG8_SCHED; PG8_LDA(At, 1, 0); PG8_STAGE(PG8_SA(0, 1), a2 + hstep, voffA);
;             PG8_WAIT_L(8); PG8_BAR; PG8_WAIT_L(0); PG8_MMA(0, 0, At, B0); PG8_BAR; PG8_SCHED;
;             PG8_LDB(B1, 1, 1); PG8_STAGE(PG8_SB(1, 0), b3, voffB);
;             PG8_BAR; PG8_WAIT_L(0); PG8_MMA(0, 1, At, B1); PG8_BAR;
;             PG8_LDA(At, 1, 1); PG8_STAGE(PG8_SA(1, 0), a3, voffA);
;             PG8_BAR; PG8_WAIT_L(0); PG8_MMA(1, 0, At, B0); PG8_BAR; PG8_SCHED;
	v_mfma_f32_16x16x32_bf16 v[52:55], v[202:205], v[168:171], 0
	v_mfma_f32_16x16x32_bf16 v[44:47], v[210:213], v[168:171], 0
	v_mfma_f32_16x16x32_bf16 v[36:39], v[202:205], v[176:179], 0
	v_mfma_f32_16x16x32_bf16 v[28:31], v[210:213], v[176:179], 0
	v_mfma_f32_16x16x32_bf16 v[20:23], v[202:205], v[184:187], 0
	v_mfma_f32_16x16x32_bf16 v[12:15], v[210:213], v[184:187], 0
	v_mfma_f32_16x16x32_bf16 v[4:7], v[202:205], v[192:195], 0
	v_mfma_f32_16x16x32_bf16 v[0:3], v[210:213], v[192:195], 0
	v_mfma_f32_16x16x32_bf16 v[52:55], v[206:209], v[172:175], v[52:55]
	v_mfma_f32_16x16x32_bf16 v[44:47], v[214:217], v[172:175], v[44:47]
	v_mfma_f32_16x16x32_bf16 v[36:39], v[206:209], v[180:183], v[36:39]
	v_mfma_f32_16x16x32_bf16 v[28:31], v[214:217], v[180:183], v[28:31]
	v_mfma_f32_16x16x32_bf16 v[20:23], v[206:209], v[188:191], v[20:23]
	v_mfma_f32_16x16x32_bf16 v[12:15], v[214:217], v[188:191], v[12:15]
	v_mfma_f32_16x16x32_bf16 v[4:7], v[206:209], v[196:199], v[4:7]
	v_mfma_f32_16x16x32_bf16 v[0:3], v[214:217], v[196:199], v[0:3]
	s_barrier
	s_setprio 0
	s_add_i32 s20, 0, 0x18000
	ds_read_b128 v[144:147], v167 offset:16384
	ds_read_b128 v[148:151], v167 offset:17408
	ds_read_b128 v[152:155], v167 offset:18432
	ds_read_b128 v[156:159], v167 offset:19456
	ds_read_b128 v[168:171], v166 offset:32768
	ds_read_b128 v[172:175], v166 offset:33792
	ds_read_b128 v[176:179], v166 offset:34816
	ds_read_b128 v[180:183], v166 offset:35840
	ds_read_b128 v[184:187], v166 offset:36864
	ds_read_b128 v[188:191], v166 offset:37888
	ds_read_b128 v[192:195], v166 offset:38912
	ds_read_b128 v[196:199], v166 offset:39936
	s_waitcnt lgkmcnt(8)
	s_waitcnt vmcnt(8)
	s_setprio 1
	s_barrier
	s_waitcnt lgkmcnt(0)
	v_mfma_f32_16x16x32_bf16 v[124:127], v[144:147], v[168:171], v[124:127]
	v_mfma_f32_16x16x32_bf16 v[120:123], v[152:155], v[168:171], v[120:123]
	v_mfma_f32_16x16x32_bf16 v[116:119], v[144:147], v[176:179], v[116:119]
	v_mfma_f32_16x16x32_bf16 v[104:107], v[152:155], v[176:179], v[104:107]
	v_mfma_f32_16x16x32_bf16 v[96:99], v[144:147], v[184:187], v[96:99]
	v_mfma_f32_16x16x32_bf16 v[88:91], v[152:155], v[184:187], v[88:91]
	v_mfma_f32_16x16x32_bf16 v[80:83], v[144:147], v[192:195], v[80:83]
	v_mfma_f32_16x16x32_bf16 v[72:75], v[152:155], v[192:195], v[72:75]
	v_mfma_f32_16x16x32_bf16 v[124:127], v[148:151], v[172:175], v[124:127]
	v_mfma_f32_16x16x32_bf16 v[120:123], v[156:159], v[172:175], v[120:123]
	v_mfma_f32_16x16x32_bf16 v[116:119], v[148:151], v[180:183], v[116:119]
	v_mfma_f32_16x16x32_bf16 v[104:107], v[156:159], v[180:183], v[104:107]
	v_mfma_f32_16x16x32_bf16 v[96:99], v[148:151], v[188:191], v[96:99]
	v_mfma_f32_16x16x32_bf16 v[88:91], v[156:159], v[188:191], v[88:91]
	v_mfma_f32_16x16x32_bf16 v[80:83], v[148:151], v[196:199], v[80:83]
	v_mfma_f32_16x16x32_bf16 v[72:75], v[156:159], v[196:199], v[72:75]
	s_barrier
	s_setprio 0
	s_add_i32 s21, 0, 0x1c000
	s_add_i32 s16, s20, s40
	v_add_u32_e32 v214, s21, v164
	s_add_u32 s8, s34, 0x80
	s_addc_u32 s9, s35, 0
	s_mov_b32 m0, s16
	ds_read_b128 v[202:205], v214
	ds_read_b128 v[206:209], v214 offset:1024
	ds_read_b128 v[210:213], v214 offset:2048
	ds_read_b128 v[214:217], v214 offset:3072
	global_load_lds_dwordx4 v132, s[8:9]
	s_add_i32 m0, s16, 0x2000
	s_nop 0
	global_load_lds_dwordx4 v128, s[8:9]
	s_waitcnt vmcnt(8)
	s_setprio 1
	s_barrier
	s_waitcnt lgkmcnt(0)
	v_mfma_f32_16x16x32_bf16 v[112:115], v[202:205], v[168:171], v[112:115]
	v_mfma_f32_16x16x32_bf16 v[108:111], v[210:213], v[168:171], v[108:111]
	v_mfma_f32_16x16x32_bf16 v[100:103], v[202:205], v[176:179], v[100:103]
	v_mfma_f32_16x16x32_bf16 v[92:95], v[210:213], v[176:179], v[92:95]
	v_mfma_f32_16x16x32_bf16 v[84:87], v[202:205], v[184:187], v[84:87]
	v_mfma_f32_16x16x32_bf16 v[76:79], v[210:213], v[184:187], v[76:79]
	v_mfma_f32_16x16x32_bf16 v[68:71], v[202:205], v[192:195], v[68:71]
	v_mfma_f32_16x16x32_bf16 v[64:67], v[210:213], v[192:195], v[64:67]
	v_mfma_f32_16x16x32_bf16 v[112:115], v[206:209], v[172:175], v[112:115]
	v_mfma_f32_16x16x32_bf16 v[108:111], v[214:217], v[172:175], v[108:111]
	v_mfma_f32_16x16x32_bf16 v[100:103], v[206:209], v[180:183], v[100:103]
	v_mfma_f32_16x16x32_bf16 v[92:95], v[214:217], v[180:183], v[92:95]
	v_mfma_f32_16x16x32_bf16 v[84:87], v[206:209], v[188:191], v[84:87]
	v_mfma_f32_16x16x32_bf16 v[76:79], v[214:217], v[188:191], v[76:79]
	v_mfma_f32_16x16x32_bf16 v[68:71], v[206:209], v[196:199], v[68:71]
	v_mfma_f32_16x16x32_bf16 v[64:67], v[214:217], v[196:199], v[64:67]
	s_barrier
	s_setprio 0
	s_mov_b32 m0, s52
	s_add_u32 s8, s36, 0x80
	s_addc_u32 s9, s37, 0
	ds_read_b128 v[168:171], v166 offset:49152
	ds_read_b128 v[172:175], v166 offset:50176
	ds_read_b128 v[176:179], v166 offset:51200
	ds_read_b128 v[180:183], v166 offset:52224
	ds_read_b128 v[184:187], v166 offset:53248
	ds_read_b128 v[188:191], v166 offset:54272
	ds_read_b128 v[192:195], v166 offset:55296
	ds_read_b128 v[196:199], v166 offset:56320
	global_load_lds_dwordx4 v134, s[8:9]
	s_mov_b32 m0, s53
	s_nop 0
	global_load_lds_dwordx4 v130, s[8:9]
	s_setprio 1
	s_barrier
	s_waitcnt lgkmcnt(0)
	v_mfma_f32_16x16x32_bf16 v[60:63], v[144:147], v[168:171], v[60:63]
	v_mfma_f32_16x16x32_bf16 v[56:59], v[152:155], v[168:171], v[56:59]
	v_mfma_f32_16x16x32_bf16 v[48:51], v[144:147], v[176:179], v[48:51]
	v_mfma_f32_16x16x32_bf16 v[40:43], v[152:155], v[176:179], v[40:43]
	v_mfma_f32_16x16x32_bf16 v[32:35], v[144:147], v[184:187], v[32:35]
	v_mfma_f32_16x16x32_bf16 v[24:27], v[152:155], v[184:187], v[24:27]
	v_mfma_f32_16x16x32_bf16 v[16:19], v[144:147], v[192:195], v[16:19]
	v_mfma_f32_16x16x32_bf16 v[8:11], v[152:155], v[192:195], v[8:11]
	v_mfma_f32_16x16x32_bf16 v[60:63], v[148:151], v[172:175], v[60:63]
	v_mfma_f32_16x16x32_bf16 v[56:59], v[156:159], v[172:175], v[56:59]
	v_mfma_f32_16x16x32_bf16 v[48:51], v[148:151], v[180:183], v[48:51]
	v_mfma_f32_16x16x32_bf16 v[40:43], v[156:159], v[180:183], v[40:43]
	v_mfma_f32_16x16x32_bf16 v[32:35], v[148:151], v[188:191], v[32:35]
	v_mfma_f32_16x16x32_bf16 v[24:27], v[156:159], v[188:191], v[24:27]
	v_mfma_f32_16x16x32_bf16 v[16:19], v[148:151], v[196:199], v[16:19]
	v_mfma_f32_16x16x32_bf16 v[8:11], v[156:159], v[196:199], v[8:11]
	s_barrier
; #define PG8_STAGE(bufoff, gbase, voff) do { _Pragma("unroll") for (int _i = 0; _i < 2; ++_i) \
;         __builtin_amdgcn_global_load_lds((const unsigned*)((const char*)(gbase) + (voff)[_i]), (LAS unsigned*)(lds + (bufoff) + ldsw + _i * 8192), 16, 0, 0); } while (0)
; #define PG8_LDA(dst, b, h) do { _Pragma("unroll") for (int m = 0; m < 4; ++m) _Pragma("unroll") for (int k = 0; k < 2; ++k) dst[m][k] = *(const LAS bf16x8*)(lds + PG8_SA(b, h) + aoff + m * 2048 + k * 1024); } while (0)
; #define PG8_LDB(dst, b, h) do { _Pragma("unroll") for (int n = 0; n < 2; ++n) _Pragma("unroll") for (int k = 0; k < 2; ++k) dst[n][k] = *(const LAS bf16x8*)(lds + PG8_SB(b, h) + boff + n * 2048 + k * 1024); } while (0)
; #define PG8_MMA(ai, bj, At, Bt) do { __builtin_amdgcn_s_setprio(1); _Pragma("unroll") for (int m = 0; m < 4; ++m) _Pragma("unroll") for (int n = 0; n < 2; ++n) _Pragma("unroll") for (int k = 0; k < 2; ++k) \
;         acc[ai][bj][m][n] = __builtin_amdgcn_mfma_f32_16x16x32_bf16(Bt[n][k], At[m][k], acc[ai][bj][m][n], 0, 0, 0); __builtin_amdgcn_s_setprio(0); } while (0)
; #define PG8_WAIT_V(n) asm volatile("s_waitcnt vmcnt(" #n ")" ::: "memory")
; #define PG8_WAIT_L(n) asm volatile("s_waitcnt lgkmcnt(" #n ")" ::: "memory")
; #define PG8_BAR __builtin_amdgcn_s_barrier()
; #define PG8_SCHED __builtin_amdgcn_sched_barrier(0)
; template <class Epi, class Sched>
; __device__ __forceinline__ void gemm_phase(LAS unsigned char* lds, const Gemm g, const Sched& S, const Epi& E) {
;     ...
;             PG8_LDB(B0, 0, 0); PG8_SCHED; PG8_LDA(At, 0, 0); PG8_STAGE(PG8_SA(1, 1), a1 + hstep, voffA);
;             PG8_WAIT_L(8); PG8_BAR; PG8_WAIT_L(0); PG8_MMA(0, 0, At, B0); PG8_BAR; PG8_SCHED;
;             PG8_LDB(B1, 0, 1); PG8_STAGE(PG8_SB(0, 0), b2, voffB);
;             PG8_BAR; PG8_WAIT_L(0); PG8_MMA(0, 1, At, B1); PG8_BAR;
;             PG8_LDA(At, 0, 1); PG8_STAGE(PG8_SA(0, 0), a2, voffA);
;             PG8_BAR; PG8_WAIT_L(0); PG8_MMA(1, 0, At, B0); PG8_BAR; PG8_SCHED;
;     ...
;             PG8_BAR; PG8_WAIT_L(0); PG8_MMA(1, 0, At, B0); PG8_BAR; PG8_SCHED;
;             PG8_STAGE(PG8_SB(1, 1), b3 + hstep, voffB);
;             PG8_WAIT_V(6); PG8_BAR; PG8_MMA(1, 1, At, B1); PG8_BAR;
;         }
	s_setprio 0
	s_add_u32 s16, s34, 0xb0080
	s_addc_u32 s17, s35, 0
	s_add_i32 s20, s21, s40
	s_mov_b32 m0, s20
	s_nop 0
	global_load_lds_dwordx4 v132, s[16:17]
	s_add_i32 m0, s20, 0x2000
	s_nop 0
	global_load_lds_dwordx4 v128, s[16:17]
	s_waitcnt vmcnt(8)
	s_setprio 1
	s_barrier
	v_mfma_f32_16x16x32_bf16 v[52:55], v[202:205], v[168:171], v[52:55]
	v_mfma_f32_16x16x32_bf16 v[44:47], v[210:213], v[168:171], v[44:47]
	v_mfma_f32_16x16x32_bf16 v[36:39], v[202:205], v[176:179], v[36:39]
	v_mfma_f32_16x16x32_bf16 v[28:31], v[210:213], v[176:179], v[28:31]
	v_mfma_f32_16x16x32_bf16 v[20:23], v[202:205], v[184:187], v[20:23]
	v_mfma_f32_16x16x32_bf16 v[12:15], v[210:213], v[184:187], v[12:15]
	v_mfma_f32_16x16x32_bf16 v[4:7], v[202:205], v[192:195], v[4:7]
	v_mfma_f32_16x16x32_bf16 v[0:3], v[210:213], v[192:195], v[0:3]
	v_mfma_f32_16x16x32_bf16 v[52:55], v[206:209], v[172:175], v[52:55]
	v_mfma_f32_16x16x32_bf16 v[44:47], v[214:217], v[172:175], v[44:47]
	v_mfma_f32_16x16x32_bf16 v[36:39], v[206:209], v[180:183], v[36:39]
	v_mfma_f32_16x16x32_bf16 v[28:31], v[214:217], v[180:183], v[28:31]
	v_mfma_f32_16x16x32_bf16 v[20:23], v[206:209], v[188:191], v[20:23]
	v_mfma_f32_16x16x32_bf16 v[12:15], v[214:217], v[188:191], v[12:15]
	v_mfma_f32_16x16x32_bf16 v[4:7], v[206:209], v[196:199], v[4:7]
	v_mfma_f32_16x16x32_bf16 v[0:3], v[214:217], v[196:199], v[0:3]
	s_barrier
	s_setprio 0
	s_add_i32 s68, s68, 2
	s_add_u32 s0, s0, 0x100
	s_addc_u32 s67, s67, 0
	s_cmp_gt_u32 s68, 41
	s_mov_b64 s[26:27], s[28:29]
.LBB0_305:
	ds_read_b128 v[144:147], v165
	ds_read_b128 v[148:151], v165 offset:1024
	ds_read_b128 v[152:155], v165 offset:2048
	ds_read_b128 v[156:159], v165 offset:3072
	s_add_u32 s28, s26, 0x100
	s_addc_u32 s29, s27, 0
	s_cmp_eq_u32 s68, 40
	s_cselect_b32 s37, s5, s29
	s_cselect_b32 s36, s4, s28
	s_cselect_b32 s35, s7, s67
	s_cselect_b32 s34, s6, s0
	v_lshl_add_u64 v[160:161], s[26:27], 0, v[136:137]
	s_add_i32 m0, s42, 0xc000
	ds_read_b128 v[168:171], v166
	ds_read_b128 v[172:175], v166 offset:1024
	ds_read_b128 v[176:179], v166 offset:2048
	ds_read_b128 v[180:183], v166 offset:3072
	ds_read_b128 v[184:187], v166 offset:4096
	ds_read_b128 v[188:191], v166 offset:5120
	ds_read_b128 v[192:195], v166 offset:6144
	ds_read_b128 v[196:199], v166 offset:7168
	global_load_lds_dwordx4 v[160:161], off
	v_lshl_add_u64 v[160:161], s[26:27], 0, v[138:139]
	s_add_i32 m0, s42, 0xe000
	s_nop 0
	global_load_lds_dwordx4 v[160:161], off
	s_waitcnt lgkmcnt(8)
	s_waitcnt vmcnt(8)
	s_setprio 1
	s_barrier
	s_waitcnt lgkmcnt(0)
	v_mfma_f32_16x16x32_bf16 v[124:127], v[144:147], v[168:171], v[124:127]
	v_mfma_f32_16x16x32_bf16 v[120:123], v[152:155], v[168:171], v[120:123]
	v_mfma_f32_16x16x32_bf16 v[116:119], v[144:147], v[176:179], v[116:119]
	v_mfma_f32_16x16x32_bf16 v[104:107], v[152:155], v[176:179], v[104:107]
	v_mfma_f32_16x16x32_bf16 v[96:99], v[144:147], v[184:187], v[96:99]
	v_mfma_f32_16x16x32_bf16 v[88:91], v[152:155], v[184:187], v[88:91]
	v_mfma_f32_16x16x32_bf16 v[80:83], v[144:147], v[192:195], v[80:83]
	v_mfma_f32_16x16x32_bf16 v[72:75], v[152:155], v[192:195], v[72:75]
	v_mfma_f32_16x16x32_bf16 v[124:127], v[148:151], v[172:175], v[124:127]
	v_mfma_f32_16x16x32_bf16 v[120:123], v[156:159], v[172:175], v[120:123]
	v_mfma_f32_16x16x32_bf16 v[116:119], v[148:151], v[180:183], v[116:119]
	v_mfma_f32_16x16x32_bf16 v[104:107], v[156:159], v[180:183], v[104:107]
	v_mfma_f32_16x16x32_bf16 v[96:99], v[148:151], v[188:191], v[96:99]
	v_mfma_f32_16x16x32_bf16 v[88:91], v[156:159], v[188:191], v[88:91]
	v_mfma_f32_16x16x32_bf16 v[80:83], v[148:151], v[196:199], v[80:83]
	v_mfma_f32_16x16x32_bf16 v[72:75], v[156:159], v[196:199], v[72:75]
	s_barrier
	s_setprio 0
	s_add_i32 s16, s58, s40
	s_mov_b32 m0, s16
	ds_read_b128 v[202:205], v167
	ds_read_b128 v[206:209], v167 offset:1024
	ds_read_b128 v[210:213], v167 offset:2048
	ds_read_b128 v[214:217], v167 offset:3072
	global_load_lds_dwordx4 v132, s[34:35]
	s_add_i32 m0, s16, 0x2000
	s_nop 0
	global_load_lds_dwordx4 v128, s[34:35]
	s_waitcnt vmcnt(8)
	s_setprio 1
	s_barrier
	s_waitcnt lgkmcnt(0)
	v_mfma_f32_16x16x32_bf16 v[112:115], v[202:205], v[168:171], v[112:115]
	v_mfma_f32_16x16x32_bf16 v[108:111], v[210:213], v[168:171], v[108:111]
	v_mfma_f32_16x16x32_bf16 v[100:103], v[202:205], v[176:179], v[100:103]
	v_mfma_f32_16x16x32_bf16 v[92:95], v[210:213], v[176:179], v[92:95]
	v_mfma_f32_16x16x32_bf16 v[84:87], v[202:205], v[184:187], v[84:87]
	v_mfma_f32_16x16x32_bf16 v[76:79], v[210:213], v[184:187], v[76:79]
	v_mfma_f32_16x16x32_bf16 v[68:71], v[202:205], v[192:195], v[68:71]
	v_mfma_f32_16x16x32_bf16 v[64:67], v[210:213], v[192:195], v[64:67]
	v_mfma_f32_16x16x32_bf16 v[112:115], v[206:209], v[172:175], v[112:115]
	v_mfma_f32_16x16x32_bf16 v[108:111], v[214:217], v[172:175], v[108:111]
	v_mfma_f32_16x16x32_bf16 v[100:103], v[206:209], v[180:183], v[100:103]
	v_mfma_f32_16x16x32_bf16 v[92:95], v[214:217], v[180:183], v[92:95]
	v_mfma_f32_16x16x32_bf16 v[84:87], v[206:209], v[188:191], v[84:87]
	v_mfma_f32_16x16x32_bf16 v[76:79], v[214:217], v[188:191], v[76:79]
	v_mfma_f32_16x16x32_bf16 v[68:71], v[206:209], v[196:199], v[68:71]
	v_mfma_f32_16x16x32_bf16 v[64:67], v[214:217], v[196:199], v[64:67]
	s_barrier
	s_setprio 0
	s_mov_b32 m0, s42
	ds_read_b128 v[168:171], v166 offset:16384
	ds_read_b128 v[172:175], v166 offset:17408
	ds_read_b128 v[176:179], v166 offset:18432
	ds_read_b128 v[180:183], v166 offset:19456
	ds_read_b128 v[184:187], v166 offset:20480
	ds_read_b128 v[188:191], v166 offset:21504
	ds_read_b128 v[192:195], v166 offset:22528
	ds_read_b128 v[196:199], v166 offset:23552
	global_load_lds_dwordx4 v134, s[36:37]
	s_mov_b32 m0, s43
	s_nop 0
	global_load_lds_dwordx4 v130, s[36:37]
	s_setprio 1
	s_barrier
; #define PG8_STAGE(bufoff, gbase, voff) do { _Pragma("unroll") for (int _i = 0; _i < 2; ++_i) \
;         __builtin_amdgcn_global_load_lds((const unsigned*)((const char*)(gbase) + (voff)[_i]), (LAS unsigned*)(lds + (bufoff) + ldsw + _i * 8192), 16, 0, 0); } while (0)
; #define PG8_LDA(dst, b, h) do { _Pragma("unroll") for (int m = 0; m < 4; ++m) _Pragma("unroll") for (int k = 0; k < 2; ++k) dst[m][k] = *(const LAS bf16x8*)(lds + PG8_SA(b, h) + aoff + m * 2048 + k * 1024); } while (0)
; #define PG8_LDB(dst, b, h) do { _Pragma("unroll") for (int n = 0; n < 2; ++n) _Pragma("unroll") for (int k = 0; k < 2; ++k) dst[n][k] = *(const LAS bf16x8*)(lds + PG8_SB(b, h) + boff + n * 2048 + k * 1024); } while (0)
; #define PG8_MMA(ai, bj, At, Bt) do { __builtin_amdgcn_s_setprio(1); _Pragma("unroll") for (int m = 0; m < 4; ++m) _Pragma("unroll") for (int n = 0; n < 2; ++n) _Pragma("unroll") for (int k = 0; k < 2; ++k) \
;         acc[ai][bj][m][n] = __builtin_amdgcn_mfma_f32_16x16x32_bf16(Bt[n][k], At[m][k], acc[ai][bj][m][n], 0, 0, 0); __builtin_amdgcn_s_setprio(0); } while (0)
; #define PG8_WAIT_V(n) asm volatile("s_waitcnt vmcnt(" #n ")" ::: "memory")
; #define PG8_WAIT_L(n) asm volatile("s_waitcnt lgkmcnt(" #n ")" ::: "memory")
; #define PG8_BAR __builtin_amdgcn_s_barrier()
; #define PG8_SCHED __builtin_amdgcn_sched_barrier(0)
; template <class Epi, class Sched>
; __device__ __forceinline__ void gemm_phase(LAS unsigned char* lds, const Gemm g, const Sched& S, const Epi& E) {
;     ...
;             PG8_BAR; PG8_WAIT_L(0); PG8_MMA(1, 0, At, B0); PG8_BAR; PG8_SCHED;
;             PG8_STAGE(PG8_SB(0, 1), b2 + hstep, voffB);
;             PG8_WAIT_V(6); PG8_BAR; PG8_MMA(1, 1, At, B1); PG8_BAR;
;             PG8_LDB(B0, 1, 0); PG8_SCHED; PG8_LDA(At, 1, 0); PG8_STAGE(PG8_SA(0, 1), a2 + hstep, voffA);
;             PG8_WAIT_L(8); PG8_BAR; PG8_WAIT_L(0); PG8_MMA(0, 0, At, B0); PG8_BAR; PG8_SCHED;
	s_waitcnt lgkmcnt(0)
	v_mfma_f32_16x16x32_bf16 v[60:63], v[144:147], v[168:171], v[60:63]
	v_mfma_f32_16x16x32_bf16 v[56:59], v[152:155], v[168:171], v[56:59]
	v_mfma_f32_16x16x32_bf16 v[48:51], v[144:147], v[176:179], v[48:51]
	v_mfma_f32_16x16x32_bf16 v[40:43], v[152:155], v[176:179], v[40:43]
	v_mfma_f32_16x16x32_bf16 v[32:35], v[144:147], v[184:187], v[32:35]
	v_mfma_f32_16x16x32_bf16 v[24:27], v[152:155], v[184:187], v[24:27]
	v_mfma_f32_16x16x32_bf16 v[16:19], v[144:147], v[192:195], v[16:19]
	v_mfma_f32_16x16x32_bf16 v[8:11], v[152:155], v[192:195], v[8:11]
	v_mfma_f32_16x16x32_bf16 v[60:63], v[148:151], v[172:175], v[60:63]
	v_mfma_f32_16x16x32_bf16 v[56:59], v[156:159], v[172:175], v[56:59]
	v_mfma_f32_16x16x32_bf16 v[48:51], v[148:151], v[180:183], v[48:51]
	v_mfma_f32_16x16x32_bf16 v[40:43], v[156:159], v[180:183], v[40:43]
	v_mfma_f32_16x16x32_bf16 v[32:35], v[148:151], v[188:191], v[32:35]
	v_mfma_f32_16x16x32_bf16 v[24:27], v[156:159], v[188:191], v[24:27]
	v_mfma_f32_16x16x32_bf16 v[16:19], v[148:151], v[196:199], v[16:19]
	v_mfma_f32_16x16x32_bf16 v[8:11], v[156:159], v[196:199], v[8:11]
	s_barrier
	s_setprio 0
	s_add_u32 s16, s34, 0xb0000
	s_addc_u32 s17, s35, 0
	s_add_i32 s20, s59, s40
	s_mov_b32 m0, s20
	s_nop 0
	global_load_lds_dwordx4 v132, s[16:17]
	s_add_i32 m0, s20, 0x2000
	s_nop 0
	global_load_lds_dwordx4 v128, s[16:17]
	s_add_u32 s16, s36, 0xb0000
	s_addc_u32 s17, s37, 0
	s_mov_b32 m0, s44
	s_nop 0
	global_load_lds_dwordx4 v134, s[16:17]
	s_mov_b32 m0, s45
	s_nop 0
	global_load_lds_dwordx4 v130, s[16:17]
	s_waitcnt vmcnt(10)
	s_setprio 1
	s_barrier
	v_mfma_f32_16x16x32_bf16 v[52:55], v[202:205], v[168:171], v[52:55]
	v_mfma_f32_16x16x32_bf16 v[44:47], v[210:213], v[168:171], v[44:47]
	v_mfma_f32_16x16x32_bf16 v[36:39], v[202:205], v[176:179], v[36:39]
	v_mfma_f32_16x16x32_bf16 v[28:31], v[210:213], v[176:179], v[28:31]
	v_mfma_f32_16x16x32_bf16 v[20:23], v[202:205], v[184:187], v[20:23]
	v_mfma_f32_16x16x32_bf16 v[12:15], v[210:213], v[184:187], v[12:15]
	v_mfma_f32_16x16x32_bf16 v[4:7], v[202:205], v[192:195], v[4:7]
	v_mfma_f32_16x16x32_bf16 v[0:3], v[210:213], v[192:195], v[0:3]
	v_mfma_f32_16x16x32_bf16 v[52:55], v[206:209], v[172:175], v[52:55]
	v_mfma_f32_16x16x32_bf16 v[44:47], v[214:217], v[172:175], v[44:47]
	v_mfma_f32_16x16x32_bf16 v[36:39], v[206:209], v[180:183], v[36:39]
	v_mfma_f32_16x16x32_bf16 v[28:31], v[214:217], v[180:183], v[28:31]
	v_mfma_f32_16x16x32_bf16 v[20:23], v[206:209], v[188:191], v[20:23]
	v_mfma_f32_16x16x32_bf16 v[12:15], v[214:217], v[188:191], v[12:15]
	v_mfma_f32_16x16x32_bf16 v[4:7], v[206:209], v[196:199], v[4:7]
	v_mfma_f32_16x16x32_bf16 v[0:3], v[214:217], v[196:199], v[0:3]
	s_barrier
	s_setprio 0
	s_add_i32 s20, 0, 0x18000
	ds_read_b128 v[144:147], v167 offset:16384
	ds_read_b128 v[148:151], v167 offset:17408
	ds_read_b128 v[152:155], v167 offset:18432
	ds_read_b128 v[156:159], v167 offset:19456
	ds_read_b128 v[168:171], v166 offset:32768
	ds_read_b128 v[172:175], v166 offset:33792
	ds_read_b128 v[176:179], v166 offset:34816
	ds_read_b128 v[180:183], v166 offset:35840
	ds_read_b128 v[184:187], v166 offset:36864
	ds_read_b128 v[188:191], v166 offset:37888
	ds_read_b128 v[192:195], v166 offset:38912
	ds_read_b128 v[196:199], v166 offset:39936
	s_waitcnt lgkmcnt(8)
	s_waitcnt vmcnt(8)
	s_setprio 1
	s_barrier
	s_waitcnt lgkmcnt(0)
	v_mfma_f32_16x16x32_bf16 v[124:127], v[144:147], v[168:171], v[124:127]
	v_mfma_f32_16x16x32_bf16 v[120:123], v[152:155], v[168:171], v[120:123]
	v_mfma_f32_16x16x32_bf16 v[116:119], v[144:147], v[176:179], v[116:119]
	v_mfma_f32_16x16x32_bf16 v[104:107], v[152:155], v[176:179], v[104:107]
	v_mfma_f32_16x16x32_bf16 v[96:99], v[144:147], v[184:187], v[96:99]
	v_mfma_f32_16x16x32_bf16 v[88:91], v[152:155], v[184:187], v[88:91]
	v_mfma_f32_16x16x32_bf16 v[80:83], v[144:147], v[192:195], v[80:83]
	v_mfma_f32_16x16x32_bf16 v[72:75], v[152:155], v[192:195], v[72:75]
	v_mfma_f32_16x16x32_bf16 v[124:127], v[148:151], v[172:175], v[124:127]
	v_mfma_f32_16x16x32_bf16 v[120:123], v[156:159], v[172:175], v[120:123]
	v_mfma_f32_16x16x32_bf16 v[116:119], v[148:151], v[180:183], v[116:119]
	v_mfma_f32_16x16x32_bf16 v[104:107], v[156:159], v[180:183], v[104:107]
	v_mfma_f32_16x16x32_bf16 v[96:99], v[148:151], v[188:191], v[96:99]
	v_mfma_f32_16x16x32_bf16 v[88:91], v[156:159], v[188:191], v[88:91]
	v_mfma_f32_16x16x32_bf16 v[80:83], v[148:151], v[196:199], v[80:83]
	v_mfma_f32_16x16x32_bf16 v[72:75], v[156:159], v[196:199], v[72:75]
	s_barrier
	s_setprio 0
	s_add_i32 s21, 0, 0x1c000
	s_add_i32 s16, s20, s40
	v_add_u32_e32 v214, s21, v164
	s_add_u32 s8, s34, 0x80
	s_addc_u32 s9, s35, 0
	s_mov_b32 m0, s16
	ds_read_b128 v[202:205], v214
	ds_read_b128 v[206:209], v214 offset:1024
	ds_read_b128 v[210:213], v214 offset:2048
	ds_read_b128 v[214:217], v214 offset:3072
	global_load_lds_dwordx4 v132, s[8:9]
	s_add_i32 m0, s16, 0x2000
	s_nop 0
	global_load_lds_dwordx4 v128, s[8:9]
	s_waitcnt vmcnt(8)
	s_setprio 1
	s_barrier
; #define PG8_STAGE(bufoff, gbase, voff) do { _Pragma("unroll") for (int _i = 0; _i < 2; ++_i) \
;         __builtin_amdgcn_global_load_lds((const unsigned*)((const char*)(gbase) + (voff)[_i]), (LAS unsigned*)(lds + (bufoff) + ldsw + _i * 8192), 16, 0, 0); } while (0)
; #define PG8_LDA(dst, b, h) do { _Pragma("unroll") for (int m = 0; m < 4; ++m) _Pragma("unroll") for (int k = 0; k < 2; ++k) dst[m][k] = *(const LAS bf16x8*)(lds + PG8_SA(b, h) + aoff + m * 2048 + k * 1024); } while (0)
; #define PG8_LDB(dst, b, h) do { _Pragma("unroll") for (int n = 0; n < 2; ++n) _Pragma("unroll") for (int k = 0; k < 2; ++k) dst[n][k] = *(const LAS bf16x8*)(lds + PG8_SB(b, h) + boff + n * 2048 + k * 1024); } while (0)
; #define PG8_MMA(ai, bj, At, Bt) do { __builtin_amdgcn_s_setprio(1); _Pragma("unroll") for (int m = 0; m < 4; ++m) _Pragma("unroll") for (int n = 0; n < 2; ++n) _Pragma("unroll") for (int k = 0; k < 2; ++k) \
;         acc[ai][bj][m][n] = __builtin_amdgcn_mfma_f32_16x16x32_bf16(Bt[n][k], At[m][k], acc[ai][bj][m][n], 0, 0, 0); __builtin_amdgcn_s_setprio(0); } while (0)
; #define PG8_WAIT_V(n) asm volatile("s_waitcnt vmcnt(" #n ")" ::: "memory")
; #define PG8_WAIT_L(n) asm volatile("s_waitcnt lgkmcnt(" #n ")" ::: "memory")
; #define PG8_BAR __builtin_amdgcn_s_barrier()
; #define PG8_SCHED __builtin_amdgcn_sched_barrier(0)
; template <class Epi, class Sched>
; __device__ __forceinline__ void gemm_phase(LAS unsigned char* lds, const Gemm g, const Sched& S, const Epi& E) {
;     ...
;             PG8_WAIT_L(8); PG8_BAR; PG8_WAIT_L(0); PG8_MMA(0, 0, At, B0); PG8_BAR; PG8_SCHED;
;             PG8_LDB(B1, 1, 1); PG8_STAGE(PG8_SB(1, 0), b3, voffB);
;             PG8_BAR; PG8_WAIT_L(0); PG8_MMA(0, 1, At, B1); PG8_BAR;
;             PG8_LDA(At, 1, 1); PG8_STAGE(PG8_SA(1, 0), a3, voffA);
;             PG8_BAR; PG8_WAIT_L(0); PG8_MMA(1, 0, At, B0); PG8_BAR; PG8_SCHED;
;             PG8_STAGE(PG8_SB(1, 1), b3 + hstep, voffB);
;             PG8_WAIT_V(6); PG8_BAR; PG8_MMA(1, 1, At, B1); PG8_BAR;
;         }
;         E(acc, cur, wr, wc, fr, fq);
	s_waitcnt lgkmcnt(0)
	v_mfma_f32_16x16x32_bf16 v[112:115], v[202:205], v[168:171], v[112:115]
	v_mfma_f32_16x16x32_bf16 v[108:111], v[210:213], v[168:171], v[108:111]
	v_mfma_f32_16x16x32_bf16 v[100:103], v[202:205], v[176:179], v[100:103]
	v_mfma_f32_16x16x32_bf16 v[92:95], v[210:213], v[176:179], v[92:95]
	v_mfma_f32_16x16x32_bf16 v[84:87], v[202:205], v[184:187], v[84:87]
	v_mfma_f32_16x16x32_bf16 v[76:79], v[210:213], v[184:187], v[76:79]
	v_mfma_f32_16x16x32_bf16 v[68:71], v[202:205], v[192:195], v[68:71]
	v_mfma_f32_16x16x32_bf16 v[64:67], v[210:213], v[192:195], v[64:67]
	v_mfma_f32_16x16x32_bf16 v[112:115], v[206:209], v[172:175], v[112:115]
	v_mfma_f32_16x16x32_bf16 v[108:111], v[214:217], v[172:175], v[108:111]
	v_mfma_f32_16x16x32_bf16 v[100:103], v[206:209], v[180:183], v[100:103]
	v_mfma_f32_16x16x32_bf16 v[92:95], v[214:217], v[180:183], v[92:95]
	v_mfma_f32_16x16x32_bf16 v[84:87], v[206:209], v[188:191], v[84:87]
	v_mfma_f32_16x16x32_bf16 v[76:79], v[214:217], v[188:191], v[76:79]
	v_mfma_f32_16x16x32_bf16 v[68:71], v[206:209], v[196:199], v[68:71]
	v_mfma_f32_16x16x32_bf16 v[64:67], v[214:217], v[196:199], v[64:67]
	s_barrier
	s_setprio 0
	s_mov_b32 m0, s52
	s_add_u32 s8, s36, 0x80
	s_addc_u32 s9, s37, 0
	ds_read_b128 v[168:171], v166 offset:49152
	ds_read_b128 v[172:175], v166 offset:50176
	ds_read_b128 v[176:179], v166 offset:51200
	ds_read_b128 v[180:183], v166 offset:52224
	ds_read_b128 v[184:187], v166 offset:53248
	ds_read_b128 v[188:191], v166 offset:54272
	ds_read_b128 v[192:195], v166 offset:55296
	ds_read_b128 v[196:199], v166 offset:56320
	global_load_lds_dwordx4 v134, s[8:9]
	s_mov_b32 m0, s53
	s_nop 0
	global_load_lds_dwordx4 v130, s[8:9]
	s_setprio 1
	s_barrier
	s_waitcnt lgkmcnt(0)
	v_mfma_f32_16x16x32_bf16 v[60:63], v[144:147], v[168:171], v[60:63]
	v_mfma_f32_16x16x32_bf16 v[56:59], v[152:155], v[168:171], v[56:59]
	v_mfma_f32_16x16x32_bf16 v[48:51], v[144:147], v[176:179], v[48:51]
	v_mfma_f32_16x16x32_bf16 v[40:43], v[152:155], v[176:179], v[40:43]
	v_mfma_f32_16x16x32_bf16 v[32:35], v[144:147], v[184:187], v[32:35]
	v_mfma_f32_16x16x32_bf16 v[24:27], v[152:155], v[184:187], v[24:27]
	v_mfma_f32_16x16x32_bf16 v[16:19], v[144:147], v[192:195], v[16:19]
	v_mfma_f32_16x16x32_bf16 v[8:11], v[152:155], v[192:195], v[8:11]
	v_mfma_f32_16x16x32_bf16 v[60:63], v[148:151], v[172:175], v[60:63]
	v_mfma_f32_16x16x32_bf16 v[56:59], v[156:159], v[172:175], v[56:59]
	v_mfma_f32_16x16x32_bf16 v[48:51], v[148:151], v[180:183], v[48:51]
	v_mfma_f32_16x16x32_bf16 v[40:43], v[156:159], v[180:183], v[40:43]
	v_mfma_f32_16x16x32_bf16 v[32:35], v[148:151], v[188:191], v[32:35]
	v_mfma_f32_16x16x32_bf16 v[24:27], v[156:159], v[188:191], v[24:27]
	v_mfma_f32_16x16x32_bf16 v[16:19], v[148:151], v[196:199], v[16:19]
	v_mfma_f32_16x16x32_bf16 v[8:11], v[156:159], v[196:199], v[8:11]
	s_barrier
	s_setprio 0
	s_add_u32 s16, s34, 0xb0080
	s_addc_u32 s17, s35, 0
	s_add_i32 s20, s21, s40
	s_mov_b32 m0, s20
	s_nop 0
	global_load_lds_dwordx4 v132, s[16:17]
	s_add_i32 m0, s20, 0x2000
	s_nop 0
	global_load_lds_dwordx4 v128, s[16:17]
	s_waitcnt vmcnt(8)
	s_setprio 1
	s_barrier
	v_mfma_f32_16x16x32_bf16 v[52:55], v[202:205], v[168:171], v[52:55]
	v_mfma_f32_16x16x32_bf16 v[44:47], v[210:213], v[168:171], v[44:47]
	v_mfma_f32_16x16x32_bf16 v[36:39], v[202:205], v[176:179], v[36:39]
	v_mfma_f32_16x16x32_bf16 v[28:31], v[210:213], v[176:179], v[28:31]
	v_mfma_f32_16x16x32_bf16 v[20:23], v[202:205], v[184:187], v[20:23]
	v_mfma_f32_16x16x32_bf16 v[12:15], v[210:213], v[184:187], v[12:15]
	v_mfma_f32_16x16x32_bf16 v[4:7], v[202:205], v[192:195], v[4:7]
	v_mfma_f32_16x16x32_bf16 v[0:3], v[210:213], v[192:195], v[0:3]
	v_mfma_f32_16x16x32_bf16 v[52:55], v[206:209], v[172:175], v[52:55]
	v_mfma_f32_16x16x32_bf16 v[44:47], v[214:217], v[172:175], v[44:47]
	v_mfma_f32_16x16x32_bf16 v[36:39], v[206:209], v[180:183], v[36:39]
	v_mfma_f32_16x16x32_bf16 v[28:31], v[214:217], v[180:183], v[28:31]
	v_mfma_f32_16x16x32_bf16 v[20:23], v[206:209], v[188:191], v[20:23]
	v_mfma_f32_16x16x32_bf16 v[12:15], v[214:217], v[188:191], v[12:15]
	v_mfma_f32_16x16x32_bf16 v[4:7], v[206:209], v[196:199], v[4:7]
	v_mfma_f32_16x16x32_bf16 v[0:3], v[214:217], v[196:199], v[0:3]
	s_barrier
	s_setprio 0
	s_add_i32 s68, s68, 2
	s_add_u32 s0, s0, 0x100
	s_addc_u32 s67, s67, 0
	s_cmp_gt_u32 s68, 41
	s_mov_b64 s[26:27], s[28:29]
	s_cbranch_scc0 .LBB0_305
	s_lshl_b32 s0, s66, 8
	v_mov_b32_e32 v145, v163
	v_mov_b32_e32 v144, v162
	s_cmpk_lt_i32 s66, 0x100
	s_cbranch_scc0 .LBB0_308
	s_ashr_i32 s29, s0, 31
	s_mov_b32 s28, s0
	s_lshl_b64 s[16:17], s[28:29], 12
	v_readlane_b32 s80, v254, 23
	v_readlane_b32 s81, v254, 24
	s_add_u32 s26, s80, s16
	v_readlane_b32 s82, v254, 25
	v_readlane_b32 s83, v254, 26
	v_readlane_b32 s84, v254, 27
	v_readlane_b32 s85, v254, 28
	v_readlane_b32 s86, v254, 29
	v_readlane_b32 s87, v254, 30
	v_readlane_b32 s88, v254, 31
	v_readlane_b32 s89, v254, 32
	v_readlane_b32 s90, v254, 33
	v_readlane_b32 s91, v254, 34
	v_readlane_b32 s92, v254, 35
	v_readlane_b32 s93, v254, 36
	v_readlane_b32 s94, v254, 37
	v_readlane_b32 s95, v254, 38
	s_addc_u32 s27, s81, s17
	s_cbranch_execnz .LBB0_297
	s_branch .LBB0_296

; #define PG8_STAGE(bufoff, gbase, voff) do { _Pragma("unroll") for (int _i = 0; _i < 2; ++_i) \
;         __builtin_amdgcn_global_load_lds((const unsigned*)((const char*)(gbase) + (voff)[_i]), (LAS unsigned*)(lds + (bufoff) + ldsw + _i * 8192), 16, 0, 0); } while (0)
; #define PG8_LDA(dst, b, h) do { _Pragma("unroll") for (int m = 0; m < 4; ++m) _Pragma("unroll") for (int k = 0; k < 2; ++k) dst[m][k] = *(const LAS bf16x8*)(lds + PG8_SA(b, h) + aoff + m * 2048 + k * 1024); } while (0)
; #define PG8_LDB(dst, b, h) do { _Pragma("unroll") for (int n = 0; n < 2; ++n) _Pragma("unroll") for (int k = 0; k < 2; ++k) dst[n][k] = *(const LAS bf16x8*)(lds + PG8_SB(b, h) + boff + n * 2048 + k * 1024); } while (0)
; #define PG8_MMA(ai, bj, At, Bt) do { __builtin_amdgcn_s_setprio(1); _Pragma("unroll") for (int m = 0; m < 4; ++m) _Pragma("unroll") for (int n = 0; n < 2; ++n) _Pragma("unroll") for (int k = 0; k < 2; ++k) \
;         acc[ai][bj][m][n] = __builtin_amdgcn_mfma_f32_16x16x32_bf16(Bt[n][k], At[m][k], acc[ai][bj][m][n], 0, 0, 0); __builtin_amdgcn_s_setprio(0); } while (0)
; #define PG8_WAIT_L(n) asm volatile("s_waitcnt lgkmcnt(" #n ")" ::: "memory")
; template <class Epi, class Sched>
; __device__ __forceinline__ void gemm_phase(LAS unsigned char* lds, const Gemm g, const Sched& S, const Epi& E) {
;     ...
;         const bool has_next = S.next(ui + 1, nxt);
;         const char* nA = has_next ? (const char*)g.A + (size_t)nxt.pm * tstep : cA; const char* nB = has_next ? (const char*)g.Bt + (size_t)nxt.pn * tstep : cB;
;         for (int t = 0; t < nt; t += 2) {
;             const bool last = (t == nt - 2);
;             const char* a1 = cA + (size_t)(t + 1) * kstep;
;             const char* a2 = last ? nA : cA + (size_t)(t + 2) * kstep; const char* b2 = last ? nB : cB + (size_t)(t + 2) * kstep;
;             const char* a3 = a2 + kstep; const char* b3 = b2 + kstep;
;             PG8_LDB(B0, 0, 0); PG8_SCHED; PG8_LDA(At, 0, 0); PG8_STAGE(PG8_SA(1, 1), a1 + hstep, voffA);
;             PG8_WAIT_L(8); PG8_BAR; PG8_WAIT_L(0); PG8_MMA(0, 0, At, B0); PG8_BAR; PG8_SCHED;
;             PG8_LDB(B1, 0, 1); PG8_STAGE(PG8_SB(0, 0), b2, voffB);
;             PG8_BAR; PG8_WAIT_L(0); PG8_MMA(0, 1, At, B1); PG8_BAR;
;             PG8_LDA(At, 0, 1); PG8_STAGE(PG8_SA(0, 0), a2, voffA);
;             PG8_BAR; PG8_WAIT_L(0); PG8_MMA(1, 0, At, B0); PG8_BAR; PG8_SCHED;
.LBB0_577:
	s_ashr_i32 s21, s20, 31
	v_cmp_lt_i64_e32 vcc, s[22:23], v[156:157]
	s_lshl_b64 s[22:23], s[20:21], 19
	s_add_u32 s22, s96, s22
	s_addc_u32 s23, s97, s23
	s_and_b64 s[24:25], vcc, exec
	s_cselect_b32 s5, s23, s7
	s_cselect_b32 s21, s22, s6
	s_ashr_i32 s19, s18, 31
	s_lshl_b64 s[24:25], s[18:19], 19
	s_add_u32 s24, s31, s24
	s_addc_u32 s25, s33, s25
	s_and_b64 s[28:29], vcc, exec
	s_cselect_b32 s19, s25, s27
	s_cselect_b32 s53, s24, s26
	s_add_u32 s6, s6, 0x40080
	s_addc_u32 s7, s7, 0
	s_add_u32 s54, s26, 0x100
	s_addc_u32 s55, s27, 0
	s_mov_b32 s56, -2
	s_waitcnt lgkmcnt(0)
	ds_read_b128 v[128:131], v167
	ds_read_b128 v[132:135], v167 offset:1024
	ds_read_b128 v[136:139], v167 offset:2048
	ds_read_b128 v[160:163], v167 offset:3072
	s_add_u32 s26, s6, 0xfffc0080
	s_addc_u32 s27, s7, -1
	s_cmp_eq_u32 s56, 12
	s_cselect_b32 s29, s5, s27
	s_cselect_b32 s28, s21, s26
	s_cselect_b32 s27, s19, s55
	s_cselect_b32 s26, s53, s54
	s_add_i32 m0, s37, 0xc000
	ds_read_b128 v[170:173], v168
	ds_read_b128 v[174:177], v168 offset:1024
	ds_read_b128 v[178:181], v168 offset:2048
	ds_read_b128 v[182:185], v168 offset:3072
	ds_read_b128 v[186:189], v168 offset:4096
	ds_read_b128 v[190:193], v168 offset:5120
	ds_read_b128 v[194:197], v168 offset:6144
	ds_read_b128 v[202:205], v168 offset:7168
	global_load_lds_dwordx4 v152, s[6:7]
	s_add_i32 m0, s37, 0xe000
	s_nop 0
	global_load_lds_dwordx4 v154, s[6:7]
	s_waitcnt lgkmcnt(8)
	s_waitcnt vmcnt(8)
	s_setprio 1
	s_barrier
	s_waitcnt lgkmcnt(0)
	v_mfma_f32_16x16x32_bf16 v[124:127], v[128:131], v[170:173], 0
	v_mfma_f32_16x16x32_bf16 v[120:123], v[136:139], v[170:173], 0
	v_mfma_f32_16x16x32_bf16 v[108:111], v[128:131], v[178:181], 0
	v_mfma_f32_16x16x32_bf16 v[104:107], v[136:139], v[178:181], 0
	v_mfma_f32_16x16x32_bf16 v[92:95], v[128:131], v[186:189], 0
	v_mfma_f32_16x16x32_bf16 v[88:91], v[136:139], v[186:189], 0
	v_mfma_f32_16x16x32_bf16 v[76:79], v[128:131], v[194:197], 0
	v_mfma_f32_16x16x32_bf16 v[72:75], v[136:139], v[194:197], 0
	v_mfma_f32_16x16x32_bf16 v[124:127], v[132:135], v[174:177], v[124:127]
	v_mfma_f32_16x16x32_bf16 v[120:123], v[160:163], v[174:177], v[120:123]
	v_mfma_f32_16x16x32_bf16 v[108:111], v[132:135], v[182:185], v[108:111]
	v_mfma_f32_16x16x32_bf16 v[104:107], v[160:163], v[182:185], v[104:107]
	v_mfma_f32_16x16x32_bf16 v[92:95], v[132:135], v[190:193], v[92:95]
	v_mfma_f32_16x16x32_bf16 v[88:91], v[160:163], v[190:193], v[88:91]
	v_mfma_f32_16x16x32_bf16 v[76:79], v[132:135], v[202:205], v[76:79]
	v_mfma_f32_16x16x32_bf16 v[72:75], v[160:163], v[202:205], v[72:75]
	s_barrier
	s_setprio 0
	s_add_i32 s57, s48, s34
	s_mov_b32 m0, s57
	ds_read_b128 v[206:209], v169
	ds_read_b128 v[210:213], v169 offset:1024
	ds_read_b128 v[214:217], v169 offset:2048
	ds_read_b128 v[218:221], v169 offset:3072
	global_load_lds_dwordx4 v146, s[26:27]
	s_add_i32 m0, s57, 0x2000
	s_nop 0
	global_load_lds_dwordx4 v142, s[26:27]
	s_waitcnt vmcnt(8)
	s_setprio 1
	s_barrier
	s_waitcnt lgkmcnt(0)
	v_mfma_f32_16x16x32_bf16 v[116:119], v[206:209], v[170:173], 0
	v_mfma_f32_16x16x32_bf16 v[112:115], v[214:217], v[170:173], 0
	v_mfma_f32_16x16x32_bf16 v[100:103], v[206:209], v[178:181], 0
	v_mfma_f32_16x16x32_bf16 v[96:99], v[214:217], v[178:181], 0
	v_mfma_f32_16x16x32_bf16 v[84:87], v[206:209], v[186:189], 0
	v_mfma_f32_16x16x32_bf16 v[80:83], v[214:217], v[186:189], 0
	v_mfma_f32_16x16x32_bf16 v[68:71], v[206:209], v[194:197], 0
	v_mfma_f32_16x16x32_bf16 v[64:67], v[214:217], v[194:197], 0
	v_mfma_f32_16x16x32_bf16 v[116:119], v[210:213], v[174:177], v[116:119]
	v_mfma_f32_16x16x32_bf16 v[112:115], v[218:221], v[174:177], v[112:115]
	v_mfma_f32_16x16x32_bf16 v[100:103], v[210:213], v[182:185], v[100:103]
	v_mfma_f32_16x16x32_bf16 v[96:99], v[218:221], v[182:185], v[96:99]
	v_mfma_f32_16x16x32_bf16 v[84:87], v[210:213], v[190:193], v[84:87]
	v_mfma_f32_16x16x32_bf16 v[80:83], v[218:221], v[190:193], v[80:83]
	v_mfma_f32_16x16x32_bf16 v[68:71], v[210:213], v[202:205], v[68:71]
	v_mfma_f32_16x16x32_bf16 v[64:67], v[218:221], v[202:205], v[64:67]
	s_barrier
	s_setprio 0
	s_mov_b32 m0, s37
	v_lshl_add_u64 v[222:223], s[28:29], 0, v[148:149]
	ds_read_b128 v[170:173], v168 offset:16384
	ds_read_b128 v[174:177], v168 offset:17408
	ds_read_b128 v[178:181], v168 offset:18432
	ds_read_b128 v[182:185], v168 offset:19456
	ds_read_b128 v[186:189], v168 offset:20480
	ds_read_b128 v[190:193], v168 offset:21504
	ds_read_b128 v[194:197], v168 offset:22528
	ds_read_b128 v[202:205], v168 offset:23552
	global_load_lds_dwordx4 v148, s[28:29]
	v_lshl_add_u64 v[224:225], s[28:29], 0, v[144:145]
	s_mov_b32 m0, s38
	s_nop 0
	global_load_lds_dwordx4 v144, s[28:29]
	s_setprio 1
	s_barrier
	s_waitcnt lgkmcnt(0)
	v_mfma_f32_16x16x32_bf16 v[60:63], v[128:131], v[170:173], 0
	v_mfma_f32_16x16x32_bf16 v[56:59], v[136:139], v[170:173], 0
	v_mfma_f32_16x16x32_bf16 v[44:47], v[128:131], v[178:181], 0
	v_mfma_f32_16x16x32_bf16 v[40:43], v[136:139], v[178:181], 0
	v_mfma_f32_16x16x32_bf16 v[28:31], v[128:131], v[186:189], 0
	v_mfma_f32_16x16x32_bf16 v[24:27], v[136:139], v[186:189], 0
	v_mfma_f32_16x16x32_bf16 v[12:15], v[128:131], v[194:197], 0
	v_mfma_f32_16x16x32_bf16 v[8:11], v[136:139], v[194:197], 0
	v_mfma_f32_16x16x32_bf16 v[60:63], v[132:135], v[174:177], v[60:63]
	v_mfma_f32_16x16x32_bf16 v[56:59], v[160:163], v[174:177], v[56:59]
	v_mfma_f32_16x16x32_bf16 v[44:47], v[132:135], v[182:185], v[44:47]
	v_mfma_f32_16x16x32_bf16 v[40:43], v[160:163], v[182:185], v[40:43]
	v_mfma_f32_16x16x32_bf16 v[28:31], v[132:135], v[190:193], v[28:31]
	v_mfma_f32_16x16x32_bf16 v[24:27], v[160:163], v[190:193], v[24:27]
	v_mfma_f32_16x16x32_bf16 v[12:15], v[132:135], v[202:205], v[12:15]
	v_mfma_f32_16x16x32_bf16 v[8:11], v[160:163], v[202:205], v[8:11]
	s_barrier
; #define PG8_STAGE(bufoff, gbase, voff) do { _Pragma("unroll") for (int _i = 0; _i < 2; ++_i) \
;         __builtin_amdgcn_global_load_lds((const unsigned*)((const char*)(gbase) + (voff)[_i]), (LAS unsigned*)(lds + (bufoff) + ldsw + _i * 8192), 16, 0, 0); } while (0)
; #define PG8_LDA(dst, b, h) do { _Pragma("unroll") for (int m = 0; m < 4; ++m) _Pragma("unroll") for (int k = 0; k < 2; ++k) dst[m][k] = *(const LAS bf16x8*)(lds + PG8_SA(b, h) + aoff + m * 2048 + k * 1024); } while (0)
; #define PG8_LDB(dst, b, h) do { _Pragma("unroll") for (int n = 0; n < 2; ++n) _Pragma("unroll") for (int k = 0; k < 2; ++k) dst[n][k] = *(const LAS bf16x8*)(lds + PG8_SB(b, h) + boff + n * 2048 + k * 1024); } while (0)
; #define PG8_MMA(ai, bj, At, Bt) do { __builtin_amdgcn_s_setprio(1); _Pragma("unroll") for (int m = 0; m < 4; ++m) _Pragma("unroll") for (int n = 0; n < 2; ++n) _Pragma("unroll") for (int k = 0; k < 2; ++k) \
;         acc[ai][bj][m][n] = __builtin_amdgcn_mfma_f32_16x16x32_bf16(Bt[n][k], At[m][k], acc[ai][bj][m][n], 0, 0, 0); __builtin_amdgcn_s_setprio(0); } while (0)
; #define PG8_WAIT_V(n) asm volatile("s_waitcnt vmcnt(" #n ")" ::: "memory")
; #define PG8_WAIT_L(n) asm volatile("s_waitcnt lgkmcnt(" #n ")" ::: "memory")
; #define PG8_BAR __builtin_amdgcn_s_barrier()
; #define PG8_SCHED __builtin_amdgcn_sched_barrier(0)
; template <class Epi, class Sched>
; __device__ __forceinline__ void gemm_phase(LAS unsigned char* lds, const Gemm g, const Sched& S, const Epi& E) {
;     ...
;             PG8_STAGE(PG8_SB(0, 1), b2 + hstep, voffB);
;             PG8_WAIT_V(6); PG8_BAR; PG8_MMA(1, 1, At, B1); PG8_BAR;
;             PG8_LDB(B0, 1, 0); PG8_SCHED; PG8_LDA(At, 1, 0); PG8_STAGE(PG8_SA(0, 1), a2 + hstep, voffA);
;             PG8_WAIT_L(8); PG8_BAR; PG8_WAIT_L(0); PG8_MMA(0, 0, At, B0); PG8_BAR; PG8_SCHED;
;             PG8_LDB(B1, 1, 1); PG8_STAGE(PG8_SB(1, 0), b3, voffB);
;             PG8_BAR; PG8_WAIT_L(0); PG8_MMA(0, 1, At, B1); PG8_BAR;
;             PG8_LDA(At, 1, 1); PG8_STAGE(PG8_SA(1, 0), a3, voffA);
;             PG8_BAR; PG8_WAIT_L(0); PG8_MMA(1, 0, At, B0); PG8_BAR; PG8_SCHED;
	s_setprio 0
	s_add_u32 s58, s26, 0x40000
	s_addc_u32 s59, s27, 0
	s_add_i32 s57, s49, s34
	s_mov_b32 m0, s57
	s_nop 0
	global_load_lds_dwordx4 v146, s[58:59]
	s_add_i32 m0, s57, 0x2000
	s_nop 0
	global_load_lds_dwordx4 v142, s[58:59]
	s_add_u32 s28, s28, 0x40000
	s_addc_u32 s29, s29, 0
	s_mov_b32 m0, s39
	s_nop 0
	global_load_lds_dwordx4 v148, s[28:29]
	s_mov_b32 m0, s40
	s_nop 0
	global_load_lds_dwordx4 v144, s[28:29]
	s_waitcnt vmcnt(10)
	s_setprio 1
	s_barrier
	v_mfma_f32_16x16x32_bf16 v[52:55], v[206:209], v[170:173], 0
	v_mfma_f32_16x16x32_bf16 v[48:51], v[214:217], v[170:173], 0
	v_mfma_f32_16x16x32_bf16 v[36:39], v[206:209], v[178:181], 0
	v_mfma_f32_16x16x32_bf16 v[32:35], v[214:217], v[178:181], 0
	v_mfma_f32_16x16x32_bf16 v[20:23], v[206:209], v[186:189], 0
	v_mfma_f32_16x16x32_bf16 v[16:19], v[214:217], v[186:189], 0
	v_mfma_f32_16x16x32_bf16 v[4:7], v[206:209], v[194:197], 0
	v_mfma_f32_16x16x32_bf16 v[0:3], v[214:217], v[194:197], 0
	v_mfma_f32_16x16x32_bf16 v[52:55], v[210:213], v[174:177], v[52:55]
	v_mfma_f32_16x16x32_bf16 v[48:51], v[218:221], v[174:177], v[48:51]
	v_mfma_f32_16x16x32_bf16 v[36:39], v[210:213], v[182:185], v[36:39]
	v_mfma_f32_16x16x32_bf16 v[32:35], v[218:221], v[182:185], v[32:35]
	v_mfma_f32_16x16x32_bf16 v[20:23], v[210:213], v[190:193], v[20:23]
	v_mfma_f32_16x16x32_bf16 v[16:19], v[218:221], v[190:193], v[16:19]
	v_mfma_f32_16x16x32_bf16 v[4:7], v[210:213], v[202:205], v[4:7]
	v_mfma_f32_16x16x32_bf16 v[0:3], v[218:221], v[202:205], v[0:3]
	s_barrier
	s_setprio 0
	s_add_i32 s57, 0, 0x18000
	ds_read_b128 v[128:131], v169 offset:16384
	ds_read_b128 v[132:135], v169 offset:17408
	ds_read_b128 v[136:139], v169 offset:18432
	ds_read_b128 v[160:163], v169 offset:19456
	ds_read_b128 v[170:173], v168 offset:32768
	ds_read_b128 v[174:177], v168 offset:33792
	ds_read_b128 v[178:181], v168 offset:34816
	ds_read_b128 v[182:185], v168 offset:35840
	ds_read_b128 v[186:189], v168 offset:36864
	ds_read_b128 v[190:193], v168 offset:37888
	ds_read_b128 v[194:197], v168 offset:38912
	ds_read_b128 v[202:205], v168 offset:39936
	s_waitcnt lgkmcnt(8)
	s_waitcnt vmcnt(8)
	s_setprio 1
	s_barrier
	s_waitcnt lgkmcnt(0)
	v_mfma_f32_16x16x32_bf16 v[124:127], v[128:131], v[170:173], v[124:127]
	v_mfma_f32_16x16x32_bf16 v[120:123], v[136:139], v[170:173], v[120:123]
	v_mfma_f32_16x16x32_bf16 v[108:111], v[128:131], v[178:181], v[108:111]
	v_mfma_f32_16x16x32_bf16 v[104:107], v[136:139], v[178:181], v[104:107]
	v_mfma_f32_16x16x32_bf16 v[92:95], v[128:131], v[186:189], v[92:95]
	v_mfma_f32_16x16x32_bf16 v[88:91], v[136:139], v[186:189], v[88:91]
	v_mfma_f32_16x16x32_bf16 v[76:79], v[128:131], v[194:197], v[76:79]
	v_mfma_f32_16x16x32_bf16 v[72:75], v[136:139], v[194:197], v[72:75]
	v_mfma_f32_16x16x32_bf16 v[124:127], v[132:135], v[174:177], v[124:127]
	v_mfma_f32_16x16x32_bf16 v[120:123], v[160:163], v[174:177], v[120:123]
	v_mfma_f32_16x16x32_bf16 v[108:111], v[132:135], v[182:185], v[108:111]
	v_mfma_f32_16x16x32_bf16 v[104:107], v[160:163], v[182:185], v[104:107]
	v_mfma_f32_16x16x32_bf16 v[92:95], v[132:135], v[190:193], v[92:95]
	v_mfma_f32_16x16x32_bf16 v[88:91], v[160:163], v[190:193], v[88:91]
	v_mfma_f32_16x16x32_bf16 v[76:79], v[132:135], v[202:205], v[76:79]
	v_mfma_f32_16x16x32_bf16 v[72:75], v[160:163], v[202:205], v[72:75]
	s_barrier
	s_setprio 0
	s_add_i32 s28, 0, 0x1c000
	s_add_i32 s29, s57, s34
	v_add_u32_e32 v150, s28, v166
	s_add_u32 s0, s26, 0x80
	s_addc_u32 s1, s27, 0
	s_mov_b32 m0, s29
	ds_read_b128 v[206:209], v150
	ds_read_b128 v[210:213], v150 offset:1024
	ds_read_b128 v[214:217], v150 offset:2048
	ds_read_b128 v[218:221], v150 offset:3072
	global_load_lds_dwordx4 v146, s[0:1]
	s_add_i32 m0, s29, 0x2000
	s_nop 0
	global_load_lds_dwordx4 v142, s[0:1]
	s_waitcnt vmcnt(8)
	s_setprio 1
	s_barrier
	s_waitcnt lgkmcnt(0)
	v_mfma_f32_16x16x32_bf16 v[116:119], v[206:209], v[170:173], v[116:119]
	v_mfma_f32_16x16x32_bf16 v[112:115], v[214:217], v[170:173], v[112:115]
	v_mfma_f32_16x16x32_bf16 v[100:103], v[206:209], v[178:181], v[100:103]
	v_mfma_f32_16x16x32_bf16 v[96:99], v[214:217], v[178:181], v[96:99]
	v_mfma_f32_16x16x32_bf16 v[84:87], v[206:209], v[186:189], v[84:87]
	v_mfma_f32_16x16x32_bf16 v[80:83], v[214:217], v[186:189], v[80:83]
	v_mfma_f32_16x16x32_bf16 v[68:71], v[206:209], v[194:197], v[68:71]
	v_mfma_f32_16x16x32_bf16 v[64:67], v[214:217], v[194:197], v[64:67]
	v_mfma_f32_16x16x32_bf16 v[116:119], v[210:213], v[174:177], v[116:119]
	v_mfma_f32_16x16x32_bf16 v[112:115], v[218:221], v[174:177], v[112:115]
	v_mfma_f32_16x16x32_bf16 v[100:103], v[210:213], v[182:185], v[100:103]
	v_mfma_f32_16x16x32_bf16 v[96:99], v[218:221], v[182:185], v[96:99]
	v_mfma_f32_16x16x32_bf16 v[84:87], v[210:213], v[190:193], v[84:87]
	v_mfma_f32_16x16x32_bf16 v[80:83], v[218:221], v[190:193], v[80:83]
	v_mfma_f32_16x16x32_bf16 v[68:71], v[210:213], v[202:205], v[68:71]
	v_mfma_f32_16x16x32_bf16 v[64:67], v[218:221], v[202:205], v[64:67]
	s_barrier
	s_setprio 0
	s_mov_b32 m0, s44
	s_mov_b64 s[0:1], 0x80
	v_lshl_add_u64 v[140:141], v[222:223], 0, s[0:1]
	ds_read_b128 v[170:173], v168 offset:49152
	ds_read_b128 v[174:177], v168 offset:50176
	ds_read_b128 v[178:181], v168 offset:51200
	ds_read_b128 v[182:185], v168 offset:52224
	ds_read_b128 v[186:189], v168 offset:53248
	ds_read_b128 v[190:193], v168 offset:54272
	ds_read_b128 v[194:197], v168 offset:55296
	ds_read_b128 v[202:205], v168 offset:56320
	global_load_lds_dwordx4 v[140:141], off
	v_lshl_add_u64 v[140:141], v[224:225], 0, s[0:1]
	s_mov_b32 m0, s45
	s_nop 0
	global_load_lds_dwordx4 v[140:141], off
	s_setprio 1
	s_barrier
; #define PG8_STAGE(bufoff, gbase, voff) do { _Pragma("unroll") for (int _i = 0; _i < 2; ++_i) \
;         __builtin_amdgcn_global_load_lds((const unsigned*)((const char*)(gbase) + (voff)[_i]), (LAS unsigned*)(lds + (bufoff) + ldsw + _i * 8192), 16, 0, 0); } while (0)
; #define PG8_LDA(dst, b, h) do { _Pragma("unroll") for (int m = 0; m < 4; ++m) _Pragma("unroll") for (int k = 0; k < 2; ++k) dst[m][k] = *(const LAS bf16x8*)(lds + PG8_SA(b, h) + aoff + m * 2048 + k * 1024); } while (0)
; #define PG8_LDB(dst, b, h) do { _Pragma("unroll") for (int n = 0; n < 2; ++n) _Pragma("unroll") for (int k = 0; k < 2; ++k) dst[n][k] = *(const LAS bf16x8*)(lds + PG8_SB(b, h) + boff + n * 2048 + k * 1024); } while (0)
; #define PG8_MMA(ai, bj, At, Bt) do { __builtin_amdgcn_s_setprio(1); _Pragma("unroll") for (int m = 0; m < 4; ++m) _Pragma("unroll") for (int n = 0; n < 2; ++n) _Pragma("unroll") for (int k = 0; k < 2; ++k) \
;         acc[ai][bj][m][n] = __builtin_amdgcn_mfma_f32_16x16x32_bf16(Bt[n][k], At[m][k], acc[ai][bj][m][n], 0, 0, 0); __builtin_amdgcn_s_setprio(0); } while (0)
; #define PG8_WAIT_V(n) asm volatile("s_waitcnt vmcnt(" #n ")" ::: "memory")
; #define PG8_WAIT_L(n) asm volatile("s_waitcnt lgkmcnt(" #n ")" ::: "memory")
; #define PG8_BAR __builtin_amdgcn_s_barrier()
; #define PG8_SCHED __builtin_amdgcn_sched_barrier(0)
; template <class Epi, class Sched>
; __device__ __forceinline__ void gemm_phase(LAS unsigned char* lds, const Gemm g, const Sched& S, const Epi& E) {
;     ...
;             PG8_LDB(B0, 0, 0); PG8_SCHED; PG8_LDA(At, 0, 0); PG8_STAGE(PG8_SA(1, 1), a1 + hstep, voffA);
;             PG8_WAIT_L(8); PG8_BAR; PG8_WAIT_L(0); PG8_MMA(0, 0, At, B0); PG8_BAR; PG8_SCHED;
;             PG8_LDB(B1, 0, 1); PG8_STAGE(PG8_SB(0, 0), b2, voffB);
;             PG8_BAR; PG8_WAIT_L(0); PG8_MMA(0, 1, At, B1); PG8_BAR;
;             PG8_LDA(At, 0, 1); PG8_STAGE(PG8_SA(0, 0), a2, voffA);
;             PG8_BAR; PG8_WAIT_L(0); PG8_MMA(1, 0, At, B0); PG8_BAR; PG8_SCHED;
;     ...
;             PG8_BAR; PG8_WAIT_L(0); PG8_MMA(1, 0, At, B0); PG8_BAR; PG8_SCHED;
;             PG8_STAGE(PG8_SB(1, 1), b3 + hstep, voffB);
;             PG8_WAIT_V(6); PG8_BAR; PG8_MMA(1, 1, At, B1); PG8_BAR;
;         }
	s_waitcnt lgkmcnt(0)
	v_mfma_f32_16x16x32_bf16 v[60:63], v[128:131], v[170:173], v[60:63]
	v_mfma_f32_16x16x32_bf16 v[56:59], v[136:139], v[170:173], v[56:59]
	v_mfma_f32_16x16x32_bf16 v[44:47], v[128:131], v[178:181], v[44:47]
	v_mfma_f32_16x16x32_bf16 v[40:43], v[136:139], v[178:181], v[40:43]
	v_mfma_f32_16x16x32_bf16 v[28:31], v[128:131], v[186:189], v[28:31]
	v_mfma_f32_16x16x32_bf16 v[24:27], v[136:139], v[186:189], v[24:27]
	v_mfma_f32_16x16x32_bf16 v[12:15], v[128:131], v[194:197], v[12:15]
	v_mfma_f32_16x16x32_bf16 v[8:11], v[136:139], v[194:197], v[8:11]
	v_mfma_f32_16x16x32_bf16 v[60:63], v[132:135], v[174:177], v[60:63]
	v_mfma_f32_16x16x32_bf16 v[56:59], v[160:163], v[174:177], v[56:59]
	v_mfma_f32_16x16x32_bf16 v[44:47], v[132:135], v[182:185], v[44:47]
	v_mfma_f32_16x16x32_bf16 v[40:43], v[160:163], v[182:185], v[40:43]
	v_mfma_f32_16x16x32_bf16 v[28:31], v[132:135], v[190:193], v[28:31]
	v_mfma_f32_16x16x32_bf16 v[24:27], v[160:163], v[190:193], v[24:27]
	v_mfma_f32_16x16x32_bf16 v[12:15], v[132:135], v[202:205], v[12:15]
	v_mfma_f32_16x16x32_bf16 v[8:11], v[160:163], v[202:205], v[8:11]
	s_barrier
	s_setprio 0
	s_add_u32 s26, s26, 0x40080
	s_addc_u32 s27, s27, 0
	s_add_i32 s28, s28, s34
	s_mov_b32 m0, s28
	s_nop 0
	global_load_lds_dwordx4 v146, s[26:27]
	s_add_i32 m0, s28, 0x2000
	s_nop 0
	global_load_lds_dwordx4 v142, s[26:27]
	s_waitcnt vmcnt(8)
	s_setprio 1
	s_barrier
	v_mfma_f32_16x16x32_bf16 v[52:55], v[206:209], v[170:173], v[52:55]
	v_mfma_f32_16x16x32_bf16 v[48:51], v[214:217], v[170:173], v[48:51]
	v_mfma_f32_16x16x32_bf16 v[36:39], v[206:209], v[178:181], v[36:39]
	v_mfma_f32_16x16x32_bf16 v[32:35], v[214:217], v[178:181], v[32:35]
	v_mfma_f32_16x16x32_bf16 v[20:23], v[206:209], v[186:189], v[20:23]
	v_mfma_f32_16x16x32_bf16 v[16:19], v[214:217], v[186:189], v[16:19]
	v_mfma_f32_16x16x32_bf16 v[4:7], v[206:209], v[194:197], v[4:7]
	v_mfma_f32_16x16x32_bf16 v[0:3], v[214:217], v[194:197], v[0:3]
	v_mfma_f32_16x16x32_bf16 v[52:55], v[210:213], v[174:177], v[52:55]
	v_mfma_f32_16x16x32_bf16 v[48:51], v[218:221], v[174:177], v[48:51]
	v_mfma_f32_16x16x32_bf16 v[36:39], v[210:213], v[182:185], v[36:39]
	v_mfma_f32_16x16x32_bf16 v[32:35], v[218:221], v[182:185], v[32:35]
	v_mfma_f32_16x16x32_bf16 v[20:23], v[210:213], v[190:193], v[20:23]
	v_mfma_f32_16x16x32_bf16 v[16:19], v[218:221], v[190:193], v[16:19]
	v_mfma_f32_16x16x32_bf16 v[4:7], v[210:213], v[202:205], v[4:7]
	v_mfma_f32_16x16x32_bf16 v[0:3], v[218:221], v[202:205], v[0:3]
	s_barrier
	s_setprio 0
	s_add_i32 s56, s56, 2
	s_add_u32 s6, s6, 0x100
	s_addc_u32 s7, s7, 0
	s_add_u32 s54, s54, 0x100
	s_addc_u32 s55, s55, 0
	s_cmp_gt_u32 s56, 13
.LBB0_578:
	ds_read_b128 v[128:131], v167
	ds_read_b128 v[132:135], v167 offset:1024
	ds_read_b128 v[136:139], v167 offset:2048
	ds_read_b128 v[160:163], v167 offset:3072
	s_add_u32 s26, s6, 0xfffc0080
	s_addc_u32 s27, s7, -1
	s_cmp_eq_u32 s56, 12
	s_cselect_b32 s29, s5, s27
	s_cselect_b32 s28, s21, s26
	s_cselect_b32 s27, s19, s55
	s_cselect_b32 s26, s53, s54
	s_add_i32 m0, s37, 0xc000
	ds_read_b128 v[170:173], v168
	ds_read_b128 v[174:177], v168 offset:1024
	ds_read_b128 v[178:181], v168 offset:2048
	ds_read_b128 v[182:185], v168 offset:3072
	ds_read_b128 v[186:189], v168 offset:4096
	ds_read_b128 v[190:193], v168 offset:5120
	ds_read_b128 v[194:197], v168 offset:6144
	ds_read_b128 v[202:205], v168 offset:7168
	global_load_lds_dwordx4 v152, s[6:7]
	s_add_i32 m0, s37, 0xe000
	s_nop 0
	global_load_lds_dwordx4 v154, s[6:7]
	s_waitcnt lgkmcnt(8)
	s_waitcnt vmcnt(8)
	s_setprio 1
	s_barrier
	s_waitcnt lgkmcnt(0)
	v_mfma_f32_16x16x32_bf16 v[124:127], v[128:131], v[170:173], v[124:127]
	v_mfma_f32_16x16x32_bf16 v[120:123], v[136:139], v[170:173], v[120:123]
	v_mfma_f32_16x16x32_bf16 v[108:111], v[128:131], v[178:181], v[108:111]
	v_mfma_f32_16x16x32_bf16 v[104:107], v[136:139], v[178:181], v[104:107]
	v_mfma_f32_16x16x32_bf16 v[92:95], v[128:131], v[186:189], v[92:95]
	v_mfma_f32_16x16x32_bf16 v[88:91], v[136:139], v[186:189], v[88:91]
	v_mfma_f32_16x16x32_bf16 v[76:79], v[128:131], v[194:197], v[76:79]
	v_mfma_f32_16x16x32_bf16 v[72:75], v[136:139], v[194:197], v[72:75]
	v_mfma_f32_16x16x32_bf16 v[124:127], v[132:135], v[174:177], v[124:127]
	v_mfma_f32_16x16x32_bf16 v[120:123], v[160:163], v[174:177], v[120:123]
	v_mfma_f32_16x16x32_bf16 v[108:111], v[132:135], v[182:185], v[108:111]
	v_mfma_f32_16x16x32_bf16 v[104:107], v[160:163], v[182:185], v[104:107]
	v_mfma_f32_16x16x32_bf16 v[92:95], v[132:135], v[190:193], v[92:95]
	v_mfma_f32_16x16x32_bf16 v[88:91], v[160:163], v[190:193], v[88:91]
	v_mfma_f32_16x16x32_bf16 v[76:79], v[132:135], v[202:205], v[76:79]
	v_mfma_f32_16x16x32_bf16 v[72:75], v[160:163], v[202:205], v[72:75]
	s_barrier
	s_setprio 0
	s_add_i32 s57, s48, s34
	s_mov_b32 m0, s57
	ds_read_b128 v[206:209], v169
	ds_read_b128 v[210:213], v169 offset:1024
	ds_read_b128 v[214:217], v169 offset:2048
	ds_read_b128 v[218:221], v169 offset:3072
	global_load_lds_dwordx4 v146, s[26:27]
	s_add_i32 m0, s57, 0x2000
	s_nop 0
	global_load_lds_dwordx4 v142, s[26:27]
	s_waitcnt vmcnt(8)
	s_setprio 1
	s_barrier
; #define PG8_STAGE(bufoff, gbase, voff) do { _Pragma("unroll") for (int _i = 0; _i < 2; ++_i) \
;         __builtin_amdgcn_global_load_lds((const unsigned*)((const char*)(gbase) + (voff)[_i]), (LAS unsigned*)(lds + (bufoff) + ldsw + _i * 8192), 16, 0, 0); } while (0)
; #define PG8_LDA(dst, b, h) do { _Pragma("unroll") for (int m = 0; m < 4; ++m) _Pragma("unroll") for (int k = 0; k < 2; ++k) dst[m][k] = *(const LAS bf16x8*)(lds + PG8_SA(b, h) + aoff + m * 2048 + k * 1024); } while (0)
; #define PG8_LDB(dst, b, h) do { _Pragma("unroll") for (int n = 0; n < 2; ++n) _Pragma("unroll") for (int k = 0; k < 2; ++k) dst[n][k] = *(const LAS bf16x8*)(lds + PG8_SB(b, h) + boff + n * 2048 + k * 1024); } while (0)
; #define PG8_MMA(ai, bj, At, Bt) do { __builtin_amdgcn_s_setprio(1); _Pragma("unroll") for (int m = 0; m < 4; ++m) _Pragma("unroll") for (int n = 0; n < 2; ++n) _Pragma("unroll") for (int k = 0; k < 2; ++k) \
;         acc[ai][bj][m][n] = __builtin_amdgcn_mfma_f32_16x16x32_bf16(Bt[n][k], At[m][k], acc[ai][bj][m][n], 0, 0, 0); __builtin_amdgcn_s_setprio(0); } while (0)
; #define PG8_WAIT_V(n) asm volatile("s_waitcnt vmcnt(" #n ")" ::: "memory")
; #define PG8_WAIT_L(n) asm volatile("s_waitcnt lgkmcnt(" #n ")" ::: "memory")
; #define PG8_BAR __builtin_amdgcn_s_barrier()
; #define PG8_SCHED __builtin_amdgcn_sched_barrier(0)
; template <class Epi, class Sched>
; __device__ __forceinline__ void gemm_phase(LAS unsigned char* lds, const Gemm g, const Sched& S, const Epi& E) {
;     ...
;             PG8_BAR; PG8_WAIT_L(0); PG8_MMA(1, 0, At, B0); PG8_BAR; PG8_SCHED;
;             PG8_STAGE(PG8_SB(0, 1), b2 + hstep, voffB);
;             PG8_WAIT_V(6); PG8_BAR; PG8_MMA(1, 1, At, B1); PG8_BAR;
;             PG8_LDB(B0, 1, 0); PG8_SCHED; PG8_LDA(At, 1, 0); PG8_STAGE(PG8_SA(0, 1), a2 + hstep, voffA);
;             PG8_WAIT_L(8); PG8_BAR; PG8_WAIT_L(0); PG8_MMA(0, 0, At, B0); PG8_BAR; PG8_SCHED;
	s_waitcnt lgkmcnt(0)
	v_mfma_f32_16x16x32_bf16 v[116:119], v[206:209], v[170:173], v[116:119]
	v_mfma_f32_16x16x32_bf16 v[112:115], v[214:217], v[170:173], v[112:115]
	v_mfma_f32_16x16x32_bf16 v[100:103], v[206:209], v[178:181], v[100:103]
	v_mfma_f32_16x16x32_bf16 v[96:99], v[214:217], v[178:181], v[96:99]
	v_mfma_f32_16x16x32_bf16 v[84:87], v[206:209], v[186:189], v[84:87]
	v_mfma_f32_16x16x32_bf16 v[80:83], v[214:217], v[186:189], v[80:83]
	v_mfma_f32_16x16x32_bf16 v[68:71], v[206:209], v[194:197], v[68:71]
	v_mfma_f32_16x16x32_bf16 v[64:67], v[214:217], v[194:197], v[64:67]
	v_mfma_f32_16x16x32_bf16 v[116:119], v[210:213], v[174:177], v[116:119]
	v_mfma_f32_16x16x32_bf16 v[112:115], v[218:221], v[174:177], v[112:115]
	v_mfma_f32_16x16x32_bf16 v[100:103], v[210:213], v[182:185], v[100:103]
	v_mfma_f32_16x16x32_bf16 v[96:99], v[218:221], v[182:185], v[96:99]
	v_mfma_f32_16x16x32_bf16 v[84:87], v[210:213], v[190:193], v[84:87]
	v_mfma_f32_16x16x32_bf16 v[80:83], v[218:221], v[190:193], v[80:83]
	v_mfma_f32_16x16x32_bf16 v[68:71], v[210:213], v[202:205], v[68:71]
	v_mfma_f32_16x16x32_bf16 v[64:67], v[218:221], v[202:205], v[64:67]
	s_barrier
	s_setprio 0
	s_mov_b32 m0, s37
	v_lshl_add_u64 v[222:223], s[28:29], 0, v[148:149]
	ds_read_b128 v[170:173], v168 offset:16384
	ds_read_b128 v[174:177], v168 offset:17408
	ds_read_b128 v[178:181], v168 offset:18432
	ds_read_b128 v[182:185], v168 offset:19456
	ds_read_b128 v[186:189], v168 offset:20480
	ds_read_b128 v[190:193], v168 offset:21504
	ds_read_b128 v[194:197], v168 offset:22528
	ds_read_b128 v[202:205], v168 offset:23552
	global_load_lds_dwordx4 v148, s[28:29]
	v_lshl_add_u64 v[224:225], s[28:29], 0, v[144:145]
	s_mov_b32 m0, s38
	s_nop 0
	global_load_lds_dwordx4 v144, s[28:29]
	s_setprio 1
	s_barrier
	s_waitcnt lgkmcnt(0)
	v_mfma_f32_16x16x32_bf16 v[60:63], v[128:131], v[170:173], v[60:63]
	v_mfma_f32_16x16x32_bf16 v[56:59], v[136:139], v[170:173], v[56:59]
	v_mfma_f32_16x16x32_bf16 v[44:47], v[128:131], v[178:181], v[44:47]
	v_mfma_f32_16x16x32_bf16 v[40:43], v[136:139], v[178:181], v[40:43]
	v_mfma_f32_16x16x32_bf16 v[28:31], v[128:131], v[186:189], v[28:31]
	v_mfma_f32_16x16x32_bf16 v[24:27], v[136:139], v[186:189], v[24:27]
	v_mfma_f32_16x16x32_bf16 v[12:15], v[128:131], v[194:197], v[12:15]
	v_mfma_f32_16x16x32_bf16 v[8:11], v[136:139], v[194:197], v[8:11]
	v_mfma_f32_16x16x32_bf16 v[60:63], v[132:135], v[174:177], v[60:63]
	v_mfma_f32_16x16x32_bf16 v[56:59], v[160:163], v[174:177], v[56:59]
	v_mfma_f32_16x16x32_bf16 v[44:47], v[132:135], v[182:185], v[44:47]
	v_mfma_f32_16x16x32_bf16 v[40:43], v[160:163], v[182:185], v[40:43]
	v_mfma_f32_16x16x32_bf16 v[28:31], v[132:135], v[190:193], v[28:31]
	v_mfma_f32_16x16x32_bf16 v[24:27], v[160:163], v[190:193], v[24:27]
	v_mfma_f32_16x16x32_bf16 v[12:15], v[132:135], v[202:205], v[12:15]
	v_mfma_f32_16x16x32_bf16 v[8:11], v[160:163], v[202:205], v[8:11]
	s_barrier
	s_setprio 0
	s_add_u32 s58, s26, 0x40000
	s_addc_u32 s59, s27, 0
	s_add_i32 s57, s49, s34
	s_mov_b32 m0, s57
	s_nop 0
	global_load_lds_dwordx4 v146, s[58:59]
	s_add_i32 m0, s57, 0x2000
	s_nop 0
	global_load_lds_dwordx4 v142, s[58:59]
	s_add_u32 s28, s28, 0x40000
	s_addc_u32 s29, s29, 0
	s_mov_b32 m0, s39
	s_nop 0
	global_load_lds_dwordx4 v148, s[28:29]
	s_mov_b32 m0, s40
	s_nop 0
	global_load_lds_dwordx4 v144, s[28:29]
	s_waitcnt vmcnt(10)
	s_setprio 1
	s_barrier
	v_mfma_f32_16x16x32_bf16 v[52:55], v[206:209], v[170:173], v[52:55]
	v_mfma_f32_16x16x32_bf16 v[48:51], v[214:217], v[170:173], v[48:51]
	v_mfma_f32_16x16x32_bf16 v[36:39], v[206:209], v[178:181], v[36:39]
	v_mfma_f32_16x16x32_bf16 v[32:35], v[214:217], v[178:181], v[32:35]
	v_mfma_f32_16x16x32_bf16 v[20:23], v[206:209], v[186:189], v[20:23]
	v_mfma_f32_16x16x32_bf16 v[16:19], v[214:217], v[186:189], v[16:19]
	v_mfma_f32_16x16x32_bf16 v[4:7], v[206:209], v[194:197], v[4:7]
	v_mfma_f32_16x16x32_bf16 v[0:3], v[214:217], v[194:197], v[0:3]
	v_mfma_f32_16x16x32_bf16 v[52:55], v[210:213], v[174:177], v[52:55]
	v_mfma_f32_16x16x32_bf16 v[48:51], v[218:221], v[174:177], v[48:51]
	v_mfma_f32_16x16x32_bf16 v[36:39], v[210:213], v[182:185], v[36:39]
	v_mfma_f32_16x16x32_bf16 v[32:35], v[218:221], v[182:185], v[32:35]
	v_mfma_f32_16x16x32_bf16 v[20:23], v[210:213], v[190:193], v[20:23]
	v_mfma_f32_16x16x32_bf16 v[16:19], v[218:221], v[190:193], v[16:19]
	v_mfma_f32_16x16x32_bf16 v[4:7], v[210:213], v[202:205], v[4:7]
	v_mfma_f32_16x16x32_bf16 v[0:3], v[218:221], v[202:205], v[0:3]
	s_barrier
	s_setprio 0
	s_add_i32 s57, 0, 0x18000
	ds_read_b128 v[128:131], v169 offset:16384
	ds_read_b128 v[132:135], v169 offset:17408
	ds_read_b128 v[136:139], v169 offset:18432
	ds_read_b128 v[160:163], v169 offset:19456
	ds_read_b128 v[170:173], v168 offset:32768
	ds_read_b128 v[174:177], v168 offset:33792
	ds_read_b128 v[178:181], v168 offset:34816
	ds_read_b128 v[182:185], v168 offset:35840
	ds_read_b128 v[186:189], v168 offset:36864
	ds_read_b128 v[190:193], v168 offset:37888
	ds_read_b128 v[194:197], v168 offset:38912
	ds_read_b128 v[202:205], v168 offset:39936
	s_waitcnt lgkmcnt(8)
	s_waitcnt vmcnt(8)
	s_setprio 1
	s_barrier
; #define PG8_STAGE(bufoff, gbase, voff) do { _Pragma("unroll") for (int _i = 0; _i < 2; ++_i) \
;         __builtin_amdgcn_global_load_lds((const unsigned*)((const char*)(gbase) + (voff)[_i]), (LAS unsigned*)(lds + (bufoff) + ldsw + _i * 8192), 16, 0, 0); } while (0)
; #define PG8_LDA(dst, b, h) do { _Pragma("unroll") for (int m = 0; m < 4; ++m) _Pragma("unroll") for (int k = 0; k < 2; ++k) dst[m][k] = *(const LAS bf16x8*)(lds + PG8_SA(b, h) + aoff + m * 2048 + k * 1024); } while (0)
; #define PG8_LDB(dst, b, h) do { _Pragma("unroll") for (int n = 0; n < 2; ++n) _Pragma("unroll") for (int k = 0; k < 2; ++k) dst[n][k] = *(const LAS bf16x8*)(lds + PG8_SB(b, h) + boff + n * 2048 + k * 1024); } while (0)
; #define PG8_MMA(ai, bj, At, Bt) do { __builtin_amdgcn_s_setprio(1); _Pragma("unroll") for (int m = 0; m < 4; ++m) _Pragma("unroll") for (int n = 0; n < 2; ++n) _Pragma("unroll") for (int k = 0; k < 2; ++k) \
;         acc[ai][bj][m][n] = __builtin_amdgcn_mfma_f32_16x16x32_bf16(Bt[n][k], At[m][k], acc[ai][bj][m][n], 0, 0, 0); __builtin_amdgcn_s_setprio(0); } while (0)
; #define PG8_WAIT_L(n) asm volatile("s_waitcnt lgkmcnt(" #n ")" ::: "memory")
; #define PG8_BAR __builtin_amdgcn_s_barrier()
; #define PG8_SCHED __builtin_amdgcn_sched_barrier(0)
; template <class Epi, class Sched>
; __device__ __forceinline__ void gemm_phase(LAS unsigned char* lds, const Gemm g, const Sched& S, const Epi& E) {
;     ...
;             PG8_WAIT_L(8); PG8_BAR; PG8_WAIT_L(0); PG8_MMA(0, 0, At, B0); PG8_BAR; PG8_SCHED;
;             PG8_LDB(B1, 1, 1); PG8_STAGE(PG8_SB(1, 0), b3, voffB);
;             PG8_BAR; PG8_WAIT_L(0); PG8_MMA(0, 1, At, B1); PG8_BAR;
;             PG8_LDA(At, 1, 1); PG8_STAGE(PG8_SA(1, 0), a3, voffA);
;             PG8_BAR; PG8_WAIT_L(0); PG8_MMA(1, 0, At, B0); PG8_BAR; PG8_SCHED;
	s_waitcnt lgkmcnt(0)
	v_mfma_f32_16x16x32_bf16 v[124:127], v[128:131], v[170:173], v[124:127]
	v_mfma_f32_16x16x32_bf16 v[120:123], v[136:139], v[170:173], v[120:123]
	v_mfma_f32_16x16x32_bf16 v[108:111], v[128:131], v[178:181], v[108:111]
	v_mfma_f32_16x16x32_bf16 v[104:107], v[136:139], v[178:181], v[104:107]
	v_mfma_f32_16x16x32_bf16 v[92:95], v[128:131], v[186:189], v[92:95]
	v_mfma_f32_16x16x32_bf16 v[88:91], v[136:139], v[186:189], v[88:91]
	v_mfma_f32_16x16x32_bf16 v[76:79], v[128:131], v[194:197], v[76:79]
	v_mfma_f32_16x16x32_bf16 v[72:75], v[136:139], v[194:197], v[72:75]
	v_mfma_f32_16x16x32_bf16 v[124:127], v[132:135], v[174:177], v[124:127]
	v_mfma_f32_16x16x32_bf16 v[120:123], v[160:163], v[174:177], v[120:123]
	v_mfma_f32_16x16x32_bf16 v[108:111], v[132:135], v[182:185], v[108:111]
	v_mfma_f32_16x16x32_bf16 v[104:107], v[160:163], v[182:185], v[104:107]
	v_mfma_f32_16x16x32_bf16 v[92:95], v[132:135], v[190:193], v[92:95]
	v_mfma_f32_16x16x32_bf16 v[88:91], v[160:163], v[190:193], v[88:91]
	v_mfma_f32_16x16x32_bf16 v[76:79], v[132:135], v[202:205], v[76:79]
	v_mfma_f32_16x16x32_bf16 v[72:75], v[160:163], v[202:205], v[72:75]
	s_barrier
	s_setprio 0
	s_add_i32 s28, 0, 0x1c000
	s_add_i32 s29, s57, s34
	v_add_u32_e32 v150, s28, v166
	s_add_u32 s0, s26, 0x80
	s_addc_u32 s1, s27, 0
	s_mov_b32 m0, s29
	ds_read_b128 v[206:209], v150
	ds_read_b128 v[210:213], v150 offset:1024
	ds_read_b128 v[214:217], v150 offset:2048
	ds_read_b128 v[218:221], v150 offset:3072
	global_load_lds_dwordx4 v146, s[0:1]
	s_add_i32 m0, s29, 0x2000
	s_nop 0
	global_load_lds_dwordx4 v142, s[0:1]
	s_waitcnt vmcnt(8)
	s_setprio 1
	s_barrier
	s_waitcnt lgkmcnt(0)
	v_mfma_f32_16x16x32_bf16 v[116:119], v[206:209], v[170:173], v[116:119]
	v_mfma_f32_16x16x32_bf16 v[112:115], v[214:217], v[170:173], v[112:115]
	v_mfma_f32_16x16x32_bf16 v[100:103], v[206:209], v[178:181], v[100:103]
	v_mfma_f32_16x16x32_bf16 v[96:99], v[214:217], v[178:181], v[96:99]
	v_mfma_f32_16x16x32_bf16 v[84:87], v[206:209], v[186:189], v[84:87]
	v_mfma_f32_16x16x32_bf16 v[80:83], v[214:217], v[186:189], v[80:83]
	v_mfma_f32_16x16x32_bf16 v[68:71], v[206:209], v[194:197], v[68:71]
	v_mfma_f32_16x16x32_bf16 v[64:67], v[214:217], v[194:197], v[64:67]
	v_mfma_f32_16x16x32_bf16 v[116:119], v[210:213], v[174:177], v[116:119]
	v_mfma_f32_16x16x32_bf16 v[112:115], v[218:221], v[174:177], v[112:115]
	v_mfma_f32_16x16x32_bf16 v[100:103], v[210:213], v[182:185], v[100:103]
	v_mfma_f32_16x16x32_bf16 v[96:99], v[218:221], v[182:185], v[96:99]
	v_mfma_f32_16x16x32_bf16 v[84:87], v[210:213], v[190:193], v[84:87]
	v_mfma_f32_16x16x32_bf16 v[80:83], v[218:221], v[190:193], v[80:83]
	v_mfma_f32_16x16x32_bf16 v[68:71], v[210:213], v[202:205], v[68:71]
	v_mfma_f32_16x16x32_bf16 v[64:67], v[218:221], v[202:205], v[64:67]
	s_barrier
	s_setprio 0
	s_mov_b32 m0, s44
	s_mov_b64 s[0:1], 0x80
	v_lshl_add_u64 v[140:141], v[222:223], 0, s[0:1]
	ds_read_b128 v[170:173], v168 offset:49152
	ds_read_b128 v[174:177], v168 offset:50176
	ds_read_b128 v[178:181], v168 offset:51200
	ds_read_b128 v[182:185], v168 offset:52224
	ds_read_b128 v[186:189], v168 offset:53248
	ds_read_b128 v[190:193], v168 offset:54272
	ds_read_b128 v[194:197], v168 offset:55296
	ds_read_b128 v[202:205], v168 offset:56320
	global_load_lds_dwordx4 v[140:141], off
	v_lshl_add_u64 v[140:141], v[224:225], 0, s[0:1]
	s_mov_b32 m0, s45
	s_nop 0
	global_load_lds_dwordx4 v[140:141], off
	s_setprio 1
	s_barrier
; #define PG8_STAGE(bufoff, gbase, voff) do { _Pragma("unroll") for (int _i = 0; _i < 2; ++_i) \
;         __builtin_amdgcn_global_load_lds((const unsigned*)((const char*)(gbase) + (voff)[_i]), (LAS unsigned*)(lds + (bufoff) + ldsw + _i * 8192), 16, 0, 0); } while (0)
; #define PG8_MMA(ai, bj, At, Bt) do { __builtin_amdgcn_s_setprio(1); _Pragma("unroll") for (int m = 0; m < 4; ++m) _Pragma("unroll") for (int n = 0; n < 2; ++n) _Pragma("unroll") for (int k = 0; k < 2; ++k) \
;         acc[ai][bj][m][n] = __builtin_amdgcn_mfma_f32_16x16x32_bf16(Bt[n][k], At[m][k], acc[ai][bj][m][n], 0, 0, 0); __builtin_amdgcn_s_setprio(0); } while (0)
; #define PG8_WAIT_V(n) asm volatile("s_waitcnt vmcnt(" #n ")" ::: "memory")
; #define PG8_WAIT_L(n) asm volatile("s_waitcnt lgkmcnt(" #n ")" ::: "memory")
; #define PG8_BAR __builtin_amdgcn_s_barrier()
; #define PG8_SCHED __builtin_amdgcn_sched_barrier(0)
; template <class Epi, class Sched>
; __device__ __forceinline__ void gemm_phase(LAS unsigned char* lds, const Gemm g, const Sched& S, const Epi& E) {
;     ...
;             PG8_BAR; PG8_WAIT_L(0); PG8_MMA(1, 0, At, B0); PG8_BAR; PG8_SCHED;
;             PG8_STAGE(PG8_SB(1, 1), b3 + hstep, voffB);
;             PG8_WAIT_V(6); PG8_BAR; PG8_MMA(1, 1, At, B1); PG8_BAR;
;         }
;     __device__ __forceinline__ void operator()(const AccT& acc, const Unit& u, int wr, int wc, int fr, int fq) const {
;     ...
;         const int row0 = u.pm * 256 + wr * 64 + fr, col0 = u.pn * 256 + wc * 32 + 8 * fq;
;         const bool rope = u.pn < 2;
;         const int i = 4 * (wc & 1) + fq;
; #pragma unroll
;         for (int ai = 0; ai < 2; ++ai)
; #pragma unroll
;             for (int m = 0; m < 4; ++m) {
;                 const int row = row0 + ai * 128 + m * 16;
;                 f32x4 cs = {1.f, 1.f, 1.f, 1.f}, sn = {0.f, 0.f, 0.f, 0.f};
;                 if (rope) { const int t = row & 2047; const int pos = (i < 4) ? (t >> 6) : (t & 63);
;                     cs = *(const f32x4*)(ropeA + pos * 16 + ((4 * i) & 15)); sn = *(const f32x4*)(ropeA + 1024 + pos * 16 + ((4 * i) & 15)); }
	s_waitcnt lgkmcnt(0)
	v_mfma_f32_16x16x32_bf16 v[60:63], v[128:131], v[170:173], v[60:63]
	v_mfma_f32_16x16x32_bf16 v[56:59], v[136:139], v[170:173], v[56:59]
	v_mfma_f32_16x16x32_bf16 v[44:47], v[128:131], v[178:181], v[44:47]
	v_mfma_f32_16x16x32_bf16 v[40:43], v[136:139], v[178:181], v[40:43]
	v_mfma_f32_16x16x32_bf16 v[28:31], v[128:131], v[186:189], v[28:31]
	v_mfma_f32_16x16x32_bf16 v[24:27], v[136:139], v[186:189], v[24:27]
	v_mfma_f32_16x16x32_bf16 v[12:15], v[128:131], v[194:197], v[12:15]
	v_mfma_f32_16x16x32_bf16 v[8:11], v[136:139], v[194:197], v[8:11]
	v_mfma_f32_16x16x32_bf16 v[60:63], v[132:135], v[174:177], v[60:63]
	v_mfma_f32_16x16x32_bf16 v[56:59], v[160:163], v[174:177], v[56:59]
	v_mfma_f32_16x16x32_bf16 v[44:47], v[132:135], v[182:185], v[44:47]
	v_mfma_f32_16x16x32_bf16 v[40:43], v[160:163], v[182:185], v[40:43]
	v_mfma_f32_16x16x32_bf16 v[28:31], v[132:135], v[190:193], v[28:31]
	v_mfma_f32_16x16x32_bf16 v[24:27], v[160:163], v[190:193], v[24:27]
	v_mfma_f32_16x16x32_bf16 v[12:15], v[132:135], v[202:205], v[12:15]
	v_mfma_f32_16x16x32_bf16 v[8:11], v[160:163], v[202:205], v[8:11]
	s_barrier
	s_setprio 0
	s_add_u32 s26, s26, 0x40080
	s_addc_u32 s27, s27, 0
	s_add_i32 s28, s28, s34
	s_mov_b32 m0, s28
	s_nop 0
	global_load_lds_dwordx4 v146, s[26:27]
	s_add_i32 m0, s28, 0x2000
	s_nop 0
	global_load_lds_dwordx4 v142, s[26:27]
	s_waitcnt vmcnt(8)
	s_setprio 1
	s_barrier
	v_mfma_f32_16x16x32_bf16 v[52:55], v[206:209], v[170:173], v[52:55]
	v_mfma_f32_16x16x32_bf16 v[48:51], v[214:217], v[170:173], v[48:51]
	v_mfma_f32_16x16x32_bf16 v[36:39], v[206:209], v[178:181], v[36:39]
	v_mfma_f32_16x16x32_bf16 v[32:35], v[214:217], v[178:181], v[32:35]
	v_mfma_f32_16x16x32_bf16 v[20:23], v[206:209], v[186:189], v[20:23]
	v_mfma_f32_16x16x32_bf16 v[16:19], v[214:217], v[186:189], v[16:19]
	v_mfma_f32_16x16x32_bf16 v[4:7], v[206:209], v[194:197], v[4:7]
	v_mfma_f32_16x16x32_bf16 v[0:3], v[214:217], v[194:197], v[0:3]
	v_mfma_f32_16x16x32_bf16 v[52:55], v[210:213], v[174:177], v[52:55]
	v_mfma_f32_16x16x32_bf16 v[48:51], v[218:221], v[174:177], v[48:51]
	v_mfma_f32_16x16x32_bf16 v[36:39], v[210:213], v[182:185], v[36:39]
	v_mfma_f32_16x16x32_bf16 v[32:35], v[218:221], v[182:185], v[32:35]
	v_mfma_f32_16x16x32_bf16 v[20:23], v[210:213], v[190:193], v[20:23]
	v_mfma_f32_16x16x32_bf16 v[16:19], v[218:221], v[190:193], v[16:19]
	v_mfma_f32_16x16x32_bf16 v[4:7], v[210:213], v[202:205], v[4:7]
	v_mfma_f32_16x16x32_bf16 v[0:3], v[218:221], v[202:205], v[0:3]
	s_barrier
	s_setprio 0
	s_add_i32 s56, s56, 2
	s_add_u32 s6, s6, 0x100
	s_addc_u32 s7, s7, 0
	s_add_u32 s54, s54, 0x100
	s_addc_u32 s55, s55, 0
	s_cmp_gt_u32 s56, 13
	s_cbranch_scc0 .LBB0_578
	v_mov_b32_e32 v129, v165
	v_mov_b32_e32 v173, v164
	s_lshl_b32 s4, s4, 8
	s_add_i32 s4, s4, s42
	v_add_u32_e32 v128, s46, v129
	v_add_u32_e32 v170, s4, v173
	v_cmp_gt_i32_e64 s[4:5], 4, v128
	v_lshlrev_b32_e32 v128, 2, v128
	s_cmp_lt_i32 s52, 2
	v_and_b32_e32 v130, 12, v128
	s_cselect_b64 s[26:27], -1, 0
	s_cmp_gt_i32 s52, 1
	v_and_b32_e32 v172, 63, v173
	v_mov_b32_e32 v128, 1.0
	v_mov_b32_e32 v132, 0
	v_lshlrev_b32_e32 v162, 2, v130
	v_mov_b32_e32 v134, 0
	v_mov_b32_e32 v135, 0
	v_mov_b32_e32 v136, 0
	v_mov_b32_e32 v137, 0
	v_mov_b32_e32 v138, 1.0
	v_mov_b32_e32 v139, 1.0
	v_mov_b32_e32 v140, 1.0
	v_mov_b32_e32 v141, 1.0
	s_cbranch_scc1 .LBB0_581
	v_bfe_u32 v130, v170, 6, 5
	v_cndmask_b32_e64 v130, v172, v130, s[4:5]
	v_lshlrev_b32_e32 v150, 6, v130
	v_lshl_add_u64 v[130:131], s[16:17], 0, v[150:151]
	v_mov_b32_e32 v163, v151
	v_lshl_add_u64 v[134:135], s[8:9], 0, v[150:151]
	v_lshl_add_u64 v[130:131], v[130:131], 0, v[162:163]
	v_lshl_add_u64 v[134:135], v[134:135], 0, v[162:163]
	global_load_dwordx4 v[138:141], v[130:131], off
	s_nop 0
	global_load_dwordx4 v[134:137], v[134:135], off
	s_waitcnt vmcnt(0)

; #define PG8_STAGE(bufoff, gbase, voff) do { _Pragma("unroll") for (int _i = 0; _i < 2; ++_i) \
;         __builtin_amdgcn_global_load_lds((const unsigned*)((const char*)(gbase) + (voff)[_i]), (LAS unsigned*)(lds + (bufoff) + ldsw + _i * 8192), 16, 0, 0); } while (0)
; #define PG8_LDA(dst, b, h) do { _Pragma("unroll") for (int m = 0; m < 4; ++m) _Pragma("unroll") for (int k = 0; k < 2; ++k) dst[m][k] = *(const LAS bf16x8*)(lds + PG8_SA(b, h) + aoff + m * 2048 + k * 1024); } while (0)
; #define PG8_LDB(dst, b, h) do { _Pragma("unroll") for (int n = 0; n < 2; ++n) _Pragma("unroll") for (int k = 0; k < 2; ++k) dst[n][k] = *(const LAS bf16x8*)(lds + PG8_SB(b, h) + boff + n * 2048 + k * 1024); } while (0)
; #define PG8_MMA(ai, bj, At, Bt) do { __builtin_amdgcn_s_setprio(1); _Pragma("unroll") for (int m = 0; m < 4; ++m) _Pragma("unroll") for (int n = 0; n < 2; ++n) _Pragma("unroll") for (int k = 0; k < 2; ++k) \
;         acc[ai][bj][m][n] = __builtin_amdgcn_mfma_f32_16x16x32_bf16(Bt[n][k], At[m][k], acc[ai][bj][m][n], 0, 0, 0); __builtin_amdgcn_s_setprio(0); } while (0)
; #define PG8_WAIT_L(n) asm volatile("s_waitcnt lgkmcnt(" #n ")" ::: "memory")
; template <class Epi, class Sched>
; __device__ __forceinline__ void gemm_phase(LAS unsigned char* lds, const Gemm g, const Sched& S, const Epi& E) {
;     ...
;         const bool has_next = S.next(ui + 1, nxt);
;         const char* nA = has_next ? (const char*)g.A + (size_t)nxt.pm * tstep : cA; const char* nB = has_next ? (const char*)g.Bt + (size_t)nxt.pn * tstep : cB;
;         for (int t = 0; t < nt; t += 2) {
;             const bool last = (t == nt - 2);
;             const char* a1 = cA + (size_t)(t + 1) * kstep;
;             const char* a2 = last ? nA : cA + (size_t)(t + 2) * kstep; const char* b2 = last ? nB : cB + (size_t)(t + 2) * kstep;
;             const char* a3 = a2 + kstep; const char* b3 = b2 + kstep;
;             PG8_LDB(B0, 0, 0); PG8_SCHED; PG8_LDA(At, 0, 0); PG8_STAGE(PG8_SA(1, 1), a1 + hstep, voffA);
;             PG8_WAIT_L(8); PG8_BAR; PG8_WAIT_L(0); PG8_MMA(0, 0, At, B0); PG8_BAR; PG8_SCHED;
;             PG8_LDB(B1, 0, 1); PG8_STAGE(PG8_SB(0, 0), b2, voffB);
;             PG8_BAR; PG8_WAIT_L(0); PG8_MMA(0, 1, At, B1); PG8_BAR;
;             PG8_LDA(At, 0, 1); PG8_STAGE(PG8_SA(0, 0), a2, voffA);
;             PG8_BAR; PG8_WAIT_L(0); PG8_MMA(1, 0, At, B0); PG8_BAR; PG8_SCHED;
.LBB0_612:
	s_ashr_i32 s35, s34, 31
	v_cmp_lt_i64_e32 vcc, s[6:7], v[142:143]
	s_lshl_b64 s[6:7], s[34:35], 19
	s_add_u32 s36, s40, s6
	s_addc_u32 s37, s41, s7
	s_and_b64 s[6:7], vcc, exec
	s_cselect_b32 s8, s37, s1
	s_cselect_b32 s9, s36, s0
	s_ashr_i32 s31, s30, 31
	s_lshl_b64 s[6:7], s[30:31], 19
	s_add_u32 s38, s96, s6
	s_addc_u32 s39, s97, s7
	s_and_b64 s[6:7], vcc, exec
	s_cselect_b32 s31, s39, s5
	s_cselect_b32 s35, s38, s4
	s_add_u32 s0, s0, 0x40080
	s_addc_u32 s1, s1, 0
	s_add_u32 s65, s4, 0x100
	s_addc_u32 s66, s5, 0
	s_mov_b32 s67, -2
	s_waitcnt lgkmcnt(0)
	ds_read_b128 v[146:149], v171
	ds_read_b128 v[150:153], v171 offset:1024
	ds_read_b128 v[154:157], v171 offset:2048
	ds_read_b128 v[158:161], v171 offset:3072
	s_add_u32 s4, s0, 0xfffc0080
	s_addc_u32 s5, s1, -1
	s_cmp_eq_u32 s67, 12
	s_cselect_b32 s7, s8, s5
	s_cselect_b32 s6, s9, s4
	s_cselect_b32 s5, s31, s66
	s_cselect_b32 s4, s35, s65
	s_add_i32 m0, s45, 0xc000
	ds_read_b128 v[162:165], v172
	ds_read_b128 v[178:181], v172 offset:1024
	ds_read_b128 v[182:185], v172 offset:2048
	ds_read_b128 v[186:189], v172 offset:3072
	ds_read_b128 v[190:193], v172 offset:4096
	ds_read_b128 v[194:197], v172 offset:5120
	ds_read_b128 v[202:205], v172 offset:6144
	ds_read_b128 v[206:209], v172 offset:7168
	global_load_lds_dwordx4 v138, s[0:1]
	s_add_i32 m0, s45, 0xe000
	s_nop 0
	global_load_lds_dwordx4 v140, s[0:1]
	s_waitcnt lgkmcnt(8)
	s_waitcnt vmcnt(8)
	s_setprio 1
	s_barrier
	s_waitcnt lgkmcnt(0)
	v_mfma_f32_16x16x32_bf16 v[124:127], v[146:149], v[162:165], 0
	v_mfma_f32_16x16x32_bf16 v[120:123], v[154:157], v[162:165], 0
	v_mfma_f32_16x16x32_bf16 v[108:111], v[146:149], v[182:185], 0
	v_mfma_f32_16x16x32_bf16 v[104:107], v[154:157], v[182:185], 0
	v_mfma_f32_16x16x32_bf16 v[92:95], v[146:149], v[190:193], 0
	v_mfma_f32_16x16x32_bf16 v[88:91], v[154:157], v[190:193], 0
	v_mfma_f32_16x16x32_bf16 v[76:79], v[146:149], v[202:205], 0
	v_mfma_f32_16x16x32_bf16 v[72:75], v[154:157], v[202:205], 0
	v_mfma_f32_16x16x32_bf16 v[124:127], v[150:153], v[178:181], v[124:127]
	v_mfma_f32_16x16x32_bf16 v[120:123], v[158:161], v[178:181], v[120:123]
	v_mfma_f32_16x16x32_bf16 v[108:111], v[150:153], v[186:189], v[108:111]
	v_mfma_f32_16x16x32_bf16 v[104:107], v[158:161], v[186:189], v[104:107]
	v_mfma_f32_16x16x32_bf16 v[92:95], v[150:153], v[194:197], v[92:95]
	v_mfma_f32_16x16x32_bf16 v[88:91], v[158:161], v[194:197], v[88:91]
	v_mfma_f32_16x16x32_bf16 v[76:79], v[150:153], v[206:209], v[76:79]
	v_mfma_f32_16x16x32_bf16 v[72:75], v[158:161], v[206:209], v[72:75]
	s_barrier
	s_setprio 0
	s_add_i32 s68, s57, s44
	s_mov_b32 m0, s68
	ds_read_b128 v[210:213], v173
	ds_read_b128 v[214:217], v173 offset:1024
	ds_read_b128 v[218:221], v173 offset:2048
	ds_read_b128 v[222:225], v173 offset:3072
	global_load_lds_dwordx4 v130, s[4:5]
	s_add_i32 m0, s68, 0x2000
	s_nop 0
	global_load_lds_dwordx4 v134, s[4:5]
	s_waitcnt vmcnt(8)
	s_setprio 1
	s_barrier
	s_waitcnt lgkmcnt(0)
	v_mfma_f32_16x16x32_bf16 v[116:119], v[210:213], v[162:165], 0
	v_mfma_f32_16x16x32_bf16 v[112:115], v[218:221], v[162:165], 0
	v_mfma_f32_16x16x32_bf16 v[100:103], v[210:213], v[182:185], 0
	v_mfma_f32_16x16x32_bf16 v[96:99], v[218:221], v[182:185], 0
	v_mfma_f32_16x16x32_bf16 v[84:87], v[210:213], v[190:193], 0
	v_mfma_f32_16x16x32_bf16 v[80:83], v[218:221], v[190:193], 0
	v_mfma_f32_16x16x32_bf16 v[68:71], v[210:213], v[202:205], 0
	v_mfma_f32_16x16x32_bf16 v[64:67], v[218:221], v[202:205], 0
	v_mfma_f32_16x16x32_bf16 v[116:119], v[214:217], v[178:181], v[116:119]
	v_mfma_f32_16x16x32_bf16 v[112:115], v[222:225], v[178:181], v[112:115]
	v_mfma_f32_16x16x32_bf16 v[100:103], v[214:217], v[186:189], v[100:103]
	v_mfma_f32_16x16x32_bf16 v[96:99], v[222:225], v[186:189], v[96:99]
	v_mfma_f32_16x16x32_bf16 v[84:87], v[214:217], v[194:197], v[84:87]
	v_mfma_f32_16x16x32_bf16 v[80:83], v[222:225], v[194:197], v[80:83]
	v_mfma_f32_16x16x32_bf16 v[68:71], v[214:217], v[206:209], v[68:71]
	v_mfma_f32_16x16x32_bf16 v[64:67], v[222:225], v[206:209], v[64:67]
	s_barrier
	s_setprio 0
	s_mov_b32 m0, s45
	v_lshl_add_u64 v[226:227], s[6:7], 0, v[128:129]
	ds_read_b128 v[162:165], v172 offset:16384
	ds_read_b128 v[178:181], v172 offset:17408
	ds_read_b128 v[182:185], v172 offset:18432
	ds_read_b128 v[186:189], v172 offset:19456
	ds_read_b128 v[190:193], v172 offset:20480
	ds_read_b128 v[194:197], v172 offset:21504
	ds_read_b128 v[202:205], v172 offset:22528
	ds_read_b128 v[206:209], v172 offset:23552
	global_load_lds_dwordx4 v128, s[6:7]
	v_lshl_add_u64 v[228:229], s[6:7], 0, v[132:133]
	s_mov_b32 m0, s46
	s_nop 0
	global_load_lds_dwordx4 v132, s[6:7]
	s_setprio 1
	s_barrier
	s_waitcnt lgkmcnt(0)
	v_mfma_f32_16x16x32_bf16 v[60:63], v[146:149], v[162:165], 0
	v_mfma_f32_16x16x32_bf16 v[56:59], v[154:157], v[162:165], 0
	v_mfma_f32_16x16x32_bf16 v[44:47], v[146:149], v[182:185], 0
	v_mfma_f32_16x16x32_bf16 v[40:43], v[154:157], v[182:185], 0
	v_mfma_f32_16x16x32_bf16 v[28:31], v[146:149], v[190:193], 0
	v_mfma_f32_16x16x32_bf16 v[24:27], v[154:157], v[190:193], 0
	v_mfma_f32_16x16x32_bf16 v[12:15], v[146:149], v[202:205], 0
	v_mfma_f32_16x16x32_bf16 v[8:11], v[154:157], v[202:205], 0
	v_mfma_f32_16x16x32_bf16 v[60:63], v[150:153], v[178:181], v[60:63]
	v_mfma_f32_16x16x32_bf16 v[56:59], v[158:161], v[178:181], v[56:59]
	v_mfma_f32_16x16x32_bf16 v[44:47], v[150:153], v[186:189], v[44:47]
	v_mfma_f32_16x16x32_bf16 v[40:43], v[158:161], v[186:189], v[40:43]
	v_mfma_f32_16x16x32_bf16 v[28:31], v[150:153], v[194:197], v[28:31]
	v_mfma_f32_16x16x32_bf16 v[24:27], v[158:161], v[194:197], v[24:27]
	v_mfma_f32_16x16x32_bf16 v[12:15], v[150:153], v[206:209], v[12:15]
	v_mfma_f32_16x16x32_bf16 v[8:11], v[158:161], v[206:209], v[8:11]
	s_barrier
; #define PG8_STAGE(bufoff, gbase, voff) do { _Pragma("unroll") for (int _i = 0; _i < 2; ++_i) \
;         __builtin_amdgcn_global_load_lds((const unsigned*)((const char*)(gbase) + (voff)[_i]), (LAS unsigned*)(lds + (bufoff) + ldsw + _i * 8192), 16, 0, 0); } while (0)
; #define PG8_LDA(dst, b, h) do { _Pragma("unroll") for (int m = 0; m < 4; ++m) _Pragma("unroll") for (int k = 0; k < 2; ++k) dst[m][k] = *(const LAS bf16x8*)(lds + PG8_SA(b, h) + aoff + m * 2048 + k * 1024); } while (0)
; #define PG8_LDB(dst, b, h) do { _Pragma("unroll") for (int n = 0; n < 2; ++n) _Pragma("unroll") for (int k = 0; k < 2; ++k) dst[n][k] = *(const LAS bf16x8*)(lds + PG8_SB(b, h) + boff + n * 2048 + k * 1024); } while (0)
; #define PG8_MMA(ai, bj, At, Bt) do { __builtin_amdgcn_s_setprio(1); _Pragma("unroll") for (int m = 0; m < 4; ++m) _Pragma("unroll") for (int n = 0; n < 2; ++n) _Pragma("unroll") for (int k = 0; k < 2; ++k) \
;         acc[ai][bj][m][n] = __builtin_amdgcn_mfma_f32_16x16x32_bf16(Bt[n][k], At[m][k], acc[ai][bj][m][n], 0, 0, 0); __builtin_amdgcn_s_setprio(0); } while (0)
; #define PG8_WAIT_V(n) asm volatile("s_waitcnt vmcnt(" #n ")" ::: "memory")
; #define PG8_WAIT_L(n) asm volatile("s_waitcnt lgkmcnt(" #n ")" ::: "memory")
; #define PG8_BAR __builtin_amdgcn_s_barrier()
; #define PG8_SCHED __builtin_amdgcn_sched_barrier(0)
; template <class Epi, class Sched>
; __device__ __forceinline__ void gemm_phase(LAS unsigned char* lds, const Gemm g, const Sched& S, const Epi& E) {
;     ...
;             PG8_STAGE(PG8_SB(0, 1), b2 + hstep, voffB);
;             PG8_WAIT_V(6); PG8_BAR; PG8_MMA(1, 1, At, B1); PG8_BAR;
;             PG8_LDB(B0, 1, 0); PG8_SCHED; PG8_LDA(At, 1, 0); PG8_STAGE(PG8_SA(0, 1), a2 + hstep, voffA);
;             PG8_WAIT_L(8); PG8_BAR; PG8_WAIT_L(0); PG8_MMA(0, 0, At, B0); PG8_BAR; PG8_SCHED;
;             PG8_LDB(B1, 1, 1); PG8_STAGE(PG8_SB(1, 0), b3, voffB);
;             PG8_BAR; PG8_WAIT_L(0); PG8_MMA(0, 1, At, B1); PG8_BAR;
;             PG8_LDA(At, 1, 1); PG8_STAGE(PG8_SA(1, 0), a3, voffA);
;             PG8_BAR; PG8_WAIT_L(0); PG8_MMA(1, 0, At, B0); PG8_BAR; PG8_SCHED;
	s_setprio 0
	s_add_u32 s68, s4, 0x40000
	s_addc_u32 s69, s5, 0
	s_add_i32 s70, s58, s44
	s_mov_b32 m0, s70
	s_nop 0
	global_load_lds_dwordx4 v130, s[68:69]
	s_add_i32 m0, s70, 0x2000
	s_nop 0
	global_load_lds_dwordx4 v134, s[68:69]
	s_add_u32 s6, s6, 0x40000
	s_addc_u32 s7, s7, 0
	s_mov_b32 m0, s47
	s_nop 0
	global_load_lds_dwordx4 v128, s[6:7]
	s_mov_b32 m0, s48
	s_nop 0
	global_load_lds_dwordx4 v132, s[6:7]
	s_waitcnt vmcnt(10)
	s_setprio 1
	s_barrier
	v_mfma_f32_16x16x32_bf16 v[52:55], v[210:213], v[162:165], 0
	v_mfma_f32_16x16x32_bf16 v[48:51], v[218:221], v[162:165], 0
	v_mfma_f32_16x16x32_bf16 v[36:39], v[210:213], v[182:185], 0
	v_mfma_f32_16x16x32_bf16 v[32:35], v[218:221], v[182:185], 0
	v_mfma_f32_16x16x32_bf16 v[20:23], v[210:213], v[190:193], 0
	v_mfma_f32_16x16x32_bf16 v[16:19], v[218:221], v[190:193], 0
	v_mfma_f32_16x16x32_bf16 v[4:7], v[210:213], v[202:205], 0
	v_mfma_f32_16x16x32_bf16 v[0:3], v[218:221], v[202:205], 0
	v_mfma_f32_16x16x32_bf16 v[52:55], v[214:217], v[178:181], v[52:55]
	v_mfma_f32_16x16x32_bf16 v[48:51], v[222:225], v[178:181], v[48:51]
	v_mfma_f32_16x16x32_bf16 v[36:39], v[214:217], v[186:189], v[36:39]
	v_mfma_f32_16x16x32_bf16 v[32:35], v[222:225], v[186:189], v[32:35]
	v_mfma_f32_16x16x32_bf16 v[20:23], v[214:217], v[194:197], v[20:23]
	v_mfma_f32_16x16x32_bf16 v[16:19], v[222:225], v[194:197], v[16:19]
	v_mfma_f32_16x16x32_bf16 v[4:7], v[214:217], v[206:209], v[4:7]
	v_mfma_f32_16x16x32_bf16 v[0:3], v[222:225], v[206:209], v[0:3]
	s_barrier
	s_setprio 0
	s_add_i32 s68, 0, 0x18000
	ds_read_b128 v[146:149], v173 offset:16384
	ds_read_b128 v[150:153], v173 offset:17408
	ds_read_b128 v[154:157], v173 offset:18432
	ds_read_b128 v[158:161], v173 offset:19456
	ds_read_b128 v[162:165], v172 offset:32768
	ds_read_b128 v[178:181], v172 offset:33792
	ds_read_b128 v[182:185], v172 offset:34816
	ds_read_b128 v[186:189], v172 offset:35840
	ds_read_b128 v[190:193], v172 offset:36864
	ds_read_b128 v[194:197], v172 offset:37888
	ds_read_b128 v[202:205], v172 offset:38912
	ds_read_b128 v[206:209], v172 offset:39936
	s_waitcnt lgkmcnt(8)
	s_waitcnt vmcnt(8)
	s_setprio 1
	s_barrier
	s_waitcnt lgkmcnt(0)
	v_mfma_f32_16x16x32_bf16 v[124:127], v[146:149], v[162:165], v[124:127]
	v_mfma_f32_16x16x32_bf16 v[120:123], v[154:157], v[162:165], v[120:123]
	v_mfma_f32_16x16x32_bf16 v[108:111], v[146:149], v[182:185], v[108:111]
	v_mfma_f32_16x16x32_bf16 v[104:107], v[154:157], v[182:185], v[104:107]
	v_mfma_f32_16x16x32_bf16 v[92:95], v[146:149], v[190:193], v[92:95]
	v_mfma_f32_16x16x32_bf16 v[88:91], v[154:157], v[190:193], v[88:91]
	v_mfma_f32_16x16x32_bf16 v[76:79], v[146:149], v[202:205], v[76:79]
	v_mfma_f32_16x16x32_bf16 v[72:75], v[154:157], v[202:205], v[72:75]
	v_mfma_f32_16x16x32_bf16 v[124:127], v[150:153], v[178:181], v[124:127]
	v_mfma_f32_16x16x32_bf16 v[120:123], v[158:161], v[178:181], v[120:123]
	v_mfma_f32_16x16x32_bf16 v[108:111], v[150:153], v[186:189], v[108:111]
	v_mfma_f32_16x16x32_bf16 v[104:107], v[158:161], v[186:189], v[104:107]
	v_mfma_f32_16x16x32_bf16 v[92:95], v[150:153], v[194:197], v[92:95]
	v_mfma_f32_16x16x32_bf16 v[88:91], v[158:161], v[194:197], v[88:91]
	v_mfma_f32_16x16x32_bf16 v[76:79], v[150:153], v[206:209], v[76:79]
	v_mfma_f32_16x16x32_bf16 v[72:75], v[158:161], v[206:209], v[72:75]
	s_barrier
	s_setprio 0
	s_add_i32 s6, 0, 0x1c000
	s_add_i32 s7, s68, s44
	v_add_u32_e32 v136, s6, v170
	s_add_u32 s20, s4, 0x80
	s_addc_u32 s21, s5, 0
	s_mov_b32 m0, s7
	ds_read_b128 v[210:213], v136
	ds_read_b128 v[214:217], v136 offset:1024
	ds_read_b128 v[218:221], v136 offset:2048
	ds_read_b128 v[222:225], v136 offset:3072
	global_load_lds_dwordx4 v130, s[20:21]
	s_add_i32 m0, s7, 0x2000
	s_nop 0
	global_load_lds_dwordx4 v134, s[20:21]
	s_waitcnt vmcnt(8)
	s_setprio 1
	s_barrier
	s_waitcnt lgkmcnt(0)
	v_mfma_f32_16x16x32_bf16 v[116:119], v[210:213], v[162:165], v[116:119]
	v_mfma_f32_16x16x32_bf16 v[112:115], v[218:221], v[162:165], v[112:115]
	v_mfma_f32_16x16x32_bf16 v[100:103], v[210:213], v[182:185], v[100:103]
	v_mfma_f32_16x16x32_bf16 v[96:99], v[218:221], v[182:185], v[96:99]
	v_mfma_f32_16x16x32_bf16 v[84:87], v[210:213], v[190:193], v[84:87]
	v_mfma_f32_16x16x32_bf16 v[80:83], v[218:221], v[190:193], v[80:83]
	v_mfma_f32_16x16x32_bf16 v[68:71], v[210:213], v[202:205], v[68:71]
	v_mfma_f32_16x16x32_bf16 v[64:67], v[218:221], v[202:205], v[64:67]
	v_mfma_f32_16x16x32_bf16 v[116:119], v[214:217], v[178:181], v[116:119]
	v_mfma_f32_16x16x32_bf16 v[112:115], v[222:225], v[178:181], v[112:115]
	v_mfma_f32_16x16x32_bf16 v[100:103], v[214:217], v[186:189], v[100:103]
	v_mfma_f32_16x16x32_bf16 v[96:99], v[222:225], v[186:189], v[96:99]
	v_mfma_f32_16x16x32_bf16 v[84:87], v[214:217], v[194:197], v[84:87]
	v_mfma_f32_16x16x32_bf16 v[80:83], v[222:225], v[194:197], v[80:83]
	v_mfma_f32_16x16x32_bf16 v[68:71], v[214:217], v[206:209], v[68:71]
	v_mfma_f32_16x16x32_bf16 v[64:67], v[222:225], v[206:209], v[64:67]
	s_barrier
	s_setprio 0
	s_mov_b32 m0, s54
	s_mov_b64 s[20:21], 0x80
	v_lshl_add_u64 v[166:167], v[226:227], 0, s[20:21]
	ds_read_b128 v[162:165], v172 offset:49152
	ds_read_b128 v[178:181], v172 offset:50176
	ds_read_b128 v[182:185], v172 offset:51200
	ds_read_b128 v[186:189], v172 offset:52224
	ds_read_b128 v[190:193], v172 offset:53248
	ds_read_b128 v[194:197], v172 offset:54272
	ds_read_b128 v[202:205], v172 offset:55296
	ds_read_b128 v[206:209], v172 offset:56320
	global_load_lds_dwordx4 v[166:167], off
	v_lshl_add_u64 v[166:167], v[228:229], 0, s[20:21]
	s_mov_b32 m0, s55
	s_nop 0
	global_load_lds_dwordx4 v[166:167], off
	s_setprio 1
	s_barrier
; #define PG8_STAGE(bufoff, gbase, voff) do { _Pragma("unroll") for (int _i = 0; _i < 2; ++_i) \
;         __builtin_amdgcn_global_load_lds((const unsigned*)((const char*)(gbase) + (voff)[_i]), (LAS unsigned*)(lds + (bufoff) + ldsw + _i * 8192), 16, 0, 0); } while (0)
; #define PG8_LDA(dst, b, h) do { _Pragma("unroll") for (int m = 0; m < 4; ++m) _Pragma("unroll") for (int k = 0; k < 2; ++k) dst[m][k] = *(const LAS bf16x8*)(lds + PG8_SA(b, h) + aoff + m * 2048 + k * 1024); } while (0)
; #define PG8_LDB(dst, b, h) do { _Pragma("unroll") for (int n = 0; n < 2; ++n) _Pragma("unroll") for (int k = 0; k < 2; ++k) dst[n][k] = *(const LAS bf16x8*)(lds + PG8_SB(b, h) + boff + n * 2048 + k * 1024); } while (0)
; #define PG8_MMA(ai, bj, At, Bt) do { __builtin_amdgcn_s_setprio(1); _Pragma("unroll") for (int m = 0; m < 4; ++m) _Pragma("unroll") for (int n = 0; n < 2; ++n) _Pragma("unroll") for (int k = 0; k < 2; ++k) \
;         acc[ai][bj][m][n] = __builtin_amdgcn_mfma_f32_16x16x32_bf16(Bt[n][k], At[m][k], acc[ai][bj][m][n], 0, 0, 0); __builtin_amdgcn_s_setprio(0); } while (0)
; #define PG8_WAIT_V(n) asm volatile("s_waitcnt vmcnt(" #n ")" ::: "memory")
; #define PG8_WAIT_L(n) asm volatile("s_waitcnt lgkmcnt(" #n ")" ::: "memory")
; #define PG8_BAR __builtin_amdgcn_s_barrier()
; #define PG8_SCHED __builtin_amdgcn_sched_barrier(0)
; template <class Epi, class Sched>
; __device__ __forceinline__ void gemm_phase(LAS unsigned char* lds, const Gemm g, const Sched& S, const Epi& E) {
;     ...
;             PG8_LDB(B0, 0, 0); PG8_SCHED; PG8_LDA(At, 0, 0); PG8_STAGE(PG8_SA(1, 1), a1 + hstep, voffA);
;             PG8_WAIT_L(8); PG8_BAR; PG8_WAIT_L(0); PG8_MMA(0, 0, At, B0); PG8_BAR; PG8_SCHED;
;             PG8_LDB(B1, 0, 1); PG8_STAGE(PG8_SB(0, 0), b2, voffB);
;             PG8_BAR; PG8_WAIT_L(0); PG8_MMA(0, 1, At, B1); PG8_BAR;
;             PG8_LDA(At, 0, 1); PG8_STAGE(PG8_SA(0, 0), a2, voffA);
;             PG8_BAR; PG8_WAIT_L(0); PG8_MMA(1, 0, At, B0); PG8_BAR; PG8_SCHED;
;     ...
;             PG8_BAR; PG8_WAIT_L(0); PG8_MMA(1, 0, At, B0); PG8_BAR; PG8_SCHED;
;             PG8_STAGE(PG8_SB(1, 1), b3 + hstep, voffB);
;             PG8_WAIT_V(6); PG8_BAR; PG8_MMA(1, 1, At, B1); PG8_BAR;
;         }
	s_waitcnt lgkmcnt(0)
	v_mfma_f32_16x16x32_bf16 v[60:63], v[146:149], v[162:165], v[60:63]
	v_mfma_f32_16x16x32_bf16 v[56:59], v[154:157], v[162:165], v[56:59]
	v_mfma_f32_16x16x32_bf16 v[44:47], v[146:149], v[182:185], v[44:47]
	v_mfma_f32_16x16x32_bf16 v[40:43], v[154:157], v[182:185], v[40:43]
	v_mfma_f32_16x16x32_bf16 v[28:31], v[146:149], v[190:193], v[28:31]
	v_mfma_f32_16x16x32_bf16 v[24:27], v[154:157], v[190:193], v[24:27]
	v_mfma_f32_16x16x32_bf16 v[12:15], v[146:149], v[202:205], v[12:15]
	v_mfma_f32_16x16x32_bf16 v[8:11], v[154:157], v[202:205], v[8:11]
	v_mfma_f32_16x16x32_bf16 v[60:63], v[150:153], v[178:181], v[60:63]
	v_mfma_f32_16x16x32_bf16 v[56:59], v[158:161], v[178:181], v[56:59]
	v_mfma_f32_16x16x32_bf16 v[44:47], v[150:153], v[186:189], v[44:47]
	v_mfma_f32_16x16x32_bf16 v[40:43], v[158:161], v[186:189], v[40:43]
	v_mfma_f32_16x16x32_bf16 v[28:31], v[150:153], v[194:197], v[28:31]
	v_mfma_f32_16x16x32_bf16 v[24:27], v[158:161], v[194:197], v[24:27]
	v_mfma_f32_16x16x32_bf16 v[12:15], v[150:153], v[206:209], v[12:15]
	v_mfma_f32_16x16x32_bf16 v[8:11], v[158:161], v[206:209], v[8:11]
	s_barrier
	s_setprio 0
	s_add_u32 s4, s4, 0x40080
	s_addc_u32 s5, s5, 0
	s_add_i32 s6, s6, s44
	s_mov_b32 m0, s6
	s_nop 0
	global_load_lds_dwordx4 v130, s[4:5]
	s_add_i32 m0, s6, 0x2000
	s_nop 0
	global_load_lds_dwordx4 v134, s[4:5]
	s_waitcnt vmcnt(8)
	s_setprio 1
	s_barrier
	v_mfma_f32_16x16x32_bf16 v[52:55], v[210:213], v[162:165], v[52:55]
	v_mfma_f32_16x16x32_bf16 v[48:51], v[218:221], v[162:165], v[48:51]
	v_mfma_f32_16x16x32_bf16 v[36:39], v[210:213], v[182:185], v[36:39]
	v_mfma_f32_16x16x32_bf16 v[32:35], v[218:221], v[182:185], v[32:35]
	v_mfma_f32_16x16x32_bf16 v[20:23], v[210:213], v[190:193], v[20:23]
	v_mfma_f32_16x16x32_bf16 v[16:19], v[218:221], v[190:193], v[16:19]
	v_mfma_f32_16x16x32_bf16 v[4:7], v[210:213], v[202:205], v[4:7]
	v_mfma_f32_16x16x32_bf16 v[0:3], v[218:221], v[202:205], v[0:3]
	v_mfma_f32_16x16x32_bf16 v[52:55], v[214:217], v[178:181], v[52:55]
	v_mfma_f32_16x16x32_bf16 v[48:51], v[222:225], v[178:181], v[48:51]
	v_mfma_f32_16x16x32_bf16 v[36:39], v[214:217], v[186:189], v[36:39]
	v_mfma_f32_16x16x32_bf16 v[32:35], v[222:225], v[186:189], v[32:35]
	v_mfma_f32_16x16x32_bf16 v[20:23], v[214:217], v[194:197], v[20:23]
	v_mfma_f32_16x16x32_bf16 v[16:19], v[222:225], v[194:197], v[16:19]
	v_mfma_f32_16x16x32_bf16 v[4:7], v[214:217], v[206:209], v[4:7]
	v_mfma_f32_16x16x32_bf16 v[0:3], v[222:225], v[206:209], v[0:3]
	s_barrier
	s_setprio 0
	s_add_i32 s67, s67, 2
	s_add_u32 s0, s0, 0x100
	s_addc_u32 s1, s1, 0
	s_add_u32 s65, s65, 0x100
	s_addc_u32 s66, s66, 0
	s_cmp_gt_u32 s67, 13
.LBB0_613:
	ds_read_b128 v[146:149], v171
	ds_read_b128 v[150:153], v171 offset:1024
	ds_read_b128 v[154:157], v171 offset:2048
	ds_read_b128 v[158:161], v171 offset:3072
	s_add_u32 s4, s0, 0xfffc0080
	s_addc_u32 s5, s1, -1
	s_cmp_eq_u32 s67, 12
	s_cselect_b32 s7, s8, s5
	s_cselect_b32 s6, s9, s4
	s_cselect_b32 s5, s31, s66
	s_cselect_b32 s4, s35, s65
	s_add_i32 m0, s45, 0xc000
	ds_read_b128 v[162:165], v172
	ds_read_b128 v[178:181], v172 offset:1024
	ds_read_b128 v[182:185], v172 offset:2048
	ds_read_b128 v[186:189], v172 offset:3072
	ds_read_b128 v[190:193], v172 offset:4096
	ds_read_b128 v[194:197], v172 offset:5120
	ds_read_b128 v[202:205], v172 offset:6144
	ds_read_b128 v[206:209], v172 offset:7168
	global_load_lds_dwordx4 v138, s[0:1]
	s_add_i32 m0, s45, 0xe000
	s_nop 0
	global_load_lds_dwordx4 v140, s[0:1]
	s_waitcnt lgkmcnt(8)
	s_waitcnt vmcnt(8)
	s_setprio 1
	s_barrier
	s_waitcnt lgkmcnt(0)
	v_mfma_f32_16x16x32_bf16 v[124:127], v[146:149], v[162:165], v[124:127]
	v_mfma_f32_16x16x32_bf16 v[120:123], v[154:157], v[162:165], v[120:123]
	v_mfma_f32_16x16x32_bf16 v[108:111], v[146:149], v[182:185], v[108:111]
	v_mfma_f32_16x16x32_bf16 v[104:107], v[154:157], v[182:185], v[104:107]
	v_mfma_f32_16x16x32_bf16 v[92:95], v[146:149], v[190:193], v[92:95]
	v_mfma_f32_16x16x32_bf16 v[88:91], v[154:157], v[190:193], v[88:91]
	v_mfma_f32_16x16x32_bf16 v[76:79], v[146:149], v[202:205], v[76:79]
	v_mfma_f32_16x16x32_bf16 v[72:75], v[154:157], v[202:205], v[72:75]
	v_mfma_f32_16x16x32_bf16 v[124:127], v[150:153], v[178:181], v[124:127]
	v_mfma_f32_16x16x32_bf16 v[120:123], v[158:161], v[178:181], v[120:123]
	v_mfma_f32_16x16x32_bf16 v[108:111], v[150:153], v[186:189], v[108:111]
	v_mfma_f32_16x16x32_bf16 v[104:107], v[158:161], v[186:189], v[104:107]
	v_mfma_f32_16x16x32_bf16 v[92:95], v[150:153], v[194:197], v[92:95]
	v_mfma_f32_16x16x32_bf16 v[88:91], v[158:161], v[194:197], v[88:91]
	v_mfma_f32_16x16x32_bf16 v[76:79], v[150:153], v[206:209], v[76:79]
	v_mfma_f32_16x16x32_bf16 v[72:75], v[158:161], v[206:209], v[72:75]
	s_barrier
	s_setprio 0
	s_add_i32 s68, s57, s44
	s_mov_b32 m0, s68
	ds_read_b128 v[210:213], v173
	ds_read_b128 v[214:217], v173 offset:1024
	ds_read_b128 v[218:221], v173 offset:2048
	ds_read_b128 v[222:225], v173 offset:3072
	global_load_lds_dwordx4 v130, s[4:5]
	s_add_i32 m0, s68, 0x2000
	s_nop 0
	global_load_lds_dwordx4 v134, s[4:5]
	s_waitcnt vmcnt(8)
	s_setprio 1
	s_barrier
; #define PG8_STAGE(bufoff, gbase, voff) do { _Pragma("unroll") for (int _i = 0; _i < 2; ++_i) \
;         __builtin_amdgcn_global_load_lds((const unsigned*)((const char*)(gbase) + (voff)[_i]), (LAS unsigned*)(lds + (bufoff) + ldsw + _i * 8192), 16, 0, 0); } while (0)
; #define PG8_LDA(dst, b, h) do { _Pragma("unroll") for (int m = 0; m < 4; ++m) _Pragma("unroll") for (int k = 0; k < 2; ++k) dst[m][k] = *(const LAS bf16x8*)(lds + PG8_SA(b, h) + aoff + m * 2048 + k * 1024); } while (0)
; #define PG8_LDB(dst, b, h) do { _Pragma("unroll") for (int n = 0; n < 2; ++n) _Pragma("unroll") for (int k = 0; k < 2; ++k) dst[n][k] = *(const LAS bf16x8*)(lds + PG8_SB(b, h) + boff + n * 2048 + k * 1024); } while (0)
; #define PG8_MMA(ai, bj, At, Bt) do { __builtin_amdgcn_s_setprio(1); _Pragma("unroll") for (int m = 0; m < 4; ++m) _Pragma("unroll") for (int n = 0; n < 2; ++n) _Pragma("unroll") for (int k = 0; k < 2; ++k) \
;         acc[ai][bj][m][n] = __builtin_amdgcn_mfma_f32_16x16x32_bf16(Bt[n][k], At[m][k], acc[ai][bj][m][n], 0, 0, 0); __builtin_amdgcn_s_setprio(0); } while (0)
; #define PG8_WAIT_V(n) asm volatile("s_waitcnt vmcnt(" #n ")" ::: "memory")
; #define PG8_WAIT_L(n) asm volatile("s_waitcnt lgkmcnt(" #n ")" ::: "memory")
; #define PG8_BAR __builtin_amdgcn_s_barrier()
; #define PG8_SCHED __builtin_amdgcn_sched_barrier(0)
; template <class Epi, class Sched>
; __device__ __forceinline__ void gemm_phase(LAS unsigned char* lds, const Gemm g, const Sched& S, const Epi& E) {
;     ...
;             PG8_BAR; PG8_WAIT_L(0); PG8_MMA(1, 0, At, B0); PG8_BAR; PG8_SCHED;
;             PG8_STAGE(PG8_SB(0, 1), b2 + hstep, voffB);
;             PG8_WAIT_V(6); PG8_BAR; PG8_MMA(1, 1, At, B1); PG8_BAR;
;             PG8_LDB(B0, 1, 0); PG8_SCHED; PG8_LDA(At, 1, 0); PG8_STAGE(PG8_SA(0, 1), a2 + hstep, voffA);
;             PG8_WAIT_L(8); PG8_BAR; PG8_WAIT_L(0); PG8_MMA(0, 0, At, B0); PG8_BAR; PG8_SCHED;
	s_waitcnt lgkmcnt(0)
	v_mfma_f32_16x16x32_bf16 v[116:119], v[210:213], v[162:165], v[116:119]
	v_mfma_f32_16x16x32_bf16 v[112:115], v[218:221], v[162:165], v[112:115]
	v_mfma_f32_16x16x32_bf16 v[100:103], v[210:213], v[182:185], v[100:103]
	v_mfma_f32_16x16x32_bf16 v[96:99], v[218:221], v[182:185], v[96:99]
	v_mfma_f32_16x16x32_bf16 v[84:87], v[210:213], v[190:193], v[84:87]
	v_mfma_f32_16x16x32_bf16 v[80:83], v[218:221], v[190:193], v[80:83]
	v_mfma_f32_16x16x32_bf16 v[68:71], v[210:213], v[202:205], v[68:71]
	v_mfma_f32_16x16x32_bf16 v[64:67], v[218:221], v[202:205], v[64:67]
	v_mfma_f32_16x16x32_bf16 v[116:119], v[214:217], v[178:181], v[116:119]
	v_mfma_f32_16x16x32_bf16 v[112:115], v[222:225], v[178:181], v[112:115]
	v_mfma_f32_16x16x32_bf16 v[100:103], v[214:217], v[186:189], v[100:103]
	v_mfma_f32_16x16x32_bf16 v[96:99], v[222:225], v[186:189], v[96:99]
	v_mfma_f32_16x16x32_bf16 v[84:87], v[214:217], v[194:197], v[84:87]
	v_mfma_f32_16x16x32_bf16 v[80:83], v[222:225], v[194:197], v[80:83]
	v_mfma_f32_16x16x32_bf16 v[68:71], v[214:217], v[206:209], v[68:71]
	v_mfma_f32_16x16x32_bf16 v[64:67], v[222:225], v[206:209], v[64:67]
	s_barrier
	s_setprio 0
	s_mov_b32 m0, s45
	v_lshl_add_u64 v[226:227], s[6:7], 0, v[128:129]
	ds_read_b128 v[162:165], v172 offset:16384
	ds_read_b128 v[178:181], v172 offset:17408
	ds_read_b128 v[182:185], v172 offset:18432
	ds_read_b128 v[186:189], v172 offset:19456
	ds_read_b128 v[190:193], v172 offset:20480
	ds_read_b128 v[194:197], v172 offset:21504
	ds_read_b128 v[202:205], v172 offset:22528
	ds_read_b128 v[206:209], v172 offset:23552
	global_load_lds_dwordx4 v128, s[6:7]
	v_lshl_add_u64 v[228:229], s[6:7], 0, v[132:133]
	s_mov_b32 m0, s46
	s_nop 0
	global_load_lds_dwordx4 v132, s[6:7]
	s_setprio 1
	s_barrier
	s_waitcnt lgkmcnt(0)
	v_mfma_f32_16x16x32_bf16 v[60:63], v[146:149], v[162:165], v[60:63]
	v_mfma_f32_16x16x32_bf16 v[56:59], v[154:157], v[162:165], v[56:59]
	v_mfma_f32_16x16x32_bf16 v[44:47], v[146:149], v[182:185], v[44:47]
	v_mfma_f32_16x16x32_bf16 v[40:43], v[154:157], v[182:185], v[40:43]
	v_mfma_f32_16x16x32_bf16 v[28:31], v[146:149], v[190:193], v[28:31]
	v_mfma_f32_16x16x32_bf16 v[24:27], v[154:157], v[190:193], v[24:27]
	v_mfma_f32_16x16x32_bf16 v[12:15], v[146:149], v[202:205], v[12:15]
	v_mfma_f32_16x16x32_bf16 v[8:11], v[154:157], v[202:205], v[8:11]
	v_mfma_f32_16x16x32_bf16 v[60:63], v[150:153], v[178:181], v[60:63]
	v_mfma_f32_16x16x32_bf16 v[56:59], v[158:161], v[178:181], v[56:59]
	v_mfma_f32_16x16x32_bf16 v[44:47], v[150:153], v[186:189], v[44:47]
	v_mfma_f32_16x16x32_bf16 v[40:43], v[158:161], v[186:189], v[40:43]
	v_mfma_f32_16x16x32_bf16 v[28:31], v[150:153], v[194:197], v[28:31]
	v_mfma_f32_16x16x32_bf16 v[24:27], v[158:161], v[194:197], v[24:27]
	v_mfma_f32_16x16x32_bf16 v[12:15], v[150:153], v[206:209], v[12:15]
	v_mfma_f32_16x16x32_bf16 v[8:11], v[158:161], v[206:209], v[8:11]
	s_barrier
	s_setprio 0
	s_add_u32 s68, s4, 0x40000
	s_addc_u32 s69, s5, 0
	s_add_i32 s70, s58, s44
	s_mov_b32 m0, s70
	s_nop 0
	global_load_lds_dwordx4 v130, s[68:69]
	s_add_i32 m0, s70, 0x2000
	s_nop 0
	global_load_lds_dwordx4 v134, s[68:69]
	s_add_u32 s6, s6, 0x40000
	s_addc_u32 s7, s7, 0
	s_mov_b32 m0, s47
	s_nop 0
	global_load_lds_dwordx4 v128, s[6:7]
	s_mov_b32 m0, s48
	s_nop 0
	global_load_lds_dwordx4 v132, s[6:7]
	s_waitcnt vmcnt(10)
	s_setprio 1
	s_barrier
	v_mfma_f32_16x16x32_bf16 v[52:55], v[210:213], v[162:165], v[52:55]
	v_mfma_f32_16x16x32_bf16 v[48:51], v[218:221], v[162:165], v[48:51]
	v_mfma_f32_16x16x32_bf16 v[36:39], v[210:213], v[182:185], v[36:39]
	v_mfma_f32_16x16x32_bf16 v[32:35], v[218:221], v[182:185], v[32:35]
	v_mfma_f32_16x16x32_bf16 v[20:23], v[210:213], v[190:193], v[20:23]
	v_mfma_f32_16x16x32_bf16 v[16:19], v[218:221], v[190:193], v[16:19]
	v_mfma_f32_16x16x32_bf16 v[4:7], v[210:213], v[202:205], v[4:7]
	v_mfma_f32_16x16x32_bf16 v[0:3], v[218:221], v[202:205], v[0:3]
	v_mfma_f32_16x16x32_bf16 v[52:55], v[214:217], v[178:181], v[52:55]
	v_mfma_f32_16x16x32_bf16 v[48:51], v[222:225], v[178:181], v[48:51]
	v_mfma_f32_16x16x32_bf16 v[36:39], v[214:217], v[186:189], v[36:39]
	v_mfma_f32_16x16x32_bf16 v[32:35], v[222:225], v[186:189], v[32:35]
	v_mfma_f32_16x16x32_bf16 v[20:23], v[214:217], v[194:197], v[20:23]
	v_mfma_f32_16x16x32_bf16 v[16:19], v[222:225], v[194:197], v[16:19]
	v_mfma_f32_16x16x32_bf16 v[4:7], v[214:217], v[206:209], v[4:7]
	v_mfma_f32_16x16x32_bf16 v[0:3], v[222:225], v[206:209], v[0:3]
	s_barrier
	s_setprio 0
	s_add_i32 s68, 0, 0x18000
	ds_read_b128 v[146:149], v173 offset:16384
	ds_read_b128 v[150:153], v173 offset:17408
	ds_read_b128 v[154:157], v173 offset:18432
	ds_read_b128 v[158:161], v173 offset:19456
	ds_read_b128 v[162:165], v172 offset:32768
	ds_read_b128 v[178:181], v172 offset:33792
	ds_read_b128 v[182:185], v172 offset:34816
	ds_read_b128 v[186:189], v172 offset:35840
	ds_read_b128 v[190:193], v172 offset:36864
	ds_read_b128 v[194:197], v172 offset:37888
	ds_read_b128 v[202:205], v172 offset:38912
	ds_read_b128 v[206:209], v172 offset:39936
	s_waitcnt lgkmcnt(8)
	s_waitcnt vmcnt(8)
	s_setprio 1
	s_barrier
; #define PG8_STAGE(bufoff, gbase, voff) do { _Pragma("unroll") for (int _i = 0; _i < 2; ++_i) \
;         __builtin_amdgcn_global_load_lds((const unsigned*)((const char*)(gbase) + (voff)[_i]), (LAS unsigned*)(lds + (bufoff) + ldsw + _i * 8192), 16, 0, 0); } while (0)
; #define PG8_LDA(dst, b, h) do { _Pragma("unroll") for (int m = 0; m < 4; ++m) _Pragma("unroll") for (int k = 0; k < 2; ++k) dst[m][k] = *(const LAS bf16x8*)(lds + PG8_SA(b, h) + aoff + m * 2048 + k * 1024); } while (0)
; #define PG8_LDB(dst, b, h) do { _Pragma("unroll") for (int n = 0; n < 2; ++n) _Pragma("unroll") for (int k = 0; k < 2; ++k) dst[n][k] = *(const LAS bf16x8*)(lds + PG8_SB(b, h) + boff + n * 2048 + k * 1024); } while (0)
; #define PG8_MMA(ai, bj, At, Bt) do { __builtin_amdgcn_s_setprio(1); _Pragma("unroll") for (int m = 0; m < 4; ++m) _Pragma("unroll") for (int n = 0; n < 2; ++n) _Pragma("unroll") for (int k = 0; k < 2; ++k) \
;         acc[ai][bj][m][n] = __builtin_amdgcn_mfma_f32_16x16x32_bf16(Bt[n][k], At[m][k], acc[ai][bj][m][n], 0, 0, 0); __builtin_amdgcn_s_setprio(0); } while (0)
; #define PG8_WAIT_V(n) asm volatile("s_waitcnt vmcnt(" #n ")" ::: "memory")
; #define PG8_WAIT_L(n) asm volatile("s_waitcnt lgkmcnt(" #n ")" ::: "memory")
; #define PG8_BAR __builtin_amdgcn_s_barrier()
; #define PG8_SCHED __builtin_amdgcn_sched_barrier(0)
; template <class Epi, class Sched>
; __device__ __forceinline__ void gemm_phase(LAS unsigned char* lds, const Gemm g, const Sched& S, const Epi& E) {
;     ...
;             PG8_WAIT_L(8); PG8_BAR; PG8_WAIT_L(0); PG8_MMA(0, 0, At, B0); PG8_BAR; PG8_SCHED;
;             PG8_LDB(B1, 1, 1); PG8_STAGE(PG8_SB(1, 0), b3, voffB);
;             PG8_BAR; PG8_WAIT_L(0); PG8_MMA(0, 1, At, B1); PG8_BAR;
;             PG8_LDA(At, 1, 1); PG8_STAGE(PG8_SA(1, 0), a3, voffA);
;             PG8_BAR; PG8_WAIT_L(0); PG8_MMA(1, 0, At, B0); PG8_BAR; PG8_SCHED;
;             PG8_STAGE(PG8_SB(1, 1), b3 + hstep, voffB);
;             PG8_WAIT_V(6); PG8_BAR; PG8_MMA(1, 1, At, B1); PG8_BAR;
	s_waitcnt lgkmcnt(0)
	v_mfma_f32_16x16x32_bf16 v[124:127], v[146:149], v[162:165], v[124:127]
	v_mfma_f32_16x16x32_bf16 v[120:123], v[154:157], v[162:165], v[120:123]
	v_mfma_f32_16x16x32_bf16 v[108:111], v[146:149], v[182:185], v[108:111]
	v_mfma_f32_16x16x32_bf16 v[104:107], v[154:157], v[182:185], v[104:107]
	v_mfma_f32_16x16x32_bf16 v[92:95], v[146:149], v[190:193], v[92:95]
	v_mfma_f32_16x16x32_bf16 v[88:91], v[154:157], v[190:193], v[88:91]
	v_mfma_f32_16x16x32_bf16 v[76:79], v[146:149], v[202:205], v[76:79]
	v_mfma_f32_16x16x32_bf16 v[72:75], v[154:157], v[202:205], v[72:75]
	v_mfma_f32_16x16x32_bf16 v[124:127], v[150:153], v[178:181], v[124:127]
	v_mfma_f32_16x16x32_bf16 v[120:123], v[158:161], v[178:181], v[120:123]
	v_mfma_f32_16x16x32_bf16 v[108:111], v[150:153], v[186:189], v[108:111]
	v_mfma_f32_16x16x32_bf16 v[104:107], v[158:161], v[186:189], v[104:107]
	v_mfma_f32_16x16x32_bf16 v[92:95], v[150:153], v[194:197], v[92:95]
	v_mfma_f32_16x16x32_bf16 v[88:91], v[158:161], v[194:197], v[88:91]
	v_mfma_f32_16x16x32_bf16 v[76:79], v[150:153], v[206:209], v[76:79]
	v_mfma_f32_16x16x32_bf16 v[72:75], v[158:161], v[206:209], v[72:75]
	s_barrier
	s_setprio 0
	s_add_i32 s6, 0, 0x1c000
	s_add_i32 s7, s68, s44
	v_add_u32_e32 v136, s6, v170
	s_add_u32 s20, s4, 0x80
	s_addc_u32 s21, s5, 0
	s_mov_b32 m0, s7
	ds_read_b128 v[210:213], v136
	ds_read_b128 v[214:217], v136 offset:1024
	ds_read_b128 v[218:221], v136 offset:2048
	ds_read_b128 v[222:225], v136 offset:3072
	global_load_lds_dwordx4 v130, s[20:21]
	s_add_i32 m0, s7, 0x2000
	s_nop 0
	global_load_lds_dwordx4 v134, s[20:21]
	s_waitcnt vmcnt(8)
	s_setprio 1
	s_barrier
	s_waitcnt lgkmcnt(0)
	v_mfma_f32_16x16x32_bf16 v[116:119], v[210:213], v[162:165], v[116:119]
	v_mfma_f32_16x16x32_bf16 v[112:115], v[218:221], v[162:165], v[112:115]
	v_mfma_f32_16x16x32_bf16 v[100:103], v[210:213], v[182:185], v[100:103]
	v_mfma_f32_16x16x32_bf16 v[96:99], v[218:221], v[182:185], v[96:99]
	v_mfma_f32_16x16x32_bf16 v[84:87], v[210:213], v[190:193], v[84:87]
	v_mfma_f32_16x16x32_bf16 v[80:83], v[218:221], v[190:193], v[80:83]
	v_mfma_f32_16x16x32_bf16 v[68:71], v[210:213], v[202:205], v[68:71]
	v_mfma_f32_16x16x32_bf16 v[64:67], v[218:221], v[202:205], v[64:67]
	v_mfma_f32_16x16x32_bf16 v[116:119], v[214:217], v[178:181], v[116:119]
	v_mfma_f32_16x16x32_bf16 v[112:115], v[222:225], v[178:181], v[112:115]
	v_mfma_f32_16x16x32_bf16 v[100:103], v[214:217], v[186:189], v[100:103]
	v_mfma_f32_16x16x32_bf16 v[96:99], v[222:225], v[186:189], v[96:99]
	v_mfma_f32_16x16x32_bf16 v[84:87], v[214:217], v[194:197], v[84:87]
	v_mfma_f32_16x16x32_bf16 v[80:83], v[222:225], v[194:197], v[80:83]
	v_mfma_f32_16x16x32_bf16 v[68:71], v[214:217], v[206:209], v[68:71]
	v_mfma_f32_16x16x32_bf16 v[64:67], v[222:225], v[206:209], v[64:67]
	s_barrier
	s_setprio 0
	s_mov_b32 m0, s54
	s_mov_b64 s[20:21], 0x80
	v_lshl_add_u64 v[166:167], v[226:227], 0, s[20:21]
	ds_read_b128 v[162:165], v172 offset:49152
	ds_read_b128 v[178:181], v172 offset:50176
	ds_read_b128 v[182:185], v172 offset:51200
	ds_read_b128 v[186:189], v172 offset:52224
	ds_read_b128 v[190:193], v172 offset:53248
	ds_read_b128 v[194:197], v172 offset:54272
	ds_read_b128 v[202:205], v172 offset:55296
	ds_read_b128 v[206:209], v172 offset:56320
	global_load_lds_dwordx4 v[166:167], off
	v_lshl_add_u64 v[166:167], v[228:229], 0, s[20:21]
	s_mov_b32 m0, s55
	s_nop 0
	global_load_lds_dwordx4 v[166:167], off
	s_setprio 1
	s_barrier
	s_waitcnt lgkmcnt(0)
	v_mfma_f32_16x16x32_bf16 v[60:63], v[146:149], v[162:165], v[60:63]
	v_mfma_f32_16x16x32_bf16 v[56:59], v[154:157], v[162:165], v[56:59]
	v_mfma_f32_16x16x32_bf16 v[44:47], v[146:149], v[182:185], v[44:47]
	v_mfma_f32_16x16x32_bf16 v[40:43], v[154:157], v[182:185], v[40:43]
	v_mfma_f32_16x16x32_bf16 v[28:31], v[146:149], v[190:193], v[28:31]
	v_mfma_f32_16x16x32_bf16 v[24:27], v[154:157], v[190:193], v[24:27]
	v_mfma_f32_16x16x32_bf16 v[12:15], v[146:149], v[202:205], v[12:15]
	v_mfma_f32_16x16x32_bf16 v[8:11], v[154:157], v[202:205], v[8:11]
	v_mfma_f32_16x16x32_bf16 v[60:63], v[150:153], v[178:181], v[60:63]
	v_mfma_f32_16x16x32_bf16 v[56:59], v[158:161], v[178:181], v[56:59]
	v_mfma_f32_16x16x32_bf16 v[44:47], v[150:153], v[186:189], v[44:47]
	v_mfma_f32_16x16x32_bf16 v[40:43], v[158:161], v[186:189], v[40:43]
	v_mfma_f32_16x16x32_bf16 v[28:31], v[150:153], v[194:197], v[28:31]
	v_mfma_f32_16x16x32_bf16 v[24:27], v[158:161], v[194:197], v[24:27]
	v_mfma_f32_16x16x32_bf16 v[12:15], v[150:153], v[206:209], v[12:15]
	v_mfma_f32_16x16x32_bf16 v[8:11], v[158:161], v[206:209], v[8:11]
	s_barrier
	s_setprio 0
	s_add_u32 s4, s4, 0x40080
	s_addc_u32 s5, s5, 0
	s_add_i32 s6, s6, s44
	s_mov_b32 m0, s6
	s_nop 0
	global_load_lds_dwordx4 v130, s[4:5]
	s_add_i32 m0, s6, 0x2000
	s_nop 0
	global_load_lds_dwordx4 v134, s[4:5]
	s_waitcnt vmcnt(8)
	s_setprio 1
	s_barrier
	v_mfma_f32_16x16x32_bf16 v[52:55], v[210:213], v[162:165], v[52:55]
	v_mfma_f32_16x16x32_bf16 v[48:51], v[218:221], v[162:165], v[48:51]
	v_mfma_f32_16x16x32_bf16 v[36:39], v[210:213], v[182:185], v[36:39]
	v_mfma_f32_16x16x32_bf16 v[32:35], v[218:221], v[182:185], v[32:35]
	v_mfma_f32_16x16x32_bf16 v[20:23], v[210:213], v[190:193], v[20:23]
	v_mfma_f32_16x16x32_bf16 v[16:19], v[218:221], v[190:193], v[16:19]
	v_mfma_f32_16x16x32_bf16 v[4:7], v[210:213], v[202:205], v[4:7]
	v_mfma_f32_16x16x32_bf16 v[0:3], v[218:221], v[202:205], v[0:3]
	v_mfma_f32_16x16x32_bf16 v[52:55], v[214:217], v[178:181], v[52:55]
	v_mfma_f32_16x16x32_bf16 v[48:51], v[222:225], v[178:181], v[48:51]
	v_mfma_f32_16x16x32_bf16 v[36:39], v[214:217], v[186:189], v[36:39]
	v_mfma_f32_16x16x32_bf16 v[32:35], v[222:225], v[186:189], v[32:35]
	v_mfma_f32_16x16x32_bf16 v[20:23], v[214:217], v[194:197], v[20:23]
	v_mfma_f32_16x16x32_bf16 v[16:19], v[222:225], v[194:197], v[16:19]
	v_mfma_f32_16x16x32_bf16 v[4:7], v[214:217], v[206:209], v[4:7]
	v_mfma_f32_16x16x32_bf16 v[0:3], v[222:225], v[206:209], v[0:3]
	s_barrier
;     __device__ __forceinline__ void operator()(const AccT& acc, const Unit& u, int wr, int wc, int fr, int fq) const {
;     ...
;         const int rbase = wr * 64 + fr;
;         const int tb = u.pn * 256 + wc * 32 + 8 * fq;
;         const int o0 = wc * 32 + 8 * fq;
;         const int j = fr & 3; const float sgn = ((fr >> 2) & 1) ? 1.0f : -1.0f;
; #pragma unroll
;         for (int ai = 0; ai < 2; ++ai) {
;             const int hh = 2 * ai + wr;
;             const float l2f = lgd[hh] * 1.4426950408889634f, l2b = lgd[4 + hh] * 1.4426950408889634f;
;             const float zf0 = exp2f((float)(127 - o0) * l2f), zfs = exp2f(-l2f), zb0 = exp2f((float)o0 * l2b), zbs = exp2f(l2b);
; #pragma unroll
;             for (int m = 0; m < 4; ++m) {
;                 const int r = rbase + ai * 128 + m * 16;
;                 const int d = 4 * (2 * m + (fr >> 3)) + j;
; #pragma unroll
;                 for (int bj = 0; bj < 2; ++bj) {
;                     const int t0 = tb + bj * 128;
;                     float v[8];
; #pragma unroll
;                     for (int jj = 0; jj < 4; ++jj) { v[jj] = acc[ai][bj][m][0][jj]; v[4 + jj] = acc[ai][bj][m][1][jj]; }
;                     if constexpr (ROPE) {
;                         const int t = t0 & 2047;
; #pragma unroll
;                         for (int hf = 0; hf < 2; ++hf) {
;                             f32x4 cs, sn;
;                             if (m < 2) { const float c1 = ropeA[(t >> 6) * 16 + d], s1 = ropeA[1024 + (t >> 6) * 16 + d]; cs = (f32x4){c1, c1, c1, c1}; sn = (f32x4){s1, s1, s1, s1}; }
;                             else { const float* cb = ropeA + 2048 + (d - 16) * 64 + (t & 63) + 4 * hf; cs = *(const f32x4*)(cb); sn = *(const f32x4*)(cb + 1024); }
; #pragma unroll
;                             for (int jj = 0; jj < 4; ++jj) { const float pr = __shfl_xor(v[4 * hf + jj], 4); v[4 * hf + jj] = v[4 * hf + jj] * cs[jj] + sgn * pr * sn[jj]; }
;                             __builtin_amdgcn_sched_barrier(0);
;                         }
;                     }
;                     float zf[8], zb[8]; zf[0] = zf0; zb[0] = zb0;
; #pragma unroll
;                     for (int jj = 1; jj < 8; ++jj) { zf[jj] = zf[jj - 1] * zfs; zb[jj] = zb[jj - 1] * zbs; }
;                     u32x4 wf, wb;
	s_setprio 0
	s_add_i32 s67, s67, 2
	s_add_u32 s0, s0, 0x100
	s_addc_u32 s1, s1, 0
	s_add_u32 s65, s65, 0x100
	s_addc_u32 s66, s66, 0
	s_cmp_gt_u32 s67, 13
	s_cbranch_scc0 .LBB0_613
	v_mov_b32_e32 v136, v169
	v_mov_b32_e32 v150, v168
	s_lshl_b32 s0, s33, 8
	global_load_dword v154, v137, s[22:23]
	global_load_dword v155, v137, s[22:23] offset:16
	s_or_b32 s0, s0, s53
	v_lshlrev_b32_e32 v151, 3, v136
	v_ashrrev_i32_e32 v136, 1, v150
	v_add_u32_e32 v162, s0, v151
	v_bfi_b32 v136, -4, v136, v150
	v_lshrrev_b32_e32 v146, 2, v162
	v_add_u32_e32 v192, 0x400, v136
	v_and_b32_e32 v187, 0x1f0, v146
	v_add_u32_e32 v146, v192, v187
	v_add_u32_e32 v148, v187, v136
	v_ashrrev_i32_e32 v147, 31, v146
	v_ashrrev_i32_e32 v149, 31, v148
	v_lshl_add_u64 v[146:147], v[146:147], 2, s[16:17]
	v_lshl_add_u64 v[148:149], v[148:149], 2, s[16:17]
	global_load_dword v153, v[146:147], off
	global_load_dword v166, v[148:149], off
	v_and_b32_e32 v157, 64, v174
	v_xor_b32_e32 v156, 4, v174
	v_add_u32_e32 v157, 64, v157
	v_cmp_lt_i32_e32 vcc, v156, v157
	v_mov_b32_e32 v152, v124
	v_add_u32_e32 v151, s53, v151
	v_cndmask_b32_e32 v156, v174, v156, vcc
	v_lshlrev_b32_e32 v177, 2, v156
	ds_bpermute_b32 v124, v177, v124
	v_sub_u32_e32 v156, 0x7f, v151
	v_add_u32_e32 v164, s52, v150
	v_and_b32_e32 v150, 4, v150
	v_cvt_f32_i32_e32 v179, v156
	v_cvt_f32_i32_e32 v178, v151
	v_cmp_eq_u32_e32 vcc, 0, v150
	ds_bpermute_b32 v157, v177, v125
	ds_bpermute_b32 v158, v177, v127
	s_waitcnt lgkmcnt(0)
	v_cndmask_b32_e64 v167, v124, -v124, vcc
	ds_bpermute_b32 v151, v177, v126
	v_ashrrev_i32_e32 v165, 31, v164
	v_and_b32_e32 v186, 56, v162
	s_waitcnt lgkmcnt(0)
	v_cndmask_b32_e64 v151, v151, -v151, vcc
	s_waitcnt vmcnt(0)
	v_mul_f32_e32 v124, 0x3fb8aa3b, v154
	v_mul_f32_e32 v150, 0x3fb8aa3b, v155
	v_cmp_lt_f32_e64 s[4:5], s60, v124
	v_mul_f32_e32 v156, v124, v179
	v_cmp_gt_f32_e64 s[6:7], s59, v150
	v_cndmask_b32_e64 v159, 0, v176, s[4:5]
	v_mul_f32_e32 v160, v150, v178
	v_cndmask_b32_e64 v161, 0, v176, s[6:7]
	v_cmp_gt_f32_e64 s[8:9], s59, v156
	v_fmac_f32_e32 v159, 0xbfb8aa3b, v154
	s_and_b64 s[0:1], s[4:5], exec
	v_cmp_gt_f32_e64 s[4:5], s59, v160
	v_fmac_f32_e32 v161, 0x3fb8aa3b, v155
	v_cndmask_b32_e64 v154, 0, v176, s[8:9]
	v_exp_f32_e32 v155, v159
	v_cndmask_b32_e64 v159, 0, v176, s[4:5]
	v_fmac_f32_e32 v154, v124, v179
	v_fmac_f32_e32 v159, v150, v178
	v_exp_f32_e32 v150, v154
	v_cndmask_b32_e64 v156, 0, v175, s[8:9]
	s_cselect_b32 s8, 0xffffffc0, 0
	v_exp_f32_e32 v161, v161
	v_exp_f32_e32 v159, v159
	v_ldexp_f32 v163, v155, s8
	v_pk_mul_f32 v[154:155], v[152:153], v[166:167]
	v_cndmask_b32_e64 v167, v157, -v157, vcc
	v_mov_b32_e32 v152, v125
	s_and_b64 s[0:1], s[6:7], exec
	v_add_f32_e32 v190, v154, v155
	v_pk_mul_f32 v[154:155], v[152:153], v[166:167]
	v_cndmask_b32_e64 v167, v158, -v158, vcc
	v_mov_b32_e32 v152, v127
	v_cndmask_b32_e64 v160, 0, v175, s[4:5]
	s_cselect_b32 s0, 0xffffffc0, 0
	v_ldexp_f32 v180, v150, v156
	v_add_f32_e32 v191, v154, v155
	v_pk_mul_f32 v[154:155], v[152:153], v[166:167]
	v_ldexp_f32 v124, v161, s0
	v_mul_f32_e32 v161, v126, v166
	v_ldexp_f32 v150, v159, v160
	v_mul_f32_e32 v181, v163, v180
	v_add_f32_e32 v193, v154, v155
	global_load_dword v188, v[148:149], off
	global_load_dword v157, v[146:147], off
	ds_bpermute_b32 v127, v177, v121
	v_mov_b32_e32 v156, v121
	ds_bpermute_b32 v121, v177, v123
	ds_bpermute_b32 v125, v177, v120
	ds_bpermute_b32 v152, v177, v122
	s_waitcnt lgkmcnt(3)
	v_cndmask_b32_e64 v189, v127, -v127, vcc
	s_waitcnt lgkmcnt(1)
	v_cndmask_b32_e64 v158, v125, -v125, vcc
	s_waitcnt lgkmcnt(0)
	v_cndmask_b32_e64 v127, v152, -v152, vcc
	s_waitcnt vmcnt(1)
	v_mul_f32_e32 v159, v120, v188
	s_waitcnt vmcnt(0)
	v_pk_mul_f32 v[154:155], v[156:157], v[188:189]
	v_cndmask_b32_e64 v189, v121, -v121, vcc
	v_mov_b32_e32 v156, v123
	v_add_f32_e32 v121, v154, v155
	v_pk_mul_f32 v[154:155], v[156:157], v[188:189]
	s_nop 0
	v_add_f32_e32 v123, v154, v155
	v_mov_b32_e32 v125, v153
	v_pk_mul_f32 v[152:153], v[124:125], v[150:151]
	v_mov_b32_e32 v125, v161
	v_pk_mul_f32 v[154:155], v[124:125], v[152:153]
	v_mov_b32_e32 v125, v157
	v_mov_b32_e32 v155, v158
	v_pk_mul_f32 v[156:157], v[124:125], v[154:155]
	v_mov_b32_e32 v158, v124
	v_pk_mul_f32 v[158:159], v[158:159], v[156:157]
	v_mul_f32_e32 v167, v163, v181
	v_mov_b32_e32 v159, v127
	v_mul_f32_e32 v183, v163, v167
	v_pk_mul_f32 v[160:161], v[124:125], v[158:159]
	v_mul_f32_e32 v182, v163, v183
	v_mul_f32_e32 v151, v124, v160
	v_mul_f32_e32 v185, v163, v182
	v_mul_f32_e32 v155, v124, v151
	v_mul_f32_e32 v124, v180, v190
	v_mul_f32_e32 v125, v181, v191
	v_fma_f32 v153, v126, v166, v153
	v_mul_f32_e32 v184, v163, v185
	v_cvt_pk_bf16_f32 v124, v124, v125
	v_mul_f32_e32 v125, v167, v153
	v_mul_f32_e32 v126, v183, v193
	v_fma_f32 v120, v120, v188, v157
	v_mul_f32_e32 v159, v163, v184
	v_cvt_pk_bf16_f32 v125, v125, v126
	v_mul_f32_e32 v126, v182, v120
	v_mul_f32_e32 v127, v185, v121
	v_fma_f32 v122, v122, v188, v161
	v_cvt_pk_bf16_f32 v126, v126, v127
	v_mul_f32_e32 v127, v184, v122
	v_mul_f32_e32 v157, v159, v123
	v_cvt_pk_bf16_f32 v127, v127, v157
	v_mul_f32_e32 v157, v150, v190
	v_mul_f32_e32 v120, v158, v120
	v_mul_f32_e32 v121, v160, v121
	v_mul_f32_e32 v161, v152, v191
	v_cvt_pk_bf16_f32 v188, v157, v161
	v_mul_f32_e32 v153, v154, v153
	v_mul_f32_e32 v157, v156, v193
	v_cvt_pk_bf16_f32 v189, v153, v157
	v_cvt_pk_bf16_f32 v190, v120, v121
	v_mul_f32_e32 v120, v151, v122
	v_mul_f32_e32 v121, v155, v123
	v_cvt_pk_bf16_f32 v191, v120, v121
	v_lshlrev_b64 v[120:121], 17, v[164:165]
	v_lshl_add_u64 v[120:121], s[80:81], 0, v[120:121]
	v_ashrrev_i32_e32 v163, 31, v162
	v_lshl_add_u64 v[120:121], v[162:163], 1, v[120:121]
	s_mov_b64 s[0:1], 0x2000000
	global_store_dwordx4 v[120:121], v[124:127], off
	s_nop 1
	v_lshl_add_u64 v[126:127], v[120:121], 0, s[0:1]
	s_brev_b32 s0, 64
	v_add_co_u32_e64 v122, s[4:5], s0, v120
	s_nop 1
	v_addc_co_u32_e64 v123, s[4:5], 0, v121, s[4:5]
	global_store_dwordx4 v[122:123], v[188:191], off
	v_add_u32_e32 v122, 0x80, v162
	v_lshrrev_b32_e32 v122, 2, v122
	v_and_b32_e32 v153, 0x1f0, v122
	v_add_u32_e32 v122, v153, v192
	v_add_u32_e32 v124, v153, v136
	v_ashrrev_i32_e32 v123, 31, v122
	v_ashrrev_i32_e32 v125, 31, v124
	v_lshl_add_u64 v[122:123], v[122:123], 2, s[16:17]
	v_lshl_add_u64 v[124:125], v[124:125], 2, s[16:17]
	global_load_dword v163, v[122:123], off
	global_load_dword v164, v[124:125], off
	ds_bpermute_b32 v157, v177, v116
	v_mov_b32_e32 v162, v116
	ds_bpermute_b32 v116, v177, v117
	ds_bpermute_b32 v161, v177, v118
	ds_bpermute_b32 v166, v177, v119
	s_waitcnt lgkmcnt(3)
;     __device__ __forceinline__ void operator()(const AccT& acc, const Unit& u, int wr, int wc, int fr, int fq) const {
;     ...
;             for (int m = 0; m < 4; ++m) {
;                 const int r = rbase + ai * 128 + m * 16;
;                 const int d = 4 * (2 * m + (fr >> 3)) + j;
; #pragma unroll
;                 for (int bj = 0; bj < 2; ++bj) {
;                     const int t0 = tb + bj * 128;
;                     float v[8];
; #pragma unroll
;                     for (int jj = 0; jj < 4; ++jj) { v[jj] = acc[ai][bj][m][0][jj]; v[4 + jj] = acc[ai][bj][m][1][jj]; }
;                     if constexpr (ROPE) {
;                         const int t = t0 & 2047;
; #pragma unroll
;                         for (int hf = 0; hf < 2; ++hf) {
;                             f32x4 cs, sn;
;                             if (m < 2) { const float c1 = ropeA[(t >> 6) * 16 + d], s1 = ropeA[1024 + (t >> 6) * 16 + d]; cs = (f32x4){c1, c1, c1, c1}; sn = (f32x4){s1, s1, s1, s1}; }
;                             else { const float* cb = ropeA + 2048 + (d - 16) * 64 + (t & 63) + 4 * hf; cs = *(const f32x4*)(cb); sn = *(const f32x4*)(cb + 1024); }
; #pragma unroll
;                             for (int jj = 0; jj < 4; ++jj) { const float pr = __shfl_xor(v[4 * hf + jj], 4); v[4 * hf + jj] = v[4 * hf + jj] * cs[jj] + sgn * pr * sn[jj]; }
;                             __builtin_amdgcn_sched_barrier(0);
;                         }
;                     }
;                     float zf[8], zb[8]; zf[0] = zf0; zb[0] = zb0;
; #pragma unroll
;                     for (int jj = 1; jj < 8; ++jj) { zf[jj] = zf[jj - 1] * zfs; zb[jj] = zb[jj - 1] * zbs; }
;                     u32x4 wf, wb;
;                     wf.x = cvt_pk_bf16(v[0] * zf[0], v[1] * zf[1]); wf.y = cvt_pk_bf16(v[2] * zf[2], v[3] * zf[3]); wf.z = cvt_pk_bf16(v[4] * zf[4], v[5] * zf[5]); wf.w = cvt_pk_bf16(v[6] * zf[6], v[7] * zf[7]);
;                     wb.x = cvt_pk_bf16(v[0] * zb[0], v[1] * zb[1]); wb.y = cvt_pk_bf16(v[2] * zb[2], v[3] * zb[3]); wb.z = cvt_pk_bf16(v[4] * zb[4], v[5] * zb[5]); wb.w = cvt_pk_bf16(v[6] * zb[6], v[7] * zb[7]);
;                     *(u32x4*)(KTZ + (size_t)r * NT + t0) = wf;
;                     *(u32x4*)(KTZ + (size_t)(256 + r) * NT + t0) = wb;
;                     __builtin_amdgcn_sched_barrier(0);
	v_cndmask_b32_e64 v165, v157, -v157, vcc
	s_waitcnt vmcnt(0)
	v_pk_mul_f32 v[188:189], v[162:163], v[164:165]
	s_waitcnt lgkmcnt(2)
	v_cndmask_b32_e64 v165, v116, -v116, vcc
	v_mov_b32_e32 v162, v117
	v_pk_mul_f32 v[116:117], v[162:163], v[164:165]
	s_waitcnt lgkmcnt(1)
	v_cndmask_b32_e64 v165, v161, -v161, vcc
	v_mov_b32_e32 v162, v118
	v_add_f32_e32 v161, v116, v117
	v_pk_mul_f32 v[116:117], v[162:163], v[164:165]
	s_waitcnt lgkmcnt(0)
	v_cndmask_b32_e64 v165, v166, -v166, vcc
	v_mov_b32_e32 v162, v119
	v_add_f32_e32 v166, v116, v117
	v_pk_mul_f32 v[116:117], v[162:163], v[164:165]
	v_add_f32_e32 v157, v188, v189
	v_add_f32_e32 v164, v116, v117
	global_load_dword v117, v[122:123], off
	global_load_dword v118, v[124:125], off
	ds_bpermute_b32 v119, v177, v112
	v_mov_b32_e32 v116, v112
	ds_bpermute_b32 v112, v177, v113
	ds_bpermute_b32 v165, v177, v114
	ds_bpermute_b32 v188, v177, v115
	s_waitcnt lgkmcnt(3)
	v_cndmask_b32_e64 v119, v119, -v119, vcc
	s_waitcnt vmcnt(0)
	v_pk_mul_f32 v[162:163], v[116:117], v[118:119]
	s_waitcnt lgkmcnt(2)
	v_cndmask_b32_e64 v119, v112, -v112, vcc
	v_mov_b32_e32 v116, v113
	v_pk_mul_f32 v[112:113], v[116:117], v[118:119]
	s_waitcnt lgkmcnt(1)
	v_cndmask_b32_e64 v119, v165, -v165, vcc
	v_mov_b32_e32 v116, v114
	v_add_f32_e32 v162, v162, v163
	v_add_f32_e32 v163, v112, v113
	v_pk_mul_f32 v[112:113], v[116:117], v[118:119]
	s_waitcnt lgkmcnt(0)
	v_cndmask_b32_e64 v119, v188, -v188, vcc
	v_mov_b32_e32 v116, v115
	v_add_f32_e32 v165, v112, v113
	v_pk_mul_f32 v[112:113], v[116:117], v[118:119]
	s_nop 0
	v_add_f32_e32 v119, v112, v113
	v_mul_f32_e32 v112, v180, v157
	v_mul_f32_e32 v113, v181, v161
	v_cvt_pk_bf16_f32 v112, v112, v113
	v_mul_f32_e32 v113, v167, v166
	v_mul_f32_e32 v114, v183, v164
	v_cvt_pk_bf16_f32 v113, v113, v114
	v_mul_f32_e32 v114, v182, v162
	v_mul_f32_e32 v115, v185, v163
	v_cvt_pk_bf16_f32 v114, v114, v115
	v_mul_f32_e32 v115, v184, v165
	v_mul_f32_e32 v116, v159, v119
	v_cvt_pk_bf16_f32 v115, v115, v116
	v_mul_f32_e32 v116, v150, v157
	v_mul_f32_e32 v117, v152, v161
	v_cvt_pk_bf16_f32 v116, v116, v117
	v_mul_f32_e32 v117, v154, v166
	v_mul_f32_e32 v118, v156, v164
	v_cvt_pk_bf16_f32 v117, v117, v118
	v_mul_f32_e32 v118, v158, v162
	v_mul_f32_e32 v157, v160, v163
	v_mul_f32_e32 v119, v155, v119
	v_cvt_pk_bf16_f32 v118, v118, v157
	v_mul_f32_e32 v157, v151, v165
	v_cvt_pk_bf16_f32 v119, v157, v119
	global_store_dwordx4 v[120:121], v[112:115], off offset:256
	global_store_dwordx4 v[126:127], v[116:119], off offset:256
	v_add_u32_e32 v161, 0x408, v136
	v_add_u32_e32 v157, 8, v136
	v_add_u32_e32 v112, v161, v187
	v_add_u32_e32 v114, v187, v157
	v_ashrrev_i32_e32 v113, 31, v112
	v_ashrrev_i32_e32 v115, 31, v114
	v_lshl_add_u64 v[112:113], v[112:113], 2, s[16:17]
	v_lshl_add_u64 v[114:115], v[114:115], 2, s[16:17]
	global_load_dword v117, v[112:113], off
	global_load_dword v118, v[114:115], off
	ds_bpermute_b32 v119, v177, v108
	v_mov_b32_e32 v116, v108
	ds_bpermute_b32 v108, v177, v109
	ds_bpermute_b32 v162, v177, v110
	ds_bpermute_b32 v163, v177, v111
	s_waitcnt lgkmcnt(3)
	v_cndmask_b32_e64 v119, v119, -v119, vcc
	s_waitcnt vmcnt(0)
	v_pk_mul_f32 v[126:127], v[116:117], v[118:119]
	s_waitcnt lgkmcnt(2)
	v_cndmask_b32_e64 v119, v108, -v108, vcc
	v_mov_b32_e32 v116, v109
	v_pk_mul_f32 v[108:109], v[116:117], v[118:119]
	s_waitcnt lgkmcnt(1)
	v_cndmask_b32_e64 v119, v162, -v162, vcc
	v_mov_b32_e32 v116, v110
	v_add_f32_e32 v126, v126, v127
	v_add_f32_e32 v127, v108, v109
	v_pk_mul_f32 v[108:109], v[116:117], v[118:119]
	s_waitcnt lgkmcnt(0)
	v_cndmask_b32_e64 v119, v163, -v163, vcc
	v_mov_b32_e32 v116, v111
	v_add_f32_e32 v162, v108, v109
	v_pk_mul_f32 v[108:109], v[116:117], v[118:119]
	s_nop 0
	v_add_f32_e32 v118, v108, v109
	global_load_dword v109, v[112:113], off
	global_load_dword v110, v[114:115], off
	ds_bpermute_b32 v111, v177, v104
	v_mov_b32_e32 v108, v104
	ds_bpermute_b32 v104, v177, v105
	ds_bpermute_b32 v119, v177, v106
	ds_bpermute_b32 v163, v177, v107
	s_waitcnt lgkmcnt(3)
	v_cndmask_b32_e64 v111, v111, -v111, vcc
	s_waitcnt vmcnt(0)
	v_pk_mul_f32 v[116:117], v[108:109], v[110:111]
	s_waitcnt lgkmcnt(2)
	v_cndmask_b32_e64 v111, v104, -v104, vcc
	v_mov_b32_e32 v108, v105
	v_pk_mul_f32 v[104:105], v[108:109], v[110:111]
	s_waitcnt lgkmcnt(1)
	v_cndmask_b32_e64 v111, v119, -v119, vcc
	v_mov_b32_e32 v108, v106
	v_add_f32_e32 v119, v104, v105
	v_pk_mul_f32 v[104:105], v[108:109], v[110:111]
	s_waitcnt lgkmcnt(0)
	v_cndmask_b32_e64 v111, v163, -v163, vcc
	v_mov_b32_e32 v108, v107
	v_add_f32_e32 v163, v104, v105
	v_pk_mul_f32 v[104:105], v[108:109], v[110:111]
	v_add_f32_e32 v164, v116, v117
	v_add_f32_e32 v108, v104, v105
	v_mul_f32_e32 v104, v180, v126
	v_mul_f32_e32 v105, v181, v127
	v_cvt_pk_bf16_f32 v104, v104, v105
	v_mul_f32_e32 v105, v167, v162
	v_mul_f32_e32 v106, v183, v118
	v_cvt_pk_bf16_f32 v105, v105, v106
	v_mul_f32_e32 v106, v182, v164
	v_mul_f32_e32 v107, v185, v119
	v_cvt_pk_bf16_f32 v106, v106, v107
	v_mul_f32_e32 v107, v184, v163
	v_mul_f32_e32 v109, v159, v108
	v_cvt_pk_bf16_f32 v107, v107, v109
	v_mul_f32_e32 v109, v150, v126
	v_mul_f32_e32 v110, v152, v127
	v_cvt_pk_bf16_f32 v116, v109, v110
	v_mul_f32_e32 v109, v154, v162
	v_mul_f32_e32 v110, v156, v118
	v_cvt_pk_bf16_f32 v117, v109, v110
	v_mul_f32_e32 v109, v158, v164
	v_mul_f32_e32 v110, v160, v119
	v_cvt_pk_bf16_f32 v118, v109, v110
	v_mul_f32_e32 v109, v151, v163
	v_mul_f32_e32 v108, v155, v108
	s_mov_b64 s[0:1], 0x200000
	v_cvt_pk_bf16_f32 v119, v109, v108
	v_lshl_add_u64 v[108:109], v[120:121], 0, s[0:1]
	s_mov_b32 s0, 0x200000
	v_add_co_u32_e64 v110, s[4:5], s0, v120
	s_mov_b64 s[0:1], 0x2200000
	s_nop 0
	v_addc_co_u32_e64 v111, s[4:5], 0, v121, s[4:5]
	global_store_dwordx4 v[110:111], v[104:107], off
	v_lshl_add_u64 v[110:111], v[120:121], 0, s[0:1]
	s_mov_b32 s0, 0x2200000
	v_add_co_u32_e64 v104, s[4:5], s0, v120
	s_nop 1
	v_addc_co_u32_e64 v105, s[4:5], 0, v121, s[4:5]
	global_store_dwordx4 v[104:105], v[116:119], off
	v_add_u32_e32 v104, v153, v161
	v_add_u32_e32 v106, v153, v157
	v_ashrrev_i32_e32 v105, 31, v104
	v_ashrrev_i32_e32 v107, 31, v106
	v_lshl_add_u64 v[104:105], v[104:105], 2, s[16:17]
	v_lshl_add_u64 v[106:107], v[106:107], 2, s[16:17]
	global_load_dword v117, v[104:105], off
	global_load_dword v118, v[106:107], off
	ds_bpermute_b32 v119, v177, v100
	v_mov_b32_e32 v116, v100
	ds_bpermute_b32 v100, v177, v101
	ds_bpermute_b32 v153, v177, v102
	ds_bpermute_b32 v157, v177, v103
	s_waitcnt lgkmcnt(3)
;     __device__ __forceinline__ void operator()(const AccT& acc, const Unit& u, int wr, int wc, int fr, int fq) const {
;     ...
;             for (int m = 0; m < 4; ++m) {
;                 const int r = rbase + ai * 128 + m * 16;
;                 const int d = 4 * (2 * m + (fr >> 3)) + j;
; #pragma unroll
;                 for (int bj = 0; bj < 2; ++bj) {
;                     const int t0 = tb + bj * 128;
;                     float v[8];
; #pragma unroll
;                     for (int jj = 0; jj < 4; ++jj) { v[jj] = acc[ai][bj][m][0][jj]; v[4 + jj] = acc[ai][bj][m][1][jj]; }
;                     if constexpr (ROPE) {
;                         const int t = t0 & 2047;
; #pragma unroll
;                         for (int hf = 0; hf < 2; ++hf) {
;                             f32x4 cs, sn;
;                             if (m < 2) { const float c1 = ropeA[(t >> 6) * 16 + d], s1 = ropeA[1024 + (t >> 6) * 16 + d]; cs = (f32x4){c1, c1, c1, c1}; sn = (f32x4){s1, s1, s1, s1}; }
;                             else { const float* cb = ropeA + 2048 + (d - 16) * 64 + (t & 63) + 4 * hf; cs = *(const f32x4*)(cb); sn = *(const f32x4*)(cb + 1024); }
; #pragma unroll
;                             for (int jj = 0; jj < 4; ++jj) { const float pr = __shfl_xor(v[4 * hf + jj], 4); v[4 * hf + jj] = v[4 * hf + jj] * cs[jj] + sgn * pr * sn[jj]; }
;                             __builtin_amdgcn_sched_barrier(0);
;                         }
;                     }
;                     float zf[8], zb[8]; zf[0] = zf0; zb[0] = zb0;
; #pragma unroll
;                     for (int jj = 1; jj < 8; ++jj) { zf[jj] = zf[jj - 1] * zfs; zb[jj] = zb[jj - 1] * zbs; }
;                     u32x4 wf, wb;
;                     wf.x = cvt_pk_bf16(v[0] * zf[0], v[1] * zf[1]); wf.y = cvt_pk_bf16(v[2] * zf[2], v[3] * zf[3]); wf.z = cvt_pk_bf16(v[4] * zf[4], v[5] * zf[5]); wf.w = cvt_pk_bf16(v[6] * zf[6], v[7] * zf[7]);
;                     wb.x = cvt_pk_bf16(v[0] * zb[0], v[1] * zb[1]); wb.y = cvt_pk_bf16(v[2] * zb[2], v[3] * zb[3]); wb.z = cvt_pk_bf16(v[4] * zb[4], v[5] * zb[5]); wb.w = cvt_pk_bf16(v[6] * zb[6], v[7] * zb[7]);
;                     *(u32x4*)(KTZ + (size_t)r * NT + t0) = wf;
;                     *(u32x4*)(KTZ + (size_t)(256 + r) * NT + t0) = wb;
;                     __builtin_amdgcn_sched_barrier(0);
	v_cndmask_b32_e64 v119, v119, -v119, vcc
	s_waitcnt vmcnt(0)
	v_pk_mul_f32 v[126:127], v[116:117], v[118:119]
	s_waitcnt lgkmcnt(2)
	v_cndmask_b32_e64 v119, v100, -v100, vcc
	v_mov_b32_e32 v116, v101
	v_pk_mul_f32 v[100:101], v[116:117], v[118:119]
	s_waitcnt lgkmcnt(1)
	v_cndmask_b32_e64 v119, v153, -v153, vcc
	v_mov_b32_e32 v116, v102
	v_add_f32_e32 v126, v126, v127
	v_add_f32_e32 v127, v100, v101
	v_pk_mul_f32 v[100:101], v[116:117], v[118:119]
	s_waitcnt lgkmcnt(0)
	v_cndmask_b32_e64 v119, v157, -v157, vcc
	v_mov_b32_e32 v116, v103
	v_add_f32_e32 v153, v100, v101
	v_pk_mul_f32 v[100:101], v[116:117], v[118:119]
	s_nop 0
	v_add_f32_e32 v118, v100, v101
	global_load_dword v101, v[104:105], off
	global_load_dword v102, v[106:107], off
	ds_bpermute_b32 v103, v177, v96
	v_mov_b32_e32 v100, v96
	ds_bpermute_b32 v96, v177, v97
	ds_bpermute_b32 v119, v177, v98
	ds_bpermute_b32 v157, v177, v99
	s_waitcnt lgkmcnt(3)
	v_cndmask_b32_e64 v103, v103, -v103, vcc
	s_waitcnt vmcnt(0)
	v_pk_mul_f32 v[116:117], v[100:101], v[102:103]
	s_waitcnt lgkmcnt(2)
	v_cndmask_b32_e64 v103, v96, -v96, vcc
	v_mov_b32_e32 v100, v97
	v_pk_mul_f32 v[96:97], v[100:101], v[102:103]
	s_waitcnt lgkmcnt(1)
	v_cndmask_b32_e64 v103, v119, -v119, vcc
	v_mov_b32_e32 v100, v98
	v_add_f32_e32 v116, v116, v117
	v_add_f32_e32 v117, v96, v97
	v_pk_mul_f32 v[96:97], v[100:101], v[102:103]
	s_waitcnt lgkmcnt(0)
	v_cndmask_b32_e64 v103, v157, -v157, vcc
	v_mov_b32_e32 v100, v99
	v_add_f32_e32 v119, v96, v97
	v_pk_mul_f32 v[96:97], v[100:101], v[102:103]
	s_nop 0
	v_add_f32_e32 v103, v96, v97
	v_mul_f32_e32 v96, v180, v126
	v_mul_f32_e32 v97, v181, v127
	v_cvt_pk_bf16_f32 v96, v96, v97
	v_mul_f32_e32 v97, v167, v153
	v_mul_f32_e32 v98, v183, v118
	v_cvt_pk_bf16_f32 v97, v97, v98
	v_mul_f32_e32 v98, v182, v116
	v_mul_f32_e32 v99, v185, v117
	v_cvt_pk_bf16_f32 v98, v98, v99
	v_mul_f32_e32 v99, v184, v119
	v_mul_f32_e32 v100, v159, v103
	v_cvt_pk_bf16_f32 v99, v99, v100
	v_mul_f32_e32 v100, v150, v126
	v_mul_f32_e32 v101, v152, v127
	v_cvt_pk_bf16_f32 v100, v100, v101
	v_mul_f32_e32 v101, v154, v153
	v_mul_f32_e32 v102, v156, v118
	v_cvt_pk_bf16_f32 v101, v101, v102
	v_mul_f32_e32 v102, v158, v116
	v_mul_f32_e32 v116, v160, v117
	v_mul_f32_e32 v103, v155, v103
	v_cvt_pk_bf16_f32 v102, v102, v116
	v_mul_f32_e32 v116, v151, v119
	v_cvt_pk_bf16_f32 v103, v116, v103
	global_store_dwordx4 v[108:109], v[96:99], off offset:256
	global_store_dwordx4 v[110:111], v[100:103], off offset:256
	s_nop 1
	v_lshlrev_b32_e32 v100, 6, v136
	v_ashrrev_i32_e32 v101, 31, v100
	v_lshlrev_b64 v[102:103], 2, v[100:101]
	v_lshl_add_u64 v[96:97], s[24:25], 0, v[102:103]
	v_lshlrev_b32_e32 v136, 2, v186
	v_lshl_add_u64 v[96:97], v[96:97], 0, v[136:137]
	v_add_co_u32_e64 v98, s[4:5], s61, v96
	ds_bpermute_b32 v101, v177, v92
	s_nop 0
	v_addc_co_u32_e64 v99, s[4:5], 0, v97, s[4:5]
	global_load_dwordx4 v[108:111], v[98:99], off
	global_load_dwordx4 v[116:119], v[96:97], off
	ds_bpermute_b32 v127, v177, v93
	ds_bpermute_b32 v153, v177, v94
	ds_bpermute_b32 v157, v177, v95
	v_mov_b32_e32 v126, v92
	v_mov_b32_e32 v92, v94
	s_waitcnt lgkmcnt(3)
	v_cndmask_b32_e64 v163, v101, -v101, vcc
	s_waitcnt lgkmcnt(2)
	v_cndmask_b32_e64 v165, v127, -v127, vcc
	s_waitcnt lgkmcnt(1)
	v_cndmask_b32_e64 v187, v153, -v153, vcc
	s_waitcnt lgkmcnt(0)
	v_cndmask_b32_e64 v189, v157, -v157, vcc
	s_waitcnt vmcnt(1)
	v_mov_b32_e32 v127, v108
	s_waitcnt vmcnt(0)
	v_mov_b32_e32 v162, v116
	v_mov_b32_e32 v108, v93
	v_mov_b32_e32 v164, v117
	v_mov_b32_e32 v93, v110
	v_mov_b32_e32 v186, v118
	v_mov_b32_e32 v110, v95
	v_mov_b32_e32 v188, v119
	v_pk_mul_f32 v[94:95], v[126:127], v[162:163]
	v_pk_mul_f32 v[108:109], v[108:109], v[164:165]
	v_pk_mul_f32 v[92:93], v[92:93], v[186:187]
	v_pk_mul_f32 v[110:111], v[110:111], v[188:189]
	v_add_f32_e32 v101, v94, v95
	v_add_f32_e32 v153, v108, v109
	v_add_f32_e32 v157, v92, v93
	v_add_f32_e32 v161, v110, v111
	v_lshl_add_u64 v[92:93], s[16:17], 0, v[102:103]
	v_lshl_add_u64 v[94:95], v[92:93], 0, v[136:137]
	v_add_co_u32_e64 v92, s[4:5], s62, v94
	ds_bpermute_b32 v103, v177, v88
	s_nop 0
	v_addc_co_u32_e64 v93, s[4:5], 0, v95, s[4:5]
	v_add_co_u32_e64 v94, s[4:5], s49, v94
	ds_bpermute_b32 v126, v177, v89
	s_nop 0
	v_addc_co_u32_e64 v95, s[4:5], 0, v95, s[4:5]
	global_load_dwordx4 v[108:111], v[92:93], off offset:16
	global_load_dwordx4 v[116:119], v[94:95], off offset:16
	ds_bpermute_b32 v162, v177, v90
	ds_bpermute_b32 v164, v177, v91
	v_mov_b32_e32 v102, v88
	v_mov_b32_e32 v88, v90
	s_waitcnt lgkmcnt(3)
	v_cndmask_b32_e64 v127, v103, -v103, vcc
	s_waitcnt lgkmcnt(2)
	v_cndmask_b32_e64 v163, v126, -v126, vcc
	s_waitcnt lgkmcnt(1)
	v_cndmask_b32_e64 v165, v162, -v162, vcc
	s_waitcnt lgkmcnt(0)
	v_cndmask_b32_e64 v187, v164, -v164, vcc
	s_waitcnt vmcnt(1)
	v_mov_b32_e32 v103, v108
	s_waitcnt vmcnt(0)
; __device__ __forceinline__ unsigned cvt_pk_bf16(float lo, float hi) { unsigned r; asm volatile("v_cvt_pk_bf16_f32 %0, %1, %2" : "=v"(r) : "v"(lo), "v"(hi)); return r; }
;     __device__ __forceinline__ void operator()(const AccT& acc, const Unit& u, int wr, int wc, int fr, int fq) const {
;     ...
;                     float v[8];
; #pragma unroll
;                     for (int jj = 0; jj < 4; ++jj) { v[jj] = acc[ai][bj][m][0][jj]; v[4 + jj] = acc[ai][bj][m][1][jj]; }
;                     if constexpr (ROPE) {
;                         const int t = t0 & 2047;
; #pragma unroll
;                         for (int hf = 0; hf < 2; ++hf) {
;                             f32x4 cs, sn;
;                             if (m < 2) { const float c1 = ropeA[(t >> 6) * 16 + d], s1 = ropeA[1024 + (t >> 6) * 16 + d]; cs = (f32x4){c1, c1, c1, c1}; sn = (f32x4){s1, s1, s1, s1}; }
;                             else { const float* cb = ropeA + 2048 + (d - 16) * 64 + (t & 63) + 4 * hf; cs = *(const f32x4*)(cb); sn = *(const f32x4*)(cb + 1024); }
; #pragma unroll
;                             for (int jj = 0; jj < 4; ++jj) { const float pr = __shfl_xor(v[4 * hf + jj], 4); v[4 * hf + jj] = v[4 * hf + jj] * cs[jj] + sgn * pr * sn[jj]; }
;                             __builtin_amdgcn_sched_barrier(0);
;                         }
;                     }
;                     float zf[8], zb[8]; zf[0] = zf0; zb[0] = zb0;
; #pragma unroll
;                     for (int jj = 1; jj < 8; ++jj) { zf[jj] = zf[jj - 1] * zfs; zb[jj] = zb[jj - 1] * zbs; }
;                     u32x4 wf, wb;
;                     wf.x = cvt_pk_bf16(v[0] * zf[0], v[1] * zf[1]); wf.y = cvt_pk_bf16(v[2] * zf[2], v[3] * zf[3]); wf.z = cvt_pk_bf16(v[4] * zf[4], v[5] * zf[5]); wf.w = cvt_pk_bf16(v[6] * zf[6], v[7] * zf[7]);
;                     wb.x = cvt_pk_bf16(v[0] * zb[0], v[1] * zb[1]); wb.y = cvt_pk_bf16(v[2] * zb[2], v[3] * zb[3]); wb.z = cvt_pk_bf16(v[4] * zb[4], v[5] * zb[5]); wb.w = cvt_pk_bf16(v[6] * zb[6], v[7] * zb[7]);
;                     *(u32x4*)(KTZ + (size_t)r * NT + t0) = wf;
;                     *(u32x4*)(KTZ + (size_t)(256 + r) * NT + t0) = wb;
;                     __builtin_amdgcn_sched_barrier(0);
	v_mov_b32_e32 v126, v116
	v_mov_b32_e32 v108, v89
	v_mov_b32_e32 v162, v117
	v_mov_b32_e32 v89, v110
	v_mov_b32_e32 v164, v118
	v_mov_b32_e32 v110, v91
	v_mov_b32_e32 v186, v119
	v_pk_mul_f32 v[90:91], v[102:103], v[126:127]
	v_pk_mul_f32 v[102:103], v[108:109], v[162:163]
	v_pk_mul_f32 v[88:89], v[88:89], v[164:165]
	v_pk_mul_f32 v[108:109], v[110:111], v[186:187]
	v_add_f32_e32 v90, v90, v91
	v_add_f32_e32 v91, v102, v103
	v_add_f32_e32 v88, v88, v89
	v_add_f32_e32 v89, v108, v109
	v_mul_f32_e32 v102, v180, v101
	v_mul_f32_e32 v103, v181, v153
	v_cvt_pk_bf16_f32 v108, v102, v103
	v_mul_f32_e32 v102, v167, v157
	v_mul_f32_e32 v103, v183, v161
	v_cvt_pk_bf16_f32 v109, v102, v103
	v_mul_f32_e32 v102, v182, v90
	v_mul_f32_e32 v103, v185, v91
	v_cvt_pk_bf16_f32 v110, v102, v103
	v_mul_f32_e32 v102, v184, v88
	v_mul_f32_e32 v103, v159, v89
	v_cvt_pk_bf16_f32 v111, v102, v103
	v_mul_f32_e32 v101, v150, v101
	v_mul_f32_e32 v102, v152, v153
	v_mul_f32_e32 v88, v151, v88
	v_mul_f32_e32 v89, v155, v89
	s_mov_b64 s[0:1], 0x400000
	v_cvt_pk_bf16_f32 v116, v101, v102
	v_mul_f32_e32 v101, v154, v157
	v_mul_f32_e32 v102, v156, v161
	v_cvt_pk_bf16_f32 v117, v101, v102
	v_mul_f32_e32 v90, v158, v90
	v_mul_f32_e32 v91, v160, v91
	v_cvt_pk_bf16_f32 v118, v90, v91
	v_cvt_pk_bf16_f32 v119, v88, v89
	v_lshl_add_u64 v[88:89], v[120:121], 0, s[0:1]
	s_mov_b32 s0, 0x400000
	v_add_co_u32_e64 v90, s[4:5], s0, v120
	s_mov_b64 s[0:1], 0x2400000
	s_nop 0
	v_addc_co_u32_e64 v91, s[4:5], 0, v121, s[4:5]
	global_store_dwordx4 v[90:91], v[108:111], off
	v_lshl_add_u64 v[90:91], v[120:121], 0, s[0:1]
	s_mov_b32 s0, 0x2400000
	v_add_co_u32_e64 v102, s[4:5], s0, v120
	s_nop 1
	v_addc_co_u32_e64 v103, s[4:5], 0, v121, s[4:5]
	global_store_dwordx4 v[102:103], v[116:119], off
	global_load_dwordx4 v[108:111], v[98:99], off
	s_nop 0
	global_load_dwordx4 v[116:119], v[96:97], off
	ds_bpermute_b32 v101, v177, v84
	ds_bpermute_b32 v103, v177, v85
	ds_bpermute_b32 v126, v177, v86
	ds_bpermute_b32 v153, v177, v87
	v_mov_b32_e32 v102, v84
	v_mov_b32_e32 v84, v86
	s_waitcnt lgkmcnt(3)
	v_cndmask_b32_e64 v127, v101, -v101, vcc
	s_waitcnt lgkmcnt(2)
	v_cndmask_b32_e64 v163, v103, -v103, vcc
	s_waitcnt lgkmcnt(1)
	v_cndmask_b32_e64 v165, v126, -v126, vcc
	s_waitcnt lgkmcnt(0)
	v_cndmask_b32_e64 v187, v153, -v153, vcc
	s_waitcnt vmcnt(1)
	v_mov_b32_e32 v103, v108
	s_waitcnt vmcnt(0)
	v_mov_b32_e32 v126, v116
	v_mov_b32_e32 v108, v85
	v_mov_b32_e32 v162, v117
	v_mov_b32_e32 v85, v110
	v_mov_b32_e32 v164, v118
	v_mov_b32_e32 v110, v87
	v_mov_b32_e32 v186, v119
	v_pk_mul_f32 v[86:87], v[102:103], v[126:127]
	v_pk_mul_f32 v[102:103], v[108:109], v[162:163]
	v_pk_mul_f32 v[84:85], v[84:85], v[164:165]
	v_pk_mul_f32 v[108:109], v[110:111], v[186:187]
	v_add_f32_e32 v101, v86, v87
	v_add_f32_e32 v153, v102, v103
	v_add_f32_e32 v157, v84, v85
	v_add_f32_e32 v161, v108, v109
	global_load_dwordx4 v[84:87], v[92:93], off offset:16
	global_load_dwordx4 v[108:111], v[94:95], off offset:16
	ds_bpermute_b32 v103, v177, v80
	ds_bpermute_b32 v116, v177, v81
	ds_bpermute_b32 v118, v177, v82
	ds_bpermute_b32 v126, v177, v83
	v_mov_b32_e32 v102, v80
	v_mov_b32_e32 v80, v82
	s_waitcnt lgkmcnt(3)
	v_cndmask_b32_e64 v117, v103, -v103, vcc
	s_waitcnt lgkmcnt(2)
	v_cndmask_b32_e64 v119, v116, -v116, vcc
	s_waitcnt lgkmcnt(1)
	v_cndmask_b32_e64 v127, v118, -v118, vcc
	s_waitcnt lgkmcnt(0)
	v_cndmask_b32_e64 v163, v126, -v126, vcc
	s_waitcnt vmcnt(1)
	v_mov_b32_e32 v103, v84
	s_waitcnt vmcnt(0)
	v_mov_b32_e32 v116, v108
	v_mov_b32_e32 v84, v81
	v_mov_b32_e32 v118, v109
	v_mov_b32_e32 v81, v86
	v_mov_b32_e32 v126, v110
	v_mov_b32_e32 v86, v83
	v_mov_b32_e32 v162, v111
	v_pk_mul_f32 v[82:83], v[102:103], v[116:117]
	v_pk_mul_f32 v[84:85], v[84:85], v[118:119]
	v_pk_mul_f32 v[80:81], v[80:81], v[126:127]
	v_pk_mul_f32 v[86:87], v[86:87], v[162:163]
	v_add_f32_e32 v102, v82, v83
	v_add_f32_e32 v103, v84, v85
	v_add_f32_e32 v108, v80, v81
	v_add_f32_e32 v87, v86, v87
	v_mul_f32_e32 v80, v180, v101
	v_mul_f32_e32 v81, v181, v153
	v_cvt_pk_bf16_f32 v80, v80, v81
	v_mul_f32_e32 v81, v167, v157
	v_mul_f32_e32 v82, v183, v161
	v_cvt_pk_bf16_f32 v81, v81, v82
	v_mul_f32_e32 v82, v182, v102
	v_mul_f32_e32 v83, v185, v103
	v_cvt_pk_bf16_f32 v82, v82, v83
	v_mul_f32_e32 v83, v184, v108
	v_mul_f32_e32 v84, v159, v87
	v_cvt_pk_bf16_f32 v83, v83, v84
	v_mul_f32_e32 v84, v150, v101
	v_mul_f32_e32 v85, v152, v153
	v_cvt_pk_bf16_f32 v84, v84, v85
	v_mul_f32_e32 v85, v154, v157
	v_mul_f32_e32 v86, v156, v161
	v_cvt_pk_bf16_f32 v85, v85, v86
	v_mul_f32_e32 v86, v158, v102
	v_mul_f32_e32 v101, v160, v103
	v_mul_f32_e32 v87, v155, v87
	v_cvt_pk_bf16_f32 v86, v86, v101
	v_mul_f32_e32 v101, v151, v108
	v_cvt_pk_bf16_f32 v87, v101, v87
	global_store_dwordx4 v[88:89], v[80:83], off offset:256
	global_store_dwordx4 v[90:91], v[84:87], off offset:256
	s_nop 0
	v_add_u32_e32 v80, 0x200, v100
	v_ashrrev_i32_e32 v81, 31, v80
	v_lshl_add_u64 v[82:83], s[24:25], 0, v[136:137]
	v_lshlrev_b64 v[100:101], 2, v[80:81]
	v_lshl_add_u64 v[80:81], v[82:83], 0, v[100:101]
	v_add_co_u32_e64 v82, s[4:5], s61, v80
	ds_bpermute_b32 v103, v177, v76
	s_nop 0
	v_addc_co_u32_e64 v83, s[4:5], 0, v81, s[4:5]
	global_load_dwordx4 v[84:87], v[82:83], off
	global_load_dwordx4 v[88:91], v[80:81], off
	ds_bpermute_b32 v108, v177, v77
	ds_bpermute_b32 v110, v177, v78
	ds_bpermute_b32 v116, v177, v79
	v_mov_b32_e32 v102, v76
	v_mov_b32_e32 v76, v78
	s_waitcnt lgkmcnt(3)
	v_cndmask_b32_e64 v109, v103, -v103, vcc
	s_waitcnt lgkmcnt(2)
	v_cndmask_b32_e64 v111, v108, -v108, vcc
	s_waitcnt lgkmcnt(1)
	v_cndmask_b32_e64 v117, v110, -v110, vcc
	s_waitcnt lgkmcnt(0)
; __device__ __forceinline__ unsigned cvt_pk_bf16(float lo, float hi) { unsigned r; asm volatile("v_cvt_pk_bf16_f32 %0, %1, %2" : "=v"(r) : "v"(lo), "v"(hi)); return r; }
;     __device__ __forceinline__ void operator()(const AccT& acc, const Unit& u, int wr, int wc, int fr, int fq) const {
;     ...
;                     float v[8];
; #pragma unroll
;                     for (int jj = 0; jj < 4; ++jj) { v[jj] = acc[ai][bj][m][0][jj]; v[4 + jj] = acc[ai][bj][m][1][jj]; }
;                     if constexpr (ROPE) {
;                         const int t = t0 & 2047;
; #pragma unroll
;                         for (int hf = 0; hf < 2; ++hf) {
;                             f32x4 cs, sn;
;                             if (m < 2) { const float c1 = ropeA[(t >> 6) * 16 + d], s1 = ropeA[1024 + (t >> 6) * 16 + d]; cs = (f32x4){c1, c1, c1, c1}; sn = (f32x4){s1, s1, s1, s1}; }
;                             else { const float* cb = ropeA + 2048 + (d - 16) * 64 + (t & 63) + 4 * hf; cs = *(const f32x4*)(cb); sn = *(const f32x4*)(cb + 1024); }
; #pragma unroll
;                             for (int jj = 0; jj < 4; ++jj) { const float pr = __shfl_xor(v[4 * hf + jj], 4); v[4 * hf + jj] = v[4 * hf + jj] * cs[jj] + sgn * pr * sn[jj]; }
;                             __builtin_amdgcn_sched_barrier(0);
;                         }
;                     }
;                     float zf[8], zb[8]; zf[0] = zf0; zb[0] = zb0;
; #pragma unroll
;                     for (int jj = 1; jj < 8; ++jj) { zf[jj] = zf[jj - 1] * zfs; zb[jj] = zb[jj - 1] * zbs; }
;                     u32x4 wf, wb;
;                     wf.x = cvt_pk_bf16(v[0] * zf[0], v[1] * zf[1]); wf.y = cvt_pk_bf16(v[2] * zf[2], v[3] * zf[3]); wf.z = cvt_pk_bf16(v[4] * zf[4], v[5] * zf[5]); wf.w = cvt_pk_bf16(v[6] * zf[6], v[7] * zf[7]);
;                     wb.x = cvt_pk_bf16(v[0] * zb[0], v[1] * zb[1]); wb.y = cvt_pk_bf16(v[2] * zb[2], v[3] * zb[3]); wb.z = cvt_pk_bf16(v[4] * zb[4], v[5] * zb[5]); wb.w = cvt_pk_bf16(v[6] * zb[6], v[7] * zb[7]);
;                     *(u32x4*)(KTZ + (size_t)r * NT + t0) = wf;
;                     *(u32x4*)(KTZ + (size_t)(256 + r) * NT + t0) = wb;
;                     __builtin_amdgcn_sched_barrier(0);
	v_cndmask_b32_e64 v119, v116, -v116, vcc
	s_waitcnt vmcnt(1)
	v_mov_b32_e32 v103, v84
	s_waitcnt vmcnt(0)
	v_mov_b32_e32 v108, v88
	v_mov_b32_e32 v84, v77
	v_mov_b32_e32 v110, v89
	v_mov_b32_e32 v77, v86
	v_mov_b32_e32 v116, v90
	v_mov_b32_e32 v86, v79
	v_mov_b32_e32 v118, v91
	v_pk_mul_f32 v[78:79], v[102:103], v[108:109]
	v_pk_mul_f32 v[84:85], v[84:85], v[110:111]
	v_pk_mul_f32 v[76:77], v[76:77], v[116:117]
	v_pk_mul_f32 v[86:87], v[86:87], v[118:119]
	v_add_f32_e32 v118, v78, v79
	v_add_f32_e32 v119, v84, v85
	v_add_f32_e32 v126, v76, v77
	v_add_f32_e32 v127, v86, v87
	v_lshl_add_u64 v[76:77], s[16:17], 0, v[100:101]
	v_lshl_add_u64 v[78:79], v[76:77], 0, v[136:137]
	v_add_co_u32_e64 v76, s[4:5], s62, v78
	ds_bpermute_b32 v101, v177, v72
	s_nop 0
	v_addc_co_u32_e64 v77, s[4:5], 0, v79, s[4:5]
	v_add_co_u32_e64 v78, s[4:5], s49, v78
	ds_bpermute_b32 v102, v177, v73
	s_nop 0
	v_addc_co_u32_e64 v79, s[4:5], 0, v79, s[4:5]
	global_load_dwordx4 v[84:87], v[76:77], off offset:16
	global_load_dwordx4 v[88:91], v[78:79], off offset:16
	ds_bpermute_b32 v108, v177, v74
	ds_bpermute_b32 v110, v177, v75
	v_mov_b32_e32 v100, v72
	v_mov_b32_e32 v72, v74
	s_waitcnt lgkmcnt(3)
	v_cndmask_b32_e64 v103, v101, -v101, vcc
	s_waitcnt lgkmcnt(2)
	v_cndmask_b32_e64 v109, v102, -v102, vcc
	s_waitcnt lgkmcnt(1)
	v_cndmask_b32_e64 v111, v108, -v108, vcc
	s_waitcnt lgkmcnt(0)
	v_cndmask_b32_e64 v117, v110, -v110, vcc
	s_waitcnt vmcnt(1)
	v_mov_b32_e32 v101, v84
	s_waitcnt vmcnt(0)
	v_mov_b32_e32 v102, v88
	v_mov_b32_e32 v84, v73
	v_mov_b32_e32 v108, v89
	v_mov_b32_e32 v73, v86
	v_mov_b32_e32 v110, v90
	v_mov_b32_e32 v86, v75
	v_mov_b32_e32 v116, v91
	v_pk_mul_f32 v[74:75], v[100:101], v[102:103]
	v_pk_mul_f32 v[84:85], v[84:85], v[108:109]
	v_pk_mul_f32 v[72:73], v[72:73], v[110:111]
	v_pk_mul_f32 v[86:87], v[86:87], v[116:117]
	v_add_f32_e32 v74, v74, v75
	v_add_f32_e32 v75, v84, v85
	v_add_f32_e32 v72, v72, v73
	v_add_f32_e32 v73, v86, v87
	v_mul_f32_e32 v84, v180, v118
	v_mul_f32_e32 v85, v181, v119
	v_cvt_pk_bf16_f32 v84, v84, v85
	v_mul_f32_e32 v85, v167, v126
	v_mul_f32_e32 v86, v183, v127
	v_cvt_pk_bf16_f32 v85, v85, v86
	v_mul_f32_e32 v86, v182, v74
	v_mul_f32_e32 v87, v185, v75
	v_cvt_pk_bf16_f32 v86, v86, v87
	v_mul_f32_e32 v87, v184, v72
	v_mul_f32_e32 v88, v159, v73
	v_cvt_pk_bf16_f32 v87, v87, v88
	v_mul_f32_e32 v88, v150, v118
	v_mul_f32_e32 v89, v152, v119
	v_cvt_pk_bf16_f32 v88, v88, v89
	v_mul_f32_e32 v89, v154, v126
	v_mul_f32_e32 v90, v156, v127
	v_mul_f32_e32 v72, v151, v72
	v_mul_f32_e32 v73, v155, v73
	s_mov_b64 s[0:1], 0x600000
	v_cvt_pk_bf16_f32 v89, v89, v90
	v_mul_f32_e32 v74, v158, v74
	v_mul_f32_e32 v75, v160, v75
	v_cvt_pk_bf16_f32 v90, v74, v75
	v_cvt_pk_bf16_f32 v91, v72, v73
	v_lshl_add_u64 v[72:73], v[120:121], 0, s[0:1]
	s_mov_b32 s0, 0x600000
	v_add_co_u32_e64 v74, s[4:5], s0, v120
	s_mov_b64 s[0:1], 0x2600000
	s_nop 0
	v_addc_co_u32_e64 v75, s[4:5], 0, v121, s[4:5]
	global_store_dwordx4 v[74:75], v[84:87], off
	v_lshl_add_u64 v[74:75], v[120:121], 0, s[0:1]
	s_mov_b32 s0, 0x2600000
	v_add_co_u32_e64 v84, s[4:5], s0, v120
	s_nop 1
	v_addc_co_u32_e64 v85, s[4:5], 0, v121, s[4:5]
	global_store_dwordx4 v[84:85], v[88:91], off
	global_load_dwordx4 v[84:87], v[82:83], off
	s_nop 0
	global_load_dwordx4 v[88:91], v[80:81], off
	ds_bpermute_b32 v101, v177, v68
	ds_bpermute_b32 v102, v177, v69
	ds_bpermute_b32 v108, v177, v70
	ds_bpermute_b32 v110, v177, v71
	v_mov_b32_e32 v100, v68
	v_mov_b32_e32 v68, v70
	s_waitcnt lgkmcnt(3)
	v_cndmask_b32_e64 v103, v101, -v101, vcc
	s_waitcnt lgkmcnt(2)
	v_cndmask_b32_e64 v109, v102, -v102, vcc
	s_waitcnt lgkmcnt(1)
	v_cndmask_b32_e64 v111, v108, -v108, vcc
	s_waitcnt lgkmcnt(0)
	v_cndmask_b32_e64 v117, v110, -v110, vcc
	s_waitcnt vmcnt(1)
	v_mov_b32_e32 v101, v84
	s_waitcnt vmcnt(0)
	v_mov_b32_e32 v102, v88
	v_mov_b32_e32 v84, v69
	v_mov_b32_e32 v108, v89
	v_mov_b32_e32 v69, v86
	v_mov_b32_e32 v110, v90
	v_mov_b32_e32 v86, v71
	v_mov_b32_e32 v116, v91
	v_pk_mul_f32 v[70:71], v[100:101], v[102:103]
	v_pk_mul_f32 v[84:85], v[84:85], v[108:109]
	v_pk_mul_f32 v[68:69], v[68:69], v[110:111]
	v_pk_mul_f32 v[86:87], v[86:87], v[116:117]
	v_add_f32_e32 v110, v70, v71
	v_add_f32_e32 v111, v84, v85
	v_add_f32_e32 v116, v68, v69
	v_add_f32_e32 v117, v86, v87
	global_load_dwordx4 v[68:71], v[76:77], off offset:16
	global_load_dwordx4 v[84:87], v[78:79], off offset:16
	ds_bpermute_b32 v89, v177, v64
	ds_bpermute_b32 v90, v177, v65
	ds_bpermute_b32 v100, v177, v66
	ds_bpermute_b32 v102, v177, v67
	v_mov_b32_e32 v88, v64
	v_mov_b32_e32 v64, v66
	s_waitcnt lgkmcnt(3)
	v_cndmask_b32_e64 v91, v89, -v89, vcc
	s_waitcnt lgkmcnt(2)
	v_cndmask_b32_e64 v101, v90, -v90, vcc
	s_waitcnt lgkmcnt(1)
	v_cndmask_b32_e64 v103, v100, -v100, vcc
	s_waitcnt lgkmcnt(0)
	v_cndmask_b32_e64 v109, v102, -v102, vcc
	s_waitcnt vmcnt(1)
	v_mov_b32_e32 v89, v68
	s_waitcnt vmcnt(0)
;     __device__ __forceinline__ void operator()(const AccT& acc, const Unit& u, int wr, int wc, int fr, int fq) const {
;     ...
;         for (int ai = 0; ai < 2; ++ai) {
;             const int hh = 2 * ai + wr;
;             const float l2f = lgd[hh] * 1.4426950408889634f, l2b = lgd[4 + hh] * 1.4426950408889634f;
;             const float zf0 = exp2f((float)(127 - o0) * l2f), zfs = exp2f(-l2f), zb0 = exp2f((float)o0 * l2b), zbs = exp2f(l2b);
; #pragma unroll
;             for (int m = 0; m < 4; ++m) {
;                 const int r = rbase + ai * 128 + m * 16;
;                 const int d = 4 * (2 * m + (fr >> 3)) + j;
; #pragma unroll
;                 for (int bj = 0; bj < 2; ++bj) {
;                     const int t0 = tb + bj * 128;
;                     float v[8];
; #pragma unroll
;                     for (int jj = 0; jj < 4; ++jj) { v[jj] = acc[ai][bj][m][0][jj]; v[4 + jj] = acc[ai][bj][m][1][jj]; }
;                     if constexpr (ROPE) {
;                         const int t = t0 & 2047;
; #pragma unroll
;                         for (int hf = 0; hf < 2; ++hf) {
;                             f32x4 cs, sn;
;                             if (m < 2) { const float c1 = ropeA[(t >> 6) * 16 + d], s1 = ropeA[1024 + (t >> 6) * 16 + d]; cs = (f32x4){c1, c1, c1, c1}; sn = (f32x4){s1, s1, s1, s1}; }
;                             else { const float* cb = ropeA + 2048 + (d - 16) * 64 + (t & 63) + 4 * hf; cs = *(const f32x4*)(cb); sn = *(const f32x4*)(cb + 1024); }
; #pragma unroll
;                             for (int jj = 0; jj < 4; ++jj) { const float pr = __shfl_xor(v[4 * hf + jj], 4); v[4 * hf + jj] = v[4 * hf + jj] * cs[jj] + sgn * pr * sn[jj]; }
;                             __builtin_amdgcn_sched_barrier(0);
;                         }
;                     }
;                     float zf[8], zb[8]; zf[0] = zf0; zb[0] = zb0;
; #pragma unroll
;                     for (int jj = 1; jj < 8; ++jj) { zf[jj] = zf[jj - 1] * zfs; zb[jj] = zb[jj - 1] * zbs; }
;                     u32x4 wf, wb;
;                     wf.x = cvt_pk_bf16(v[0] * zf[0], v[1] * zf[1]); wf.y = cvt_pk_bf16(v[2] * zf[2], v[3] * zf[3]); wf.z = cvt_pk_bf16(v[4] * zf[4], v[5] * zf[5]); wf.w = cvt_pk_bf16(v[6] * zf[6], v[7] * zf[7]);
	v_mov_b32_e32 v90, v84
	v_mov_b32_e32 v68, v65
	v_mov_b32_e32 v100, v85
	v_mov_b32_e32 v65, v70
	v_mov_b32_e32 v102, v86
	v_mov_b32_e32 v70, v67
	v_mov_b32_e32 v108, v87
	v_pk_mul_f32 v[66:67], v[88:89], v[90:91]
	v_pk_mul_f32 v[68:69], v[68:69], v[100:101]
	v_pk_mul_f32 v[64:65], v[64:65], v[102:103]
	v_pk_mul_f32 v[70:71], v[70:71], v[108:109]
	v_add_f32_e32 v84, v66, v67
	v_add_f32_e32 v85, v68, v69
	v_add_f32_e32 v86, v64, v65
	v_add_f32_e32 v71, v70, v71
	v_mul_f32_e32 v64, v180, v110
	v_mul_f32_e32 v65, v181, v111
	v_cvt_pk_bf16_f32 v64, v64, v65
	v_mul_f32_e32 v65, v167, v116
	v_mul_f32_e32 v66, v183, v117
	v_cvt_pk_bf16_f32 v65, v65, v66
	v_mul_f32_e32 v66, v182, v84
	v_mul_f32_e32 v67, v185, v85
	v_cvt_pk_bf16_f32 v66, v66, v67
	v_mul_f32_e32 v67, v184, v86
	v_mul_f32_e32 v68, v159, v71
	v_cvt_pk_bf16_f32 v67, v67, v68
	v_mul_f32_e32 v68, v150, v110
	v_mul_f32_e32 v69, v152, v111
	v_cvt_pk_bf16_f32 v68, v68, v69
	v_mul_f32_e32 v69, v154, v116
	v_mul_f32_e32 v70, v156, v117
	v_cvt_pk_bf16_f32 v69, v69, v70
	v_mul_f32_e32 v70, v158, v84
	v_mul_f32_e32 v84, v160, v85
	v_mul_f32_e32 v71, v155, v71
	v_cvt_pk_bf16_f32 v70, v70, v84
	v_mul_f32_e32 v84, v151, v86
	v_cvt_pk_bf16_f32 v71, v84, v71
	global_store_dwordx4 v[72:73], v[64:67], off offset:256
	global_store_dwordx4 v[74:75], v[68:71], off offset:256
	global_load_dword v64, v137, s[22:23] offset:8
	s_nop 0
	global_load_dword v70, v137, s[22:23] offset:24
	global_load_dword v67, v[146:147], off
	global_load_dword v74, v[148:149], off
	ds_bpermute_b32 v65, v177, v60
	ds_bpermute_b32 v68, v177, v62
	v_mov_b32_e32 v66, v60
	ds_bpermute_b32 v60, v177, v61
	ds_bpermute_b32 v71, v177, v63
	s_waitcnt lgkmcnt(3)
	v_cndmask_b32_e64 v75, v65, -v65, vcc
	s_waitcnt lgkmcnt(2)
	v_cndmask_b32_e64 v65, v68, -v68, vcc
	s_waitcnt vmcnt(3)
	v_mul_f32_e32 v72, 0x3fb8aa3b, v64
	s_waitcnt vmcnt(2)
	v_mul_f32_e32 v73, 0x3fb8aa3b, v70
	v_mul_f32_e32 v84, v72, v179
	s_waitcnt vmcnt(0)
	v_pk_mul_f32 v[68:69], v[66:67], v[74:75]
	s_waitcnt lgkmcnt(1)
	v_cndmask_b32_e64 v75, v60, -v60, vcc
	v_mov_b32_e32 v66, v61
	v_cmp_lt_f32_e64 s[4:5], s60, v72
	v_mul_f32_e32 v87, v73, v178
	v_pk_mul_f32 v[60:61], v[66:67], v[74:75]
	s_waitcnt lgkmcnt(0)
	v_cndmask_b32_e64 v75, v71, -v71, vcc
	v_mov_b32_e32 v66, v63
	v_cmp_gt_f32_e64 s[8:9], s59, v84
	v_cndmask_b32_e64 v86, 0, v176, s[4:5]
	v_cmp_gt_f32_e64 s[6:7], s59, v73
	s_and_b64 s[0:1], s[4:5], exec
	v_cmp_gt_f32_e64 s[4:5], s59, v87
	v_add_f32_e32 v110, v60, v61
	v_pk_mul_f32 v[60:61], v[66:67], v[74:75]
	v_cndmask_b32_e64 v66, 0, v176, s[8:9]
	v_cndmask_b32_e64 v88, 0, v176, s[6:7]
	v_add_f32_e32 v89, v68, v69
	v_fmac_f32_e32 v86, 0xbfb8aa3b, v64
	v_cndmask_b32_e64 v69, 0, v176, s[4:5]
	v_fmac_f32_e32 v66, v72, v179
	v_fmac_f32_e32 v88, 0x3fb8aa3b, v70
	v_exp_f32_e32 v68, v86
	v_fmac_f32_e32 v69, v73, v178
	v_exp_f32_e32 v66, v66
	v_exp_f32_e32 v70, v88
	v_exp_f32_e32 v69, v69
	v_cndmask_b32_e64 v63, 0, v175, s[8:9]
	s_cselect_b32 s8, 0xffffffc0, 0
	s_and_b64 s[0:1], s[6:7], exec
	v_cndmask_b32_e64 v64, 0, v175, s[4:5]
	s_cselect_b32 s0, 0xffffffc0, 0
	v_ldexp_f32 v100, v68, s8
	v_ldexp_f32 v63, v66, v63
	v_mul_f32_e32 v85, v62, v74
	v_ldexp_f32 v90, v70, s0
	v_ldexp_f32 v64, v69, v64
	v_mul_f32_e32 v75, v100, v63
	v_add_f32_e32 v111, v60, v61
	global_load_dword v108, v[148:149], off
	global_load_dword v69, v[146:147], off
	ds_bpermute_b32 v61, v177, v57
	ds_bpermute_b32 v60, v177, v56
	v_mov_b32_e32 v68, v57
	ds_bpermute_b32 v57, v177, v59
	ds_bpermute_b32 v66, v177, v58
	s_waitcnt lgkmcnt(3)
	v_cndmask_b32_e64 v109, v61, -v61, vcc
	s_waitcnt lgkmcnt(2)
	v_cndmask_b32_e64 v70, v60, -v60, vcc
	s_waitcnt lgkmcnt(0)
	v_cndmask_b32_e64 v72, v66, -v66, vcc
	s_waitcnt vmcnt(1)
	v_mul_f32_e32 v71, v56, v108
	s_waitcnt vmcnt(0)
	v_pk_mul_f32 v[60:61], v[68:69], v[108:109]
	v_cndmask_b32_e64 v109, v57, -v57, vcc
	v_mov_b32_e32 v68, v59
	v_add_f32_e32 v57, v60, v61
	v_pk_mul_f32 v[60:61], v[68:69], v[108:109]
	s_nop 0
	v_add_f32_e32 v59, v60, v61
	v_mov_b32_e32 v91, v67
	v_pk_mul_f32 v[60:61], v[90:91], v[64:65]
	v_mov_b32_e32 v91, v85
	v_pk_mul_f32 v[66:67], v[90:91], v[60:61]
	v_mov_b32_e32 v91, v69
	v_mov_b32_e32 v67, v70
	v_mul_f32_e32 v84, v100, v75
	v_pk_mul_f32 v[68:69], v[90:91], v[66:67]
	v_mov_b32_e32 v70, v90
	v_mul_f32_e32 v86, v100, v84
	v_pk_mul_f32 v[70:71], v[70:71], v[68:69]
	v_mul_f32_e32 v85, v100, v86
	v_mov_b32_e32 v71, v72
	v_mul_f32_e32 v88, v100, v85
	v_pk_mul_f32 v[72:73], v[90:91], v[70:71]
	v_fma_f32 v61, v62, v74, v61
	v_mul_f32_e32 v87, v100, v88
	v_mul_f32_e32 v65, v90, v72
	v_mul_f32_e32 v62, v84, v61
	v_fma_f32 v56, v56, v108, v69
	v_mul_f32_e32 v71, v100, v87
	v_mul_f32_e32 v67, v90, v65
	v_mul_f32_e32 v90, v63, v89
	v_mul_f32_e32 v91, v75, v110
	v_cvt_pk_bf16_f32 v100, v90, v91
	v_mul_f32_e32 v74, v86, v111
	v_cvt_pk_bf16_f32 v101, v62, v74
	v_mul_f32_e32 v62, v85, v56
	v_fma_f32 v58, v58, v108, v73
	v_mul_f32_e32 v69, v88, v57
	v_cvt_pk_bf16_f32 v102, v62, v69
	v_mul_f32_e32 v62, v87, v58
	v_mul_f32_e32 v69, v71, v59
	v_cvt_pk_bf16_f32 v103, v62, v69
	v_mul_f32_e32 v62, v64, v89
	v_mul_f32_e32 v56, v70, v56
	v_mul_f32_e32 v57, v72, v57
	v_mul_f32_e32 v69, v60, v110
	v_cvt_pk_bf16_f32 v108, v62, v69
	v_mul_f32_e32 v61, v66, v61
	v_mul_f32_e32 v62, v68, v111
	v_cvt_pk_bf16_f32 v109, v61, v62
	v_cvt_pk_bf16_f32 v110, v56, v57
	v_mul_f32_e32 v56, v65, v58
	v_mul_f32_e32 v57, v67, v59
	s_mov_b64 s[0:1], 0x1000000
	v_cvt_pk_bf16_f32 v111, v56, v57
	v_lshl_add_u64 v[56:57], v[120:121], 0, s[0:1]
	s_mov_b32 s0, 0x1000000
	v_add_co_u32_e64 v58, s[4:5], s0, v120
	s_mov_b64 s[0:1], 0x3000000
	s_nop 0
	v_addc_co_u32_e64 v59, s[4:5], 0, v121, s[4:5]
	global_store_dwordx4 v[58:59], v[100:103], off
	v_lshl_add_u64 v[58:59], v[120:121], 0, s[0:1]
	s_mov_b32 s0, 0x3000000
	v_add_co_u32_e64 v90, s[4:5], s0, v120
	s_nop 1
	v_addc_co_u32_e64 v91, s[4:5], 0, v121, s[4:5]
	global_store_dwordx4 v[90:91], v[108:111], off
	global_load_dword v91, v[122:123], off
	s_nop 0
	global_load_dword v100, v[124:125], off
	ds_bpermute_b32 v61, v177, v52
	v_mov_b32_e32 v90, v52
	ds_bpermute_b32 v52, v177, v53
	ds_bpermute_b32 v62, v177, v54
	ds_bpermute_b32 v69, v177, v55
	s_waitcnt lgkmcnt(3)
;     __device__ __forceinline__ void operator()(const AccT& acc, const Unit& u, int wr, int wc, int fr, int fq) const {
;     ...
;             for (int m = 0; m < 4; ++m) {
;                 const int r = rbase + ai * 128 + m * 16;
;                 const int d = 4 * (2 * m + (fr >> 3)) + j;
; #pragma unroll
;                 for (int bj = 0; bj < 2; ++bj) {
;                     const int t0 = tb + bj * 128;
;                     float v[8];
; #pragma unroll
;                     for (int jj = 0; jj < 4; ++jj) { v[jj] = acc[ai][bj][m][0][jj]; v[4 + jj] = acc[ai][bj][m][1][jj]; }
;                     if constexpr (ROPE) {
;                         const int t = t0 & 2047;
; #pragma unroll
;                         for (int hf = 0; hf < 2; ++hf) {
;                             f32x4 cs, sn;
;                             if (m < 2) { const float c1 = ropeA[(t >> 6) * 16 + d], s1 = ropeA[1024 + (t >> 6) * 16 + d]; cs = (f32x4){c1, c1, c1, c1}; sn = (f32x4){s1, s1, s1, s1}; }
;                             else { const float* cb = ropeA + 2048 + (d - 16) * 64 + (t & 63) + 4 * hf; cs = *(const f32x4*)(cb); sn = *(const f32x4*)(cb + 1024); }
; #pragma unroll
;                             for (int jj = 0; jj < 4; ++jj) { const float pr = __shfl_xor(v[4 * hf + jj], 4); v[4 * hf + jj] = v[4 * hf + jj] * cs[jj] + sgn * pr * sn[jj]; }
;                             __builtin_amdgcn_sched_barrier(0);
;                         }
;                     }
;                     float zf[8], zb[8]; zf[0] = zf0; zb[0] = zb0;
; #pragma unroll
;                     for (int jj = 1; jj < 8; ++jj) { zf[jj] = zf[jj - 1] * zfs; zb[jj] = zb[jj - 1] * zbs; }
;                     u32x4 wf, wb;
;                     wf.x = cvt_pk_bf16(v[0] * zf[0], v[1] * zf[1]); wf.y = cvt_pk_bf16(v[2] * zf[2], v[3] * zf[3]); wf.z = cvt_pk_bf16(v[4] * zf[4], v[5] * zf[5]); wf.w = cvt_pk_bf16(v[6] * zf[6], v[7] * zf[7]);
;                     wb.x = cvt_pk_bf16(v[0] * zb[0], v[1] * zb[1]); wb.y = cvt_pk_bf16(v[2] * zb[2], v[3] * zb[3]); wb.z = cvt_pk_bf16(v[4] * zb[4], v[5] * zb[5]); wb.w = cvt_pk_bf16(v[6] * zb[6], v[7] * zb[7]);
;                     *(u32x4*)(KTZ + (size_t)r * NT + t0) = wf;
;                     *(u32x4*)(KTZ + (size_t)(256 + r) * NT + t0) = wb;
;                     __builtin_amdgcn_sched_barrier(0);
	v_cndmask_b32_e64 v101, v61, -v61, vcc
	s_waitcnt vmcnt(0)
	v_pk_mul_f32 v[102:103], v[90:91], v[100:101]
	s_waitcnt lgkmcnt(2)
	v_cndmask_b32_e64 v101, v52, -v52, vcc
	v_mov_b32_e32 v90, v53
	v_pk_mul_f32 v[52:53], v[90:91], v[100:101]
	s_waitcnt lgkmcnt(1)
	v_cndmask_b32_e64 v101, v62, -v62, vcc
	v_mov_b32_e32 v90, v54
	v_add_f32_e32 v62, v52, v53
	v_pk_mul_f32 v[52:53], v[90:91], v[100:101]
	s_waitcnt lgkmcnt(0)
	v_cndmask_b32_e64 v101, v69, -v69, vcc
	v_mov_b32_e32 v90, v55
	v_add_f32_e32 v69, v52, v53
	v_pk_mul_f32 v[52:53], v[90:91], v[100:101]
	v_add_f32_e32 v61, v102, v103
	v_add_f32_e32 v73, v52, v53
	global_load_dword v53, v[122:123], off
	global_load_dword v54, v[124:125], off
	ds_bpermute_b32 v55, v177, v48
	v_mov_b32_e32 v52, v48
	ds_bpermute_b32 v48, v177, v49
	ds_bpermute_b32 v74, v177, v50
	ds_bpermute_b32 v89, v177, v51
	s_waitcnt lgkmcnt(3)
	v_cndmask_b32_e64 v55, v55, -v55, vcc
	s_waitcnt vmcnt(0)
	v_pk_mul_f32 v[90:91], v[52:53], v[54:55]
	s_waitcnt lgkmcnt(2)
	v_cndmask_b32_e64 v55, v48, -v48, vcc
	v_mov_b32_e32 v52, v49
	v_pk_mul_f32 v[48:49], v[52:53], v[54:55]
	s_waitcnt lgkmcnt(1)
	v_cndmask_b32_e64 v55, v74, -v74, vcc
	v_mov_b32_e32 v52, v50
	v_add_f32_e32 v74, v48, v49
	v_pk_mul_f32 v[48:49], v[52:53], v[54:55]
	s_waitcnt lgkmcnt(0)
	v_cndmask_b32_e64 v55, v89, -v89, vcc
	v_mov_b32_e32 v52, v51
	v_add_f32_e32 v89, v48, v49
	v_pk_mul_f32 v[48:49], v[52:53], v[54:55]
	v_add_f32_e32 v90, v90, v91
	v_add_f32_e32 v55, v48, v49
	v_mul_f32_e32 v48, v63, v61
	v_mul_f32_e32 v49, v75, v62
	v_cvt_pk_bf16_f32 v48, v48, v49
	v_mul_f32_e32 v49, v84, v69
	v_mul_f32_e32 v50, v86, v73
	v_cvt_pk_bf16_f32 v49, v49, v50
	v_mul_f32_e32 v50, v85, v90
	v_mul_f32_e32 v51, v88, v74
	v_cvt_pk_bf16_f32 v50, v50, v51
	v_mul_f32_e32 v51, v87, v89
	v_mul_f32_e32 v52, v71, v55
	v_cvt_pk_bf16_f32 v51, v51, v52
	v_mul_f32_e32 v52, v64, v61
	v_mul_f32_e32 v53, v60, v62
	v_cvt_pk_bf16_f32 v52, v52, v53
	v_mul_f32_e32 v53, v66, v69
	v_mul_f32_e32 v54, v68, v73
	v_cvt_pk_bf16_f32 v53, v53, v54
	v_mul_f32_e32 v54, v70, v90
	v_mul_f32_e32 v61, v72, v74
	v_mul_f32_e32 v55, v67, v55
	v_cvt_pk_bf16_f32 v54, v54, v61
	v_mul_f32_e32 v61, v65, v89
	v_cvt_pk_bf16_f32 v55, v61, v55
	global_store_dwordx4 v[56:57], v[48:51], off offset:256
	global_store_dwordx4 v[58:59], v[52:55], off offset:256
	global_load_dword v49, v[112:113], off
	s_nop 0
	global_load_dword v50, v[114:115], off
	ds_bpermute_b32 v51, v177, v44
	v_mov_b32_e32 v48, v44
	ds_bpermute_b32 v44, v177, v45
	ds_bpermute_b32 v54, v177, v46
	ds_bpermute_b32 v55, v177, v47
	s_waitcnt lgkmcnt(3)
	v_cndmask_b32_e64 v51, v51, -v51, vcc
	s_waitcnt vmcnt(0)
	v_pk_mul_f32 v[52:53], v[48:49], v[50:51]
	s_waitcnt lgkmcnt(2)
	v_cndmask_b32_e64 v51, v44, -v44, vcc
	v_mov_b32_e32 v48, v45
	v_pk_mul_f32 v[44:45], v[48:49], v[50:51]
	s_waitcnt lgkmcnt(1)
	v_cndmask_b32_e64 v51, v54, -v54, vcc
	v_mov_b32_e32 v48, v46
	v_add_f32_e32 v52, v52, v53
	v_add_f32_e32 v53, v44, v45
	v_pk_mul_f32 v[44:45], v[48:49], v[50:51]
	s_waitcnt lgkmcnt(0)
	v_cndmask_b32_e64 v51, v55, -v55, vcc
	v_mov_b32_e32 v48, v47
	v_add_f32_e32 v54, v44, v45
	v_pk_mul_f32 v[44:45], v[48:49], v[50:51]
	s_nop 0
	v_add_f32_e32 v50, v44, v45
	global_load_dword v45, v[112:113], off
	global_load_dword v46, v[114:115], off
	ds_bpermute_b32 v47, v177, v40
	v_mov_b32_e32 v44, v40
	ds_bpermute_b32 v40, v177, v41
	ds_bpermute_b32 v51, v177, v42
	ds_bpermute_b32 v55, v177, v43
	s_waitcnt lgkmcnt(3)
	v_cndmask_b32_e64 v47, v47, -v47, vcc
	s_waitcnt vmcnt(0)
	v_pk_mul_f32 v[48:49], v[44:45], v[46:47]
	s_waitcnt lgkmcnt(2)
	v_cndmask_b32_e64 v47, v40, -v40, vcc
	v_mov_b32_e32 v44, v41
	v_pk_mul_f32 v[40:41], v[44:45], v[46:47]
	s_waitcnt lgkmcnt(1)
	v_cndmask_b32_e64 v47, v51, -v51, vcc
	v_mov_b32_e32 v44, v42
	v_add_f32_e32 v48, v48, v49
	v_add_f32_e32 v49, v40, v41
	v_pk_mul_f32 v[40:41], v[44:45], v[46:47]
	s_waitcnt lgkmcnt(0)
	v_cndmask_b32_e64 v47, v55, -v55, vcc
	v_mov_b32_e32 v44, v43
	v_add_f32_e32 v51, v40, v41
	v_pk_mul_f32 v[40:41], v[44:45], v[46:47]
	s_nop 0
	v_add_f32_e32 v40, v40, v41
	v_mul_f32_e32 v41, v63, v52
	v_mul_f32_e32 v42, v75, v53
	v_cvt_pk_bf16_f32 v42, v41, v42
	v_mul_f32_e32 v41, v84, v54
	v_mul_f32_e32 v43, v86, v50
	v_cvt_pk_bf16_f32 v43, v41, v43
	v_mul_f32_e32 v41, v85, v48
	v_mul_f32_e32 v44, v88, v49
	v_cvt_pk_bf16_f32 v44, v41, v44
	v_mul_f32_e32 v41, v87, v51
	v_mul_f32_e32 v45, v71, v40
	v_cvt_pk_bf16_f32 v45, v41, v45
	v_mul_f32_e32 v41, v64, v52
	v_mul_f32_e32 v46, v60, v53
	v_cvt_pk_bf16_f32 v46, v41, v46
	v_mul_f32_e32 v41, v66, v54
	v_mul_f32_e32 v47, v68, v50
	v_cvt_pk_bf16_f32 v47, v41, v47
	v_mul_f32_e32 v41, v70, v48
	v_mul_f32_e32 v48, v72, v49
	v_cvt_pk_bf16_f32 v48, v41, v48
	v_mul_f32_e32 v41, v65, v51
	v_mul_f32_e32 v40, v67, v40
	s_mov_b64 s[0:1], 0x1200000
	v_cvt_pk_bf16_f32 v49, v41, v40
	v_lshl_add_u64 v[40:41], v[120:121], 0, s[0:1]
	s_mov_b32 s0, 0x1200000
	v_add_co_u32_e64 v50, s[4:5], s0, v120
	s_mov_b64 s[0:1], 0x3200000
	s_nop 0
	v_addc_co_u32_e64 v51, s[4:5], 0, v121, s[4:5]
	global_store_dwordx4 v[50:51], v[42:45], off
	s_nop 1
	v_lshl_add_u64 v[42:43], v[120:121], 0, s[0:1]
	s_mov_b32 s0, 0x3200000
	v_add_co_u32_e64 v44, s[4:5], s0, v120
	s_nop 1
	v_addc_co_u32_e64 v45, s[4:5], 0, v121, s[4:5]
	global_store_dwordx4 v[44:45], v[46:49], off
	global_load_dword v45, v[104:105], off
	s_nop 0
	global_load_dword v46, v[106:107], off
	ds_bpermute_b32 v47, v177, v36
	v_mov_b32_e32 v44, v36
	ds_bpermute_b32 v36, v177, v37
	ds_bpermute_b32 v50, v177, v38
	ds_bpermute_b32 v51, v177, v39
	s_waitcnt lgkmcnt(3)
	v_cndmask_b32_e64 v47, v47, -v47, vcc
	s_waitcnt vmcnt(0)
	v_pk_mul_f32 v[48:49], v[44:45], v[46:47]
	s_waitcnt lgkmcnt(2)
;     __device__ __forceinline__ void operator()(const AccT& acc, const Unit& u, int wr, int wc, int fr, int fq) const {
;     ...
;             for (int m = 0; m < 4; ++m) {
;                 const int r = rbase + ai * 128 + m * 16;
;                 const int d = 4 * (2 * m + (fr >> 3)) + j;
; #pragma unroll
;                 for (int bj = 0; bj < 2; ++bj) {
;                     const int t0 = tb + bj * 128;
;                     float v[8];
; #pragma unroll
;                     for (int jj = 0; jj < 4; ++jj) { v[jj] = acc[ai][bj][m][0][jj]; v[4 + jj] = acc[ai][bj][m][1][jj]; }
;                     if constexpr (ROPE) {
;                         const int t = t0 & 2047;
; #pragma unroll
;                         for (int hf = 0; hf < 2; ++hf) {
;                             f32x4 cs, sn;
;                             if (m < 2) { const float c1 = ropeA[(t >> 6) * 16 + d], s1 = ropeA[1024 + (t >> 6) * 16 + d]; cs = (f32x4){c1, c1, c1, c1}; sn = (f32x4){s1, s1, s1, s1}; }
;                             else { const float* cb = ropeA + 2048 + (d - 16) * 64 + (t & 63) + 4 * hf; cs = *(const f32x4*)(cb); sn = *(const f32x4*)(cb + 1024); }
; #pragma unroll
;                             for (int jj = 0; jj < 4; ++jj) { const float pr = __shfl_xor(v[4 * hf + jj], 4); v[4 * hf + jj] = v[4 * hf + jj] * cs[jj] + sgn * pr * sn[jj]; }
;                             __builtin_amdgcn_sched_barrier(0);
;                         }
;                     }
;                     float zf[8], zb[8]; zf[0] = zf0; zb[0] = zb0;
; #pragma unroll
;                     for (int jj = 1; jj < 8; ++jj) { zf[jj] = zf[jj - 1] * zfs; zb[jj] = zb[jj - 1] * zbs; }
;                     u32x4 wf, wb;
;                     wf.x = cvt_pk_bf16(v[0] * zf[0], v[1] * zf[1]); wf.y = cvt_pk_bf16(v[2] * zf[2], v[3] * zf[3]); wf.z = cvt_pk_bf16(v[4] * zf[4], v[5] * zf[5]); wf.w = cvt_pk_bf16(v[6] * zf[6], v[7] * zf[7]);
;                     wb.x = cvt_pk_bf16(v[0] * zb[0], v[1] * zb[1]); wb.y = cvt_pk_bf16(v[2] * zb[2], v[3] * zb[3]); wb.z = cvt_pk_bf16(v[4] * zb[4], v[5] * zb[5]); wb.w = cvt_pk_bf16(v[6] * zb[6], v[7] * zb[7]);
;                     *(u32x4*)(KTZ + (size_t)r * NT + t0) = wf;
;                     *(u32x4*)(KTZ + (size_t)(256 + r) * NT + t0) = wb;
;                     __builtin_amdgcn_sched_barrier(0);
	v_cndmask_b32_e64 v47, v36, -v36, vcc
	v_mov_b32_e32 v44, v37
	v_pk_mul_f32 v[36:37], v[44:45], v[46:47]
	s_waitcnt lgkmcnt(1)
	v_cndmask_b32_e64 v47, v50, -v50, vcc
	v_mov_b32_e32 v44, v38
	v_add_f32_e32 v48, v48, v49
	v_add_f32_e32 v49, v36, v37
	v_pk_mul_f32 v[36:37], v[44:45], v[46:47]
	s_waitcnt lgkmcnt(0)
	v_cndmask_b32_e64 v47, v51, -v51, vcc
	v_mov_b32_e32 v44, v39
	v_add_f32_e32 v50, v36, v37
	v_pk_mul_f32 v[36:37], v[44:45], v[46:47]
	s_nop 0
	v_add_f32_e32 v46, v36, v37
	global_load_dword v37, v[104:105], off
	global_load_dword v38, v[106:107], off
	ds_bpermute_b32 v39, v177, v32
	v_mov_b32_e32 v36, v32
	ds_bpermute_b32 v32, v177, v33
	ds_bpermute_b32 v47, v177, v34
	ds_bpermute_b32 v51, v177, v35
	s_waitcnt lgkmcnt(3)
	v_cndmask_b32_e64 v39, v39, -v39, vcc
	s_waitcnt vmcnt(0)
	v_pk_mul_f32 v[44:45], v[36:37], v[38:39]
	s_waitcnt lgkmcnt(2)
	v_cndmask_b32_e64 v39, v32, -v32, vcc
	v_mov_b32_e32 v36, v33
	v_pk_mul_f32 v[32:33], v[36:37], v[38:39]
	s_waitcnt lgkmcnt(1)
	v_cndmask_b32_e64 v39, v47, -v47, vcc
	v_mov_b32_e32 v36, v34
	v_add_f32_e32 v44, v44, v45
	v_add_f32_e32 v45, v32, v33
	v_pk_mul_f32 v[32:33], v[36:37], v[38:39]
	s_waitcnt lgkmcnt(0)
	v_cndmask_b32_e64 v39, v51, -v51, vcc
	v_mov_b32_e32 v36, v35
	v_add_f32_e32 v47, v32, v33
	v_pk_mul_f32 v[32:33], v[36:37], v[38:39]
	s_nop 0
	v_add_f32_e32 v39, v32, v33
	v_mul_f32_e32 v32, v63, v48
	v_mul_f32_e32 v33, v75, v49
	v_cvt_pk_bf16_f32 v32, v32, v33
	v_mul_f32_e32 v33, v84, v50
	v_mul_f32_e32 v34, v86, v46
	v_cvt_pk_bf16_f32 v33, v33, v34
	v_mul_f32_e32 v34, v85, v44
	v_mul_f32_e32 v35, v88, v45
	v_cvt_pk_bf16_f32 v34, v34, v35
	v_mul_f32_e32 v35, v87, v47
	v_mul_f32_e32 v36, v71, v39
	v_cvt_pk_bf16_f32 v35, v35, v36
	v_mul_f32_e32 v36, v64, v48
	v_mul_f32_e32 v37, v60, v49
	v_cvt_pk_bf16_f32 v36, v36, v37
	v_mul_f32_e32 v37, v66, v50
	v_mul_f32_e32 v38, v68, v46
	v_cvt_pk_bf16_f32 v37, v37, v38
	v_mul_f32_e32 v38, v70, v44
	v_mul_f32_e32 v44, v72, v45
	v_mul_f32_e32 v39, v67, v39
	v_cvt_pk_bf16_f32 v38, v38, v44
	v_mul_f32_e32 v44, v65, v47
	v_cvt_pk_bf16_f32 v39, v44, v39
	global_store_dwordx4 v[40:41], v[32:35], off offset:256
	global_store_dwordx4 v[42:43], v[36:39], off offset:256
	global_load_dwordx4 v[32:35], v[98:99], off
	s_nop 0
	global_load_dwordx4 v[36:39], v[96:97], off
	ds_bpermute_b32 v41, v177, v28
	ds_bpermute_b32 v42, v177, v29
	ds_bpermute_b32 v44, v177, v30
	ds_bpermute_b32 v46, v177, v31
	v_mov_b32_e32 v40, v28
	v_mov_b32_e32 v28, v30
	s_waitcnt lgkmcnt(3)
	v_cndmask_b32_e64 v43, v41, -v41, vcc
	s_waitcnt lgkmcnt(2)
	v_cndmask_b32_e64 v45, v42, -v42, vcc
	s_waitcnt lgkmcnt(1)
	v_cndmask_b32_e64 v47, v44, -v44, vcc
	s_waitcnt lgkmcnt(0)
	v_cndmask_b32_e64 v49, v46, -v46, vcc
	s_waitcnt vmcnt(1)
	v_mov_b32_e32 v41, v32
	s_waitcnt vmcnt(0)
	v_mov_b32_e32 v42, v36
	v_mov_b32_e32 v32, v29
	v_mov_b32_e32 v44, v37
	v_mov_b32_e32 v29, v34
	v_mov_b32_e32 v46, v38
	v_mov_b32_e32 v34, v31
	v_mov_b32_e32 v48, v39
	v_pk_mul_f32 v[30:31], v[40:41], v[42:43]
	v_pk_mul_f32 v[32:33], v[32:33], v[44:45]
	v_pk_mul_f32 v[28:29], v[28:29], v[46:47]
	v_pk_mul_f32 v[34:35], v[34:35], v[48:49]
	v_add_f32_e32 v46, v30, v31
	v_add_f32_e32 v47, v32, v33
	v_add_f32_e32 v48, v28, v29
	v_add_f32_e32 v49, v34, v35
	global_load_dwordx4 v[28:31], v[92:93], off offset:16
	global_load_dwordx4 v[32:35], v[94:95], off offset:16
	ds_bpermute_b32 v37, v177, v24
	ds_bpermute_b32 v38, v177, v25
	ds_bpermute_b32 v40, v177, v26
	ds_bpermute_b32 v42, v177, v27
	v_mov_b32_e32 v36, v24
	v_mov_b32_e32 v24, v26
	s_waitcnt lgkmcnt(3)
	v_cndmask_b32_e64 v39, v37, -v37, vcc
	s_waitcnt lgkmcnt(2)
	v_cndmask_b32_e64 v41, v38, -v38, vcc
	s_waitcnt lgkmcnt(1)
	v_cndmask_b32_e64 v43, v40, -v40, vcc
	s_waitcnt lgkmcnt(0)
	v_cndmask_b32_e64 v45, v42, -v42, vcc
	s_waitcnt vmcnt(1)
	v_mov_b32_e32 v37, v28
	s_waitcnt vmcnt(0)
	v_mov_b32_e32 v38, v32
	v_mov_b32_e32 v28, v25
	v_mov_b32_e32 v40, v33
	v_mov_b32_e32 v25, v30
	v_mov_b32_e32 v42, v34
	v_mov_b32_e32 v30, v27
	v_mov_b32_e32 v44, v35
	v_pk_mul_f32 v[26:27], v[36:37], v[38:39]
	v_pk_mul_f32 v[28:29], v[28:29], v[40:41]
	v_pk_mul_f32 v[24:25], v[24:25], v[42:43]
	v_pk_mul_f32 v[30:31], v[30:31], v[44:45]
	v_add_f32_e32 v32, v26, v27
	v_add_f32_e32 v33, v28, v29
	v_add_f32_e32 v24, v24, v25
	v_add_f32_e32 v25, v30, v31
	v_mul_f32_e32 v26, v63, v46
	v_mul_f32_e32 v27, v75, v47
	v_cvt_pk_bf16_f32 v26, v26, v27
	v_mul_f32_e32 v27, v84, v48
	v_mul_f32_e32 v28, v86, v49
	v_cvt_pk_bf16_f32 v27, v27, v28
	v_mul_f32_e32 v28, v85, v32
	v_mul_f32_e32 v29, v88, v33
	v_cvt_pk_bf16_f32 v28, v28, v29
	v_mul_f32_e32 v29, v87, v24
	v_mul_f32_e32 v30, v71, v25
	v_cvt_pk_bf16_f32 v29, v29, v30
	v_mul_f32_e32 v30, v64, v46
	v_mul_f32_e32 v31, v60, v47
	v_cvt_pk_bf16_f32 v30, v30, v31
	v_mul_f32_e32 v31, v66, v48
	v_mul_f32_e32 v32, v70, v32
	v_mul_f32_e32 v33, v72, v33
	v_mul_f32_e32 v24, v65, v24
	v_mul_f32_e32 v25, v67, v25
	s_mov_b64 s[0:1], 0x1400000
	v_mul_f32_e32 v34, v68, v49
	v_cvt_pk_bf16_f32 v31, v31, v34
	v_cvt_pk_bf16_f32 v32, v32, v33
	v_cvt_pk_bf16_f32 v33, v24, v25
	v_lshl_add_u64 v[24:25], v[120:121], 0, s[0:1]
	s_mov_b32 s0, 0x1400000
	v_add_co_u32_e64 v34, s[4:5], s0, v120
	s_mov_b64 s[0:1], 0x3400000
	s_nop 0
	v_addc_co_u32_e64 v35, s[4:5], 0, v121, s[4:5]
	global_store_dwordx4 v[34:35], v[26:29], off
	s_nop 1
	v_lshl_add_u64 v[26:27], v[120:121], 0, s[0:1]
	s_mov_b32 s0, 0x3400000
	v_add_co_u32_e64 v28, s[4:5], s0, v120
	s_nop 1
	v_addc_co_u32_e64 v29, s[4:5], 0, v121, s[4:5]
	global_store_dwordx4 v[28:29], v[30:33], off
	global_load_dwordx4 v[28:31], v[98:99], off
	s_nop 0
	global_load_dwordx4 v[32:35], v[96:97], off
	ds_bpermute_b32 v37, v177, v20
	ds_bpermute_b32 v38, v177, v21
	ds_bpermute_b32 v40, v177, v22
	ds_bpermute_b32 v42, v177, v23
	v_mov_b32_e32 v36, v20
	v_mov_b32_e32 v20, v22
	s_waitcnt lgkmcnt(3)
; __device__ __forceinline__ unsigned cvt_pk_bf16(float lo, float hi) { unsigned r; asm volatile("v_cvt_pk_bf16_f32 %0, %1, %2" : "=v"(r) : "v"(lo), "v"(hi)); return r; }
;     __device__ __forceinline__ void operator()(const AccT& acc, const Unit& u, int wr, int wc, int fr, int fq) const {
;     ...
;                     float v[8];
; #pragma unroll
;                     for (int jj = 0; jj < 4; ++jj) { v[jj] = acc[ai][bj][m][0][jj]; v[4 + jj] = acc[ai][bj][m][1][jj]; }
;                     if constexpr (ROPE) {
;                         const int t = t0 & 2047;
; #pragma unroll
;                         for (int hf = 0; hf < 2; ++hf) {
;                             f32x4 cs, sn;
;                             if (m < 2) { const float c1 = ropeA[(t >> 6) * 16 + d], s1 = ropeA[1024 + (t >> 6) * 16 + d]; cs = (f32x4){c1, c1, c1, c1}; sn = (f32x4){s1, s1, s1, s1}; }
;                             else { const float* cb = ropeA + 2048 + (d - 16) * 64 + (t & 63) + 4 * hf; cs = *(const f32x4*)(cb); sn = *(const f32x4*)(cb + 1024); }
; #pragma unroll
;                             for (int jj = 0; jj < 4; ++jj) { const float pr = __shfl_xor(v[4 * hf + jj], 4); v[4 * hf + jj] = v[4 * hf + jj] * cs[jj] + sgn * pr * sn[jj]; }
;                             __builtin_amdgcn_sched_barrier(0);
;                         }
;                     }
;                     float zf[8], zb[8]; zf[0] = zf0; zb[0] = zb0;
; #pragma unroll
;                     for (int jj = 1; jj < 8; ++jj) { zf[jj] = zf[jj - 1] * zfs; zb[jj] = zb[jj - 1] * zbs; }
;                     u32x4 wf, wb;
;                     wf.x = cvt_pk_bf16(v[0] * zf[0], v[1] * zf[1]); wf.y = cvt_pk_bf16(v[2] * zf[2], v[3] * zf[3]); wf.z = cvt_pk_bf16(v[4] * zf[4], v[5] * zf[5]); wf.w = cvt_pk_bf16(v[6] * zf[6], v[7] * zf[7]);
;                     wb.x = cvt_pk_bf16(v[0] * zb[0], v[1] * zb[1]); wb.y = cvt_pk_bf16(v[2] * zb[2], v[3] * zb[3]); wb.z = cvt_pk_bf16(v[4] * zb[4], v[5] * zb[5]); wb.w = cvt_pk_bf16(v[6] * zb[6], v[7] * zb[7]);
;                     *(u32x4*)(KTZ + (size_t)r * NT + t0) = wf;
;                     *(u32x4*)(KTZ + (size_t)(256 + r) * NT + t0) = wb;
;                     __builtin_amdgcn_sched_barrier(0);
	v_cndmask_b32_e64 v39, v37, -v37, vcc
	s_waitcnt lgkmcnt(2)
	v_cndmask_b32_e64 v41, v38, -v38, vcc
	s_waitcnt lgkmcnt(1)
	v_cndmask_b32_e64 v43, v40, -v40, vcc
	s_waitcnt lgkmcnt(0)
	v_cndmask_b32_e64 v45, v42, -v42, vcc
	s_waitcnt vmcnt(1)
	v_mov_b32_e32 v37, v28
	s_waitcnt vmcnt(0)
	v_mov_b32_e32 v38, v32
	v_mov_b32_e32 v28, v21
	v_mov_b32_e32 v40, v33
	v_mov_b32_e32 v21, v30
	v_mov_b32_e32 v42, v34
	v_mov_b32_e32 v30, v23
	v_mov_b32_e32 v44, v35
	v_pk_mul_f32 v[22:23], v[36:37], v[38:39]
	v_pk_mul_f32 v[28:29], v[28:29], v[40:41]
	v_pk_mul_f32 v[20:21], v[20:21], v[42:43]
	v_pk_mul_f32 v[30:31], v[30:31], v[44:45]
	v_add_f32_e32 v42, v22, v23
	v_add_f32_e32 v43, v28, v29
	v_add_f32_e32 v44, v20, v21
	v_add_f32_e32 v45, v30, v31
	global_load_dwordx4 v[20:23], v[92:93], off offset:16
	global_load_dwordx4 v[28:31], v[94:95], off offset:16
	ds_bpermute_b32 v33, v177, v16
	ds_bpermute_b32 v34, v177, v17
	ds_bpermute_b32 v36, v177, v18
	ds_bpermute_b32 v38, v177, v19
	v_mov_b32_e32 v32, v16
	v_mov_b32_e32 v16, v18
	s_waitcnt lgkmcnt(3)
	v_cndmask_b32_e64 v35, v33, -v33, vcc
	s_waitcnt lgkmcnt(2)
	v_cndmask_b32_e64 v37, v34, -v34, vcc
	s_waitcnt lgkmcnt(1)
	v_cndmask_b32_e64 v39, v36, -v36, vcc
	s_waitcnt lgkmcnt(0)
	v_cndmask_b32_e64 v41, v38, -v38, vcc
	s_waitcnt vmcnt(1)
	v_mov_b32_e32 v33, v20
	s_waitcnt vmcnt(0)
	v_mov_b32_e32 v34, v28
	v_mov_b32_e32 v20, v17
	v_mov_b32_e32 v36, v29
	v_mov_b32_e32 v17, v22
	v_mov_b32_e32 v38, v30
	v_mov_b32_e32 v22, v19
	v_mov_b32_e32 v40, v31
	v_pk_mul_f32 v[18:19], v[32:33], v[34:35]
	v_pk_mul_f32 v[20:21], v[20:21], v[36:37]
	v_pk_mul_f32 v[16:17], v[16:17], v[38:39]
	v_pk_mul_f32 v[22:23], v[22:23], v[40:41]
	v_add_f32_e32 v28, v18, v19
	v_add_f32_e32 v29, v20, v21
	v_add_f32_e32 v30, v16, v17
	v_add_f32_e32 v23, v22, v23
	v_mul_f32_e32 v16, v63, v42
	v_mul_f32_e32 v17, v75, v43
	v_cvt_pk_bf16_f32 v16, v16, v17
	v_mul_f32_e32 v17, v84, v44
	v_mul_f32_e32 v18, v86, v45
	v_cvt_pk_bf16_f32 v17, v17, v18
	v_mul_f32_e32 v18, v85, v28
	v_mul_f32_e32 v19, v88, v29
	v_cvt_pk_bf16_f32 v18, v18, v19
	v_mul_f32_e32 v19, v87, v30
	v_mul_f32_e32 v20, v71, v23
	v_cvt_pk_bf16_f32 v19, v19, v20
	v_mul_f32_e32 v20, v64, v42
	v_mul_f32_e32 v21, v60, v43
	v_cvt_pk_bf16_f32 v20, v20, v21
	v_mul_f32_e32 v21, v66, v44
	v_mul_f32_e32 v22, v68, v45
	v_cvt_pk_bf16_f32 v21, v21, v22
	v_mul_f32_e32 v22, v70, v28
	v_mul_f32_e32 v28, v72, v29
	v_mul_f32_e32 v23, v67, v23
	v_cvt_pk_bf16_f32 v22, v22, v28
	v_mul_f32_e32 v28, v65, v30
	v_cvt_pk_bf16_f32 v23, v28, v23
	global_store_dwordx4 v[24:25], v[16:19], off offset:256
	global_store_dwordx4 v[26:27], v[20:23], off offset:256
	global_load_dwordx4 v[16:19], v[82:83], off
	s_nop 0
	global_load_dwordx4 v[20:23], v[80:81], off
	ds_bpermute_b32 v25, v177, v12
	ds_bpermute_b32 v26, v177, v13
	ds_bpermute_b32 v28, v177, v14
	ds_bpermute_b32 v30, v177, v15
	v_mov_b32_e32 v24, v12
	v_mov_b32_e32 v12, v14
	s_waitcnt lgkmcnt(3)
	v_cndmask_b32_e64 v27, v25, -v25, vcc
	s_waitcnt lgkmcnt(2)
	v_cndmask_b32_e64 v29, v26, -v26, vcc
	s_waitcnt lgkmcnt(1)
	v_cndmask_b32_e64 v31, v28, -v28, vcc
	s_waitcnt lgkmcnt(0)
	v_cndmask_b32_e64 v33, v30, -v30, vcc
	s_waitcnt vmcnt(1)
	v_mov_b32_e32 v25, v16
	s_waitcnt vmcnt(0)
	v_mov_b32_e32 v26, v20
	v_mov_b32_e32 v16, v13
	v_mov_b32_e32 v28, v21
	v_mov_b32_e32 v13, v18
	v_mov_b32_e32 v30, v22
	v_mov_b32_e32 v18, v15
	v_mov_b32_e32 v32, v23
	v_pk_mul_f32 v[14:15], v[24:25], v[26:27]
	v_pk_mul_f32 v[16:17], v[16:17], v[28:29]
	v_pk_mul_f32 v[12:13], v[12:13], v[30:31]
	v_pk_mul_f32 v[18:19], v[18:19], v[32:33]
	v_add_f32_e32 v30, v14, v15
	v_add_f32_e32 v31, v16, v17
	v_add_f32_e32 v32, v12, v13
	v_add_f32_e32 v33, v18, v19
	global_load_dwordx4 v[12:15], v[76:77], off offset:16
	global_load_dwordx4 v[16:19], v[78:79], off offset:16
	ds_bpermute_b32 v21, v177, v8
	ds_bpermute_b32 v22, v177, v9
	ds_bpermute_b32 v24, v177, v10
	ds_bpermute_b32 v26, v177, v11
	v_mov_b32_e32 v20, v8
	v_mov_b32_e32 v8, v10
	s_waitcnt lgkmcnt(3)
	v_cndmask_b32_e64 v23, v21, -v21, vcc
	s_waitcnt lgkmcnt(2)
	v_cndmask_b32_e64 v25, v22, -v22, vcc
	s_waitcnt lgkmcnt(1)
	v_cndmask_b32_e64 v27, v24, -v24, vcc
	s_waitcnt lgkmcnt(0)
	v_cndmask_b32_e64 v29, v26, -v26, vcc
	s_waitcnt vmcnt(1)
	v_mov_b32_e32 v21, v12
	s_waitcnt vmcnt(0)
; __device__ __forceinline__ unsigned cvt_pk_bf16(float lo, float hi) { unsigned r; asm volatile("v_cvt_pk_bf16_f32 %0, %1, %2" : "=v"(r) : "v"(lo), "v"(hi)); return r; }
; #define PG8_WAIT_V(n) asm volatile("s_waitcnt vmcnt(" #n ")" ::: "memory")
; #define PG8_BAR __builtin_amdgcn_s_barrier()
; template <class Epi, class Sched>
; __device__ __forceinline__ void gemm_phase(LAS unsigned char* lds, const Gemm g, const Sched& S, const Epi& E) {
;     ...
;         E(acc, cur, wr, wc, fr, fq);
;         if (!has_next) break;
; #pragma unroll
;         for (int a = 0; a < 2; ++a)
; #pragma unroll
;             for (int b = 0; b < 2; ++b)
; #pragma unroll
;                 for (int m = 0; m < 4; ++m)
; #pragma unroll
;                     for (int n = 0; n < 2; ++n) acc[a][b][m][n] = (f32x4){0.f, 0.f, 0.f, 0.f};
;         cur = nxt; cA = nA; cB = nB; ++ui;
;     }
;     PG8_WAIT_V(0);
;     if (wr == 0) PG8_BAR;
;     PG8_BAR;
;     __device__ __forceinline__ void operator()(const AccT& acc, const Unit& u, int wr, int wc, int fr, int fq) const {
;     ...
;                     float zf[8], zb[8]; zf[0] = zf0; zb[0] = zb0;
; #pragma unroll
;                     for (int jj = 1; jj < 8; ++jj) { zf[jj] = zf[jj - 1] * zfs; zb[jj] = zb[jj - 1] * zbs; }
;                     u32x4 wf, wb;
;                     wf.x = cvt_pk_bf16(v[0] * zf[0], v[1] * zf[1]); wf.y = cvt_pk_bf16(v[2] * zf[2], v[3] * zf[3]); wf.z = cvt_pk_bf16(v[4] * zf[4], v[5] * zf[5]); wf.w = cvt_pk_bf16(v[6] * zf[6], v[7] * zf[7]);
;                     wb.x = cvt_pk_bf16(v[0] * zb[0], v[1] * zb[1]); wb.y = cvt_pk_bf16(v[2] * zb[2], v[3] * zb[3]); wb.z = cvt_pk_bf16(v[4] * zb[4], v[5] * zb[5]); wb.w = cvt_pk_bf16(v[6] * zb[6], v[7] * zb[7]);
;                     *(u32x4*)(KTZ + (size_t)r * NT + t0) = wf;
;                     *(u32x4*)(KTZ + (size_t)(256 + r) * NT + t0) = wb;
;                     __builtin_amdgcn_sched_barrier(0);
	v_mov_b32_e32 v22, v16
	v_mov_b32_e32 v12, v9
	v_mov_b32_e32 v24, v17
	v_mov_b32_e32 v9, v14
	v_mov_b32_e32 v26, v18
	v_mov_b32_e32 v14, v11
	v_mov_b32_e32 v28, v19
	v_pk_mul_f32 v[10:11], v[20:21], v[22:23]
	v_pk_mul_f32 v[12:13], v[12:13], v[24:25]
	v_pk_mul_f32 v[8:9], v[8:9], v[26:27]
	v_pk_mul_f32 v[14:15], v[14:15], v[28:29]
	v_add_f32_e32 v16, v10, v11
	v_add_f32_e32 v17, v12, v13
	v_add_f32_e32 v8, v8, v9
	v_add_f32_e32 v9, v14, v15
	v_mul_f32_e32 v10, v63, v30
	v_mul_f32_e32 v11, v75, v31
	v_cvt_pk_bf16_f32 v10, v10, v11
	v_mul_f32_e32 v11, v84, v32
	v_mul_f32_e32 v12, v86, v33
	v_cvt_pk_bf16_f32 v11, v11, v12
	v_mul_f32_e32 v12, v85, v16
	v_mul_f32_e32 v13, v88, v17
	v_cvt_pk_bf16_f32 v12, v12, v13
	v_mul_f32_e32 v13, v87, v8
	v_mul_f32_e32 v14, v71, v9
	v_cvt_pk_bf16_f32 v13, v13, v14
	v_mul_f32_e32 v14, v64, v30
	v_mul_f32_e32 v15, v60, v31
	v_cvt_pk_bf16_f32 v14, v14, v15
	v_mul_f32_e32 v15, v66, v32
	v_mul_f32_e32 v18, v68, v33
	v_cvt_pk_bf16_f32 v15, v15, v18
	v_add_co_u32_e64 v18, s[4:5], s63, v120
	v_mul_f32_e32 v16, v70, v16
	v_mul_f32_e32 v17, v72, v17
	v_addc_co_u32_e64 v19, s[4:5], 0, v121, s[4:5]
	v_cvt_pk_bf16_f32 v16, v16, v17
	v_mul_f32_e32 v8, v65, v8
	v_mul_f32_e32 v9, v67, v9
	v_cvt_pk_bf16_f32 v17, v8, v9
	global_store_dwordx4 v[18:19], v[10:13], off
	v_lshl_add_u64 v[8:9], v[120:121], 0, s[26:27]
	s_nop 0
	v_add_co_u32_e64 v12, s[4:5], s64, v120
	v_lshl_add_u64 v[10:11], v[120:121], 0, s[28:29]
	s_nop 0
	v_addc_co_u32_e64 v13, s[4:5], 0, v121, s[4:5]
	global_store_dwordx4 v[12:13], v[14:17], off
	global_load_dwordx4 v[12:15], v[82:83], off
	s_nop 0
	global_load_dwordx4 v[16:19], v[80:81], off
	ds_bpermute_b32 v34, v177, v4
	ds_bpermute_b32 v32, v177, v5
	ds_bpermute_b32 v33, v177, v6
	ds_bpermute_b32 v28, v177, v7
	global_load_dwordx4 v[20:23], v[76:77], off offset:16
	global_load_dwordx4 v[24:27], v[78:79], off offset:16
	s_waitcnt lgkmcnt(0)
	v_cndmask_b32_e64 v29, v28, -v28, vcc
	v_mov_b32_e32 v30, v7
	s_waitcnt vmcnt(3)
	v_mov_b32_e32 v31, v15
	s_waitcnt vmcnt(2)
	v_mov_b32_e32 v28, v19
	v_cndmask_b32_e64 v19, v33, -v33, vcc
	v_mov_b32_e32 v7, v14
	v_cndmask_b32_e64 v15, v32, -v32, vcc
	v_mov_b32_e32 v32, v5
	v_mov_b32_e32 v33, v13
	v_mov_b32_e32 v14, v17
	v_cndmask_b32_e64 v17, v34, -v34, vcc
	v_mov_b32_e32 v5, v12
	ds_bpermute_b32 v13, v177, v0
	v_mov_b32_e32 v12, v0
	ds_bpermute_b32 v34, v177, v1
	ds_bpermute_b32 v35, v177, v2
	v_mov_b32_e32 v0, v2
	ds_bpermute_b32 v2, v177, v3
	v_pk_mul_f32 v[28:29], v[30:31], v[28:29]
	v_pk_mul_f32 v[6:7], v[6:7], v[18:19]
	v_pk_mul_f32 v[14:15], v[32:33], v[14:15]
	v_pk_mul_f32 v[4:5], v[4:5], v[16:17]
	v_add_f32_e32 v18, v28, v29
	v_add_f32_e32 v19, v6, v7
	v_add_f32_e32 v28, v14, v15
	v_add_f32_e32 v29, v4, v5
	s_waitcnt lgkmcnt(3)
	v_cndmask_b32_e64 v5, v13, -v13, vcc
	s_waitcnt lgkmcnt(2)
	v_cndmask_b32_e64 v7, v34, -v34, vcc
	s_waitcnt lgkmcnt(1)
	v_cndmask_b32_e64 v15, v35, -v35, vcc
	s_waitcnt lgkmcnt(0)
	v_cndmask_b32_e64 v17, v2, -v2, vcc
	s_waitcnt vmcnt(1)
	v_mov_b32_e32 v13, v20
	s_waitcnt vmcnt(0)
	v_mov_b32_e32 v4, v24
	v_mov_b32_e32 v20, v1
	v_mov_b32_e32 v6, v25
	v_mov_b32_e32 v1, v22
	v_mov_b32_e32 v14, v26
	v_mov_b32_e32 v22, v3
	v_mov_b32_e32 v16, v27
	v_pk_mul_f32 v[2:3], v[12:13], v[4:5]
	v_pk_mul_f32 v[4:5], v[20:21], v[6:7]
	v_pk_mul_f32 v[0:1], v[0:1], v[14:15]
	v_pk_mul_f32 v[6:7], v[22:23], v[16:17]
	v_add_f32_e32 v12, v2, v3
	v_add_f32_e32 v13, v4, v5
	v_add_f32_e32 v14, v0, v1
	v_add_f32_e32 v7, v6, v7
	v_mul_f32_e32 v0, v63, v29
	v_mul_f32_e32 v1, v75, v28
	v_cvt_pk_bf16_f32 v0, v0, v1
	v_mul_f32_e32 v1, v84, v19
	v_mul_f32_e32 v2, v86, v18
	v_cvt_pk_bf16_f32 v1, v1, v2
	v_mul_f32_e32 v2, v85, v12
	v_mul_f32_e32 v3, v88, v13
	v_cvt_pk_bf16_f32 v2, v2, v3
	v_mul_f32_e32 v3, v87, v14
	v_mul_f32_e32 v4, v71, v7
	v_cvt_pk_bf16_f32 v3, v3, v4
	v_mul_f32_e32 v4, v64, v29
	v_mul_f32_e32 v5, v60, v28
	v_cvt_pk_bf16_f32 v4, v4, v5
	v_mul_f32_e32 v5, v66, v19
	v_mul_f32_e32 v6, v68, v18
	v_cvt_pk_bf16_f32 v5, v5, v6
	v_mul_f32_e32 v6, v70, v12
	v_mul_f32_e32 v12, v72, v13
	v_mul_f32_e32 v7, v67, v7
	v_cvt_pk_bf16_f32 v6, v6, v12
	v_mul_f32_e32 v12, v65, v14
	v_cvt_pk_bf16_f32 v7, v12, v7
	global_store_dwordx4 v[8:9], v[0:3], off offset:256
	global_store_dwordx4 v[10:11], v[4:7], off offset:256
	s_and_b64 vcc, exec, s[2:3]
	s_mov_b32 s33, s30
	s_mov_b64 s[4:5], s[38:39]
	s_mov_b64 s[0:1], s[36:37]
	s_cbranch_vccz .LBB0_606
	s_waitcnt vmcnt(0)
	s_cmpk_gt_u32 s42, 0xff
	s_cbranch_scc1 .LBB0_617
	s_barrier

; #define PG8_STAGE(bufoff, gbase, voff) do { _Pragma("unroll") for (int _i = 0; _i < 2; ++_i) \
;         __builtin_amdgcn_global_load_lds((const unsigned*)((const char*)(gbase) + (voff)[_i]), (LAS unsigned*)(lds + (bufoff) + ldsw + _i * 8192), 16, 0, 0); } while (0)
; #define PG8_LDA(dst, b, h) do { _Pragma("unroll") for (int m = 0; m < 4; ++m) _Pragma("unroll") for (int k = 0; k < 2; ++k) dst[m][k] = *(const LAS bf16x8*)(lds + PG8_SA(b, h) + aoff + m * 2048 + k * 1024); } while (0)
; #define PG8_LDB(dst, b, h) do { _Pragma("unroll") for (int n = 0; n < 2; ++n) _Pragma("unroll") for (int k = 0; k < 2; ++k) dst[n][k] = *(const LAS bf16x8*)(lds + PG8_SB(b, h) + boff + n * 2048 + k * 1024); } while (0)
; #define PG8_MMA(ai, bj, At, Bt) do { __builtin_amdgcn_s_setprio(1); _Pragma("unroll") for (int m = 0; m < 4; ++m) _Pragma("unroll") for (int n = 0; n < 2; ++n) _Pragma("unroll") for (int k = 0; k < 2; ++k) \
;         acc[ai][bj][m][n] = __builtin_amdgcn_mfma_f32_16x16x32_bf16(Bt[n][k], At[m][k], acc[ai][bj][m][n], 0, 0, 0); __builtin_amdgcn_s_setprio(0); } while (0)
; #define PG8_WAIT_L(n) asm volatile("s_waitcnt lgkmcnt(" #n ")" ::: "memory")
; template <class Epi, class Sched>
; __device__ __forceinline__ void gemm_phase(LAS unsigned char* lds, const Gemm g, const Sched& S, const Epi& E) {
;     ...
;         const bool has_next = S.next(ui + 1, nxt);
;         const char* nA = has_next ? (const char*)g.A + (size_t)nxt.pm * tstep : cA; const char* nB = has_next ? (const char*)g.Bt + (size_t)nxt.pn * tstep : cB;
;         for (int t = 0; t < nt; t += 2) {
;             const bool last = (t == nt - 2);
;             const char* a1 = cA + (size_t)(t + 1) * kstep;
;             const char* a2 = last ? nA : cA + (size_t)(t + 2) * kstep; const char* b2 = last ? nB : cB + (size_t)(t + 2) * kstep;
;             const char* a3 = a2 + kstep; const char* b3 = b2 + kstep;
;             PG8_LDB(B0, 0, 0); PG8_SCHED; PG8_LDA(At, 0, 0); PG8_STAGE(PG8_SA(1, 1), a1 + hstep, voffA);
;             PG8_WAIT_L(8); PG8_BAR; PG8_WAIT_L(0); PG8_MMA(0, 0, At, B0); PG8_BAR; PG8_SCHED;
;             PG8_LDB(B1, 0, 1); PG8_STAGE(PG8_SB(0, 0), b2, voffB);
;             PG8_BAR; PG8_WAIT_L(0); PG8_MMA(0, 1, At, B1); PG8_BAR;
;             PG8_LDA(At, 0, 1); PG8_STAGE(PG8_SA(0, 0), a2, voffA);
;             PG8_BAR; PG8_WAIT_L(0); PG8_MMA(1, 0, At, B0); PG8_BAR; PG8_SCHED;
.LBB0_632:
	s_ashr_i32 s23, s22, 31
	v_cmp_lt_i64_e32 vcc, s[24:25], v[140:141]
	s_lshl_b64 s[24:25], s[22:23], 19
	s_add_u32 s24, s38, s24
	s_addc_u32 s25, s39, s25
	s_and_b64 s[26:27], vcc, exec
	s_cselect_b32 s23, s25, s31
	s_cselect_b32 s61, s24, s30
	s_ashr_i32 s21, s20, 31
	s_lshl_b64 s[26:27], s[20:21], 19
	s_add_u32 s26, s96, s26
	s_addc_u32 s27, s97, s27
	s_and_b64 s[36:37], vcc, exec
	s_cselect_b32 s21, s27, s35
	s_cselect_b32 s62, s26, s34
	s_add_u32 s30, s30, 0x40080
	s_addc_u32 s31, s31, 0
	s_add_u32 s63, s34, 0x100
	s_addc_u32 s64, s35, 0
	s_mov_b32 s65, -2
	s_waitcnt lgkmcnt(0)
	ds_read_b128 v[150:153], v147
	ds_read_b128 v[154:157], v147 offset:1024
	ds_read_b128 v[158:161], v147 offset:2048
	ds_read_b128 v[162:165], v147 offset:3072
	s_add_u32 s34, s30, 0xfffc0080
	s_addc_u32 s35, s31, -1
	s_cmp_eq_u32 s65, 12
	s_cselect_b32 s37, s23, s35
	s_cselect_b32 s36, s61, s34
	s_cselect_b32 s35, s21, s64
	s_cselect_b32 s34, s62, s63
	s_add_i32 m0, s29, 0xc000
	ds_read_b128 v[166:169], v148
	ds_read_b128 v[170:173], v148 offset:1024
	ds_read_b128 v[174:177], v148 offset:2048
	ds_read_b128 v[178:181], v148 offset:3072
	ds_read_b128 v[182:185], v148 offset:4096
	ds_read_b128 v[186:189], v148 offset:5120
	ds_read_b128 v[190:193], v148 offset:6144
	ds_read_b128 v[194:197], v148 offset:7168
	global_load_lds_dwordx4 v136, s[30:31]
	s_add_i32 m0, s29, 0xe000
	s_nop 0
	global_load_lds_dwordx4 v138, s[30:31]
	s_waitcnt lgkmcnt(8)
	s_waitcnt vmcnt(8)
	s_setprio 1
	s_barrier
	s_waitcnt lgkmcnt(0)
	v_mfma_f32_16x16x32_bf16 v[124:127], v[150:153], v[166:169], 0
	v_mfma_f32_16x16x32_bf16 v[120:123], v[158:161], v[166:169], 0
	v_mfma_f32_16x16x32_bf16 v[116:119], v[150:153], v[174:177], 0
	v_mfma_f32_16x16x32_bf16 v[108:111], v[158:161], v[174:177], 0
	v_mfma_f32_16x16x32_bf16 v[100:103], v[150:153], v[182:185], 0
	v_mfma_f32_16x16x32_bf16 v[92:95], v[158:161], v[182:185], 0
	v_mfma_f32_16x16x32_bf16 v[84:87], v[150:153], v[190:193], 0
	v_mfma_f32_16x16x32_bf16 v[76:79], v[158:161], v[190:193], 0
	v_mfma_f32_16x16x32_bf16 v[124:127], v[154:157], v[170:173], v[124:127]
	v_mfma_f32_16x16x32_bf16 v[120:123], v[162:165], v[170:173], v[120:123]
	v_mfma_f32_16x16x32_bf16 v[116:119], v[154:157], v[178:181], v[116:119]
	v_mfma_f32_16x16x32_bf16 v[108:111], v[162:165], v[178:181], v[108:111]
	v_mfma_f32_16x16x32_bf16 v[100:103], v[154:157], v[186:189], v[100:103]
	v_mfma_f32_16x16x32_bf16 v[92:95], v[162:165], v[186:189], v[92:95]
	v_mfma_f32_16x16x32_bf16 v[84:87], v[154:157], v[194:197], v[84:87]
	v_mfma_f32_16x16x32_bf16 v[76:79], v[162:165], v[194:197], v[76:79]
	s_barrier
	s_setprio 0
	s_add_i32 s66, s54, s43
	s_mov_b32 m0, s66
	ds_read_b128 v[202:205], v149
	ds_read_b128 v[206:209], v149 offset:1024
	ds_read_b128 v[210:213], v149 offset:2048
	ds_read_b128 v[214:217], v149 offset:3072
	global_load_lds_dwordx4 v130, s[34:35]
	s_add_i32 m0, s66, 0x2000
	s_nop 0
	global_load_lds_dwordx4 v134, s[34:35]
	s_waitcnt vmcnt(8)
	s_setprio 1
	s_barrier
	s_waitcnt lgkmcnt(0)
	v_mfma_f32_16x16x32_bf16 v[112:115], v[202:205], v[166:169], 0
	v_mfma_f32_16x16x32_bf16 v[104:107], v[210:213], v[166:169], 0
	v_mfma_f32_16x16x32_bf16 v[96:99], v[202:205], v[174:177], 0
	v_mfma_f32_16x16x32_bf16 v[88:91], v[210:213], v[174:177], 0
	v_mfma_f32_16x16x32_bf16 v[80:83], v[202:205], v[182:185], 0
	v_mfma_f32_16x16x32_bf16 v[72:75], v[210:213], v[182:185], 0
	v_mfma_f32_16x16x32_bf16 v[68:71], v[202:205], v[190:193], 0
	v_mfma_f32_16x16x32_bf16 v[64:67], v[210:213], v[190:193], 0
	v_mfma_f32_16x16x32_bf16 v[112:115], v[206:209], v[170:173], v[112:115]
	v_mfma_f32_16x16x32_bf16 v[104:107], v[214:217], v[170:173], v[104:107]
	v_mfma_f32_16x16x32_bf16 v[96:99], v[206:209], v[178:181], v[96:99]
	v_mfma_f32_16x16x32_bf16 v[88:91], v[214:217], v[178:181], v[88:91]
	v_mfma_f32_16x16x32_bf16 v[80:83], v[206:209], v[186:189], v[80:83]
	v_mfma_f32_16x16x32_bf16 v[72:75], v[214:217], v[186:189], v[72:75]
	v_mfma_f32_16x16x32_bf16 v[68:71], v[206:209], v[194:197], v[68:71]
	v_mfma_f32_16x16x32_bf16 v[64:67], v[214:217], v[194:197], v[64:67]
	s_barrier
	s_setprio 0
	s_mov_b32 m0, s29
	v_lshl_add_u64 v[220:221], s[36:37], 0, v[128:129]
	ds_read_b128 v[166:169], v148 offset:16384
	ds_read_b128 v[170:173], v148 offset:17408
	ds_read_b128 v[174:177], v148 offset:18432
	ds_read_b128 v[178:181], v148 offset:19456
	ds_read_b128 v[182:185], v148 offset:20480
	ds_read_b128 v[186:189], v148 offset:21504
	ds_read_b128 v[190:193], v148 offset:22528
	ds_read_b128 v[194:197], v148 offset:23552
	global_load_lds_dwordx4 v128, s[36:37]
	v_lshl_add_u64 v[222:223], s[36:37], 0, v[132:133]
	s_mov_b32 m0, s44
	s_nop 0
	global_load_lds_dwordx4 v132, s[36:37]
	s_setprio 1
	s_barrier
	s_waitcnt lgkmcnt(0)
	v_mfma_f32_16x16x32_bf16 v[60:63], v[150:153], v[166:169], 0
	v_mfma_f32_16x16x32_bf16 v[56:59], v[158:161], v[166:169], 0
	v_mfma_f32_16x16x32_bf16 v[52:55], v[150:153], v[174:177], 0
	v_mfma_f32_16x16x32_bf16 v[44:47], v[158:161], v[174:177], 0
	v_mfma_f32_16x16x32_bf16 v[36:39], v[150:153], v[182:185], 0
	v_mfma_f32_16x16x32_bf16 v[28:31], v[158:161], v[182:185], 0
	v_mfma_f32_16x16x32_bf16 v[20:23], v[150:153], v[190:193], 0
	v_mfma_f32_16x16x32_bf16 v[12:15], v[158:161], v[190:193], 0
	v_mfma_f32_16x16x32_bf16 v[60:63], v[154:157], v[170:173], v[60:63]
	v_mfma_f32_16x16x32_bf16 v[56:59], v[162:165], v[170:173], v[56:59]
	v_mfma_f32_16x16x32_bf16 v[52:55], v[154:157], v[178:181], v[52:55]
	v_mfma_f32_16x16x32_bf16 v[44:47], v[162:165], v[178:181], v[44:47]
	v_mfma_f32_16x16x32_bf16 v[36:39], v[154:157], v[186:189], v[36:39]
	v_mfma_f32_16x16x32_bf16 v[28:31], v[162:165], v[186:189], v[28:31]
	v_mfma_f32_16x16x32_bf16 v[20:23], v[154:157], v[194:197], v[20:23]
	v_mfma_f32_16x16x32_bf16 v[12:15], v[162:165], v[194:197], v[12:15]
	s_barrier
; #define PG8_STAGE(bufoff, gbase, voff) do { _Pragma("unroll") for (int _i = 0; _i < 2; ++_i) \
;         __builtin_amdgcn_global_load_lds((const unsigned*)((const char*)(gbase) + (voff)[_i]), (LAS unsigned*)(lds + (bufoff) + ldsw + _i * 8192), 16, 0, 0); } while (0)
; #define PG8_LDA(dst, b, h) do { _Pragma("unroll") for (int m = 0; m < 4; ++m) _Pragma("unroll") for (int k = 0; k < 2; ++k) dst[m][k] = *(const LAS bf16x8*)(lds + PG8_SA(b, h) + aoff + m * 2048 + k * 1024); } while (0)
; #define PG8_LDB(dst, b, h) do { _Pragma("unroll") for (int n = 0; n < 2; ++n) _Pragma("unroll") for (int k = 0; k < 2; ++k) dst[n][k] = *(const LAS bf16x8*)(lds + PG8_SB(b, h) + boff + n * 2048 + k * 1024); } while (0)
; #define PG8_MMA(ai, bj, At, Bt) do { __builtin_amdgcn_s_setprio(1); _Pragma("unroll") for (int m = 0; m < 4; ++m) _Pragma("unroll") for (int n = 0; n < 2; ++n) _Pragma("unroll") for (int k = 0; k < 2; ++k) \
;         acc[ai][bj][m][n] = __builtin_amdgcn_mfma_f32_16x16x32_bf16(Bt[n][k], At[m][k], acc[ai][bj][m][n], 0, 0, 0); __builtin_amdgcn_s_setprio(0); } while (0)
; #define PG8_WAIT_V(n) asm volatile("s_waitcnt vmcnt(" #n ")" ::: "memory")
; #define PG8_WAIT_L(n) asm volatile("s_waitcnt lgkmcnt(" #n ")" ::: "memory")
; #define PG8_BAR __builtin_amdgcn_s_barrier()
; #define PG8_SCHED __builtin_amdgcn_sched_barrier(0)
; template <class Epi, class Sched>
; __device__ __forceinline__ void gemm_phase(LAS unsigned char* lds, const Gemm g, const Sched& S, const Epi& E) {
;     ...
;             PG8_STAGE(PG8_SB(0, 1), b2 + hstep, voffB);
;             PG8_WAIT_V(6); PG8_BAR; PG8_MMA(1, 1, At, B1); PG8_BAR;
;             PG8_LDB(B0, 1, 0); PG8_SCHED; PG8_LDA(At, 1, 0); PG8_STAGE(PG8_SA(0, 1), a2 + hstep, voffA);
;             PG8_WAIT_L(8); PG8_BAR; PG8_WAIT_L(0); PG8_MMA(0, 0, At, B0); PG8_BAR; PG8_SCHED;
;             PG8_LDB(B1, 1, 1); PG8_STAGE(PG8_SB(1, 0), b3, voffB);
;             PG8_BAR; PG8_WAIT_L(0); PG8_MMA(0, 1, At, B1); PG8_BAR;
;             PG8_LDA(At, 1, 1); PG8_STAGE(PG8_SA(1, 0), a3, voffA);
	s_setprio 0
	s_add_u32 s66, s34, 0x40000
	s_addc_u32 s67, s35, 0
	s_add_i32 s68, s55, s43
	s_mov_b32 m0, s68
	s_nop 0
	global_load_lds_dwordx4 v130, s[66:67]
	s_add_i32 m0, s68, 0x2000
	s_nop 0
	global_load_lds_dwordx4 v134, s[66:67]
	s_add_u32 s36, s36, 0x40000
	s_addc_u32 s37, s37, 0
	s_mov_b32 m0, s45
	s_nop 0
	global_load_lds_dwordx4 v128, s[36:37]
	s_mov_b32 m0, s46
	s_nop 0
	global_load_lds_dwordx4 v132, s[36:37]
	s_waitcnt vmcnt(10)
	s_setprio 1
	s_barrier
	v_mfma_f32_16x16x32_bf16 v[48:51], v[202:205], v[166:169], 0
	v_mfma_f32_16x16x32_bf16 v[40:43], v[210:213], v[166:169], 0
	v_mfma_f32_16x16x32_bf16 v[32:35], v[202:205], v[174:177], 0
	v_mfma_f32_16x16x32_bf16 v[24:27], v[210:213], v[174:177], 0
	v_mfma_f32_16x16x32_bf16 v[16:19], v[202:205], v[182:185], 0
	v_mfma_f32_16x16x32_bf16 v[8:11], v[210:213], v[182:185], 0
	v_mfma_f32_16x16x32_bf16 v[4:7], v[202:205], v[190:193], 0
	v_mfma_f32_16x16x32_bf16 v[0:3], v[210:213], v[190:193], 0
	v_mfma_f32_16x16x32_bf16 v[48:51], v[206:209], v[170:173], v[48:51]
	v_mfma_f32_16x16x32_bf16 v[40:43], v[214:217], v[170:173], v[40:43]
	v_mfma_f32_16x16x32_bf16 v[32:35], v[206:209], v[178:181], v[32:35]
	v_mfma_f32_16x16x32_bf16 v[24:27], v[214:217], v[178:181], v[24:27]
	v_mfma_f32_16x16x32_bf16 v[16:19], v[206:209], v[186:189], v[16:19]
	v_mfma_f32_16x16x32_bf16 v[8:11], v[214:217], v[186:189], v[8:11]
	v_mfma_f32_16x16x32_bf16 v[4:7], v[206:209], v[194:197], v[4:7]
	v_mfma_f32_16x16x32_bf16 v[0:3], v[214:217], v[194:197], v[0:3]
	s_barrier
	s_setprio 0
	s_add_i32 s66, 0, 0x18000
	ds_read_b128 v[150:153], v149 offset:16384
	ds_read_b128 v[154:157], v149 offset:17408
	ds_read_b128 v[158:161], v149 offset:18432
	ds_read_b128 v[162:165], v149 offset:19456
	ds_read_b128 v[166:169], v148 offset:32768
	ds_read_b128 v[170:173], v148 offset:33792
	ds_read_b128 v[174:177], v148 offset:34816
	ds_read_b128 v[178:181], v148 offset:35840
	ds_read_b128 v[182:185], v148 offset:36864
	ds_read_b128 v[186:189], v148 offset:37888
	ds_read_b128 v[190:193], v148 offset:38912
	ds_read_b128 v[194:197], v148 offset:39936
	s_waitcnt lgkmcnt(8)
	s_waitcnt vmcnt(8)
	s_setprio 1
	s_barrier
	s_waitcnt lgkmcnt(0)
	v_mfma_f32_16x16x32_bf16 v[124:127], v[150:153], v[166:169], v[124:127]
	v_mfma_f32_16x16x32_bf16 v[120:123], v[158:161], v[166:169], v[120:123]
	v_mfma_f32_16x16x32_bf16 v[116:119], v[150:153], v[174:177], v[116:119]
	v_mfma_f32_16x16x32_bf16 v[108:111], v[158:161], v[174:177], v[108:111]
	v_mfma_f32_16x16x32_bf16 v[100:103], v[150:153], v[182:185], v[100:103]
	v_mfma_f32_16x16x32_bf16 v[92:95], v[158:161], v[182:185], v[92:95]
	v_mfma_f32_16x16x32_bf16 v[84:87], v[150:153], v[190:193], v[84:87]
	v_mfma_f32_16x16x32_bf16 v[76:79], v[158:161], v[190:193], v[76:79]
	v_mfma_f32_16x16x32_bf16 v[124:127], v[154:157], v[170:173], v[124:127]
	v_mfma_f32_16x16x32_bf16 v[120:123], v[162:165], v[170:173], v[120:123]
	v_mfma_f32_16x16x32_bf16 v[116:119], v[154:157], v[178:181], v[116:119]
	v_mfma_f32_16x16x32_bf16 v[108:111], v[162:165], v[178:181], v[108:111]
	v_mfma_f32_16x16x32_bf16 v[100:103], v[154:157], v[186:189], v[100:103]
	v_mfma_f32_16x16x32_bf16 v[92:95], v[162:165], v[186:189], v[92:95]
	v_mfma_f32_16x16x32_bf16 v[84:87], v[154:157], v[194:197], v[84:87]
	v_mfma_f32_16x16x32_bf16 v[76:79], v[162:165], v[194:197], v[76:79]
	s_barrier
	s_setprio 0
	s_add_i32 s36, 0, 0x1c000
	s_add_i32 s37, s66, s43
	v_add_u32_e32 v214, s36, v146
	s_add_u32 s4, s34, 0x80
	s_addc_u32 s5, s35, 0
	s_mov_b32 m0, s37
	ds_read_b128 v[202:205], v214
	ds_read_b128 v[206:209], v214 offset:1024
	ds_read_b128 v[210:213], v214 offset:2048
	ds_read_b128 v[214:217], v214 offset:3072
	global_load_lds_dwordx4 v130, s[4:5]
	s_add_i32 m0, s37, 0x2000
	s_nop 0
	global_load_lds_dwordx4 v134, s[4:5]
	s_waitcnt vmcnt(8)
	s_setprio 1
	s_barrier
	s_waitcnt lgkmcnt(0)
	v_mfma_f32_16x16x32_bf16 v[112:115], v[202:205], v[166:169], v[112:115]
	v_mfma_f32_16x16x32_bf16 v[104:107], v[210:213], v[166:169], v[104:107]
	v_mfma_f32_16x16x32_bf16 v[96:99], v[202:205], v[174:177], v[96:99]
	v_mfma_f32_16x16x32_bf16 v[88:91], v[210:213], v[174:177], v[88:91]
	v_mfma_f32_16x16x32_bf16 v[80:83], v[202:205], v[182:185], v[80:83]
	v_mfma_f32_16x16x32_bf16 v[72:75], v[210:213], v[182:185], v[72:75]
	v_mfma_f32_16x16x32_bf16 v[68:71], v[202:205], v[190:193], v[68:71]
	v_mfma_f32_16x16x32_bf16 v[64:67], v[210:213], v[190:193], v[64:67]
	v_mfma_f32_16x16x32_bf16 v[112:115], v[206:209], v[170:173], v[112:115]
	v_mfma_f32_16x16x32_bf16 v[104:107], v[214:217], v[170:173], v[104:107]
	v_mfma_f32_16x16x32_bf16 v[96:99], v[206:209], v[178:181], v[96:99]
	v_mfma_f32_16x16x32_bf16 v[88:91], v[214:217], v[178:181], v[88:91]
	v_mfma_f32_16x16x32_bf16 v[80:83], v[206:209], v[186:189], v[80:83]
	v_mfma_f32_16x16x32_bf16 v[72:75], v[214:217], v[186:189], v[72:75]
	v_mfma_f32_16x16x32_bf16 v[68:71], v[206:209], v[194:197], v[68:71]
	v_mfma_f32_16x16x32_bf16 v[64:67], v[214:217], v[194:197], v[64:67]
	s_barrier
	s_setprio 0
	s_mov_b32 m0, s51
	s_mov_b64 s[4:5], 0x80
	v_lshl_add_u64 v[198:199], v[220:221], 0, s[4:5]
	ds_read_b128 v[166:169], v148 offset:49152
	ds_read_b128 v[170:173], v148 offset:50176
	ds_read_b128 v[174:177], v148 offset:51200
	ds_read_b128 v[178:181], v148 offset:52224
	ds_read_b128 v[182:185], v148 offset:53248
	ds_read_b128 v[186:189], v148 offset:54272
	ds_read_b128 v[190:193], v148 offset:55296
	ds_read_b128 v[194:197], v148 offset:56320
	global_load_lds_dwordx4 v[198:199], off
	v_lshl_add_u64 v[198:199], v[222:223], 0, s[4:5]
	s_mov_b32 m0, s52
	s_nop 0
	global_load_lds_dwordx4 v[198:199], off
	s_setprio 1
	s_barrier
; #define PG8_STAGE(bufoff, gbase, voff) do { _Pragma("unroll") for (int _i = 0; _i < 2; ++_i) \
;         __builtin_amdgcn_global_load_lds((const unsigned*)((const char*)(gbase) + (voff)[_i]), (LAS unsigned*)(lds + (bufoff) + ldsw + _i * 8192), 16, 0, 0); } while (0)
; #define PG8_LDA(dst, b, h) do { _Pragma("unroll") for (int m = 0; m < 4; ++m) _Pragma("unroll") for (int k = 0; k < 2; ++k) dst[m][k] = *(const LAS bf16x8*)(lds + PG8_SA(b, h) + aoff + m * 2048 + k * 1024); } while (0)
; #define PG8_LDB(dst, b, h) do { _Pragma("unroll") for (int n = 0; n < 2; ++n) _Pragma("unroll") for (int k = 0; k < 2; ++k) dst[n][k] = *(const LAS bf16x8*)(lds + PG8_SB(b, h) + boff + n * 2048 + k * 1024); } while (0)
; #define PG8_MMA(ai, bj, At, Bt) do { __builtin_amdgcn_s_setprio(1); _Pragma("unroll") for (int m = 0; m < 4; ++m) _Pragma("unroll") for (int n = 0; n < 2; ++n) _Pragma("unroll") for (int k = 0; k < 2; ++k) \
;         acc[ai][bj][m][n] = __builtin_amdgcn_mfma_f32_16x16x32_bf16(Bt[n][k], At[m][k], acc[ai][bj][m][n], 0, 0, 0); __builtin_amdgcn_s_setprio(0); } while (0)
; #define PG8_WAIT_V(n) asm volatile("s_waitcnt vmcnt(" #n ")" ::: "memory")
; #define PG8_WAIT_L(n) asm volatile("s_waitcnt lgkmcnt(" #n ")" ::: "memory")
; #define PG8_BAR __builtin_amdgcn_s_barrier()
; #define PG8_SCHED __builtin_amdgcn_sched_barrier(0)
; template <class Epi, class Sched>
; __device__ __forceinline__ void gemm_phase(LAS unsigned char* lds, const Gemm g, const Sched& S, const Epi& E) {
;     ...
;         for (int t = 0; t < nt; t += 2) {
;             const bool last = (t == nt - 2);
;             const char* a1 = cA + (size_t)(t + 1) * kstep;
;             const char* a2 = last ? nA : cA + (size_t)(t + 2) * kstep; const char* b2 = last ? nB : cB + (size_t)(t + 2) * kstep;
;             const char* a3 = a2 + kstep; const char* b3 = b2 + kstep;
;             PG8_LDB(B0, 0, 0); PG8_SCHED; PG8_LDA(At, 0, 0); PG8_STAGE(PG8_SA(1, 1), a1 + hstep, voffA);
;             PG8_WAIT_L(8); PG8_BAR; PG8_WAIT_L(0); PG8_MMA(0, 0, At, B0); PG8_BAR; PG8_SCHED;
;             PG8_LDB(B1, 0, 1); PG8_STAGE(PG8_SB(0, 0), b2, voffB);
;             PG8_BAR; PG8_WAIT_L(0); PG8_MMA(0, 1, At, B1); PG8_BAR;
;     ...
;             PG8_BAR; PG8_WAIT_L(0); PG8_MMA(1, 0, At, B0); PG8_BAR; PG8_SCHED;
;             PG8_STAGE(PG8_SB(1, 1), b3 + hstep, voffB);
;             PG8_WAIT_V(6); PG8_BAR; PG8_MMA(1, 1, At, B1); PG8_BAR;
	s_waitcnt lgkmcnt(0)
	v_mfma_f32_16x16x32_bf16 v[60:63], v[150:153], v[166:169], v[60:63]
	v_mfma_f32_16x16x32_bf16 v[56:59], v[158:161], v[166:169], v[56:59]
	v_mfma_f32_16x16x32_bf16 v[52:55], v[150:153], v[174:177], v[52:55]
	v_mfma_f32_16x16x32_bf16 v[44:47], v[158:161], v[174:177], v[44:47]
	v_mfma_f32_16x16x32_bf16 v[36:39], v[150:153], v[182:185], v[36:39]
	v_mfma_f32_16x16x32_bf16 v[28:31], v[158:161], v[182:185], v[28:31]
	v_mfma_f32_16x16x32_bf16 v[20:23], v[150:153], v[190:193], v[20:23]
	v_mfma_f32_16x16x32_bf16 v[12:15], v[158:161], v[190:193], v[12:15]
	v_mfma_f32_16x16x32_bf16 v[60:63], v[154:157], v[170:173], v[60:63]
	v_mfma_f32_16x16x32_bf16 v[56:59], v[162:165], v[170:173], v[56:59]
	v_mfma_f32_16x16x32_bf16 v[52:55], v[154:157], v[178:181], v[52:55]
	v_mfma_f32_16x16x32_bf16 v[44:47], v[162:165], v[178:181], v[44:47]
	v_mfma_f32_16x16x32_bf16 v[36:39], v[154:157], v[186:189], v[36:39]
	v_mfma_f32_16x16x32_bf16 v[28:31], v[162:165], v[186:189], v[28:31]
	v_mfma_f32_16x16x32_bf16 v[20:23], v[154:157], v[194:197], v[20:23]
	v_mfma_f32_16x16x32_bf16 v[12:15], v[162:165], v[194:197], v[12:15]
	s_barrier
	s_setprio 0
	s_add_u32 s34, s34, 0x40080
	s_addc_u32 s35, s35, 0
	s_add_i32 s36, s36, s43
	s_mov_b32 m0, s36
	s_nop 0
	global_load_lds_dwordx4 v130, s[34:35]
	s_add_i32 m0, s36, 0x2000
	s_nop 0
	global_load_lds_dwordx4 v134, s[34:35]
	s_waitcnt vmcnt(8)
	s_setprio 1
	s_barrier
	v_mfma_f32_16x16x32_bf16 v[48:51], v[202:205], v[166:169], v[48:51]
	v_mfma_f32_16x16x32_bf16 v[40:43], v[210:213], v[166:169], v[40:43]
	v_mfma_f32_16x16x32_bf16 v[32:35], v[202:205], v[174:177], v[32:35]
	v_mfma_f32_16x16x32_bf16 v[24:27], v[210:213], v[174:177], v[24:27]
	v_mfma_f32_16x16x32_bf16 v[16:19], v[202:205], v[182:185], v[16:19]
	v_mfma_f32_16x16x32_bf16 v[8:11], v[210:213], v[182:185], v[8:11]
	v_mfma_f32_16x16x32_bf16 v[4:7], v[202:205], v[190:193], v[4:7]
	v_mfma_f32_16x16x32_bf16 v[0:3], v[210:213], v[190:193], v[0:3]
	v_mfma_f32_16x16x32_bf16 v[48:51], v[206:209], v[170:173], v[48:51]
	v_mfma_f32_16x16x32_bf16 v[40:43], v[214:217], v[170:173], v[40:43]
	v_mfma_f32_16x16x32_bf16 v[32:35], v[206:209], v[178:181], v[32:35]
	v_mfma_f32_16x16x32_bf16 v[24:27], v[214:217], v[178:181], v[24:27]
	v_mfma_f32_16x16x32_bf16 v[16:19], v[206:209], v[186:189], v[16:19]
	v_mfma_f32_16x16x32_bf16 v[8:11], v[214:217], v[186:189], v[8:11]
	v_mfma_f32_16x16x32_bf16 v[4:7], v[206:209], v[194:197], v[4:7]
	v_mfma_f32_16x16x32_bf16 v[0:3], v[214:217], v[194:197], v[0:3]
	s_barrier
	s_setprio 0
	s_add_i32 s65, s65, 2
	s_add_u32 s30, s30, 0x100
	s_addc_u32 s31, s31, 0
	s_add_u32 s63, s63, 0x100
	s_addc_u32 s64, s64, 0
	s_cmp_gt_u32 s65, 13
.LBB0_633:
	ds_read_b128 v[150:153], v147
	ds_read_b128 v[154:157], v147 offset:1024
	ds_read_b128 v[158:161], v147 offset:2048
	ds_read_b128 v[162:165], v147 offset:3072
	s_add_u32 s34, s30, 0xfffc0080
	s_addc_u32 s35, s31, -1
	s_cmp_eq_u32 s65, 12
	s_cselect_b32 s37, s23, s35
	s_cselect_b32 s36, s61, s34
	s_cselect_b32 s35, s21, s64
	s_cselect_b32 s34, s62, s63
	s_add_i32 m0, s29, 0xc000
	ds_read_b128 v[166:169], v148
	ds_read_b128 v[170:173], v148 offset:1024
	ds_read_b128 v[174:177], v148 offset:2048
	ds_read_b128 v[178:181], v148 offset:3072
	ds_read_b128 v[182:185], v148 offset:4096
	ds_read_b128 v[186:189], v148 offset:5120
	ds_read_b128 v[190:193], v148 offset:6144
	ds_read_b128 v[194:197], v148 offset:7168
	global_load_lds_dwordx4 v136, s[30:31]
	s_add_i32 m0, s29, 0xe000
	s_nop 0
	global_load_lds_dwordx4 v138, s[30:31]
	s_waitcnt lgkmcnt(8)
	s_waitcnt vmcnt(8)
	s_setprio 1
	s_barrier
	s_waitcnt lgkmcnt(0)
	v_mfma_f32_16x16x32_bf16 v[124:127], v[150:153], v[166:169], v[124:127]
	v_mfma_f32_16x16x32_bf16 v[120:123], v[158:161], v[166:169], v[120:123]
	v_mfma_f32_16x16x32_bf16 v[116:119], v[150:153], v[174:177], v[116:119]
	v_mfma_f32_16x16x32_bf16 v[108:111], v[158:161], v[174:177], v[108:111]
	v_mfma_f32_16x16x32_bf16 v[100:103], v[150:153], v[182:185], v[100:103]
	v_mfma_f32_16x16x32_bf16 v[92:95], v[158:161], v[182:185], v[92:95]
	v_mfma_f32_16x16x32_bf16 v[84:87], v[150:153], v[190:193], v[84:87]
	v_mfma_f32_16x16x32_bf16 v[76:79], v[158:161], v[190:193], v[76:79]
	v_mfma_f32_16x16x32_bf16 v[124:127], v[154:157], v[170:173], v[124:127]
	v_mfma_f32_16x16x32_bf16 v[120:123], v[162:165], v[170:173], v[120:123]
	v_mfma_f32_16x16x32_bf16 v[116:119], v[154:157], v[178:181], v[116:119]
	v_mfma_f32_16x16x32_bf16 v[108:111], v[162:165], v[178:181], v[108:111]
	v_mfma_f32_16x16x32_bf16 v[100:103], v[154:157], v[186:189], v[100:103]
	v_mfma_f32_16x16x32_bf16 v[92:95], v[162:165], v[186:189], v[92:95]
	v_mfma_f32_16x16x32_bf16 v[84:87], v[154:157], v[194:197], v[84:87]
	v_mfma_f32_16x16x32_bf16 v[76:79], v[162:165], v[194:197], v[76:79]
	s_barrier
	s_setprio 0
	s_add_i32 s66, s54, s43
	s_mov_b32 m0, s66
	ds_read_b128 v[202:205], v149
	ds_read_b128 v[206:209], v149 offset:1024
	ds_read_b128 v[210:213], v149 offset:2048
	ds_read_b128 v[214:217], v149 offset:3072
	global_load_lds_dwordx4 v130, s[34:35]
	s_add_i32 m0, s66, 0x2000
	s_nop 0
	global_load_lds_dwordx4 v134, s[34:35]
	s_waitcnt vmcnt(8)
	s_setprio 1
	s_barrier
; #define PG8_STAGE(bufoff, gbase, voff) do { _Pragma("unroll") for (int _i = 0; _i < 2; ++_i) \
;         __builtin_amdgcn_global_load_lds((const unsigned*)((const char*)(gbase) + (voff)[_i]), (LAS unsigned*)(lds + (bufoff) + ldsw + _i * 8192), 16, 0, 0); } while (0)
; #define PG8_LDA(dst, b, h) do { _Pragma("unroll") for (int m = 0; m < 4; ++m) _Pragma("unroll") for (int k = 0; k < 2; ++k) dst[m][k] = *(const LAS bf16x8*)(lds + PG8_SA(b, h) + aoff + m * 2048 + k * 1024); } while (0)
; #define PG8_LDB(dst, b, h) do { _Pragma("unroll") for (int n = 0; n < 2; ++n) _Pragma("unroll") for (int k = 0; k < 2; ++k) dst[n][k] = *(const LAS bf16x8*)(lds + PG8_SB(b, h) + boff + n * 2048 + k * 1024); } while (0)
; #define PG8_MMA(ai, bj, At, Bt) do { __builtin_amdgcn_s_setprio(1); _Pragma("unroll") for (int m = 0; m < 4; ++m) _Pragma("unroll") for (int n = 0; n < 2; ++n) _Pragma("unroll") for (int k = 0; k < 2; ++k) \
;         acc[ai][bj][m][n] = __builtin_amdgcn_mfma_f32_16x16x32_bf16(Bt[n][k], At[m][k], acc[ai][bj][m][n], 0, 0, 0); __builtin_amdgcn_s_setprio(0); } while (0)
; #define PG8_WAIT_V(n) asm volatile("s_waitcnt vmcnt(" #n ")" ::: "memory")
; #define PG8_WAIT_L(n) asm volatile("s_waitcnt lgkmcnt(" #n ")" ::: "memory")
; #define PG8_BAR __builtin_amdgcn_s_barrier()
; #define PG8_SCHED __builtin_amdgcn_sched_barrier(0)
; template <class Epi, class Sched>
; __device__ __forceinline__ void gemm_phase(LAS unsigned char* lds, const Gemm g, const Sched& S, const Epi& E) {
;     ...
;             PG8_BAR; PG8_WAIT_L(0); PG8_MMA(0, 1, At, B1); PG8_BAR;
;             PG8_LDA(At, 0, 1); PG8_STAGE(PG8_SA(0, 0), a2, voffA);
;             PG8_BAR; PG8_WAIT_L(0); PG8_MMA(1, 0, At, B0); PG8_BAR; PG8_SCHED;
;             PG8_STAGE(PG8_SB(0, 1), b2 + hstep, voffB);
;             PG8_WAIT_V(6); PG8_BAR; PG8_MMA(1, 1, At, B1); PG8_BAR;
;             PG8_LDB(B0, 1, 0); PG8_SCHED; PG8_LDA(At, 1, 0); PG8_STAGE(PG8_SA(0, 1), a2 + hstep, voffA);
;             PG8_WAIT_L(8); PG8_BAR; PG8_WAIT_L(0); PG8_MMA(0, 0, At, B0); PG8_BAR; PG8_SCHED;
	s_waitcnt lgkmcnt(0)
	v_mfma_f32_16x16x32_bf16 v[112:115], v[202:205], v[166:169], v[112:115]
	v_mfma_f32_16x16x32_bf16 v[104:107], v[210:213], v[166:169], v[104:107]
	v_mfma_f32_16x16x32_bf16 v[96:99], v[202:205], v[174:177], v[96:99]
	v_mfma_f32_16x16x32_bf16 v[88:91], v[210:213], v[174:177], v[88:91]
	v_mfma_f32_16x16x32_bf16 v[80:83], v[202:205], v[182:185], v[80:83]
	v_mfma_f32_16x16x32_bf16 v[72:75], v[210:213], v[182:185], v[72:75]
	v_mfma_f32_16x16x32_bf16 v[68:71], v[202:205], v[190:193], v[68:71]
	v_mfma_f32_16x16x32_bf16 v[64:67], v[210:213], v[190:193], v[64:67]
	v_mfma_f32_16x16x32_bf16 v[112:115], v[206:209], v[170:173], v[112:115]
	v_mfma_f32_16x16x32_bf16 v[104:107], v[214:217], v[170:173], v[104:107]
	v_mfma_f32_16x16x32_bf16 v[96:99], v[206:209], v[178:181], v[96:99]
	v_mfma_f32_16x16x32_bf16 v[88:91], v[214:217], v[178:181], v[88:91]
	v_mfma_f32_16x16x32_bf16 v[80:83], v[206:209], v[186:189], v[80:83]
	v_mfma_f32_16x16x32_bf16 v[72:75], v[214:217], v[186:189], v[72:75]
	v_mfma_f32_16x16x32_bf16 v[68:71], v[206:209], v[194:197], v[68:71]
	v_mfma_f32_16x16x32_bf16 v[64:67], v[214:217], v[194:197], v[64:67]
	s_barrier
	s_setprio 0
	s_mov_b32 m0, s29
	v_lshl_add_u64 v[220:221], s[36:37], 0, v[128:129]
	ds_read_b128 v[166:169], v148 offset:16384
	ds_read_b128 v[170:173], v148 offset:17408
	ds_read_b128 v[174:177], v148 offset:18432
	ds_read_b128 v[178:181], v148 offset:19456
	ds_read_b128 v[182:185], v148 offset:20480
	ds_read_b128 v[186:189], v148 offset:21504
	ds_read_b128 v[190:193], v148 offset:22528
	ds_read_b128 v[194:197], v148 offset:23552
	global_load_lds_dwordx4 v128, s[36:37]
	v_lshl_add_u64 v[222:223], s[36:37], 0, v[132:133]
	s_mov_b32 m0, s44
	s_nop 0
	global_load_lds_dwordx4 v132, s[36:37]
	s_setprio 1
	s_barrier
	s_waitcnt lgkmcnt(0)
	v_mfma_f32_16x16x32_bf16 v[60:63], v[150:153], v[166:169], v[60:63]
	v_mfma_f32_16x16x32_bf16 v[56:59], v[158:161], v[166:169], v[56:59]
	v_mfma_f32_16x16x32_bf16 v[52:55], v[150:153], v[174:177], v[52:55]
	v_mfma_f32_16x16x32_bf16 v[44:47], v[158:161], v[174:177], v[44:47]
	v_mfma_f32_16x16x32_bf16 v[36:39], v[150:153], v[182:185], v[36:39]
	v_mfma_f32_16x16x32_bf16 v[28:31], v[158:161], v[182:185], v[28:31]
	v_mfma_f32_16x16x32_bf16 v[20:23], v[150:153], v[190:193], v[20:23]
	v_mfma_f32_16x16x32_bf16 v[12:15], v[158:161], v[190:193], v[12:15]
	v_mfma_f32_16x16x32_bf16 v[60:63], v[154:157], v[170:173], v[60:63]
	v_mfma_f32_16x16x32_bf16 v[56:59], v[162:165], v[170:173], v[56:59]
	v_mfma_f32_16x16x32_bf16 v[52:55], v[154:157], v[178:181], v[52:55]
	v_mfma_f32_16x16x32_bf16 v[44:47], v[162:165], v[178:181], v[44:47]
	v_mfma_f32_16x16x32_bf16 v[36:39], v[154:157], v[186:189], v[36:39]
	v_mfma_f32_16x16x32_bf16 v[28:31], v[162:165], v[186:189], v[28:31]
	v_mfma_f32_16x16x32_bf16 v[20:23], v[154:157], v[194:197], v[20:23]
	v_mfma_f32_16x16x32_bf16 v[12:15], v[162:165], v[194:197], v[12:15]
	s_barrier
	s_setprio 0
	s_add_u32 s66, s34, 0x40000
	s_addc_u32 s67, s35, 0
	s_add_i32 s68, s55, s43
	s_mov_b32 m0, s68
	s_nop 0
	global_load_lds_dwordx4 v130, s[66:67]
	s_add_i32 m0, s68, 0x2000
	s_nop 0
	global_load_lds_dwordx4 v134, s[66:67]
	s_add_u32 s36, s36, 0x40000
	s_addc_u32 s37, s37, 0
	s_mov_b32 m0, s45
	s_nop 0
	global_load_lds_dwordx4 v128, s[36:37]
	s_mov_b32 m0, s46
	s_nop 0
	global_load_lds_dwordx4 v132, s[36:37]
	s_waitcnt vmcnt(10)
	s_setprio 1
	s_barrier
	v_mfma_f32_16x16x32_bf16 v[48:51], v[202:205], v[166:169], v[48:51]
	v_mfma_f32_16x16x32_bf16 v[40:43], v[210:213], v[166:169], v[40:43]
	v_mfma_f32_16x16x32_bf16 v[32:35], v[202:205], v[174:177], v[32:35]
	v_mfma_f32_16x16x32_bf16 v[24:27], v[210:213], v[174:177], v[24:27]
	v_mfma_f32_16x16x32_bf16 v[16:19], v[202:205], v[182:185], v[16:19]
	v_mfma_f32_16x16x32_bf16 v[8:11], v[210:213], v[182:185], v[8:11]
	v_mfma_f32_16x16x32_bf16 v[4:7], v[202:205], v[190:193], v[4:7]
	v_mfma_f32_16x16x32_bf16 v[0:3], v[210:213], v[190:193], v[0:3]
	v_mfma_f32_16x16x32_bf16 v[48:51], v[206:209], v[170:173], v[48:51]
	v_mfma_f32_16x16x32_bf16 v[40:43], v[214:217], v[170:173], v[40:43]
	v_mfma_f32_16x16x32_bf16 v[32:35], v[206:209], v[178:181], v[32:35]
	v_mfma_f32_16x16x32_bf16 v[24:27], v[214:217], v[178:181], v[24:27]
	v_mfma_f32_16x16x32_bf16 v[16:19], v[206:209], v[186:189], v[16:19]
	v_mfma_f32_16x16x32_bf16 v[8:11], v[214:217], v[186:189], v[8:11]
	v_mfma_f32_16x16x32_bf16 v[4:7], v[206:209], v[194:197], v[4:7]
	v_mfma_f32_16x16x32_bf16 v[0:3], v[214:217], v[194:197], v[0:3]
	s_barrier
	s_setprio 0
	s_add_i32 s66, 0, 0x18000
	ds_read_b128 v[150:153], v149 offset:16384
	ds_read_b128 v[154:157], v149 offset:17408
	ds_read_b128 v[158:161], v149 offset:18432
	ds_read_b128 v[162:165], v149 offset:19456
	ds_read_b128 v[166:169], v148 offset:32768
	ds_read_b128 v[170:173], v148 offset:33792
	ds_read_b128 v[174:177], v148 offset:34816
	ds_read_b128 v[178:181], v148 offset:35840
	ds_read_b128 v[182:185], v148 offset:36864
	ds_read_b128 v[186:189], v148 offset:37888
	ds_read_b128 v[190:193], v148 offset:38912
	ds_read_b128 v[194:197], v148 offset:39936
	s_waitcnt lgkmcnt(8)
	s_waitcnt vmcnt(8)
	s_setprio 1
	s_barrier
; #define PG8_STAGE(bufoff, gbase, voff) do { _Pragma("unroll") for (int _i = 0; _i < 2; ++_i) \
;         __builtin_amdgcn_global_load_lds((const unsigned*)((const char*)(gbase) + (voff)[_i]), (LAS unsigned*)(lds + (bufoff) + ldsw + _i * 8192), 16, 0, 0); } while (0)
; #define PG8_LDA(dst, b, h) do { _Pragma("unroll") for (int m = 0; m < 4; ++m) _Pragma("unroll") for (int k = 0; k < 2; ++k) dst[m][k] = *(const LAS bf16x8*)(lds + PG8_SA(b, h) + aoff + m * 2048 + k * 1024); } while (0)
; #define PG8_LDB(dst, b, h) do { _Pragma("unroll") for (int n = 0; n < 2; ++n) _Pragma("unroll") for (int k = 0; k < 2; ++k) dst[n][k] = *(const LAS bf16x8*)(lds + PG8_SB(b, h) + boff + n * 2048 + k * 1024); } while (0)
; #define PG8_MMA(ai, bj, At, Bt) do { __builtin_amdgcn_s_setprio(1); _Pragma("unroll") for (int m = 0; m < 4; ++m) _Pragma("unroll") for (int n = 0; n < 2; ++n) _Pragma("unroll") for (int k = 0; k < 2; ++k) \
;         acc[ai][bj][m][n] = __builtin_amdgcn_mfma_f32_16x16x32_bf16(Bt[n][k], At[m][k], acc[ai][bj][m][n], 0, 0, 0); __builtin_amdgcn_s_setprio(0); } while (0)
; #define PG8_WAIT_V(n) asm volatile("s_waitcnt vmcnt(" #n ")" ::: "memory")
; #define PG8_WAIT_L(n) asm volatile("s_waitcnt lgkmcnt(" #n ")" ::: "memory")
; #define PG8_BAR __builtin_amdgcn_s_barrier()
; #define PG8_SCHED __builtin_amdgcn_sched_barrier(0)
; template <class Epi, class Sched>
; __device__ __forceinline__ void gemm_phase(LAS unsigned char* lds, const Gemm g, const Sched& S, const Epi& E) {
;     ...
;             PG8_WAIT_L(8); PG8_BAR; PG8_WAIT_L(0); PG8_MMA(0, 0, At, B0); PG8_BAR; PG8_SCHED;
;             PG8_LDB(B1, 1, 1); PG8_STAGE(PG8_SB(1, 0), b3, voffB);
;             PG8_BAR; PG8_WAIT_L(0); PG8_MMA(0, 1, At, B1); PG8_BAR;
;             PG8_LDA(At, 1, 1); PG8_STAGE(PG8_SA(1, 0), a3, voffA);
;             PG8_BAR; PG8_WAIT_L(0); PG8_MMA(1, 0, At, B0); PG8_BAR; PG8_SCHED;
;             PG8_STAGE(PG8_SB(1, 1), b3 + hstep, voffB);
;             PG8_WAIT_V(6); PG8_BAR; PG8_MMA(1, 1, At, B1); PG8_BAR;
	s_waitcnt lgkmcnt(0)
	v_mfma_f32_16x16x32_bf16 v[124:127], v[150:153], v[166:169], v[124:127]
	v_mfma_f32_16x16x32_bf16 v[120:123], v[158:161], v[166:169], v[120:123]
	v_mfma_f32_16x16x32_bf16 v[116:119], v[150:153], v[174:177], v[116:119]
	v_mfma_f32_16x16x32_bf16 v[108:111], v[158:161], v[174:177], v[108:111]
	v_mfma_f32_16x16x32_bf16 v[100:103], v[150:153], v[182:185], v[100:103]
	v_mfma_f32_16x16x32_bf16 v[92:95], v[158:161], v[182:185], v[92:95]
	v_mfma_f32_16x16x32_bf16 v[84:87], v[150:153], v[190:193], v[84:87]
	v_mfma_f32_16x16x32_bf16 v[76:79], v[158:161], v[190:193], v[76:79]
	v_mfma_f32_16x16x32_bf16 v[124:127], v[154:157], v[170:173], v[124:127]
	v_mfma_f32_16x16x32_bf16 v[120:123], v[162:165], v[170:173], v[120:123]
	v_mfma_f32_16x16x32_bf16 v[116:119], v[154:157], v[178:181], v[116:119]
	v_mfma_f32_16x16x32_bf16 v[108:111], v[162:165], v[178:181], v[108:111]
	v_mfma_f32_16x16x32_bf16 v[100:103], v[154:157], v[186:189], v[100:103]
	v_mfma_f32_16x16x32_bf16 v[92:95], v[162:165], v[186:189], v[92:95]
	v_mfma_f32_16x16x32_bf16 v[84:87], v[154:157], v[194:197], v[84:87]
	v_mfma_f32_16x16x32_bf16 v[76:79], v[162:165], v[194:197], v[76:79]
	s_barrier
	s_setprio 0
	s_add_i32 s36, 0, 0x1c000
	s_add_i32 s37, s66, s43
	v_add_u32_e32 v214, s36, v146
	s_add_u32 s4, s34, 0x80
	s_addc_u32 s5, s35, 0
	s_mov_b32 m0, s37
	ds_read_b128 v[202:205], v214
	ds_read_b128 v[206:209], v214 offset:1024
	ds_read_b128 v[210:213], v214 offset:2048
	ds_read_b128 v[214:217], v214 offset:3072
	global_load_lds_dwordx4 v130, s[4:5]
	s_add_i32 m0, s37, 0x2000
	s_nop 0
	global_load_lds_dwordx4 v134, s[4:5]
	s_waitcnt vmcnt(8)
	s_setprio 1
	s_barrier
	s_waitcnt lgkmcnt(0)
	v_mfma_f32_16x16x32_bf16 v[112:115], v[202:205], v[166:169], v[112:115]
	v_mfma_f32_16x16x32_bf16 v[104:107], v[210:213], v[166:169], v[104:107]
	v_mfma_f32_16x16x32_bf16 v[96:99], v[202:205], v[174:177], v[96:99]
	v_mfma_f32_16x16x32_bf16 v[88:91], v[210:213], v[174:177], v[88:91]
	v_mfma_f32_16x16x32_bf16 v[80:83], v[202:205], v[182:185], v[80:83]
	v_mfma_f32_16x16x32_bf16 v[72:75], v[210:213], v[182:185], v[72:75]
	v_mfma_f32_16x16x32_bf16 v[68:71], v[202:205], v[190:193], v[68:71]
	v_mfma_f32_16x16x32_bf16 v[64:67], v[210:213], v[190:193], v[64:67]
	v_mfma_f32_16x16x32_bf16 v[112:115], v[206:209], v[170:173], v[112:115]
	v_mfma_f32_16x16x32_bf16 v[104:107], v[214:217], v[170:173], v[104:107]
	v_mfma_f32_16x16x32_bf16 v[96:99], v[206:209], v[178:181], v[96:99]
	v_mfma_f32_16x16x32_bf16 v[88:91], v[214:217], v[178:181], v[88:91]
	v_mfma_f32_16x16x32_bf16 v[80:83], v[206:209], v[186:189], v[80:83]
	v_mfma_f32_16x16x32_bf16 v[72:75], v[214:217], v[186:189], v[72:75]
	v_mfma_f32_16x16x32_bf16 v[68:71], v[206:209], v[194:197], v[68:71]
	v_mfma_f32_16x16x32_bf16 v[64:67], v[214:217], v[194:197], v[64:67]
	s_barrier
	s_setprio 0
	s_mov_b32 m0, s51
	s_mov_b64 s[4:5], 0x80
	v_lshl_add_u64 v[198:199], v[220:221], 0, s[4:5]
	ds_read_b128 v[166:169], v148 offset:49152
	ds_read_b128 v[170:173], v148 offset:50176
	ds_read_b128 v[174:177], v148 offset:51200
	ds_read_b128 v[178:181], v148 offset:52224
	ds_read_b128 v[182:185], v148 offset:53248
	ds_read_b128 v[186:189], v148 offset:54272
	ds_read_b128 v[190:193], v148 offset:55296
	ds_read_b128 v[194:197], v148 offset:56320
	global_load_lds_dwordx4 v[198:199], off
	v_lshl_add_u64 v[198:199], v[222:223], 0, s[4:5]
	s_mov_b32 m0, s52
	s_nop 0
	global_load_lds_dwordx4 v[198:199], off
	s_setprio 1
	s_barrier
	s_waitcnt lgkmcnt(0)
	v_mfma_f32_16x16x32_bf16 v[60:63], v[150:153], v[166:169], v[60:63]
	v_mfma_f32_16x16x32_bf16 v[56:59], v[158:161], v[166:169], v[56:59]
	v_mfma_f32_16x16x32_bf16 v[52:55], v[150:153], v[174:177], v[52:55]
	v_mfma_f32_16x16x32_bf16 v[44:47], v[158:161], v[174:177], v[44:47]
	v_mfma_f32_16x16x32_bf16 v[36:39], v[150:153], v[182:185], v[36:39]
	v_mfma_f32_16x16x32_bf16 v[28:31], v[158:161], v[182:185], v[28:31]
	v_mfma_f32_16x16x32_bf16 v[20:23], v[150:153], v[190:193], v[20:23]
	v_mfma_f32_16x16x32_bf16 v[12:15], v[158:161], v[190:193], v[12:15]
	v_mfma_f32_16x16x32_bf16 v[60:63], v[154:157], v[170:173], v[60:63]
	v_mfma_f32_16x16x32_bf16 v[56:59], v[162:165], v[170:173], v[56:59]
	v_mfma_f32_16x16x32_bf16 v[52:55], v[154:157], v[178:181], v[52:55]
	v_mfma_f32_16x16x32_bf16 v[44:47], v[162:165], v[178:181], v[44:47]
	v_mfma_f32_16x16x32_bf16 v[36:39], v[154:157], v[186:189], v[36:39]
	v_mfma_f32_16x16x32_bf16 v[28:31], v[162:165], v[186:189], v[28:31]
	v_mfma_f32_16x16x32_bf16 v[20:23], v[154:157], v[194:197], v[20:23]
	v_mfma_f32_16x16x32_bf16 v[12:15], v[162:165], v[194:197], v[12:15]
	s_barrier
	s_setprio 0
	s_add_u32 s34, s34, 0x40080
	s_addc_u32 s35, s35, 0
	s_add_i32 s36, s36, s43
	s_mov_b32 m0, s36
	s_nop 0
	global_load_lds_dwordx4 v130, s[34:35]
	s_add_i32 m0, s36, 0x2000
	s_nop 0
	global_load_lds_dwordx4 v134, s[34:35]
	s_waitcnt vmcnt(8)
	s_setprio 1
	s_barrier
	v_mfma_f32_16x16x32_bf16 v[48:51], v[202:205], v[166:169], v[48:51]
	v_mfma_f32_16x16x32_bf16 v[40:43], v[210:213], v[166:169], v[40:43]
	v_mfma_f32_16x16x32_bf16 v[32:35], v[202:205], v[174:177], v[32:35]
	v_mfma_f32_16x16x32_bf16 v[24:27], v[210:213], v[174:177], v[24:27]
	v_mfma_f32_16x16x32_bf16 v[16:19], v[202:205], v[182:185], v[16:19]
	v_mfma_f32_16x16x32_bf16 v[8:11], v[210:213], v[182:185], v[8:11]
	v_mfma_f32_16x16x32_bf16 v[4:7], v[202:205], v[190:193], v[4:7]
	v_mfma_f32_16x16x32_bf16 v[0:3], v[210:213], v[190:193], v[0:3]
	v_mfma_f32_16x16x32_bf16 v[48:51], v[206:209], v[170:173], v[48:51]
	v_mfma_f32_16x16x32_bf16 v[40:43], v[214:217], v[170:173], v[40:43]
	v_mfma_f32_16x16x32_bf16 v[32:35], v[206:209], v[178:181], v[32:35]
	v_mfma_f32_16x16x32_bf16 v[24:27], v[214:217], v[178:181], v[24:27]
	v_mfma_f32_16x16x32_bf16 v[16:19], v[206:209], v[186:189], v[16:19]
	v_mfma_f32_16x16x32_bf16 v[8:11], v[214:217], v[186:189], v[8:11]
	v_mfma_f32_16x16x32_bf16 v[4:7], v[206:209], v[194:197], v[4:7]
	v_mfma_f32_16x16x32_bf16 v[0:3], v[214:217], v[194:197], v[0:3]
	s_barrier
; __device__ __forceinline__ unsigned cvt_pk_bf16(float lo, float hi) { unsigned r; asm volatile("v_cvt_pk_bf16_f32 %0, %1, %2" : "=v"(r) : "v"(lo), "v"(hi)); return r; }
; #define PG8_WAIT_V(n) asm volatile("s_waitcnt vmcnt(" #n ")" ::: "memory")
; #define PG8_BAR __builtin_amdgcn_s_barrier()
; template <class Epi, class Sched>
; __device__ __forceinline__ void gemm_phase(LAS unsigned char* lds, const Gemm g, const Sched& S, const Epi& E) {
;     ...
;         E(acc, cur, wr, wc, fr, fq);
;         if (!has_next) break;
; #pragma unroll
;         for (int a = 0; a < 2; ++a)
; #pragma unroll
;             for (int b = 0; b < 2; ++b)
; #pragma unroll
;                 for (int m = 0; m < 4; ++m)
; #pragma unroll
;                     for (int n = 0; n < 2; ++n) acc[a][b][m][n] = (f32x4){0.f, 0.f, 0.f, 0.f};
;         cur = nxt; cA = nA; cB = nB; ++ui;
;     }
;     PG8_WAIT_V(0);
;     if (wr == 0) PG8_BAR;
;     PG8_BAR;
;     __device__ __forceinline__ void operator()(const AccT& acc, const Unit& u, int wr, int wc, int fr, int fq) const {
;         asm volatile("" : "+v"(fr), "+v"(fq));
;         const int rbase = u.pm * 256 + wr * 64 + fr;
;         const int tb = u.pn * 256 + wc * 32 + 8 * fq;
; #pragma unroll
;         for (int ai = 0; ai < 2; ++ai)
; #pragma unroll
;             for (int m = 0; m < 4; ++m) {
;                 const int r = rbase + ai * 128 + m * 16;
; #pragma unroll
;                 for (int bj = 0; bj < 2; ++bj) {
;                     const int t0 = tb + bj * 128;
;                     const f32x4 v0 = acc[ai][bj][m][0], v1 = acc[ai][bj][m][1];
;                     u32x4 w; w.x = cvt_pk_bf16(v0[0], v0[1]); w.y = cvt_pk_bf16(v0[2], v0[3]); w.z = cvt_pk_bf16(v1[0], v1[1]); w.w = cvt_pk_bf16(v1[2], v1[3]);
;                     *(u32x4*)(VT + (size_t)r * NT + t0) = w;
;                 }
;             }
;     }
	s_setprio 0
	s_add_i32 s65, s65, 2
	s_add_u32 s30, s30, 0x100
	s_addc_u32 s31, s31, 0
	s_add_u32 s63, s63, 0x100
	s_addc_u32 s64, s64, 0
	s_cmp_gt_u32 s65, 13
	s_cbranch_scc0 .LBB0_633
	v_mov_b32_e32 v150, v144
	v_mov_b32_e32 v151, v145
	s_lshl_b32 s21, s28, 8
	s_add_i32 s21, s21, s48
	v_add_u32_e32 v150, s21, v150
	s_lshl_b32 s21, s60, 8
	s_or_b32 s21, s21, s49
	v_lshl_add_u32 v152, v151, 3, s21
	v_ashrrev_i32_e32 v151, 31, v150
	v_cvt_pk_bf16_f32 v124, v124, v125
	v_cvt_pk_bf16_f32 v125, v126, v127
	v_cvt_pk_bf16_f32 v126, v120, v121
	v_lshlrev_b64 v[120:121], 17, v[150:151]
	v_lshl_add_u64 v[120:121], s[0:1], 0, v[120:121]
	v_ashrrev_i32_e32 v153, 31, v152
	v_lshl_add_u64 v[120:121], v[152:153], 1, v[120:121]
	s_mov_b32 s21, 0x200000
	v_cvt_pk_bf16_f32 v127, v122, v123
	global_store_dwordx4 v[120:121], v[124:127], off
	v_cvt_pk_bf16_f32 v112, v112, v113
	v_cvt_pk_bf16_f32 v113, v114, v115
	v_cvt_pk_bf16_f32 v114, v104, v105
	v_cvt_pk_bf16_f32 v115, v106, v107
	global_store_dwordx4 v[120:121], v[112:115], off offset:256
	v_cvt_pk_bf16_f32 v104, v116, v117
	v_cvt_pk_bf16_f32 v105, v118, v119
	v_cvt_pk_bf16_f32 v106, v108, v109
	v_cvt_pk_bf16_f32 v107, v110, v111
	s_mov_b64 s[30:31], 0x200000
	v_add_co_u32_e32 v110, vcc, s21, v120
	v_lshl_add_u64 v[108:109], v[120:121], 0, s[30:31]
	s_nop 0
	v_addc_co_u32_e32 v111, vcc, 0, v121, vcc
	s_mov_b32 s21, 0x400000
	global_store_dwordx4 v[110:111], v[104:107], off
	v_cvt_pk_bf16_f32 v96, v96, v97
	v_cvt_pk_bf16_f32 v97, v98, v99
	v_cvt_pk_bf16_f32 v98, v88, v89
	v_cvt_pk_bf16_f32 v99, v90, v91
	global_store_dwordx4 v[108:109], v[96:99], off offset:256
	v_cvt_pk_bf16_f32 v88, v100, v101
	v_cvt_pk_bf16_f32 v89, v102, v103
	v_cvt_pk_bf16_f32 v90, v92, v93
	v_cvt_pk_bf16_f32 v91, v94, v95
	s_mov_b64 s[30:31], 0x400000
	v_add_co_u32_e32 v94, vcc, s21, v120
	v_lshl_add_u64 v[92:93], v[120:121], 0, s[30:31]
	s_nop 0
	v_addc_co_u32_e32 v95, vcc, 0, v121, vcc
	s_mov_b32 s21, 0x600000
	global_store_dwordx4 v[94:95], v[88:91], off
	v_cvt_pk_bf16_f32 v80, v80, v81
	v_cvt_pk_bf16_f32 v81, v82, v83
	v_cvt_pk_bf16_f32 v82, v72, v73
	v_cvt_pk_bf16_f32 v83, v74, v75
	global_store_dwordx4 v[92:93], v[80:83], off offset:256
	v_cvt_pk_bf16_f32 v72, v84, v85
	v_cvt_pk_bf16_f32 v73, v86, v87
	v_cvt_pk_bf16_f32 v74, v76, v77
	v_cvt_pk_bf16_f32 v75, v78, v79
	s_mov_b64 s[30:31], 0x600000
	v_add_co_u32_e32 v78, vcc, s21, v120
	v_lshl_add_u64 v[76:77], v[120:121], 0, s[30:31]
	s_nop 0
	v_addc_co_u32_e32 v79, vcc, 0, v121, vcc
	global_store_dwordx4 v[78:79], v[72:75], off
	v_cvt_pk_bf16_f32 v68, v68, v69
	v_cvt_pk_bf16_f32 v69, v70, v71
	v_cvt_pk_bf16_f32 v70, v64, v65
	v_cvt_pk_bf16_f32 v71, v66, v67
	global_store_dwordx4 v[76:77], v[68:71], off offset:256
	v_cvt_pk_bf16_f32 v60, v60, v61
	v_cvt_pk_bf16_f32 v61, v62, v63
	v_cvt_pk_bf16_f32 v62, v56, v57
	v_cvt_pk_bf16_f32 v63, v58, v59
	s_mov_b64 s[30:31], 0x1000000
	v_add_co_u32_e32 v58, vcc, s56, v120
	v_lshl_add_u64 v[56:57], v[120:121], 0, s[30:31]
	s_nop 0
	v_addc_co_u32_e32 v59, vcc, 0, v121, vcc
	global_store_dwordx4 v[58:59], v[60:63], off
	v_cvt_pk_bf16_f32 v48, v48, v49
	v_cvt_pk_bf16_f32 v49, v50, v51
	v_cvt_pk_bf16_f32 v50, v40, v41
	v_cvt_pk_bf16_f32 v51, v42, v43
	global_store_dwordx4 v[56:57], v[48:51], off offset:256
	v_cvt_pk_bf16_f32 v40, v52, v53
	v_cvt_pk_bf16_f32 v41, v54, v55
	v_cvt_pk_bf16_f32 v42, v44, v45
	v_cvt_pk_bf16_f32 v43, v46, v47
	v_add_co_u32_e32 v46, vcc, s57, v120
	v_lshl_add_u64 v[44:45], v[120:121], 0, s[6:7]
	s_nop 0
	v_addc_co_u32_e32 v47, vcc, 0, v121, vcc
	global_store_dwordx4 v[46:47], v[40:43], off
	v_cvt_pk_bf16_f32 v32, v32, v33
	v_cvt_pk_bf16_f32 v33, v34, v35
	v_cvt_pk_bf16_f32 v34, v24, v25
	v_cvt_pk_bf16_f32 v35, v26, v27
	global_store_dwordx4 v[44:45], v[32:35], off offset:256
	v_cvt_pk_bf16_f32 v24, v36, v37
	v_cvt_pk_bf16_f32 v25, v38, v39
	v_cvt_pk_bf16_f32 v26, v28, v29
	v_cvt_pk_bf16_f32 v27, v30, v31
	v_add_co_u32_e32 v30, vcc, s58, v120
	v_lshl_add_u64 v[28:29], v[120:121], 0, s[8:9]
	s_nop 0
	v_addc_co_u32_e32 v31, vcc, 0, v121, vcc
	global_store_dwordx4 v[30:31], v[24:27], off
	v_cvt_pk_bf16_f32 v16, v16, v17
	v_cvt_pk_bf16_f32 v17, v18, v19
	v_cvt_pk_bf16_f32 v18, v8, v9
	v_cvt_pk_bf16_f32 v19, v10, v11
	global_store_dwordx4 v[28:29], v[16:19], off offset:256
	v_cvt_pk_bf16_f32 v8, v20, v21
	v_cvt_pk_bf16_f32 v9, v22, v23
	v_cvt_pk_bf16_f32 v10, v12, v13
	v_cvt_pk_bf16_f32 v11, v14, v15
	v_add_co_u32_e32 v14, vcc, s59, v120
	v_lshl_add_u64 v[12:13], v[120:121], 0, s[16:17]
	s_nop 0
	v_addc_co_u32_e32 v15, vcc, 0, v121, vcc
	s_and_b64 vcc, exec, s[2:3]
	s_mov_b32 s60, s20
	s_mov_b32 s28, s22
	s_mov_b64 s[34:35], s[26:27]
	s_mov_b64 s[30:31], s[24:25]
	global_store_dwordx4 v[14:15], v[8:11], off
	v_cvt_pk_bf16_f32 v4, v4, v5
	v_cvt_pk_bf16_f32 v5, v6, v7
	v_cvt_pk_bf16_f32 v6, v0, v1
	v_cvt_pk_bf16_f32 v7, v2, v3
	global_store_dwordx4 v[12:13], v[4:7], off offset:256
	s_cbranch_vccz .LBB0_626
	s_waitcnt vmcnt(0)
	s_cmpk_gt_u32 s33, 0xff
	s_cbranch_scc1 .LBB0_637
	s_barrier

; #define PG8_STAGE(bufoff, gbase, voff) do { _Pragma("unroll") for (int _i = 0; _i < 2; ++_i) \
;         __builtin_amdgcn_global_load_lds((const unsigned*)((const char*)(gbase) + (voff)[_i]), (LAS unsigned*)(lds + (bufoff) + ldsw + _i * 8192), 16, 0, 0); } while (0)
; #define PG8_LDA(dst, b, h) do { _Pragma("unroll") for (int m = 0; m < 4; ++m) _Pragma("unroll") for (int k = 0; k < 2; ++k) dst[m][k] = *(const LAS bf16x8*)(lds + PG8_SA(b, h) + aoff + m * 2048 + k * 1024); } while (0)
; #define PG8_LDB(dst, b, h) do { _Pragma("unroll") for (int n = 0; n < 2; ++n) _Pragma("unroll") for (int k = 0; k < 2; ++k) dst[n][k] = *(const LAS bf16x8*)(lds + PG8_SB(b, h) + boff + n * 2048 + k * 1024); } while (0)
; #define PG8_MMA(ai, bj, At, Bt) do { __builtin_amdgcn_s_setprio(1); _Pragma("unroll") for (int m = 0; m < 4; ++m) _Pragma("unroll") for (int n = 0; n < 2; ++n) _Pragma("unroll") for (int k = 0; k < 2; ++k) \
;         acc[ai][bj][m][n] = __builtin_amdgcn_mfma_f32_16x16x32_bf16(Bt[n][k], At[m][k], acc[ai][bj][m][n], 0, 0, 0); __builtin_amdgcn_s_setprio(0); } while (0)
; #define PG8_WAIT_L(n) asm volatile("s_waitcnt lgkmcnt(" #n ")" ::: "memory")
; template <class Epi, class Sched>
; __device__ __forceinline__ void gemm_phase(LAS unsigned char* lds, const Gemm g, const Sched& S, const Epi& E) {
;     ...
;         const bool has_next = S.next(ui + 1, nxt);
;         const char* nA = has_next ? (const char*)g.A + (size_t)nxt.pm * tstep : cA; const char* nB = has_next ? (const char*)g.Bt + (size_t)nxt.pn * tstep : cB;
;         for (int t = 0; t < nt; t += 2) {
;             const bool last = (t == nt - 2);
;             const char* a1 = cA + (size_t)(t + 1) * kstep;
;             const char* a2 = last ? nA : cA + (size_t)(t + 2) * kstep; const char* b2 = last ? nB : cB + (size_t)(t + 2) * kstep;
;             const char* a3 = a2 + kstep; const char* b3 = b2 + kstep;
;             PG8_LDB(B0, 0, 0); PG8_SCHED; PG8_LDA(At, 0, 0); PG8_STAGE(PG8_SA(1, 1), a1 + hstep, voffA);
;             PG8_WAIT_L(8); PG8_BAR; PG8_WAIT_L(0); PG8_MMA(0, 0, At, B0); PG8_BAR; PG8_SCHED;
;             PG8_LDB(B1, 0, 1); PG8_STAGE(PG8_SB(0, 0), b2, voffB);
;             PG8_BAR; PG8_WAIT_L(0); PG8_MMA(0, 1, At, B1); PG8_BAR;
;             PG8_LDA(At, 0, 1); PG8_STAGE(PG8_SA(0, 0), a2, voffA);
;             PG8_BAR; PG8_WAIT_L(0); PG8_MMA(1, 0, At, B0); PG8_BAR; PG8_SCHED;
.LBB0_652:
	s_ashr_i32 s9, s8, 31
	v_cmp_lt_i64_e32 vcc, s[16:17], v[142:143]
	s_lshl_b64 s[16:17], s[8:9], 19
	s_add_u32 s16, s14, s16
	s_addc_u32 s17, s15, s17
	s_and_b64 s[18:19], vcc, exec
	s_cselect_b32 s9, s17, s23
	s_cselect_b32 s48, s16, s22
	s_ashr_i32 s7, s6, 31
	s_lshl_b64 s[18:19], s[6:7], 19
	s_add_u32 s18, s12, s18
	s_addc_u32 s19, s13, s19
	s_and_b64 s[26:27], vcc, exec
	s_cselect_b32 s7, s19, s25
	s_cselect_b32 s49, s18, s24
	s_add_u32 s22, s22, 0x40080
	s_addc_u32 s23, s23, 0
	s_add_u32 s51, s24, 0x100
	s_addc_u32 s52, s25, 0
	s_mov_b32 s53, -2
	s_waitcnt lgkmcnt(0)
	ds_read_b128 v[152:155], v149
	ds_read_b128 v[156:159], v149 offset:1024
	ds_read_b128 v[160:163], v149 offset:2048
	ds_read_b128 v[164:167], v149 offset:3072
	s_add_u32 s24, s22, 0xfffc0080
	s_addc_u32 s25, s23, -1
	s_cmp_eq_u32 s53, 12
	s_cselect_b32 s27, s9, s25
	s_cselect_b32 s26, s48, s24
	s_cselect_b32 s25, s7, s52
	s_cselect_b32 s24, s49, s51
	s_add_i32 m0, s21, 0xc000
	ds_read_b128 v[168:171], v150
	ds_read_b128 v[172:175], v150 offset:1024
	ds_read_b128 v[176:179], v150 offset:2048
	ds_read_b128 v[180:183], v150 offset:3072
	ds_read_b128 v[184:187], v150 offset:4096
	ds_read_b128 v[188:191], v150 offset:5120
	ds_read_b128 v[192:195], v150 offset:6144
	ds_read_b128 v[196:199], v150 offset:7168
	global_load_lds_dwordx4 v138, s[22:23]
	s_add_i32 m0, s21, 0xe000
	s_nop 0
	global_load_lds_dwordx4 v140, s[22:23]
	s_waitcnt lgkmcnt(8)
	s_waitcnt vmcnt(8)
	s_setprio 1
	s_barrier
	s_waitcnt lgkmcnt(0)
	v_mfma_f32_16x16x32_bf16 v[124:127], v[152:155], v[168:171], 0
	v_mfma_f32_16x16x32_bf16 v[120:123], v[160:163], v[168:171], 0
	v_mfma_f32_16x16x32_bf16 v[112:115], v[152:155], v[176:179], 0
	v_mfma_f32_16x16x32_bf16 v[104:107], v[160:163], v[176:179], 0
	v_mfma_f32_16x16x32_bf16 v[96:99], v[152:155], v[184:187], 0
	v_mfma_f32_16x16x32_bf16 v[88:91], v[160:163], v[184:187], 0
	v_mfma_f32_16x16x32_bf16 v[80:83], v[152:155], v[192:195], 0
	v_mfma_f32_16x16x32_bf16 v[72:75], v[160:163], v[192:195], 0
	v_mfma_f32_16x16x32_bf16 v[124:127], v[156:159], v[172:175], v[124:127]
	v_mfma_f32_16x16x32_bf16 v[120:123], v[164:167], v[172:175], v[120:123]
	v_mfma_f32_16x16x32_bf16 v[112:115], v[156:159], v[180:183], v[112:115]
	v_mfma_f32_16x16x32_bf16 v[104:107], v[164:167], v[180:183], v[104:107]
	v_mfma_f32_16x16x32_bf16 v[96:99], v[156:159], v[188:191], v[96:99]
	v_mfma_f32_16x16x32_bf16 v[88:91], v[164:167], v[188:191], v[88:91]
	v_mfma_f32_16x16x32_bf16 v[80:83], v[156:159], v[196:199], v[80:83]
	v_mfma_f32_16x16x32_bf16 v[72:75], v[164:167], v[196:199], v[72:75]
	s_barrier
	s_setprio 0
	s_add_i32 s54, s45, s30
	s_mov_b32 m0, s54
	ds_read_b128 v[202:205], v151
	ds_read_b128 v[206:209], v151 offset:1024
	ds_read_b128 v[210:213], v151 offset:2048
	ds_read_b128 v[214:217], v151 offset:3072
	global_load_lds_dwordx4 v130, s[24:25]
	s_add_i32 m0, s54, 0x2000
	s_nop 0
	global_load_lds_dwordx4 v134, s[24:25]
	s_waitcnt vmcnt(8)
	s_setprio 1
	s_barrier
	s_waitcnt lgkmcnt(0)
	v_mfma_f32_16x16x32_bf16 v[116:119], v[202:205], v[168:171], 0
	v_mfma_f32_16x16x32_bf16 v[108:111], v[210:213], v[168:171], 0
	v_mfma_f32_16x16x32_bf16 v[100:103], v[202:205], v[176:179], 0
	v_mfma_f32_16x16x32_bf16 v[92:95], v[210:213], v[176:179], 0
	v_mfma_f32_16x16x32_bf16 v[84:87], v[202:205], v[184:187], 0
	v_mfma_f32_16x16x32_bf16 v[76:79], v[210:213], v[184:187], 0
	v_mfma_f32_16x16x32_bf16 v[68:71], v[202:205], v[192:195], 0
	v_mfma_f32_16x16x32_bf16 v[64:67], v[210:213], v[192:195], 0
	v_mfma_f32_16x16x32_bf16 v[116:119], v[206:209], v[172:175], v[116:119]
	v_mfma_f32_16x16x32_bf16 v[108:111], v[214:217], v[172:175], v[108:111]
	v_mfma_f32_16x16x32_bf16 v[100:103], v[206:209], v[180:183], v[100:103]
	v_mfma_f32_16x16x32_bf16 v[92:95], v[214:217], v[180:183], v[92:95]
	v_mfma_f32_16x16x32_bf16 v[84:87], v[206:209], v[188:191], v[84:87]
	v_mfma_f32_16x16x32_bf16 v[76:79], v[214:217], v[188:191], v[76:79]
	v_mfma_f32_16x16x32_bf16 v[68:71], v[206:209], v[196:199], v[68:71]
	v_mfma_f32_16x16x32_bf16 v[64:67], v[214:217], v[196:199], v[64:67]
	s_barrier
	s_setprio 0
	s_mov_b32 m0, s21
	v_lshl_add_u64 v[222:223], s[26:27], 0, v[128:129]
	ds_read_b128 v[168:171], v150 offset:16384
	ds_read_b128 v[172:175], v150 offset:17408
	ds_read_b128 v[176:179], v150 offset:18432
	ds_read_b128 v[180:183], v150 offset:19456
	ds_read_b128 v[184:187], v150 offset:20480
	ds_read_b128 v[188:191], v150 offset:21504
	ds_read_b128 v[192:195], v150 offset:22528
	ds_read_b128 v[196:199], v150 offset:23552
	global_load_lds_dwordx4 v128, s[26:27]
	v_lshl_add_u64 v[224:225], s[26:27], 0, v[132:133]
	s_mov_b32 m0, s31
	s_nop 0
	global_load_lds_dwordx4 v132, s[26:27]
	s_setprio 1
	s_barrier
	s_waitcnt lgkmcnt(0)
	v_mfma_f32_16x16x32_bf16 v[60:63], v[152:155], v[168:171], 0
	v_mfma_f32_16x16x32_bf16 v[56:59], v[160:163], v[168:171], 0
	v_mfma_f32_16x16x32_bf16 v[48:51], v[152:155], v[176:179], 0
	v_mfma_f32_16x16x32_bf16 v[40:43], v[160:163], v[176:179], 0
	v_mfma_f32_16x16x32_bf16 v[32:35], v[152:155], v[184:187], 0
	v_mfma_f32_16x16x32_bf16 v[24:27], v[160:163], v[184:187], 0
	v_mfma_f32_16x16x32_bf16 v[16:19], v[152:155], v[192:195], 0
	v_mfma_f32_16x16x32_bf16 v[8:11], v[160:163], v[192:195], 0
	v_mfma_f32_16x16x32_bf16 v[60:63], v[156:159], v[172:175], v[60:63]
	v_mfma_f32_16x16x32_bf16 v[56:59], v[164:167], v[172:175], v[56:59]
	v_mfma_f32_16x16x32_bf16 v[48:51], v[156:159], v[180:183], v[48:51]
	v_mfma_f32_16x16x32_bf16 v[40:43], v[164:167], v[180:183], v[40:43]
	v_mfma_f32_16x16x32_bf16 v[32:35], v[156:159], v[188:191], v[32:35]
	v_mfma_f32_16x16x32_bf16 v[24:27], v[164:167], v[188:191], v[24:27]
	v_mfma_f32_16x16x32_bf16 v[16:19], v[156:159], v[196:199], v[16:19]
	v_mfma_f32_16x16x32_bf16 v[8:11], v[164:167], v[196:199], v[8:11]
	s_barrier
; #define PG8_STAGE(bufoff, gbase, voff) do { _Pragma("unroll") for (int _i = 0; _i < 2; ++_i) \
;         __builtin_amdgcn_global_load_lds((const unsigned*)((const char*)(gbase) + (voff)[_i]), (LAS unsigned*)(lds + (bufoff) + ldsw + _i * 8192), 16, 0, 0); } while (0)
; #define PG8_LDA(dst, b, h) do { _Pragma("unroll") for (int m = 0; m < 4; ++m) _Pragma("unroll") for (int k = 0; k < 2; ++k) dst[m][k] = *(const LAS bf16x8*)(lds + PG8_SA(b, h) + aoff + m * 2048 + k * 1024); } while (0)
; #define PG8_LDB(dst, b, h) do { _Pragma("unroll") for (int n = 0; n < 2; ++n) _Pragma("unroll") for (int k = 0; k < 2; ++k) dst[n][k] = *(const LAS bf16x8*)(lds + PG8_SB(b, h) + boff + n * 2048 + k * 1024); } while (0)
; #define PG8_MMA(ai, bj, At, Bt) do { __builtin_amdgcn_s_setprio(1); _Pragma("unroll") for (int m = 0; m < 4; ++m) _Pragma("unroll") for (int n = 0; n < 2; ++n) _Pragma("unroll") for (int k = 0; k < 2; ++k) \
;         acc[ai][bj][m][n] = __builtin_amdgcn_mfma_f32_16x16x32_bf16(Bt[n][k], At[m][k], acc[ai][bj][m][n], 0, 0, 0); __builtin_amdgcn_s_setprio(0); } while (0)
; #define PG8_WAIT_V(n) asm volatile("s_waitcnt vmcnt(" #n ")" ::: "memory")
; #define PG8_WAIT_L(n) asm volatile("s_waitcnt lgkmcnt(" #n ")" ::: "memory")
; #define PG8_BAR __builtin_amdgcn_s_barrier()
; #define PG8_SCHED __builtin_amdgcn_sched_barrier(0)
; template <class Epi, class Sched>
; __device__ __forceinline__ void gemm_phase(LAS unsigned char* lds, const Gemm g, const Sched& S, const Epi& E) {
;     ...
;             PG8_STAGE(PG8_SB(0, 1), b2 + hstep, voffB);
;             PG8_WAIT_V(6); PG8_BAR; PG8_MMA(1, 1, At, B1); PG8_BAR;
;             PG8_LDB(B0, 1, 0); PG8_SCHED; PG8_LDA(At, 1, 0); PG8_STAGE(PG8_SA(0, 1), a2 + hstep, voffA);
;             PG8_WAIT_L(8); PG8_BAR; PG8_WAIT_L(0); PG8_MMA(0, 0, At, B0); PG8_BAR; PG8_SCHED;
;             PG8_LDB(B1, 1, 1); PG8_STAGE(PG8_SB(1, 0), b3, voffB);
;             PG8_BAR; PG8_WAIT_L(0); PG8_MMA(0, 1, At, B1); PG8_BAR;
;             PG8_LDA(At, 1, 1); PG8_STAGE(PG8_SA(1, 0), a3, voffA);
	s_setprio 0
	s_add_u32 s54, s24, 0x40000
	s_addc_u32 s55, s25, 0
	s_add_i32 s56, s46, s30
	s_mov_b32 m0, s56
	s_nop 0
	global_load_lds_dwordx4 v130, s[54:55]
	s_add_i32 m0, s56, 0x2000
	s_nop 0
	global_load_lds_dwordx4 v134, s[54:55]
	s_add_u32 s26, s26, 0x40000
	s_addc_u32 s27, s27, 0
	s_mov_b32 m0, s33
	s_nop 0
	global_load_lds_dwordx4 v128, s[26:27]
	s_mov_b32 m0, s34
	s_nop 0
	global_load_lds_dwordx4 v132, s[26:27]
	s_waitcnt vmcnt(10)
	s_setprio 1
	s_barrier
	v_mfma_f32_16x16x32_bf16 v[52:55], v[202:205], v[168:171], 0
	v_mfma_f32_16x16x32_bf16 v[44:47], v[210:213], v[168:171], 0
	v_mfma_f32_16x16x32_bf16 v[36:39], v[202:205], v[176:179], 0
	v_mfma_f32_16x16x32_bf16 v[28:31], v[210:213], v[176:179], 0
	v_mfma_f32_16x16x32_bf16 v[20:23], v[202:205], v[184:187], 0
	v_mfma_f32_16x16x32_bf16 v[12:15], v[210:213], v[184:187], 0
	v_mfma_f32_16x16x32_bf16 v[4:7], v[202:205], v[192:195], 0
	v_mfma_f32_16x16x32_bf16 v[0:3], v[210:213], v[192:195], 0
	v_mfma_f32_16x16x32_bf16 v[52:55], v[206:209], v[172:175], v[52:55]
	v_mfma_f32_16x16x32_bf16 v[44:47], v[214:217], v[172:175], v[44:47]
	v_mfma_f32_16x16x32_bf16 v[36:39], v[206:209], v[180:183], v[36:39]
	v_mfma_f32_16x16x32_bf16 v[28:31], v[214:217], v[180:183], v[28:31]
	v_mfma_f32_16x16x32_bf16 v[20:23], v[206:209], v[188:191], v[20:23]
	v_mfma_f32_16x16x32_bf16 v[12:15], v[214:217], v[188:191], v[12:15]
	v_mfma_f32_16x16x32_bf16 v[4:7], v[206:209], v[196:199], v[4:7]
	v_mfma_f32_16x16x32_bf16 v[0:3], v[214:217], v[196:199], v[0:3]
	s_barrier
	s_setprio 0
	s_add_i32 s54, 0, 0x18000
	ds_read_b128 v[152:155], v151 offset:16384
	ds_read_b128 v[156:159], v151 offset:17408
	ds_read_b128 v[160:163], v151 offset:18432
	ds_read_b128 v[164:167], v151 offset:19456
	ds_read_b128 v[168:171], v150 offset:32768
	ds_read_b128 v[172:175], v150 offset:33792
	ds_read_b128 v[176:179], v150 offset:34816
	ds_read_b128 v[180:183], v150 offset:35840
	ds_read_b128 v[184:187], v150 offset:36864
	ds_read_b128 v[188:191], v150 offset:37888
	ds_read_b128 v[192:195], v150 offset:38912
	ds_read_b128 v[196:199], v150 offset:39936
	s_waitcnt lgkmcnt(8)
	s_waitcnt vmcnt(8)
	s_setprio 1
	s_barrier
	s_waitcnt lgkmcnt(0)
	v_mfma_f32_16x16x32_bf16 v[124:127], v[152:155], v[168:171], v[124:127]
	v_mfma_f32_16x16x32_bf16 v[120:123], v[160:163], v[168:171], v[120:123]
	v_mfma_f32_16x16x32_bf16 v[112:115], v[152:155], v[176:179], v[112:115]
	v_mfma_f32_16x16x32_bf16 v[104:107], v[160:163], v[176:179], v[104:107]
	v_mfma_f32_16x16x32_bf16 v[96:99], v[152:155], v[184:187], v[96:99]
	v_mfma_f32_16x16x32_bf16 v[88:91], v[160:163], v[184:187], v[88:91]
	v_mfma_f32_16x16x32_bf16 v[80:83], v[152:155], v[192:195], v[80:83]
	v_mfma_f32_16x16x32_bf16 v[72:75], v[160:163], v[192:195], v[72:75]
	v_mfma_f32_16x16x32_bf16 v[124:127], v[156:159], v[172:175], v[124:127]
	v_mfma_f32_16x16x32_bf16 v[120:123], v[164:167], v[172:175], v[120:123]
	v_mfma_f32_16x16x32_bf16 v[112:115], v[156:159], v[180:183], v[112:115]
	v_mfma_f32_16x16x32_bf16 v[104:107], v[164:167], v[180:183], v[104:107]
	v_mfma_f32_16x16x32_bf16 v[96:99], v[156:159], v[188:191], v[96:99]
	v_mfma_f32_16x16x32_bf16 v[88:91], v[164:167], v[188:191], v[88:91]
	v_mfma_f32_16x16x32_bf16 v[80:83], v[156:159], v[196:199], v[80:83]
	v_mfma_f32_16x16x32_bf16 v[72:75], v[164:167], v[196:199], v[72:75]
	s_barrier
	s_setprio 0
	s_add_i32 s26, 0, 0x1c000
	s_add_i32 s27, s54, s30
	v_add_u32_e32 v136, s26, v148
	s_add_u32 s0, s24, 0x80
	s_addc_u32 s1, s25, 0
	s_mov_b32 m0, s27
	ds_read_b128 v[202:205], v136
	ds_read_b128 v[206:209], v136 offset:1024
	ds_read_b128 v[210:213], v136 offset:2048
	ds_read_b128 v[214:217], v136 offset:3072
	global_load_lds_dwordx4 v130, s[0:1]
	s_add_i32 m0, s27, 0x2000
	s_nop 0
	global_load_lds_dwordx4 v134, s[0:1]
	s_waitcnt vmcnt(8)
	s_setprio 1
	s_barrier
	s_waitcnt lgkmcnt(0)
	v_mfma_f32_16x16x32_bf16 v[116:119], v[202:205], v[168:171], v[116:119]
	v_mfma_f32_16x16x32_bf16 v[108:111], v[210:213], v[168:171], v[108:111]
	v_mfma_f32_16x16x32_bf16 v[100:103], v[202:205], v[176:179], v[100:103]
	v_mfma_f32_16x16x32_bf16 v[92:95], v[210:213], v[176:179], v[92:95]
	v_mfma_f32_16x16x32_bf16 v[84:87], v[202:205], v[184:187], v[84:87]
	v_mfma_f32_16x16x32_bf16 v[76:79], v[210:213], v[184:187], v[76:79]
	v_mfma_f32_16x16x32_bf16 v[68:71], v[202:205], v[192:195], v[68:71]
	v_mfma_f32_16x16x32_bf16 v[64:67], v[210:213], v[192:195], v[64:67]
	v_mfma_f32_16x16x32_bf16 v[116:119], v[206:209], v[172:175], v[116:119]
	v_mfma_f32_16x16x32_bf16 v[108:111], v[214:217], v[172:175], v[108:111]
	v_mfma_f32_16x16x32_bf16 v[100:103], v[206:209], v[180:183], v[100:103]
	v_mfma_f32_16x16x32_bf16 v[92:95], v[214:217], v[180:183], v[92:95]
	v_mfma_f32_16x16x32_bf16 v[84:87], v[206:209], v[188:191], v[84:87]
	v_mfma_f32_16x16x32_bf16 v[76:79], v[214:217], v[188:191], v[76:79]
	v_mfma_f32_16x16x32_bf16 v[68:71], v[206:209], v[196:199], v[68:71]
	v_mfma_f32_16x16x32_bf16 v[64:67], v[214:217], v[196:199], v[64:67]
	s_barrier
	s_setprio 0
	s_mov_b32 m0, s42
	s_mov_b64 s[0:1], 0x80
	v_lshl_add_u64 v[218:219], v[222:223], 0, s[0:1]
	ds_read_b128 v[168:171], v150 offset:49152
	ds_read_b128 v[172:175], v150 offset:50176
	ds_read_b128 v[176:179], v150 offset:51200
	ds_read_b128 v[180:183], v150 offset:52224
	ds_read_b128 v[184:187], v150 offset:53248
	ds_read_b128 v[188:191], v150 offset:54272
	ds_read_b128 v[192:195], v150 offset:55296
	ds_read_b128 v[196:199], v150 offset:56320
	global_load_lds_dwordx4 v[218:219], off
	v_lshl_add_u64 v[218:219], v[224:225], 0, s[0:1]
	s_mov_b32 m0, s43
	s_nop 0
	global_load_lds_dwordx4 v[218:219], off
	s_setprio 1
	s_barrier
; #define PG8_STAGE(bufoff, gbase, voff) do { _Pragma("unroll") for (int _i = 0; _i < 2; ++_i) \
;         __builtin_amdgcn_global_load_lds((const unsigned*)((const char*)(gbase) + (voff)[_i]), (LAS unsigned*)(lds + (bufoff) + ldsw + _i * 8192), 16, 0, 0); } while (0)
; #define PG8_LDA(dst, b, h) do { _Pragma("unroll") for (int m = 0; m < 4; ++m) _Pragma("unroll") for (int k = 0; k < 2; ++k) dst[m][k] = *(const LAS bf16x8*)(lds + PG8_SA(b, h) + aoff + m * 2048 + k * 1024); } while (0)
; #define PG8_LDB(dst, b, h) do { _Pragma("unroll") for (int n = 0; n < 2; ++n) _Pragma("unroll") for (int k = 0; k < 2; ++k) dst[n][k] = *(const LAS bf16x8*)(lds + PG8_SB(b, h) + boff + n * 2048 + k * 1024); } while (0)
; #define PG8_MMA(ai, bj, At, Bt) do { __builtin_amdgcn_s_setprio(1); _Pragma("unroll") for (int m = 0; m < 4; ++m) _Pragma("unroll") for (int n = 0; n < 2; ++n) _Pragma("unroll") for (int k = 0; k < 2; ++k) \
;         acc[ai][bj][m][n] = __builtin_amdgcn_mfma_f32_16x16x32_bf16(Bt[n][k], At[m][k], acc[ai][bj][m][n], 0, 0, 0); __builtin_amdgcn_s_setprio(0); } while (0)
; #define PG8_WAIT_V(n) asm volatile("s_waitcnt vmcnt(" #n ")" ::: "memory")
; #define PG8_WAIT_L(n) asm volatile("s_waitcnt lgkmcnt(" #n ")" ::: "memory")
; #define PG8_BAR __builtin_amdgcn_s_barrier()
; #define PG8_SCHED __builtin_amdgcn_sched_barrier(0)
; template <class Epi, class Sched>
; __device__ __forceinline__ void gemm_phase(LAS unsigned char* lds, const Gemm g, const Sched& S, const Epi& E) {
;     ...
;         for (int t = 0; t < nt; t += 2) {
;             const bool last = (t == nt - 2);
;             const char* a1 = cA + (size_t)(t + 1) * kstep;
;             const char* a2 = last ? nA : cA + (size_t)(t + 2) * kstep; const char* b2 = last ? nB : cB + (size_t)(t + 2) * kstep;
;             const char* a3 = a2 + kstep; const char* b3 = b2 + kstep;
;             PG8_LDB(B0, 0, 0); PG8_SCHED; PG8_LDA(At, 0, 0); PG8_STAGE(PG8_SA(1, 1), a1 + hstep, voffA);
;             PG8_WAIT_L(8); PG8_BAR; PG8_WAIT_L(0); PG8_MMA(0, 0, At, B0); PG8_BAR; PG8_SCHED;
;             PG8_LDB(B1, 0, 1); PG8_STAGE(PG8_SB(0, 0), b2, voffB);
;             PG8_BAR; PG8_WAIT_L(0); PG8_MMA(0, 1, At, B1); PG8_BAR;
;     ...
;             PG8_BAR; PG8_WAIT_L(0); PG8_MMA(1, 0, At, B0); PG8_BAR; PG8_SCHED;
;             PG8_STAGE(PG8_SB(1, 1), b3 + hstep, voffB);
;             PG8_WAIT_V(6); PG8_BAR; PG8_MMA(1, 1, At, B1); PG8_BAR;
	s_waitcnt lgkmcnt(0)
	v_mfma_f32_16x16x32_bf16 v[60:63], v[152:155], v[168:171], v[60:63]
	v_mfma_f32_16x16x32_bf16 v[56:59], v[160:163], v[168:171], v[56:59]
	v_mfma_f32_16x16x32_bf16 v[48:51], v[152:155], v[176:179], v[48:51]
	v_mfma_f32_16x16x32_bf16 v[40:43], v[160:163], v[176:179], v[40:43]
	v_mfma_f32_16x16x32_bf16 v[32:35], v[152:155], v[184:187], v[32:35]
	v_mfma_f32_16x16x32_bf16 v[24:27], v[160:163], v[184:187], v[24:27]
	v_mfma_f32_16x16x32_bf16 v[16:19], v[152:155], v[192:195], v[16:19]
	v_mfma_f32_16x16x32_bf16 v[8:11], v[160:163], v[192:195], v[8:11]
	v_mfma_f32_16x16x32_bf16 v[60:63], v[156:159], v[172:175], v[60:63]
	v_mfma_f32_16x16x32_bf16 v[56:59], v[164:167], v[172:175], v[56:59]
	v_mfma_f32_16x16x32_bf16 v[48:51], v[156:159], v[180:183], v[48:51]
	v_mfma_f32_16x16x32_bf16 v[40:43], v[164:167], v[180:183], v[40:43]
	v_mfma_f32_16x16x32_bf16 v[32:35], v[156:159], v[188:191], v[32:35]
	v_mfma_f32_16x16x32_bf16 v[24:27], v[164:167], v[188:191], v[24:27]
	v_mfma_f32_16x16x32_bf16 v[16:19], v[156:159], v[196:199], v[16:19]
	v_mfma_f32_16x16x32_bf16 v[8:11], v[164:167], v[196:199], v[8:11]
	s_barrier
	s_setprio 0
	s_add_u32 s24, s24, 0x40080
	s_addc_u32 s25, s25, 0
	s_add_i32 s26, s26, s30
	s_mov_b32 m0, s26
	s_nop 0
	global_load_lds_dwordx4 v130, s[24:25]
	s_add_i32 m0, s26, 0x2000
	s_nop 0
	global_load_lds_dwordx4 v134, s[24:25]
	s_waitcnt vmcnt(8)
	s_setprio 1
	s_barrier
	v_mfma_f32_16x16x32_bf16 v[52:55], v[202:205], v[168:171], v[52:55]
	v_mfma_f32_16x16x32_bf16 v[44:47], v[210:213], v[168:171], v[44:47]
	v_mfma_f32_16x16x32_bf16 v[36:39], v[202:205], v[176:179], v[36:39]
	v_mfma_f32_16x16x32_bf16 v[28:31], v[210:213], v[176:179], v[28:31]
	v_mfma_f32_16x16x32_bf16 v[20:23], v[202:205], v[184:187], v[20:23]
	v_mfma_f32_16x16x32_bf16 v[12:15], v[210:213], v[184:187], v[12:15]
	v_mfma_f32_16x16x32_bf16 v[4:7], v[202:205], v[192:195], v[4:7]
	v_mfma_f32_16x16x32_bf16 v[0:3], v[210:213], v[192:195], v[0:3]
	v_mfma_f32_16x16x32_bf16 v[52:55], v[206:209], v[172:175], v[52:55]
	v_mfma_f32_16x16x32_bf16 v[44:47], v[214:217], v[172:175], v[44:47]
	v_mfma_f32_16x16x32_bf16 v[36:39], v[206:209], v[180:183], v[36:39]
	v_mfma_f32_16x16x32_bf16 v[28:31], v[214:217], v[180:183], v[28:31]
	v_mfma_f32_16x16x32_bf16 v[20:23], v[206:209], v[188:191], v[20:23]
	v_mfma_f32_16x16x32_bf16 v[12:15], v[214:217], v[188:191], v[12:15]
	v_mfma_f32_16x16x32_bf16 v[4:7], v[206:209], v[196:199], v[4:7]
	v_mfma_f32_16x16x32_bf16 v[0:3], v[214:217], v[196:199], v[0:3]
	s_barrier
	s_setprio 0
	s_add_i32 s53, s53, 2
	s_add_u32 s22, s22, 0x100
	s_addc_u32 s23, s23, 0
	s_add_u32 s51, s51, 0x100
	s_addc_u32 s52, s52, 0
	s_cmp_gt_u32 s53, 13
.LBB0_653:
	ds_read_b128 v[152:155], v149
	ds_read_b128 v[156:159], v149 offset:1024
	ds_read_b128 v[160:163], v149 offset:2048
	ds_read_b128 v[164:167], v149 offset:3072
	s_add_u32 s24, s22, 0xfffc0080
	s_addc_u32 s25, s23, -1
	s_cmp_eq_u32 s53, 12
	s_cselect_b32 s27, s9, s25
	s_cselect_b32 s26, s48, s24
	s_cselect_b32 s25, s7, s52
	s_cselect_b32 s24, s49, s51
	s_add_i32 m0, s21, 0xc000
	ds_read_b128 v[168:171], v150
	ds_read_b128 v[172:175], v150 offset:1024
	ds_read_b128 v[176:179], v150 offset:2048
	ds_read_b128 v[180:183], v150 offset:3072
	ds_read_b128 v[184:187], v150 offset:4096
	ds_read_b128 v[188:191], v150 offset:5120
	ds_read_b128 v[192:195], v150 offset:6144
	ds_read_b128 v[196:199], v150 offset:7168
	global_load_lds_dwordx4 v138, s[22:23]
	s_add_i32 m0, s21, 0xe000
	s_nop 0
	global_load_lds_dwordx4 v140, s[22:23]
	s_waitcnt lgkmcnt(8)
	s_waitcnt vmcnt(8)
	s_setprio 1
	s_barrier
	s_waitcnt lgkmcnt(0)
	v_mfma_f32_16x16x32_bf16 v[124:127], v[152:155], v[168:171], v[124:127]
	v_mfma_f32_16x16x32_bf16 v[120:123], v[160:163], v[168:171], v[120:123]
	v_mfma_f32_16x16x32_bf16 v[112:115], v[152:155], v[176:179], v[112:115]
	v_mfma_f32_16x16x32_bf16 v[104:107], v[160:163], v[176:179], v[104:107]
	v_mfma_f32_16x16x32_bf16 v[96:99], v[152:155], v[184:187], v[96:99]
	v_mfma_f32_16x16x32_bf16 v[88:91], v[160:163], v[184:187], v[88:91]
	v_mfma_f32_16x16x32_bf16 v[80:83], v[152:155], v[192:195], v[80:83]
	v_mfma_f32_16x16x32_bf16 v[72:75], v[160:163], v[192:195], v[72:75]
	v_mfma_f32_16x16x32_bf16 v[124:127], v[156:159], v[172:175], v[124:127]
	v_mfma_f32_16x16x32_bf16 v[120:123], v[164:167], v[172:175], v[120:123]
	v_mfma_f32_16x16x32_bf16 v[112:115], v[156:159], v[180:183], v[112:115]
	v_mfma_f32_16x16x32_bf16 v[104:107], v[164:167], v[180:183], v[104:107]
	v_mfma_f32_16x16x32_bf16 v[96:99], v[156:159], v[188:191], v[96:99]
	v_mfma_f32_16x16x32_bf16 v[88:91], v[164:167], v[188:191], v[88:91]
	v_mfma_f32_16x16x32_bf16 v[80:83], v[156:159], v[196:199], v[80:83]
	v_mfma_f32_16x16x32_bf16 v[72:75], v[164:167], v[196:199], v[72:75]
	s_barrier
	s_setprio 0
	s_add_i32 s54, s45, s30
	s_mov_b32 m0, s54
	ds_read_b128 v[202:205], v151
	ds_read_b128 v[206:209], v151 offset:1024
	ds_read_b128 v[210:213], v151 offset:2048
	ds_read_b128 v[214:217], v151 offset:3072
	global_load_lds_dwordx4 v130, s[24:25]
	s_add_i32 m0, s54, 0x2000
	s_nop 0
	global_load_lds_dwordx4 v134, s[24:25]
	s_waitcnt vmcnt(8)
	s_setprio 1
	s_barrier
; #define PG8_STAGE(bufoff, gbase, voff) do { _Pragma("unroll") for (int _i = 0; _i < 2; ++_i) \
;         __builtin_amdgcn_global_load_lds((const unsigned*)((const char*)(gbase) + (voff)[_i]), (LAS unsigned*)(lds + (bufoff) + ldsw + _i * 8192), 16, 0, 0); } while (0)
; #define PG8_LDA(dst, b, h) do { _Pragma("unroll") for (int m = 0; m < 4; ++m) _Pragma("unroll") for (int k = 0; k < 2; ++k) dst[m][k] = *(const LAS bf16x8*)(lds + PG8_SA(b, h) + aoff + m * 2048 + k * 1024); } while (0)
; #define PG8_LDB(dst, b, h) do { _Pragma("unroll") for (int n = 0; n < 2; ++n) _Pragma("unroll") for (int k = 0; k < 2; ++k) dst[n][k] = *(const LAS bf16x8*)(lds + PG8_SB(b, h) + boff + n * 2048 + k * 1024); } while (0)
; #define PG8_MMA(ai, bj, At, Bt) do { __builtin_amdgcn_s_setprio(1); _Pragma("unroll") for (int m = 0; m < 4; ++m) _Pragma("unroll") for (int n = 0; n < 2; ++n) _Pragma("unroll") for (int k = 0; k < 2; ++k) \
;         acc[ai][bj][m][n] = __builtin_amdgcn_mfma_f32_16x16x32_bf16(Bt[n][k], At[m][k], acc[ai][bj][m][n], 0, 0, 0); __builtin_amdgcn_s_setprio(0); } while (0)
; #define PG8_WAIT_V(n) asm volatile("s_waitcnt vmcnt(" #n ")" ::: "memory")
; #define PG8_WAIT_L(n) asm volatile("s_waitcnt lgkmcnt(" #n ")" ::: "memory")
; #define PG8_BAR __builtin_amdgcn_s_barrier()
; #define PG8_SCHED __builtin_amdgcn_sched_barrier(0)
; template <class Epi, class Sched>
; __device__ __forceinline__ void gemm_phase(LAS unsigned char* lds, const Gemm g, const Sched& S, const Epi& E) {
;     ...
;             PG8_BAR; PG8_WAIT_L(0); PG8_MMA(0, 1, At, B1); PG8_BAR;
;             PG8_LDA(At, 0, 1); PG8_STAGE(PG8_SA(0, 0), a2, voffA);
;             PG8_BAR; PG8_WAIT_L(0); PG8_MMA(1, 0, At, B0); PG8_BAR; PG8_SCHED;
;             PG8_STAGE(PG8_SB(0, 1), b2 + hstep, voffB);
;             PG8_WAIT_V(6); PG8_BAR; PG8_MMA(1, 1, At, B1); PG8_BAR;
;             PG8_LDB(B0, 1, 0); PG8_SCHED; PG8_LDA(At, 1, 0); PG8_STAGE(PG8_SA(0, 1), a2 + hstep, voffA);
;             PG8_WAIT_L(8); PG8_BAR; PG8_WAIT_L(0); PG8_MMA(0, 0, At, B0); PG8_BAR; PG8_SCHED;
	s_waitcnt lgkmcnt(0)
	v_mfma_f32_16x16x32_bf16 v[116:119], v[202:205], v[168:171], v[116:119]
	v_mfma_f32_16x16x32_bf16 v[108:111], v[210:213], v[168:171], v[108:111]
	v_mfma_f32_16x16x32_bf16 v[100:103], v[202:205], v[176:179], v[100:103]
	v_mfma_f32_16x16x32_bf16 v[92:95], v[210:213], v[176:179], v[92:95]
	v_mfma_f32_16x16x32_bf16 v[84:87], v[202:205], v[184:187], v[84:87]
	v_mfma_f32_16x16x32_bf16 v[76:79], v[210:213], v[184:187], v[76:79]
	v_mfma_f32_16x16x32_bf16 v[68:71], v[202:205], v[192:195], v[68:71]
	v_mfma_f32_16x16x32_bf16 v[64:67], v[210:213], v[192:195], v[64:67]
	v_mfma_f32_16x16x32_bf16 v[116:119], v[206:209], v[172:175], v[116:119]
	v_mfma_f32_16x16x32_bf16 v[108:111], v[214:217], v[172:175], v[108:111]
	v_mfma_f32_16x16x32_bf16 v[100:103], v[206:209], v[180:183], v[100:103]
	v_mfma_f32_16x16x32_bf16 v[92:95], v[214:217], v[180:183], v[92:95]
	v_mfma_f32_16x16x32_bf16 v[84:87], v[206:209], v[188:191], v[84:87]
	v_mfma_f32_16x16x32_bf16 v[76:79], v[214:217], v[188:191], v[76:79]
	v_mfma_f32_16x16x32_bf16 v[68:71], v[206:209], v[196:199], v[68:71]
	v_mfma_f32_16x16x32_bf16 v[64:67], v[214:217], v[196:199], v[64:67]
	s_barrier
	s_setprio 0
	s_mov_b32 m0, s21
	v_lshl_add_u64 v[222:223], s[26:27], 0, v[128:129]
	ds_read_b128 v[168:171], v150 offset:16384
	ds_read_b128 v[172:175], v150 offset:17408
	ds_read_b128 v[176:179], v150 offset:18432
	ds_read_b128 v[180:183], v150 offset:19456
	ds_read_b128 v[184:187], v150 offset:20480
	ds_read_b128 v[188:191], v150 offset:21504
	ds_read_b128 v[192:195], v150 offset:22528
	ds_read_b128 v[196:199], v150 offset:23552
	global_load_lds_dwordx4 v128, s[26:27]
	v_lshl_add_u64 v[224:225], s[26:27], 0, v[132:133]
	s_mov_b32 m0, s31
	s_nop 0
	global_load_lds_dwordx4 v132, s[26:27]
	s_setprio 1
	s_barrier
	s_waitcnt lgkmcnt(0)
	v_mfma_f32_16x16x32_bf16 v[60:63], v[152:155], v[168:171], v[60:63]
	v_mfma_f32_16x16x32_bf16 v[56:59], v[160:163], v[168:171], v[56:59]
	v_mfma_f32_16x16x32_bf16 v[48:51], v[152:155], v[176:179], v[48:51]
	v_mfma_f32_16x16x32_bf16 v[40:43], v[160:163], v[176:179], v[40:43]
	v_mfma_f32_16x16x32_bf16 v[32:35], v[152:155], v[184:187], v[32:35]
	v_mfma_f32_16x16x32_bf16 v[24:27], v[160:163], v[184:187], v[24:27]
	v_mfma_f32_16x16x32_bf16 v[16:19], v[152:155], v[192:195], v[16:19]
	v_mfma_f32_16x16x32_bf16 v[8:11], v[160:163], v[192:195], v[8:11]
	v_mfma_f32_16x16x32_bf16 v[60:63], v[156:159], v[172:175], v[60:63]
	v_mfma_f32_16x16x32_bf16 v[56:59], v[164:167], v[172:175], v[56:59]
	v_mfma_f32_16x16x32_bf16 v[48:51], v[156:159], v[180:183], v[48:51]
	v_mfma_f32_16x16x32_bf16 v[40:43], v[164:167], v[180:183], v[40:43]
	v_mfma_f32_16x16x32_bf16 v[32:35], v[156:159], v[188:191], v[32:35]
	v_mfma_f32_16x16x32_bf16 v[24:27], v[164:167], v[188:191], v[24:27]
	v_mfma_f32_16x16x32_bf16 v[16:19], v[156:159], v[196:199], v[16:19]
	v_mfma_f32_16x16x32_bf16 v[8:11], v[164:167], v[196:199], v[8:11]
	s_barrier
	s_setprio 0
	s_add_u32 s54, s24, 0x40000
	s_addc_u32 s55, s25, 0
	s_add_i32 s56, s46, s30
	s_mov_b32 m0, s56
	s_nop 0
	global_load_lds_dwordx4 v130, s[54:55]
	s_add_i32 m0, s56, 0x2000
	s_nop 0
	global_load_lds_dwordx4 v134, s[54:55]
	s_add_u32 s26, s26, 0x40000
	s_addc_u32 s27, s27, 0
	s_mov_b32 m0, s33
	s_nop 0
	global_load_lds_dwordx4 v128, s[26:27]
	s_mov_b32 m0, s34
	s_nop 0
	global_load_lds_dwordx4 v132, s[26:27]
	s_waitcnt vmcnt(10)
	s_setprio 1
	s_barrier
	v_mfma_f32_16x16x32_bf16 v[52:55], v[202:205], v[168:171], v[52:55]
	v_mfma_f32_16x16x32_bf16 v[44:47], v[210:213], v[168:171], v[44:47]
	v_mfma_f32_16x16x32_bf16 v[36:39], v[202:205], v[176:179], v[36:39]
	v_mfma_f32_16x16x32_bf16 v[28:31], v[210:213], v[176:179], v[28:31]
	v_mfma_f32_16x16x32_bf16 v[20:23], v[202:205], v[184:187], v[20:23]
	v_mfma_f32_16x16x32_bf16 v[12:15], v[210:213], v[184:187], v[12:15]
	v_mfma_f32_16x16x32_bf16 v[4:7], v[202:205], v[192:195], v[4:7]
	v_mfma_f32_16x16x32_bf16 v[0:3], v[210:213], v[192:195], v[0:3]
	v_mfma_f32_16x16x32_bf16 v[52:55], v[206:209], v[172:175], v[52:55]
	v_mfma_f32_16x16x32_bf16 v[44:47], v[214:217], v[172:175], v[44:47]
	v_mfma_f32_16x16x32_bf16 v[36:39], v[206:209], v[180:183], v[36:39]
	v_mfma_f32_16x16x32_bf16 v[28:31], v[214:217], v[180:183], v[28:31]
	v_mfma_f32_16x16x32_bf16 v[20:23], v[206:209], v[188:191], v[20:23]
	v_mfma_f32_16x16x32_bf16 v[12:15], v[214:217], v[188:191], v[12:15]
	v_mfma_f32_16x16x32_bf16 v[4:7], v[206:209], v[196:199], v[4:7]
	v_mfma_f32_16x16x32_bf16 v[0:3], v[214:217], v[196:199], v[0:3]
	s_barrier
	s_setprio 0
	s_add_i32 s54, 0, 0x18000
	ds_read_b128 v[152:155], v151 offset:16384
	ds_read_b128 v[156:159], v151 offset:17408
	ds_read_b128 v[160:163], v151 offset:18432
	ds_read_b128 v[164:167], v151 offset:19456
	ds_read_b128 v[168:171], v150 offset:32768
	ds_read_b128 v[172:175], v150 offset:33792
	ds_read_b128 v[176:179], v150 offset:34816
	ds_read_b128 v[180:183], v150 offset:35840
	ds_read_b128 v[184:187], v150 offset:36864
	ds_read_b128 v[188:191], v150 offset:37888
	ds_read_b128 v[192:195], v150 offset:38912
	ds_read_b128 v[196:199], v150 offset:39936
	s_waitcnt lgkmcnt(8)
	s_waitcnt vmcnt(8)
	s_setprio 1
	s_barrier
; #define PG8_STAGE(bufoff, gbase, voff) do { _Pragma("unroll") for (int _i = 0; _i < 2; ++_i) \
;         __builtin_amdgcn_global_load_lds((const unsigned*)((const char*)(gbase) + (voff)[_i]), (LAS unsigned*)(lds + (bufoff) + ldsw + _i * 8192), 16, 0, 0); } while (0)
; #define PG8_LDA(dst, b, h) do { _Pragma("unroll") for (int m = 0; m < 4; ++m) _Pragma("unroll") for (int k = 0; k < 2; ++k) dst[m][k] = *(const LAS bf16x8*)(lds + PG8_SA(b, h) + aoff + m * 2048 + k * 1024); } while (0)
; #define PG8_LDB(dst, b, h) do { _Pragma("unroll") for (int n = 0; n < 2; ++n) _Pragma("unroll") for (int k = 0; k < 2; ++k) dst[n][k] = *(const LAS bf16x8*)(lds + PG8_SB(b, h) + boff + n * 2048 + k * 1024); } while (0)
; #define PG8_MMA(ai, bj, At, Bt) do { __builtin_amdgcn_s_setprio(1); _Pragma("unroll") for (int m = 0; m < 4; ++m) _Pragma("unroll") for (int n = 0; n < 2; ++n) _Pragma("unroll") for (int k = 0; k < 2; ++k) \
;         acc[ai][bj][m][n] = __builtin_amdgcn_mfma_f32_16x16x32_bf16(Bt[n][k], At[m][k], acc[ai][bj][m][n], 0, 0, 0); __builtin_amdgcn_s_setprio(0); } while (0)
; #define PG8_WAIT_V(n) asm volatile("s_waitcnt vmcnt(" #n ")" ::: "memory")
; #define PG8_WAIT_L(n) asm volatile("s_waitcnt lgkmcnt(" #n ")" ::: "memory")
; #define PG8_BAR __builtin_amdgcn_s_barrier()
; #define PG8_SCHED __builtin_amdgcn_sched_barrier(0)
; template <class Epi, class Sched>
; __device__ __forceinline__ void gemm_phase(LAS unsigned char* lds, const Gemm g, const Sched& S, const Epi& E) {
;     ...
;             PG8_WAIT_L(8); PG8_BAR; PG8_WAIT_L(0); PG8_MMA(0, 0, At, B0); PG8_BAR; PG8_SCHED;
;             PG8_LDB(B1, 1, 1); PG8_STAGE(PG8_SB(1, 0), b3, voffB);
;             PG8_BAR; PG8_WAIT_L(0); PG8_MMA(0, 1, At, B1); PG8_BAR;
;             PG8_LDA(At, 1, 1); PG8_STAGE(PG8_SA(1, 0), a3, voffA);
;             PG8_BAR; PG8_WAIT_L(0); PG8_MMA(1, 0, At, B0); PG8_BAR; PG8_SCHED;
;             PG8_STAGE(PG8_SB(1, 1), b3 + hstep, voffB);
;             PG8_WAIT_V(6); PG8_BAR; PG8_MMA(1, 1, At, B1); PG8_BAR;
	s_waitcnt lgkmcnt(0)
	v_mfma_f32_16x16x32_bf16 v[124:127], v[152:155], v[168:171], v[124:127]
	v_mfma_f32_16x16x32_bf16 v[120:123], v[160:163], v[168:171], v[120:123]
	v_mfma_f32_16x16x32_bf16 v[112:115], v[152:155], v[176:179], v[112:115]
	v_mfma_f32_16x16x32_bf16 v[104:107], v[160:163], v[176:179], v[104:107]
	v_mfma_f32_16x16x32_bf16 v[96:99], v[152:155], v[184:187], v[96:99]
	v_mfma_f32_16x16x32_bf16 v[88:91], v[160:163], v[184:187], v[88:91]
	v_mfma_f32_16x16x32_bf16 v[80:83], v[152:155], v[192:195], v[80:83]
	v_mfma_f32_16x16x32_bf16 v[72:75], v[160:163], v[192:195], v[72:75]
	v_mfma_f32_16x16x32_bf16 v[124:127], v[156:159], v[172:175], v[124:127]
	v_mfma_f32_16x16x32_bf16 v[120:123], v[164:167], v[172:175], v[120:123]
	v_mfma_f32_16x16x32_bf16 v[112:115], v[156:159], v[180:183], v[112:115]
	v_mfma_f32_16x16x32_bf16 v[104:107], v[164:167], v[180:183], v[104:107]
	v_mfma_f32_16x16x32_bf16 v[96:99], v[156:159], v[188:191], v[96:99]
	v_mfma_f32_16x16x32_bf16 v[88:91], v[164:167], v[188:191], v[88:91]
	v_mfma_f32_16x16x32_bf16 v[80:83], v[156:159], v[196:199], v[80:83]
	v_mfma_f32_16x16x32_bf16 v[72:75], v[164:167], v[196:199], v[72:75]
	s_barrier
	s_setprio 0
	s_add_i32 s26, 0, 0x1c000
	s_add_i32 s27, s54, s30
	v_add_u32_e32 v136, s26, v148
	s_add_u32 s0, s24, 0x80
	s_addc_u32 s1, s25, 0
	s_mov_b32 m0, s27
	ds_read_b128 v[202:205], v136
	ds_read_b128 v[206:209], v136 offset:1024
	ds_read_b128 v[210:213], v136 offset:2048
	ds_read_b128 v[214:217], v136 offset:3072
	global_load_lds_dwordx4 v130, s[0:1]
	s_add_i32 m0, s27, 0x2000
	s_nop 0
	global_load_lds_dwordx4 v134, s[0:1]
	s_waitcnt vmcnt(8)
	s_setprio 1
	s_barrier
	s_waitcnt lgkmcnt(0)
	v_mfma_f32_16x16x32_bf16 v[116:119], v[202:205], v[168:171], v[116:119]
	v_mfma_f32_16x16x32_bf16 v[108:111], v[210:213], v[168:171], v[108:111]
	v_mfma_f32_16x16x32_bf16 v[100:103], v[202:205], v[176:179], v[100:103]
	v_mfma_f32_16x16x32_bf16 v[92:95], v[210:213], v[176:179], v[92:95]
	v_mfma_f32_16x16x32_bf16 v[84:87], v[202:205], v[184:187], v[84:87]
	v_mfma_f32_16x16x32_bf16 v[76:79], v[210:213], v[184:187], v[76:79]
	v_mfma_f32_16x16x32_bf16 v[68:71], v[202:205], v[192:195], v[68:71]
	v_mfma_f32_16x16x32_bf16 v[64:67], v[210:213], v[192:195], v[64:67]
	v_mfma_f32_16x16x32_bf16 v[116:119], v[206:209], v[172:175], v[116:119]
	v_mfma_f32_16x16x32_bf16 v[108:111], v[214:217], v[172:175], v[108:111]
	v_mfma_f32_16x16x32_bf16 v[100:103], v[206:209], v[180:183], v[100:103]
	v_mfma_f32_16x16x32_bf16 v[92:95], v[214:217], v[180:183], v[92:95]
	v_mfma_f32_16x16x32_bf16 v[84:87], v[206:209], v[188:191], v[84:87]
	v_mfma_f32_16x16x32_bf16 v[76:79], v[214:217], v[188:191], v[76:79]
	v_mfma_f32_16x16x32_bf16 v[68:71], v[206:209], v[196:199], v[68:71]
	v_mfma_f32_16x16x32_bf16 v[64:67], v[214:217], v[196:199], v[64:67]
	s_barrier
	s_setprio 0
	s_mov_b32 m0, s42
	s_mov_b64 s[0:1], 0x80
	v_lshl_add_u64 v[218:219], v[222:223], 0, s[0:1]
	ds_read_b128 v[168:171], v150 offset:49152
	ds_read_b128 v[172:175], v150 offset:50176
	ds_read_b128 v[176:179], v150 offset:51200
	ds_read_b128 v[180:183], v150 offset:52224
	ds_read_b128 v[184:187], v150 offset:53248
	ds_read_b128 v[188:191], v150 offset:54272
	ds_read_b128 v[192:195], v150 offset:55296
	ds_read_b128 v[196:199], v150 offset:56320
	global_load_lds_dwordx4 v[218:219], off
	v_lshl_add_u64 v[218:219], v[224:225], 0, s[0:1]
	s_mov_b32 m0, s43
	s_nop 0
	global_load_lds_dwordx4 v[218:219], off
	s_setprio 1
	s_barrier
	s_waitcnt lgkmcnt(0)
	v_mfma_f32_16x16x32_bf16 v[60:63], v[152:155], v[168:171], v[60:63]
	v_mfma_f32_16x16x32_bf16 v[56:59], v[160:163], v[168:171], v[56:59]
	v_mfma_f32_16x16x32_bf16 v[48:51], v[152:155], v[176:179], v[48:51]
	v_mfma_f32_16x16x32_bf16 v[40:43], v[160:163], v[176:179], v[40:43]
	v_mfma_f32_16x16x32_bf16 v[32:35], v[152:155], v[184:187], v[32:35]
	v_mfma_f32_16x16x32_bf16 v[24:27], v[160:163], v[184:187], v[24:27]
	v_mfma_f32_16x16x32_bf16 v[16:19], v[152:155], v[192:195], v[16:19]
	v_mfma_f32_16x16x32_bf16 v[8:11], v[160:163], v[192:195], v[8:11]
	v_mfma_f32_16x16x32_bf16 v[60:63], v[156:159], v[172:175], v[60:63]
	v_mfma_f32_16x16x32_bf16 v[56:59], v[164:167], v[172:175], v[56:59]
	v_mfma_f32_16x16x32_bf16 v[48:51], v[156:159], v[180:183], v[48:51]
	v_mfma_f32_16x16x32_bf16 v[40:43], v[164:167], v[180:183], v[40:43]
	v_mfma_f32_16x16x32_bf16 v[32:35], v[156:159], v[188:191], v[32:35]
	v_mfma_f32_16x16x32_bf16 v[24:27], v[164:167], v[188:191], v[24:27]
	v_mfma_f32_16x16x32_bf16 v[16:19], v[156:159], v[196:199], v[16:19]
	v_mfma_f32_16x16x32_bf16 v[8:11], v[164:167], v[196:199], v[8:11]
	s_barrier
	s_setprio 0
	s_add_u32 s24, s24, 0x40080
	s_addc_u32 s25, s25, 0
	s_add_i32 s26, s26, s30
	s_mov_b32 m0, s26
	s_nop 0
	global_load_lds_dwordx4 v130, s[24:25]
	s_add_i32 m0, s26, 0x2000
	s_nop 0
	global_load_lds_dwordx4 v134, s[24:25]
	s_waitcnt vmcnt(8)
	s_setprio 1
	s_barrier
	v_mfma_f32_16x16x32_bf16 v[52:55], v[202:205], v[168:171], v[52:55]
	v_mfma_f32_16x16x32_bf16 v[44:47], v[210:213], v[168:171], v[44:47]
	v_mfma_f32_16x16x32_bf16 v[36:39], v[202:205], v[176:179], v[36:39]
	v_mfma_f32_16x16x32_bf16 v[28:31], v[210:213], v[176:179], v[28:31]
	v_mfma_f32_16x16x32_bf16 v[20:23], v[202:205], v[184:187], v[20:23]
	v_mfma_f32_16x16x32_bf16 v[12:15], v[210:213], v[184:187], v[12:15]
	v_mfma_f32_16x16x32_bf16 v[4:7], v[202:205], v[192:195], v[4:7]
	v_mfma_f32_16x16x32_bf16 v[0:3], v[210:213], v[192:195], v[0:3]
	v_mfma_f32_16x16x32_bf16 v[52:55], v[206:209], v[172:175], v[52:55]
	v_mfma_f32_16x16x32_bf16 v[44:47], v[214:217], v[172:175], v[44:47]
	v_mfma_f32_16x16x32_bf16 v[36:39], v[206:209], v[180:183], v[36:39]
	v_mfma_f32_16x16x32_bf16 v[28:31], v[214:217], v[180:183], v[28:31]
	v_mfma_f32_16x16x32_bf16 v[20:23], v[206:209], v[188:191], v[20:23]
	v_mfma_f32_16x16x32_bf16 v[12:15], v[214:217], v[188:191], v[12:15]
	v_mfma_f32_16x16x32_bf16 v[4:7], v[206:209], v[196:199], v[4:7]
	v_mfma_f32_16x16x32_bf16 v[0:3], v[214:217], v[196:199], v[0:3]
	s_barrier
; __device__ __forceinline__ unsigned cvt_pk_bf16(float lo, float hi) { unsigned r; asm volatile("v_cvt_pk_bf16_f32 %0, %1, %2" : "=v"(r) : "v"(lo), "v"(hi)); return r; }
; #define PG8_MMA(ai, bj, At, Bt) do { __builtin_amdgcn_s_setprio(1); _Pragma("unroll") for (int m = 0; m < 4; ++m) _Pragma("unroll") for (int n = 0; n < 2; ++n) _Pragma("unroll") for (int k = 0; k < 2; ++k) \
;         acc[ai][bj][m][n] = __builtin_amdgcn_mfma_f32_16x16x32_bf16(Bt[n][k], At[m][k], acc[ai][bj][m][n], 0, 0, 0); __builtin_amdgcn_s_setprio(0); } while (0)
; #define PG8_WAIT_V(n) asm volatile("s_waitcnt vmcnt(" #n ")" ::: "memory")
; #define PG8_BAR __builtin_amdgcn_s_barrier()
; template <class Epi, class Sched>
; __device__ __forceinline__ void gemm_phase(LAS unsigned char* lds, const Gemm g, const Sched& S, const Epi& E) {
;     ...
;             PG8_WAIT_V(6); PG8_BAR; PG8_MMA(1, 1, At, B1); PG8_BAR;
;         }
;     __device__ __forceinline__ void operator()(const AccT& acc, const Unit& u, int wr, int wc, int fr, int fq) const {
;     ...
;         const int rbase = u.pm * 256 + wr * 64 + fr;
;         const int tb = u.pn * 256 + wc * 32 + 8 * fq;
; #pragma unroll
;         for (int ai = 0; ai < 2; ++ai)
; #pragma unroll
;             for (int m = 0; m < 4; ++m) {
;                 const int gm = rbase + ai * 128 + m * 16;
; #pragma unroll
;                 for (int bj = 0; bj < 2; ++bj) {
;                     const int t0 = tb + bj * 128;
;                     const f32x4 v0 = acc[ai][bj][m][0], v1 = acc[ai][bj][m][1];
;                     u32x4 w; w.x = cvt_pk_bf16(v0[0], v0[1]); w.y = cvt_pk_bf16(v0[2], v0[3]); w.z = cvt_pk_bf16(v1[0], v1[1]); w.w = cvt_pk_bf16(v1[2], v1[3]);
;                     *(u32x4*)(YT + ((size_t)((t0 >> 10) * 512 + gm)) * 2048 + part * 1024 + (t0 & 1023)) = w;
;                 }
	s_setprio 0
	s_add_i32 s53, s53, 2
	s_add_u32 s22, s22, 0x100
	s_addc_u32 s23, s23, 0
	s_add_u32 s51, s51, 0x100
	s_addc_u32 s52, s52, 0
	s_cmp_gt_u32 s53, 13
	s_cbranch_scc0 .LBB0_653
	v_mov_b32_e32 v136, v147
	v_mov_b32_e32 v152, v146
	s_lshl_b32 s7, s20, 8
	s_add_i32 s7, s7, s36
	v_add_u32_e32 v152, s7, v152
	s_lshl_b32 s7, s47, 8
	s_or_b32 s7, s7, s37
	v_lshl_add_u32 v153, v136, 3, s7
	v_cvt_pk_bf16_f32 v124, v124, v125
	v_cvt_pk_bf16_f32 v125, v126, v127
	v_cvt_pk_bf16_f32 v126, v120, v121
	v_ashrrev_i32_e32 v120, 1, v153
	v_cvt_pk_bf16_f32 v127, v122, v123
	v_and_b32_e32 v122, 0xfffffe00, v120
	v_add_u32_e32 v120, v122, v152
	v_ashrrev_i32_e32 v121, 31, v120
	v_lshlrev_b64 v[120:121], 12, v[120:121]
	v_and_b32_e32 v123, 0x3f8, v153
	v_lshl_add_u64 v[120:121], s[68:69], 0, v[120:121]
	v_lshlrev_b32_e32 v136, 1, v123
	v_lshl_add_u64 v[120:121], v[120:121], 0, v[136:137]
	global_store_dwordx4 v[120:121], v[124:127], off
	v_add_u32_e32 v120, 0x80, v153
	v_cvt_pk_bf16_f32 v116, v116, v117
	v_cvt_pk_bf16_f32 v117, v118, v119
	v_cvt_pk_bf16_f32 v118, v108, v109
	v_ashrrev_i32_e32 v108, 1, v120
	v_and_b32_e32 v121, 0xfffffe00, v108
	v_add_u32_e32 v108, v121, v152
	v_ashrrev_i32_e32 v109, 31, v108
	v_lshlrev_b64 v[108:109], 12, v[108:109]
	v_cvt_pk_bf16_f32 v119, v110, v111
	v_lshl_add_u64 v[110:111], s[68:69], 0, v[108:109]
	v_and_b32_e32 v108, 0x3f8, v120
	v_lshlrev_b32_e32 v108, 1, v108
	v_mov_b32_e32 v109, v137
	v_lshl_add_u64 v[110:111], v[110:111], 0, v[108:109]
	global_store_dwordx4 v[110:111], v[116:119], off
	v_cvt_pk_bf16_f32 v110, v112, v113
	v_cvt_pk_bf16_f32 v111, v114, v115
	v_cvt_pk_bf16_f32 v112, v104, v105
	v_cvt_pk_bf16_f32 v113, v106, v107
	s_and_b64 vcc, exec, s[4:5]
	s_nop 0
	v_add_u32_e32 v116, 16, v152
	v_add_u32_e32 v104, v122, v116
	v_ashrrev_i32_e32 v105, 31, v104
	v_lshlrev_b64 v[104:105], 12, v[104:105]
	v_lshl_add_u64 v[104:105], s[68:69], 0, v[104:105]
	v_lshl_add_u64 v[104:105], v[104:105], 0, v[136:137]
	global_store_dwordx4 v[104:105], v[110:113], off
	v_cvt_pk_bf16_f32 v100, v100, v101
	v_cvt_pk_bf16_f32 v101, v102, v103
	v_cvt_pk_bf16_f32 v102, v92, v93
	v_add_u32_e32 v92, v121, v116
	v_ashrrev_i32_e32 v93, 31, v92
	v_lshlrev_b64 v[92:93], 12, v[92:93]
	v_lshl_add_u64 v[92:93], s[68:69], 0, v[92:93]
	v_lshl_add_u64 v[92:93], v[92:93], 0, v[108:109]
	v_cvt_pk_bf16_f32 v103, v94, v95
	global_store_dwordx4 v[92:93], v[100:103], off
	v_cvt_pk_bf16_f32 v92, v96, v97
	v_cvt_pk_bf16_f32 v93, v98, v99
	v_cvt_pk_bf16_f32 v94, v88, v89
	v_cvt_pk_bf16_f32 v95, v90, v91
	s_mov_b32 s47, s6
	s_nop 0
	v_add_u32_e32 v100, 32, v152
	v_add_u32_e32 v88, v122, v100
	v_ashrrev_i32_e32 v89, 31, v88
	v_lshlrev_b64 v[88:89], 12, v[88:89]
	v_lshl_add_u64 v[88:89], s[68:69], 0, v[88:89]
	v_lshl_add_u64 v[88:89], v[88:89], 0, v[136:137]
	global_store_dwordx4 v[88:89], v[92:95], off
	v_cvt_pk_bf16_f32 v84, v84, v85
	v_cvt_pk_bf16_f32 v85, v86, v87
	v_cvt_pk_bf16_f32 v86, v76, v77
	v_add_u32_e32 v76, v121, v100
	v_ashrrev_i32_e32 v77, 31, v76
	v_lshlrev_b64 v[76:77], 12, v[76:77]
	v_lshl_add_u64 v[76:77], s[68:69], 0, v[76:77]
	v_lshl_add_u64 v[76:77], v[76:77], 0, v[108:109]
	v_cvt_pk_bf16_f32 v87, v78, v79
	global_store_dwordx4 v[76:77], v[84:87], off
	v_cvt_pk_bf16_f32 v76, v80, v81
	v_cvt_pk_bf16_f32 v77, v82, v83
	v_cvt_pk_bf16_f32 v78, v72, v73
	v_cvt_pk_bf16_f32 v79, v74, v75
	s_mov_b32 s20, s8
	s_nop 0
	v_add_u32_e32 v84, 48, v152
	v_add_u32_e32 v72, v122, v84
	v_ashrrev_i32_e32 v73, 31, v72
	v_lshlrev_b64 v[72:73], 12, v[72:73]
	v_lshl_add_u64 v[72:73], s[68:69], 0, v[72:73]
	v_lshl_add_u64 v[72:73], v[72:73], 0, v[136:137]
	global_store_dwordx4 v[72:73], v[76:79], off
; __device__ __forceinline__ unsigned cvt_pk_bf16(float lo, float hi) { unsigned r; asm volatile("v_cvt_pk_bf16_f32 %0, %1, %2" : "=v"(r) : "v"(lo), "v"(hi)); return r; }
; #define PG8_WAIT_V(n) asm volatile("s_waitcnt vmcnt(" #n ")" ::: "memory")
; #define PG8_BAR __builtin_amdgcn_s_barrier()
; template <class Epi, class Sched>
; __device__ __forceinline__ void gemm_phase(LAS unsigned char* lds, const Gemm g, const Sched& S, const Epi& E) {
;     ...
;         if (!has_next) break;
; #pragma unroll
;         for (int a = 0; a < 2; ++a)
; #pragma unroll
;             for (int b = 0; b < 2; ++b)
; #pragma unroll
;                 for (int m = 0; m < 4; ++m)
; #pragma unroll
;                     for (int n = 0; n < 2; ++n) acc[a][b][m][n] = (f32x4){0.f, 0.f, 0.f, 0.f};
;         cur = nxt; cA = nA; cB = nB; ++ui;
;     }
;     PG8_WAIT_V(0);
;     if (wr == 0) PG8_BAR;
;     __device__ __forceinline__ void operator()(const AccT& acc, const Unit& u, int wr, int wc, int fr, int fq) const {
;     ...
;                 const int gm = rbase + ai * 128 + m * 16;
; #pragma unroll
;                 for (int bj = 0; bj < 2; ++bj) {
;                     const int t0 = tb + bj * 128;
;                     const f32x4 v0 = acc[ai][bj][m][0], v1 = acc[ai][bj][m][1];
;                     u32x4 w; w.x = cvt_pk_bf16(v0[0], v0[1]); w.y = cvt_pk_bf16(v0[2], v0[3]); w.z = cvt_pk_bf16(v1[0], v1[1]); w.w = cvt_pk_bf16(v1[2], v1[3]);
;                     *(u32x4*)(YT + ((size_t)((t0 >> 10) * 512 + gm)) * 2048 + part * 1024 + (t0 & 1023)) = w;
;                 }
	v_cvt_pk_bf16_f32 v68, v68, v69
	v_cvt_pk_bf16_f32 v69, v70, v71
	v_cvt_pk_bf16_f32 v70, v64, v65
	v_add_u32_e32 v64, v121, v84
	v_ashrrev_i32_e32 v65, 31, v64
	v_lshlrev_b64 v[64:65], 12, v[64:65]
	v_lshl_add_u64 v[64:65], s[68:69], 0, v[64:65]
	v_lshl_add_u64 v[64:65], v[64:65], 0, v[108:109]
	v_cvt_pk_bf16_f32 v71, v66, v67
	global_store_dwordx4 v[64:65], v[68:71], off
	v_add_u32_e32 v64, 0x80, v152
	v_cvt_pk_bf16_f32 v60, v60, v61
	v_cvt_pk_bf16_f32 v61, v62, v63
	v_cvt_pk_bf16_f32 v62, v56, v57
	v_add_u32_e32 v56, v122, v64
	v_ashrrev_i32_e32 v57, 31, v56
	v_lshlrev_b64 v[56:57], 12, v[56:57]
	v_lshl_add_u64 v[56:57], s[68:69], 0, v[56:57]
	v_lshl_add_u64 v[56:57], v[56:57], 0, v[136:137]
	v_cvt_pk_bf16_f32 v63, v58, v59
	global_store_dwordx4 v[56:57], v[60:63], off
	v_cvt_pk_bf16_f32 v52, v52, v53
	v_cvt_pk_bf16_f32 v53, v54, v55
	v_cvt_pk_bf16_f32 v54, v44, v45
	v_add_u32_e32 v44, v121, v64
	v_ashrrev_i32_e32 v45, 31, v44
	v_lshlrev_b64 v[44:45], 12, v[44:45]
	v_lshl_add_u64 v[44:45], s[68:69], 0, v[44:45]
	v_lshl_add_u64 v[44:45], v[44:45], 0, v[108:109]
	v_cvt_pk_bf16_f32 v55, v46, v47
	global_store_dwordx4 v[44:45], v[52:55], off
	v_cvt_pk_bf16_f32 v44, v48, v49
	v_cvt_pk_bf16_f32 v45, v50, v51
	v_cvt_pk_bf16_f32 v46, v40, v41
	v_cvt_pk_bf16_f32 v47, v42, v43
	s_mov_b64 s[24:25], s[18:19]
	s_nop 0
	v_add_u32_e32 v52, 0x90, v152
	v_add_u32_e32 v40, v122, v52
	v_ashrrev_i32_e32 v41, 31, v40
	v_lshlrev_b64 v[40:41], 12, v[40:41]
	v_lshl_add_u64 v[40:41], s[68:69], 0, v[40:41]
	v_lshl_add_u64 v[40:41], v[40:41], 0, v[136:137]
	global_store_dwordx4 v[40:41], v[44:47], off
	v_cvt_pk_bf16_f32 v36, v36, v37
	v_cvt_pk_bf16_f32 v37, v38, v39
	v_cvt_pk_bf16_f32 v38, v28, v29
	v_add_u32_e32 v28, v121, v52
	v_ashrrev_i32_e32 v29, 31, v28
	v_lshlrev_b64 v[28:29], 12, v[28:29]
	v_lshl_add_u64 v[28:29], s[68:69], 0, v[28:29]
	v_lshl_add_u64 v[28:29], v[28:29], 0, v[108:109]
	v_cvt_pk_bf16_f32 v39, v30, v31
	global_store_dwordx4 v[28:29], v[36:39], off
	v_cvt_pk_bf16_f32 v28, v32, v33
	v_cvt_pk_bf16_f32 v29, v34, v35
	v_cvt_pk_bf16_f32 v30, v24, v25
	v_cvt_pk_bf16_f32 v31, v26, v27
	s_mov_b64 s[22:23], s[16:17]
	s_nop 0
	v_add_u32_e32 v36, 0xa0, v152
	v_add_u32_e32 v24, v122, v36
	v_ashrrev_i32_e32 v25, 31, v24
	v_lshlrev_b64 v[24:25], 12, v[24:25]
	v_lshl_add_u64 v[24:25], s[68:69], 0, v[24:25]
	v_lshl_add_u64 v[24:25], v[24:25], 0, v[136:137]
	global_store_dwordx4 v[24:25], v[28:31], off
	v_cvt_pk_bf16_f32 v20, v20, v21
	v_cvt_pk_bf16_f32 v21, v22, v23
	v_cvt_pk_bf16_f32 v22, v12, v13
	v_add_u32_e32 v12, v121, v36
	v_ashrrev_i32_e32 v13, 31, v12
	v_lshlrev_b64 v[12:13], 12, v[12:13]
	v_lshl_add_u64 v[12:13], s[68:69], 0, v[12:13]
	v_lshl_add_u64 v[12:13], v[12:13], 0, v[108:109]
	v_cvt_pk_bf16_f32 v23, v14, v15
	global_store_dwordx4 v[12:13], v[20:23], off
	v_cvt_pk_bf16_f32 v12, v16, v17
	v_cvt_pk_bf16_f32 v13, v18, v19
	v_cvt_pk_bf16_f32 v14, v8, v9
	v_cvt_pk_bf16_f32 v15, v10, v11
	s_nop 1
	v_add_u32_e32 v20, 0xb0, v152
	v_add_u32_e32 v8, v122, v20
	v_ashrrev_i32_e32 v9, 31, v8
	v_lshlrev_b64 v[8:9], 12, v[8:9]
	v_lshl_add_u64 v[8:9], s[68:69], 0, v[8:9]
	v_lshl_add_u64 v[8:9], v[8:9], 0, v[136:137]
	global_store_dwordx4 v[8:9], v[12:15], off
	v_cvt_pk_bf16_f32 v4, v4, v5
	v_cvt_pk_bf16_f32 v5, v6, v7
	v_cvt_pk_bf16_f32 v6, v0, v1
	v_add_u32_e32 v0, v121, v20
	v_ashrrev_i32_e32 v1, 31, v0
	v_lshlrev_b64 v[0:1], 12, v[0:1]
	v_lshl_add_u64 v[0:1], s[68:69], 0, v[0:1]
	v_lshl_add_u64 v[0:1], v[0:1], 0, v[108:109]
	v_cvt_pk_bf16_f32 v7, v2, v3
	global_store_dwordx4 v[0:1], v[4:7], off
	s_cbranch_vccz .LBB0_646
	s_waitcnt vmcnt(0)
	s_cmpk_gt_u32 s28, 0xff
	s_cbranch_scc1 .LBB0_657
	s_barrier

; #define PG8_STAGE(bufoff, gbase, voff) do { _Pragma("unroll") for (int _i = 0; _i < 2; ++_i) \
;         __builtin_amdgcn_global_load_lds((const unsigned*)((const char*)(gbase) + (voff)[_i]), (LAS unsigned*)(lds + (bufoff) + ldsw + _i * 8192), 16, 0, 0); } while (0)
; #define PG8_LDA(dst, b, h) do { _Pragma("unroll") for (int m = 0; m < 4; ++m) _Pragma("unroll") for (int k = 0; k < 2; ++k) dst[m][k] = *(const LAS bf16x8*)(lds + PG8_SA(b, h) + aoff + m * 2048 + k * 1024); } while (0)
; #define PG8_LDB(dst, b, h) do { _Pragma("unroll") for (int n = 0; n < 2; ++n) _Pragma("unroll") for (int k = 0; k < 2; ++k) dst[n][k] = *(const LAS bf16x8*)(lds + PG8_SB(b, h) + boff + n * 2048 + k * 1024); } while (0)
; #define PG8_WAIT_V(n) asm volatile("s_waitcnt vmcnt(" #n ")" ::: "memory")
; #define PG8_BAR __builtin_amdgcn_s_barrier()
; template <class Epi, class Sched>
; __device__ __forceinline__ void gemm_phase(LAS unsigned char* lds, const Gemm g, const Sched& S, const Epi& E) {
;     ...
;         const bool has_next = S.next(ui + 1, nxt);
;         const char* nA = has_next ? (const char*)g.A + (size_t)nxt.pm * tstep : cA; const char* nB = has_next ? (const char*)g.Bt + (size_t)nxt.pn * tstep : cB;
;         for (int t = 0; t < nt; t += 2) {
;             const bool last = (t == nt - 2);
;             const char* a1 = cA + (size_t)(t + 1) * kstep;
;             const char* a2 = last ? nA : cA + (size_t)(t + 2) * kstep; const char* b2 = last ? nB : cB + (size_t)(t + 2) * kstep;
;             const char* a3 = a2 + kstep; const char* b3 = b2 + kstep;
;             PG8_LDB(B0, 0, 0); PG8_SCHED; PG8_LDA(At, 0, 0); PG8_STAGE(PG8_SA(1, 1), a1 + hstep, voffA);
;             PG8_WAIT_L(8); PG8_BAR; PG8_WAIT_L(0); PG8_MMA(0, 0, At, B0); PG8_BAR; PG8_SCHED;
;             PG8_LDB(B1, 0, 1); PG8_STAGE(PG8_SB(0, 0), b2, voffB);
;             PG8_BAR; PG8_WAIT_L(0); PG8_MMA(0, 1, At, B1); PG8_BAR;
;             PG8_LDA(At, 0, 1); PG8_STAGE(PG8_SA(0, 0), a2, voffA);
;             PG8_BAR; PG8_WAIT_L(0); PG8_MMA(1, 0, At, B0); PG8_BAR; PG8_SCHED;
;             PG8_STAGE(PG8_SB(0, 1), b2 + hstep, voffB);
;             PG8_WAIT_V(6); PG8_BAR; PG8_MMA(1, 1, At, B1); PG8_BAR;
;             PG8_LDB(B0, 1, 0); PG8_SCHED; PG8_LDA(At, 1, 0); PG8_STAGE(PG8_SA(0, 1), a2 + hstep, voffA);
;             PG8_WAIT_L(8); PG8_BAR; PG8_WAIT_L(0); PG8_MMA(0, 0, At, B0); PG8_BAR; PG8_SCHED;
.LBB0_672:
	s_ashr_i32 s9, s8, 31
	v_cmp_lt_i64_e32 vcc, s[12:13], v[142:143]
	s_lshl_b64 s[12:13], s[8:9], 19
	s_add_u32 s12, s26, s12
	s_addc_u32 s13, s27, s13
	s_and_b64 s[14:15], vcc, exec
	s_cselect_b32 s9, s13, s19
	s_cselect_b32 s46, s12, s18
	s_ashr_i32 s7, s6, 31
	s_lshl_b64 s[14:15], s[6:7], 19
	s_add_u32 s14, s10, s14
	s_addc_u32 s15, s11, s15
	s_and_b64 s[22:23], vcc, exec
	s_cselect_b32 s7, s15, s21
	s_cselect_b32 s47, s14, s20
	s_add_u32 s18, s18, 0x40080
	s_addc_u32 s19, s19, 0
	s_add_u32 s48, s20, 0x100
	s_addc_u32 s49, s21, 0
	s_mov_b32 s51, -2
	s_waitcnt lgkmcnt(0)
	ds_read_b128 v[152:155], v149
	ds_read_b128 v[156:159], v149 offset:1024
	ds_read_b128 v[160:163], v149 offset:2048
	ds_read_b128 v[164:167], v149 offset:3072
	s_add_u32 s20, s18, 0xfffc0080
	s_addc_u32 s21, s19, -1
	s_cmp_eq_u32 s51, 12
	s_cselect_b32 s23, s9, s21
	s_cselect_b32 s22, s46, s20
	s_cselect_b32 s21, s7, s49
	s_cselect_b32 s20, s47, s48
	s_add_i32 m0, s17, 0xc000
	ds_read_b128 v[168:171], v150
	ds_read_b128 v[172:175], v150 offset:1024
	ds_read_b128 v[176:179], v150 offset:2048
	ds_read_b128 v[180:183], v150 offset:3072
	ds_read_b128 v[184:187], v150 offset:4096
	ds_read_b128 v[188:191], v150 offset:5120
	ds_read_b128 v[192:195], v150 offset:6144
	ds_read_b128 v[196:199], v150 offset:7168
	global_load_lds_dwordx4 v138, s[18:19]
	s_add_i32 m0, s17, 0xe000
	s_nop 0
	global_load_lds_dwordx4 v140, s[18:19]
	s_waitcnt lgkmcnt(8)
	s_waitcnt vmcnt(8)
	s_setprio 1
	s_barrier
	s_waitcnt lgkmcnt(0)
	v_mfma_f32_16x16x32_bf16 v[124:127], v[152:155], v[168:171], 0
	v_mfma_f32_16x16x32_bf16 v[120:123], v[160:163], v[168:171], 0
	v_mfma_f32_16x16x32_bf16 v[112:115], v[152:155], v[176:179], 0
	v_mfma_f32_16x16x32_bf16 v[104:107], v[160:163], v[176:179], 0
	v_mfma_f32_16x16x32_bf16 v[96:99], v[152:155], v[184:187], 0
	v_mfma_f32_16x16x32_bf16 v[88:91], v[160:163], v[184:187], 0
	v_mfma_f32_16x16x32_bf16 v[80:83], v[152:155], v[192:195], 0
	v_mfma_f32_16x16x32_bf16 v[72:75], v[160:163], v[192:195], 0
	v_mfma_f32_16x16x32_bf16 v[124:127], v[156:159], v[172:175], v[124:127]
	v_mfma_f32_16x16x32_bf16 v[120:123], v[164:167], v[172:175], v[120:123]
	v_mfma_f32_16x16x32_bf16 v[112:115], v[156:159], v[180:183], v[112:115]
	v_mfma_f32_16x16x32_bf16 v[104:107], v[164:167], v[180:183], v[104:107]
	v_mfma_f32_16x16x32_bf16 v[96:99], v[156:159], v[188:191], v[96:99]
	v_mfma_f32_16x16x32_bf16 v[88:91], v[164:167], v[188:191], v[88:91]
	v_mfma_f32_16x16x32_bf16 v[80:83], v[156:159], v[196:199], v[80:83]
	v_mfma_f32_16x16x32_bf16 v[72:75], v[164:167], v[196:199], v[72:75]
	s_barrier
	s_setprio 0
	s_add_i32 s52, s43, s28
	s_mov_b32 m0, s52
	ds_read_b128 v[202:205], v151
	ds_read_b128 v[206:209], v151 offset:1024
	ds_read_b128 v[210:213], v151 offset:2048
	ds_read_b128 v[214:217], v151 offset:3072
	global_load_lds_dwordx4 v130, s[20:21]
	s_add_i32 m0, s52, 0x2000
	s_nop 0
	global_load_lds_dwordx4 v134, s[20:21]
	s_waitcnt vmcnt(8)
	s_setprio 1
	s_barrier
	s_waitcnt lgkmcnt(0)
	v_mfma_f32_16x16x32_bf16 v[116:119], v[202:205], v[168:171], 0
	v_mfma_f32_16x16x32_bf16 v[108:111], v[210:213], v[168:171], 0
	v_mfma_f32_16x16x32_bf16 v[100:103], v[202:205], v[176:179], 0
	v_mfma_f32_16x16x32_bf16 v[92:95], v[210:213], v[176:179], 0
	v_mfma_f32_16x16x32_bf16 v[84:87], v[202:205], v[184:187], 0
	v_mfma_f32_16x16x32_bf16 v[76:79], v[210:213], v[184:187], 0
	v_mfma_f32_16x16x32_bf16 v[68:71], v[202:205], v[192:195], 0
	v_mfma_f32_16x16x32_bf16 v[64:67], v[210:213], v[192:195], 0
	v_mfma_f32_16x16x32_bf16 v[116:119], v[206:209], v[172:175], v[116:119]
	v_mfma_f32_16x16x32_bf16 v[108:111], v[214:217], v[172:175], v[108:111]
	v_mfma_f32_16x16x32_bf16 v[100:103], v[206:209], v[180:183], v[100:103]
	v_mfma_f32_16x16x32_bf16 v[92:95], v[214:217], v[180:183], v[92:95]
	v_mfma_f32_16x16x32_bf16 v[84:87], v[206:209], v[188:191], v[84:87]
	v_mfma_f32_16x16x32_bf16 v[76:79], v[214:217], v[188:191], v[76:79]
	v_mfma_f32_16x16x32_bf16 v[68:71], v[206:209], v[196:199], v[68:71]
	v_mfma_f32_16x16x32_bf16 v[64:67], v[214:217], v[196:199], v[64:67]
	s_barrier
	s_setprio 0
	s_mov_b32 m0, s17
	v_lshl_add_u64 v[222:223], s[22:23], 0, v[128:129]
	ds_read_b128 v[168:171], v150 offset:16384
	ds_read_b128 v[172:175], v150 offset:17408
	ds_read_b128 v[176:179], v150 offset:18432
	ds_read_b128 v[180:183], v150 offset:19456
	ds_read_b128 v[184:187], v150 offset:20480
	ds_read_b128 v[188:191], v150 offset:21504
	ds_read_b128 v[192:195], v150 offset:22528
	ds_read_b128 v[196:199], v150 offset:23552
	global_load_lds_dwordx4 v128, s[22:23]
	v_lshl_add_u64 v[224:225], s[22:23], 0, v[132:133]
	s_mov_b32 m0, s29
	s_nop 0
	global_load_lds_dwordx4 v132, s[22:23]
	s_setprio 1
	s_barrier
	s_waitcnt lgkmcnt(0)
	v_mfma_f32_16x16x32_bf16 v[60:63], v[152:155], v[168:171], 0
	v_mfma_f32_16x16x32_bf16 v[56:59], v[160:163], v[168:171], 0
	v_mfma_f32_16x16x32_bf16 v[48:51], v[152:155], v[176:179], 0
	v_mfma_f32_16x16x32_bf16 v[40:43], v[160:163], v[176:179], 0
	v_mfma_f32_16x16x32_bf16 v[32:35], v[152:155], v[184:187], 0
	v_mfma_f32_16x16x32_bf16 v[24:27], v[160:163], v[184:187], 0
	v_mfma_f32_16x16x32_bf16 v[16:19], v[152:155], v[192:195], 0
	v_mfma_f32_16x16x32_bf16 v[8:11], v[160:163], v[192:195], 0
	v_mfma_f32_16x16x32_bf16 v[60:63], v[156:159], v[172:175], v[60:63]
	v_mfma_f32_16x16x32_bf16 v[56:59], v[164:167], v[172:175], v[56:59]
	v_mfma_f32_16x16x32_bf16 v[48:51], v[156:159], v[180:183], v[48:51]
	v_mfma_f32_16x16x32_bf16 v[40:43], v[164:167], v[180:183], v[40:43]
	v_mfma_f32_16x16x32_bf16 v[32:35], v[156:159], v[188:191], v[32:35]
	v_mfma_f32_16x16x32_bf16 v[24:27], v[164:167], v[188:191], v[24:27]
	v_mfma_f32_16x16x32_bf16 v[16:19], v[156:159], v[196:199], v[16:19]
	v_mfma_f32_16x16x32_bf16 v[8:11], v[164:167], v[196:199], v[8:11]
	s_barrier
; #define PG8_STAGE(bufoff, gbase, voff) do { _Pragma("unroll") for (int _i = 0; _i < 2; ++_i) \
;         __builtin_amdgcn_global_load_lds((const unsigned*)((const char*)(gbase) + (voff)[_i]), (LAS unsigned*)(lds + (bufoff) + ldsw + _i * 8192), 16, 0, 0); } while (0)
; #define PG8_LDA(dst, b, h) do { _Pragma("unroll") for (int m = 0; m < 4; ++m) _Pragma("unroll") for (int k = 0; k < 2; ++k) dst[m][k] = *(const LAS bf16x8*)(lds + PG8_SA(b, h) + aoff + m * 2048 + k * 1024); } while (0)
; #define PG8_LDB(dst, b, h) do { _Pragma("unroll") for (int n = 0; n < 2; ++n) _Pragma("unroll") for (int k = 0; k < 2; ++k) dst[n][k] = *(const LAS bf16x8*)(lds + PG8_SB(b, h) + boff + n * 2048 + k * 1024); } while (0)
; #define PG8_MMA(ai, bj, At, Bt) do { __builtin_amdgcn_s_setprio(1); _Pragma("unroll") for (int m = 0; m < 4; ++m) _Pragma("unroll") for (int n = 0; n < 2; ++n) _Pragma("unroll") for (int k = 0; k < 2; ++k) \
;         acc[ai][bj][m][n] = __builtin_amdgcn_mfma_f32_16x16x32_bf16(Bt[n][k], At[m][k], acc[ai][bj][m][n], 0, 0, 0); __builtin_amdgcn_s_setprio(0); } while (0)
; #define PG8_WAIT_V(n) asm volatile("s_waitcnt vmcnt(" #n ")" ::: "memory")
; #define PG8_WAIT_L(n) asm volatile("s_waitcnt lgkmcnt(" #n ")" ::: "memory")
; #define PG8_BAR __builtin_amdgcn_s_barrier()
; #define PG8_SCHED __builtin_amdgcn_sched_barrier(0)
; template <class Epi, class Sched>
; __device__ __forceinline__ void gemm_phase(LAS unsigned char* lds, const Gemm g, const Sched& S, const Epi& E) {
;     ...
;             PG8_STAGE(PG8_SB(0, 1), b2 + hstep, voffB);
;             PG8_WAIT_V(6); PG8_BAR; PG8_MMA(1, 1, At, B1); PG8_BAR;
;             PG8_LDB(B0, 1, 0); PG8_SCHED; PG8_LDA(At, 1, 0); PG8_STAGE(PG8_SA(0, 1), a2 + hstep, voffA);
;             PG8_WAIT_L(8); PG8_BAR; PG8_WAIT_L(0); PG8_MMA(0, 0, At, B0); PG8_BAR; PG8_SCHED;
;             PG8_LDB(B1, 1, 1); PG8_STAGE(PG8_SB(1, 0), b3, voffB);
;             PG8_BAR; PG8_WAIT_L(0); PG8_MMA(0, 1, At, B1); PG8_BAR;
;             PG8_LDA(At, 1, 1); PG8_STAGE(PG8_SA(1, 0), a3, voffA);
;             PG8_BAR; PG8_WAIT_L(0); PG8_MMA(1, 0, At, B0); PG8_BAR; PG8_SCHED;
;             PG8_STAGE(PG8_SB(1, 1), b3 + hstep, voffB);
;             PG8_WAIT_V(6); PG8_BAR; PG8_MMA(1, 1, At, B1); PG8_BAR;
	s_setprio 0
	s_add_u32 s52, s20, 0x40000
	s_addc_u32 s53, s21, 0
	s_add_i32 s54, s44, s28
	s_mov_b32 m0, s54
	s_nop 0
	global_load_lds_dwordx4 v130, s[52:53]
	s_add_i32 m0, s54, 0x2000
	s_nop 0
	global_load_lds_dwordx4 v134, s[52:53]
	s_add_u32 s22, s22, 0x40000
	s_addc_u32 s23, s23, 0
	s_mov_b32 m0, s30
	s_nop 0
	global_load_lds_dwordx4 v128, s[22:23]
	s_mov_b32 m0, s31
	s_nop 0
	global_load_lds_dwordx4 v132, s[22:23]
	s_waitcnt vmcnt(10)
	s_setprio 1
	s_barrier
	v_mfma_f32_16x16x32_bf16 v[52:55], v[202:205], v[168:171], 0
	v_mfma_f32_16x16x32_bf16 v[44:47], v[210:213], v[168:171], 0
	v_mfma_f32_16x16x32_bf16 v[36:39], v[202:205], v[176:179], 0
	v_mfma_f32_16x16x32_bf16 v[28:31], v[210:213], v[176:179], 0
	v_mfma_f32_16x16x32_bf16 v[20:23], v[202:205], v[184:187], 0
	v_mfma_f32_16x16x32_bf16 v[12:15], v[210:213], v[184:187], 0
	v_mfma_f32_16x16x32_bf16 v[4:7], v[202:205], v[192:195], 0
	v_mfma_f32_16x16x32_bf16 v[0:3], v[210:213], v[192:195], 0
	v_mfma_f32_16x16x32_bf16 v[52:55], v[206:209], v[172:175], v[52:55]
	v_mfma_f32_16x16x32_bf16 v[44:47], v[214:217], v[172:175], v[44:47]
	v_mfma_f32_16x16x32_bf16 v[36:39], v[206:209], v[180:183], v[36:39]
	v_mfma_f32_16x16x32_bf16 v[28:31], v[214:217], v[180:183], v[28:31]
	v_mfma_f32_16x16x32_bf16 v[20:23], v[206:209], v[188:191], v[20:23]
	v_mfma_f32_16x16x32_bf16 v[12:15], v[214:217], v[188:191], v[12:15]
	v_mfma_f32_16x16x32_bf16 v[4:7], v[206:209], v[196:199], v[4:7]
	v_mfma_f32_16x16x32_bf16 v[0:3], v[214:217], v[196:199], v[0:3]
	s_barrier
	s_setprio 0
	s_add_i32 s52, 0, 0x18000
	ds_read_b128 v[152:155], v151 offset:16384
	ds_read_b128 v[156:159], v151 offset:17408
	ds_read_b128 v[160:163], v151 offset:18432
	ds_read_b128 v[164:167], v151 offset:19456
	ds_read_b128 v[168:171], v150 offset:32768
	ds_read_b128 v[172:175], v150 offset:33792
	ds_read_b128 v[176:179], v150 offset:34816
	ds_read_b128 v[180:183], v150 offset:35840
	ds_read_b128 v[184:187], v150 offset:36864
	ds_read_b128 v[188:191], v150 offset:37888
	ds_read_b128 v[192:195], v150 offset:38912
	ds_read_b128 v[196:199], v150 offset:39936
	s_waitcnt lgkmcnt(8)
	s_waitcnt vmcnt(8)
	s_setprio 1
	s_barrier
	s_waitcnt lgkmcnt(0)
	v_mfma_f32_16x16x32_bf16 v[124:127], v[152:155], v[168:171], v[124:127]
	v_mfma_f32_16x16x32_bf16 v[120:123], v[160:163], v[168:171], v[120:123]
	v_mfma_f32_16x16x32_bf16 v[112:115], v[152:155], v[176:179], v[112:115]
	v_mfma_f32_16x16x32_bf16 v[104:107], v[160:163], v[176:179], v[104:107]
	v_mfma_f32_16x16x32_bf16 v[96:99], v[152:155], v[184:187], v[96:99]
	v_mfma_f32_16x16x32_bf16 v[88:91], v[160:163], v[184:187], v[88:91]
	v_mfma_f32_16x16x32_bf16 v[80:83], v[152:155], v[192:195], v[80:83]
	v_mfma_f32_16x16x32_bf16 v[72:75], v[160:163], v[192:195], v[72:75]
	v_mfma_f32_16x16x32_bf16 v[124:127], v[156:159], v[172:175], v[124:127]
	v_mfma_f32_16x16x32_bf16 v[120:123], v[164:167], v[172:175], v[120:123]
	v_mfma_f32_16x16x32_bf16 v[112:115], v[156:159], v[180:183], v[112:115]
	v_mfma_f32_16x16x32_bf16 v[104:107], v[164:167], v[180:183], v[104:107]
	v_mfma_f32_16x16x32_bf16 v[96:99], v[156:159], v[188:191], v[96:99]
	v_mfma_f32_16x16x32_bf16 v[88:91], v[164:167], v[188:191], v[88:91]
	v_mfma_f32_16x16x32_bf16 v[80:83], v[156:159], v[196:199], v[80:83]
	v_mfma_f32_16x16x32_bf16 v[72:75], v[164:167], v[196:199], v[72:75]
	s_barrier
	s_setprio 0
	s_add_i32 s22, 0, 0x1c000
	s_add_i32 s23, s52, s28
	v_add_u32_e32 v136, s22, v148
	s_add_u32 s0, s20, 0x80
	s_addc_u32 s1, s21, 0
	s_mov_b32 m0, s23
	ds_read_b128 v[202:205], v136
	ds_read_b128 v[206:209], v136 offset:1024
	ds_read_b128 v[210:213], v136 offset:2048
	ds_read_b128 v[214:217], v136 offset:3072
	global_load_lds_dwordx4 v130, s[0:1]
	s_add_i32 m0, s23, 0x2000
	s_nop 0
	global_load_lds_dwordx4 v134, s[0:1]
	s_waitcnt vmcnt(8)
	s_setprio 1
	s_barrier
	s_waitcnt lgkmcnt(0)
	v_mfma_f32_16x16x32_bf16 v[116:119], v[202:205], v[168:171], v[116:119]
	v_mfma_f32_16x16x32_bf16 v[108:111], v[210:213], v[168:171], v[108:111]
	v_mfma_f32_16x16x32_bf16 v[100:103], v[202:205], v[176:179], v[100:103]
	v_mfma_f32_16x16x32_bf16 v[92:95], v[210:213], v[176:179], v[92:95]
	v_mfma_f32_16x16x32_bf16 v[84:87], v[202:205], v[184:187], v[84:87]
	v_mfma_f32_16x16x32_bf16 v[76:79], v[210:213], v[184:187], v[76:79]
	v_mfma_f32_16x16x32_bf16 v[68:71], v[202:205], v[192:195], v[68:71]
	v_mfma_f32_16x16x32_bf16 v[64:67], v[210:213], v[192:195], v[64:67]
	v_mfma_f32_16x16x32_bf16 v[116:119], v[206:209], v[172:175], v[116:119]
	v_mfma_f32_16x16x32_bf16 v[108:111], v[214:217], v[172:175], v[108:111]
	v_mfma_f32_16x16x32_bf16 v[100:103], v[206:209], v[180:183], v[100:103]
	v_mfma_f32_16x16x32_bf16 v[92:95], v[214:217], v[180:183], v[92:95]
	v_mfma_f32_16x16x32_bf16 v[84:87], v[206:209], v[188:191], v[84:87]
	v_mfma_f32_16x16x32_bf16 v[76:79], v[214:217], v[188:191], v[76:79]
	v_mfma_f32_16x16x32_bf16 v[68:71], v[206:209], v[196:199], v[68:71]
	v_mfma_f32_16x16x32_bf16 v[64:67], v[214:217], v[196:199], v[64:67]
	s_barrier
	s_setprio 0
	s_mov_b32 m0, s36
	s_mov_b64 s[0:1], 0x80
	v_lshl_add_u64 v[218:219], v[222:223], 0, s[0:1]
	ds_read_b128 v[168:171], v150 offset:49152
	ds_read_b128 v[172:175], v150 offset:50176
	ds_read_b128 v[176:179], v150 offset:51200
	ds_read_b128 v[180:183], v150 offset:52224
	ds_read_b128 v[184:187], v150 offset:53248
	ds_read_b128 v[188:191], v150 offset:54272
	ds_read_b128 v[192:195], v150 offset:55296
	ds_read_b128 v[196:199], v150 offset:56320
	global_load_lds_dwordx4 v[218:219], off
	v_lshl_add_u64 v[218:219], v[224:225], 0, s[0:1]
	s_mov_b32 m0, s37
	s_nop 0
	global_load_lds_dwordx4 v[218:219], off
	s_setprio 1
	s_barrier
; #define PG8_STAGE(bufoff, gbase, voff) do { _Pragma("unroll") for (int _i = 0; _i < 2; ++_i) \
;         __builtin_amdgcn_global_load_lds((const unsigned*)((const char*)(gbase) + (voff)[_i]), (LAS unsigned*)(lds + (bufoff) + ldsw + _i * 8192), 16, 0, 0); } while (0)
; #define PG8_LDA(dst, b, h) do { _Pragma("unroll") for (int m = 0; m < 4; ++m) _Pragma("unroll") for (int k = 0; k < 2; ++k) dst[m][k] = *(const LAS bf16x8*)(lds + PG8_SA(b, h) + aoff + m * 2048 + k * 1024); } while (0)
; #define PG8_WAIT_V(n) asm volatile("s_waitcnt vmcnt(" #n ")" ::: "memory")
; #define PG8_WAIT_L(n) asm volatile("s_waitcnt lgkmcnt(" #n ")" ::: "memory")
; template <class Epi, class Sched>
; __device__ __forceinline__ void gemm_phase(LAS unsigned char* lds, const Gemm g, const Sched& S, const Epi& E) {
;     ...
;         for (int t = 0; t < nt; t += 2) {
;             const bool last = (t == nt - 2);
;             const char* a1 = cA + (size_t)(t + 1) * kstep;
;             const char* a2 = last ? nA : cA + (size_t)(t + 2) * kstep; const char* b2 = last ? nB : cB + (size_t)(t + 2) * kstep;
;             const char* a3 = a2 + kstep; const char* b3 = b2 + kstep;
;             PG8_LDB(B0, 0, 0); PG8_SCHED; PG8_LDA(At, 0, 0); PG8_STAGE(PG8_SA(1, 1), a1 + hstep, voffA);
;             PG8_WAIT_L(8); PG8_BAR; PG8_WAIT_L(0); PG8_MMA(0, 0, At, B0); PG8_BAR; PG8_SCHED;
;             PG8_LDB(B1, 0, 1); PG8_STAGE(PG8_SB(0, 0), b2, voffB);
;             PG8_BAR; PG8_WAIT_L(0); PG8_MMA(0, 1, At, B1); PG8_BAR;
;             PG8_LDA(At, 0, 1); PG8_STAGE(PG8_SA(0, 0), a2, voffA);
;             PG8_BAR; PG8_WAIT_L(0); PG8_MMA(1, 0, At, B0); PG8_BAR; PG8_SCHED;
;             PG8_STAGE(PG8_SB(0, 1), b2 + hstep, voffB);
;             PG8_WAIT_V(6); PG8_BAR; PG8_MMA(1, 1, At, B1); PG8_BAR;
;             PG8_LDB(B0, 1, 0); PG8_SCHED; PG8_LDA(At, 1, 0); PG8_STAGE(PG8_SA(0, 1), a2 + hstep, voffA);
;             PG8_WAIT_L(8); PG8_BAR; PG8_WAIT_L(0); PG8_MMA(0, 0, At, B0); PG8_BAR; PG8_SCHED;
;             PG8_LDB(B1, 1, 1); PG8_STAGE(PG8_SB(1, 0), b3, voffB);
;             PG8_BAR; PG8_WAIT_L(0); PG8_MMA(0, 1, At, B1); PG8_BAR;
;             PG8_LDA(At, 1, 1); PG8_STAGE(PG8_SA(1, 0), a3, voffA);
;             PG8_BAR; PG8_WAIT_L(0); PG8_MMA(1, 0, At, B0); PG8_BAR; PG8_SCHED;
;             PG8_STAGE(PG8_SB(1, 1), b3 + hstep, voffB);
;             PG8_WAIT_V(6); PG8_BAR; PG8_MMA(1, 1, At, B1); PG8_BAR;
	s_waitcnt lgkmcnt(0)
	v_mfma_f32_16x16x32_bf16 v[60:63], v[152:155], v[168:171], v[60:63]
	v_mfma_f32_16x16x32_bf16 v[56:59], v[160:163], v[168:171], v[56:59]
	v_mfma_f32_16x16x32_bf16 v[48:51], v[152:155], v[176:179], v[48:51]
	v_mfma_f32_16x16x32_bf16 v[40:43], v[160:163], v[176:179], v[40:43]
	v_mfma_f32_16x16x32_bf16 v[32:35], v[152:155], v[184:187], v[32:35]
	v_mfma_f32_16x16x32_bf16 v[24:27], v[160:163], v[184:187], v[24:27]
	v_mfma_f32_16x16x32_bf16 v[16:19], v[152:155], v[192:195], v[16:19]
	v_mfma_f32_16x16x32_bf16 v[8:11], v[160:163], v[192:195], v[8:11]
	v_mfma_f32_16x16x32_bf16 v[60:63], v[156:159], v[172:175], v[60:63]
	v_mfma_f32_16x16x32_bf16 v[56:59], v[164:167], v[172:175], v[56:59]
	v_mfma_f32_16x16x32_bf16 v[48:51], v[156:159], v[180:183], v[48:51]
	v_mfma_f32_16x16x32_bf16 v[40:43], v[164:167], v[180:183], v[40:43]
	v_mfma_f32_16x16x32_bf16 v[32:35], v[156:159], v[188:191], v[32:35]
	v_mfma_f32_16x16x32_bf16 v[24:27], v[164:167], v[188:191], v[24:27]
	v_mfma_f32_16x16x32_bf16 v[16:19], v[156:159], v[196:199], v[16:19]
	v_mfma_f32_16x16x32_bf16 v[8:11], v[164:167], v[196:199], v[8:11]
	s_barrier
	s_setprio 0
	s_add_u32 s20, s20, 0x40080
	s_addc_u32 s21, s21, 0
	s_add_i32 s22, s22, s28
	s_mov_b32 m0, s22
	s_nop 0
	global_load_lds_dwordx4 v130, s[20:21]
	s_add_i32 m0, s22, 0x2000
	s_nop 0
	global_load_lds_dwordx4 v134, s[20:21]
	s_waitcnt vmcnt(8)
	s_setprio 1
	s_barrier
	v_mfma_f32_16x16x32_bf16 v[52:55], v[202:205], v[168:171], v[52:55]
	v_mfma_f32_16x16x32_bf16 v[44:47], v[210:213], v[168:171], v[44:47]
	v_mfma_f32_16x16x32_bf16 v[36:39], v[202:205], v[176:179], v[36:39]
	v_mfma_f32_16x16x32_bf16 v[28:31], v[210:213], v[176:179], v[28:31]
	v_mfma_f32_16x16x32_bf16 v[20:23], v[202:205], v[184:187], v[20:23]
	v_mfma_f32_16x16x32_bf16 v[12:15], v[210:213], v[184:187], v[12:15]
	v_mfma_f32_16x16x32_bf16 v[4:7], v[202:205], v[192:195], v[4:7]
	v_mfma_f32_16x16x32_bf16 v[0:3], v[210:213], v[192:195], v[0:3]
	v_mfma_f32_16x16x32_bf16 v[52:55], v[206:209], v[172:175], v[52:55]
	v_mfma_f32_16x16x32_bf16 v[44:47], v[214:217], v[172:175], v[44:47]
	v_mfma_f32_16x16x32_bf16 v[36:39], v[206:209], v[180:183], v[36:39]
	v_mfma_f32_16x16x32_bf16 v[28:31], v[214:217], v[180:183], v[28:31]
	v_mfma_f32_16x16x32_bf16 v[20:23], v[206:209], v[188:191], v[20:23]
	v_mfma_f32_16x16x32_bf16 v[12:15], v[214:217], v[188:191], v[12:15]
	v_mfma_f32_16x16x32_bf16 v[4:7], v[206:209], v[196:199], v[4:7]
	v_mfma_f32_16x16x32_bf16 v[0:3], v[214:217], v[196:199], v[0:3]
	s_barrier
	s_setprio 0
	s_add_i32 s51, s51, 2
	s_add_u32 s18, s18, 0x100
	s_addc_u32 s19, s19, 0
	s_add_u32 s48, s48, 0x100
	s_addc_u32 s49, s49, 0
	s_cmp_gt_u32 s51, 13
.LBB0_673:
	ds_read_b128 v[152:155], v149
	ds_read_b128 v[156:159], v149 offset:1024
	ds_read_b128 v[160:163], v149 offset:2048
	ds_read_b128 v[164:167], v149 offset:3072
	s_add_u32 s20, s18, 0xfffc0080
	s_addc_u32 s21, s19, -1
	s_cmp_eq_u32 s51, 12
	s_cselect_b32 s23, s9, s21
	s_cselect_b32 s22, s46, s20
	s_cselect_b32 s21, s7, s49
	s_cselect_b32 s20, s47, s48
	s_add_i32 m0, s17, 0xc000
	ds_read_b128 v[168:171], v150
	ds_read_b128 v[172:175], v150 offset:1024
	ds_read_b128 v[176:179], v150 offset:2048
	ds_read_b128 v[180:183], v150 offset:3072
	ds_read_b128 v[184:187], v150 offset:4096
	ds_read_b128 v[188:191], v150 offset:5120
	ds_read_b128 v[192:195], v150 offset:6144
	ds_read_b128 v[196:199], v150 offset:7168
	global_load_lds_dwordx4 v138, s[18:19]
	s_add_i32 m0, s17, 0xe000
	s_nop 0
	global_load_lds_dwordx4 v140, s[18:19]
	s_waitcnt lgkmcnt(8)
	s_waitcnt vmcnt(8)
	s_setprio 1
	s_barrier
	s_waitcnt lgkmcnt(0)
	v_mfma_f32_16x16x32_bf16 v[124:127], v[152:155], v[168:171], v[124:127]
	v_mfma_f32_16x16x32_bf16 v[120:123], v[160:163], v[168:171], v[120:123]
	v_mfma_f32_16x16x32_bf16 v[112:115], v[152:155], v[176:179], v[112:115]
	v_mfma_f32_16x16x32_bf16 v[104:107], v[160:163], v[176:179], v[104:107]
	v_mfma_f32_16x16x32_bf16 v[96:99], v[152:155], v[184:187], v[96:99]
	v_mfma_f32_16x16x32_bf16 v[88:91], v[160:163], v[184:187], v[88:91]
	v_mfma_f32_16x16x32_bf16 v[80:83], v[152:155], v[192:195], v[80:83]
	v_mfma_f32_16x16x32_bf16 v[72:75], v[160:163], v[192:195], v[72:75]
	v_mfma_f32_16x16x32_bf16 v[124:127], v[156:159], v[172:175], v[124:127]
	v_mfma_f32_16x16x32_bf16 v[120:123], v[164:167], v[172:175], v[120:123]
	v_mfma_f32_16x16x32_bf16 v[112:115], v[156:159], v[180:183], v[112:115]
	v_mfma_f32_16x16x32_bf16 v[104:107], v[164:167], v[180:183], v[104:107]
	v_mfma_f32_16x16x32_bf16 v[96:99], v[156:159], v[188:191], v[96:99]
	v_mfma_f32_16x16x32_bf16 v[88:91], v[164:167], v[188:191], v[88:91]
	v_mfma_f32_16x16x32_bf16 v[80:83], v[156:159], v[196:199], v[80:83]
	v_mfma_f32_16x16x32_bf16 v[72:75], v[164:167], v[196:199], v[72:75]
	s_barrier
	s_setprio 0
	s_add_i32 s52, s43, s28
	s_mov_b32 m0, s52
	ds_read_b128 v[202:205], v151
	ds_read_b128 v[206:209], v151 offset:1024
	ds_read_b128 v[210:213], v151 offset:2048
	ds_read_b128 v[214:217], v151 offset:3072
	global_load_lds_dwordx4 v130, s[20:21]
	s_add_i32 m0, s52, 0x2000
	s_nop 0
	global_load_lds_dwordx4 v134, s[20:21]
	s_waitcnt vmcnt(8)
	s_setprio 1
	s_barrier
; #define PG8_STAGE(bufoff, gbase, voff) do { _Pragma("unroll") for (int _i = 0; _i < 2; ++_i) \
;         __builtin_amdgcn_global_load_lds((const unsigned*)((const char*)(gbase) + (voff)[_i]), (LAS unsigned*)(lds + (bufoff) + ldsw + _i * 8192), 16, 0, 0); } while (0)
; #define PG8_LDA(dst, b, h) do { _Pragma("unroll") for (int m = 0; m < 4; ++m) _Pragma("unroll") for (int k = 0; k < 2; ++k) dst[m][k] = *(const LAS bf16x8*)(lds + PG8_SA(b, h) + aoff + m * 2048 + k * 1024); } while (0)
; #define PG8_LDB(dst, b, h) do { _Pragma("unroll") for (int n = 0; n < 2; ++n) _Pragma("unroll") for (int k = 0; k < 2; ++k) dst[n][k] = *(const LAS bf16x8*)(lds + PG8_SB(b, h) + boff + n * 2048 + k * 1024); } while (0)
; #define PG8_MMA(ai, bj, At, Bt) do { __builtin_amdgcn_s_setprio(1); _Pragma("unroll") for (int m = 0; m < 4; ++m) _Pragma("unroll") for (int n = 0; n < 2; ++n) _Pragma("unroll") for (int k = 0; k < 2; ++k) \
;         acc[ai][bj][m][n] = __builtin_amdgcn_mfma_f32_16x16x32_bf16(Bt[n][k], At[m][k], acc[ai][bj][m][n], 0, 0, 0); __builtin_amdgcn_s_setprio(0); } while (0)
; #define PG8_WAIT_V(n) asm volatile("s_waitcnt vmcnt(" #n ")" ::: "memory")
; #define PG8_WAIT_L(n) asm volatile("s_waitcnt lgkmcnt(" #n ")" ::: "memory")
; #define PG8_BAR __builtin_amdgcn_s_barrier()
; #define PG8_SCHED __builtin_amdgcn_sched_barrier(0)
; template <class Epi, class Sched>
; __device__ __forceinline__ void gemm_phase(LAS unsigned char* lds, const Gemm g, const Sched& S, const Epi& E) {
;     ...
;             PG8_LDB(B1, 0, 1); PG8_STAGE(PG8_SB(0, 0), b2, voffB);
;             PG8_BAR; PG8_WAIT_L(0); PG8_MMA(0, 1, At, B1); PG8_BAR;
;             PG8_LDA(At, 0, 1); PG8_STAGE(PG8_SA(0, 0), a2, voffA);
;             PG8_BAR; PG8_WAIT_L(0); PG8_MMA(1, 0, At, B0); PG8_BAR; PG8_SCHED;
;             PG8_STAGE(PG8_SB(0, 1), b2 + hstep, voffB);
;             PG8_WAIT_V(6); PG8_BAR; PG8_MMA(1, 1, At, B1); PG8_BAR;
;             PG8_LDB(B0, 1, 0); PG8_SCHED; PG8_LDA(At, 1, 0); PG8_STAGE(PG8_SA(0, 1), a2 + hstep, voffA);
;             PG8_WAIT_L(8); PG8_BAR; PG8_WAIT_L(0); PG8_MMA(0, 0, At, B0); PG8_BAR; PG8_SCHED;
	s_waitcnt lgkmcnt(0)
	v_mfma_f32_16x16x32_bf16 v[116:119], v[202:205], v[168:171], v[116:119]
	v_mfma_f32_16x16x32_bf16 v[108:111], v[210:213], v[168:171], v[108:111]
	v_mfma_f32_16x16x32_bf16 v[100:103], v[202:205], v[176:179], v[100:103]
	v_mfma_f32_16x16x32_bf16 v[92:95], v[210:213], v[176:179], v[92:95]
	v_mfma_f32_16x16x32_bf16 v[84:87], v[202:205], v[184:187], v[84:87]
	v_mfma_f32_16x16x32_bf16 v[76:79], v[210:213], v[184:187], v[76:79]
	v_mfma_f32_16x16x32_bf16 v[68:71], v[202:205], v[192:195], v[68:71]
	v_mfma_f32_16x16x32_bf16 v[64:67], v[210:213], v[192:195], v[64:67]
	v_mfma_f32_16x16x32_bf16 v[116:119], v[206:209], v[172:175], v[116:119]
	v_mfma_f32_16x16x32_bf16 v[108:111], v[214:217], v[172:175], v[108:111]
	v_mfma_f32_16x16x32_bf16 v[100:103], v[206:209], v[180:183], v[100:103]
	v_mfma_f32_16x16x32_bf16 v[92:95], v[214:217], v[180:183], v[92:95]
	v_mfma_f32_16x16x32_bf16 v[84:87], v[206:209], v[188:191], v[84:87]
	v_mfma_f32_16x16x32_bf16 v[76:79], v[214:217], v[188:191], v[76:79]
	v_mfma_f32_16x16x32_bf16 v[68:71], v[206:209], v[196:199], v[68:71]
	v_mfma_f32_16x16x32_bf16 v[64:67], v[214:217], v[196:199], v[64:67]
	s_barrier
	s_setprio 0
	s_mov_b32 m0, s17
	v_lshl_add_u64 v[222:223], s[22:23], 0, v[128:129]
	ds_read_b128 v[168:171], v150 offset:16384
	ds_read_b128 v[172:175], v150 offset:17408
	ds_read_b128 v[176:179], v150 offset:18432
	ds_read_b128 v[180:183], v150 offset:19456
	ds_read_b128 v[184:187], v150 offset:20480
	ds_read_b128 v[188:191], v150 offset:21504
	ds_read_b128 v[192:195], v150 offset:22528
	ds_read_b128 v[196:199], v150 offset:23552
	global_load_lds_dwordx4 v128, s[22:23]
	v_lshl_add_u64 v[224:225], s[22:23], 0, v[132:133]
	s_mov_b32 m0, s29
	s_nop 0
	global_load_lds_dwordx4 v132, s[22:23]
	s_setprio 1
	s_barrier
	s_waitcnt lgkmcnt(0)
	v_mfma_f32_16x16x32_bf16 v[60:63], v[152:155], v[168:171], v[60:63]
	v_mfma_f32_16x16x32_bf16 v[56:59], v[160:163], v[168:171], v[56:59]
	v_mfma_f32_16x16x32_bf16 v[48:51], v[152:155], v[176:179], v[48:51]
	v_mfma_f32_16x16x32_bf16 v[40:43], v[160:163], v[176:179], v[40:43]
	v_mfma_f32_16x16x32_bf16 v[32:35], v[152:155], v[184:187], v[32:35]
	v_mfma_f32_16x16x32_bf16 v[24:27], v[160:163], v[184:187], v[24:27]
	v_mfma_f32_16x16x32_bf16 v[16:19], v[152:155], v[192:195], v[16:19]
	v_mfma_f32_16x16x32_bf16 v[8:11], v[160:163], v[192:195], v[8:11]
	v_mfma_f32_16x16x32_bf16 v[60:63], v[156:159], v[172:175], v[60:63]
	v_mfma_f32_16x16x32_bf16 v[56:59], v[164:167], v[172:175], v[56:59]
	v_mfma_f32_16x16x32_bf16 v[48:51], v[156:159], v[180:183], v[48:51]
	v_mfma_f32_16x16x32_bf16 v[40:43], v[164:167], v[180:183], v[40:43]
	v_mfma_f32_16x16x32_bf16 v[32:35], v[156:159], v[188:191], v[32:35]
	v_mfma_f32_16x16x32_bf16 v[24:27], v[164:167], v[188:191], v[24:27]
	v_mfma_f32_16x16x32_bf16 v[16:19], v[156:159], v[196:199], v[16:19]
	v_mfma_f32_16x16x32_bf16 v[8:11], v[164:167], v[196:199], v[8:11]
	s_barrier
	s_setprio 0
	s_add_u32 s52, s20, 0x40000
	s_addc_u32 s53, s21, 0
	s_add_i32 s54, s44, s28
	s_mov_b32 m0, s54
	s_nop 0
	global_load_lds_dwordx4 v130, s[52:53]
	s_add_i32 m0, s54, 0x2000
	s_nop 0
	global_load_lds_dwordx4 v134, s[52:53]
	s_add_u32 s22, s22, 0x40000
	s_addc_u32 s23, s23, 0
	s_mov_b32 m0, s30
	s_nop 0
	global_load_lds_dwordx4 v128, s[22:23]
	s_mov_b32 m0, s31
	s_nop 0
	global_load_lds_dwordx4 v132, s[22:23]
	s_waitcnt vmcnt(10)
	s_setprio 1
	s_barrier
	v_mfma_f32_16x16x32_bf16 v[52:55], v[202:205], v[168:171], v[52:55]
	v_mfma_f32_16x16x32_bf16 v[44:47], v[210:213], v[168:171], v[44:47]
	v_mfma_f32_16x16x32_bf16 v[36:39], v[202:205], v[176:179], v[36:39]
	v_mfma_f32_16x16x32_bf16 v[28:31], v[210:213], v[176:179], v[28:31]
	v_mfma_f32_16x16x32_bf16 v[20:23], v[202:205], v[184:187], v[20:23]
	v_mfma_f32_16x16x32_bf16 v[12:15], v[210:213], v[184:187], v[12:15]
	v_mfma_f32_16x16x32_bf16 v[4:7], v[202:205], v[192:195], v[4:7]
	v_mfma_f32_16x16x32_bf16 v[0:3], v[210:213], v[192:195], v[0:3]
	v_mfma_f32_16x16x32_bf16 v[52:55], v[206:209], v[172:175], v[52:55]
	v_mfma_f32_16x16x32_bf16 v[44:47], v[214:217], v[172:175], v[44:47]
	v_mfma_f32_16x16x32_bf16 v[36:39], v[206:209], v[180:183], v[36:39]
	v_mfma_f32_16x16x32_bf16 v[28:31], v[214:217], v[180:183], v[28:31]
	v_mfma_f32_16x16x32_bf16 v[20:23], v[206:209], v[188:191], v[20:23]
	v_mfma_f32_16x16x32_bf16 v[12:15], v[214:217], v[188:191], v[12:15]
	v_mfma_f32_16x16x32_bf16 v[4:7], v[206:209], v[196:199], v[4:7]
	v_mfma_f32_16x16x32_bf16 v[0:3], v[214:217], v[196:199], v[0:3]
	s_barrier
	s_setprio 0
	s_add_i32 s52, 0, 0x18000
	ds_read_b128 v[152:155], v151 offset:16384
	ds_read_b128 v[156:159], v151 offset:17408
	ds_read_b128 v[160:163], v151 offset:18432
	ds_read_b128 v[164:167], v151 offset:19456
	ds_read_b128 v[168:171], v150 offset:32768
	ds_read_b128 v[172:175], v150 offset:33792
	ds_read_b128 v[176:179], v150 offset:34816
	ds_read_b128 v[180:183], v150 offset:35840
	ds_read_b128 v[184:187], v150 offset:36864
	ds_read_b128 v[188:191], v150 offset:37888
	ds_read_b128 v[192:195], v150 offset:38912
	ds_read_b128 v[196:199], v150 offset:39936
	s_waitcnt lgkmcnt(8)
	s_waitcnt vmcnt(8)
	s_setprio 1
	s_barrier
; #define PG8_STAGE(bufoff, gbase, voff) do { _Pragma("unroll") for (int _i = 0; _i < 2; ++_i) \
;         __builtin_amdgcn_global_load_lds((const unsigned*)((const char*)(gbase) + (voff)[_i]), (LAS unsigned*)(lds + (bufoff) + ldsw + _i * 8192), 16, 0, 0); } while (0)
; #define PG8_LDA(dst, b, h) do { _Pragma("unroll") for (int m = 0; m < 4; ++m) _Pragma("unroll") for (int k = 0; k < 2; ++k) dst[m][k] = *(const LAS bf16x8*)(lds + PG8_SA(b, h) + aoff + m * 2048 + k * 1024); } while (0)
; #define PG8_LDB(dst, b, h) do { _Pragma("unroll") for (int n = 0; n < 2; ++n) _Pragma("unroll") for (int k = 0; k < 2; ++k) dst[n][k] = *(const LAS bf16x8*)(lds + PG8_SB(b, h) + boff + n * 2048 + k * 1024); } while (0)
; #define PG8_MMA(ai, bj, At, Bt) do { __builtin_amdgcn_s_setprio(1); _Pragma("unroll") for (int m = 0; m < 4; ++m) _Pragma("unroll") for (int n = 0; n < 2; ++n) _Pragma("unroll") for (int k = 0; k < 2; ++k) \
;         acc[ai][bj][m][n] = __builtin_amdgcn_mfma_f32_16x16x32_bf16(Bt[n][k], At[m][k], acc[ai][bj][m][n], 0, 0, 0); __builtin_amdgcn_s_setprio(0); } while (0)
; #define PG8_WAIT_V(n) asm volatile("s_waitcnt vmcnt(" #n ")" ::: "memory")
; #define PG8_WAIT_L(n) asm volatile("s_waitcnt lgkmcnt(" #n ")" ::: "memory")
; #define PG8_BAR __builtin_amdgcn_s_barrier()
; #define PG8_SCHED __builtin_amdgcn_sched_barrier(0)
; template <class Epi, class Sched>
; __device__ __forceinline__ void gemm_phase(LAS unsigned char* lds, const Gemm g, const Sched& S, const Epi& E) {
;     ...
;             PG8_WAIT_L(8); PG8_BAR; PG8_WAIT_L(0); PG8_MMA(0, 0, At, B0); PG8_BAR; PG8_SCHED;
;             PG8_LDB(B1, 1, 1); PG8_STAGE(PG8_SB(1, 0), b3, voffB);
;             PG8_BAR; PG8_WAIT_L(0); PG8_MMA(0, 1, At, B1); PG8_BAR;
;             PG8_LDA(At, 1, 1); PG8_STAGE(PG8_SA(1, 0), a3, voffA);
;             PG8_BAR; PG8_WAIT_L(0); PG8_MMA(1, 0, At, B0); PG8_BAR; PG8_SCHED;
;             PG8_STAGE(PG8_SB(1, 1), b3 + hstep, voffB);
;             PG8_WAIT_V(6); PG8_BAR; PG8_MMA(1, 1, At, B1); PG8_BAR;
	s_waitcnt lgkmcnt(0)
	v_mfma_f32_16x16x32_bf16 v[124:127], v[152:155], v[168:171], v[124:127]
	v_mfma_f32_16x16x32_bf16 v[120:123], v[160:163], v[168:171], v[120:123]
	v_mfma_f32_16x16x32_bf16 v[112:115], v[152:155], v[176:179], v[112:115]
	v_mfma_f32_16x16x32_bf16 v[104:107], v[160:163], v[176:179], v[104:107]
	v_mfma_f32_16x16x32_bf16 v[96:99], v[152:155], v[184:187], v[96:99]
	v_mfma_f32_16x16x32_bf16 v[88:91], v[160:163], v[184:187], v[88:91]
	v_mfma_f32_16x16x32_bf16 v[80:83], v[152:155], v[192:195], v[80:83]
	v_mfma_f32_16x16x32_bf16 v[72:75], v[160:163], v[192:195], v[72:75]
	v_mfma_f32_16x16x32_bf16 v[124:127], v[156:159], v[172:175], v[124:127]
	v_mfma_f32_16x16x32_bf16 v[120:123], v[164:167], v[172:175], v[120:123]
	v_mfma_f32_16x16x32_bf16 v[112:115], v[156:159], v[180:183], v[112:115]
	v_mfma_f32_16x16x32_bf16 v[104:107], v[164:167], v[180:183], v[104:107]
	v_mfma_f32_16x16x32_bf16 v[96:99], v[156:159], v[188:191], v[96:99]
	v_mfma_f32_16x16x32_bf16 v[88:91], v[164:167], v[188:191], v[88:91]
	v_mfma_f32_16x16x32_bf16 v[80:83], v[156:159], v[196:199], v[80:83]
	v_mfma_f32_16x16x32_bf16 v[72:75], v[164:167], v[196:199], v[72:75]
	s_barrier
	s_setprio 0
	s_add_i32 s22, 0, 0x1c000
	s_add_i32 s23, s52, s28
	v_add_u32_e32 v136, s22, v148
	s_add_u32 s0, s20, 0x80
	s_addc_u32 s1, s21, 0
	s_mov_b32 m0, s23
	ds_read_b128 v[202:205], v136
	ds_read_b128 v[206:209], v136 offset:1024
	ds_read_b128 v[210:213], v136 offset:2048
	ds_read_b128 v[214:217], v136 offset:3072
	global_load_lds_dwordx4 v130, s[0:1]
	s_add_i32 m0, s23, 0x2000
	s_nop 0
	global_load_lds_dwordx4 v134, s[0:1]
	s_waitcnt vmcnt(8)
	s_setprio 1
	s_barrier
	s_waitcnt lgkmcnt(0)
	v_mfma_f32_16x16x32_bf16 v[116:119], v[202:205], v[168:171], v[116:119]
	v_mfma_f32_16x16x32_bf16 v[108:111], v[210:213], v[168:171], v[108:111]
	v_mfma_f32_16x16x32_bf16 v[100:103], v[202:205], v[176:179], v[100:103]
	v_mfma_f32_16x16x32_bf16 v[92:95], v[210:213], v[176:179], v[92:95]
	v_mfma_f32_16x16x32_bf16 v[84:87], v[202:205], v[184:187], v[84:87]
	v_mfma_f32_16x16x32_bf16 v[76:79], v[210:213], v[184:187], v[76:79]
	v_mfma_f32_16x16x32_bf16 v[68:71], v[202:205], v[192:195], v[68:71]
	v_mfma_f32_16x16x32_bf16 v[64:67], v[210:213], v[192:195], v[64:67]
	v_mfma_f32_16x16x32_bf16 v[116:119], v[206:209], v[172:175], v[116:119]
	v_mfma_f32_16x16x32_bf16 v[108:111], v[214:217], v[172:175], v[108:111]
	v_mfma_f32_16x16x32_bf16 v[100:103], v[206:209], v[180:183], v[100:103]
	v_mfma_f32_16x16x32_bf16 v[92:95], v[214:217], v[180:183], v[92:95]
	v_mfma_f32_16x16x32_bf16 v[84:87], v[206:209], v[188:191], v[84:87]
	v_mfma_f32_16x16x32_bf16 v[76:79], v[214:217], v[188:191], v[76:79]
	v_mfma_f32_16x16x32_bf16 v[68:71], v[206:209], v[196:199], v[68:71]
	v_mfma_f32_16x16x32_bf16 v[64:67], v[214:217], v[196:199], v[64:67]
	s_barrier
	s_setprio 0
	s_mov_b32 m0, s36
	s_mov_b64 s[0:1], 0x80
	v_lshl_add_u64 v[218:219], v[222:223], 0, s[0:1]
	ds_read_b128 v[168:171], v150 offset:49152
	ds_read_b128 v[172:175], v150 offset:50176
	ds_read_b128 v[176:179], v150 offset:51200
	ds_read_b128 v[180:183], v150 offset:52224
	ds_read_b128 v[184:187], v150 offset:53248
	ds_read_b128 v[188:191], v150 offset:54272
	ds_read_b128 v[192:195], v150 offset:55296
	ds_read_b128 v[196:199], v150 offset:56320
	global_load_lds_dwordx4 v[218:219], off
	v_lshl_add_u64 v[218:219], v[224:225], 0, s[0:1]
	s_mov_b32 m0, s37
	s_nop 0
	global_load_lds_dwordx4 v[218:219], off
	s_setprio 1
	s_barrier
	s_waitcnt lgkmcnt(0)
	v_mfma_f32_16x16x32_bf16 v[60:63], v[152:155], v[168:171], v[60:63]
	v_mfma_f32_16x16x32_bf16 v[56:59], v[160:163], v[168:171], v[56:59]
	v_mfma_f32_16x16x32_bf16 v[48:51], v[152:155], v[176:179], v[48:51]
	v_mfma_f32_16x16x32_bf16 v[40:43], v[160:163], v[176:179], v[40:43]
	v_mfma_f32_16x16x32_bf16 v[32:35], v[152:155], v[184:187], v[32:35]
	v_mfma_f32_16x16x32_bf16 v[24:27], v[160:163], v[184:187], v[24:27]
	v_mfma_f32_16x16x32_bf16 v[16:19], v[152:155], v[192:195], v[16:19]
	v_mfma_f32_16x16x32_bf16 v[8:11], v[160:163], v[192:195], v[8:11]
	v_mfma_f32_16x16x32_bf16 v[60:63], v[156:159], v[172:175], v[60:63]
	v_mfma_f32_16x16x32_bf16 v[56:59], v[164:167], v[172:175], v[56:59]
	v_mfma_f32_16x16x32_bf16 v[48:51], v[156:159], v[180:183], v[48:51]
	v_mfma_f32_16x16x32_bf16 v[40:43], v[164:167], v[180:183], v[40:43]
	v_mfma_f32_16x16x32_bf16 v[32:35], v[156:159], v[188:191], v[32:35]
	v_mfma_f32_16x16x32_bf16 v[24:27], v[164:167], v[188:191], v[24:27]
	v_mfma_f32_16x16x32_bf16 v[16:19], v[156:159], v[196:199], v[16:19]
	v_mfma_f32_16x16x32_bf16 v[8:11], v[164:167], v[196:199], v[8:11]
	s_barrier
	s_setprio 0
	s_add_u32 s20, s20, 0x40080
	s_addc_u32 s21, s21, 0
	s_add_i32 s22, s22, s28
	s_mov_b32 m0, s22
	s_nop 0
	global_load_lds_dwordx4 v130, s[20:21]
	s_add_i32 m0, s22, 0x2000
	s_nop 0
	global_load_lds_dwordx4 v134, s[20:21]
	s_waitcnt vmcnt(8)
	s_setprio 1
	s_barrier
	v_mfma_f32_16x16x32_bf16 v[52:55], v[202:205], v[168:171], v[52:55]
	v_mfma_f32_16x16x32_bf16 v[44:47], v[210:213], v[168:171], v[44:47]
	v_mfma_f32_16x16x32_bf16 v[36:39], v[202:205], v[176:179], v[36:39]
	v_mfma_f32_16x16x32_bf16 v[28:31], v[210:213], v[176:179], v[28:31]
	v_mfma_f32_16x16x32_bf16 v[20:23], v[202:205], v[184:187], v[20:23]
	v_mfma_f32_16x16x32_bf16 v[12:15], v[210:213], v[184:187], v[12:15]
	v_mfma_f32_16x16x32_bf16 v[4:7], v[202:205], v[192:195], v[4:7]
	v_mfma_f32_16x16x32_bf16 v[0:3], v[210:213], v[192:195], v[0:3]
	v_mfma_f32_16x16x32_bf16 v[52:55], v[206:209], v[172:175], v[52:55]
	v_mfma_f32_16x16x32_bf16 v[44:47], v[214:217], v[172:175], v[44:47]
	v_mfma_f32_16x16x32_bf16 v[36:39], v[206:209], v[180:183], v[36:39]
	v_mfma_f32_16x16x32_bf16 v[28:31], v[214:217], v[180:183], v[28:31]
	v_mfma_f32_16x16x32_bf16 v[20:23], v[206:209], v[188:191], v[20:23]
	v_mfma_f32_16x16x32_bf16 v[12:15], v[214:217], v[188:191], v[12:15]
	v_mfma_f32_16x16x32_bf16 v[4:7], v[206:209], v[196:199], v[4:7]
	v_mfma_f32_16x16x32_bf16 v[0:3], v[214:217], v[196:199], v[0:3]
	s_barrier
; __device__ __forceinline__ unsigned cvt_pk_bf16(float lo, float hi) { unsigned r; asm volatile("v_cvt_pk_bf16_f32 %0, %1, %2" : "=v"(r) : "v"(lo), "v"(hi)); return r; }
;     __device__ __forceinline__ void operator()(const AccT& acc, const Unit& u, int wr, int wc, int fr, int fq) const {
;     ...
;         const int rbase = u.pm * 256 + wr * 64 + fr;
;         const int tb = u.pn * 256 + wc * 32 + 8 * fq;
; #pragma unroll
;         for (int ai = 0; ai < 2; ++ai)
; #pragma unroll
;             for (int m = 0; m < 4; ++m) {
;                 const int gm = rbase + ai * 128 + m * 16;
; #pragma unroll
;                 for (int bj = 0; bj < 2; ++bj) {
;                     const int t0 = tb + bj * 128;
;                     const f32x4 v0 = acc[ai][bj][m][0], v1 = acc[ai][bj][m][1];
;                     u32x4 w; w.x = cvt_pk_bf16(v0[0], v0[1]); w.y = cvt_pk_bf16(v0[2], v0[3]); w.z = cvt_pk_bf16(v1[0], v1[1]); w.w = cvt_pk_bf16(v1[2], v1[3]);
;                     *(u32x4*)(YT + ((size_t)((t0 >> 10) * 512 + gm)) * 2048 + part * 1024 + (t0 & 1023)) = w;
;                 }
	s_setprio 0
	s_add_i32 s51, s51, 2
	s_add_u32 s18, s18, 0x100
	s_addc_u32 s19, s19, 0
	s_add_u32 s48, s48, 0x100
	s_addc_u32 s49, s49, 0
	s_cmp_gt_u32 s51, 13
	s_cbranch_scc0 .LBB0_673
	v_mov_b32_e32 v136, v147
	v_mov_b32_e32 v152, v146
	s_lshl_b32 s7, s16, 8
	s_add_i32 s7, s7, s34
	v_add_u32_e32 v152, s7, v152
	s_lshl_b32 s7, s45, 8
	s_or_b32 s7, s7, s35
	v_lshl_add_u32 v153, v136, 3, s7
	v_cvt_pk_bf16_f32 v124, v124, v125
	v_cvt_pk_bf16_f32 v125, v126, v127
	v_cvt_pk_bf16_f32 v126, v120, v121
	v_ashrrev_i32_e32 v120, 1, v153
	v_cvt_pk_bf16_f32 v127, v122, v123
	v_and_b32_e32 v122, 0xfffffe00, v120
	v_add_u32_e32 v120, v122, v152
	v_ashrrev_i32_e32 v121, 31, v120
	v_lshlrev_b64 v[120:121], 12, v[120:121]
	v_and_b32_e32 v123, 0x3f8, v153
	v_lshl_add_u64 v[120:121], s[4:5], 0, v[120:121]
	v_lshlrev_b32_e32 v136, 1, v123
	v_lshl_add_u64 v[120:121], v[120:121], 0, v[136:137]
	global_store_dwordx4 v[120:121], v[124:127], off
	v_add_u32_e32 v120, 0x80, v153
	v_cvt_pk_bf16_f32 v116, v116, v117
	v_cvt_pk_bf16_f32 v117, v118, v119
	v_cvt_pk_bf16_f32 v118, v108, v109
	v_ashrrev_i32_e32 v108, 1, v120
	v_and_b32_e32 v121, 0xfffffe00, v108
	v_add_u32_e32 v108, v121, v152
	v_ashrrev_i32_e32 v109, 31, v108
	v_lshlrev_b64 v[108:109], 12, v[108:109]
	v_cvt_pk_bf16_f32 v119, v110, v111
	v_lshl_add_u64 v[110:111], s[4:5], 0, v[108:109]
	v_and_b32_e32 v108, 0x3f8, v120
	v_lshlrev_b32_e32 v108, 1, v108
	v_mov_b32_e32 v109, v137
	v_lshl_add_u64 v[110:111], v[110:111], 0, v[108:109]
	global_store_dwordx4 v[110:111], v[116:119], off
	v_cvt_pk_bf16_f32 v110, v112, v113
	v_cvt_pk_bf16_f32 v111, v114, v115
	v_cvt_pk_bf16_f32 v112, v104, v105
	v_cvt_pk_bf16_f32 v113, v106, v107
	s_and_b64 vcc, exec, s[2:3]
	s_nop 0
	v_add_u32_e32 v116, 16, v152
	v_add_u32_e32 v104, v122, v116
	v_ashrrev_i32_e32 v105, 31, v104
	v_lshlrev_b64 v[104:105], 12, v[104:105]
	v_lshl_add_u64 v[104:105], s[4:5], 0, v[104:105]
	v_lshl_add_u64 v[104:105], v[104:105], 0, v[136:137]
	global_store_dwordx4 v[104:105], v[110:113], off
	v_cvt_pk_bf16_f32 v100, v100, v101
	v_cvt_pk_bf16_f32 v101, v102, v103
	v_cvt_pk_bf16_f32 v102, v92, v93
	v_add_u32_e32 v92, v121, v116
	v_ashrrev_i32_e32 v93, 31, v92
	v_lshlrev_b64 v[92:93], 12, v[92:93]
	v_lshl_add_u64 v[92:93], s[4:5], 0, v[92:93]
	v_lshl_add_u64 v[92:93], v[92:93], 0, v[108:109]
	v_cvt_pk_bf16_f32 v103, v94, v95
	global_store_dwordx4 v[92:93], v[100:103], off
	v_cvt_pk_bf16_f32 v92, v96, v97
	v_cvt_pk_bf16_f32 v93, v98, v99
	v_cvt_pk_bf16_f32 v94, v88, v89
	v_cvt_pk_bf16_f32 v95, v90, v91
	s_mov_b32 s45, s6
	s_nop 0
	v_add_u32_e32 v100, 32, v152
	v_add_u32_e32 v88, v122, v100
	v_ashrrev_i32_e32 v89, 31, v88
	v_lshlrev_b64 v[88:89], 12, v[88:89]
	v_lshl_add_u64 v[88:89], s[4:5], 0, v[88:89]
	v_lshl_add_u64 v[88:89], v[88:89], 0, v[136:137]
	global_store_dwordx4 v[88:89], v[92:95], off
	v_cvt_pk_bf16_f32 v84, v84, v85
	v_cvt_pk_bf16_f32 v85, v86, v87
	v_cvt_pk_bf16_f32 v86, v76, v77
	v_add_u32_e32 v76, v121, v100
	v_ashrrev_i32_e32 v77, 31, v76
	v_lshlrev_b64 v[76:77], 12, v[76:77]
	v_lshl_add_u64 v[76:77], s[4:5], 0, v[76:77]
	v_lshl_add_u64 v[76:77], v[76:77], 0, v[108:109]
	v_cvt_pk_bf16_f32 v87, v78, v79
	global_store_dwordx4 v[76:77], v[84:87], off
	v_cvt_pk_bf16_f32 v76, v80, v81
	v_cvt_pk_bf16_f32 v77, v82, v83
	v_cvt_pk_bf16_f32 v78, v72, v73
	v_cvt_pk_bf16_f32 v79, v74, v75
	s_mov_b32 s16, s8
	s_nop 0
	v_add_u32_e32 v84, 48, v152
	v_add_u32_e32 v72, v122, v84
	v_ashrrev_i32_e32 v73, 31, v72
	v_lshlrev_b64 v[72:73], 12, v[72:73]
	v_lshl_add_u64 v[72:73], s[4:5], 0, v[72:73]
	v_lshl_add_u64 v[72:73], v[72:73], 0, v[136:137]
	global_store_dwordx4 v[72:73], v[76:79], off
; __device__ __forceinline__ unsigned cvt_pk_bf16(float lo, float hi) { unsigned r; asm volatile("v_cvt_pk_bf16_f32 %0, %1, %2" : "=v"(r) : "v"(lo), "v"(hi)); return r; }
; #define PG8_WAIT_V(n) asm volatile("s_waitcnt vmcnt(" #n ")" ::: "memory")
; #define PG8_BAR __builtin_amdgcn_s_barrier()
; template <class Epi, class Sched>
; __device__ __forceinline__ void gemm_phase(LAS unsigned char* lds, const Gemm g, const Sched& S, const Epi& E) {
;     ...
;         if (!has_next) break;
; #pragma unroll
;         for (int a = 0; a < 2; ++a)
; #pragma unroll
;             for (int b = 0; b < 2; ++b)
; #pragma unroll
;                 for (int m = 0; m < 4; ++m)
; #pragma unroll
;                     for (int n = 0; n < 2; ++n) acc[a][b][m][n] = (f32x4){0.f, 0.f, 0.f, 0.f};
;         cur = nxt; cA = nA; cB = nB; ++ui;
;     }
;     PG8_WAIT_V(0);
;     if (wr == 0) PG8_BAR;
;     __device__ __forceinline__ void operator()(const AccT& acc, const Unit& u, int wr, int wc, int fr, int fq) const {
;     ...
;                 const int gm = rbase + ai * 128 + m * 16;
; #pragma unroll
;                 for (int bj = 0; bj < 2; ++bj) {
;                     const int t0 = tb + bj * 128;
;                     const f32x4 v0 = acc[ai][bj][m][0], v1 = acc[ai][bj][m][1];
;                     u32x4 w; w.x = cvt_pk_bf16(v0[0], v0[1]); w.y = cvt_pk_bf16(v0[2], v0[3]); w.z = cvt_pk_bf16(v1[0], v1[1]); w.w = cvt_pk_bf16(v1[2], v1[3]);
;                     *(u32x4*)(YT + ((size_t)((t0 >> 10) * 512 + gm)) * 2048 + part * 1024 + (t0 & 1023)) = w;
;                 }
	v_cvt_pk_bf16_f32 v68, v68, v69
	v_cvt_pk_bf16_f32 v69, v70, v71
	v_cvt_pk_bf16_f32 v70, v64, v65
	v_add_u32_e32 v64, v121, v84
	v_ashrrev_i32_e32 v65, 31, v64
	v_lshlrev_b64 v[64:65], 12, v[64:65]
	v_lshl_add_u64 v[64:65], s[4:5], 0, v[64:65]
	v_lshl_add_u64 v[64:65], v[64:65], 0, v[108:109]
	v_cvt_pk_bf16_f32 v71, v66, v67
	global_store_dwordx4 v[64:65], v[68:71], off
	v_add_u32_e32 v64, 0x80, v152
	v_cvt_pk_bf16_f32 v60, v60, v61
	v_cvt_pk_bf16_f32 v61, v62, v63
	v_cvt_pk_bf16_f32 v62, v56, v57
	v_add_u32_e32 v56, v122, v64
	v_ashrrev_i32_e32 v57, 31, v56
	v_lshlrev_b64 v[56:57], 12, v[56:57]
	v_lshl_add_u64 v[56:57], s[4:5], 0, v[56:57]
	v_lshl_add_u64 v[56:57], v[56:57], 0, v[136:137]
	v_cvt_pk_bf16_f32 v63, v58, v59
	global_store_dwordx4 v[56:57], v[60:63], off
	v_cvt_pk_bf16_f32 v52, v52, v53
	v_cvt_pk_bf16_f32 v53, v54, v55
	v_cvt_pk_bf16_f32 v54, v44, v45
	v_add_u32_e32 v44, v121, v64
	v_ashrrev_i32_e32 v45, 31, v44
	v_lshlrev_b64 v[44:45], 12, v[44:45]
	v_lshl_add_u64 v[44:45], s[4:5], 0, v[44:45]
	v_lshl_add_u64 v[44:45], v[44:45], 0, v[108:109]
	v_cvt_pk_bf16_f32 v55, v46, v47
	global_store_dwordx4 v[44:45], v[52:55], off
	v_cvt_pk_bf16_f32 v44, v48, v49
	v_cvt_pk_bf16_f32 v45, v50, v51
	v_cvt_pk_bf16_f32 v46, v40, v41
	v_cvt_pk_bf16_f32 v47, v42, v43
	s_mov_b64 s[20:21], s[14:15]
	s_nop 0
	v_add_u32_e32 v52, 0x90, v152
	v_add_u32_e32 v40, v122, v52
	v_ashrrev_i32_e32 v41, 31, v40
	v_lshlrev_b64 v[40:41], 12, v[40:41]
	v_lshl_add_u64 v[40:41], s[4:5], 0, v[40:41]
	v_lshl_add_u64 v[40:41], v[40:41], 0, v[136:137]
	global_store_dwordx4 v[40:41], v[44:47], off
	v_cvt_pk_bf16_f32 v36, v36, v37
	v_cvt_pk_bf16_f32 v37, v38, v39
	v_cvt_pk_bf16_f32 v38, v28, v29
	v_add_u32_e32 v28, v121, v52
	v_ashrrev_i32_e32 v29, 31, v28
	v_lshlrev_b64 v[28:29], 12, v[28:29]
	v_lshl_add_u64 v[28:29], s[4:5], 0, v[28:29]
	v_lshl_add_u64 v[28:29], v[28:29], 0, v[108:109]
	v_cvt_pk_bf16_f32 v39, v30, v31
	global_store_dwordx4 v[28:29], v[36:39], off
	v_cvt_pk_bf16_f32 v28, v32, v33
	v_cvt_pk_bf16_f32 v29, v34, v35
	v_cvt_pk_bf16_f32 v30, v24, v25
	v_cvt_pk_bf16_f32 v31, v26, v27
	s_mov_b64 s[18:19], s[12:13]
	s_nop 0
	v_add_u32_e32 v36, 0xa0, v152
	v_add_u32_e32 v24, v122, v36
	v_ashrrev_i32_e32 v25, 31, v24
	v_lshlrev_b64 v[24:25], 12, v[24:25]
	v_lshl_add_u64 v[24:25], s[4:5], 0, v[24:25]
	v_lshl_add_u64 v[24:25], v[24:25], 0, v[136:137]
	global_store_dwordx4 v[24:25], v[28:31], off
	v_cvt_pk_bf16_f32 v20, v20, v21
	v_cvt_pk_bf16_f32 v21, v22, v23
	v_cvt_pk_bf16_f32 v22, v12, v13
	v_add_u32_e32 v12, v121, v36
	v_ashrrev_i32_e32 v13, 31, v12
	v_lshlrev_b64 v[12:13], 12, v[12:13]
	v_lshl_add_u64 v[12:13], s[4:5], 0, v[12:13]
	v_lshl_add_u64 v[12:13], v[12:13], 0, v[108:109]
	v_cvt_pk_bf16_f32 v23, v14, v15
	global_store_dwordx4 v[12:13], v[20:23], off
	v_cvt_pk_bf16_f32 v12, v16, v17
	v_cvt_pk_bf16_f32 v13, v18, v19
	v_cvt_pk_bf16_f32 v14, v8, v9
	v_cvt_pk_bf16_f32 v15, v10, v11
	s_nop 1
	v_add_u32_e32 v20, 0xb0, v152
	v_add_u32_e32 v8, v122, v20
	v_ashrrev_i32_e32 v9, 31, v8
	v_lshlrev_b64 v[8:9], 12, v[8:9]
	v_lshl_add_u64 v[8:9], s[4:5], 0, v[8:9]
	v_lshl_add_u64 v[8:9], v[8:9], 0, v[136:137]
	global_store_dwordx4 v[8:9], v[12:15], off
	v_cvt_pk_bf16_f32 v4, v4, v5
	v_cvt_pk_bf16_f32 v5, v6, v7
	v_cvt_pk_bf16_f32 v6, v0, v1
	v_add_u32_e32 v0, v121, v20
	v_ashrrev_i32_e32 v1, 31, v0
	v_lshlrev_b64 v[0:1], 12, v[0:1]
	v_lshl_add_u64 v[0:1], s[4:5], 0, v[0:1]
	v_lshl_add_u64 v[0:1], v[0:1], 0, v[108:109]
	v_cvt_pk_bf16_f32 v7, v2, v3
	global_store_dwordx4 v[0:1], v[4:7], off
	s_cbranch_vccz .LBB0_666
	s_waitcnt vmcnt(0)
	s_cmpk_gt_u32 s24, 0xff
	s_cbranch_scc1 .LBB0_677
	s_barrier

; #define PG8_STAGE(bufoff, gbase, voff) do { _Pragma("unroll") for (int _i = 0; _i < 2; ++_i) \
;         __builtin_amdgcn_global_load_lds((const unsigned*)((const char*)(gbase) + (voff)[_i]), (LAS unsigned*)(lds + (bufoff) + ldsw + _i * 8192), 16, 0, 0); } while (0)
; #define PG8_LDA(dst, b, h) do { _Pragma("unroll") for (int m = 0; m < 4; ++m) _Pragma("unroll") for (int k = 0; k < 2; ++k) dst[m][k] = *(const LAS bf16x8*)(lds + PG8_SA(b, h) + aoff + m * 2048 + k * 1024); } while (0)
; #define PG8_LDB(dst, b, h) do { _Pragma("unroll") for (int n = 0; n < 2; ++n) _Pragma("unroll") for (int k = 0; k < 2; ++k) dst[n][k] = *(const LAS bf16x8*)(lds + PG8_SB(b, h) + boff + n * 2048 + k * 1024); } while (0)
; #define PG8_WAIT_V(n) asm volatile("s_waitcnt vmcnt(" #n ")" ::: "memory")
; #define PG8_BAR __builtin_amdgcn_s_barrier()
; template <class Epi, class Sched>
; __device__ __forceinline__ void gemm_phase(LAS unsigned char* lds, const Gemm g, const Sched& S, const Epi& E) {
;     ...
;         const bool has_next = S.next(ui + 1, nxt);
;         const char* nA = has_next ? (const char*)g.A + (size_t)nxt.pm * tstep : cA; const char* nB = has_next ? (const char*)g.Bt + (size_t)nxt.pn * tstep : cB;
;         for (int t = 0; t < nt; t += 2) {
;             const bool last = (t == nt - 2);
;             const char* a1 = cA + (size_t)(t + 1) * kstep;
;             const char* a2 = last ? nA : cA + (size_t)(t + 2) * kstep; const char* b2 = last ? nB : cB + (size_t)(t + 2) * kstep;
;             const char* a3 = a2 + kstep; const char* b3 = b2 + kstep;
;             PG8_LDB(B0, 0, 0); PG8_SCHED; PG8_LDA(At, 0, 0); PG8_STAGE(PG8_SA(1, 1), a1 + hstep, voffA);
;             PG8_WAIT_L(8); PG8_BAR; PG8_WAIT_L(0); PG8_MMA(0, 0, At, B0); PG8_BAR; PG8_SCHED;
;             PG8_LDB(B1, 0, 1); PG8_STAGE(PG8_SB(0, 0), b2, voffB);
;             PG8_BAR; PG8_WAIT_L(0); PG8_MMA(0, 1, At, B1); PG8_BAR;
;             PG8_LDA(At, 0, 1); PG8_STAGE(PG8_SA(0, 0), a2, voffA);
;             PG8_BAR; PG8_WAIT_L(0); PG8_MMA(1, 0, At, B0); PG8_BAR; PG8_SCHED;
;             PG8_STAGE(PG8_SB(0, 1), b2 + hstep, voffB);
;             PG8_WAIT_V(6); PG8_BAR; PG8_MMA(1, 1, At, B1); PG8_BAR;
;             PG8_LDB(B0, 1, 0); PG8_SCHED; PG8_LDA(At, 1, 0); PG8_STAGE(PG8_SA(0, 1), a2 + hstep, voffA);
;             PG8_WAIT_L(8); PG8_BAR; PG8_WAIT_L(0); PG8_MMA(0, 0, At, B0); PG8_BAR; PG8_SCHED;
.LBB0_692:
	s_ashr_i32 s19, s18, 31
	v_cmp_lt_i64_e64 s[24:25], s[20:21], 32
	s_lshl_b64 s[20:21], s[18:19], 19
	s_add_u32 s20, s40, s20
	s_addc_u32 s21, s41, s21
	s_and_b64 s[22:23], s[24:25], exec
	s_cselect_b32 s19, s21, s3
	s_cselect_b32 s57, s20, s2
	s_ashr_i32 s17, s16, 31
	s_lshl_b64 s[22:23], s[16:17], 19
	s_add_u32 s22, s28, s22
	s_addc_u32 s23, s29, s23
	s_and_b64 s[24:25], s[24:25], exec
	s_cselect_b32 s17, s23, s5
	s_cselect_b32 s58, s22, s4
	s_add_u32 s2, s2, 0x40080
	s_addc_u32 s3, s3, 0
	s_add_u32 s59, s4, 0x100
	s_addc_u32 s60, s5, 0
	s_mov_b32 s61, -2
	s_waitcnt lgkmcnt(0)
	ds_read_b128 v[140:143], v149
	ds_read_b128 v[154:157], v149 offset:1024
	ds_read_b128 v[158:161], v149 offset:2048
	ds_read_b128 v[162:165], v149 offset:3072
	s_add_u32 s4, s2, 0xfffc0080
	s_addc_u32 s5, s3, -1
	s_cmp_eq_u32 s61, 12
	s_cselect_b32 s25, s19, s5
	s_cselect_b32 s24, s57, s4
	s_cselect_b32 s5, s17, s60
	s_cselect_b32 s4, s58, s59
	s_add_i32 m0, s33, 0xc000
	ds_read_b128 v[166:169], v150
	ds_read_b128 v[170:173], v150 offset:1024
	ds_read_b128 v[174:177], v150 offset:2048
	ds_read_b128 v[178:181], v150 offset:3072
	ds_read_b128 v[182:185], v150 offset:4096
	ds_read_b128 v[186:189], v150 offset:5120
	ds_read_b128 v[190:193], v150 offset:6144
	ds_read_b128 v[194:197], v150 offset:7168
	global_load_lds_dwordx4 v136, s[2:3]
	s_add_i32 m0, s33, 0xe000
	s_nop 0
	global_load_lds_dwordx4 v138, s[2:3]
	s_waitcnt lgkmcnt(8)
	s_waitcnt vmcnt(8)
	s_setprio 1
	s_barrier
	s_waitcnt lgkmcnt(0)
	v_mfma_f32_16x16x32_bf16 v[124:127], v[140:143], v[166:169], 0
	v_mfma_f32_16x16x32_bf16 v[120:123], v[158:161], v[166:169], 0
	v_mfma_f32_16x16x32_bf16 v[108:111], v[140:143], v[174:177], 0
	v_mfma_f32_16x16x32_bf16 v[104:107], v[158:161], v[174:177], 0
	v_mfma_f32_16x16x32_bf16 v[92:95], v[140:143], v[182:185], 0
	v_mfma_f32_16x16x32_bf16 v[88:91], v[158:161], v[182:185], 0
	v_mfma_f32_16x16x32_bf16 v[76:79], v[140:143], v[190:193], 0
	v_mfma_f32_16x16x32_bf16 v[72:75], v[158:161], v[190:193], 0
	v_mfma_f32_16x16x32_bf16 v[124:127], v[154:157], v[170:173], v[124:127]
	v_mfma_f32_16x16x32_bf16 v[120:123], v[162:165], v[170:173], v[120:123]
	v_mfma_f32_16x16x32_bf16 v[108:111], v[154:157], v[178:181], v[108:111]
	v_mfma_f32_16x16x32_bf16 v[104:107], v[162:165], v[178:181], v[104:107]
	v_mfma_f32_16x16x32_bf16 v[92:95], v[154:157], v[186:189], v[92:95]
	v_mfma_f32_16x16x32_bf16 v[88:91], v[162:165], v[186:189], v[88:91]
	v_mfma_f32_16x16x32_bf16 v[76:79], v[154:157], v[194:197], v[76:79]
	v_mfma_f32_16x16x32_bf16 v[72:75], v[162:165], v[194:197], v[72:75]
	s_barrier
	s_setprio 0
	s_add_i32 s62, s47, s31
	s_mov_b32 m0, s62
	ds_read_b128 v[202:205], v151
	ds_read_b128 v[206:209], v151 offset:1024
	ds_read_b128 v[210:213], v151 offset:2048
	ds_read_b128 v[214:217], v151 offset:3072
	global_load_lds_dwordx4 v130, s[4:5]
	s_add_i32 m0, s62, 0x2000
	s_nop 0
	global_load_lds_dwordx4 v134, s[4:5]
	s_waitcnt vmcnt(8)
	s_setprio 1
	s_barrier
	s_waitcnt lgkmcnt(0)
	v_mfma_f32_16x16x32_bf16 v[116:119], v[202:205], v[166:169], 0
	v_mfma_f32_16x16x32_bf16 v[112:115], v[210:213], v[166:169], 0
	v_mfma_f32_16x16x32_bf16 v[100:103], v[202:205], v[174:177], 0
	v_mfma_f32_16x16x32_bf16 v[96:99], v[210:213], v[174:177], 0
	v_mfma_f32_16x16x32_bf16 v[84:87], v[202:205], v[182:185], 0
	v_mfma_f32_16x16x32_bf16 v[80:83], v[210:213], v[182:185], 0
	v_mfma_f32_16x16x32_bf16 v[68:71], v[202:205], v[190:193], 0
	v_mfma_f32_16x16x32_bf16 v[64:67], v[210:213], v[190:193], 0
	v_mfma_f32_16x16x32_bf16 v[116:119], v[206:209], v[170:173], v[116:119]
	v_mfma_f32_16x16x32_bf16 v[112:115], v[214:217], v[170:173], v[112:115]
	v_mfma_f32_16x16x32_bf16 v[100:103], v[206:209], v[178:181], v[100:103]
	v_mfma_f32_16x16x32_bf16 v[96:99], v[214:217], v[178:181], v[96:99]
	v_mfma_f32_16x16x32_bf16 v[84:87], v[206:209], v[186:189], v[84:87]
	v_mfma_f32_16x16x32_bf16 v[80:83], v[214:217], v[186:189], v[80:83]
	v_mfma_f32_16x16x32_bf16 v[68:71], v[206:209], v[194:197], v[68:71]
	v_mfma_f32_16x16x32_bf16 v[64:67], v[214:217], v[194:197], v[64:67]
	s_barrier
	s_setprio 0
	s_mov_b32 m0, s33
	v_lshl_add_u64 v[218:219], s[24:25], 0, v[128:129]
	ds_read_b128 v[166:169], v150 offset:16384
	ds_read_b128 v[170:173], v150 offset:17408
	ds_read_b128 v[174:177], v150 offset:18432
	ds_read_b128 v[178:181], v150 offset:19456
	ds_read_b128 v[182:185], v150 offset:20480
	ds_read_b128 v[186:189], v150 offset:21504
	ds_read_b128 v[190:193], v150 offset:22528
	ds_read_b128 v[194:197], v150 offset:23552
	global_load_lds_dwordx4 v128, s[24:25]
	v_lshl_add_u64 v[220:221], s[24:25], 0, v[132:133]
	s_mov_b32 m0, s34
	s_nop 0
	global_load_lds_dwordx4 v132, s[24:25]
	s_setprio 1
	s_barrier
	s_waitcnt lgkmcnt(0)
	v_mfma_f32_16x16x32_bf16 v[60:63], v[140:143], v[166:169], 0
	v_mfma_f32_16x16x32_bf16 v[56:59], v[158:161], v[166:169], 0
	v_mfma_f32_16x16x32_bf16 v[44:47], v[140:143], v[174:177], 0
	v_mfma_f32_16x16x32_bf16 v[40:43], v[158:161], v[174:177], 0
	v_mfma_f32_16x16x32_bf16 v[28:31], v[140:143], v[182:185], 0
	v_mfma_f32_16x16x32_bf16 v[24:27], v[158:161], v[182:185], 0
	v_mfma_f32_16x16x32_bf16 v[12:15], v[140:143], v[190:193], 0
	v_mfma_f32_16x16x32_bf16 v[8:11], v[158:161], v[190:193], 0
	v_mfma_f32_16x16x32_bf16 v[60:63], v[154:157], v[170:173], v[60:63]
	v_mfma_f32_16x16x32_bf16 v[56:59], v[162:165], v[170:173], v[56:59]
	v_mfma_f32_16x16x32_bf16 v[44:47], v[154:157], v[178:181], v[44:47]
	v_mfma_f32_16x16x32_bf16 v[40:43], v[162:165], v[178:181], v[40:43]
	v_mfma_f32_16x16x32_bf16 v[28:31], v[154:157], v[186:189], v[28:31]
	v_mfma_f32_16x16x32_bf16 v[24:27], v[162:165], v[186:189], v[24:27]
	v_mfma_f32_16x16x32_bf16 v[12:15], v[154:157], v[194:197], v[12:15]
	v_mfma_f32_16x16x32_bf16 v[8:11], v[162:165], v[194:197], v[8:11]
	s_barrier
; #define PG8_STAGE(bufoff, gbase, voff) do { _Pragma("unroll") for (int _i = 0; _i < 2; ++_i) \
;         __builtin_amdgcn_global_load_lds((const unsigned*)((const char*)(gbase) + (voff)[_i]), (LAS unsigned*)(lds + (bufoff) + ldsw + _i * 8192), 16, 0, 0); } while (0)
; #define PG8_LDA(dst, b, h) do { _Pragma("unroll") for (int m = 0; m < 4; ++m) _Pragma("unroll") for (int k = 0; k < 2; ++k) dst[m][k] = *(const LAS bf16x8*)(lds + PG8_SA(b, h) + aoff + m * 2048 + k * 1024); } while (0)
; #define PG8_LDB(dst, b, h) do { _Pragma("unroll") for (int n = 0; n < 2; ++n) _Pragma("unroll") for (int k = 0; k < 2; ++k) dst[n][k] = *(const LAS bf16x8*)(lds + PG8_SB(b, h) + boff + n * 2048 + k * 1024); } while (0)
; #define PG8_MMA(ai, bj, At, Bt) do { __builtin_amdgcn_s_setprio(1); _Pragma("unroll") for (int m = 0; m < 4; ++m) _Pragma("unroll") for (int n = 0; n < 2; ++n) _Pragma("unroll") for (int k = 0; k < 2; ++k) \
;         acc[ai][bj][m][n] = __builtin_amdgcn_mfma_f32_16x16x32_bf16(Bt[n][k], At[m][k], acc[ai][bj][m][n], 0, 0, 0); __builtin_amdgcn_s_setprio(0); } while (0)
; #define PG8_WAIT_V(n) asm volatile("s_waitcnt vmcnt(" #n ")" ::: "memory")
; #define PG8_WAIT_L(n) asm volatile("s_waitcnt lgkmcnt(" #n ")" ::: "memory")
; #define PG8_BAR __builtin_amdgcn_s_barrier()
; #define PG8_SCHED __builtin_amdgcn_sched_barrier(0)
; template <class Epi, class Sched>
; __device__ __forceinline__ void gemm_phase(LAS unsigned char* lds, const Gemm g, const Sched& S, const Epi& E) {
;     ...
;             PG8_STAGE(PG8_SB(0, 1), b2 + hstep, voffB);
;             PG8_WAIT_V(6); PG8_BAR; PG8_MMA(1, 1, At, B1); PG8_BAR;
;             PG8_LDB(B0, 1, 0); PG8_SCHED; PG8_LDA(At, 1, 0); PG8_STAGE(PG8_SA(0, 1), a2 + hstep, voffA);
;             PG8_WAIT_L(8); PG8_BAR; PG8_WAIT_L(0); PG8_MMA(0, 0, At, B0); PG8_BAR; PG8_SCHED;
;             PG8_LDB(B1, 1, 1); PG8_STAGE(PG8_SB(1, 0), b3, voffB);
;             PG8_BAR; PG8_WAIT_L(0); PG8_MMA(0, 1, At, B1); PG8_BAR;
;             PG8_LDA(At, 1, 1); PG8_STAGE(PG8_SA(1, 0), a3, voffA);
;             PG8_BAR; PG8_WAIT_L(0); PG8_MMA(1, 0, At, B0); PG8_BAR; PG8_SCHED;
;             PG8_STAGE(PG8_SB(1, 1), b3 + hstep, voffB);
;             PG8_WAIT_V(6); PG8_BAR; PG8_MMA(1, 1, At, B1); PG8_BAR;
	s_setprio 0
	s_add_u32 s62, s4, 0x40000
	s_addc_u32 s63, s5, 0
	s_add_i32 s64, s48, s31
	s_mov_b32 m0, s64
	s_nop 0
	global_load_lds_dwordx4 v130, s[62:63]
	s_add_i32 m0, s64, 0x2000
	s_nop 0
	global_load_lds_dwordx4 v134, s[62:63]
	s_add_u32 s24, s24, 0x40000
	s_addc_u32 s25, s25, 0
	s_mov_b32 m0, s35
	s_nop 0
	global_load_lds_dwordx4 v128, s[24:25]
	s_mov_b32 m0, s36
	s_nop 0
	global_load_lds_dwordx4 v132, s[24:25]
	s_waitcnt vmcnt(10)
	s_setprio 1
	s_barrier
	v_mfma_f32_16x16x32_bf16 v[52:55], v[202:205], v[166:169], 0
	v_mfma_f32_16x16x32_bf16 v[48:51], v[210:213], v[166:169], 0
	v_mfma_f32_16x16x32_bf16 v[36:39], v[202:205], v[174:177], 0
	v_mfma_f32_16x16x32_bf16 v[32:35], v[210:213], v[174:177], 0
	v_mfma_f32_16x16x32_bf16 v[20:23], v[202:205], v[182:185], 0
	v_mfma_f32_16x16x32_bf16 v[16:19], v[210:213], v[182:185], 0
	v_mfma_f32_16x16x32_bf16 v[4:7], v[202:205], v[190:193], 0
	v_mfma_f32_16x16x32_bf16 v[0:3], v[210:213], v[190:193], 0
	v_mfma_f32_16x16x32_bf16 v[52:55], v[206:209], v[170:173], v[52:55]
	v_mfma_f32_16x16x32_bf16 v[48:51], v[214:217], v[170:173], v[48:51]
	v_mfma_f32_16x16x32_bf16 v[36:39], v[206:209], v[178:181], v[36:39]
	v_mfma_f32_16x16x32_bf16 v[32:35], v[214:217], v[178:181], v[32:35]
	v_mfma_f32_16x16x32_bf16 v[20:23], v[206:209], v[186:189], v[20:23]
	v_mfma_f32_16x16x32_bf16 v[16:19], v[214:217], v[186:189], v[16:19]
	v_mfma_f32_16x16x32_bf16 v[4:7], v[206:209], v[194:197], v[4:7]
	v_mfma_f32_16x16x32_bf16 v[0:3], v[214:217], v[194:197], v[0:3]
	s_barrier
	s_setprio 0
	s_add_i32 s62, 0, 0x18000
	ds_read_b128 v[140:143], v151 offset:16384
	ds_read_b128 v[154:157], v151 offset:17408
	ds_read_b128 v[158:161], v151 offset:18432
	ds_read_b128 v[162:165], v151 offset:19456
	ds_read_b128 v[166:169], v150 offset:32768
	ds_read_b128 v[170:173], v150 offset:33792
	ds_read_b128 v[174:177], v150 offset:34816
	ds_read_b128 v[178:181], v150 offset:35840
	ds_read_b128 v[182:185], v150 offset:36864
	ds_read_b128 v[186:189], v150 offset:37888
	ds_read_b128 v[190:193], v150 offset:38912
	ds_read_b128 v[194:197], v150 offset:39936
	s_waitcnt lgkmcnt(8)
	s_waitcnt vmcnt(8)
	s_setprio 1
	s_barrier
	s_waitcnt lgkmcnt(0)
	v_mfma_f32_16x16x32_bf16 v[124:127], v[140:143], v[166:169], v[124:127]
	v_mfma_f32_16x16x32_bf16 v[120:123], v[158:161], v[166:169], v[120:123]
	v_mfma_f32_16x16x32_bf16 v[108:111], v[140:143], v[174:177], v[108:111]
	v_mfma_f32_16x16x32_bf16 v[104:107], v[158:161], v[174:177], v[104:107]
	v_mfma_f32_16x16x32_bf16 v[92:95], v[140:143], v[182:185], v[92:95]
	v_mfma_f32_16x16x32_bf16 v[88:91], v[158:161], v[182:185], v[88:91]
	v_mfma_f32_16x16x32_bf16 v[76:79], v[140:143], v[190:193], v[76:79]
	v_mfma_f32_16x16x32_bf16 v[72:75], v[158:161], v[190:193], v[72:75]
	v_mfma_f32_16x16x32_bf16 v[124:127], v[154:157], v[170:173], v[124:127]
	v_mfma_f32_16x16x32_bf16 v[120:123], v[162:165], v[170:173], v[120:123]
	v_mfma_f32_16x16x32_bf16 v[108:111], v[154:157], v[178:181], v[108:111]
	v_mfma_f32_16x16x32_bf16 v[104:107], v[162:165], v[178:181], v[104:107]
	v_mfma_f32_16x16x32_bf16 v[92:95], v[154:157], v[186:189], v[92:95]
	v_mfma_f32_16x16x32_bf16 v[88:91], v[162:165], v[186:189], v[88:91]
	v_mfma_f32_16x16x32_bf16 v[76:79], v[154:157], v[194:197], v[76:79]
	v_mfma_f32_16x16x32_bf16 v[72:75], v[162:165], v[194:197], v[72:75]
	s_barrier
	s_setprio 0
	s_add_i32 s24, 0, 0x1c000
	s_add_i32 s25, s62, s31
	v_add_u32_e32 v214, s24, v148
	s_add_u32 s0, s4, 0x80
	s_addc_u32 s1, s5, 0
	s_mov_b32 m0, s25
	ds_read_b128 v[202:205], v214
	ds_read_b128 v[206:209], v214 offset:1024
	ds_read_b128 v[210:213], v214 offset:2048
	ds_read_b128 v[214:217], v214 offset:3072
	global_load_lds_dwordx4 v130, s[0:1]
	s_add_i32 m0, s25, 0x2000
	s_nop 0
	global_load_lds_dwordx4 v134, s[0:1]
	s_waitcnt vmcnt(8)
	s_setprio 1
	s_barrier
	s_waitcnt lgkmcnt(0)
	v_mfma_f32_16x16x32_bf16 v[116:119], v[202:205], v[166:169], v[116:119]
	v_mfma_f32_16x16x32_bf16 v[112:115], v[210:213], v[166:169], v[112:115]
	v_mfma_f32_16x16x32_bf16 v[100:103], v[202:205], v[174:177], v[100:103]
	v_mfma_f32_16x16x32_bf16 v[96:99], v[210:213], v[174:177], v[96:99]
	v_mfma_f32_16x16x32_bf16 v[84:87], v[202:205], v[182:185], v[84:87]
	v_mfma_f32_16x16x32_bf16 v[80:83], v[210:213], v[182:185], v[80:83]
	v_mfma_f32_16x16x32_bf16 v[68:71], v[202:205], v[190:193], v[68:71]
	v_mfma_f32_16x16x32_bf16 v[64:67], v[210:213], v[190:193], v[64:67]
	v_mfma_f32_16x16x32_bf16 v[116:119], v[206:209], v[170:173], v[116:119]
	v_mfma_f32_16x16x32_bf16 v[112:115], v[214:217], v[170:173], v[112:115]
	v_mfma_f32_16x16x32_bf16 v[100:103], v[206:209], v[178:181], v[100:103]
	v_mfma_f32_16x16x32_bf16 v[96:99], v[214:217], v[178:181], v[96:99]
	v_mfma_f32_16x16x32_bf16 v[84:87], v[206:209], v[186:189], v[84:87]
	v_mfma_f32_16x16x32_bf16 v[80:83], v[214:217], v[186:189], v[80:83]
	v_mfma_f32_16x16x32_bf16 v[68:71], v[206:209], v[194:197], v[68:71]
	v_mfma_f32_16x16x32_bf16 v[64:67], v[214:217], v[194:197], v[64:67]
	s_barrier
	s_setprio 0
	s_mov_b32 m0, s44
	s_mov_b64 s[0:1], 0x80
	v_lshl_add_u64 v[144:145], v[218:219], 0, s[0:1]
	ds_read_b128 v[166:169], v150 offset:49152
	ds_read_b128 v[170:173], v150 offset:50176
	ds_read_b128 v[174:177], v150 offset:51200
	ds_read_b128 v[178:181], v150 offset:52224
	ds_read_b128 v[182:185], v150 offset:53248
	ds_read_b128 v[186:189], v150 offset:54272
	ds_read_b128 v[190:193], v150 offset:55296
	ds_read_b128 v[194:197], v150 offset:56320
	global_load_lds_dwordx4 v[144:145], off
	v_lshl_add_u64 v[144:145], v[220:221], 0, s[0:1]
	s_mov_b32 m0, s45
	s_nop 0
	global_load_lds_dwordx4 v[144:145], off
	s_setprio 1
	s_barrier
; #define PG8_STAGE(bufoff, gbase, voff) do { _Pragma("unroll") for (int _i = 0; _i < 2; ++_i) \
;         __builtin_amdgcn_global_load_lds((const unsigned*)((const char*)(gbase) + (voff)[_i]), (LAS unsigned*)(lds + (bufoff) + ldsw + _i * 8192), 16, 0, 0); } while (0)
; #define PG8_LDA(dst, b, h) do { _Pragma("unroll") for (int m = 0; m < 4; ++m) _Pragma("unroll") for (int k = 0; k < 2; ++k) dst[m][k] = *(const LAS bf16x8*)(lds + PG8_SA(b, h) + aoff + m * 2048 + k * 1024); } while (0)
; #define PG8_WAIT_V(n) asm volatile("s_waitcnt vmcnt(" #n ")" ::: "memory")
; #define PG8_WAIT_L(n) asm volatile("s_waitcnt lgkmcnt(" #n ")" ::: "memory")
; template <class Epi, class Sched>
; __device__ __forceinline__ void gemm_phase(LAS unsigned char* lds, const Gemm g, const Sched& S, const Epi& E) {
;     ...
;         for (int t = 0; t < nt; t += 2) {
;             const bool last = (t == nt - 2);
;             const char* a1 = cA + (size_t)(t + 1) * kstep;
;             const char* a2 = last ? nA : cA + (size_t)(t + 2) * kstep; const char* b2 = last ? nB : cB + (size_t)(t + 2) * kstep;
;             const char* a3 = a2 + kstep; const char* b3 = b2 + kstep;
;             PG8_LDB(B0, 0, 0); PG8_SCHED; PG8_LDA(At, 0, 0); PG8_STAGE(PG8_SA(1, 1), a1 + hstep, voffA);
;             PG8_WAIT_L(8); PG8_BAR; PG8_WAIT_L(0); PG8_MMA(0, 0, At, B0); PG8_BAR; PG8_SCHED;
;             PG8_LDB(B1, 0, 1); PG8_STAGE(PG8_SB(0, 0), b2, voffB);
;             PG8_BAR; PG8_WAIT_L(0); PG8_MMA(0, 1, At, B1); PG8_BAR;
;             PG8_LDA(At, 0, 1); PG8_STAGE(PG8_SA(0, 0), a2, voffA);
;             PG8_BAR; PG8_WAIT_L(0); PG8_MMA(1, 0, At, B0); PG8_BAR; PG8_SCHED;
;             PG8_STAGE(PG8_SB(0, 1), b2 + hstep, voffB);
;             PG8_WAIT_V(6); PG8_BAR; PG8_MMA(1, 1, At, B1); PG8_BAR;
;             PG8_LDB(B0, 1, 0); PG8_SCHED; PG8_LDA(At, 1, 0); PG8_STAGE(PG8_SA(0, 1), a2 + hstep, voffA);
;             PG8_WAIT_L(8); PG8_BAR; PG8_WAIT_L(0); PG8_MMA(0, 0, At, B0); PG8_BAR; PG8_SCHED;
;             PG8_LDB(B1, 1, 1); PG8_STAGE(PG8_SB(1, 0), b3, voffB);
;             PG8_BAR; PG8_WAIT_L(0); PG8_MMA(0, 1, At, B1); PG8_BAR;
;             PG8_LDA(At, 1, 1); PG8_STAGE(PG8_SA(1, 0), a3, voffA);
;             PG8_BAR; PG8_WAIT_L(0); PG8_MMA(1, 0, At, B0); PG8_BAR; PG8_SCHED;
;             PG8_STAGE(PG8_SB(1, 1), b3 + hstep, voffB);
;             PG8_WAIT_V(6); PG8_BAR; PG8_MMA(1, 1, At, B1); PG8_BAR;
	s_waitcnt lgkmcnt(0)
	v_mfma_f32_16x16x32_bf16 v[60:63], v[140:143], v[166:169], v[60:63]
	v_mfma_f32_16x16x32_bf16 v[56:59], v[158:161], v[166:169], v[56:59]
	v_mfma_f32_16x16x32_bf16 v[44:47], v[140:143], v[174:177], v[44:47]
	v_mfma_f32_16x16x32_bf16 v[40:43], v[158:161], v[174:177], v[40:43]
	v_mfma_f32_16x16x32_bf16 v[28:31], v[140:143], v[182:185], v[28:31]
	v_mfma_f32_16x16x32_bf16 v[24:27], v[158:161], v[182:185], v[24:27]
	v_mfma_f32_16x16x32_bf16 v[12:15], v[140:143], v[190:193], v[12:15]
	v_mfma_f32_16x16x32_bf16 v[8:11], v[158:161], v[190:193], v[8:11]
	v_mfma_f32_16x16x32_bf16 v[60:63], v[154:157], v[170:173], v[60:63]
	v_mfma_f32_16x16x32_bf16 v[56:59], v[162:165], v[170:173], v[56:59]
	v_mfma_f32_16x16x32_bf16 v[44:47], v[154:157], v[178:181], v[44:47]
	v_mfma_f32_16x16x32_bf16 v[40:43], v[162:165], v[178:181], v[40:43]
	v_mfma_f32_16x16x32_bf16 v[28:31], v[154:157], v[186:189], v[28:31]
	v_mfma_f32_16x16x32_bf16 v[24:27], v[162:165], v[186:189], v[24:27]
	v_mfma_f32_16x16x32_bf16 v[12:15], v[154:157], v[194:197], v[12:15]
	v_mfma_f32_16x16x32_bf16 v[8:11], v[162:165], v[194:197], v[8:11]
	s_barrier
	s_setprio 0
	s_add_u32 s4, s4, 0x40080
	s_addc_u32 s5, s5, 0
	s_add_i32 s24, s24, s31
	s_mov_b32 m0, s24
	s_nop 0
	global_load_lds_dwordx4 v130, s[4:5]
	s_add_i32 m0, s24, 0x2000
	s_nop 0
	global_load_lds_dwordx4 v134, s[4:5]
	s_waitcnt vmcnt(8)
	s_setprio 1
	s_barrier
	v_mfma_f32_16x16x32_bf16 v[52:55], v[202:205], v[166:169], v[52:55]
	v_mfma_f32_16x16x32_bf16 v[48:51], v[210:213], v[166:169], v[48:51]
	v_mfma_f32_16x16x32_bf16 v[36:39], v[202:205], v[174:177], v[36:39]
	v_mfma_f32_16x16x32_bf16 v[32:35], v[210:213], v[174:177], v[32:35]
	v_mfma_f32_16x16x32_bf16 v[20:23], v[202:205], v[182:185], v[20:23]
	v_mfma_f32_16x16x32_bf16 v[16:19], v[210:213], v[182:185], v[16:19]
	v_mfma_f32_16x16x32_bf16 v[4:7], v[202:205], v[190:193], v[4:7]
	v_mfma_f32_16x16x32_bf16 v[0:3], v[210:213], v[190:193], v[0:3]
	v_mfma_f32_16x16x32_bf16 v[52:55], v[206:209], v[170:173], v[52:55]
	v_mfma_f32_16x16x32_bf16 v[48:51], v[214:217], v[170:173], v[48:51]
	v_mfma_f32_16x16x32_bf16 v[36:39], v[206:209], v[178:181], v[36:39]
	v_mfma_f32_16x16x32_bf16 v[32:35], v[214:217], v[178:181], v[32:35]
	v_mfma_f32_16x16x32_bf16 v[20:23], v[206:209], v[186:189], v[20:23]
	v_mfma_f32_16x16x32_bf16 v[16:19], v[214:217], v[186:189], v[16:19]
	v_mfma_f32_16x16x32_bf16 v[4:7], v[206:209], v[194:197], v[4:7]
	v_mfma_f32_16x16x32_bf16 v[0:3], v[214:217], v[194:197], v[0:3]
	s_barrier
	s_setprio 0
	s_add_i32 s61, s61, 2
	s_add_u32 s2, s2, 0x100
	s_addc_u32 s3, s3, 0
	s_add_u32 s59, s59, 0x100
	s_addc_u32 s60, s60, 0
	s_cmp_gt_u32 s61, 13
.LBB0_693:
	ds_read_b128 v[140:143], v149
	ds_read_b128 v[154:157], v149 offset:1024
	ds_read_b128 v[158:161], v149 offset:2048
	ds_read_b128 v[162:165], v149 offset:3072
	s_add_u32 s4, s2, 0xfffc0080
	s_addc_u32 s5, s3, -1
	s_cmp_eq_u32 s61, 12
	s_cselect_b32 s25, s19, s5
	s_cselect_b32 s24, s57, s4
	s_cselect_b32 s5, s17, s60
	s_cselect_b32 s4, s58, s59
	s_add_i32 m0, s33, 0xc000
	ds_read_b128 v[166:169], v150
	ds_read_b128 v[170:173], v150 offset:1024
	ds_read_b128 v[174:177], v150 offset:2048
	ds_read_b128 v[178:181], v150 offset:3072
	ds_read_b128 v[182:185], v150 offset:4096
	ds_read_b128 v[186:189], v150 offset:5120
	ds_read_b128 v[190:193], v150 offset:6144
	ds_read_b128 v[194:197], v150 offset:7168
	global_load_lds_dwordx4 v136, s[2:3]
	s_add_i32 m0, s33, 0xe000
	s_nop 0
	global_load_lds_dwordx4 v138, s[2:3]
	s_waitcnt lgkmcnt(8)
	s_waitcnt vmcnt(8)
	s_setprio 1
	s_barrier
	s_waitcnt lgkmcnt(0)
	v_mfma_f32_16x16x32_bf16 v[124:127], v[140:143], v[166:169], v[124:127]
	v_mfma_f32_16x16x32_bf16 v[120:123], v[158:161], v[166:169], v[120:123]
	v_mfma_f32_16x16x32_bf16 v[108:111], v[140:143], v[174:177], v[108:111]
	v_mfma_f32_16x16x32_bf16 v[104:107], v[158:161], v[174:177], v[104:107]
	v_mfma_f32_16x16x32_bf16 v[92:95], v[140:143], v[182:185], v[92:95]
	v_mfma_f32_16x16x32_bf16 v[88:91], v[158:161], v[182:185], v[88:91]
	v_mfma_f32_16x16x32_bf16 v[76:79], v[140:143], v[190:193], v[76:79]
	v_mfma_f32_16x16x32_bf16 v[72:75], v[158:161], v[190:193], v[72:75]
	v_mfma_f32_16x16x32_bf16 v[124:127], v[154:157], v[170:173], v[124:127]
	v_mfma_f32_16x16x32_bf16 v[120:123], v[162:165], v[170:173], v[120:123]
	v_mfma_f32_16x16x32_bf16 v[108:111], v[154:157], v[178:181], v[108:111]
	v_mfma_f32_16x16x32_bf16 v[104:107], v[162:165], v[178:181], v[104:107]
	v_mfma_f32_16x16x32_bf16 v[92:95], v[154:157], v[186:189], v[92:95]
	v_mfma_f32_16x16x32_bf16 v[88:91], v[162:165], v[186:189], v[88:91]
	v_mfma_f32_16x16x32_bf16 v[76:79], v[154:157], v[194:197], v[76:79]
	v_mfma_f32_16x16x32_bf16 v[72:75], v[162:165], v[194:197], v[72:75]
	s_barrier
	s_setprio 0
	s_add_i32 s62, s47, s31
	s_mov_b32 m0, s62
	ds_read_b128 v[202:205], v151
	ds_read_b128 v[206:209], v151 offset:1024
	ds_read_b128 v[210:213], v151 offset:2048
	ds_read_b128 v[214:217], v151 offset:3072
	global_load_lds_dwordx4 v130, s[4:5]
	s_add_i32 m0, s62, 0x2000
	s_nop 0
	global_load_lds_dwordx4 v134, s[4:5]
	s_waitcnt vmcnt(8)
	s_setprio 1
	s_barrier
; #define PG8_STAGE(bufoff, gbase, voff) do { _Pragma("unroll") for (int _i = 0; _i < 2; ++_i) \
;         __builtin_amdgcn_global_load_lds((const unsigned*)((const char*)(gbase) + (voff)[_i]), (LAS unsigned*)(lds + (bufoff) + ldsw + _i * 8192), 16, 0, 0); } while (0)
; #define PG8_LDA(dst, b, h) do { _Pragma("unroll") for (int m = 0; m < 4; ++m) _Pragma("unroll") for (int k = 0; k < 2; ++k) dst[m][k] = *(const LAS bf16x8*)(lds + PG8_SA(b, h) + aoff + m * 2048 + k * 1024); } while (0)
; #define PG8_LDB(dst, b, h) do { _Pragma("unroll") for (int n = 0; n < 2; ++n) _Pragma("unroll") for (int k = 0; k < 2; ++k) dst[n][k] = *(const LAS bf16x8*)(lds + PG8_SB(b, h) + boff + n * 2048 + k * 1024); } while (0)
; #define PG8_MMA(ai, bj, At, Bt) do { __builtin_amdgcn_s_setprio(1); _Pragma("unroll") for (int m = 0; m < 4; ++m) _Pragma("unroll") for (int n = 0; n < 2; ++n) _Pragma("unroll") for (int k = 0; k < 2; ++k) \
;         acc[ai][bj][m][n] = __builtin_amdgcn_mfma_f32_16x16x32_bf16(Bt[n][k], At[m][k], acc[ai][bj][m][n], 0, 0, 0); __builtin_amdgcn_s_setprio(0); } while (0)
; #define PG8_WAIT_V(n) asm volatile("s_waitcnt vmcnt(" #n ")" ::: "memory")
; #define PG8_WAIT_L(n) asm volatile("s_waitcnt lgkmcnt(" #n ")" ::: "memory")
; #define PG8_BAR __builtin_amdgcn_s_barrier()
; #define PG8_SCHED __builtin_amdgcn_sched_barrier(0)
; template <class Epi, class Sched>
; __device__ __forceinline__ void gemm_phase(LAS unsigned char* lds, const Gemm g, const Sched& S, const Epi& E) {
;     ...
;             PG8_LDB(B1, 0, 1); PG8_STAGE(PG8_SB(0, 0), b2, voffB);
;             PG8_BAR; PG8_WAIT_L(0); PG8_MMA(0, 1, At, B1); PG8_BAR;
;             PG8_LDA(At, 0, 1); PG8_STAGE(PG8_SA(0, 0), a2, voffA);
;             PG8_BAR; PG8_WAIT_L(0); PG8_MMA(1, 0, At, B0); PG8_BAR; PG8_SCHED;
;             PG8_STAGE(PG8_SB(0, 1), b2 + hstep, voffB);
;             PG8_WAIT_V(6); PG8_BAR; PG8_MMA(1, 1, At, B1); PG8_BAR;
;             PG8_LDB(B0, 1, 0); PG8_SCHED; PG8_LDA(At, 1, 0); PG8_STAGE(PG8_SA(0, 1), a2 + hstep, voffA);
;             PG8_WAIT_L(8); PG8_BAR; PG8_WAIT_L(0); PG8_MMA(0, 0, At, B0); PG8_BAR; PG8_SCHED;
	s_waitcnt lgkmcnt(0)
	v_mfma_f32_16x16x32_bf16 v[116:119], v[202:205], v[166:169], v[116:119]
	v_mfma_f32_16x16x32_bf16 v[112:115], v[210:213], v[166:169], v[112:115]
	v_mfma_f32_16x16x32_bf16 v[100:103], v[202:205], v[174:177], v[100:103]
	v_mfma_f32_16x16x32_bf16 v[96:99], v[210:213], v[174:177], v[96:99]
	v_mfma_f32_16x16x32_bf16 v[84:87], v[202:205], v[182:185], v[84:87]
	v_mfma_f32_16x16x32_bf16 v[80:83], v[210:213], v[182:185], v[80:83]
	v_mfma_f32_16x16x32_bf16 v[68:71], v[202:205], v[190:193], v[68:71]
	v_mfma_f32_16x16x32_bf16 v[64:67], v[210:213], v[190:193], v[64:67]
	v_mfma_f32_16x16x32_bf16 v[116:119], v[206:209], v[170:173], v[116:119]
	v_mfma_f32_16x16x32_bf16 v[112:115], v[214:217], v[170:173], v[112:115]
	v_mfma_f32_16x16x32_bf16 v[100:103], v[206:209], v[178:181], v[100:103]
	v_mfma_f32_16x16x32_bf16 v[96:99], v[214:217], v[178:181], v[96:99]
	v_mfma_f32_16x16x32_bf16 v[84:87], v[206:209], v[186:189], v[84:87]
	v_mfma_f32_16x16x32_bf16 v[80:83], v[214:217], v[186:189], v[80:83]
	v_mfma_f32_16x16x32_bf16 v[68:71], v[206:209], v[194:197], v[68:71]
	v_mfma_f32_16x16x32_bf16 v[64:67], v[214:217], v[194:197], v[64:67]
	s_barrier
	s_setprio 0
	s_mov_b32 m0, s33
	v_lshl_add_u64 v[218:219], s[24:25], 0, v[128:129]
	ds_read_b128 v[166:169], v150 offset:16384
	ds_read_b128 v[170:173], v150 offset:17408
	ds_read_b128 v[174:177], v150 offset:18432
	ds_read_b128 v[178:181], v150 offset:19456
	ds_read_b128 v[182:185], v150 offset:20480
	ds_read_b128 v[186:189], v150 offset:21504
	ds_read_b128 v[190:193], v150 offset:22528
	ds_read_b128 v[194:197], v150 offset:23552
	global_load_lds_dwordx4 v128, s[24:25]
	v_lshl_add_u64 v[220:221], s[24:25], 0, v[132:133]
	s_mov_b32 m0, s34
	s_nop 0
	global_load_lds_dwordx4 v132, s[24:25]
	s_setprio 1
	s_barrier
	s_waitcnt lgkmcnt(0)
	v_mfma_f32_16x16x32_bf16 v[60:63], v[140:143], v[166:169], v[60:63]
	v_mfma_f32_16x16x32_bf16 v[56:59], v[158:161], v[166:169], v[56:59]
	v_mfma_f32_16x16x32_bf16 v[44:47], v[140:143], v[174:177], v[44:47]
	v_mfma_f32_16x16x32_bf16 v[40:43], v[158:161], v[174:177], v[40:43]
	v_mfma_f32_16x16x32_bf16 v[28:31], v[140:143], v[182:185], v[28:31]
	v_mfma_f32_16x16x32_bf16 v[24:27], v[158:161], v[182:185], v[24:27]
	v_mfma_f32_16x16x32_bf16 v[12:15], v[140:143], v[190:193], v[12:15]
	v_mfma_f32_16x16x32_bf16 v[8:11], v[158:161], v[190:193], v[8:11]
	v_mfma_f32_16x16x32_bf16 v[60:63], v[154:157], v[170:173], v[60:63]
	v_mfma_f32_16x16x32_bf16 v[56:59], v[162:165], v[170:173], v[56:59]
	v_mfma_f32_16x16x32_bf16 v[44:47], v[154:157], v[178:181], v[44:47]
	v_mfma_f32_16x16x32_bf16 v[40:43], v[162:165], v[178:181], v[40:43]
	v_mfma_f32_16x16x32_bf16 v[28:31], v[154:157], v[186:189], v[28:31]
	v_mfma_f32_16x16x32_bf16 v[24:27], v[162:165], v[186:189], v[24:27]
	v_mfma_f32_16x16x32_bf16 v[12:15], v[154:157], v[194:197], v[12:15]
	v_mfma_f32_16x16x32_bf16 v[8:11], v[162:165], v[194:197], v[8:11]
	s_barrier
	s_setprio 0
	s_add_u32 s62, s4, 0x40000
	s_addc_u32 s63, s5, 0
	s_add_i32 s64, s48, s31
	s_mov_b32 m0, s64
	s_nop 0
	global_load_lds_dwordx4 v130, s[62:63]
	s_add_i32 m0, s64, 0x2000
	s_nop 0
	global_load_lds_dwordx4 v134, s[62:63]
	s_add_u32 s24, s24, 0x40000
	s_addc_u32 s25, s25, 0
	s_mov_b32 m0, s35
	s_nop 0
	global_load_lds_dwordx4 v128, s[24:25]
	s_mov_b32 m0, s36
	s_nop 0
	global_load_lds_dwordx4 v132, s[24:25]
	s_waitcnt vmcnt(10)
	s_setprio 1
	s_barrier
	v_mfma_f32_16x16x32_bf16 v[52:55], v[202:205], v[166:169], v[52:55]
	v_mfma_f32_16x16x32_bf16 v[48:51], v[210:213], v[166:169], v[48:51]
	v_mfma_f32_16x16x32_bf16 v[36:39], v[202:205], v[174:177], v[36:39]
	v_mfma_f32_16x16x32_bf16 v[32:35], v[210:213], v[174:177], v[32:35]
	v_mfma_f32_16x16x32_bf16 v[20:23], v[202:205], v[182:185], v[20:23]
	v_mfma_f32_16x16x32_bf16 v[16:19], v[210:213], v[182:185], v[16:19]
	v_mfma_f32_16x16x32_bf16 v[4:7], v[202:205], v[190:193], v[4:7]
	v_mfma_f32_16x16x32_bf16 v[0:3], v[210:213], v[190:193], v[0:3]
	v_mfma_f32_16x16x32_bf16 v[52:55], v[206:209], v[170:173], v[52:55]
	v_mfma_f32_16x16x32_bf16 v[48:51], v[214:217], v[170:173], v[48:51]
	v_mfma_f32_16x16x32_bf16 v[36:39], v[206:209], v[178:181], v[36:39]
	v_mfma_f32_16x16x32_bf16 v[32:35], v[214:217], v[178:181], v[32:35]
	v_mfma_f32_16x16x32_bf16 v[20:23], v[206:209], v[186:189], v[20:23]
	v_mfma_f32_16x16x32_bf16 v[16:19], v[214:217], v[186:189], v[16:19]
	v_mfma_f32_16x16x32_bf16 v[4:7], v[206:209], v[194:197], v[4:7]
	v_mfma_f32_16x16x32_bf16 v[0:3], v[214:217], v[194:197], v[0:3]
	s_barrier
	s_setprio 0
	s_add_i32 s62, 0, 0x18000
	ds_read_b128 v[140:143], v151 offset:16384
	ds_read_b128 v[154:157], v151 offset:17408
	ds_read_b128 v[158:161], v151 offset:18432
	ds_read_b128 v[162:165], v151 offset:19456
	ds_read_b128 v[166:169], v150 offset:32768
	ds_read_b128 v[170:173], v150 offset:33792
	ds_read_b128 v[174:177], v150 offset:34816
	ds_read_b128 v[178:181], v150 offset:35840
	ds_read_b128 v[182:185], v150 offset:36864
	ds_read_b128 v[186:189], v150 offset:37888
	ds_read_b128 v[190:193], v150 offset:38912
	ds_read_b128 v[194:197], v150 offset:39936
	s_waitcnt lgkmcnt(8)
	s_waitcnt vmcnt(8)
	s_setprio 1
	s_barrier
; #define PG8_STAGE(bufoff, gbase, voff) do { _Pragma("unroll") for (int _i = 0; _i < 2; ++_i) \
;         __builtin_amdgcn_global_load_lds((const unsigned*)((const char*)(gbase) + (voff)[_i]), (LAS unsigned*)(lds + (bufoff) + ldsw + _i * 8192), 16, 0, 0); } while (0)
; #define PG8_LDA(dst, b, h) do { _Pragma("unroll") for (int m = 0; m < 4; ++m) _Pragma("unroll") for (int k = 0; k < 2; ++k) dst[m][k] = *(const LAS bf16x8*)(lds + PG8_SA(b, h) + aoff + m * 2048 + k * 1024); } while (0)
; #define PG8_LDB(dst, b, h) do { _Pragma("unroll") for (int n = 0; n < 2; ++n) _Pragma("unroll") for (int k = 0; k < 2; ++k) dst[n][k] = *(const LAS bf16x8*)(lds + PG8_SB(b, h) + boff + n * 2048 + k * 1024); } while (0)
; #define PG8_MMA(ai, bj, At, Bt) do { __builtin_amdgcn_s_setprio(1); _Pragma("unroll") for (int m = 0; m < 4; ++m) _Pragma("unroll") for (int n = 0; n < 2; ++n) _Pragma("unroll") for (int k = 0; k < 2; ++k) \
;         acc[ai][bj][m][n] = __builtin_amdgcn_mfma_f32_16x16x32_bf16(Bt[n][k], At[m][k], acc[ai][bj][m][n], 0, 0, 0); __builtin_amdgcn_s_setprio(0); } while (0)
; #define PG8_WAIT_V(n) asm volatile("s_waitcnt vmcnt(" #n ")" ::: "memory")
; #define PG8_WAIT_L(n) asm volatile("s_waitcnt lgkmcnt(" #n ")" ::: "memory")
; #define PG8_BAR __builtin_amdgcn_s_barrier()
; #define PG8_SCHED __builtin_amdgcn_sched_barrier(0)
; template <class Epi, class Sched>
; __device__ __forceinline__ void gemm_phase(LAS unsigned char* lds, const Gemm g, const Sched& S, const Epi& E) {
;     ...
;             PG8_WAIT_L(8); PG8_BAR; PG8_WAIT_L(0); PG8_MMA(0, 0, At, B0); PG8_BAR; PG8_SCHED;
;             PG8_LDB(B1, 1, 1); PG8_STAGE(PG8_SB(1, 0), b3, voffB);
;             PG8_BAR; PG8_WAIT_L(0); PG8_MMA(0, 1, At, B1); PG8_BAR;
;             PG8_LDA(At, 1, 1); PG8_STAGE(PG8_SA(1, 0), a3, voffA);
;             PG8_BAR; PG8_WAIT_L(0); PG8_MMA(1, 0, At, B0); PG8_BAR; PG8_SCHED;
;             PG8_STAGE(PG8_SB(1, 1), b3 + hstep, voffB);
;             PG8_WAIT_V(6); PG8_BAR; PG8_MMA(1, 1, At, B1); PG8_BAR;
	s_waitcnt lgkmcnt(0)
	v_mfma_f32_16x16x32_bf16 v[124:127], v[140:143], v[166:169], v[124:127]
	v_mfma_f32_16x16x32_bf16 v[120:123], v[158:161], v[166:169], v[120:123]
	v_mfma_f32_16x16x32_bf16 v[108:111], v[140:143], v[174:177], v[108:111]
	v_mfma_f32_16x16x32_bf16 v[104:107], v[158:161], v[174:177], v[104:107]
	v_mfma_f32_16x16x32_bf16 v[92:95], v[140:143], v[182:185], v[92:95]
	v_mfma_f32_16x16x32_bf16 v[88:91], v[158:161], v[182:185], v[88:91]
	v_mfma_f32_16x16x32_bf16 v[76:79], v[140:143], v[190:193], v[76:79]
	v_mfma_f32_16x16x32_bf16 v[72:75], v[158:161], v[190:193], v[72:75]
	v_mfma_f32_16x16x32_bf16 v[124:127], v[154:157], v[170:173], v[124:127]
	v_mfma_f32_16x16x32_bf16 v[120:123], v[162:165], v[170:173], v[120:123]
	v_mfma_f32_16x16x32_bf16 v[108:111], v[154:157], v[178:181], v[108:111]
	v_mfma_f32_16x16x32_bf16 v[104:107], v[162:165], v[178:181], v[104:107]
	v_mfma_f32_16x16x32_bf16 v[92:95], v[154:157], v[186:189], v[92:95]
	v_mfma_f32_16x16x32_bf16 v[88:91], v[162:165], v[186:189], v[88:91]
	v_mfma_f32_16x16x32_bf16 v[76:79], v[154:157], v[194:197], v[76:79]
	v_mfma_f32_16x16x32_bf16 v[72:75], v[162:165], v[194:197], v[72:75]
	s_barrier
	s_setprio 0
	s_add_i32 s24, 0, 0x1c000
	s_add_i32 s25, s62, s31
	v_add_u32_e32 v214, s24, v148
	s_add_u32 s0, s4, 0x80
	s_addc_u32 s1, s5, 0
	s_mov_b32 m0, s25
	ds_read_b128 v[202:205], v214
	ds_read_b128 v[206:209], v214 offset:1024
	ds_read_b128 v[210:213], v214 offset:2048
	ds_read_b128 v[214:217], v214 offset:3072
	global_load_lds_dwordx4 v130, s[0:1]
	s_add_i32 m0, s25, 0x2000
	s_nop 0
	global_load_lds_dwordx4 v134, s[0:1]
	s_waitcnt vmcnt(8)
	s_setprio 1
	s_barrier
	s_waitcnt lgkmcnt(0)
	v_mfma_f32_16x16x32_bf16 v[116:119], v[202:205], v[166:169], v[116:119]
	v_mfma_f32_16x16x32_bf16 v[112:115], v[210:213], v[166:169], v[112:115]
	v_mfma_f32_16x16x32_bf16 v[100:103], v[202:205], v[174:177], v[100:103]
	v_mfma_f32_16x16x32_bf16 v[96:99], v[210:213], v[174:177], v[96:99]
	v_mfma_f32_16x16x32_bf16 v[84:87], v[202:205], v[182:185], v[84:87]
	v_mfma_f32_16x16x32_bf16 v[80:83], v[210:213], v[182:185], v[80:83]
	v_mfma_f32_16x16x32_bf16 v[68:71], v[202:205], v[190:193], v[68:71]
	v_mfma_f32_16x16x32_bf16 v[64:67], v[210:213], v[190:193], v[64:67]
	v_mfma_f32_16x16x32_bf16 v[116:119], v[206:209], v[170:173], v[116:119]
	v_mfma_f32_16x16x32_bf16 v[112:115], v[214:217], v[170:173], v[112:115]
	v_mfma_f32_16x16x32_bf16 v[100:103], v[206:209], v[178:181], v[100:103]
	v_mfma_f32_16x16x32_bf16 v[96:99], v[214:217], v[178:181], v[96:99]
	v_mfma_f32_16x16x32_bf16 v[84:87], v[206:209], v[186:189], v[84:87]
	v_mfma_f32_16x16x32_bf16 v[80:83], v[214:217], v[186:189], v[80:83]
	v_mfma_f32_16x16x32_bf16 v[68:71], v[206:209], v[194:197], v[68:71]
	v_mfma_f32_16x16x32_bf16 v[64:67], v[214:217], v[194:197], v[64:67]
	s_barrier
	s_setprio 0
	s_mov_b32 m0, s44
	s_mov_b64 s[0:1], 0x80
	v_lshl_add_u64 v[144:145], v[218:219], 0, s[0:1]
	ds_read_b128 v[166:169], v150 offset:49152
	ds_read_b128 v[170:173], v150 offset:50176
	ds_read_b128 v[174:177], v150 offset:51200
	ds_read_b128 v[178:181], v150 offset:52224
	ds_read_b128 v[182:185], v150 offset:53248
	ds_read_b128 v[186:189], v150 offset:54272
	ds_read_b128 v[190:193], v150 offset:55296
	ds_read_b128 v[194:197], v150 offset:56320
	global_load_lds_dwordx4 v[144:145], off
	v_lshl_add_u64 v[144:145], v[220:221], 0, s[0:1]
	s_mov_b32 m0, s45
	s_nop 0
	global_load_lds_dwordx4 v[144:145], off
	s_setprio 1
	s_barrier
	s_waitcnt lgkmcnt(0)
	v_mfma_f32_16x16x32_bf16 v[60:63], v[140:143], v[166:169], v[60:63]
	v_mfma_f32_16x16x32_bf16 v[56:59], v[158:161], v[166:169], v[56:59]
	v_mfma_f32_16x16x32_bf16 v[44:47], v[140:143], v[174:177], v[44:47]
	v_mfma_f32_16x16x32_bf16 v[40:43], v[158:161], v[174:177], v[40:43]
	v_mfma_f32_16x16x32_bf16 v[28:31], v[140:143], v[182:185], v[28:31]
	v_mfma_f32_16x16x32_bf16 v[24:27], v[158:161], v[182:185], v[24:27]
	v_mfma_f32_16x16x32_bf16 v[12:15], v[140:143], v[190:193], v[12:15]
	v_mfma_f32_16x16x32_bf16 v[8:11], v[158:161], v[190:193], v[8:11]
	v_mfma_f32_16x16x32_bf16 v[60:63], v[154:157], v[170:173], v[60:63]
	v_mfma_f32_16x16x32_bf16 v[56:59], v[162:165], v[170:173], v[56:59]
	v_mfma_f32_16x16x32_bf16 v[44:47], v[154:157], v[178:181], v[44:47]
	v_mfma_f32_16x16x32_bf16 v[40:43], v[162:165], v[178:181], v[40:43]
	v_mfma_f32_16x16x32_bf16 v[28:31], v[154:157], v[186:189], v[28:31]
	v_mfma_f32_16x16x32_bf16 v[24:27], v[162:165], v[186:189], v[24:27]
	v_mfma_f32_16x16x32_bf16 v[12:15], v[154:157], v[194:197], v[12:15]
	v_mfma_f32_16x16x32_bf16 v[8:11], v[162:165], v[194:197], v[8:11]
	s_barrier
	s_setprio 0
	s_add_u32 s4, s4, 0x40080
	s_addc_u32 s5, s5, 0
	s_add_i32 s24, s24, s31
	s_mov_b32 m0, s24
	s_nop 0
	global_load_lds_dwordx4 v130, s[4:5]
	s_add_i32 m0, s24, 0x2000
	s_nop 0
	global_load_lds_dwordx4 v134, s[4:5]
	s_waitcnt vmcnt(8)
	s_setprio 1
	s_barrier
	v_mfma_f32_16x16x32_bf16 v[52:55], v[202:205], v[166:169], v[52:55]
	v_mfma_f32_16x16x32_bf16 v[48:51], v[210:213], v[166:169], v[48:51]
	v_mfma_f32_16x16x32_bf16 v[36:39], v[202:205], v[174:177], v[36:39]
	v_mfma_f32_16x16x32_bf16 v[32:35], v[210:213], v[174:177], v[32:35]
	v_mfma_f32_16x16x32_bf16 v[20:23], v[202:205], v[182:185], v[20:23]
	v_mfma_f32_16x16x32_bf16 v[16:19], v[210:213], v[182:185], v[16:19]
	v_mfma_f32_16x16x32_bf16 v[4:7], v[202:205], v[190:193], v[4:7]
	v_mfma_f32_16x16x32_bf16 v[0:3], v[210:213], v[190:193], v[0:3]
	v_mfma_f32_16x16x32_bf16 v[52:55], v[206:209], v[170:173], v[52:55]
	v_mfma_f32_16x16x32_bf16 v[48:51], v[214:217], v[170:173], v[48:51]
	v_mfma_f32_16x16x32_bf16 v[36:39], v[206:209], v[178:181], v[36:39]
	v_mfma_f32_16x16x32_bf16 v[32:35], v[214:217], v[178:181], v[32:35]
	v_mfma_f32_16x16x32_bf16 v[20:23], v[206:209], v[186:189], v[20:23]
	v_mfma_f32_16x16x32_bf16 v[16:19], v[214:217], v[186:189], v[16:19]
	v_mfma_f32_16x16x32_bf16 v[4:7], v[206:209], v[194:197], v[4:7]
	v_mfma_f32_16x16x32_bf16 v[0:3], v[214:217], v[194:197], v[0:3]
	s_barrier
;     __device__ __forceinline__ void operator()(const AccT& acc, const Unit& u, int wr, int wc, int fr, int fq) const {
;     ...
;         const int rbase = wr * 64 + fr;
;         const int tb = u.pn * 256 + wc * 32 + 8 * fq;
;         const int o0 = wc * 32 + 8 * fq;
;         const int j = fr & 3; const float sgn = ((fr >> 2) & 1) ? 1.0f : -1.0f;
; #pragma unroll
;         for (int ai = 0; ai < 2; ++ai) {
;             const int hh = 2 * ai + wr;
;             const float l2f = lgd[hh] * 1.4426950408889634f, l2b = lgd[4 + hh] * 1.4426950408889634f;
;             const float zf0 = exp2f((float)(127 - o0) * l2f), zfs = exp2f(-l2f), zb0 = exp2f((float)o0 * l2b), zbs = exp2f(l2b);
; #pragma unroll
;             for (int m = 0; m < 4; ++m) {
;                 const int r = rbase + ai * 128 + m * 16;
;                 const int d = 4 * (2 * m + (fr >> 3)) + j;
; #pragma unroll
;                 for (int bj = 0; bj < 2; ++bj) {
;                     const int t0 = tb + bj * 128;
;                     float v[8];
; #pragma unroll
;                     for (int jj = 0; jj < 4; ++jj) { v[jj] = acc[ai][bj][m][0][jj]; v[4 + jj] = acc[ai][bj][m][1][jj]; }
;                     if constexpr (ROPE) {
;                         const int t = t0 & 2047;
; #pragma unroll
;                         for (int hf = 0; hf < 2; ++hf) {
;                             f32x4 cs, sn;
;                             if (m < 2) { const float c1 = ropeA[(t >> 6) * 16 + d], s1 = ropeA[1024 + (t >> 6) * 16 + d]; cs = (f32x4){c1, c1, c1, c1}; sn = (f32x4){s1, s1, s1, s1}; }
;                             else { const float* cb = ropeA + 2048 + (d - 16) * 64 + (t & 63) + 4 * hf; cs = *(const f32x4*)(cb); sn = *(const f32x4*)(cb + 1024); }
; #pragma unroll
;                             for (int jj = 0; jj < 4; ++jj) { const float pr = __shfl_xor(v[4 * hf + jj], 4); v[4 * hf + jj] = v[4 * hf + jj] * cs[jj] + sgn * pr * sn[jj]; }
;                             __builtin_amdgcn_sched_barrier(0);
;                         }
;                     }
;                     float zf[8], zb[8]; zf[0] = zf0; zb[0] = zb0;
; #pragma unroll
;                     for (int jj = 1; jj < 8; ++jj) { zf[jj] = zf[jj - 1] * zfs; zb[jj] = zb[jj - 1] * zbs; }
;                     u32x4 wf, wb;
	s_setprio 0
	s_add_i32 s61, s61, 2
	s_add_u32 s2, s2, 0x100
	s_addc_u32 s3, s3, 0
	s_add_u32 s59, s59, 0x100
	s_addc_u32 s60, s60, 0
	s_cmp_gt_u32 s61, 13
	s_cbranch_scc0 .LBB0_693
	v_mov_b32_e32 v141, v147
	v_mov_b32_e32 v140, v146
	global_load_dword v156, v131, s[6:7]
	global_load_dword v157, v131, s[6:7] offset:16
	s_lshl_b32 s2, s56, 8
	s_or_b32 s2, s2, s43
	v_add_u32_e32 v140, s42, v140
	v_lshlrev_b32_e32 v141, 3, v141
	v_add_u32_e32 v142, s2, v141
	v_add_u32_e32 v143, s43, v141
	v_ashrrev_i32_e32 v141, 31, v140
	v_sub_u32_e32 v144, 0x7f, v143
	v_lshlrev_b64 v[140:141], 14, v[140:141]
	v_cvt_f32_i32_e32 v154, v143
	v_ashrrev_i32_e32 v143, 31, v142
	v_cvt_f32_i32_e32 v155, v144
	v_lshl_add_u64 v[140:141], s[70:71], 0, v[140:141]
	s_mov_b32 s3, 0x400000
	v_lshl_add_u64 v[140:141], v[142:143], 1, v[140:141]
	v_add_co_u32_e32 v144, vcc, s3, v140
	s_mov_b64 s[4:5], 0x400000
	s_nop 0
	v_addc_co_u32_e32 v145, vcc, 0, v141, vcc
	v_lshl_add_u64 v[142:143], v[140:141], 0, s[4:5]
	s_waitcnt vmcnt(0)
	v_mul_f32_e32 v158, 0x3fb8aa3b, v156
	v_mul_f32_e32 v159, 0x3fb8aa3b, v157
	v_mul_f32_e32 v160, v158, v155
	v_cmp_lt_f32_e32 vcc, s51, v158
	v_mul_f32_e32 v162, v159, v154
	v_cmp_gt_f32_e64 s[2:3], s49, v159
	v_cndmask_b32_e32 v161, 0, v153, vcc
	v_cmp_gt_f32_e64 s[4:5], s49, v160
	v_cndmask_b32_e64 v163, 0, v153, s[2:3]
	s_and_b64 s[24:25], vcc, exec
	v_cmp_gt_f32_e32 vcc, s49, v162
	v_fmac_f32_e32 v163, 0x3fb8aa3b, v157
	v_cndmask_b32_e64 v157, 0, v153, s[4:5]
	v_cndmask_b32_e32 v162, 0, v153, vcc
	v_fmac_f32_e32 v161, 0xbfb8aa3b, v156
	v_fmac_f32_e32 v157, v158, v155
	v_fmac_f32_e32 v162, v159, v154
	v_exp_f32_e32 v161, v161
	v_exp_f32_e32 v163, v163
	v_exp_f32_e32 v157, v157
	v_exp_f32_e32 v158, v162
	v_cndmask_b32_e64 v160, 0, v152, s[4:5]
	s_cselect_b32 s4, 0xffffffc0, 0
	s_and_b64 s[2:3], s[2:3], exec
	v_cndmask_b32_e32 v156, 0, v152, vcc
	s_cselect_b32 s2, 0xffffffc0, 0
	v_ldexp_f32 v161, v161, s4
	v_ldexp_f32 v162, v163, s2
	v_ldexp_f32 v163, v157, v160
	v_ldexp_f32 v156, v158, v156
	v_mul_f32_e32 v164, v161, v163
	v_mul_f32_e32 v157, v162, v156
	v_mul_f32_e32 v158, v124, v163
	v_mul_f32_e32 v165, v124, v156
	v_mul_f32_e32 v166, v161, v164
	v_mul_f32_e32 v124, v162, v157
	v_mul_f32_e32 v159, v125, v164
	v_mul_f32_e32 v167, v125, v157
	v_mul_f32_e32 v168, v161, v166
	v_mul_f32_e32 v125, v162, v124
	v_cvt_pk_bf16_f32 v158, v158, v159
	v_mul_f32_e32 v159, v126, v166
	v_mul_f32_e32 v169, v126, v124
	v_mul_f32_e32 v170, v161, v168
	v_mul_f32_e32 v126, v162, v125
	v_mul_f32_e32 v171, v161, v170
	v_mul_f32_e32 v172, v162, v126
	v_mul_f32_e32 v160, v127, v168
	v_mul_f32_e32 v174, v161, v171
	v_mul_f32_e32 v175, v162, v172
	v_cvt_pk_bf16_f32 v159, v159, v160
	v_mul_f32_e32 v160, v120, v170
	v_mul_f32_e32 v173, v120, v126
	v_mul_f32_e32 v120, v121, v171
	v_mul_f32_e32 v177, v161, v174
	v_mul_f32_e32 v162, v162, v175
	v_mul_f32_e32 v176, v121, v172
	v_cvt_pk_bf16_f32 v160, v160, v120
	v_mul_f32_e32 v120, v122, v174
	v_mul_f32_e32 v121, v123, v177
	v_mul_f32_e32 v123, v123, v162
	v_cvt_pk_bf16_f32 v161, v120, v121
	v_mul_f32_e32 v127, v127, v125
	v_mul_f32_e32 v178, v122, v175
	v_cvt_pk_bf16_f32 v120, v165, v167
	v_cvt_pk_bf16_f32 v121, v169, v127
	v_cvt_pk_bf16_f32 v122, v173, v176
	v_cvt_pk_bf16_f32 v123, v178, v123
	global_store_dwordx4 v[140:141], v[158:161], off
	global_store_dwordx4 v[144:145], v[120:123], off
	s_nop 1
	v_mul_f32_e32 v120, v116, v163
	v_mul_f32_e32 v121, v117, v164
	v_cvt_pk_bf16_f32 v120, v120, v121
	v_mul_f32_e32 v121, v118, v166
	v_mul_f32_e32 v122, v119, v168
	v_cvt_pk_bf16_f32 v121, v121, v122
	v_mul_f32_e32 v122, v112, v170
	v_mul_f32_e32 v123, v113, v171
	v_cvt_pk_bf16_f32 v122, v122, v123
	v_mul_f32_e32 v123, v114, v174
	v_mul_f32_e32 v116, v116, v156
	v_mul_f32_e32 v117, v117, v157
	v_mul_f32_e32 v127, v115, v177
	v_cvt_pk_bf16_f32 v123, v123, v127
	v_cvt_pk_bf16_f32 v116, v116, v117
	v_mul_f32_e32 v117, v118, v124
	v_mul_f32_e32 v118, v119, v125
	v_mul_f32_e32 v112, v112, v126
	v_mul_f32_e32 v113, v113, v172
	v_cvt_pk_bf16_f32 v117, v117, v118
	v_cvt_pk_bf16_f32 v118, v112, v113
	v_mul_f32_e32 v112, v114, v175
	v_mul_f32_e32 v113, v115, v162
	v_cvt_pk_bf16_f32 v119, v112, v113
	global_store_dwordx4 v[140:141], v[120:123], off offset:256
	global_store_dwordx4 v[142:143], v[116:119], off offset:256
	v_mul_f32_e32 v112, v108, v163
	v_mul_f32_e32 v113, v109, v164
	v_cvt_pk_bf16_f32 v112, v112, v113
	v_mul_f32_e32 v113, v110, v166
	v_mul_f32_e32 v114, v111, v168
	v_cvt_pk_bf16_f32 v113, v113, v114
	v_mul_f32_e32 v114, v104, v170
	v_mul_f32_e32 v115, v105, v171
	v_cvt_pk_bf16_f32 v114, v114, v115
	v_mul_f32_e32 v115, v106, v174
	v_mul_f32_e32 v108, v108, v156
	v_mul_f32_e32 v109, v109, v157
	v_mul_f32_e32 v116, v107, v177
	v_cvt_pk_bf16_f32 v115, v115, v116
	v_cvt_pk_bf16_f32 v108, v108, v109
	v_mul_f32_e32 v109, v110, v124
	v_mul_f32_e32 v110, v111, v125
	v_mul_f32_e32 v104, v104, v126
	s_mov_b64 s[2:3], 0x40000
	v_cvt_pk_bf16_f32 v109, v109, v110
	v_mul_f32_e32 v105, v105, v172
	v_cvt_pk_bf16_f32 v110, v104, v105
	v_mul_f32_e32 v104, v106, v175
	v_lshl_add_u64 v[116:117], v[140:141], 0, s[2:3]
	s_mov_b32 s2, 0x40000
	v_mul_f32_e32 v105, v107, v162
	v_cvt_pk_bf16_f32 v111, v104, v105
	v_add_co_u32_e32 v104, vcc, s2, v140
	s_mov_b64 s[2:3], 0x440000
	s_nop 0
	v_addc_co_u32_e32 v105, vcc, 0, v141, vcc
	global_store_dwordx4 v[104:105], v[112:115], off
	s_nop 1
	v_lshl_add_u64 v[112:113], v[140:141], 0, s[2:3]
	s_mov_b32 s2, 0x440000
	v_add_co_u32_e32 v104, vcc, s2, v140
	s_nop 1
	v_addc_co_u32_e32 v105, vcc, 0, v141, vcc
	global_store_dwordx4 v[104:105], v[108:111], off
	v_mul_f32_e32 v104, v100, v163
	v_mul_f32_e32 v105, v101, v164
;     __device__ __forceinline__ void operator()(const AccT& acc, const Unit& u, int wr, int wc, int fr, int fq) const {
;     ...
;             for (int m = 0; m < 4; ++m) {
;                 const int r = rbase + ai * 128 + m * 16;
;                 const int d = 4 * (2 * m + (fr >> 3)) + j;
; #pragma unroll
;                 for (int bj = 0; bj < 2; ++bj) {
;                     const int t0 = tb + bj * 128;
;                     float v[8];
; #pragma unroll
;                     for (int jj = 0; jj < 4; ++jj) { v[jj] = acc[ai][bj][m][0][jj]; v[4 + jj] = acc[ai][bj][m][1][jj]; }
;                     if constexpr (ROPE) {
;                         const int t = t0 & 2047;
; #pragma unroll
;                         for (int hf = 0; hf < 2; ++hf) {
;                             f32x4 cs, sn;
;                             if (m < 2) { const float c1 = ropeA[(t >> 6) * 16 + d], s1 = ropeA[1024 + (t >> 6) * 16 + d]; cs = (f32x4){c1, c1, c1, c1}; sn = (f32x4){s1, s1, s1, s1}; }
;                             else { const float* cb = ropeA + 2048 + (d - 16) * 64 + (t & 63) + 4 * hf; cs = *(const f32x4*)(cb); sn = *(const f32x4*)(cb + 1024); }
; #pragma unroll
;                             for (int jj = 0; jj < 4; ++jj) { const float pr = __shfl_xor(v[4 * hf + jj], 4); v[4 * hf + jj] = v[4 * hf + jj] * cs[jj] + sgn * pr * sn[jj]; }
;                             __builtin_amdgcn_sched_barrier(0);
;                         }
;                     }
;                     float zf[8], zb[8]; zf[0] = zf0; zb[0] = zb0;
; #pragma unroll
;                     for (int jj = 1; jj < 8; ++jj) { zf[jj] = zf[jj - 1] * zfs; zb[jj] = zb[jj - 1] * zbs; }
;                     u32x4 wf, wb;
;                     wf.x = cvt_pk_bf16(v[0] * zf[0], v[1] * zf[1]); wf.y = cvt_pk_bf16(v[2] * zf[2], v[3] * zf[3]); wf.z = cvt_pk_bf16(v[4] * zf[4], v[5] * zf[5]); wf.w = cvt_pk_bf16(v[6] * zf[6], v[7] * zf[7]);
;                     wb.x = cvt_pk_bf16(v[0] * zb[0], v[1] * zb[1]); wb.y = cvt_pk_bf16(v[2] * zb[2], v[3] * zb[3]); wb.z = cvt_pk_bf16(v[4] * zb[4], v[5] * zb[5]); wb.w = cvt_pk_bf16(v[6] * zb[6], v[7] * zb[7]);
;                     *(u32x4*)(KTZ + (size_t)r * NT + t0) = wf;
;                     *(u32x4*)(KTZ + (size_t)(256 + r) * NT + t0) = wb;
	v_cvt_pk_bf16_f32 v104, v104, v105
	v_mul_f32_e32 v105, v102, v166
	v_mul_f32_e32 v106, v103, v168
	v_cvt_pk_bf16_f32 v105, v105, v106
	v_mul_f32_e32 v106, v96, v170
	v_mul_f32_e32 v107, v97, v171
	v_cvt_pk_bf16_f32 v106, v106, v107
	v_mul_f32_e32 v107, v98, v174
	v_mul_f32_e32 v100, v100, v156
	v_mul_f32_e32 v101, v101, v157
	v_mul_f32_e32 v108, v99, v177
	v_cvt_pk_bf16_f32 v107, v107, v108
	v_cvt_pk_bf16_f32 v100, v100, v101
	v_mul_f32_e32 v101, v102, v124
	v_mul_f32_e32 v102, v103, v125
	v_mul_f32_e32 v96, v96, v126
	v_mul_f32_e32 v97, v97, v172
	v_cvt_pk_bf16_f32 v101, v101, v102
	v_cvt_pk_bf16_f32 v102, v96, v97
	v_mul_f32_e32 v96, v98, v175
	v_mul_f32_e32 v97, v99, v162
	v_cvt_pk_bf16_f32 v103, v96, v97
	global_store_dwordx4 v[116:117], v[104:107], off offset:256
	global_store_dwordx4 v[112:113], v[100:103], off offset:256
	v_mul_f32_e32 v96, v92, v163
	v_mul_f32_e32 v97, v93, v164
	v_cvt_pk_bf16_f32 v96, v96, v97
	v_mul_f32_e32 v97, v94, v166
	v_mul_f32_e32 v98, v95, v168
	v_cvt_pk_bf16_f32 v97, v97, v98
	v_mul_f32_e32 v98, v88, v170
	v_mul_f32_e32 v99, v89, v171
	v_cvt_pk_bf16_f32 v98, v98, v99
	v_mul_f32_e32 v99, v90, v174
	v_mul_f32_e32 v92, v92, v156
	v_mul_f32_e32 v93, v93, v157
	v_mul_f32_e32 v100, v91, v177
	v_cvt_pk_bf16_f32 v99, v99, v100
	v_cvt_pk_bf16_f32 v92, v92, v93
	v_mul_f32_e32 v93, v94, v124
	v_mul_f32_e32 v94, v95, v125
	v_mul_f32_e32 v88, v88, v126
	s_mov_b64 s[2:3], 0x80000
	v_cvt_pk_bf16_f32 v93, v93, v94
	v_mul_f32_e32 v89, v89, v172
	v_cvt_pk_bf16_f32 v94, v88, v89
	v_mul_f32_e32 v88, v90, v175
	v_lshl_add_u64 v[100:101], v[140:141], 0, s[2:3]
	s_mov_b32 s2, 0x80000
	v_mul_f32_e32 v89, v91, v162
	v_cvt_pk_bf16_f32 v95, v88, v89
	v_add_co_u32_e32 v88, vcc, s2, v140
	s_mov_b64 s[2:3], 0x480000
	s_nop 0
	v_addc_co_u32_e32 v89, vcc, 0, v141, vcc
	global_store_dwordx4 v[88:89], v[96:99], off
	s_nop 1
	v_lshl_add_u64 v[96:97], v[140:141], 0, s[2:3]
	s_mov_b32 s2, 0x480000
	v_add_co_u32_e32 v88, vcc, s2, v140
	s_nop 1
	v_addc_co_u32_e32 v89, vcc, 0, v141, vcc
	global_store_dwordx4 v[88:89], v[92:95], off
	v_mul_f32_e32 v88, v84, v163
	v_mul_f32_e32 v89, v85, v164
	v_cvt_pk_bf16_f32 v88, v88, v89
	v_mul_f32_e32 v89, v86, v166
	v_mul_f32_e32 v90, v87, v168
	v_cvt_pk_bf16_f32 v89, v89, v90
	v_mul_f32_e32 v90, v80, v170
	v_mul_f32_e32 v91, v81, v171
	v_cvt_pk_bf16_f32 v90, v90, v91
	v_mul_f32_e32 v91, v82, v174
	v_mul_f32_e32 v84, v84, v156
	v_mul_f32_e32 v85, v85, v157
	v_mul_f32_e32 v92, v83, v177
	v_cvt_pk_bf16_f32 v91, v91, v92
	v_cvt_pk_bf16_f32 v84, v84, v85
	v_mul_f32_e32 v85, v86, v124
	v_mul_f32_e32 v86, v87, v125
	v_mul_f32_e32 v80, v80, v126
	v_mul_f32_e32 v81, v81, v172
	v_cvt_pk_bf16_f32 v85, v85, v86
	v_cvt_pk_bf16_f32 v86, v80, v81
	v_mul_f32_e32 v80, v82, v175
	v_mul_f32_e32 v81, v83, v162
	v_cvt_pk_bf16_f32 v87, v80, v81
	global_store_dwordx4 v[100:101], v[88:91], off offset:256
	global_store_dwordx4 v[96:97], v[84:87], off offset:256
	v_mul_f32_e32 v80, v76, v163
	v_mul_f32_e32 v81, v77, v164
	v_cvt_pk_bf16_f32 v80, v80, v81
	v_mul_f32_e32 v81, v78, v166
	v_mul_f32_e32 v82, v79, v168
	v_cvt_pk_bf16_f32 v81, v81, v82
	v_mul_f32_e32 v82, v72, v170
	v_mul_f32_e32 v83, v73, v171
	v_cvt_pk_bf16_f32 v82, v82, v83
	v_mul_f32_e32 v83, v74, v174
	v_mul_f32_e32 v76, v76, v156
	v_mul_f32_e32 v77, v77, v157
	v_mul_f32_e32 v84, v75, v177
	v_cvt_pk_bf16_f32 v83, v83, v84
	v_cvt_pk_bf16_f32 v76, v76, v77
	v_mul_f32_e32 v77, v78, v124
	v_mul_f32_e32 v78, v79, v125
	v_mul_f32_e32 v72, v72, v126
	s_mov_b64 s[2:3], 0xc0000
	v_cvt_pk_bf16_f32 v77, v77, v78
	v_mul_f32_e32 v73, v73, v172
	v_cvt_pk_bf16_f32 v78, v72, v73
	v_mul_f32_e32 v72, v74, v175
	v_lshl_add_u64 v[84:85], v[140:141], 0, s[2:3]
	s_mov_b32 s2, 0xc0000
	v_mul_f32_e32 v73, v75, v162
	v_cvt_pk_bf16_f32 v79, v72, v73
	v_add_co_u32_e32 v72, vcc, s2, v140
	s_mov_b64 s[2:3], 0x4c0000
	s_nop 0
	v_addc_co_u32_e32 v73, vcc, 0, v141, vcc
	global_store_dwordx4 v[72:73], v[80:83], off
	s_nop 1
	v_lshl_add_u64 v[80:81], v[140:141], 0, s[2:3]
	s_mov_b32 s2, 0x4c0000
	v_add_co_u32_e32 v72, vcc, s2, v140
	s_nop 1
	v_addc_co_u32_e32 v73, vcc, 0, v141, vcc
	global_store_dwordx4 v[72:73], v[76:79], off
	v_mul_f32_e32 v72, v68, v163
	v_mul_f32_e32 v73, v69, v164
	v_cvt_pk_bf16_f32 v72, v72, v73
	v_mul_f32_e32 v73, v70, v166
	v_mul_f32_e32 v74, v71, v168
	v_cvt_pk_bf16_f32 v73, v73, v74
	v_mul_f32_e32 v74, v64, v170
	v_mul_f32_e32 v75, v65, v171
	v_cvt_pk_bf16_f32 v74, v74, v75
	v_mul_f32_e32 v75, v66, v174
	v_mul_f32_e32 v68, v68, v156
	v_mul_f32_e32 v69, v69, v157
	v_mul_f32_e32 v76, v67, v177
	v_cvt_pk_bf16_f32 v75, v75, v76
	v_cvt_pk_bf16_f32 v68, v68, v69
	v_mul_f32_e32 v69, v70, v124
	v_mul_f32_e32 v70, v71, v125
	v_mul_f32_e32 v64, v64, v126
	v_mul_f32_e32 v65, v65, v172
	v_cvt_pk_bf16_f32 v69, v69, v70
	v_cvt_pk_bf16_f32 v70, v64, v65
	v_mul_f32_e32 v64, v66, v175
	v_mul_f32_e32 v65, v67, v162
	v_cvt_pk_bf16_f32 v71, v64, v65
	global_store_dwordx4 v[84:85], v[72:75], off offset:256
	global_store_dwordx4 v[80:81], v[68:71], off offset:256
	global_load_dword v70, v131, s[6:7] offset:8
	s_nop 0
	global_load_dword v71, v131, s[6:7] offset:24
	s_mov_b32 s17, 0x200000
	v_add_co_u32_e32 v76, vcc, s17, v140
	s_mov_b32 s19, 0x600000
	s_nop 0
	v_addc_co_u32_e32 v77, vcc, 0, v141, vcc
	v_add_co_u32_e32 v68, vcc, s19, v140
	s_mov_b64 s[2:3], 0x200000
	s_nop 0
	v_addc_co_u32_e32 v69, vcc, 0, v141, vcc
	s_mov_b64 s[4:5], 0x600000
	v_lshl_add_u64 v[64:65], v[140:141], 0, s[2:3]
	v_lshl_add_u64 v[66:67], v[140:141], 0, s[4:5]
	s_waitcnt vmcnt(0)
;     __device__ __forceinline__ void operator()(const AccT& acc, const Unit& u, int wr, int wc, int fr, int fq) const {
;     ...
;         for (int ai = 0; ai < 2; ++ai) {
;             const int hh = 2 * ai + wr;
;             const float l2f = lgd[hh] * 1.4426950408889634f, l2b = lgd[4 + hh] * 1.4426950408889634f;
;             const float zf0 = exp2f((float)(127 - o0) * l2f), zfs = exp2f(-l2f), zb0 = exp2f((float)o0 * l2b), zbs = exp2f(l2b);
; #pragma unroll
;             for (int m = 0; m < 4; ++m) {
;                 const int r = rbase + ai * 128 + m * 16;
;                 const int d = 4 * (2 * m + (fr >> 3)) + j;
; #pragma unroll
;                 for (int bj = 0; bj < 2; ++bj) {
;                     const int t0 = tb + bj * 128;
;                     float v[8];
; #pragma unroll
;                     for (int jj = 0; jj < 4; ++jj) { v[jj] = acc[ai][bj][m][0][jj]; v[4 + jj] = acc[ai][bj][m][1][jj]; }
;                     if constexpr (ROPE) {
;                         const int t = t0 & 2047;
; #pragma unroll
;                         for (int hf = 0; hf < 2; ++hf) {
;                             f32x4 cs, sn;
;                             if (m < 2) { const float c1 = ropeA[(t >> 6) * 16 + d], s1 = ropeA[1024 + (t >> 6) * 16 + d]; cs = (f32x4){c1, c1, c1, c1}; sn = (f32x4){s1, s1, s1, s1}; }
;                             else { const float* cb = ropeA + 2048 + (d - 16) * 64 + (t & 63) + 4 * hf; cs = *(const f32x4*)(cb); sn = *(const f32x4*)(cb + 1024); }
; #pragma unroll
;                             for (int jj = 0; jj < 4; ++jj) { const float pr = __shfl_xor(v[4 * hf + jj], 4); v[4 * hf + jj] = v[4 * hf + jj] * cs[jj] + sgn * pr * sn[jj]; }
;                             __builtin_amdgcn_sched_barrier(0);
;                         }
;                     }
;                     float zf[8], zb[8]; zf[0] = zf0; zb[0] = zb0;
; #pragma unroll
;                     for (int jj = 1; jj < 8; ++jj) { zf[jj] = zf[jj - 1] * zfs; zb[jj] = zb[jj - 1] * zbs; }
;                     u32x4 wf, wb;
;                     wf.x = cvt_pk_bf16(v[0] * zf[0], v[1] * zf[1]); wf.y = cvt_pk_bf16(v[2] * zf[2], v[3] * zf[3]); wf.z = cvt_pk_bf16(v[4] * zf[4], v[5] * zf[5]); wf.w = cvt_pk_bf16(v[6] * zf[6], v[7] * zf[7]);
	v_mul_f32_e32 v72, 0x3fb8aa3b, v70
	v_mul_f32_e32 v73, 0x3fb8aa3b, v71
	v_mul_f32_e32 v74, v72, v155
	v_cmp_lt_f32_e32 vcc, s51, v72
	v_mul_f32_e32 v78, v73, v154
	v_cmp_gt_f32_e64 s[2:3], s49, v73
	v_cndmask_b32_e32 v75, 0, v153, vcc
	v_cmp_gt_f32_e64 s[4:5], s49, v74
	v_cndmask_b32_e64 v79, 0, v153, s[2:3]
	s_and_b64 s[24:25], vcc, exec
	v_cmp_gt_f32_e32 vcc, s49, v78
	v_fmac_f32_e32 v79, 0x3fb8aa3b, v71
	v_cndmask_b32_e64 v71, 0, v153, s[4:5]
	v_cndmask_b32_e32 v78, 0, v153, vcc
	v_fmac_f32_e32 v75, 0xbfb8aa3b, v70
	v_fmac_f32_e32 v71, v72, v155
	v_fmac_f32_e32 v78, v73, v154
	v_exp_f32_e32 v75, v75
	v_exp_f32_e32 v79, v79
	v_exp_f32_e32 v71, v71
	v_exp_f32_e32 v72, v78
	v_cndmask_b32_e64 v74, 0, v152, s[4:5]
	s_cselect_b32 s4, 0xffffffc0, 0
	s_and_b64 s[2:3], s[2:3], exec
	v_cndmask_b32_e32 v70, 0, v152, vcc
	s_cselect_b32 s2, 0xffffffc0, 0
	v_ldexp_f32 v75, v75, s4
	v_ldexp_f32 v78, v79, s2
	v_ldexp_f32 v79, v71, v74
	v_ldexp_f32 v70, v72, v70
	v_mul_f32_e32 v80, v75, v79
	v_mul_f32_e32 v71, v78, v70
	v_mul_f32_e32 v72, v60, v79
	v_mul_f32_e32 v81, v60, v70
	v_mul_f32_e32 v82, v75, v80
	v_mul_f32_e32 v60, v78, v71
	v_mul_f32_e32 v83, v75, v82
	v_mul_f32_e32 v84, v78, v60
	v_mul_f32_e32 v85, v75, v83
	v_mul_f32_e32 v86, v78, v84
	v_mul_f32_e32 v73, v61, v80
	v_mul_f32_e32 v87, v75, v85
	v_mul_f32_e32 v88, v78, v86
	v_cvt_pk_bf16_f32 v72, v72, v73
	v_mul_f32_e32 v73, v62, v82
	v_mul_f32_e32 v74, v63, v83
	v_mul_f32_e32 v90, v75, v87
	v_mul_f32_e32 v91, v78, v88
	v_cvt_pk_bf16_f32 v73, v73, v74
	v_mul_f32_e32 v74, v56, v85
	v_mul_f32_e32 v89, v56, v86
	v_mul_f32_e32 v56, v57, v87
	v_mul_f32_e32 v93, v75, v90
	v_mul_f32_e32 v78, v78, v91
	v_mul_f32_e32 v92, v57, v88
	v_cvt_pk_bf16_f32 v74, v74, v56
	v_mul_f32_e32 v56, v58, v90
	v_mul_f32_e32 v57, v59, v93
	v_mul_f32_e32 v59, v59, v78
	v_cvt_pk_bf16_f32 v75, v56, v57
	v_mul_f32_e32 v61, v61, v71
	v_mul_f32_e32 v62, v62, v60
	v_mul_f32_e32 v63, v63, v84
	v_mul_f32_e32 v94, v58, v91
	v_cvt_pk_bf16_f32 v56, v81, v61
	v_cvt_pk_bf16_f32 v57, v62, v63
	v_cvt_pk_bf16_f32 v58, v89, v92
	v_cvt_pk_bf16_f32 v59, v94, v59
	global_store_dwordx4 v[76:77], v[72:75], off
	global_store_dwordx4 v[68:69], v[56:59], off
	s_nop 1
	v_mul_f32_e32 v56, v52, v79
	v_mul_f32_e32 v57, v53, v80
	v_cvt_pk_bf16_f32 v56, v56, v57
	v_mul_f32_e32 v57, v54, v82
	v_mul_f32_e32 v58, v55, v83
	v_cvt_pk_bf16_f32 v57, v57, v58
	v_mul_f32_e32 v58, v48, v85
	v_mul_f32_e32 v59, v49, v87
	v_cvt_pk_bf16_f32 v58, v58, v59
	v_mul_f32_e32 v59, v50, v90
	v_mul_f32_e32 v52, v52, v70
	v_mul_f32_e32 v53, v53, v71
	v_mul_f32_e32 v61, v51, v93
	v_cvt_pk_bf16_f32 v59, v59, v61
	v_cvt_pk_bf16_f32 v52, v52, v53
	v_mul_f32_e32 v53, v54, v60
	v_mul_f32_e32 v54, v55, v84
	v_mul_f32_e32 v48, v48, v86
	v_mul_f32_e32 v49, v49, v88
	v_cvt_pk_bf16_f32 v53, v53, v54
	v_cvt_pk_bf16_f32 v54, v48, v49
	v_mul_f32_e32 v48, v50, v91
	v_mul_f32_e32 v49, v51, v78
	v_cvt_pk_bf16_f32 v55, v48, v49
	global_store_dwordx4 v[64:65], v[56:59], off offset:256
	global_store_dwordx4 v[66:67], v[52:55], off offset:256
	v_mul_f32_e32 v48, v44, v79
	v_mul_f32_e32 v49, v45, v80
	v_cvt_pk_bf16_f32 v48, v48, v49
	v_mul_f32_e32 v49, v46, v82
	v_mul_f32_e32 v50, v47, v83
	v_cvt_pk_bf16_f32 v49, v49, v50
	v_mul_f32_e32 v50, v40, v85
	v_mul_f32_e32 v51, v41, v87
	v_cvt_pk_bf16_f32 v50, v50, v51
	v_mul_f32_e32 v51, v42, v90
	v_mul_f32_e32 v44, v44, v70
	v_mul_f32_e32 v45, v45, v71
	v_mul_f32_e32 v52, v43, v93
	v_cvt_pk_bf16_f32 v51, v51, v52
	v_cvt_pk_bf16_f32 v44, v44, v45
	v_mul_f32_e32 v45, v46, v60
	v_mul_f32_e32 v46, v47, v84
	v_mul_f32_e32 v40, v40, v86
	s_mov_b64 s[2:3], 0x240000
	v_cvt_pk_bf16_f32 v45, v45, v46
	v_mul_f32_e32 v41, v41, v88
	v_cvt_pk_bf16_f32 v46, v40, v41
	v_mul_f32_e32 v40, v42, v91
	v_lshl_add_u64 v[52:53], v[140:141], 0, s[2:3]
	s_mov_b32 s2, 0x240000
	v_mul_f32_e32 v41, v43, v78
	v_cvt_pk_bf16_f32 v47, v40, v41
	v_add_co_u32_e32 v40, vcc, s2, v140
	s_mov_b64 s[2:3], 0x640000
	s_nop 0
	v_addc_co_u32_e32 v41, vcc, 0, v141, vcc
	global_store_dwordx4 v[40:41], v[48:51], off
	s_nop 1
	v_lshl_add_u64 v[48:49], v[140:141], 0, s[2:3]
	s_mov_b32 s2, 0x640000
	v_add_co_u32_e32 v40, vcc, s2, v140
	s_nop 1
	v_addc_co_u32_e32 v41, vcc, 0, v141, vcc
	global_store_dwordx4 v[40:41], v[44:47], off
	v_mul_f32_e32 v40, v36, v79
	v_mul_f32_e32 v41, v37, v80
	v_cvt_pk_bf16_f32 v40, v40, v41
	v_mul_f32_e32 v41, v38, v82
	v_mul_f32_e32 v42, v39, v83
	v_cvt_pk_bf16_f32 v41, v41, v42
	v_mul_f32_e32 v42, v32, v85
	v_mul_f32_e32 v43, v33, v87
	v_cvt_pk_bf16_f32 v42, v42, v43
	v_mul_f32_e32 v43, v34, v90
	v_mul_f32_e32 v36, v36, v70
; __device__ __forceinline__ unsigned cvt_pk_bf16(float lo, float hi) { unsigned r; asm volatile("v_cvt_pk_bf16_f32 %0, %1, %2" : "=v"(r) : "v"(lo), "v"(hi)); return r; }
; #define PG8_WAIT_V(n) asm volatile("s_waitcnt vmcnt(" #n ")" ::: "memory")
; #define PG8_BAR __builtin_amdgcn_s_barrier()
; template <class Epi, class Sched>
; __device__ __forceinline__ void gemm_phase(LAS unsigned char* lds, const Gemm g, const Sched& S, const Epi& E) {
;     ...
;         if (!has_next) break;
; #pragma unroll
;         for (int a = 0; a < 2; ++a)
; #pragma unroll
;             for (int b = 0; b < 2; ++b)
; #pragma unroll
;                 for (int m = 0; m < 4; ++m)
; #pragma unroll
;                     for (int n = 0; n < 2; ++n) acc[a][b][m][n] = (f32x4){0.f, 0.f, 0.f, 0.f};
;         cur = nxt; cA = nA; cB = nB; ++ui;
;     }
;     PG8_WAIT_V(0);
;     if (wr == 0) PG8_BAR;
;     __device__ __forceinline__ void operator()(const AccT& acc, const Unit& u, int wr, int wc, int fr, int fq) const {
;     ...
;                     float zf[8], zb[8]; zf[0] = zf0; zb[0] = zb0;
; #pragma unroll
;                     for (int jj = 1; jj < 8; ++jj) { zf[jj] = zf[jj - 1] * zfs; zb[jj] = zb[jj - 1] * zbs; }
;                     u32x4 wf, wb;
;                     wf.x = cvt_pk_bf16(v[0] * zf[0], v[1] * zf[1]); wf.y = cvt_pk_bf16(v[2] * zf[2], v[3] * zf[3]); wf.z = cvt_pk_bf16(v[4] * zf[4], v[5] * zf[5]); wf.w = cvt_pk_bf16(v[6] * zf[6], v[7] * zf[7]);
;                     wb.x = cvt_pk_bf16(v[0] * zb[0], v[1] * zb[1]); wb.y = cvt_pk_bf16(v[2] * zb[2], v[3] * zb[3]); wb.z = cvt_pk_bf16(v[4] * zb[4], v[5] * zb[5]); wb.w = cvt_pk_bf16(v[6] * zb[6], v[7] * zb[7]);
;                     *(u32x4*)(KTZ + (size_t)r * NT + t0) = wf;
;                     *(u32x4*)(KTZ + (size_t)(256 + r) * NT + t0) = wb;
;                     __builtin_amdgcn_sched_barrier(0);
;                 }
;             }
	v_mul_f32_e32 v37, v37, v71
	v_mul_f32_e32 v44, v35, v93
	v_cvt_pk_bf16_f32 v43, v43, v44
	v_cvt_pk_bf16_f32 v36, v36, v37
	v_mul_f32_e32 v37, v38, v60
	v_mul_f32_e32 v38, v39, v84
	v_mul_f32_e32 v32, v32, v86
	v_mul_f32_e32 v33, v33, v88
	v_cvt_pk_bf16_f32 v37, v37, v38
	v_cvt_pk_bf16_f32 v38, v32, v33
	v_mul_f32_e32 v32, v34, v91
	v_mul_f32_e32 v33, v35, v78
	v_cvt_pk_bf16_f32 v39, v32, v33
	global_store_dwordx4 v[52:53], v[40:43], off offset:256
	global_store_dwordx4 v[48:49], v[36:39], off offset:256
	v_mul_f32_e32 v32, v28, v79
	v_mul_f32_e32 v33, v29, v80
	v_cvt_pk_bf16_f32 v32, v32, v33
	v_mul_f32_e32 v33, v30, v82
	v_mul_f32_e32 v34, v31, v83
	v_cvt_pk_bf16_f32 v33, v33, v34
	v_mul_f32_e32 v34, v24, v85
	v_mul_f32_e32 v35, v25, v87
	v_cvt_pk_bf16_f32 v34, v34, v35
	v_mul_f32_e32 v35, v26, v90
	v_mul_f32_e32 v28, v28, v70
	v_mul_f32_e32 v29, v29, v71
	v_mul_f32_e32 v36, v27, v93
	v_cvt_pk_bf16_f32 v35, v35, v36
	v_cvt_pk_bf16_f32 v28, v28, v29
	v_mul_f32_e32 v29, v30, v60
	v_mul_f32_e32 v30, v31, v84
	v_mul_f32_e32 v24, v24, v86
	v_cvt_pk_bf16_f32 v29, v29, v30
	v_mul_f32_e32 v25, v25, v88
	v_cvt_pk_bf16_f32 v30, v24, v25
	v_mul_f32_e32 v24, v26, v91
	v_mul_f32_e32 v25, v27, v78
	v_cvt_pk_bf16_f32 v31, v24, v25
	v_add_co_u32_e32 v24, vcc, s52, v140
	s_mov_b64 s[2:3], 0x280000
	s_nop 0
	v_addc_co_u32_e32 v25, vcc, 0, v141, vcc
	global_store_dwordx4 v[24:25], v[32:35], off
	v_add_co_u32_e32 v24, vcc, s53, v140
	v_lshl_add_u64 v[36:37], v[140:141], 0, s[2:3]
	s_nop 0
	v_addc_co_u32_e32 v25, vcc, 0, v141, vcc
	v_lshl_add_u64 v[32:33], v[140:141], 0, s[8:9]
	global_store_dwordx4 v[24:25], v[28:31], off
	v_mul_f32_e32 v24, v20, v79
	v_mul_f32_e32 v25, v21, v80
	v_cvt_pk_bf16_f32 v24, v24, v25
	v_mul_f32_e32 v25, v22, v82
	v_mul_f32_e32 v26, v23, v83
	v_cvt_pk_bf16_f32 v25, v25, v26
	v_mul_f32_e32 v26, v16, v85
	v_mul_f32_e32 v27, v17, v87
	v_cvt_pk_bf16_f32 v26, v26, v27
	v_mul_f32_e32 v27, v18, v90
	v_mul_f32_e32 v20, v20, v70
	v_mul_f32_e32 v21, v21, v71
	v_mul_f32_e32 v28, v19, v93
	v_cvt_pk_bf16_f32 v27, v27, v28
	v_cvt_pk_bf16_f32 v20, v20, v21
	v_mul_f32_e32 v21, v22, v60
	v_mul_f32_e32 v22, v23, v84
	v_mul_f32_e32 v16, v16, v86
	v_mul_f32_e32 v17, v17, v88
	v_cvt_pk_bf16_f32 v21, v21, v22
	v_cvt_pk_bf16_f32 v22, v16, v17
	v_mul_f32_e32 v16, v18, v91
	v_mul_f32_e32 v17, v19, v78
	v_cvt_pk_bf16_f32 v23, v16, v17
	global_store_dwordx4 v[36:37], v[24:27], off offset:256
	global_store_dwordx4 v[32:33], v[20:23], off offset:256
	v_mul_f32_e32 v16, v12, v79
	v_mul_f32_e32 v17, v13, v80
	v_cvt_pk_bf16_f32 v16, v16, v17
	v_mul_f32_e32 v17, v14, v82
	v_mul_f32_e32 v18, v15, v83
	v_cvt_pk_bf16_f32 v17, v17, v18
	v_mul_f32_e32 v18, v8, v85
	v_mul_f32_e32 v19, v9, v87
	v_cvt_pk_bf16_f32 v18, v18, v19
	v_mul_f32_e32 v19, v10, v90
	v_mul_f32_e32 v12, v12, v70
	v_mul_f32_e32 v13, v13, v71
	v_mul_f32_e32 v20, v11, v93
	v_cvt_pk_bf16_f32 v19, v19, v20
	v_cvt_pk_bf16_f32 v12, v12, v13
	v_mul_f32_e32 v13, v14, v60
	v_mul_f32_e32 v14, v15, v84
	v_mul_f32_e32 v8, v8, v86
	v_cvt_pk_bf16_f32 v13, v13, v14
	v_mul_f32_e32 v9, v9, v88
	v_cvt_pk_bf16_f32 v14, v8, v9
	v_mul_f32_e32 v8, v10, v91
	v_mul_f32_e32 v9, v11, v78
	v_cvt_pk_bf16_f32 v15, v8, v9
	v_add_co_u32_e32 v8, vcc, s54, v140
	v_lshl_add_u64 v[20:21], v[140:141], 0, s[10:11]
	s_nop 0
	v_addc_co_u32_e32 v9, vcc, 0, v141, vcc
	global_store_dwordx4 v[8:9], v[16:19], off
	v_add_co_u32_e32 v8, vcc, s55, v140
	s_nop 0
	v_lshl_add_u64 v[16:17], v[140:141], 0, s[12:13]
	v_addc_co_u32_e32 v9, vcc, 0, v141, vcc
	global_store_dwordx4 v[8:9], v[12:15], off
	v_mul_f32_e32 v8, v4, v79
	v_mul_f32_e32 v9, v5, v80
	v_cvt_pk_bf16_f32 v8, v8, v9
	v_mul_f32_e32 v9, v6, v82
	v_mul_f32_e32 v10, v7, v83
	v_cvt_pk_bf16_f32 v9, v9, v10
	v_mul_f32_e32 v10, v0, v85
	v_mul_f32_e32 v11, v1, v87
	v_cvt_pk_bf16_f32 v10, v10, v11
	v_mul_f32_e32 v11, v2, v90
	v_mul_f32_e32 v4, v4, v70
	v_mul_f32_e32 v5, v5, v71
	v_mul_f32_e32 v12, v3, v93
	v_cvt_pk_bf16_f32 v11, v11, v12
	v_cvt_pk_bf16_f32 v4, v4, v5
	v_mul_f32_e32 v5, v6, v60
	v_mul_f32_e32 v6, v7, v84
	v_mul_f32_e32 v0, v0, v86
	v_mul_f32_e32 v1, v1, v88
	v_cvt_pk_bf16_f32 v5, v5, v6
	v_cvt_pk_bf16_f32 v6, v0, v1
	v_mul_f32_e32 v0, v2, v91
	v_mul_f32_e32 v1, v3, v78
	v_cvt_pk_bf16_f32 v7, v0, v1
	global_store_dwordx4 v[20:21], v[8:11], off offset:256
	global_store_dwordx4 v[16:17], v[4:7], off offset:256
	s_and_b64 vcc, exec, s[14:15]
	s_mov_b32 s56, s16
	s_mov_b64 s[4:5], s[22:23]
	s_mov_b64 s[2:3], s[20:21]
	s_cbranch_vccz .LBB0_686
	s_waitcnt vmcnt(0)
	s_cmpk_gt_u32 s27, 0xff
	s_cbranch_scc1 .LBB0_697
	s_barrier

; #define PG8_STAGE(bufoff, gbase, voff) do { _Pragma("unroll") for (int _i = 0; _i < 2; ++_i) \
;         __builtin_amdgcn_global_load_lds((const unsigned*)((const char*)(gbase) + (voff)[_i]), (LAS unsigned*)(lds + (bufoff) + ldsw + _i * 8192), 16, 0, 0); } while (0)
; #define PG8_LDA(dst, b, h) do { _Pragma("unroll") for (int m = 0; m < 4; ++m) _Pragma("unroll") for (int k = 0; k < 2; ++k) dst[m][k] = *(const LAS bf16x8*)(lds + PG8_SA(b, h) + aoff + m * 2048 + k * 1024); } while (0)
; #define PG8_LDB(dst, b, h) do { _Pragma("unroll") for (int n = 0; n < 2; ++n) _Pragma("unroll") for (int k = 0; k < 2; ++k) dst[n][k] = *(const LAS bf16x8*)(lds + PG8_SB(b, h) + boff + n * 2048 + k * 1024); } while (0)
; #define PG8_WAIT_V(n) asm volatile("s_waitcnt vmcnt(" #n ")" ::: "memory")
; #define PG8_BAR __builtin_amdgcn_s_barrier()
; template <class Epi, class Sched>
; __device__ __forceinline__ void gemm_phase(LAS unsigned char* lds, const Gemm g, const Sched& S, const Epi& E) {
;     ...
;         const bool has_next = S.next(ui + 1, nxt);
;         const char* nA = has_next ? (const char*)g.A + (size_t)nxt.pm * tstep : cA; const char* nB = has_next ? (const char*)g.Bt + (size_t)nxt.pn * tstep : cB;
;         for (int t = 0; t < nt; t += 2) {
;             const bool last = (t == nt - 2);
;             const char* a1 = cA + (size_t)(t + 1) * kstep;
;             const char* a2 = last ? nA : cA + (size_t)(t + 2) * kstep; const char* b2 = last ? nB : cB + (size_t)(t + 2) * kstep;
;             const char* a3 = a2 + kstep; const char* b3 = b2 + kstep;
;             PG8_LDB(B0, 0, 0); PG8_SCHED; PG8_LDA(At, 0, 0); PG8_STAGE(PG8_SA(1, 1), a1 + hstep, voffA);
;             PG8_WAIT_L(8); PG8_BAR; PG8_WAIT_L(0); PG8_MMA(0, 0, At, B0); PG8_BAR; PG8_SCHED;
;             PG8_LDB(B1, 0, 1); PG8_STAGE(PG8_SB(0, 0), b2, voffB);
;             PG8_BAR; PG8_WAIT_L(0); PG8_MMA(0, 1, At, B1); PG8_BAR;
;             PG8_LDA(At, 0, 1); PG8_STAGE(PG8_SA(0, 0), a2, voffA);
;             PG8_BAR; PG8_WAIT_L(0); PG8_MMA(1, 0, At, B0); PG8_BAR; PG8_SCHED;
;             PG8_STAGE(PG8_SB(0, 1), b2 + hstep, voffB);
;             PG8_WAIT_V(6); PG8_BAR; PG8_MMA(1, 1, At, B1); PG8_BAR;
;             PG8_LDB(B0, 1, 0); PG8_SCHED; PG8_LDA(At, 1, 0); PG8_STAGE(PG8_SA(0, 1), a2 + hstep, voffA);
;             PG8_WAIT_L(8); PG8_BAR; PG8_WAIT_L(0); PG8_MMA(0, 0, At, B0); PG8_BAR; PG8_SCHED;
.LBB0_712:
	s_ashr_i32 s15, s14, 31
	v_cmp_lt_i64_e64 s[26:27], s[16:17], 64
	s_lshl_b64 s[16:17], s[14:15], 19
	s_add_u32 s16, s38, s16
	s_addc_u32 s17, s39, s17
	s_and_b64 s[18:19], s[26:27], exec
	s_cselect_b32 s15, s17, s23
	s_cselect_b32 s54, s16, s22
	s_ashr_i32 s13, s12, 31
	s_lshl_b64 s[18:19], s[12:13], 19
	s_add_u32 s18, s28, s18
	s_addc_u32 s19, s29, s19
	s_and_b64 s[26:27], s[26:27], exec
	s_cselect_b32 s13, s19, s25
	s_cselect_b32 s55, s18, s24
	s_add_u32 s22, s22, 0x40080
	s_addc_u32 s23, s23, 0
	s_add_u32 s56, s24, 0x100
	s_addc_u32 s57, s25, 0
	s_mov_b32 s58, -2
	s_waitcnt lgkmcnt(0)
	ds_read_b128 v[146:149], v143
	ds_read_b128 v[150:153], v143 offset:1024
	ds_read_b128 v[154:157], v143 offset:2048
	ds_read_b128 v[158:161], v143 offset:3072
	s_add_u32 s24, s22, 0xfffc0080
	s_addc_u32 s25, s23, -1
	s_cmp_eq_u32 s58, 12
	s_cselect_b32 s27, s15, s25
	s_cselect_b32 s26, s54, s24
	s_cselect_b32 s25, s13, s57
	s_cselect_b32 s24, s55, s56
	s_add_i32 m0, s21, 0xc000
	ds_read_b128 v[162:165], v144
	ds_read_b128 v[166:169], v144 offset:1024
	ds_read_b128 v[170:173], v144 offset:2048
	ds_read_b128 v[174:177], v144 offset:3072
	ds_read_b128 v[178:181], v144 offset:4096
	ds_read_b128 v[182:185], v144 offset:5120
	ds_read_b128 v[186:189], v144 offset:6144
	ds_read_b128 v[190:193], v144 offset:7168
	global_load_lds_dwordx4 v136, s[22:23]
	s_add_i32 m0, s21, 0xe000
	s_nop 0
	global_load_lds_dwordx4 v138, s[22:23]
	s_waitcnt lgkmcnt(8)
	s_waitcnt vmcnt(8)
	s_setprio 1
	s_barrier
	s_waitcnt lgkmcnt(0)
	v_mfma_f32_16x16x32_bf16 v[124:127], v[146:149], v[162:165], 0
	v_mfma_f32_16x16x32_bf16 v[120:123], v[154:157], v[162:165], 0
	v_mfma_f32_16x16x32_bf16 v[116:119], v[146:149], v[170:173], 0
	v_mfma_f32_16x16x32_bf16 v[108:111], v[154:157], v[170:173], 0
	v_mfma_f32_16x16x32_bf16 v[100:103], v[146:149], v[178:181], 0
	v_mfma_f32_16x16x32_bf16 v[92:95], v[154:157], v[178:181], 0
	v_mfma_f32_16x16x32_bf16 v[84:87], v[146:149], v[186:189], 0
	v_mfma_f32_16x16x32_bf16 v[76:79], v[154:157], v[186:189], 0
	v_mfma_f32_16x16x32_bf16 v[124:127], v[150:153], v[166:169], v[124:127]
	v_mfma_f32_16x16x32_bf16 v[120:123], v[158:161], v[166:169], v[120:123]
	v_mfma_f32_16x16x32_bf16 v[116:119], v[150:153], v[174:177], v[116:119]
	v_mfma_f32_16x16x32_bf16 v[108:111], v[158:161], v[174:177], v[108:111]
	v_mfma_f32_16x16x32_bf16 v[100:103], v[150:153], v[182:185], v[100:103]
	v_mfma_f32_16x16x32_bf16 v[92:95], v[158:161], v[182:185], v[92:95]
	v_mfma_f32_16x16x32_bf16 v[84:87], v[150:153], v[190:193], v[84:87]
	v_mfma_f32_16x16x32_bf16 v[76:79], v[158:161], v[190:193], v[76:79]
	s_barrier
	s_setprio 0
	s_add_i32 s59, s46, s34
	s_mov_b32 m0, s59
	ds_read_b128 v[194:197], v145
	ds_read_b128 v[202:205], v145 offset:1024
	ds_read_b128 v[206:209], v145 offset:2048
	ds_read_b128 v[210:213], v145 offset:3072
	global_load_lds_dwordx4 v130, s[24:25]
	s_add_i32 m0, s59, 0x2000
	s_nop 0
	global_load_lds_dwordx4 v134, s[24:25]
	s_waitcnt vmcnt(8)
	s_setprio 1
	s_barrier
	s_waitcnt lgkmcnt(0)
	v_mfma_f32_16x16x32_bf16 v[112:115], v[194:197], v[162:165], 0
	v_mfma_f32_16x16x32_bf16 v[104:107], v[206:209], v[162:165], 0
	v_mfma_f32_16x16x32_bf16 v[96:99], v[194:197], v[170:173], 0
	v_mfma_f32_16x16x32_bf16 v[88:91], v[206:209], v[170:173], 0
	v_mfma_f32_16x16x32_bf16 v[80:83], v[194:197], v[178:181], 0
	v_mfma_f32_16x16x32_bf16 v[72:75], v[206:209], v[178:181], 0
	v_mfma_f32_16x16x32_bf16 v[68:71], v[194:197], v[186:189], 0
	v_mfma_f32_16x16x32_bf16 v[64:67], v[206:209], v[186:189], 0
	v_mfma_f32_16x16x32_bf16 v[112:115], v[202:205], v[166:169], v[112:115]
	v_mfma_f32_16x16x32_bf16 v[104:107], v[210:213], v[166:169], v[104:107]
	v_mfma_f32_16x16x32_bf16 v[96:99], v[202:205], v[174:177], v[96:99]
	v_mfma_f32_16x16x32_bf16 v[88:91], v[210:213], v[174:177], v[88:91]
	v_mfma_f32_16x16x32_bf16 v[80:83], v[202:205], v[182:185], v[80:83]
	v_mfma_f32_16x16x32_bf16 v[72:75], v[210:213], v[182:185], v[72:75]
	v_mfma_f32_16x16x32_bf16 v[68:71], v[202:205], v[190:193], v[68:71]
	v_mfma_f32_16x16x32_bf16 v[64:67], v[210:213], v[190:193], v[64:67]
	s_barrier
	s_setprio 0
	s_mov_b32 m0, s21
	v_lshl_add_u64 v[216:217], s[26:27], 0, v[128:129]
	ds_read_b128 v[162:165], v144 offset:16384
	ds_read_b128 v[166:169], v144 offset:17408
	ds_read_b128 v[170:173], v144 offset:18432
	ds_read_b128 v[174:177], v144 offset:19456
	ds_read_b128 v[178:181], v144 offset:20480
	ds_read_b128 v[182:185], v144 offset:21504
	ds_read_b128 v[186:189], v144 offset:22528
	ds_read_b128 v[190:193], v144 offset:23552
	global_load_lds_dwordx4 v128, s[26:27]
	v_lshl_add_u64 v[218:219], s[26:27], 0, v[132:133]
	s_mov_b32 m0, s35
	s_nop 0
	global_load_lds_dwordx4 v132, s[26:27]
	s_setprio 1
	s_barrier
	s_waitcnt lgkmcnt(0)
	v_mfma_f32_16x16x32_bf16 v[60:63], v[146:149], v[162:165], 0
	v_mfma_f32_16x16x32_bf16 v[56:59], v[154:157], v[162:165], 0
	v_mfma_f32_16x16x32_bf16 v[52:55], v[146:149], v[170:173], 0
	v_mfma_f32_16x16x32_bf16 v[44:47], v[154:157], v[170:173], 0
	v_mfma_f32_16x16x32_bf16 v[36:39], v[146:149], v[178:181], 0
	v_mfma_f32_16x16x32_bf16 v[28:31], v[154:157], v[178:181], 0
	v_mfma_f32_16x16x32_bf16 v[20:23], v[146:149], v[186:189], 0
	v_mfma_f32_16x16x32_bf16 v[12:15], v[154:157], v[186:189], 0
	v_mfma_f32_16x16x32_bf16 v[60:63], v[150:153], v[166:169], v[60:63]
	v_mfma_f32_16x16x32_bf16 v[56:59], v[158:161], v[166:169], v[56:59]
	v_mfma_f32_16x16x32_bf16 v[52:55], v[150:153], v[174:177], v[52:55]
	v_mfma_f32_16x16x32_bf16 v[44:47], v[158:161], v[174:177], v[44:47]
	v_mfma_f32_16x16x32_bf16 v[36:39], v[150:153], v[182:185], v[36:39]
	v_mfma_f32_16x16x32_bf16 v[28:31], v[158:161], v[182:185], v[28:31]
	v_mfma_f32_16x16x32_bf16 v[20:23], v[150:153], v[190:193], v[20:23]
	v_mfma_f32_16x16x32_bf16 v[12:15], v[158:161], v[190:193], v[12:15]
	s_barrier
; #define PG8_STAGE(bufoff, gbase, voff) do { _Pragma("unroll") for (int _i = 0; _i < 2; ++_i) \
;         __builtin_amdgcn_global_load_lds((const unsigned*)((const char*)(gbase) + (voff)[_i]), (LAS unsigned*)(lds + (bufoff) + ldsw + _i * 8192), 16, 0, 0); } while (0)
; #define PG8_LDA(dst, b, h) do { _Pragma("unroll") for (int m = 0; m < 4; ++m) _Pragma("unroll") for (int k = 0; k < 2; ++k) dst[m][k] = *(const LAS bf16x8*)(lds + PG8_SA(b, h) + aoff + m * 2048 + k * 1024); } while (0)
; #define PG8_LDB(dst, b, h) do { _Pragma("unroll") for (int n = 0; n < 2; ++n) _Pragma("unroll") for (int k = 0; k < 2; ++k) dst[n][k] = *(const LAS bf16x8*)(lds + PG8_SB(b, h) + boff + n * 2048 + k * 1024); } while (0)
; #define PG8_MMA(ai, bj, At, Bt) do { __builtin_amdgcn_s_setprio(1); _Pragma("unroll") for (int m = 0; m < 4; ++m) _Pragma("unroll") for (int n = 0; n < 2; ++n) _Pragma("unroll") for (int k = 0; k < 2; ++k) \
;         acc[ai][bj][m][n] = __builtin_amdgcn_mfma_f32_16x16x32_bf16(Bt[n][k], At[m][k], acc[ai][bj][m][n], 0, 0, 0); __builtin_amdgcn_s_setprio(0); } while (0)
; #define PG8_WAIT_V(n) asm volatile("s_waitcnt vmcnt(" #n ")" ::: "memory")
; #define PG8_WAIT_L(n) asm volatile("s_waitcnt lgkmcnt(" #n ")" ::: "memory")
; #define PG8_BAR __builtin_amdgcn_s_barrier()
; #define PG8_SCHED __builtin_amdgcn_sched_barrier(0)
; template <class Epi, class Sched>
; __device__ __forceinline__ void gemm_phase(LAS unsigned char* lds, const Gemm g, const Sched& S, const Epi& E) {
;     ...
;             PG8_STAGE(PG8_SB(0, 1), b2 + hstep, voffB);
;             PG8_WAIT_V(6); PG8_BAR; PG8_MMA(1, 1, At, B1); PG8_BAR;
;             PG8_LDB(B0, 1, 0); PG8_SCHED; PG8_LDA(At, 1, 0); PG8_STAGE(PG8_SA(0, 1), a2 + hstep, voffA);
;             PG8_WAIT_L(8); PG8_BAR; PG8_WAIT_L(0); PG8_MMA(0, 0, At, B0); PG8_BAR; PG8_SCHED;
;             PG8_LDB(B1, 1, 1); PG8_STAGE(PG8_SB(1, 0), b3, voffB);
;             PG8_BAR; PG8_WAIT_L(0); PG8_MMA(0, 1, At, B1); PG8_BAR;
;             PG8_LDA(At, 1, 1); PG8_STAGE(PG8_SA(1, 0), a3, voffA);
;             PG8_BAR; PG8_WAIT_L(0); PG8_MMA(1, 0, At, B0); PG8_BAR; PG8_SCHED;
;             PG8_STAGE(PG8_SB(1, 1), b3 + hstep, voffB);
;             PG8_WAIT_V(6); PG8_BAR; PG8_MMA(1, 1, At, B1); PG8_BAR;
	s_setprio 0
	s_add_u32 s60, s24, 0x40000
	s_addc_u32 s61, s25, 0
	s_add_i32 s59, s47, s34
	s_mov_b32 m0, s59
	s_nop 0
	global_load_lds_dwordx4 v130, s[60:61]
	s_add_i32 m0, s59, 0x2000
	s_nop 0
	global_load_lds_dwordx4 v134, s[60:61]
	s_add_u32 s26, s26, 0x40000
	s_addc_u32 s27, s27, 0
	s_mov_b32 m0, s36
	s_nop 0
	global_load_lds_dwordx4 v128, s[26:27]
	s_mov_b32 m0, s37
	s_nop 0
	global_load_lds_dwordx4 v132, s[26:27]
	s_waitcnt vmcnt(10)
	s_setprio 1
	s_barrier
	v_mfma_f32_16x16x32_bf16 v[48:51], v[194:197], v[162:165], 0
	v_mfma_f32_16x16x32_bf16 v[40:43], v[206:209], v[162:165], 0
	v_mfma_f32_16x16x32_bf16 v[32:35], v[194:197], v[170:173], 0
	v_mfma_f32_16x16x32_bf16 v[24:27], v[206:209], v[170:173], 0
	v_mfma_f32_16x16x32_bf16 v[16:19], v[194:197], v[178:181], 0
	v_mfma_f32_16x16x32_bf16 v[8:11], v[206:209], v[178:181], 0
	v_mfma_f32_16x16x32_bf16 v[4:7], v[194:197], v[186:189], 0
	v_mfma_f32_16x16x32_bf16 v[0:3], v[206:209], v[186:189], 0
	v_mfma_f32_16x16x32_bf16 v[48:51], v[202:205], v[166:169], v[48:51]
	v_mfma_f32_16x16x32_bf16 v[40:43], v[210:213], v[166:169], v[40:43]
	v_mfma_f32_16x16x32_bf16 v[32:35], v[202:205], v[174:177], v[32:35]
	v_mfma_f32_16x16x32_bf16 v[24:27], v[210:213], v[174:177], v[24:27]
	v_mfma_f32_16x16x32_bf16 v[16:19], v[202:205], v[182:185], v[16:19]
	v_mfma_f32_16x16x32_bf16 v[8:11], v[210:213], v[182:185], v[8:11]
	v_mfma_f32_16x16x32_bf16 v[4:7], v[202:205], v[190:193], v[4:7]
	v_mfma_f32_16x16x32_bf16 v[0:3], v[210:213], v[190:193], v[0:3]
	s_barrier
	s_setprio 0
	s_add_i32 s59, 0, 0x18000
	ds_read_b128 v[146:149], v145 offset:16384
	ds_read_b128 v[150:153], v145 offset:17408
	ds_read_b128 v[154:157], v145 offset:18432
	ds_read_b128 v[158:161], v145 offset:19456
	ds_read_b128 v[162:165], v144 offset:32768
	ds_read_b128 v[166:169], v144 offset:33792
	ds_read_b128 v[170:173], v144 offset:34816
	ds_read_b128 v[174:177], v144 offset:35840
	ds_read_b128 v[178:181], v144 offset:36864
	ds_read_b128 v[182:185], v144 offset:37888
	ds_read_b128 v[186:189], v144 offset:38912
	ds_read_b128 v[190:193], v144 offset:39936
	s_waitcnt lgkmcnt(8)
	s_waitcnt vmcnt(8)
	s_setprio 1
	s_barrier
	s_waitcnt lgkmcnt(0)
	v_mfma_f32_16x16x32_bf16 v[124:127], v[146:149], v[162:165], v[124:127]
	v_mfma_f32_16x16x32_bf16 v[120:123], v[154:157], v[162:165], v[120:123]
	v_mfma_f32_16x16x32_bf16 v[116:119], v[146:149], v[170:173], v[116:119]
	v_mfma_f32_16x16x32_bf16 v[108:111], v[154:157], v[170:173], v[108:111]
	v_mfma_f32_16x16x32_bf16 v[100:103], v[146:149], v[178:181], v[100:103]
	v_mfma_f32_16x16x32_bf16 v[92:95], v[154:157], v[178:181], v[92:95]
	v_mfma_f32_16x16x32_bf16 v[84:87], v[146:149], v[186:189], v[84:87]
	v_mfma_f32_16x16x32_bf16 v[76:79], v[154:157], v[186:189], v[76:79]
	v_mfma_f32_16x16x32_bf16 v[124:127], v[150:153], v[166:169], v[124:127]
	v_mfma_f32_16x16x32_bf16 v[120:123], v[158:161], v[166:169], v[120:123]
	v_mfma_f32_16x16x32_bf16 v[116:119], v[150:153], v[174:177], v[116:119]
	v_mfma_f32_16x16x32_bf16 v[108:111], v[158:161], v[174:177], v[108:111]
	v_mfma_f32_16x16x32_bf16 v[100:103], v[150:153], v[182:185], v[100:103]
	v_mfma_f32_16x16x32_bf16 v[92:95], v[158:161], v[182:185], v[92:95]
	v_mfma_f32_16x16x32_bf16 v[84:87], v[150:153], v[190:193], v[84:87]
	v_mfma_f32_16x16x32_bf16 v[76:79], v[158:161], v[190:193], v[76:79]
	s_barrier
	s_setprio 0
	s_add_i32 s26, 0, 0x1c000
	s_add_i32 s27, s59, s34
	v_add_u32_e32 v210, s26, v142
	s_add_u32 s0, s24, 0x80
	s_addc_u32 s1, s25, 0
	s_mov_b32 m0, s27
	ds_read_b128 v[194:197], v210
	ds_read_b128 v[202:205], v210 offset:1024
	ds_read_b128 v[206:209], v210 offset:2048
	ds_read_b128 v[210:213], v210 offset:3072
	global_load_lds_dwordx4 v130, s[0:1]
	s_add_i32 m0, s27, 0x2000
	s_nop 0
	global_load_lds_dwordx4 v134, s[0:1]
	s_waitcnt vmcnt(8)
	s_setprio 1
	s_barrier
	s_waitcnt lgkmcnt(0)
	v_mfma_f32_16x16x32_bf16 v[112:115], v[194:197], v[162:165], v[112:115]
	v_mfma_f32_16x16x32_bf16 v[104:107], v[206:209], v[162:165], v[104:107]
	v_mfma_f32_16x16x32_bf16 v[96:99], v[194:197], v[170:173], v[96:99]
	v_mfma_f32_16x16x32_bf16 v[88:91], v[206:209], v[170:173], v[88:91]
	v_mfma_f32_16x16x32_bf16 v[80:83], v[194:197], v[178:181], v[80:83]
	v_mfma_f32_16x16x32_bf16 v[72:75], v[206:209], v[178:181], v[72:75]
	v_mfma_f32_16x16x32_bf16 v[68:71], v[194:197], v[186:189], v[68:71]
	v_mfma_f32_16x16x32_bf16 v[64:67], v[206:209], v[186:189], v[64:67]
	v_mfma_f32_16x16x32_bf16 v[112:115], v[202:205], v[166:169], v[112:115]
	v_mfma_f32_16x16x32_bf16 v[104:107], v[210:213], v[166:169], v[104:107]
	v_mfma_f32_16x16x32_bf16 v[96:99], v[202:205], v[174:177], v[96:99]
	v_mfma_f32_16x16x32_bf16 v[88:91], v[210:213], v[174:177], v[88:91]
	v_mfma_f32_16x16x32_bf16 v[80:83], v[202:205], v[182:185], v[80:83]
	v_mfma_f32_16x16x32_bf16 v[72:75], v[210:213], v[182:185], v[72:75]
	v_mfma_f32_16x16x32_bf16 v[68:71], v[202:205], v[190:193], v[68:71]
	v_mfma_f32_16x16x32_bf16 v[64:67], v[210:213], v[190:193], v[64:67]
	s_barrier
	s_setprio 0
	s_mov_b32 m0, s43
	s_mov_b64 s[0:1], 0x80
	v_lshl_add_u64 v[198:199], v[216:217], 0, s[0:1]
	ds_read_b128 v[162:165], v144 offset:49152
	ds_read_b128 v[166:169], v144 offset:50176
	ds_read_b128 v[170:173], v144 offset:51200
	ds_read_b128 v[174:177], v144 offset:52224
	ds_read_b128 v[178:181], v144 offset:53248
	ds_read_b128 v[182:185], v144 offset:54272
	ds_read_b128 v[186:189], v144 offset:55296
	ds_read_b128 v[190:193], v144 offset:56320
	global_load_lds_dwordx4 v[198:199], off
	v_lshl_add_u64 v[198:199], v[218:219], 0, s[0:1]
	s_mov_b32 m0, s44
	s_nop 0
	global_load_lds_dwordx4 v[198:199], off
	s_setprio 1
	s_barrier
; #define PG8_STAGE(bufoff, gbase, voff) do { _Pragma("unroll") for (int _i = 0; _i < 2; ++_i) \
;         __builtin_amdgcn_global_load_lds((const unsigned*)((const char*)(gbase) + (voff)[_i]), (LAS unsigned*)(lds + (bufoff) + ldsw + _i * 8192), 16, 0, 0); } while (0)
; #define PG8_LDA(dst, b, h) do { _Pragma("unroll") for (int m = 0; m < 4; ++m) _Pragma("unroll") for (int k = 0; k < 2; ++k) dst[m][k] = *(const LAS bf16x8*)(lds + PG8_SA(b, h) + aoff + m * 2048 + k * 1024); } while (0)
; #define PG8_WAIT_V(n) asm volatile("s_waitcnt vmcnt(" #n ")" ::: "memory")
; #define PG8_WAIT_L(n) asm volatile("s_waitcnt lgkmcnt(" #n ")" ::: "memory")
; template <class Epi, class Sched>
; __device__ __forceinline__ void gemm_phase(LAS unsigned char* lds, const Gemm g, const Sched& S, const Epi& E) {
;     ...
;         for (int t = 0; t < nt; t += 2) {
;             const bool last = (t == nt - 2);
;             const char* a1 = cA + (size_t)(t + 1) * kstep;
;             const char* a2 = last ? nA : cA + (size_t)(t + 2) * kstep; const char* b2 = last ? nB : cB + (size_t)(t + 2) * kstep;
;             const char* a3 = a2 + kstep; const char* b3 = b2 + kstep;
;             PG8_LDB(B0, 0, 0); PG8_SCHED; PG8_LDA(At, 0, 0); PG8_STAGE(PG8_SA(1, 1), a1 + hstep, voffA);
;             PG8_WAIT_L(8); PG8_BAR; PG8_WAIT_L(0); PG8_MMA(0, 0, At, B0); PG8_BAR; PG8_SCHED;
;             PG8_LDB(B1, 0, 1); PG8_STAGE(PG8_SB(0, 0), b2, voffB);
;             PG8_BAR; PG8_WAIT_L(0); PG8_MMA(0, 1, At, B1); PG8_BAR;
;             PG8_LDA(At, 0, 1); PG8_STAGE(PG8_SA(0, 0), a2, voffA);
;             PG8_BAR; PG8_WAIT_L(0); PG8_MMA(1, 0, At, B0); PG8_BAR; PG8_SCHED;
;             PG8_STAGE(PG8_SB(0, 1), b2 + hstep, voffB);
;             PG8_WAIT_V(6); PG8_BAR; PG8_MMA(1, 1, At, B1); PG8_BAR;
;             PG8_LDB(B0, 1, 0); PG8_SCHED; PG8_LDA(At, 1, 0); PG8_STAGE(PG8_SA(0, 1), a2 + hstep, voffA);
;             PG8_WAIT_L(8); PG8_BAR; PG8_WAIT_L(0); PG8_MMA(0, 0, At, B0); PG8_BAR; PG8_SCHED;
;             PG8_LDB(B1, 1, 1); PG8_STAGE(PG8_SB(1, 0), b3, voffB);
;             PG8_BAR; PG8_WAIT_L(0); PG8_MMA(0, 1, At, B1); PG8_BAR;
;             PG8_LDA(At, 1, 1); PG8_STAGE(PG8_SA(1, 0), a3, voffA);
;             PG8_BAR; PG8_WAIT_L(0); PG8_MMA(1, 0, At, B0); PG8_BAR; PG8_SCHED;
;             PG8_STAGE(PG8_SB(1, 1), b3 + hstep, voffB);
;             PG8_WAIT_V(6); PG8_BAR; PG8_MMA(1, 1, At, B1); PG8_BAR;
	s_waitcnt lgkmcnt(0)
	v_mfma_f32_16x16x32_bf16 v[60:63], v[146:149], v[162:165], v[60:63]
	v_mfma_f32_16x16x32_bf16 v[56:59], v[154:157], v[162:165], v[56:59]
	v_mfma_f32_16x16x32_bf16 v[52:55], v[146:149], v[170:173], v[52:55]
	v_mfma_f32_16x16x32_bf16 v[44:47], v[154:157], v[170:173], v[44:47]
	v_mfma_f32_16x16x32_bf16 v[36:39], v[146:149], v[178:181], v[36:39]
	v_mfma_f32_16x16x32_bf16 v[28:31], v[154:157], v[178:181], v[28:31]
	v_mfma_f32_16x16x32_bf16 v[20:23], v[146:149], v[186:189], v[20:23]
	v_mfma_f32_16x16x32_bf16 v[12:15], v[154:157], v[186:189], v[12:15]
	v_mfma_f32_16x16x32_bf16 v[60:63], v[150:153], v[166:169], v[60:63]
	v_mfma_f32_16x16x32_bf16 v[56:59], v[158:161], v[166:169], v[56:59]
	v_mfma_f32_16x16x32_bf16 v[52:55], v[150:153], v[174:177], v[52:55]
	v_mfma_f32_16x16x32_bf16 v[44:47], v[158:161], v[174:177], v[44:47]
	v_mfma_f32_16x16x32_bf16 v[36:39], v[150:153], v[182:185], v[36:39]
	v_mfma_f32_16x16x32_bf16 v[28:31], v[158:161], v[182:185], v[28:31]
	v_mfma_f32_16x16x32_bf16 v[20:23], v[150:153], v[190:193], v[20:23]
	v_mfma_f32_16x16x32_bf16 v[12:15], v[158:161], v[190:193], v[12:15]
	s_barrier
	s_setprio 0
	s_add_u32 s24, s24, 0x40080
	s_addc_u32 s25, s25, 0
	s_add_i32 s26, s26, s34
	s_mov_b32 m0, s26
	s_nop 0
	global_load_lds_dwordx4 v130, s[24:25]
	s_add_i32 m0, s26, 0x2000
	s_nop 0
	global_load_lds_dwordx4 v134, s[24:25]
	s_waitcnt vmcnt(8)
	s_setprio 1
	s_barrier
	v_mfma_f32_16x16x32_bf16 v[48:51], v[194:197], v[162:165], v[48:51]
	v_mfma_f32_16x16x32_bf16 v[40:43], v[206:209], v[162:165], v[40:43]
	v_mfma_f32_16x16x32_bf16 v[32:35], v[194:197], v[170:173], v[32:35]
	v_mfma_f32_16x16x32_bf16 v[24:27], v[206:209], v[170:173], v[24:27]
	v_mfma_f32_16x16x32_bf16 v[16:19], v[194:197], v[178:181], v[16:19]
	v_mfma_f32_16x16x32_bf16 v[8:11], v[206:209], v[178:181], v[8:11]
	v_mfma_f32_16x16x32_bf16 v[4:7], v[194:197], v[186:189], v[4:7]
	v_mfma_f32_16x16x32_bf16 v[0:3], v[206:209], v[186:189], v[0:3]
	v_mfma_f32_16x16x32_bf16 v[48:51], v[202:205], v[166:169], v[48:51]
	v_mfma_f32_16x16x32_bf16 v[40:43], v[210:213], v[166:169], v[40:43]
	v_mfma_f32_16x16x32_bf16 v[32:35], v[202:205], v[174:177], v[32:35]
	v_mfma_f32_16x16x32_bf16 v[24:27], v[210:213], v[174:177], v[24:27]
	v_mfma_f32_16x16x32_bf16 v[16:19], v[202:205], v[182:185], v[16:19]
	v_mfma_f32_16x16x32_bf16 v[8:11], v[210:213], v[182:185], v[8:11]
	v_mfma_f32_16x16x32_bf16 v[4:7], v[202:205], v[190:193], v[4:7]
	v_mfma_f32_16x16x32_bf16 v[0:3], v[210:213], v[190:193], v[0:3]
	s_barrier
	s_setprio 0
	s_add_i32 s58, s58, 2
	s_add_u32 s22, s22, 0x100
	s_addc_u32 s23, s23, 0
	s_add_u32 s56, s56, 0x100
	s_addc_u32 s57, s57, 0
	s_cmp_gt_u32 s58, 13
.LBB0_713:
	ds_read_b128 v[146:149], v143
	ds_read_b128 v[150:153], v143 offset:1024
	ds_read_b128 v[154:157], v143 offset:2048
	ds_read_b128 v[158:161], v143 offset:3072
	s_add_u32 s24, s22, 0xfffc0080
	s_addc_u32 s25, s23, -1
	s_cmp_eq_u32 s58, 12
	s_cselect_b32 s27, s15, s25
	s_cselect_b32 s26, s54, s24
	s_cselect_b32 s25, s13, s57
	s_cselect_b32 s24, s55, s56
	s_add_i32 m0, s21, 0xc000
	ds_read_b128 v[162:165], v144
	ds_read_b128 v[166:169], v144 offset:1024
	ds_read_b128 v[170:173], v144 offset:2048
	ds_read_b128 v[174:177], v144 offset:3072
	ds_read_b128 v[178:181], v144 offset:4096
	ds_read_b128 v[182:185], v144 offset:5120
	ds_read_b128 v[186:189], v144 offset:6144
	ds_read_b128 v[190:193], v144 offset:7168
	global_load_lds_dwordx4 v136, s[22:23]
	s_add_i32 m0, s21, 0xe000
	s_nop 0
	global_load_lds_dwordx4 v138, s[22:23]
	s_waitcnt lgkmcnt(8)
	s_waitcnt vmcnt(8)
	s_setprio 1
	s_barrier
	s_waitcnt lgkmcnt(0)
	v_mfma_f32_16x16x32_bf16 v[124:127], v[146:149], v[162:165], v[124:127]
	v_mfma_f32_16x16x32_bf16 v[120:123], v[154:157], v[162:165], v[120:123]
	v_mfma_f32_16x16x32_bf16 v[116:119], v[146:149], v[170:173], v[116:119]
	v_mfma_f32_16x16x32_bf16 v[108:111], v[154:157], v[170:173], v[108:111]
	v_mfma_f32_16x16x32_bf16 v[100:103], v[146:149], v[178:181], v[100:103]
	v_mfma_f32_16x16x32_bf16 v[92:95], v[154:157], v[178:181], v[92:95]
	v_mfma_f32_16x16x32_bf16 v[84:87], v[146:149], v[186:189], v[84:87]
	v_mfma_f32_16x16x32_bf16 v[76:79], v[154:157], v[186:189], v[76:79]
	v_mfma_f32_16x16x32_bf16 v[124:127], v[150:153], v[166:169], v[124:127]
	v_mfma_f32_16x16x32_bf16 v[120:123], v[158:161], v[166:169], v[120:123]
	v_mfma_f32_16x16x32_bf16 v[116:119], v[150:153], v[174:177], v[116:119]
	v_mfma_f32_16x16x32_bf16 v[108:111], v[158:161], v[174:177], v[108:111]
	v_mfma_f32_16x16x32_bf16 v[100:103], v[150:153], v[182:185], v[100:103]
	v_mfma_f32_16x16x32_bf16 v[92:95], v[158:161], v[182:185], v[92:95]
	v_mfma_f32_16x16x32_bf16 v[84:87], v[150:153], v[190:193], v[84:87]
	v_mfma_f32_16x16x32_bf16 v[76:79], v[158:161], v[190:193], v[76:79]
	s_barrier
	s_setprio 0
	s_add_i32 s59, s46, s34
	s_mov_b32 m0, s59
	ds_read_b128 v[194:197], v145
	ds_read_b128 v[202:205], v145 offset:1024
	ds_read_b128 v[206:209], v145 offset:2048
	ds_read_b128 v[210:213], v145 offset:3072
	global_load_lds_dwordx4 v130, s[24:25]
	s_add_i32 m0, s59, 0x2000
	s_nop 0
	global_load_lds_dwordx4 v134, s[24:25]
	s_waitcnt vmcnt(8)
	s_setprio 1
	s_barrier
; #define PG8_STAGE(bufoff, gbase, voff) do { _Pragma("unroll") for (int _i = 0; _i < 2; ++_i) \
;         __builtin_amdgcn_global_load_lds((const unsigned*)((const char*)(gbase) + (voff)[_i]), (LAS unsigned*)(lds + (bufoff) + ldsw + _i * 8192), 16, 0, 0); } while (0)
; #define PG8_LDA(dst, b, h) do { _Pragma("unroll") for (int m = 0; m < 4; ++m) _Pragma("unroll") for (int k = 0; k < 2; ++k) dst[m][k] = *(const LAS bf16x8*)(lds + PG8_SA(b, h) + aoff + m * 2048 + k * 1024); } while (0)
; #define PG8_LDB(dst, b, h) do { _Pragma("unroll") for (int n = 0; n < 2; ++n) _Pragma("unroll") for (int k = 0; k < 2; ++k) dst[n][k] = *(const LAS bf16x8*)(lds + PG8_SB(b, h) + boff + n * 2048 + k * 1024); } while (0)
; #define PG8_MMA(ai, bj, At, Bt) do { __builtin_amdgcn_s_setprio(1); _Pragma("unroll") for (int m = 0; m < 4; ++m) _Pragma("unroll") for (int n = 0; n < 2; ++n) _Pragma("unroll") for (int k = 0; k < 2; ++k) \
;         acc[ai][bj][m][n] = __builtin_amdgcn_mfma_f32_16x16x32_bf16(Bt[n][k], At[m][k], acc[ai][bj][m][n], 0, 0, 0); __builtin_amdgcn_s_setprio(0); } while (0)
; #define PG8_WAIT_V(n) asm volatile("s_waitcnt vmcnt(" #n ")" ::: "memory")
; #define PG8_WAIT_L(n) asm volatile("s_waitcnt lgkmcnt(" #n ")" ::: "memory")
; #define PG8_BAR __builtin_amdgcn_s_barrier()
; #define PG8_SCHED __builtin_amdgcn_sched_barrier(0)
; template <class Epi, class Sched>
; __device__ __forceinline__ void gemm_phase(LAS unsigned char* lds, const Gemm g, const Sched& S, const Epi& E) {
;     ...
;             PG8_LDB(B1, 0, 1); PG8_STAGE(PG8_SB(0, 0), b2, voffB);
;             PG8_BAR; PG8_WAIT_L(0); PG8_MMA(0, 1, At, B1); PG8_BAR;
;             PG8_LDA(At, 0, 1); PG8_STAGE(PG8_SA(0, 0), a2, voffA);
;             PG8_BAR; PG8_WAIT_L(0); PG8_MMA(1, 0, At, B0); PG8_BAR; PG8_SCHED;
;             PG8_STAGE(PG8_SB(0, 1), b2 + hstep, voffB);
;             PG8_WAIT_V(6); PG8_BAR; PG8_MMA(1, 1, At, B1); PG8_BAR;
;             PG8_LDB(B0, 1, 0); PG8_SCHED; PG8_LDA(At, 1, 0); PG8_STAGE(PG8_SA(0, 1), a2 + hstep, voffA);
;             PG8_WAIT_L(8); PG8_BAR; PG8_WAIT_L(0); PG8_MMA(0, 0, At, B0); PG8_BAR; PG8_SCHED;
	s_waitcnt lgkmcnt(0)
	v_mfma_f32_16x16x32_bf16 v[112:115], v[194:197], v[162:165], v[112:115]
	v_mfma_f32_16x16x32_bf16 v[104:107], v[206:209], v[162:165], v[104:107]
	v_mfma_f32_16x16x32_bf16 v[96:99], v[194:197], v[170:173], v[96:99]
	v_mfma_f32_16x16x32_bf16 v[88:91], v[206:209], v[170:173], v[88:91]
	v_mfma_f32_16x16x32_bf16 v[80:83], v[194:197], v[178:181], v[80:83]
	v_mfma_f32_16x16x32_bf16 v[72:75], v[206:209], v[178:181], v[72:75]
	v_mfma_f32_16x16x32_bf16 v[68:71], v[194:197], v[186:189], v[68:71]
	v_mfma_f32_16x16x32_bf16 v[64:67], v[206:209], v[186:189], v[64:67]
	v_mfma_f32_16x16x32_bf16 v[112:115], v[202:205], v[166:169], v[112:115]
	v_mfma_f32_16x16x32_bf16 v[104:107], v[210:213], v[166:169], v[104:107]
	v_mfma_f32_16x16x32_bf16 v[96:99], v[202:205], v[174:177], v[96:99]
	v_mfma_f32_16x16x32_bf16 v[88:91], v[210:213], v[174:177], v[88:91]
	v_mfma_f32_16x16x32_bf16 v[80:83], v[202:205], v[182:185], v[80:83]
	v_mfma_f32_16x16x32_bf16 v[72:75], v[210:213], v[182:185], v[72:75]
	v_mfma_f32_16x16x32_bf16 v[68:71], v[202:205], v[190:193], v[68:71]
	v_mfma_f32_16x16x32_bf16 v[64:67], v[210:213], v[190:193], v[64:67]
	s_barrier
	s_setprio 0
	s_mov_b32 m0, s21
	v_lshl_add_u64 v[216:217], s[26:27], 0, v[128:129]
	ds_read_b128 v[162:165], v144 offset:16384
	ds_read_b128 v[166:169], v144 offset:17408
	ds_read_b128 v[170:173], v144 offset:18432
	ds_read_b128 v[174:177], v144 offset:19456
	ds_read_b128 v[178:181], v144 offset:20480
	ds_read_b128 v[182:185], v144 offset:21504
	ds_read_b128 v[186:189], v144 offset:22528
	ds_read_b128 v[190:193], v144 offset:23552
	global_load_lds_dwordx4 v128, s[26:27]
	v_lshl_add_u64 v[218:219], s[26:27], 0, v[132:133]
	s_mov_b32 m0, s35
	s_nop 0
	global_load_lds_dwordx4 v132, s[26:27]
	s_setprio 1
	s_barrier
	s_waitcnt lgkmcnt(0)
	v_mfma_f32_16x16x32_bf16 v[60:63], v[146:149], v[162:165], v[60:63]
	v_mfma_f32_16x16x32_bf16 v[56:59], v[154:157], v[162:165], v[56:59]
	v_mfma_f32_16x16x32_bf16 v[52:55], v[146:149], v[170:173], v[52:55]
	v_mfma_f32_16x16x32_bf16 v[44:47], v[154:157], v[170:173], v[44:47]
	v_mfma_f32_16x16x32_bf16 v[36:39], v[146:149], v[178:181], v[36:39]
	v_mfma_f32_16x16x32_bf16 v[28:31], v[154:157], v[178:181], v[28:31]
	v_mfma_f32_16x16x32_bf16 v[20:23], v[146:149], v[186:189], v[20:23]
	v_mfma_f32_16x16x32_bf16 v[12:15], v[154:157], v[186:189], v[12:15]
	v_mfma_f32_16x16x32_bf16 v[60:63], v[150:153], v[166:169], v[60:63]
	v_mfma_f32_16x16x32_bf16 v[56:59], v[158:161], v[166:169], v[56:59]
	v_mfma_f32_16x16x32_bf16 v[52:55], v[150:153], v[174:177], v[52:55]
	v_mfma_f32_16x16x32_bf16 v[44:47], v[158:161], v[174:177], v[44:47]
	v_mfma_f32_16x16x32_bf16 v[36:39], v[150:153], v[182:185], v[36:39]
	v_mfma_f32_16x16x32_bf16 v[28:31], v[158:161], v[182:185], v[28:31]
	v_mfma_f32_16x16x32_bf16 v[20:23], v[150:153], v[190:193], v[20:23]
	v_mfma_f32_16x16x32_bf16 v[12:15], v[158:161], v[190:193], v[12:15]
	s_barrier
	s_setprio 0
	s_add_u32 s60, s24, 0x40000
	s_addc_u32 s61, s25, 0
	s_add_i32 s59, s47, s34
	s_mov_b32 m0, s59
	s_nop 0
	global_load_lds_dwordx4 v130, s[60:61]
	s_add_i32 m0, s59, 0x2000
	s_nop 0
	global_load_lds_dwordx4 v134, s[60:61]
	s_add_u32 s26, s26, 0x40000
	s_addc_u32 s27, s27, 0
	s_mov_b32 m0, s36
	s_nop 0
	global_load_lds_dwordx4 v128, s[26:27]
	s_mov_b32 m0, s37
	s_nop 0
	global_load_lds_dwordx4 v132, s[26:27]
	s_waitcnt vmcnt(10)
	s_setprio 1
	s_barrier
	v_mfma_f32_16x16x32_bf16 v[48:51], v[194:197], v[162:165], v[48:51]
	v_mfma_f32_16x16x32_bf16 v[40:43], v[206:209], v[162:165], v[40:43]
	v_mfma_f32_16x16x32_bf16 v[32:35], v[194:197], v[170:173], v[32:35]
	v_mfma_f32_16x16x32_bf16 v[24:27], v[206:209], v[170:173], v[24:27]
	v_mfma_f32_16x16x32_bf16 v[16:19], v[194:197], v[178:181], v[16:19]
	v_mfma_f32_16x16x32_bf16 v[8:11], v[206:209], v[178:181], v[8:11]
	v_mfma_f32_16x16x32_bf16 v[4:7], v[194:197], v[186:189], v[4:7]
	v_mfma_f32_16x16x32_bf16 v[0:3], v[206:209], v[186:189], v[0:3]
	v_mfma_f32_16x16x32_bf16 v[48:51], v[202:205], v[166:169], v[48:51]
	v_mfma_f32_16x16x32_bf16 v[40:43], v[210:213], v[166:169], v[40:43]
	v_mfma_f32_16x16x32_bf16 v[32:35], v[202:205], v[174:177], v[32:35]
	v_mfma_f32_16x16x32_bf16 v[24:27], v[210:213], v[174:177], v[24:27]
	v_mfma_f32_16x16x32_bf16 v[16:19], v[202:205], v[182:185], v[16:19]
	v_mfma_f32_16x16x32_bf16 v[8:11], v[210:213], v[182:185], v[8:11]
	v_mfma_f32_16x16x32_bf16 v[4:7], v[202:205], v[190:193], v[4:7]
	v_mfma_f32_16x16x32_bf16 v[0:3], v[210:213], v[190:193], v[0:3]
	s_barrier
	s_setprio 0
	s_add_i32 s59, 0, 0x18000
	ds_read_b128 v[146:149], v145 offset:16384
	ds_read_b128 v[150:153], v145 offset:17408
	ds_read_b128 v[154:157], v145 offset:18432
	ds_read_b128 v[158:161], v145 offset:19456
	ds_read_b128 v[162:165], v144 offset:32768
	ds_read_b128 v[166:169], v144 offset:33792
	ds_read_b128 v[170:173], v144 offset:34816
	ds_read_b128 v[174:177], v144 offset:35840
	ds_read_b128 v[178:181], v144 offset:36864
	ds_read_b128 v[182:185], v144 offset:37888
	ds_read_b128 v[186:189], v144 offset:38912
	ds_read_b128 v[190:193], v144 offset:39936
	s_waitcnt lgkmcnt(8)
	s_waitcnt vmcnt(8)
	s_setprio 1
	s_barrier
; #define PG8_STAGE(bufoff, gbase, voff) do { _Pragma("unroll") for (int _i = 0; _i < 2; ++_i) \
;         __builtin_amdgcn_global_load_lds((const unsigned*)((const char*)(gbase) + (voff)[_i]), (LAS unsigned*)(lds + (bufoff) + ldsw + _i * 8192), 16, 0, 0); } while (0)
; #define PG8_LDA(dst, b, h) do { _Pragma("unroll") for (int m = 0; m < 4; ++m) _Pragma("unroll") for (int k = 0; k < 2; ++k) dst[m][k] = *(const LAS bf16x8*)(lds + PG8_SA(b, h) + aoff + m * 2048 + k * 1024); } while (0)
; #define PG8_LDB(dst, b, h) do { _Pragma("unroll") for (int n = 0; n < 2; ++n) _Pragma("unroll") for (int k = 0; k < 2; ++k) dst[n][k] = *(const LAS bf16x8*)(lds + PG8_SB(b, h) + boff + n * 2048 + k * 1024); } while (0)
; #define PG8_MMA(ai, bj, At, Bt) do { __builtin_amdgcn_s_setprio(1); _Pragma("unroll") for (int m = 0; m < 4; ++m) _Pragma("unroll") for (int n = 0; n < 2; ++n) _Pragma("unroll") for (int k = 0; k < 2; ++k) \
;         acc[ai][bj][m][n] = __builtin_amdgcn_mfma_f32_16x16x32_bf16(Bt[n][k], At[m][k], acc[ai][bj][m][n], 0, 0, 0); __builtin_amdgcn_s_setprio(0); } while (0)
; #define PG8_WAIT_V(n) asm volatile("s_waitcnt vmcnt(" #n ")" ::: "memory")
; #define PG8_WAIT_L(n) asm volatile("s_waitcnt lgkmcnt(" #n ")" ::: "memory")
; #define PG8_BAR __builtin_amdgcn_s_barrier()
; #define PG8_SCHED __builtin_amdgcn_sched_barrier(0)
; template <class Epi, class Sched>
; __device__ __forceinline__ void gemm_phase(LAS unsigned char* lds, const Gemm g, const Sched& S, const Epi& E) {
;     ...
;             PG8_WAIT_L(8); PG8_BAR; PG8_WAIT_L(0); PG8_MMA(0, 0, At, B0); PG8_BAR; PG8_SCHED;
;             PG8_LDB(B1, 1, 1); PG8_STAGE(PG8_SB(1, 0), b3, voffB);
;             PG8_BAR; PG8_WAIT_L(0); PG8_MMA(0, 1, At, B1); PG8_BAR;
;             PG8_LDA(At, 1, 1); PG8_STAGE(PG8_SA(1, 0), a3, voffA);
;             PG8_BAR; PG8_WAIT_L(0); PG8_MMA(1, 0, At, B0); PG8_BAR; PG8_SCHED;
;             PG8_STAGE(PG8_SB(1, 1), b3 + hstep, voffB);
;             PG8_WAIT_V(6); PG8_BAR; PG8_MMA(1, 1, At, B1); PG8_BAR;
	s_waitcnt lgkmcnt(0)
	v_mfma_f32_16x16x32_bf16 v[124:127], v[146:149], v[162:165], v[124:127]
	v_mfma_f32_16x16x32_bf16 v[120:123], v[154:157], v[162:165], v[120:123]
	v_mfma_f32_16x16x32_bf16 v[116:119], v[146:149], v[170:173], v[116:119]
	v_mfma_f32_16x16x32_bf16 v[108:111], v[154:157], v[170:173], v[108:111]
	v_mfma_f32_16x16x32_bf16 v[100:103], v[146:149], v[178:181], v[100:103]
	v_mfma_f32_16x16x32_bf16 v[92:95], v[154:157], v[178:181], v[92:95]
	v_mfma_f32_16x16x32_bf16 v[84:87], v[146:149], v[186:189], v[84:87]
	v_mfma_f32_16x16x32_bf16 v[76:79], v[154:157], v[186:189], v[76:79]
	v_mfma_f32_16x16x32_bf16 v[124:127], v[150:153], v[166:169], v[124:127]
	v_mfma_f32_16x16x32_bf16 v[120:123], v[158:161], v[166:169], v[120:123]
	v_mfma_f32_16x16x32_bf16 v[116:119], v[150:153], v[174:177], v[116:119]
	v_mfma_f32_16x16x32_bf16 v[108:111], v[158:161], v[174:177], v[108:111]
	v_mfma_f32_16x16x32_bf16 v[100:103], v[150:153], v[182:185], v[100:103]
	v_mfma_f32_16x16x32_bf16 v[92:95], v[158:161], v[182:185], v[92:95]
	v_mfma_f32_16x16x32_bf16 v[84:87], v[150:153], v[190:193], v[84:87]
	v_mfma_f32_16x16x32_bf16 v[76:79], v[158:161], v[190:193], v[76:79]
	s_barrier
	s_setprio 0
	s_add_i32 s26, 0, 0x1c000
	s_add_i32 s27, s59, s34
	v_add_u32_e32 v210, s26, v142
	s_add_u32 s0, s24, 0x80
	s_addc_u32 s1, s25, 0
	s_mov_b32 m0, s27
	ds_read_b128 v[194:197], v210
	ds_read_b128 v[202:205], v210 offset:1024
	ds_read_b128 v[206:209], v210 offset:2048
	ds_read_b128 v[210:213], v210 offset:3072
	global_load_lds_dwordx4 v130, s[0:1]
	s_add_i32 m0, s27, 0x2000
	s_nop 0
	global_load_lds_dwordx4 v134, s[0:1]
	s_waitcnt vmcnt(8)
	s_setprio 1
	s_barrier
	s_waitcnt lgkmcnt(0)
	v_mfma_f32_16x16x32_bf16 v[112:115], v[194:197], v[162:165], v[112:115]
	v_mfma_f32_16x16x32_bf16 v[104:107], v[206:209], v[162:165], v[104:107]
	v_mfma_f32_16x16x32_bf16 v[96:99], v[194:197], v[170:173], v[96:99]
	v_mfma_f32_16x16x32_bf16 v[88:91], v[206:209], v[170:173], v[88:91]
	v_mfma_f32_16x16x32_bf16 v[80:83], v[194:197], v[178:181], v[80:83]
	v_mfma_f32_16x16x32_bf16 v[72:75], v[206:209], v[178:181], v[72:75]
	v_mfma_f32_16x16x32_bf16 v[68:71], v[194:197], v[186:189], v[68:71]
	v_mfma_f32_16x16x32_bf16 v[64:67], v[206:209], v[186:189], v[64:67]
	v_mfma_f32_16x16x32_bf16 v[112:115], v[202:205], v[166:169], v[112:115]
	v_mfma_f32_16x16x32_bf16 v[104:107], v[210:213], v[166:169], v[104:107]
	v_mfma_f32_16x16x32_bf16 v[96:99], v[202:205], v[174:177], v[96:99]
	v_mfma_f32_16x16x32_bf16 v[88:91], v[210:213], v[174:177], v[88:91]
	v_mfma_f32_16x16x32_bf16 v[80:83], v[202:205], v[182:185], v[80:83]
	v_mfma_f32_16x16x32_bf16 v[72:75], v[210:213], v[182:185], v[72:75]
	v_mfma_f32_16x16x32_bf16 v[68:71], v[202:205], v[190:193], v[68:71]
	v_mfma_f32_16x16x32_bf16 v[64:67], v[210:213], v[190:193], v[64:67]
	s_barrier
	s_setprio 0
	s_mov_b32 m0, s43
	s_mov_b64 s[0:1], 0x80
	v_lshl_add_u64 v[198:199], v[216:217], 0, s[0:1]
	ds_read_b128 v[162:165], v144 offset:49152
	ds_read_b128 v[166:169], v144 offset:50176
	ds_read_b128 v[170:173], v144 offset:51200
	ds_read_b128 v[174:177], v144 offset:52224
	ds_read_b128 v[178:181], v144 offset:53248
	ds_read_b128 v[182:185], v144 offset:54272
	ds_read_b128 v[186:189], v144 offset:55296
	ds_read_b128 v[190:193], v144 offset:56320
	global_load_lds_dwordx4 v[198:199], off
	v_lshl_add_u64 v[198:199], v[218:219], 0, s[0:1]
	s_mov_b32 m0, s44
	s_nop 0
	global_load_lds_dwordx4 v[198:199], off
	s_setprio 1
	s_barrier
	s_waitcnt lgkmcnt(0)
	v_mfma_f32_16x16x32_bf16 v[60:63], v[146:149], v[162:165], v[60:63]
	v_mfma_f32_16x16x32_bf16 v[56:59], v[154:157], v[162:165], v[56:59]
	v_mfma_f32_16x16x32_bf16 v[52:55], v[146:149], v[170:173], v[52:55]
	v_mfma_f32_16x16x32_bf16 v[44:47], v[154:157], v[170:173], v[44:47]
	v_mfma_f32_16x16x32_bf16 v[36:39], v[146:149], v[178:181], v[36:39]
	v_mfma_f32_16x16x32_bf16 v[28:31], v[154:157], v[178:181], v[28:31]
	v_mfma_f32_16x16x32_bf16 v[20:23], v[146:149], v[186:189], v[20:23]
	v_mfma_f32_16x16x32_bf16 v[12:15], v[154:157], v[186:189], v[12:15]
	v_mfma_f32_16x16x32_bf16 v[60:63], v[150:153], v[166:169], v[60:63]
	v_mfma_f32_16x16x32_bf16 v[56:59], v[158:161], v[166:169], v[56:59]
	v_mfma_f32_16x16x32_bf16 v[52:55], v[150:153], v[174:177], v[52:55]
	v_mfma_f32_16x16x32_bf16 v[44:47], v[158:161], v[174:177], v[44:47]
	v_mfma_f32_16x16x32_bf16 v[36:39], v[150:153], v[182:185], v[36:39]
	v_mfma_f32_16x16x32_bf16 v[28:31], v[158:161], v[182:185], v[28:31]
	v_mfma_f32_16x16x32_bf16 v[20:23], v[150:153], v[190:193], v[20:23]
	v_mfma_f32_16x16x32_bf16 v[12:15], v[158:161], v[190:193], v[12:15]
	s_barrier
	s_setprio 0
	s_add_u32 s24, s24, 0x40080
	s_addc_u32 s25, s25, 0
	s_add_i32 s26, s26, s34
	s_mov_b32 m0, s26
	s_nop 0
	global_load_lds_dwordx4 v130, s[24:25]
	s_add_i32 m0, s26, 0x2000
	s_nop 0
	global_load_lds_dwordx4 v134, s[24:25]
	s_waitcnt vmcnt(8)
	s_setprio 1
	s_barrier
	v_mfma_f32_16x16x32_bf16 v[48:51], v[194:197], v[162:165], v[48:51]
	v_mfma_f32_16x16x32_bf16 v[40:43], v[206:209], v[162:165], v[40:43]
	v_mfma_f32_16x16x32_bf16 v[32:35], v[194:197], v[170:173], v[32:35]
	v_mfma_f32_16x16x32_bf16 v[24:27], v[206:209], v[170:173], v[24:27]
	v_mfma_f32_16x16x32_bf16 v[16:19], v[194:197], v[178:181], v[16:19]
	v_mfma_f32_16x16x32_bf16 v[8:11], v[206:209], v[178:181], v[8:11]
	v_mfma_f32_16x16x32_bf16 v[4:7], v[194:197], v[186:189], v[4:7]
	v_mfma_f32_16x16x32_bf16 v[0:3], v[206:209], v[186:189], v[0:3]
	v_mfma_f32_16x16x32_bf16 v[48:51], v[202:205], v[166:169], v[48:51]
	v_mfma_f32_16x16x32_bf16 v[40:43], v[210:213], v[166:169], v[40:43]
	v_mfma_f32_16x16x32_bf16 v[32:35], v[202:205], v[174:177], v[32:35]
	v_mfma_f32_16x16x32_bf16 v[24:27], v[210:213], v[174:177], v[24:27]
	v_mfma_f32_16x16x32_bf16 v[16:19], v[202:205], v[182:185], v[16:19]
	v_mfma_f32_16x16x32_bf16 v[8:11], v[210:213], v[182:185], v[8:11]
	v_mfma_f32_16x16x32_bf16 v[4:7], v[202:205], v[190:193], v[4:7]
	v_mfma_f32_16x16x32_bf16 v[0:3], v[210:213], v[190:193], v[0:3]
	s_barrier
; __device__ __forceinline__ unsigned cvt_pk_bf16(float lo, float hi) { unsigned r; asm volatile("v_cvt_pk_bf16_f32 %0, %1, %2" : "=v"(r) : "v"(lo), "v"(hi)); return r; }
; #define PG8_WAIT_V(n) asm volatile("s_waitcnt vmcnt(" #n ")" ::: "memory")
; #define PG8_BAR __builtin_amdgcn_s_barrier()
; template <class Epi, class Sched>
; __device__ __forceinline__ void gemm_phase(LAS unsigned char* lds, const Gemm g, const Sched& S, const Epi& E) {
;     ...
;         if (!has_next) break;
; #pragma unroll
;         for (int a = 0; a < 2; ++a)
; #pragma unroll
;             for (int b = 0; b < 2; ++b)
; #pragma unroll
;                 for (int m = 0; m < 4; ++m)
; #pragma unroll
;                     for (int n = 0; n < 2; ++n) acc[a][b][m][n] = (f32x4){0.f, 0.f, 0.f, 0.f};
;         cur = nxt; cA = nA; cB = nB; ++ui;
;     }
;     PG8_WAIT_V(0);
;     if (wr == 0) PG8_BAR;
;     __device__ __forceinline__ void operator()(const AccT& acc, const Unit& u, int wr, int wc, int fr, int fq) const {
;     ...
;         const int rbase = u.pm * 256 + wr * 64 + fr;
;         const int tb = u.pn * 256 + wc * 32 + 8 * fq;
; #pragma unroll
;         for (int ai = 0; ai < 2; ++ai)
; #pragma unroll
;             for (int m = 0; m < 4; ++m) {
;                 const int r = rbase + ai * 128 + m * 16;
; #pragma unroll
;                 for (int bj = 0; bj < 2; ++bj) {
;                     const int t0 = tb + bj * 128;
;                     const f32x4 v0 = acc[ai][bj][m][0], v1 = acc[ai][bj][m][1];
;                     u32x4 w; w.x = cvt_pk_bf16(v0[0], v0[1]); w.y = cvt_pk_bf16(v0[2], v0[3]); w.z = cvt_pk_bf16(v1[0], v1[1]); w.w = cvt_pk_bf16(v1[2], v1[3]);
;                     *(u32x4*)(VT + (size_t)r * NT + t0) = w;
;                 }
;             }
	s_setprio 0
	s_add_i32 s58, s58, 2
	s_add_u32 s22, s22, 0x100
	s_addc_u32 s23, s23, 0
	s_add_u32 s56, s56, 0x100
	s_addc_u32 s57, s57, 0
	s_cmp_gt_u32 s58, 13
	s_cbranch_scc0 .LBB0_713
	v_mov_b32_e32 v146, v140
	v_mov_b32_e32 v147, v141
	s_lshl_b32 s13, s20, 8
	s_add_i32 s13, s13, s41
	v_add_u32_e32 v146, s13, v146
	s_lshl_b32 s13, s53, 8
	s_or_b32 s13, s13, s42
	v_lshl_add_u32 v148, v147, 3, s13
	v_ashrrev_i32_e32 v147, 31, v146
	v_cvt_pk_bf16_f32 v124, v124, v125
	v_cvt_pk_bf16_f32 v125, v126, v127
	v_cvt_pk_bf16_f32 v126, v120, v121
	v_lshlrev_b64 v[120:121], 14, v[146:147]
	v_lshl_add_u64 v[120:121], s[62:63], 0, v[120:121]
	v_ashrrev_i32_e32 v149, 31, v148
	v_lshl_add_u64 v[120:121], v[148:149], 1, v[120:121]
	s_mov_b32 s13, 0x40000
	v_cvt_pk_bf16_f32 v127, v122, v123
	global_store_dwordx4 v[120:121], v[124:127], off
	v_cvt_pk_bf16_f32 v112, v112, v113
	v_cvt_pk_bf16_f32 v113, v114, v115
	v_cvt_pk_bf16_f32 v114, v104, v105
	v_cvt_pk_bf16_f32 v115, v106, v107
	global_store_dwordx4 v[120:121], v[112:115], off offset:256
	v_cvt_pk_bf16_f32 v104, v116, v117
	v_cvt_pk_bf16_f32 v105, v118, v119
	v_cvt_pk_bf16_f32 v106, v108, v109
	v_cvt_pk_bf16_f32 v107, v110, v111
	s_mov_b64 s[22:23], 0x40000
	v_add_co_u32_e32 v110, vcc, s13, v120
	v_lshl_add_u64 v[108:109], v[120:121], 0, s[22:23]
	s_nop 0
	v_addc_co_u32_e32 v111, vcc, 0, v121, vcc
	s_mov_b32 s13, 0x80000
	global_store_dwordx4 v[110:111], v[104:107], off
	v_cvt_pk_bf16_f32 v96, v96, v97
	v_cvt_pk_bf16_f32 v97, v98, v99
	v_cvt_pk_bf16_f32 v98, v88, v89
	v_cvt_pk_bf16_f32 v99, v90, v91
	global_store_dwordx4 v[108:109], v[96:99], off offset:256
	v_cvt_pk_bf16_f32 v88, v100, v101
	v_cvt_pk_bf16_f32 v89, v102, v103
	v_cvt_pk_bf16_f32 v90, v92, v93
	v_cvt_pk_bf16_f32 v91, v94, v95
	s_mov_b64 s[22:23], 0x80000
	v_add_co_u32_e32 v94, vcc, s13, v120
	v_lshl_add_u64 v[92:93], v[120:121], 0, s[22:23]
	s_nop 0
	v_addc_co_u32_e32 v95, vcc, 0, v121, vcc
	global_store_dwordx4 v[94:95], v[88:91], off
	v_cvt_pk_bf16_f32 v80, v80, v81
	v_cvt_pk_bf16_f32 v81, v82, v83
	v_cvt_pk_bf16_f32 v82, v72, v73
	v_cvt_pk_bf16_f32 v83, v74, v75
	global_store_dwordx4 v[92:93], v[80:83], off offset:256
	v_cvt_pk_bf16_f32 v72, v84, v85
	v_cvt_pk_bf16_f32 v73, v86, v87
	v_cvt_pk_bf16_f32 v74, v76, v77
	v_cvt_pk_bf16_f32 v75, v78, v79
	s_mov_b64 s[22:23], 0xc0000
	v_add_co_u32_e32 v78, vcc, s48, v120
	v_lshl_add_u64 v[76:77], v[120:121], 0, s[22:23]
	s_nop 0
	v_addc_co_u32_e32 v79, vcc, 0, v121, vcc
	global_store_dwordx4 v[78:79], v[72:75], off
	v_cvt_pk_bf16_f32 v68, v68, v69
	v_cvt_pk_bf16_f32 v69, v70, v71
	v_cvt_pk_bf16_f32 v70, v64, v65
	v_cvt_pk_bf16_f32 v71, v66, v67
	global_store_dwordx4 v[76:77], v[68:71], off offset:256
	v_cvt_pk_bf16_f32 v60, v60, v61
	v_cvt_pk_bf16_f32 v61, v62, v63
	v_cvt_pk_bf16_f32 v62, v56, v57
	v_cvt_pk_bf16_f32 v63, v58, v59
	v_add_co_u32_e32 v58, vcc, s49, v120
	v_lshl_add_u64 v[56:57], v[120:121], 0, s[2:3]
	s_nop 0
	v_addc_co_u32_e32 v59, vcc, 0, v121, vcc
	global_store_dwordx4 v[58:59], v[60:63], off
	v_cvt_pk_bf16_f32 v48, v48, v49
	v_cvt_pk_bf16_f32 v49, v50, v51
	v_cvt_pk_bf16_f32 v50, v40, v41
	v_cvt_pk_bf16_f32 v51, v42, v43
	global_store_dwordx4 v[56:57], v[48:51], off offset:256
	v_cvt_pk_bf16_f32 v40, v52, v53
	v_cvt_pk_bf16_f32 v41, v54, v55
	v_cvt_pk_bf16_f32 v42, v44, v45
	v_cvt_pk_bf16_f32 v43, v46, v47
	v_add_co_u32_e32 v46, vcc, s50, v120
	v_lshl_add_u64 v[44:45], v[120:121], 0, s[4:5]
	s_nop 0
	v_addc_co_u32_e32 v47, vcc, 0, v121, vcc
	global_store_dwordx4 v[46:47], v[40:43], off
	v_cvt_pk_bf16_f32 v32, v32, v33
	v_cvt_pk_bf16_f32 v33, v34, v35
	v_cvt_pk_bf16_f32 v34, v24, v25
	v_cvt_pk_bf16_f32 v35, v26, v27
	global_store_dwordx4 v[44:45], v[32:35], off offset:256
	v_cvt_pk_bf16_f32 v24, v36, v37
	v_cvt_pk_bf16_f32 v25, v38, v39
	v_cvt_pk_bf16_f32 v26, v28, v29
	v_cvt_pk_bf16_f32 v27, v30, v31
	v_add_co_u32_e32 v30, vcc, s51, v120
	v_lshl_add_u64 v[28:29], v[120:121], 0, s[6:7]
	s_nop 0
	v_addc_co_u32_e32 v31, vcc, 0, v121, vcc
	global_store_dwordx4 v[30:31], v[24:27], off
	v_cvt_pk_bf16_f32 v16, v16, v17
	v_cvt_pk_bf16_f32 v17, v18, v19
	v_cvt_pk_bf16_f32 v18, v8, v9
	v_cvt_pk_bf16_f32 v19, v10, v11
	global_store_dwordx4 v[28:29], v[16:19], off offset:256
	v_cvt_pk_bf16_f32 v8, v20, v21
	v_cvt_pk_bf16_f32 v9, v22, v23
	v_cvt_pk_bf16_f32 v10, v12, v13
	v_cvt_pk_bf16_f32 v11, v14, v15
	v_add_co_u32_e32 v14, vcc, s52, v120
	v_lshl_add_u64 v[12:13], v[120:121], 0, s[8:9]
	s_nop 0
	v_addc_co_u32_e32 v15, vcc, 0, v121, vcc
	s_and_b64 vcc, exec, s[10:11]
	s_mov_b32 s53, s12
	s_mov_b32 s20, s14
	s_mov_b64 s[24:25], s[18:19]
	s_mov_b64 s[22:23], s[16:17]
	global_store_dwordx4 v[14:15], v[8:11], off
	v_cvt_pk_bf16_f32 v4, v4, v5
	v_cvt_pk_bf16_f32 v5, v6, v7
	v_cvt_pk_bf16_f32 v6, v0, v1
	v_cvt_pk_bf16_f32 v7, v2, v3
	global_store_dwordx4 v[12:13], v[4:7], off offset:256
	s_cbranch_vccz .LBB0_706
	s_waitcnt vmcnt(0)
	s_cmpk_gt_u32 s31, 0xff
	s_cbranch_scc1 .LBB0_717
	s_barrier

; #define PG8_STAGE(bufoff, gbase, voff) do { _Pragma("unroll") for (int _i = 0; _i < 2; ++_i) \
;         __builtin_amdgcn_global_load_lds((const unsigned*)((const char*)(gbase) + (voff)[_i]), (LAS unsigned*)(lds + (bufoff) + ldsw + _i * 8192), 16, 0, 0); } while (0)
; #define PG8_LDA(dst, b, h) do { _Pragma("unroll") for (int m = 0; m < 4; ++m) _Pragma("unroll") for (int k = 0; k < 2; ++k) dst[m][k] = *(const LAS bf16x8*)(lds + PG8_SA(b, h) + aoff + m * 2048 + k * 1024); } while (0)
; #define PG8_LDB(dst, b, h) do { _Pragma("unroll") for (int n = 0; n < 2; ++n) _Pragma("unroll") for (int k = 0; k < 2; ++k) dst[n][k] = *(const LAS bf16x8*)(lds + PG8_SB(b, h) + boff + n * 2048 + k * 1024); } while (0)
; #define PG8_WAIT_V(n) asm volatile("s_waitcnt vmcnt(" #n ")" ::: "memory")
; #define PG8_WAIT_L(n) asm volatile("s_waitcnt lgkmcnt(" #n ")" ::: "memory")
; #define PG8_BAR __builtin_amdgcn_s_barrier()
; #define PG8_SCHED __builtin_amdgcn_sched_barrier(0)
; template <class Epi, class Sched>
; __device__ __forceinline__ void gemm_phase(LAS unsigned char* lds, const Gemm g, const Sched& S, const Epi& E) {
;     ...
;         const bool has_next = S.next(ui + 1, nxt);
;         const char* nA = has_next ? (const char*)g.A + (size_t)nxt.pm * tstep : cA; const char* nB = has_next ? (const char*)g.Bt + (size_t)nxt.pn * tstep : cB;
;         for (int t = 0; t < nt; t += 2) {
;             const bool last = (t == nt - 2);
;             const char* a1 = cA + (size_t)(t + 1) * kstep;
;             const char* a2 = last ? nA : cA + (size_t)(t + 2) * kstep; const char* b2 = last ? nB : cB + (size_t)(t + 2) * kstep;
;             const char* a3 = a2 + kstep; const char* b3 = b2 + kstep;
;             PG8_LDB(B0, 0, 0); PG8_SCHED; PG8_LDA(At, 0, 0); PG8_STAGE(PG8_SA(1, 1), a1 + hstep, voffA);
;             PG8_WAIT_L(8); PG8_BAR; PG8_WAIT_L(0); PG8_MMA(0, 0, At, B0); PG8_BAR; PG8_SCHED;
;             PG8_LDB(B1, 0, 1); PG8_STAGE(PG8_SB(0, 0), b2, voffB);
;             PG8_BAR; PG8_WAIT_L(0); PG8_MMA(0, 1, At, B1); PG8_BAR;
;             PG8_LDA(At, 0, 1); PG8_STAGE(PG8_SA(0, 0), a2, voffA);
;             PG8_BAR; PG8_WAIT_L(0); PG8_MMA(1, 0, At, B0); PG8_BAR; PG8_SCHED;
;             PG8_STAGE(PG8_SB(0, 1), b2 + hstep, voffB);
;             PG8_WAIT_V(6); PG8_BAR; PG8_MMA(1, 1, At, B1); PG8_BAR;
.LBB0_825:
	s_ashr_i32 s7, s6, 31
	v_cmp_lt_i64_e32 vcc, s[8:9], v[156:157]
	s_lshl_b64 s[8:9], s[6:7], 20
	s_add_u32 s8, s22, s8
	s_addc_u32 s9, s23, s9
	s_and_b64 s[10:11], vcc, exec
	s_cselect_b32 s7, s9, s15
	s_cselect_b32 s39, s8, s14
	s_ashr_i32 s5, s4, 31
	s_lshl_b64 s[10:11], s[4:5], 20
	s_add_u32 s10, s50, s10
	s_addc_u32 s11, s51, s11
	s_and_b64 s[18:19], vcc, exec
	s_cselect_b32 s5, s11, s17
	s_cselect_b32 s40, s10, s16
	s_add_u32 s14, s14, 0x80080
	s_addc_u32 s15, s15, 0
	s_add_u32 s41, s16, 0x100
	s_addc_u32 s42, s17, 0
	s_mov_b32 s43, -2
	ds_read_b128 v[128:131], v168
	ds_read_b128 v[132:135], v168 offset:1024
	ds_read_b128 v[136:139], v168 offset:2048
	ds_read_b128 v[140:143], v168 offset:3072
	s_add_u32 s16, s14, 0xfff80080
	s_addc_u32 s17, s15, -1
	s_cmp_eq_u32 s43, 28
	s_cselect_b32 s19, s7, s17
	s_cselect_b32 s18, s39, s16
	s_cselect_b32 s17, s5, s42
	s_cselect_b32 s16, s40, s41
	s_add_i32 m0, s13, 0xc000
	ds_read_b128 v[162:165], v169
	ds_read_b128 v[172:175], v169 offset:1024
	ds_read_b128 v[176:179], v169 offset:2048
	ds_read_b128 v[180:183], v169 offset:3072
	ds_read_b128 v[184:187], v169 offset:4096
	ds_read_b128 v[188:191], v169 offset:5120
	ds_read_b128 v[192:195], v169 offset:6144
	ds_read_b128 v[196:199], v169 offset:7168
	global_load_lds_dwordx4 v152, s[14:15]
	s_add_i32 m0, s13, 0xe000
	s_nop 0
	global_load_lds_dwordx4 v154, s[14:15]
	s_waitcnt lgkmcnt(8)
	s_waitcnt vmcnt(8)
	s_setprio 1
	s_barrier
	s_waitcnt lgkmcnt(0)
	v_mfma_f32_16x16x32_bf16 v[124:127], v[128:131], v[162:165], 0
	v_mfma_f32_16x16x32_bf16 v[120:123], v[136:139], v[162:165], 0
	v_mfma_f32_16x16x32_bf16 v[116:119], v[128:131], v[176:179], 0
	v_mfma_f32_16x16x32_bf16 v[112:115], v[136:139], v[176:179], 0
	v_mfma_f32_16x16x32_bf16 v[108:111], v[128:131], v[184:187], 0
	v_mfma_f32_16x16x32_bf16 v[100:103], v[136:139], v[184:187], 0
	v_mfma_f32_16x16x32_bf16 v[76:79], v[128:131], v[192:195], 0
	v_mfma_f32_16x16x32_bf16 v[72:75], v[136:139], v[192:195], 0
	v_mfma_f32_16x16x32_bf16 v[124:127], v[132:135], v[172:175], v[124:127]
	v_mfma_f32_16x16x32_bf16 v[120:123], v[140:143], v[172:175], v[120:123]
	v_mfma_f32_16x16x32_bf16 v[116:119], v[132:135], v[180:183], v[116:119]
	v_mfma_f32_16x16x32_bf16 v[112:115], v[140:143], v[180:183], v[112:115]
	v_mfma_f32_16x16x32_bf16 v[108:111], v[132:135], v[188:191], v[108:111]
	v_mfma_f32_16x16x32_bf16 v[100:103], v[140:143], v[188:191], v[100:103]
	v_mfma_f32_16x16x32_bf16 v[76:79], v[132:135], v[196:199], v[76:79]
	v_mfma_f32_16x16x32_bf16 v[72:75], v[140:143], v[196:199], v[72:75]
	s_barrier
	s_setprio 0
	s_add_i32 s44, s35, s24
	s_mov_b32 m0, s44
	ds_read_b128 v[202:205], v170
	ds_read_b128 v[206:209], v170 offset:1024
	ds_read_b128 v[210:213], v170 offset:2048
	ds_read_b128 v[214:217], v170 offset:3072
	global_load_lds_dwordx4 v146, s[16:17]
	s_add_i32 m0, s44, 0x2000
	s_nop 0
	global_load_lds_dwordx4 v150, s[16:17]
	s_waitcnt vmcnt(8)
	s_setprio 1
	s_barrier
	s_waitcnt lgkmcnt(0)
	v_mfma_f32_16x16x32_bf16 v[104:107], v[202:205], v[162:165], 0
	v_mfma_f32_16x16x32_bf16 v[96:99], v[210:213], v[162:165], 0
	v_mfma_f32_16x16x32_bf16 v[92:95], v[202:205], v[176:179], 0
	v_mfma_f32_16x16x32_bf16 v[88:91], v[210:213], v[176:179], 0
	v_mfma_f32_16x16x32_bf16 v[84:87], v[202:205], v[184:187], 0
	v_mfma_f32_16x16x32_bf16 v[80:83], v[210:213], v[184:187], 0
	v_mfma_f32_16x16x32_bf16 v[68:71], v[202:205], v[192:195], 0
	v_mfma_f32_16x16x32_bf16 v[64:67], v[210:213], v[192:195], 0
	v_mfma_f32_16x16x32_bf16 v[104:107], v[206:209], v[172:175], v[104:107]
	v_mfma_f32_16x16x32_bf16 v[96:99], v[214:217], v[172:175], v[96:99]
	v_mfma_f32_16x16x32_bf16 v[92:95], v[206:209], v[180:183], v[92:95]
	v_mfma_f32_16x16x32_bf16 v[88:91], v[214:217], v[180:183], v[88:91]
	v_mfma_f32_16x16x32_bf16 v[84:87], v[206:209], v[188:191], v[84:87]
	v_mfma_f32_16x16x32_bf16 v[80:83], v[214:217], v[188:191], v[80:83]
	v_mfma_f32_16x16x32_bf16 v[68:71], v[206:209], v[196:199], v[68:71]
	v_mfma_f32_16x16x32_bf16 v[64:67], v[214:217], v[196:199], v[64:67]
	s_barrier
	s_setprio 0
	s_mov_b32 m0, s13
	v_lshl_add_u64 v[222:223], s[18:19], 0, v[144:145]
	ds_read_b128 v[162:165], v169 offset:16384
	ds_read_b128 v[172:175], v169 offset:17408
	ds_read_b128 v[176:179], v169 offset:18432
	ds_read_b128 v[180:183], v169 offset:19456
	ds_read_b128 v[184:187], v169 offset:20480
	ds_read_b128 v[188:191], v169 offset:21504
	ds_read_b128 v[192:195], v169 offset:22528
	ds_read_b128 v[196:199], v169 offset:23552
	global_load_lds_dwordx4 v144, s[18:19]
	v_lshl_add_u64 v[224:225], s[18:19], 0, v[148:149]
	s_mov_b32 m0, s25
	s_nop 0
	global_load_lds_dwordx4 v148, s[18:19]
	s_setprio 1
	s_barrier
	s_waitcnt lgkmcnt(0)
	v_mfma_f32_16x16x32_bf16 v[60:63], v[128:131], v[162:165], 0
	v_mfma_f32_16x16x32_bf16 v[56:59], v[136:139], v[162:165], 0
	v_mfma_f32_16x16x32_bf16 v[48:51], v[128:131], v[176:179], 0
	v_mfma_f32_16x16x32_bf16 v[40:43], v[136:139], v[176:179], 0
	v_mfma_f32_16x16x32_bf16 v[32:35], v[128:131], v[184:187], 0
	v_mfma_f32_16x16x32_bf16 v[24:27], v[136:139], v[184:187], 0
	v_mfma_f32_16x16x32_bf16 v[16:19], v[128:131], v[192:195], 0
	v_mfma_f32_16x16x32_bf16 v[8:11], v[136:139], v[192:195], 0
	v_mfma_f32_16x16x32_bf16 v[60:63], v[132:135], v[172:175], v[60:63]
	v_mfma_f32_16x16x32_bf16 v[56:59], v[140:143], v[172:175], v[56:59]
	v_mfma_f32_16x16x32_bf16 v[48:51], v[132:135], v[180:183], v[48:51]
	v_mfma_f32_16x16x32_bf16 v[40:43], v[140:143], v[180:183], v[40:43]
	v_mfma_f32_16x16x32_bf16 v[32:35], v[132:135], v[188:191], v[32:35]
	v_mfma_f32_16x16x32_bf16 v[24:27], v[140:143], v[188:191], v[24:27]
	v_mfma_f32_16x16x32_bf16 v[16:19], v[132:135], v[196:199], v[16:19]
	v_mfma_f32_16x16x32_bf16 v[8:11], v[140:143], v[196:199], v[8:11]
	s_barrier
; #define PG8_STAGE(bufoff, gbase, voff) do { _Pragma("unroll") for (int _i = 0; _i < 2; ++_i) \
;         __builtin_amdgcn_global_load_lds((const unsigned*)((const char*)(gbase) + (voff)[_i]), (LAS unsigned*)(lds + (bufoff) + ldsw + _i * 8192), 16, 0, 0); } while (0)
; #define PG8_LDA(dst, b, h) do { _Pragma("unroll") for (int m = 0; m < 4; ++m) _Pragma("unroll") for (int k = 0; k < 2; ++k) dst[m][k] = *(const LAS bf16x8*)(lds + PG8_SA(b, h) + aoff + m * 2048 + k * 1024); } while (0)
; #define PG8_LDB(dst, b, h) do { _Pragma("unroll") for (int n = 0; n < 2; ++n) _Pragma("unroll") for (int k = 0; k < 2; ++k) dst[n][k] = *(const LAS bf16x8*)(lds + PG8_SB(b, h) + boff + n * 2048 + k * 1024); } while (0)
; #define PG8_MMA(ai, bj, At, Bt) do { __builtin_amdgcn_s_setprio(1); _Pragma("unroll") for (int m = 0; m < 4; ++m) _Pragma("unroll") for (int n = 0; n < 2; ++n) _Pragma("unroll") for (int k = 0; k < 2; ++k) \
;         acc[ai][bj][m][n] = __builtin_amdgcn_mfma_f32_16x16x32_bf16(Bt[n][k], At[m][k], acc[ai][bj][m][n], 0, 0, 0); __builtin_amdgcn_s_setprio(0); } while (0)
; #define PG8_WAIT_V(n) asm volatile("s_waitcnt vmcnt(" #n ")" ::: "memory")
; #define PG8_WAIT_L(n) asm volatile("s_waitcnt lgkmcnt(" #n ")" ::: "memory")
; #define PG8_BAR __builtin_amdgcn_s_barrier()
; #define PG8_SCHED __builtin_amdgcn_sched_barrier(0)
; template <class Epi, class Sched>
; __device__ __forceinline__ void gemm_phase(LAS unsigned char* lds, const Gemm g, const Sched& S, const Epi& E) {
;     ...
;             PG8_STAGE(PG8_SB(0, 1), b2 + hstep, voffB);
;             PG8_WAIT_V(6); PG8_BAR; PG8_MMA(1, 1, At, B1); PG8_BAR;
;             PG8_LDB(B0, 1, 0); PG8_SCHED; PG8_LDA(At, 1, 0); PG8_STAGE(PG8_SA(0, 1), a2 + hstep, voffA);
;             PG8_WAIT_L(8); PG8_BAR; PG8_WAIT_L(0); PG8_MMA(0, 0, At, B0); PG8_BAR; PG8_SCHED;
;             PG8_LDB(B1, 1, 1); PG8_STAGE(PG8_SB(1, 0), b3, voffB);
;             PG8_BAR; PG8_WAIT_L(0); PG8_MMA(0, 1, At, B1); PG8_BAR;
;             PG8_LDA(At, 1, 1); PG8_STAGE(PG8_SA(1, 0), a3, voffA);
	s_setprio 0
	s_add_u32 s44, s16, 0x80000
	s_addc_u32 s45, s17, 0
	s_add_i32 s46, s36, s24
	s_mov_b32 m0, s46
	s_nop 0
	global_load_lds_dwordx4 v146, s[44:45]
	s_add_i32 m0, s46, 0x2000
	s_nop 0
	global_load_lds_dwordx4 v150, s[44:45]
	s_add_u32 s18, s18, 0x80000
	s_addc_u32 s19, s19, 0
	s_mov_b32 m0, s26
	s_nop 0
	global_load_lds_dwordx4 v144, s[18:19]
	s_mov_b32 m0, s27
	s_nop 0
	global_load_lds_dwordx4 v148, s[18:19]
	s_waitcnt vmcnt(10)
	s_setprio 1
	s_barrier
	v_mfma_f32_16x16x32_bf16 v[52:55], v[202:205], v[162:165], 0
	v_mfma_f32_16x16x32_bf16 v[44:47], v[210:213], v[162:165], 0
	v_mfma_f32_16x16x32_bf16 v[36:39], v[202:205], v[176:179], 0
	v_mfma_f32_16x16x32_bf16 v[28:31], v[210:213], v[176:179], 0
	v_mfma_f32_16x16x32_bf16 v[20:23], v[202:205], v[184:187], 0
	v_mfma_f32_16x16x32_bf16 v[12:15], v[210:213], v[184:187], 0
	v_mfma_f32_16x16x32_bf16 v[4:7], v[202:205], v[192:195], 0
	v_mfma_f32_16x16x32_bf16 v[0:3], v[210:213], v[192:195], 0
	v_mfma_f32_16x16x32_bf16 v[52:55], v[206:209], v[172:175], v[52:55]
	v_mfma_f32_16x16x32_bf16 v[44:47], v[214:217], v[172:175], v[44:47]
	v_mfma_f32_16x16x32_bf16 v[36:39], v[206:209], v[180:183], v[36:39]
	v_mfma_f32_16x16x32_bf16 v[28:31], v[214:217], v[180:183], v[28:31]
	v_mfma_f32_16x16x32_bf16 v[20:23], v[206:209], v[188:191], v[20:23]
	v_mfma_f32_16x16x32_bf16 v[12:15], v[214:217], v[188:191], v[12:15]
	v_mfma_f32_16x16x32_bf16 v[4:7], v[206:209], v[196:199], v[4:7]
	v_mfma_f32_16x16x32_bf16 v[0:3], v[214:217], v[196:199], v[0:3]
	s_barrier
	s_setprio 0
	s_add_i32 s44, 0, 0x18000
	ds_read_b128 v[128:131], v170 offset:16384
	ds_read_b128 v[132:135], v170 offset:17408
	ds_read_b128 v[136:139], v170 offset:18432
	ds_read_b128 v[140:143], v170 offset:19456
	ds_read_b128 v[162:165], v169 offset:32768
	ds_read_b128 v[172:175], v169 offset:33792
	ds_read_b128 v[176:179], v169 offset:34816
	ds_read_b128 v[180:183], v169 offset:35840
	ds_read_b128 v[184:187], v169 offset:36864
	ds_read_b128 v[188:191], v169 offset:37888
	ds_read_b128 v[192:195], v169 offset:38912
	ds_read_b128 v[196:199], v169 offset:39936
	s_waitcnt lgkmcnt(8)
	s_waitcnt vmcnt(8)
	s_setprio 1
	s_barrier
	s_waitcnt lgkmcnt(0)
	v_mfma_f32_16x16x32_bf16 v[124:127], v[128:131], v[162:165], v[124:127]
	v_mfma_f32_16x16x32_bf16 v[120:123], v[136:139], v[162:165], v[120:123]
	v_mfma_f32_16x16x32_bf16 v[116:119], v[128:131], v[176:179], v[116:119]
	v_mfma_f32_16x16x32_bf16 v[112:115], v[136:139], v[176:179], v[112:115]
	v_mfma_f32_16x16x32_bf16 v[108:111], v[128:131], v[184:187], v[108:111]
	v_mfma_f32_16x16x32_bf16 v[100:103], v[136:139], v[184:187], v[100:103]
	v_mfma_f32_16x16x32_bf16 v[76:79], v[128:131], v[192:195], v[76:79]
	v_mfma_f32_16x16x32_bf16 v[72:75], v[136:139], v[192:195], v[72:75]
	v_mfma_f32_16x16x32_bf16 v[124:127], v[132:135], v[172:175], v[124:127]
	v_mfma_f32_16x16x32_bf16 v[120:123], v[140:143], v[172:175], v[120:123]
	v_mfma_f32_16x16x32_bf16 v[116:119], v[132:135], v[180:183], v[116:119]
	v_mfma_f32_16x16x32_bf16 v[112:115], v[140:143], v[180:183], v[112:115]
	v_mfma_f32_16x16x32_bf16 v[108:111], v[132:135], v[188:191], v[108:111]
	v_mfma_f32_16x16x32_bf16 v[100:103], v[140:143], v[188:191], v[100:103]
	v_mfma_f32_16x16x32_bf16 v[76:79], v[132:135], v[196:199], v[76:79]
	v_mfma_f32_16x16x32_bf16 v[72:75], v[140:143], v[196:199], v[72:75]
	s_barrier
	s_setprio 0
	s_add_i32 s18, 0, 0x1c000
	s_add_i32 s19, s44, s24
	v_add_u32_e32 v160, s18, v167
	s_add_u32 s0, s16, 0x80
	s_addc_u32 s1, s17, 0
	s_mov_b32 m0, s19
	ds_read_b128 v[202:205], v160
	ds_read_b128 v[206:209], v160 offset:1024
	ds_read_b128 v[210:213], v160 offset:2048
	ds_read_b128 v[214:217], v160 offset:3072
	global_load_lds_dwordx4 v146, s[0:1]
	s_add_i32 m0, s19, 0x2000
	s_nop 0
	global_load_lds_dwordx4 v150, s[0:1]
	s_waitcnt vmcnt(8)
	s_setprio 1
	s_barrier
	s_waitcnt lgkmcnt(0)
	v_mfma_f32_16x16x32_bf16 v[104:107], v[202:205], v[162:165], v[104:107]
	v_mfma_f32_16x16x32_bf16 v[96:99], v[210:213], v[162:165], v[96:99]
	v_mfma_f32_16x16x32_bf16 v[92:95], v[202:205], v[176:179], v[92:95]
	v_mfma_f32_16x16x32_bf16 v[88:91], v[210:213], v[176:179], v[88:91]
	v_mfma_f32_16x16x32_bf16 v[84:87], v[202:205], v[184:187], v[84:87]
	v_mfma_f32_16x16x32_bf16 v[80:83], v[210:213], v[184:187], v[80:83]
	v_mfma_f32_16x16x32_bf16 v[68:71], v[202:205], v[192:195], v[68:71]
	v_mfma_f32_16x16x32_bf16 v[64:67], v[210:213], v[192:195], v[64:67]
	v_mfma_f32_16x16x32_bf16 v[104:107], v[206:209], v[172:175], v[104:107]
	v_mfma_f32_16x16x32_bf16 v[96:99], v[214:217], v[172:175], v[96:99]
	v_mfma_f32_16x16x32_bf16 v[92:95], v[206:209], v[180:183], v[92:95]
	v_mfma_f32_16x16x32_bf16 v[88:91], v[214:217], v[180:183], v[88:91]
	v_mfma_f32_16x16x32_bf16 v[84:87], v[206:209], v[188:191], v[84:87]
	v_mfma_f32_16x16x32_bf16 v[80:83], v[214:217], v[188:191], v[80:83]
	v_mfma_f32_16x16x32_bf16 v[68:71], v[206:209], v[196:199], v[68:71]
	v_mfma_f32_16x16x32_bf16 v[64:67], v[214:217], v[196:199], v[64:67]
	s_barrier
	s_setprio 0
	s_mov_b32 m0, s31
	s_mov_b64 s[0:1], 0x80
	v_lshl_add_u64 v[218:219], v[222:223], 0, s[0:1]
	ds_read_b128 v[162:165], v169 offset:49152
	ds_read_b128 v[172:175], v169 offset:50176
	ds_read_b128 v[176:179], v169 offset:51200
	ds_read_b128 v[180:183], v169 offset:52224
	ds_read_b128 v[184:187], v169 offset:53248
	ds_read_b128 v[188:191], v169 offset:54272
	ds_read_b128 v[192:195], v169 offset:55296
	ds_read_b128 v[196:199], v169 offset:56320
	global_load_lds_dwordx4 v[218:219], off
	v_lshl_add_u64 v[218:219], v[224:225], 0, s[0:1]
	s_mov_b32 m0, s33
	s_nop 0
	global_load_lds_dwordx4 v[218:219], off
	s_setprio 1
	s_barrier
; #define PG8_STAGE(bufoff, gbase, voff) do { _Pragma("unroll") for (int _i = 0; _i < 2; ++_i) \
;         __builtin_amdgcn_global_load_lds((const unsigned*)((const char*)(gbase) + (voff)[_i]), (LAS unsigned*)(lds + (bufoff) + ldsw + _i * 8192), 16, 0, 0); } while (0)
; #define PG8_LDA(dst, b, h) do { _Pragma("unroll") for (int m = 0; m < 4; ++m) _Pragma("unroll") for (int k = 0; k < 2; ++k) dst[m][k] = *(const LAS bf16x8*)(lds + PG8_SA(b, h) + aoff + m * 2048 + k * 1024); } while (0)
; #define PG8_LDB(dst, b, h) do { _Pragma("unroll") for (int n = 0; n < 2; ++n) _Pragma("unroll") for (int k = 0; k < 2; ++k) dst[n][k] = *(const LAS bf16x8*)(lds + PG8_SB(b, h) + boff + n * 2048 + k * 1024); } while (0)
; #define PG8_MMA(ai, bj, At, Bt) do { __builtin_amdgcn_s_setprio(1); _Pragma("unroll") for (int m = 0; m < 4; ++m) _Pragma("unroll") for (int n = 0; n < 2; ++n) _Pragma("unroll") for (int k = 0; k < 2; ++k) \
;         acc[ai][bj][m][n] = __builtin_amdgcn_mfma_f32_16x16x32_bf16(Bt[n][k], At[m][k], acc[ai][bj][m][n], 0, 0, 0); __builtin_amdgcn_s_setprio(0); } while (0)
; #define PG8_WAIT_V(n) asm volatile("s_waitcnt vmcnt(" #n ")" ::: "memory")
; #define PG8_WAIT_L(n) asm volatile("s_waitcnt lgkmcnt(" #n ")" ::: "memory")
; template <class Epi, class Sched>
; __device__ __forceinline__ void gemm_phase(LAS unsigned char* lds, const Gemm g, const Sched& S, const Epi& E) {
;     ...
;         for (int t = 0; t < nt; t += 2) {
;             const bool last = (t == nt - 2);
;             const char* a1 = cA + (size_t)(t + 1) * kstep;
;             const char* a2 = last ? nA : cA + (size_t)(t + 2) * kstep; const char* b2 = last ? nB : cB + (size_t)(t + 2) * kstep;
;             const char* a3 = a2 + kstep; const char* b3 = b2 + kstep;
;             PG8_LDB(B0, 0, 0); PG8_SCHED; PG8_LDA(At, 0, 0); PG8_STAGE(PG8_SA(1, 1), a1 + hstep, voffA);
;             PG8_WAIT_L(8); PG8_BAR; PG8_WAIT_L(0); PG8_MMA(0, 0, At, B0); PG8_BAR; PG8_SCHED;
;             PG8_LDB(B1, 0, 1); PG8_STAGE(PG8_SB(0, 0), b2, voffB);
;             PG8_BAR; PG8_WAIT_L(0); PG8_MMA(0, 1, At, B1); PG8_BAR;
;             PG8_LDA(At, 0, 1); PG8_STAGE(PG8_SA(0, 0), a2, voffA);
;             PG8_BAR; PG8_WAIT_L(0); PG8_MMA(1, 0, At, B0); PG8_BAR; PG8_SCHED;
;             PG8_STAGE(PG8_SB(0, 1), b2 + hstep, voffB);
;             PG8_WAIT_V(6); PG8_BAR; PG8_MMA(1, 1, At, B1); PG8_BAR;
	s_waitcnt lgkmcnt(0)
	v_mfma_f32_16x16x32_bf16 v[60:63], v[128:131], v[162:165], v[60:63]
	v_mfma_f32_16x16x32_bf16 v[56:59], v[136:139], v[162:165], v[56:59]
	v_mfma_f32_16x16x32_bf16 v[48:51], v[128:131], v[176:179], v[48:51]
	v_mfma_f32_16x16x32_bf16 v[40:43], v[136:139], v[176:179], v[40:43]
	v_mfma_f32_16x16x32_bf16 v[32:35], v[128:131], v[184:187], v[32:35]
	v_mfma_f32_16x16x32_bf16 v[24:27], v[136:139], v[184:187], v[24:27]
	v_mfma_f32_16x16x32_bf16 v[16:19], v[128:131], v[192:195], v[16:19]
	v_mfma_f32_16x16x32_bf16 v[8:11], v[136:139], v[192:195], v[8:11]
	v_mfma_f32_16x16x32_bf16 v[60:63], v[132:135], v[172:175], v[60:63]
	v_mfma_f32_16x16x32_bf16 v[56:59], v[140:143], v[172:175], v[56:59]
	v_mfma_f32_16x16x32_bf16 v[48:51], v[132:135], v[180:183], v[48:51]
	v_mfma_f32_16x16x32_bf16 v[40:43], v[140:143], v[180:183], v[40:43]
	v_mfma_f32_16x16x32_bf16 v[32:35], v[132:135], v[188:191], v[32:35]
	v_mfma_f32_16x16x32_bf16 v[24:27], v[140:143], v[188:191], v[24:27]
	v_mfma_f32_16x16x32_bf16 v[16:19], v[132:135], v[196:199], v[16:19]
	v_mfma_f32_16x16x32_bf16 v[8:11], v[140:143], v[196:199], v[8:11]
	s_barrier
	s_setprio 0
	s_add_u32 s16, s16, 0x80080
	s_addc_u32 s17, s17, 0
	s_add_i32 s18, s18, s24
	s_mov_b32 m0, s18
	s_nop 0
	global_load_lds_dwordx4 v146, s[16:17]
	s_add_i32 m0, s18, 0x2000
	s_nop 0
	global_load_lds_dwordx4 v150, s[16:17]
	s_waitcnt vmcnt(8)
	s_setprio 1
	s_barrier
	v_mfma_f32_16x16x32_bf16 v[52:55], v[202:205], v[162:165], v[52:55]
	v_mfma_f32_16x16x32_bf16 v[44:47], v[210:213], v[162:165], v[44:47]
	v_mfma_f32_16x16x32_bf16 v[36:39], v[202:205], v[176:179], v[36:39]
	v_mfma_f32_16x16x32_bf16 v[28:31], v[210:213], v[176:179], v[28:31]
	v_mfma_f32_16x16x32_bf16 v[20:23], v[202:205], v[184:187], v[20:23]
	v_mfma_f32_16x16x32_bf16 v[12:15], v[210:213], v[184:187], v[12:15]
	v_mfma_f32_16x16x32_bf16 v[4:7], v[202:205], v[192:195], v[4:7]
	v_mfma_f32_16x16x32_bf16 v[0:3], v[210:213], v[192:195], v[0:3]
	v_mfma_f32_16x16x32_bf16 v[52:55], v[206:209], v[172:175], v[52:55]
	v_mfma_f32_16x16x32_bf16 v[44:47], v[214:217], v[172:175], v[44:47]
	v_mfma_f32_16x16x32_bf16 v[36:39], v[206:209], v[180:183], v[36:39]
	v_mfma_f32_16x16x32_bf16 v[28:31], v[214:217], v[180:183], v[28:31]
	v_mfma_f32_16x16x32_bf16 v[20:23], v[206:209], v[188:191], v[20:23]
	v_mfma_f32_16x16x32_bf16 v[12:15], v[214:217], v[188:191], v[12:15]
	v_mfma_f32_16x16x32_bf16 v[4:7], v[206:209], v[196:199], v[4:7]
	v_mfma_f32_16x16x32_bf16 v[0:3], v[214:217], v[196:199], v[0:3]
	s_barrier
	s_setprio 0
	s_add_i32 s43, s43, 2
	s_add_u32 s14, s14, 0x100
	s_addc_u32 s15, s15, 0
	s_add_u32 s41, s41, 0x100
	s_addc_u32 s42, s42, 0
	s_cmp_gt_u32 s43, 29
.LBB0_826:
	ds_read_b128 v[128:131], v168
	ds_read_b128 v[132:135], v168 offset:1024
	ds_read_b128 v[136:139], v168 offset:2048
	ds_read_b128 v[140:143], v168 offset:3072
	s_add_u32 s16, s14, 0xfff80080
	s_addc_u32 s17, s15, -1
	s_cmp_eq_u32 s43, 28
	s_cselect_b32 s19, s7, s17
	s_cselect_b32 s18, s39, s16
	s_cselect_b32 s17, s5, s42
	s_cselect_b32 s16, s40, s41
	s_add_i32 m0, s13, 0xc000
	ds_read_b128 v[162:165], v169
	ds_read_b128 v[172:175], v169 offset:1024
	ds_read_b128 v[176:179], v169 offset:2048
	ds_read_b128 v[180:183], v169 offset:3072
	ds_read_b128 v[184:187], v169 offset:4096
	ds_read_b128 v[188:191], v169 offset:5120
	ds_read_b128 v[192:195], v169 offset:6144
	ds_read_b128 v[196:199], v169 offset:7168
	global_load_lds_dwordx4 v152, s[14:15]
	s_add_i32 m0, s13, 0xe000
	s_nop 0
	global_load_lds_dwordx4 v154, s[14:15]
	s_waitcnt lgkmcnt(8)
	s_waitcnt vmcnt(8)
	s_setprio 1
	s_barrier
	s_waitcnt lgkmcnt(0)
	v_mfma_f32_16x16x32_bf16 v[124:127], v[128:131], v[162:165], v[124:127]
	v_mfma_f32_16x16x32_bf16 v[120:123], v[136:139], v[162:165], v[120:123]
	v_mfma_f32_16x16x32_bf16 v[116:119], v[128:131], v[176:179], v[116:119]
	v_mfma_f32_16x16x32_bf16 v[112:115], v[136:139], v[176:179], v[112:115]
	v_mfma_f32_16x16x32_bf16 v[108:111], v[128:131], v[184:187], v[108:111]
	v_mfma_f32_16x16x32_bf16 v[100:103], v[136:139], v[184:187], v[100:103]
	v_mfma_f32_16x16x32_bf16 v[76:79], v[128:131], v[192:195], v[76:79]
	v_mfma_f32_16x16x32_bf16 v[72:75], v[136:139], v[192:195], v[72:75]
	v_mfma_f32_16x16x32_bf16 v[124:127], v[132:135], v[172:175], v[124:127]
	v_mfma_f32_16x16x32_bf16 v[120:123], v[140:143], v[172:175], v[120:123]
	v_mfma_f32_16x16x32_bf16 v[116:119], v[132:135], v[180:183], v[116:119]
	v_mfma_f32_16x16x32_bf16 v[112:115], v[140:143], v[180:183], v[112:115]
	v_mfma_f32_16x16x32_bf16 v[108:111], v[132:135], v[188:191], v[108:111]
	v_mfma_f32_16x16x32_bf16 v[100:103], v[140:143], v[188:191], v[100:103]
	v_mfma_f32_16x16x32_bf16 v[76:79], v[132:135], v[196:199], v[76:79]
	v_mfma_f32_16x16x32_bf16 v[72:75], v[140:143], v[196:199], v[72:75]
	s_barrier
	s_setprio 0
	s_add_i32 s44, s35, s24
	s_mov_b32 m0, s44
	ds_read_b128 v[202:205], v170
	ds_read_b128 v[206:209], v170 offset:1024
	ds_read_b128 v[210:213], v170 offset:2048
	ds_read_b128 v[214:217], v170 offset:3072
	global_load_lds_dwordx4 v146, s[16:17]
	s_add_i32 m0, s44, 0x2000
	s_nop 0
	global_load_lds_dwordx4 v150, s[16:17]
	s_waitcnt vmcnt(8)
	s_setprio 1
	s_barrier
; #define PG8_STAGE(bufoff, gbase, voff) do { _Pragma("unroll") for (int _i = 0; _i < 2; ++_i) \
;         __builtin_amdgcn_global_load_lds((const unsigned*)((const char*)(gbase) + (voff)[_i]), (LAS unsigned*)(lds + (bufoff) + ldsw + _i * 8192), 16, 0, 0); } while (0)
; #define PG8_LDA(dst, b, h) do { _Pragma("unroll") for (int m = 0; m < 4; ++m) _Pragma("unroll") for (int k = 0; k < 2; ++k) dst[m][k] = *(const LAS bf16x8*)(lds + PG8_SA(b, h) + aoff + m * 2048 + k * 1024); } while (0)
; #define PG8_LDB(dst, b, h) do { _Pragma("unroll") for (int n = 0; n < 2; ++n) _Pragma("unroll") for (int k = 0; k < 2; ++k) dst[n][k] = *(const LAS bf16x8*)(lds + PG8_SB(b, h) + boff + n * 2048 + k * 1024); } while (0)
; #define PG8_MMA(ai, bj, At, Bt) do { __builtin_amdgcn_s_setprio(1); _Pragma("unroll") for (int m = 0; m < 4; ++m) _Pragma("unroll") for (int n = 0; n < 2; ++n) _Pragma("unroll") for (int k = 0; k < 2; ++k) \
;         acc[ai][bj][m][n] = __builtin_amdgcn_mfma_f32_16x16x32_bf16(Bt[n][k], At[m][k], acc[ai][bj][m][n], 0, 0, 0); __builtin_amdgcn_s_setprio(0); } while (0)
; #define PG8_WAIT_V(n) asm volatile("s_waitcnt vmcnt(" #n ")" ::: "memory")
; #define PG8_WAIT_L(n) asm volatile("s_waitcnt lgkmcnt(" #n ")" ::: "memory")
; #define PG8_BAR __builtin_amdgcn_s_barrier()
; #define PG8_SCHED __builtin_amdgcn_sched_barrier(0)
; template <class Epi, class Sched>
; __device__ __forceinline__ void gemm_phase(LAS unsigned char* lds, const Gemm g, const Sched& S, const Epi& E) {
;     ...
;             PG8_BAR; PG8_WAIT_L(0); PG8_MMA(1, 0, At, B0); PG8_BAR; PG8_SCHED;
;             PG8_STAGE(PG8_SB(0, 1), b2 + hstep, voffB);
;             PG8_WAIT_V(6); PG8_BAR; PG8_MMA(1, 1, At, B1); PG8_BAR;
;             PG8_LDB(B0, 1, 0); PG8_SCHED; PG8_LDA(At, 1, 0); PG8_STAGE(PG8_SA(0, 1), a2 + hstep, voffA);
;             PG8_WAIT_L(8); PG8_BAR; PG8_WAIT_L(0); PG8_MMA(0, 0, At, B0); PG8_BAR; PG8_SCHED;
;             PG8_LDB(B1, 1, 1); PG8_STAGE(PG8_SB(1, 0), b3, voffB);
;             PG8_BAR; PG8_WAIT_L(0); PG8_MMA(0, 1, At, B1); PG8_BAR;
;             PG8_LDA(At, 1, 1); PG8_STAGE(PG8_SA(1, 0), a3, voffA);
	s_waitcnt lgkmcnt(0)
	v_mfma_f32_16x16x32_bf16 v[104:107], v[202:205], v[162:165], v[104:107]
	v_mfma_f32_16x16x32_bf16 v[96:99], v[210:213], v[162:165], v[96:99]
	v_mfma_f32_16x16x32_bf16 v[92:95], v[202:205], v[176:179], v[92:95]
	v_mfma_f32_16x16x32_bf16 v[88:91], v[210:213], v[176:179], v[88:91]
	v_mfma_f32_16x16x32_bf16 v[84:87], v[202:205], v[184:187], v[84:87]
	v_mfma_f32_16x16x32_bf16 v[80:83], v[210:213], v[184:187], v[80:83]
	v_mfma_f32_16x16x32_bf16 v[68:71], v[202:205], v[192:195], v[68:71]
	v_mfma_f32_16x16x32_bf16 v[64:67], v[210:213], v[192:195], v[64:67]
	v_mfma_f32_16x16x32_bf16 v[104:107], v[206:209], v[172:175], v[104:107]
	v_mfma_f32_16x16x32_bf16 v[96:99], v[214:217], v[172:175], v[96:99]
	v_mfma_f32_16x16x32_bf16 v[92:95], v[206:209], v[180:183], v[92:95]
	v_mfma_f32_16x16x32_bf16 v[88:91], v[214:217], v[180:183], v[88:91]
	v_mfma_f32_16x16x32_bf16 v[84:87], v[206:209], v[188:191], v[84:87]
	v_mfma_f32_16x16x32_bf16 v[80:83], v[214:217], v[188:191], v[80:83]
	v_mfma_f32_16x16x32_bf16 v[68:71], v[206:209], v[196:199], v[68:71]
	v_mfma_f32_16x16x32_bf16 v[64:67], v[214:217], v[196:199], v[64:67]
	s_barrier
	s_setprio 0
	s_mov_b32 m0, s13
	v_lshl_add_u64 v[222:223], s[18:19], 0, v[144:145]
	ds_read_b128 v[162:165], v169 offset:16384
	ds_read_b128 v[172:175], v169 offset:17408
	ds_read_b128 v[176:179], v169 offset:18432
	ds_read_b128 v[180:183], v169 offset:19456
	ds_read_b128 v[184:187], v169 offset:20480
	ds_read_b128 v[188:191], v169 offset:21504
	ds_read_b128 v[192:195], v169 offset:22528
	ds_read_b128 v[196:199], v169 offset:23552
	global_load_lds_dwordx4 v144, s[18:19]
	v_lshl_add_u64 v[224:225], s[18:19], 0, v[148:149]
	s_mov_b32 m0, s25
	s_nop 0
	global_load_lds_dwordx4 v148, s[18:19]
	s_setprio 1
	s_barrier
	s_waitcnt lgkmcnt(0)
	v_mfma_f32_16x16x32_bf16 v[60:63], v[128:131], v[162:165], v[60:63]
	v_mfma_f32_16x16x32_bf16 v[56:59], v[136:139], v[162:165], v[56:59]
	v_mfma_f32_16x16x32_bf16 v[48:51], v[128:131], v[176:179], v[48:51]
	v_mfma_f32_16x16x32_bf16 v[40:43], v[136:139], v[176:179], v[40:43]
	v_mfma_f32_16x16x32_bf16 v[32:35], v[128:131], v[184:187], v[32:35]
	v_mfma_f32_16x16x32_bf16 v[24:27], v[136:139], v[184:187], v[24:27]
	v_mfma_f32_16x16x32_bf16 v[16:19], v[128:131], v[192:195], v[16:19]
	v_mfma_f32_16x16x32_bf16 v[8:11], v[136:139], v[192:195], v[8:11]
	v_mfma_f32_16x16x32_bf16 v[60:63], v[132:135], v[172:175], v[60:63]
	v_mfma_f32_16x16x32_bf16 v[56:59], v[140:143], v[172:175], v[56:59]
	v_mfma_f32_16x16x32_bf16 v[48:51], v[132:135], v[180:183], v[48:51]
	v_mfma_f32_16x16x32_bf16 v[40:43], v[140:143], v[180:183], v[40:43]
	v_mfma_f32_16x16x32_bf16 v[32:35], v[132:135], v[188:191], v[32:35]
	v_mfma_f32_16x16x32_bf16 v[24:27], v[140:143], v[188:191], v[24:27]
	v_mfma_f32_16x16x32_bf16 v[16:19], v[132:135], v[196:199], v[16:19]
	v_mfma_f32_16x16x32_bf16 v[8:11], v[140:143], v[196:199], v[8:11]
	s_barrier
	s_setprio 0
	s_add_u32 s44, s16, 0x80000
	s_addc_u32 s45, s17, 0
	s_add_i32 s46, s36, s24
	s_mov_b32 m0, s46
	s_nop 0
	global_load_lds_dwordx4 v146, s[44:45]
	s_add_i32 m0, s46, 0x2000
	s_nop 0
	global_load_lds_dwordx4 v150, s[44:45]
	s_add_u32 s18, s18, 0x80000
	s_addc_u32 s19, s19, 0
	s_mov_b32 m0, s26
	s_nop 0
	global_load_lds_dwordx4 v144, s[18:19]
	s_mov_b32 m0, s27
	s_nop 0
	global_load_lds_dwordx4 v148, s[18:19]
	s_waitcnt vmcnt(10)
	s_setprio 1
	s_barrier
	v_mfma_f32_16x16x32_bf16 v[52:55], v[202:205], v[162:165], v[52:55]
	v_mfma_f32_16x16x32_bf16 v[44:47], v[210:213], v[162:165], v[44:47]
	v_mfma_f32_16x16x32_bf16 v[36:39], v[202:205], v[176:179], v[36:39]
	v_mfma_f32_16x16x32_bf16 v[28:31], v[210:213], v[176:179], v[28:31]
	v_mfma_f32_16x16x32_bf16 v[20:23], v[202:205], v[184:187], v[20:23]
	v_mfma_f32_16x16x32_bf16 v[12:15], v[210:213], v[184:187], v[12:15]
	v_mfma_f32_16x16x32_bf16 v[4:7], v[202:205], v[192:195], v[4:7]
	v_mfma_f32_16x16x32_bf16 v[0:3], v[210:213], v[192:195], v[0:3]
	v_mfma_f32_16x16x32_bf16 v[52:55], v[206:209], v[172:175], v[52:55]
	v_mfma_f32_16x16x32_bf16 v[44:47], v[214:217], v[172:175], v[44:47]
	v_mfma_f32_16x16x32_bf16 v[36:39], v[206:209], v[180:183], v[36:39]
	v_mfma_f32_16x16x32_bf16 v[28:31], v[214:217], v[180:183], v[28:31]
	v_mfma_f32_16x16x32_bf16 v[20:23], v[206:209], v[188:191], v[20:23]
	v_mfma_f32_16x16x32_bf16 v[12:15], v[214:217], v[188:191], v[12:15]
	v_mfma_f32_16x16x32_bf16 v[4:7], v[206:209], v[196:199], v[4:7]
	v_mfma_f32_16x16x32_bf16 v[0:3], v[214:217], v[196:199], v[0:3]
	s_barrier
	s_setprio 0
	s_add_i32 s44, 0, 0x18000
	ds_read_b128 v[128:131], v170 offset:16384
	ds_read_b128 v[132:135], v170 offset:17408
	ds_read_b128 v[136:139], v170 offset:18432
	ds_read_b128 v[140:143], v170 offset:19456
	ds_read_b128 v[162:165], v169 offset:32768
	ds_read_b128 v[172:175], v169 offset:33792
	ds_read_b128 v[176:179], v169 offset:34816
	ds_read_b128 v[180:183], v169 offset:35840
	ds_read_b128 v[184:187], v169 offset:36864
	ds_read_b128 v[188:191], v169 offset:37888
	ds_read_b128 v[192:195], v169 offset:38912
	ds_read_b128 v[196:199], v169 offset:39936
	s_waitcnt lgkmcnt(8)
	s_waitcnt vmcnt(8)
	s_setprio 1
	s_barrier
; #define PG8_STAGE(bufoff, gbase, voff) do { _Pragma("unroll") for (int _i = 0; _i < 2; ++_i) \
;         __builtin_amdgcn_global_load_lds((const unsigned*)((const char*)(gbase) + (voff)[_i]), (LAS unsigned*)(lds + (bufoff) + ldsw + _i * 8192), 16, 0, 0); } while (0)
; #define PG8_LDA(dst, b, h) do { _Pragma("unroll") for (int m = 0; m < 4; ++m) _Pragma("unroll") for (int k = 0; k < 2; ++k) dst[m][k] = *(const LAS bf16x8*)(lds + PG8_SA(b, h) + aoff + m * 2048 + k * 1024); } while (0)
; #define PG8_LDB(dst, b, h) do { _Pragma("unroll") for (int n = 0; n < 2; ++n) _Pragma("unroll") for (int k = 0; k < 2; ++k) dst[n][k] = *(const LAS bf16x8*)(lds + PG8_SB(b, h) + boff + n * 2048 + k * 1024); } while (0)
; #define PG8_MMA(ai, bj, At, Bt) do { __builtin_amdgcn_s_setprio(1); _Pragma("unroll") for (int m = 0; m < 4; ++m) _Pragma("unroll") for (int n = 0; n < 2; ++n) _Pragma("unroll") for (int k = 0; k < 2; ++k) \
;         acc[ai][bj][m][n] = __builtin_amdgcn_mfma_f32_16x16x32_bf16(Bt[n][k], At[m][k], acc[ai][bj][m][n], 0, 0, 0); __builtin_amdgcn_s_setprio(0); } while (0)
; #define PG8_WAIT_V(n) asm volatile("s_waitcnt vmcnt(" #n ")" ::: "memory")
; #define PG8_WAIT_L(n) asm volatile("s_waitcnt lgkmcnt(" #n ")" ::: "memory")
; #define PG8_BAR __builtin_amdgcn_s_barrier()
; #define PG8_SCHED __builtin_amdgcn_sched_barrier(0)
; template <class Epi, class Sched>
; __device__ __forceinline__ void gemm_phase(LAS unsigned char* lds, const Gemm g, const Sched& S, const Epi& E) {
;     ...
;             PG8_WAIT_L(8); PG8_BAR; PG8_WAIT_L(0); PG8_MMA(0, 0, At, B0); PG8_BAR; PG8_SCHED;
;             PG8_LDB(B1, 1, 1); PG8_STAGE(PG8_SB(1, 0), b3, voffB);
;             PG8_BAR; PG8_WAIT_L(0); PG8_MMA(0, 1, At, B1); PG8_BAR;
;             PG8_LDA(At, 1, 1); PG8_STAGE(PG8_SA(1, 0), a3, voffA);
;             PG8_BAR; PG8_WAIT_L(0); PG8_MMA(1, 0, At, B0); PG8_BAR; PG8_SCHED;
;             PG8_STAGE(PG8_SB(1, 1), b3 + hstep, voffB);
;             PG8_WAIT_V(6); PG8_BAR; PG8_MMA(1, 1, At, B1); PG8_BAR;
	s_waitcnt lgkmcnt(0)
	v_mfma_f32_16x16x32_bf16 v[124:127], v[128:131], v[162:165], v[124:127]
	v_mfma_f32_16x16x32_bf16 v[120:123], v[136:139], v[162:165], v[120:123]
	v_mfma_f32_16x16x32_bf16 v[116:119], v[128:131], v[176:179], v[116:119]
	v_mfma_f32_16x16x32_bf16 v[112:115], v[136:139], v[176:179], v[112:115]
	v_mfma_f32_16x16x32_bf16 v[108:111], v[128:131], v[184:187], v[108:111]
	v_mfma_f32_16x16x32_bf16 v[100:103], v[136:139], v[184:187], v[100:103]
	v_mfma_f32_16x16x32_bf16 v[76:79], v[128:131], v[192:195], v[76:79]
	v_mfma_f32_16x16x32_bf16 v[72:75], v[136:139], v[192:195], v[72:75]
	v_mfma_f32_16x16x32_bf16 v[124:127], v[132:135], v[172:175], v[124:127]
	v_mfma_f32_16x16x32_bf16 v[120:123], v[140:143], v[172:175], v[120:123]
	v_mfma_f32_16x16x32_bf16 v[116:119], v[132:135], v[180:183], v[116:119]
	v_mfma_f32_16x16x32_bf16 v[112:115], v[140:143], v[180:183], v[112:115]
	v_mfma_f32_16x16x32_bf16 v[108:111], v[132:135], v[188:191], v[108:111]
	v_mfma_f32_16x16x32_bf16 v[100:103], v[140:143], v[188:191], v[100:103]
	v_mfma_f32_16x16x32_bf16 v[76:79], v[132:135], v[196:199], v[76:79]
	v_mfma_f32_16x16x32_bf16 v[72:75], v[140:143], v[196:199], v[72:75]
	s_barrier
	s_setprio 0
	s_add_i32 s18, 0, 0x1c000
	s_add_i32 s19, s44, s24
	v_add_u32_e32 v160, s18, v167
	s_add_u32 s0, s16, 0x80
	s_addc_u32 s1, s17, 0
	s_mov_b32 m0, s19
	ds_read_b128 v[202:205], v160
	ds_read_b128 v[206:209], v160 offset:1024
	ds_read_b128 v[210:213], v160 offset:2048
	ds_read_b128 v[214:217], v160 offset:3072
	global_load_lds_dwordx4 v146, s[0:1]
	s_add_i32 m0, s19, 0x2000
	s_nop 0
	global_load_lds_dwordx4 v150, s[0:1]
	s_waitcnt vmcnt(8)
	s_setprio 1
	s_barrier
	s_waitcnt lgkmcnt(0)
	v_mfma_f32_16x16x32_bf16 v[104:107], v[202:205], v[162:165], v[104:107]
	v_mfma_f32_16x16x32_bf16 v[96:99], v[210:213], v[162:165], v[96:99]
	v_mfma_f32_16x16x32_bf16 v[92:95], v[202:205], v[176:179], v[92:95]
	v_mfma_f32_16x16x32_bf16 v[88:91], v[210:213], v[176:179], v[88:91]
	v_mfma_f32_16x16x32_bf16 v[84:87], v[202:205], v[184:187], v[84:87]
	v_mfma_f32_16x16x32_bf16 v[80:83], v[210:213], v[184:187], v[80:83]
	v_mfma_f32_16x16x32_bf16 v[68:71], v[202:205], v[192:195], v[68:71]
	v_mfma_f32_16x16x32_bf16 v[64:67], v[210:213], v[192:195], v[64:67]
	v_mfma_f32_16x16x32_bf16 v[104:107], v[206:209], v[172:175], v[104:107]
	v_mfma_f32_16x16x32_bf16 v[96:99], v[214:217], v[172:175], v[96:99]
	v_mfma_f32_16x16x32_bf16 v[92:95], v[206:209], v[180:183], v[92:95]
	v_mfma_f32_16x16x32_bf16 v[88:91], v[214:217], v[180:183], v[88:91]
	v_mfma_f32_16x16x32_bf16 v[84:87], v[206:209], v[188:191], v[84:87]
	v_mfma_f32_16x16x32_bf16 v[80:83], v[214:217], v[188:191], v[80:83]
	v_mfma_f32_16x16x32_bf16 v[68:71], v[206:209], v[196:199], v[68:71]
	v_mfma_f32_16x16x32_bf16 v[64:67], v[214:217], v[196:199], v[64:67]
	s_barrier
	s_setprio 0
	s_mov_b32 m0, s31
	s_mov_b64 s[0:1], 0x80
	v_lshl_add_u64 v[218:219], v[222:223], 0, s[0:1]
	ds_read_b128 v[162:165], v169 offset:49152
	ds_read_b128 v[172:175], v169 offset:50176
	ds_read_b128 v[176:179], v169 offset:51200
	ds_read_b128 v[180:183], v169 offset:52224
	ds_read_b128 v[184:187], v169 offset:53248
	ds_read_b128 v[188:191], v169 offset:54272
	ds_read_b128 v[192:195], v169 offset:55296
	ds_read_b128 v[196:199], v169 offset:56320
	global_load_lds_dwordx4 v[218:219], off
	v_lshl_add_u64 v[218:219], v[224:225], 0, s[0:1]
	s_mov_b32 m0, s33
	s_nop 0
	global_load_lds_dwordx4 v[218:219], off
	s_setprio 1
	s_barrier
	s_waitcnt lgkmcnt(0)
	v_mfma_f32_16x16x32_bf16 v[60:63], v[128:131], v[162:165], v[60:63]
	v_mfma_f32_16x16x32_bf16 v[56:59], v[136:139], v[162:165], v[56:59]
	v_mfma_f32_16x16x32_bf16 v[48:51], v[128:131], v[176:179], v[48:51]
	v_mfma_f32_16x16x32_bf16 v[40:43], v[136:139], v[176:179], v[40:43]
	v_mfma_f32_16x16x32_bf16 v[32:35], v[128:131], v[184:187], v[32:35]
	v_mfma_f32_16x16x32_bf16 v[24:27], v[136:139], v[184:187], v[24:27]
	v_mfma_f32_16x16x32_bf16 v[16:19], v[128:131], v[192:195], v[16:19]
	v_mfma_f32_16x16x32_bf16 v[8:11], v[136:139], v[192:195], v[8:11]
	v_mfma_f32_16x16x32_bf16 v[60:63], v[132:135], v[172:175], v[60:63]
	v_mfma_f32_16x16x32_bf16 v[56:59], v[140:143], v[172:175], v[56:59]
	v_mfma_f32_16x16x32_bf16 v[48:51], v[132:135], v[180:183], v[48:51]
	v_mfma_f32_16x16x32_bf16 v[40:43], v[140:143], v[180:183], v[40:43]
	v_mfma_f32_16x16x32_bf16 v[32:35], v[132:135], v[188:191], v[32:35]
	v_mfma_f32_16x16x32_bf16 v[24:27], v[140:143], v[188:191], v[24:27]
	v_mfma_f32_16x16x32_bf16 v[16:19], v[132:135], v[196:199], v[16:19]
	v_mfma_f32_16x16x32_bf16 v[8:11], v[140:143], v[196:199], v[8:11]
	s_barrier
	s_setprio 0
	s_add_u32 s16, s16, 0x80080
	s_addc_u32 s17, s17, 0
	s_add_i32 s18, s18, s24
	s_mov_b32 m0, s18
	s_nop 0
	global_load_lds_dwordx4 v146, s[16:17]
	s_add_i32 m0, s18, 0x2000
	s_nop 0
	global_load_lds_dwordx4 v150, s[16:17]
	s_waitcnt vmcnt(8)
	s_setprio 1
	s_barrier
	v_mfma_f32_16x16x32_bf16 v[52:55], v[202:205], v[162:165], v[52:55]
	v_mfma_f32_16x16x32_bf16 v[44:47], v[210:213], v[162:165], v[44:47]
	v_mfma_f32_16x16x32_bf16 v[36:39], v[202:205], v[176:179], v[36:39]
	v_mfma_f32_16x16x32_bf16 v[28:31], v[210:213], v[176:179], v[28:31]
	v_mfma_f32_16x16x32_bf16 v[20:23], v[202:205], v[184:187], v[20:23]
	v_mfma_f32_16x16x32_bf16 v[12:15], v[210:213], v[184:187], v[12:15]
	v_mfma_f32_16x16x32_bf16 v[4:7], v[202:205], v[192:195], v[4:7]
	v_mfma_f32_16x16x32_bf16 v[0:3], v[210:213], v[192:195], v[0:3]
	v_mfma_f32_16x16x32_bf16 v[52:55], v[206:209], v[172:175], v[52:55]
	v_mfma_f32_16x16x32_bf16 v[44:47], v[214:217], v[172:175], v[44:47]
	v_mfma_f32_16x16x32_bf16 v[36:39], v[206:209], v[180:183], v[36:39]
	v_mfma_f32_16x16x32_bf16 v[28:31], v[214:217], v[180:183], v[28:31]
	v_mfma_f32_16x16x32_bf16 v[20:23], v[206:209], v[188:191], v[20:23]
	v_mfma_f32_16x16x32_bf16 v[12:15], v[214:217], v[188:191], v[12:15]
	v_mfma_f32_16x16x32_bf16 v[4:7], v[206:209], v[196:199], v[4:7]
	v_mfma_f32_16x16x32_bf16 v[0:3], v[214:217], v[196:199], v[0:3]
	s_barrier
; __device__ __forceinline__ unsigned cvt_pk_bf16(float lo, float hi) { unsigned r; asm volatile("v_cvt_pk_bf16_f32 %0, %1, %2" : "=v"(r) : "v"(lo), "v"(hi)); return r; }
;     __device__ __forceinline__ void operator()(const AccT& acc, const Unit& u, int wr, int wc, int fr, int fq) const {
;         asm volatile("" : "+v"(fr), "+v"(fq));
;         const int row0 = u.pm * 256 + wr * 64 + fr; const int b = u.pn >> 1, ch0 = (u.pn & 1) * 256 + wc * 32 + 8 * fq;
;         const float sg = (fr & 1) ? -1.0f : 1.0f;
;         f32x4 yh[2][2];
; #pragma unroll
;         for (int bj = 0; bj < 2; ++bj)
; #pragma unroll
;             for (int n = 0; n < 2; ++n) yh[bj][n] = *(const f32x4*)(YCH + b * 512 + ch0 + bj * 128 + 4 * n) * sg;
; #pragma unroll
;         for (int ai = 0; ai < 2; ++ai)
; #pragma unroll
;             for (int m = 0; m < 4; ++m) {
;                 const int k = row0 + ai * 128 + m * 16;
; #pragma unroll
;                 for (int bj = 0; bj < 2; ++bj) {
;                     const f32x4 v0 = acc[ai][bj][m][0] + yh[bj][0], v1 = acc[ai][bj][m][1] + yh[bj][1];
;                     u32x4 w; w.x = cvt_pk_bf16(v0[0], v0[1]); w.y = cvt_pk_bf16(v0[2], v0[3]); w.z = cvt_pk_bf16(v1[0], v1[1]); w.w = cvt_pk_bf16(v1[2], v1[3]);
;                     *(u32x4*)(CAT + (size_t)(b * 2048 + k) * CATW + 1024 + ch0 + bj * 128) = w;
	s_setprio 0
	s_add_i32 s43, s43, 2
	s_add_u32 s14, s14, 0x100
	s_addc_u32 s15, s15, 0
	s_add_u32 s41, s41, 0x100
	s_addc_u32 s42, s42, 0
	s_cmp_gt_u32 s43, 29
	s_cbranch_scc0 .LBB0_826
	s_ashr_i32 s5, s38, 1
	s_lshl_b32 s7, s38, 8
	s_lshl_b32 s14, s5, 9
	s_and_b32 s7, s7, 0x100
	s_ashr_i32 s15, s14, 31
	v_mov_b32_e32 v171, v161
	v_mov_b32_e32 v128, v166
	s_or_b32 s7, s7, s30
	s_lshl_b64 s[14:15], s[14:15], 2
	s_add_u32 s14, s48, s14
	v_lshl_add_u32 v164, v128, 3, s7
	s_addc_u32 s15, s49, s15
	v_ashrrev_i32_e32 v165, 31, v164
	v_lshl_add_u64 v[128:129], v[164:165], 2, s[14:15]
	global_load_dwordx4 v[140:143], v[128:129], off
	global_load_dwordx4 v[136:139], v[128:129], off offset:16
	global_load_dwordx4 v[132:135], v[128:129], off offset:512
	s_nop 0
	global_load_dwordx4 v[128:131], v[128:129], off offset:528
	s_lshl_b32 s7, s12, 8
	s_lshl_b32 s5, s5, 11
	s_add_i32 s7, s7, s29
	v_and_b32_e32 v160, 1, v171
	s_add_i32 s7, s7, s5
	v_mov_b64_e32 v[162:163], s[96:97]
	v_cmp_eq_u32_e32 vcc, 0, v160
	v_add_u32_e32 v171, s7, v171
	v_lshlrev_b64 v[164:165], 1, v[164:165]
	v_cndmask_b32_e64 v160, -1.0, 1.0, vcc
	v_mad_i64_i32 v[172:173], s[14:15], v171, s37, v[162:163]
	v_add_u32_e32 v174, 16, v171
	v_lshl_add_u64 v[172:173], v[172:173], 0, v[164:165]
	v_mad_i64_i32 v[174:175], s[14:15], v174, s37, v[162:163]
	v_add_u32_e32 v176, 32, v171
	v_lshl_add_u64 v[174:175], v[174:175], 0, v[164:165]
	v_mad_i64_i32 v[176:177], s[14:15], v176, s37, v[162:163]
	v_lshl_add_u64 v[176:177], v[176:177], 0, v[164:165]
	v_add_u32_e32 v182, 48, v171
	s_and_b64 vcc, exec, s[2:3]
	s_mov_b32 s38, s4
	s_mov_b32 s12, s6
	s_mov_b64 s[16:17], s[10:11]
	s_waitcnt vmcnt(0)
	v_pk_fma_f32 v[126:127], v[142:143], v[160:161], v[126:127] op_sel_hi:[1,0,1]
	v_pk_fma_f32 v[124:125], v[140:141], v[160:161], v[124:125] op_sel_hi:[1,0,1]
	v_pk_fma_f32 v[122:123], v[138:139], v[160:161], v[122:123] op_sel_hi:[1,0,1]
	v_pk_fma_f32 v[180:181], v[128:129], v[160:161], v[80:81] op_sel_hi:[1,0,1]
	v_cvt_pk_bf16_f32 v80, v124, v125
	v_cvt_pk_bf16_f32 v81, v126, v127
	v_pk_fma_f32 v[120:121], v[136:137], v[160:161], v[120:121] op_sel_hi:[1,0,1]
	v_pk_fma_f32 v[106:107], v[134:135], v[160:161], v[106:107] op_sel_hi:[1,0,1]
	v_pk_fma_f32 v[104:105], v[132:133], v[160:161], v[104:105] op_sel_hi:[1,0,1]
	v_pk_fma_f32 v[178:179], v[130:131], v[160:161], v[82:83] op_sel_hi:[1,0,1]
	v_cvt_pk_bf16_f32 v82, v120, v121
	v_cvt_pk_bf16_f32 v83, v122, v123
	global_store_dwordx4 v[172:173], v[80:83], off offset:2048
	v_pk_fma_f32 v[98:99], v[130:131], v[160:161], v[98:99] op_sel_hi:[1,0,1]
	v_pk_fma_f32 v[96:97], v[128:129], v[160:161], v[96:97] op_sel_hi:[1,0,1]
	v_cvt_pk_bf16_f32 v80, v104, v105
	v_cvt_pk_bf16_f32 v81, v106, v107
	v_pk_fma_f32 v[118:119], v[142:143], v[160:161], v[118:119] op_sel_hi:[1,0,1]
	v_pk_fma_f32 v[116:117], v[140:141], v[160:161], v[116:117] op_sel_hi:[1,0,1]
	v_cvt_pk_bf16_f32 v82, v96, v97
	v_cvt_pk_bf16_f32 v83, v98, v99
	global_store_dwordx4 v[172:173], v[80:83], off offset:2304
	v_pk_fma_f32 v[114:115], v[138:139], v[160:161], v[114:115] op_sel_hi:[1,0,1]
	v_pk_fma_f32 v[112:113], v[136:137], v[160:161], v[112:113] op_sel_hi:[1,0,1]
	v_cvt_pk_bf16_f32 v80, v116, v117
	v_cvt_pk_bf16_f32 v81, v118, v119
	v_pk_fma_f32 v[94:95], v[134:135], v[160:161], v[94:95] op_sel_hi:[1,0,1]
	v_pk_fma_f32 v[92:93], v[132:133], v[160:161], v[92:93] op_sel_hi:[1,0,1]
	v_cvt_pk_bf16_f32 v82, v112, v113
	v_cvt_pk_bf16_f32 v83, v114, v115
	global_store_dwordx4 v[174:175], v[80:83], off offset:2048
	v_pk_fma_f32 v[90:91], v[130:131], v[160:161], v[90:91] op_sel_hi:[1,0,1]
	v_pk_fma_f32 v[88:89], v[128:129], v[160:161], v[88:89] op_sel_hi:[1,0,1]
	v_cvt_pk_bf16_f32 v80, v92, v93
	v_cvt_pk_bf16_f32 v81, v94, v95
	v_pk_fma_f32 v[110:111], v[142:143], v[160:161], v[110:111] op_sel_hi:[1,0,1]
	v_pk_fma_f32 v[108:109], v[140:141], v[160:161], v[108:109] op_sel_hi:[1,0,1]
	v_cvt_pk_bf16_f32 v82, v88, v89
	v_cvt_pk_bf16_f32 v83, v90, v91
	global_store_dwordx4 v[174:175], v[80:83], off offset:2304
	v_pk_fma_f32 v[102:103], v[138:139], v[160:161], v[102:103] op_sel_hi:[1,0,1]
	v_pk_fma_f32 v[100:101], v[136:137], v[160:161], v[100:101] op_sel_hi:[1,0,1]
	v_cvt_pk_bf16_f32 v80, v108, v109
	v_cvt_pk_bf16_f32 v81, v110, v111
	v_pk_fma_f32 v[86:87], v[134:135], v[160:161], v[86:87] op_sel_hi:[1,0,1]
	v_pk_fma_f32 v[84:85], v[132:133], v[160:161], v[84:85] op_sel_hi:[1,0,1]
	v_cvt_pk_bf16_f32 v82, v100, v101
	v_cvt_pk_bf16_f32 v83, v102, v103
	global_store_dwordx4 v[176:177], v[80:83], off offset:2048
	v_pk_fma_f32 v[76:77], v[140:141], v[160:161], v[76:77] op_sel_hi:[1,0,1]
	v_pk_fma_f32 v[78:79], v[142:143], v[160:161], v[78:79] op_sel_hi:[1,0,1]
	v_cvt_pk_bf16_f32 v80, v84, v85
	v_cvt_pk_bf16_f32 v81, v86, v87
	v_cvt_pk_bf16_f32 v82, v180, v181
	v_cvt_pk_bf16_f32 v83, v178, v179
	global_store_dwordx4 v[176:177], v[80:83], off offset:2304
	v_pk_fma_f32 v[70:71], v[134:135], v[160:161], v[70:71] op_sel_hi:[1,0,1]
	v_pk_fma_f32 v[68:69], v[132:133], v[160:161], v[68:69] op_sel_hi:[1,0,1]
	v_pk_fma_f32 v[80:81], v[138:139], v[160:161], v[74:75] op_sel_hi:[1,0,1]
	v_pk_fma_f32 v[74:75], v[136:137], v[160:161], v[72:73] op_sel_hi:[1,0,1]
	v_cvt_pk_bf16_f32 v72, v76, v77
; __device__ __forceinline__ unsigned cvt_pk_bf16(float lo, float hi) { unsigned r; asm volatile("v_cvt_pk_bf16_f32 %0, %1, %2" : "=v"(r) : "v"(lo), "v"(hi)); return r; }
; #define PG8_WAIT_V(n) asm volatile("s_waitcnt vmcnt(" #n ")" ::: "memory")
; #define PG8_BAR __builtin_amdgcn_s_barrier()
; template <class Epi, class Sched>
; __device__ __forceinline__ void gemm_phase(LAS unsigned char* lds, const Gemm g, const Sched& S, const Epi& E) {
;     ...
;     PG8_WAIT_V(0);
;     if (wr == 0) PG8_BAR;
;     PG8_BAR;
;     __device__ __forceinline__ void operator()(const AccT& acc, const Unit& u, int wr, int wc, int fr, int fq) const {
;     ...
;         for (int ai = 0; ai < 2; ++ai)
; #pragma unroll
;             for (int m = 0; m < 4; ++m) {
;                 const int k = row0 + ai * 128 + m * 16;
; #pragma unroll
;                 for (int bj = 0; bj < 2; ++bj) {
;                     const f32x4 v0 = acc[ai][bj][m][0] + yh[bj][0], v1 = acc[ai][bj][m][1] + yh[bj][1];
;                     u32x4 w; w.x = cvt_pk_bf16(v0[0], v0[1]); w.y = cvt_pk_bf16(v0[2], v0[3]); w.z = cvt_pk_bf16(v1[0], v1[1]); w.w = cvt_pk_bf16(v1[2], v1[3]);
;                     *(u32x4*)(CAT + (size_t)(b * 2048 + k) * CATW + 1024 + ch0 + bj * 128) = w;
;                 }
;             }
	v_mad_i64_i32 v[76:77], s[14:15], v182, s37, v[162:163]
	v_cvt_pk_bf16_f32 v73, v78, v79
	v_lshl_add_u64 v[76:77], v[76:77], 0, v[164:165]
	v_cvt_pk_bf16_f32 v74, v74, v75
	v_cvt_pk_bf16_f32 v75, v80, v81
	global_store_dwordx4 v[76:77], v[72:75], off offset:2048
	v_pk_fma_f32 v[60:61], v[140:141], v[160:161], v[60:61] op_sel_hi:[1,0,1]
	v_pk_fma_f32 v[62:63], v[142:143], v[160:161], v[62:63] op_sel_hi:[1,0,1]
	v_pk_fma_f32 v[72:73], v[130:131], v[160:161], v[66:67] op_sel_hi:[1,0,1]
	v_pk_fma_f32 v[66:67], v[128:129], v[160:161], v[64:65] op_sel_hi:[1,0,1]
	v_cvt_pk_bf16_f32 v64, v68, v69
	v_cvt_pk_bf16_f32 v65, v70, v71
	v_pk_fma_f32 v[54:55], v[134:135], v[160:161], v[54:55] op_sel_hi:[1,0,1]
	v_cvt_pk_bf16_f32 v66, v66, v67
	v_cvt_pk_bf16_f32 v67, v72, v73
	global_store_dwordx4 v[76:77], v[64:67], off offset:2304
	v_pk_fma_f32 v[52:53], v[132:133], v[160:161], v[52:53] op_sel_hi:[1,0,1]
	v_pk_fma_f32 v[38:39], v[134:135], v[160:161], v[38:39] op_sel_hi:[1,0,1]
	v_add_u32_e32 v66, 0x80, v171
	v_pk_fma_f32 v[64:65], v[138:139], v[160:161], v[58:59] op_sel_hi:[1,0,1]
	v_pk_fma_f32 v[58:59], v[136:137], v[160:161], v[56:57] op_sel_hi:[1,0,1]
	v_cvt_pk_bf16_f32 v56, v60, v61
	v_mad_i64_i32 v[60:61], s[14:15], v66, s37, v[162:163]
	v_cvt_pk_bf16_f32 v57, v62, v63
	v_lshl_add_u64 v[60:61], v[60:61], 0, v[164:165]
	v_cvt_pk_bf16_f32 v58, v58, v59
	v_cvt_pk_bf16_f32 v59, v64, v65
	global_store_dwordx4 v[60:61], v[56:59], off offset:2048
	v_pk_fma_f32 v[36:37], v[132:133], v[160:161], v[36:37] op_sel_hi:[1,0,1]
	v_pk_fma_f32 v[22:23], v[134:135], v[160:161], v[22:23] op_sel_hi:[1,0,1]
	v_pk_fma_f32 v[56:57], v[130:131], v[160:161], v[46:47] op_sel_hi:[1,0,1]
	v_pk_fma_f32 v[46:47], v[128:129], v[160:161], v[44:45] op_sel_hi:[1,0,1]
	v_cvt_pk_bf16_f32 v44, v52, v53
	v_cvt_pk_bf16_f32 v45, v54, v55
	v_add_u32_e32 v52, 0x90, v171
	v_cvt_pk_bf16_f32 v46, v46, v47
	v_cvt_pk_bf16_f32 v47, v56, v57
	global_store_dwordx4 v[60:61], v[44:47], off offset:2304
	v_pk_fma_f32 v[20:21], v[132:133], v[160:161], v[20:21] op_sel_hi:[1,0,1]
	v_pk_fma_f32 v[6:7], v[134:135], v[160:161], v[6:7] op_sel_hi:[1,0,1]
	v_pk_fma_f32 v[44:45], v[142:143], v[160:161], v[50:51] op_sel_hi:[1,0,1]
	v_pk_fma_f32 v[46:47], v[140:141], v[160:161], v[48:49] op_sel_hi:[1,0,1]
	v_pk_fma_f32 v[48:49], v[138:139], v[160:161], v[42:43] op_sel_hi:[1,0,1]
	v_pk_fma_f32 v[42:43], v[136:137], v[160:161], v[40:41] op_sel_hi:[1,0,1]
	v_cvt_pk_bf16_f32 v40, v46, v47
	v_cvt_pk_bf16_f32 v41, v44, v45
	v_mad_i64_i32 v[44:45], s[14:15], v52, s37, v[162:163]
	v_lshl_add_u64 v[44:45], v[44:45], 0, v[164:165]
	v_cvt_pk_bf16_f32 v42, v42, v43
	v_cvt_pk_bf16_f32 v43, v48, v49
	global_store_dwordx4 v[44:45], v[40:43], off offset:2048
	v_pk_fma_f32 v[4:5], v[132:133], v[160:161], v[4:5] op_sel_hi:[1,0,1]
	s_nop 0
	v_pk_fma_f32 v[40:41], v[130:131], v[160:161], v[30:31] op_sel_hi:[1,0,1]
	v_pk_fma_f32 v[30:31], v[128:129], v[160:161], v[28:29] op_sel_hi:[1,0,1]
	v_cvt_pk_bf16_f32 v28, v36, v37
	v_cvt_pk_bf16_f32 v29, v38, v39
	v_add_u32_e32 v36, 0xa0, v171
	v_cvt_pk_bf16_f32 v30, v30, v31
	v_cvt_pk_bf16_f32 v31, v40, v41
	global_store_dwordx4 v[44:45], v[28:31], off offset:2304
	s_nop 1
	v_pk_fma_f32 v[28:29], v[142:143], v[160:161], v[34:35] op_sel_hi:[1,0,1]
	v_pk_fma_f32 v[30:31], v[140:141], v[160:161], v[32:33] op_sel_hi:[1,0,1]
	v_pk_fma_f32 v[32:33], v[138:139], v[160:161], v[26:27] op_sel_hi:[1,0,1]
	v_pk_fma_f32 v[26:27], v[136:137], v[160:161], v[24:25] op_sel_hi:[1,0,1]
	v_cvt_pk_bf16_f32 v24, v30, v31
	v_cvt_pk_bf16_f32 v25, v28, v29
	v_mad_i64_i32 v[28:29], s[14:15], v36, s37, v[162:163]
	v_lshl_add_u64 v[28:29], v[28:29], 0, v[164:165]
	v_cvt_pk_bf16_f32 v26, v26, v27
	v_cvt_pk_bf16_f32 v27, v32, v33
	global_store_dwordx4 v[28:29], v[24:27], off offset:2048
	s_nop 1
	v_pk_fma_f32 v[24:25], v[130:131], v[160:161], v[14:15] op_sel_hi:[1,0,1]
	v_pk_fma_f32 v[14:15], v[128:129], v[160:161], v[12:13] op_sel_hi:[1,0,1]
	v_cvt_pk_bf16_f32 v12, v20, v21
	v_cvt_pk_bf16_f32 v13, v22, v23
	v_add_u32_e32 v20, 0xb0, v171
	v_cvt_pk_bf16_f32 v14, v14, v15
	v_cvt_pk_bf16_f32 v15, v24, v25
	global_store_dwordx4 v[28:29], v[12:15], off offset:2304
	s_nop 1
	v_pk_fma_f32 v[12:13], v[142:143], v[160:161], v[18:19] op_sel_hi:[1,0,1]
	v_pk_fma_f32 v[14:15], v[140:141], v[160:161], v[16:17] op_sel_hi:[1,0,1]
	v_pk_fma_f32 v[16:17], v[138:139], v[160:161], v[10:11] op_sel_hi:[1,0,1]
	v_pk_fma_f32 v[10:11], v[136:137], v[160:161], v[8:9] op_sel_hi:[1,0,1]
	v_cvt_pk_bf16_f32 v8, v14, v15
	v_cvt_pk_bf16_f32 v9, v12, v13
	v_mad_i64_i32 v[12:13], s[14:15], v20, s37, v[162:163]
	v_lshl_add_u64 v[12:13], v[12:13], 0, v[164:165]
	v_cvt_pk_bf16_f32 v10, v10, v11
	v_cvt_pk_bf16_f32 v11, v16, v17
	global_store_dwordx4 v[12:13], v[8:11], off offset:2048
	s_mov_b64 s[14:15], s[8:9]
	s_nop 0
	v_pk_fma_f32 v[8:9], v[130:131], v[160:161], v[2:3] op_sel_hi:[1,0,1]
	v_pk_fma_f32 v[2:3], v[128:129], v[160:161], v[0:1] op_sel_hi:[1,0,1]
	v_cvt_pk_bf16_f32 v0, v4, v5
	v_cvt_pk_bf16_f32 v1, v6, v7
	s_nop 0
	v_cvt_pk_bf16_f32 v2, v2, v3
	v_cvt_pk_bf16_f32 v3, v8, v9
	global_store_dwordx4 v[12:13], v[0:3], off offset:2304
	s_cbranch_vccz .LBB0_819
	s_waitcnt vmcnt(0)
	s_cmpk_gt_u32 s20, 0xff
	s_cbranch_scc1 .LBB0_830
	s_barrier

; #define PG8_STAGE(bufoff, gbase, voff) do { _Pragma("unroll") for (int _i = 0; _i < 2; ++_i) \
;         __builtin_amdgcn_global_load_lds((const unsigned*)((const char*)(gbase) + (voff)[_i]), (LAS unsigned*)(lds + (bufoff) + ldsw + _i * 8192), 16, 0, 0); } while (0)
; #define PG8_LDA(dst, b, h) do { _Pragma("unroll") for (int m = 0; m < 4; ++m) _Pragma("unroll") for (int k = 0; k < 2; ++k) dst[m][k] = *(const LAS bf16x8*)(lds + PG8_SA(b, h) + aoff + m * 2048 + k * 1024); } while (0)
; #define PG8_LDB(dst, b, h) do { _Pragma("unroll") for (int n = 0; n < 2; ++n) _Pragma("unroll") for (int k = 0; k < 2; ++k) dst[n][k] = *(const LAS bf16x8*)(lds + PG8_SB(b, h) + boff + n * 2048 + k * 1024); } while (0)
; #define PG8_MMA(ai, bj, At, Bt) do { __builtin_amdgcn_s_setprio(1); _Pragma("unroll") for (int m = 0; m < 4; ++m) _Pragma("unroll") for (int n = 0; n < 2; ++n) _Pragma("unroll") for (int k = 0; k < 2; ++k) \
;         acc[ai][bj][m][n] = __builtin_amdgcn_mfma_f32_16x16x32_bf16(Bt[n][k], At[m][k], acc[ai][bj][m][n], 0, 0, 0); __builtin_amdgcn_s_setprio(0); } while (0)
; #define PG8_WAIT_L(n) asm volatile("s_waitcnt lgkmcnt(" #n ")" ::: "memory")
; template <class Epi, class Sched>
; __device__ __forceinline__ void gemm_phase(LAS unsigned char* lds, const Gemm g, const Sched& S, const Epi& E) {
;     ...
;         const bool has_next = S.next(ui + 1, nxt);
;         const char* nA = has_next ? (const char*)g.A + (size_t)nxt.pm * tstep : cA; const char* nB = has_next ? (const char*)g.Bt + (size_t)nxt.pn * tstep : cB;
;         for (int t = 0; t < nt; t += 2) {
;             const bool last = (t == nt - 2);
;             const char* a1 = cA + (size_t)(t + 1) * kstep;
;             const char* a2 = last ? nA : cA + (size_t)(t + 2) * kstep; const char* b2 = last ? nB : cB + (size_t)(t + 2) * kstep;
;             const char* a3 = a2 + kstep; const char* b3 = b2 + kstep;
;             PG8_LDB(B0, 0, 0); PG8_SCHED; PG8_LDA(At, 0, 0); PG8_STAGE(PG8_SA(1, 1), a1 + hstep, voffA);
;             PG8_WAIT_L(8); PG8_BAR; PG8_WAIT_L(0); PG8_MMA(0, 0, At, B0); PG8_BAR; PG8_SCHED;
;             PG8_LDB(B1, 0, 1); PG8_STAGE(PG8_SB(0, 0), b2, voffB);
;             PG8_BAR; PG8_WAIT_L(0); PG8_MMA(0, 1, At, B1); PG8_BAR;
;             PG8_LDA(At, 0, 1); PG8_STAGE(PG8_SA(0, 0), a2, voffA);
;             PG8_BAR; PG8_WAIT_L(0); PG8_MMA(1, 0, At, B0); PG8_BAR; PG8_SCHED;
.LBB0_901:
	s_add_u32 s56, s26, 0x100
	s_addc_u32 s57, s27, 0
	s_mov_b32 s58, -2
	s_waitcnt vmcnt(0)
	ds_read_b128 v[128:131], v237
	ds_read_b128 v[132:135], v237 offset:1024
	ds_read_b128 v[136:139], v237 offset:2048
	ds_read_b128 v[140:143], v237 offset:3072
	s_add_u32 s26, s24, 0x100
	s_addc_u32 s27, s25, 0
	s_cmp_eq_u32 s58, 20
	s_cselect_b32 s31, s5, s27
	s_cselect_b32 s30, s4, s26
	s_cselect_b32 s29, s7, s57
	s_cselect_b32 s28, s6, s56
	v_lshl_add_u64 v[176:177], s[24:25], 0, v[210:211]
	s_add_i32 m0, s38, 0xc000
	ds_read_b128 v[144:147], v238
	ds_read_b128 v[148:151], v238 offset:1024
	ds_read_b128 v[152:155], v238 offset:2048
	ds_read_b128 v[156:159], v238 offset:3072
	ds_read_b128 v[160:163], v238 offset:4096
	ds_read_b128 v[164:167], v238 offset:5120
	ds_read_b128 v[168:171], v238 offset:6144
	ds_read_b128 v[172:175], v238 offset:7168
	global_load_lds_dwordx4 v[176:177], off
	v_lshl_add_u64 v[176:177], s[24:25], 0, v[212:213]
	s_add_i32 m0, s38, 0xe000
	s_nop 0
	global_load_lds_dwordx4 v[176:177], off
	s_waitcnt lgkmcnt(8)
	s_waitcnt vmcnt(8)
	s_setprio 1
	s_barrier
	s_waitcnt lgkmcnt(0)
	v_mfma_f32_16x16x32_bf16 v[124:127], v[128:131], v[144:147], 0
	v_mfma_f32_16x16x32_bf16 v[120:123], v[136:139], v[144:147], 0
	v_mfma_f32_16x16x32_bf16 v[108:111], v[128:131], v[152:155], 0
	v_mfma_f32_16x16x32_bf16 v[104:107], v[136:139], v[152:155], 0
	v_mfma_f32_16x16x32_bf16 v[92:95], v[128:131], v[160:163], 0
	v_mfma_f32_16x16x32_bf16 v[88:91], v[136:139], v[160:163], 0
	v_mfma_f32_16x16x32_bf16 v[76:79], v[128:131], v[168:171], 0
	v_mfma_f32_16x16x32_bf16 v[72:75], v[136:139], v[168:171], 0
	v_mfma_f32_16x16x32_bf16 v[124:127], v[132:135], v[148:151], v[124:127]
	v_mfma_f32_16x16x32_bf16 v[120:123], v[140:143], v[148:151], v[120:123]
	v_mfma_f32_16x16x32_bf16 v[108:111], v[132:135], v[156:159], v[108:111]
	v_mfma_f32_16x16x32_bf16 v[104:107], v[140:143], v[156:159], v[104:107]
	v_mfma_f32_16x16x32_bf16 v[92:95], v[132:135], v[164:167], v[92:95]
	v_mfma_f32_16x16x32_bf16 v[88:91], v[140:143], v[164:167], v[88:91]
	v_mfma_f32_16x16x32_bf16 v[76:79], v[132:135], v[172:175], v[76:79]
	v_mfma_f32_16x16x32_bf16 v[72:75], v[140:143], v[172:175], v[72:75]
	s_barrier
	s_setprio 0
	s_add_i32 s24, s50, s37
	s_mov_b32 m0, s24
	ds_read_b128 v[176:179], v239
	ds_read_b128 v[180:183], v239 offset:1024
	ds_read_b128 v[184:187], v239 offset:2048
	ds_read_b128 v[188:191], v239 offset:3072
	global_load_lds_dwordx4 v204, s[28:29]
	s_add_i32 m0, s24, 0x2000
	s_nop 0
	global_load_lds_dwordx4 v208, s[28:29]
	s_waitcnt vmcnt(8)
	s_setprio 1
	s_barrier
	s_waitcnt lgkmcnt(0)
	v_mfma_f32_16x16x32_bf16 v[116:119], v[176:179], v[144:147], 0
	v_mfma_f32_16x16x32_bf16 v[112:115], v[184:187], v[144:147], 0
	v_mfma_f32_16x16x32_bf16 v[100:103], v[176:179], v[152:155], 0
	v_mfma_f32_16x16x32_bf16 v[96:99], v[184:187], v[152:155], 0
	v_mfma_f32_16x16x32_bf16 v[84:87], v[176:179], v[160:163], 0
	v_mfma_f32_16x16x32_bf16 v[80:83], v[184:187], v[160:163], 0
	v_mfma_f32_16x16x32_bf16 v[68:71], v[176:179], v[168:171], 0
	v_mfma_f32_16x16x32_bf16 v[64:67], v[184:187], v[168:171], 0
	v_mfma_f32_16x16x32_bf16 v[116:119], v[180:183], v[148:151], v[116:119]
	v_mfma_f32_16x16x32_bf16 v[112:115], v[188:191], v[148:151], v[112:115]
	v_mfma_f32_16x16x32_bf16 v[100:103], v[180:183], v[156:159], v[100:103]
	v_mfma_f32_16x16x32_bf16 v[96:99], v[188:191], v[156:159], v[96:99]
	v_mfma_f32_16x16x32_bf16 v[84:87], v[180:183], v[164:167], v[84:87]
	v_mfma_f32_16x16x32_bf16 v[80:83], v[188:191], v[164:167], v[80:83]
	v_mfma_f32_16x16x32_bf16 v[68:71], v[180:183], v[172:175], v[68:71]
	v_mfma_f32_16x16x32_bf16 v[64:67], v[188:191], v[172:175], v[64:67]
	s_barrier
	s_setprio 0
	s_mov_b32 m0, s38
	v_lshl_add_u64 v[196:197], s[30:31], 0, v[202:203]
	ds_read_b128 v[144:147], v238 offset:16384
	ds_read_b128 v[148:151], v238 offset:17408
	ds_read_b128 v[152:155], v238 offset:18432
	ds_read_b128 v[156:159], v238 offset:19456
	ds_read_b128 v[160:163], v238 offset:20480
	ds_read_b128 v[164:167], v238 offset:21504
	ds_read_b128 v[168:171], v238 offset:22528
	ds_read_b128 v[172:175], v238 offset:23552
	global_load_lds_dwordx4 v202, s[30:31]
	v_lshl_add_u64 v[198:199], s[30:31], 0, v[206:207]
	s_mov_b32 m0, s39
	s_nop 0
	global_load_lds_dwordx4 v206, s[30:31]
	s_setprio 1
	s_barrier
	s_waitcnt lgkmcnt(0)
	v_mfma_f32_16x16x32_bf16 v[60:63], v[128:131], v[144:147], 0
	v_mfma_f32_16x16x32_bf16 v[56:59], v[136:139], v[144:147], 0
	v_mfma_f32_16x16x32_bf16 v[44:47], v[128:131], v[152:155], 0
	v_mfma_f32_16x16x32_bf16 v[40:43], v[136:139], v[152:155], 0
	v_mfma_f32_16x16x32_bf16 v[28:31], v[128:131], v[160:163], 0
	v_mfma_f32_16x16x32_bf16 v[24:27], v[136:139], v[160:163], 0
	v_mfma_f32_16x16x32_bf16 v[12:15], v[128:131], v[168:171], 0
	v_mfma_f32_16x16x32_bf16 v[8:11], v[136:139], v[168:171], 0
	v_mfma_f32_16x16x32_bf16 v[60:63], v[132:135], v[148:151], v[60:63]
	v_mfma_f32_16x16x32_bf16 v[56:59], v[140:143], v[148:151], v[56:59]
	v_mfma_f32_16x16x32_bf16 v[44:47], v[132:135], v[156:159], v[44:47]
	v_mfma_f32_16x16x32_bf16 v[40:43], v[140:143], v[156:159], v[40:43]
	v_mfma_f32_16x16x32_bf16 v[28:31], v[132:135], v[164:167], v[28:31]
	v_mfma_f32_16x16x32_bf16 v[24:27], v[140:143], v[164:167], v[24:27]
	v_mfma_f32_16x16x32_bf16 v[12:15], v[132:135], v[172:175], v[12:15]
	v_mfma_f32_16x16x32_bf16 v[8:11], v[140:143], v[172:175], v[8:11]
	s_barrier
	s_setprio 0
	s_add_u32 s24, s28, 0x60000
	s_addc_u32 s25, s29, 0
	s_add_i32 s59, s51, s37
	s_mov_b32 m0, s59
	s_nop 0
	global_load_lds_dwordx4 v204, s[24:25]
	s_add_i32 m0, s59, 0x2000
	s_nop 0
	global_load_lds_dwordx4 v208, s[24:25]
	s_add_u32 s24, s30, 0x60000
	s_addc_u32 s25, s31, 0
	s_mov_b32 m0, s40
	s_nop 0
	global_load_lds_dwordx4 v202, s[24:25]
	s_mov_b32 m0, s41
	s_nop 0
	global_load_lds_dwordx4 v206, s[24:25]
	s_waitcnt vmcnt(10)
	s_setprio 1
	s_barrier
; #define PG8_STAGE(bufoff, gbase, voff) do { _Pragma("unroll") for (int _i = 0; _i < 2; ++_i) \
;         __builtin_amdgcn_global_load_lds((const unsigned*)((const char*)(gbase) + (voff)[_i]), (LAS unsigned*)(lds + (bufoff) + ldsw + _i * 8192), 16, 0, 0); } while (0)
; #define PG8_LDA(dst, b, h) do { _Pragma("unroll") for (int m = 0; m < 4; ++m) _Pragma("unroll") for (int k = 0; k < 2; ++k) dst[m][k] = *(const LAS bf16x8*)(lds + PG8_SA(b, h) + aoff + m * 2048 + k * 1024); } while (0)
; #define PG8_LDB(dst, b, h) do { _Pragma("unroll") for (int n = 0; n < 2; ++n) _Pragma("unroll") for (int k = 0; k < 2; ++k) dst[n][k] = *(const LAS bf16x8*)(lds + PG8_SB(b, h) + boff + n * 2048 + k * 1024); } while (0)
; #define PG8_MMA(ai, bj, At, Bt) do { __builtin_amdgcn_s_setprio(1); _Pragma("unroll") for (int m = 0; m < 4; ++m) _Pragma("unroll") for (int n = 0; n < 2; ++n) _Pragma("unroll") for (int k = 0; k < 2; ++k) \
;         acc[ai][bj][m][n] = __builtin_amdgcn_mfma_f32_16x16x32_bf16(Bt[n][k], At[m][k], acc[ai][bj][m][n], 0, 0, 0); __builtin_amdgcn_s_setprio(0); } while (0)
; #define PG8_WAIT_V(n) asm volatile("s_waitcnt vmcnt(" #n ")" ::: "memory")
; #define PG8_WAIT_L(n) asm volatile("s_waitcnt lgkmcnt(" #n ")" ::: "memory")
; #define PG8_BAR __builtin_amdgcn_s_barrier()
; #define PG8_SCHED __builtin_amdgcn_sched_barrier(0)
; template <class Epi, class Sched>
; __device__ __forceinline__ void gemm_phase(LAS unsigned char* lds, const Gemm g, const Sched& S, const Epi& E) {
;     ...
;             PG8_STAGE(PG8_SB(0, 1), b2 + hstep, voffB);
;             PG8_WAIT_V(6); PG8_BAR; PG8_MMA(1, 1, At, B1); PG8_BAR;
;             PG8_LDB(B0, 1, 0); PG8_SCHED; PG8_LDA(At, 1, 0); PG8_STAGE(PG8_SA(0, 1), a2 + hstep, voffA);
;             PG8_WAIT_L(8); PG8_BAR; PG8_WAIT_L(0); PG8_MMA(0, 0, At, B0); PG8_BAR; PG8_SCHED;
;             PG8_LDB(B1, 1, 1); PG8_STAGE(PG8_SB(1, 0), b3, voffB);
;             PG8_BAR; PG8_WAIT_L(0); PG8_MMA(0, 1, At, B1); PG8_BAR;
;             PG8_LDA(At, 1, 1); PG8_STAGE(PG8_SA(1, 0), a3, voffA);
	v_mfma_f32_16x16x32_bf16 v[52:55], v[176:179], v[144:147], 0
	v_mfma_f32_16x16x32_bf16 v[48:51], v[184:187], v[144:147], 0
	v_mfma_f32_16x16x32_bf16 v[36:39], v[176:179], v[152:155], 0
	v_mfma_f32_16x16x32_bf16 v[32:35], v[184:187], v[152:155], 0
	v_mfma_f32_16x16x32_bf16 v[20:23], v[176:179], v[160:163], 0
	v_mfma_f32_16x16x32_bf16 v[16:19], v[184:187], v[160:163], 0
	v_mfma_f32_16x16x32_bf16 v[4:7], v[176:179], v[168:171], 0
	v_mfma_f32_16x16x32_bf16 v[0:3], v[184:187], v[168:171], 0
	v_mfma_f32_16x16x32_bf16 v[52:55], v[180:183], v[148:151], v[52:55]
	v_mfma_f32_16x16x32_bf16 v[48:51], v[188:191], v[148:151], v[48:51]
	v_mfma_f32_16x16x32_bf16 v[36:39], v[180:183], v[156:159], v[36:39]
	v_mfma_f32_16x16x32_bf16 v[32:35], v[188:191], v[156:159], v[32:35]
	v_mfma_f32_16x16x32_bf16 v[20:23], v[180:183], v[164:167], v[20:23]
	v_mfma_f32_16x16x32_bf16 v[16:19], v[188:191], v[164:167], v[16:19]
	v_mfma_f32_16x16x32_bf16 v[4:7], v[180:183], v[172:175], v[4:7]
	v_mfma_f32_16x16x32_bf16 v[0:3], v[188:191], v[172:175], v[0:3]
	s_barrier
	s_setprio 0
	s_add_i32 s59, 0, 0x18000
	ds_read_b128 v[128:131], v239 offset:16384
	ds_read_b128 v[132:135], v239 offset:17408
	ds_read_b128 v[136:139], v239 offset:18432
	ds_read_b128 v[140:143], v239 offset:19456
	ds_read_b128 v[144:147], v238 offset:32768
	ds_read_b128 v[148:151], v238 offset:33792
	ds_read_b128 v[152:155], v238 offset:34816
	ds_read_b128 v[156:159], v238 offset:35840
	ds_read_b128 v[160:163], v238 offset:36864
	ds_read_b128 v[164:167], v238 offset:37888
	ds_read_b128 v[168:171], v238 offset:38912
	ds_read_b128 v[172:175], v238 offset:39936
	s_waitcnt lgkmcnt(8)
	s_waitcnt vmcnt(8)
	s_setprio 1
	s_barrier
	s_waitcnt lgkmcnt(0)
	v_mfma_f32_16x16x32_bf16 v[124:127], v[128:131], v[144:147], v[124:127]
	v_mfma_f32_16x16x32_bf16 v[120:123], v[136:139], v[144:147], v[120:123]
	v_mfma_f32_16x16x32_bf16 v[108:111], v[128:131], v[152:155], v[108:111]
	v_mfma_f32_16x16x32_bf16 v[104:107], v[136:139], v[152:155], v[104:107]
	v_mfma_f32_16x16x32_bf16 v[92:95], v[128:131], v[160:163], v[92:95]
	v_mfma_f32_16x16x32_bf16 v[88:91], v[136:139], v[160:163], v[88:91]
	v_mfma_f32_16x16x32_bf16 v[76:79], v[128:131], v[168:171], v[76:79]
	v_mfma_f32_16x16x32_bf16 v[72:75], v[136:139], v[168:171], v[72:75]
	v_mfma_f32_16x16x32_bf16 v[124:127], v[132:135], v[148:151], v[124:127]
	v_mfma_f32_16x16x32_bf16 v[120:123], v[140:143], v[148:151], v[120:123]
	v_mfma_f32_16x16x32_bf16 v[108:111], v[132:135], v[156:159], v[108:111]
	v_mfma_f32_16x16x32_bf16 v[104:107], v[140:143], v[156:159], v[104:107]
	v_mfma_f32_16x16x32_bf16 v[92:95], v[132:135], v[164:167], v[92:95]
	v_mfma_f32_16x16x32_bf16 v[88:91], v[140:143], v[164:167], v[88:91]
	v_mfma_f32_16x16x32_bf16 v[76:79], v[132:135], v[172:175], v[76:79]
	v_mfma_f32_16x16x32_bf16 v[72:75], v[140:143], v[172:175], v[72:75]
	s_barrier
	s_setprio 0
	s_add_i32 s30, 0, 0x1c000
	s_add_i32 s24, s59, s37
	v_add_u32_e32 v188, s30, v236
	s_add_u32 s0, s28, 0x80
	s_addc_u32 s1, s29, 0
	s_mov_b32 m0, s24
	ds_read_b128 v[176:179], v188
	ds_read_b128 v[180:183], v188 offset:1024
	ds_read_b128 v[184:187], v188 offset:2048
	ds_read_b128 v[188:191], v188 offset:3072
	global_load_lds_dwordx4 v204, s[0:1]
	s_add_i32 m0, s24, 0x2000
	s_nop 0
	global_load_lds_dwordx4 v208, s[0:1]
	s_waitcnt vmcnt(8)
	s_setprio 1
	s_barrier
	s_waitcnt lgkmcnt(0)
	v_mfma_f32_16x16x32_bf16 v[116:119], v[176:179], v[144:147], v[116:119]
	v_mfma_f32_16x16x32_bf16 v[112:115], v[184:187], v[144:147], v[112:115]
	v_mfma_f32_16x16x32_bf16 v[100:103], v[176:179], v[152:155], v[100:103]
	v_mfma_f32_16x16x32_bf16 v[96:99], v[184:187], v[152:155], v[96:99]
	v_mfma_f32_16x16x32_bf16 v[84:87], v[176:179], v[160:163], v[84:87]
	v_mfma_f32_16x16x32_bf16 v[80:83], v[184:187], v[160:163], v[80:83]
	v_mfma_f32_16x16x32_bf16 v[68:71], v[176:179], v[168:171], v[68:71]
	v_mfma_f32_16x16x32_bf16 v[64:67], v[184:187], v[168:171], v[64:67]
	v_mfma_f32_16x16x32_bf16 v[116:119], v[180:183], v[148:151], v[116:119]
	v_mfma_f32_16x16x32_bf16 v[112:115], v[188:191], v[148:151], v[112:115]
	v_mfma_f32_16x16x32_bf16 v[100:103], v[180:183], v[156:159], v[100:103]
	v_mfma_f32_16x16x32_bf16 v[96:99], v[188:191], v[156:159], v[96:99]
	v_mfma_f32_16x16x32_bf16 v[84:87], v[180:183], v[164:167], v[84:87]
	v_mfma_f32_16x16x32_bf16 v[80:83], v[188:191], v[164:167], v[80:83]
	v_mfma_f32_16x16x32_bf16 v[68:71], v[180:183], v[172:175], v[68:71]
	v_mfma_f32_16x16x32_bf16 v[64:67], v[188:191], v[172:175], v[64:67]
	s_barrier
	s_setprio 0
	s_mov_b32 m0, s47
	s_mov_b64 s[0:1], 0x80
	v_lshl_add_u64 v[192:193], v[196:197], 0, s[0:1]
	ds_read_b128 v[144:147], v238 offset:49152
	ds_read_b128 v[148:151], v238 offset:50176
	ds_read_b128 v[152:155], v238 offset:51200
	ds_read_b128 v[156:159], v238 offset:52224
	ds_read_b128 v[160:163], v238 offset:53248
	ds_read_b128 v[164:167], v238 offset:54272
	ds_read_b128 v[168:171], v238 offset:55296
	ds_read_b128 v[172:175], v238 offset:56320
	global_load_lds_dwordx4 v[192:193], off
	v_lshl_add_u64 v[192:193], v[198:199], 0, s[0:1]
	s_mov_b32 m0, s48
	s_nop 0
	global_load_lds_dwordx4 v[192:193], off
	s_setprio 1
	s_barrier
; #define PG8_STAGE(bufoff, gbase, voff) do { _Pragma("unroll") for (int _i = 0; _i < 2; ++_i) \
;         __builtin_amdgcn_global_load_lds((const unsigned*)((const char*)(gbase) + (voff)[_i]), (LAS unsigned*)(lds + (bufoff) + ldsw + _i * 8192), 16, 0, 0); } while (0)
; #define PG8_LDA(dst, b, h) do { _Pragma("unroll") for (int m = 0; m < 4; ++m) _Pragma("unroll") for (int k = 0; k < 2; ++k) dst[m][k] = *(const LAS bf16x8*)(lds + PG8_SA(b, h) + aoff + m * 2048 + k * 1024); } while (0)
; #define PG8_LDB(dst, b, h) do { _Pragma("unroll") for (int n = 0; n < 2; ++n) _Pragma("unroll") for (int k = 0; k < 2; ++k) dst[n][k] = *(const LAS bf16x8*)(lds + PG8_SB(b, h) + boff + n * 2048 + k * 1024); } while (0)
; #define PG8_WAIT_V(n) asm volatile("s_waitcnt vmcnt(" #n ")" ::: "memory")
; #define PG8_WAIT_L(n) asm volatile("s_waitcnt lgkmcnt(" #n ")" ::: "memory")
; #define PG8_BAR __builtin_amdgcn_s_barrier()
; #define PG8_SCHED __builtin_amdgcn_sched_barrier(0)
; template <class Epi, class Sched>
; __device__ __forceinline__ void gemm_phase(LAS unsigned char* lds, const Gemm g, const Sched& S, const Epi& E) {
;     ...
;             PG8_LDB(B0, 0, 0); PG8_SCHED; PG8_LDA(At, 0, 0); PG8_STAGE(PG8_SA(1, 1), a1 + hstep, voffA);
;             PG8_WAIT_L(8); PG8_BAR; PG8_WAIT_L(0); PG8_MMA(0, 0, At, B0); PG8_BAR; PG8_SCHED;
;             PG8_LDB(B1, 0, 1); PG8_STAGE(PG8_SB(0, 0), b2, voffB);
;             PG8_BAR; PG8_WAIT_L(0); PG8_MMA(0, 1, At, B1); PG8_BAR;
;             PG8_LDA(At, 0, 1); PG8_STAGE(PG8_SA(0, 0), a2, voffA);
;             PG8_BAR; PG8_WAIT_L(0); PG8_MMA(1, 0, At, B0); PG8_BAR; PG8_SCHED;
;             PG8_STAGE(PG8_SB(0, 1), b2 + hstep, voffB);
;             PG8_WAIT_V(6); PG8_BAR; PG8_MMA(1, 1, At, B1); PG8_BAR;
;             PG8_LDB(B0, 1, 0); PG8_SCHED; PG8_LDA(At, 1, 0); PG8_STAGE(PG8_SA(0, 1), a2 + hstep, voffA);
;             PG8_WAIT_L(8); PG8_BAR; PG8_WAIT_L(0); PG8_MMA(0, 0, At, B0); PG8_BAR; PG8_SCHED;
;             PG8_LDB(B1, 1, 1); PG8_STAGE(PG8_SB(1, 0), b3, voffB);
;             PG8_BAR; PG8_WAIT_L(0); PG8_MMA(0, 1, At, B1); PG8_BAR;
;             PG8_LDA(At, 1, 1); PG8_STAGE(PG8_SA(1, 0), a3, voffA);
;             PG8_BAR; PG8_WAIT_L(0); PG8_MMA(1, 0, At, B0); PG8_BAR; PG8_SCHED;
;             PG8_STAGE(PG8_SB(1, 1), b3 + hstep, voffB);
;             PG8_WAIT_V(6); PG8_BAR; PG8_MMA(1, 1, At, B1); PG8_BAR;
	s_waitcnt lgkmcnt(0)
	v_mfma_f32_16x16x32_bf16 v[60:63], v[128:131], v[144:147], v[60:63]
	v_mfma_f32_16x16x32_bf16 v[56:59], v[136:139], v[144:147], v[56:59]
	v_mfma_f32_16x16x32_bf16 v[44:47], v[128:131], v[152:155], v[44:47]
	v_mfma_f32_16x16x32_bf16 v[40:43], v[136:139], v[152:155], v[40:43]
	v_mfma_f32_16x16x32_bf16 v[28:31], v[128:131], v[160:163], v[28:31]
	v_mfma_f32_16x16x32_bf16 v[24:27], v[136:139], v[160:163], v[24:27]
	v_mfma_f32_16x16x32_bf16 v[12:15], v[128:131], v[168:171], v[12:15]
	v_mfma_f32_16x16x32_bf16 v[8:11], v[136:139], v[168:171], v[8:11]
	v_mfma_f32_16x16x32_bf16 v[60:63], v[132:135], v[148:151], v[60:63]
	v_mfma_f32_16x16x32_bf16 v[56:59], v[140:143], v[148:151], v[56:59]
	v_mfma_f32_16x16x32_bf16 v[44:47], v[132:135], v[156:159], v[44:47]
	v_mfma_f32_16x16x32_bf16 v[40:43], v[140:143], v[156:159], v[40:43]
	v_mfma_f32_16x16x32_bf16 v[28:31], v[132:135], v[164:167], v[28:31]
	v_mfma_f32_16x16x32_bf16 v[24:27], v[140:143], v[164:167], v[24:27]
	v_mfma_f32_16x16x32_bf16 v[12:15], v[132:135], v[172:175], v[12:15]
	v_mfma_f32_16x16x32_bf16 v[8:11], v[140:143], v[172:175], v[8:11]
	s_barrier
	s_setprio 0
	s_add_u32 s24, s28, 0x60080
	s_addc_u32 s25, s29, 0
	s_add_i32 s28, s30, s37
	s_mov_b32 m0, s28
	s_nop 0
	global_load_lds_dwordx4 v204, s[24:25]
	s_add_i32 m0, s28, 0x2000
	s_nop 0
	global_load_lds_dwordx4 v208, s[24:25]
	s_waitcnt vmcnt(8)
	s_setprio 1
	s_barrier
	v_mfma_f32_16x16x32_bf16 v[52:55], v[176:179], v[144:147], v[52:55]
	v_mfma_f32_16x16x32_bf16 v[48:51], v[184:187], v[144:147], v[48:51]
	v_mfma_f32_16x16x32_bf16 v[36:39], v[176:179], v[152:155], v[36:39]
	v_mfma_f32_16x16x32_bf16 v[32:35], v[184:187], v[152:155], v[32:35]
	v_mfma_f32_16x16x32_bf16 v[20:23], v[176:179], v[160:163], v[20:23]
	v_mfma_f32_16x16x32_bf16 v[16:19], v[184:187], v[160:163], v[16:19]
	v_mfma_f32_16x16x32_bf16 v[4:7], v[176:179], v[168:171], v[4:7]
	v_mfma_f32_16x16x32_bf16 v[0:3], v[184:187], v[168:171], v[0:3]
	v_mfma_f32_16x16x32_bf16 v[52:55], v[180:183], v[148:151], v[52:55]
	v_mfma_f32_16x16x32_bf16 v[48:51], v[188:191], v[148:151], v[48:51]
	v_mfma_f32_16x16x32_bf16 v[36:39], v[180:183], v[156:159], v[36:39]
	v_mfma_f32_16x16x32_bf16 v[32:35], v[188:191], v[156:159], v[32:35]
	v_mfma_f32_16x16x32_bf16 v[20:23], v[180:183], v[164:167], v[20:23]
	v_mfma_f32_16x16x32_bf16 v[16:19], v[188:191], v[164:167], v[16:19]
	v_mfma_f32_16x16x32_bf16 v[4:7], v[180:183], v[172:175], v[4:7]
	v_mfma_f32_16x16x32_bf16 v[0:3], v[188:191], v[172:175], v[0:3]
	s_barrier
	s_setprio 0
	s_add_i32 s58, s58, 2
	s_add_u32 s56, s56, 0x100
	s_addc_u32 s57, s57, 0
	s_cmp_gt_u32 s58, 21
	s_mov_b64 s[24:25], s[26:27]
.LBB0_902:
	ds_read_b128 v[128:131], v237
	ds_read_b128 v[132:135], v237 offset:1024
	ds_read_b128 v[136:139], v237 offset:2048
	ds_read_b128 v[140:143], v237 offset:3072
	s_add_u32 s26, s24, 0x100
	s_addc_u32 s27, s25, 0
	s_cmp_eq_u32 s58, 20
	s_cselect_b32 s31, s5, s27
	s_cselect_b32 s30, s4, s26
	s_cselect_b32 s29, s7, s57
	s_cselect_b32 s28, s6, s56
	v_lshl_add_u64 v[176:177], s[24:25], 0, v[210:211]
	s_add_i32 m0, s38, 0xc000
	ds_read_b128 v[144:147], v238
	ds_read_b128 v[148:151], v238 offset:1024
	ds_read_b128 v[152:155], v238 offset:2048
	ds_read_b128 v[156:159], v238 offset:3072
	ds_read_b128 v[160:163], v238 offset:4096
	ds_read_b128 v[164:167], v238 offset:5120
	ds_read_b128 v[168:171], v238 offset:6144
	ds_read_b128 v[172:175], v238 offset:7168
	global_load_lds_dwordx4 v[176:177], off
	v_lshl_add_u64 v[176:177], s[24:25], 0, v[212:213]
	s_add_i32 m0, s38, 0xe000
	s_nop 0
	global_load_lds_dwordx4 v[176:177], off
	s_waitcnt lgkmcnt(8)
	s_waitcnt vmcnt(8)
	s_setprio 1
	s_barrier
	s_waitcnt lgkmcnt(0)
	v_mfma_f32_16x16x32_bf16 v[124:127], v[128:131], v[144:147], v[124:127]
	v_mfma_f32_16x16x32_bf16 v[120:123], v[136:139], v[144:147], v[120:123]
	v_mfma_f32_16x16x32_bf16 v[108:111], v[128:131], v[152:155], v[108:111]
	v_mfma_f32_16x16x32_bf16 v[104:107], v[136:139], v[152:155], v[104:107]
	v_mfma_f32_16x16x32_bf16 v[92:95], v[128:131], v[160:163], v[92:95]
	v_mfma_f32_16x16x32_bf16 v[88:91], v[136:139], v[160:163], v[88:91]
	v_mfma_f32_16x16x32_bf16 v[76:79], v[128:131], v[168:171], v[76:79]
	v_mfma_f32_16x16x32_bf16 v[72:75], v[136:139], v[168:171], v[72:75]
	v_mfma_f32_16x16x32_bf16 v[124:127], v[132:135], v[148:151], v[124:127]
	v_mfma_f32_16x16x32_bf16 v[120:123], v[140:143], v[148:151], v[120:123]
	v_mfma_f32_16x16x32_bf16 v[108:111], v[132:135], v[156:159], v[108:111]
	v_mfma_f32_16x16x32_bf16 v[104:107], v[140:143], v[156:159], v[104:107]
	v_mfma_f32_16x16x32_bf16 v[92:95], v[132:135], v[164:167], v[92:95]
	v_mfma_f32_16x16x32_bf16 v[88:91], v[140:143], v[164:167], v[88:91]
	v_mfma_f32_16x16x32_bf16 v[76:79], v[132:135], v[172:175], v[76:79]
	v_mfma_f32_16x16x32_bf16 v[72:75], v[140:143], v[172:175], v[72:75]
	s_barrier
	s_setprio 0
	s_add_i32 s24, s50, s37
	s_mov_b32 m0, s24
	ds_read_b128 v[176:179], v239
	ds_read_b128 v[180:183], v239 offset:1024
	ds_read_b128 v[184:187], v239 offset:2048
	ds_read_b128 v[188:191], v239 offset:3072
	global_load_lds_dwordx4 v204, s[28:29]
	s_add_i32 m0, s24, 0x2000
	s_nop 0
	global_load_lds_dwordx4 v208, s[28:29]
	s_waitcnt vmcnt(8)
	s_setprio 1
	s_barrier
; #define PG8_STAGE(bufoff, gbase, voff) do { _Pragma("unroll") for (int _i = 0; _i < 2; ++_i) \
;         __builtin_amdgcn_global_load_lds((const unsigned*)((const char*)(gbase) + (voff)[_i]), (LAS unsigned*)(lds + (bufoff) + ldsw + _i * 8192), 16, 0, 0); } while (0)
; #define PG8_LDA(dst, b, h) do { _Pragma("unroll") for (int m = 0; m < 4; ++m) _Pragma("unroll") for (int k = 0; k < 2; ++k) dst[m][k] = *(const LAS bf16x8*)(lds + PG8_SA(b, h) + aoff + m * 2048 + k * 1024); } while (0)
; #define PG8_LDB(dst, b, h) do { _Pragma("unroll") for (int n = 0; n < 2; ++n) _Pragma("unroll") for (int k = 0; k < 2; ++k) dst[n][k] = *(const LAS bf16x8*)(lds + PG8_SB(b, h) + boff + n * 2048 + k * 1024); } while (0)
; #define PG8_MMA(ai, bj, At, Bt) do { __builtin_amdgcn_s_setprio(1); _Pragma("unroll") for (int m = 0; m < 4; ++m) _Pragma("unroll") for (int n = 0; n < 2; ++n) _Pragma("unroll") for (int k = 0; k < 2; ++k) \
;         acc[ai][bj][m][n] = __builtin_amdgcn_mfma_f32_16x16x32_bf16(Bt[n][k], At[m][k], acc[ai][bj][m][n], 0, 0, 0); __builtin_amdgcn_s_setprio(0); } while (0)
; #define PG8_WAIT_V(n) asm volatile("s_waitcnt vmcnt(" #n ")" ::: "memory")
; #define PG8_WAIT_L(n) asm volatile("s_waitcnt lgkmcnt(" #n ")" ::: "memory")
; #define PG8_BAR __builtin_amdgcn_s_barrier()
; #define PG8_SCHED __builtin_amdgcn_sched_barrier(0)
; template <class Epi, class Sched>
; __device__ __forceinline__ void gemm_phase(LAS unsigned char* lds, const Gemm g, const Sched& S, const Epi& E) {
;     ...
;             PG8_BAR; PG8_WAIT_L(0); PG8_MMA(1, 0, At, B0); PG8_BAR; PG8_SCHED;
;             PG8_STAGE(PG8_SB(0, 1), b2 + hstep, voffB);
;             PG8_WAIT_V(6); PG8_BAR; PG8_MMA(1, 1, At, B1); PG8_BAR;
;             PG8_LDB(B0, 1, 0); PG8_SCHED; PG8_LDA(At, 1, 0); PG8_STAGE(PG8_SA(0, 1), a2 + hstep, voffA);
;             PG8_WAIT_L(8); PG8_BAR; PG8_WAIT_L(0); PG8_MMA(0, 0, At, B0); PG8_BAR; PG8_SCHED;
;             PG8_LDB(B1, 1, 1); PG8_STAGE(PG8_SB(1, 0), b3, voffB);
;             PG8_BAR; PG8_WAIT_L(0); PG8_MMA(0, 1, At, B1); PG8_BAR;
;             PG8_LDA(At, 1, 1); PG8_STAGE(PG8_SA(1, 0), a3, voffA);
	s_waitcnt lgkmcnt(0)
	v_mfma_f32_16x16x32_bf16 v[116:119], v[176:179], v[144:147], v[116:119]
	v_mfma_f32_16x16x32_bf16 v[112:115], v[184:187], v[144:147], v[112:115]
	v_mfma_f32_16x16x32_bf16 v[100:103], v[176:179], v[152:155], v[100:103]
	v_mfma_f32_16x16x32_bf16 v[96:99], v[184:187], v[152:155], v[96:99]
	v_mfma_f32_16x16x32_bf16 v[84:87], v[176:179], v[160:163], v[84:87]
	v_mfma_f32_16x16x32_bf16 v[80:83], v[184:187], v[160:163], v[80:83]
	v_mfma_f32_16x16x32_bf16 v[68:71], v[176:179], v[168:171], v[68:71]
	v_mfma_f32_16x16x32_bf16 v[64:67], v[184:187], v[168:171], v[64:67]
	v_mfma_f32_16x16x32_bf16 v[116:119], v[180:183], v[148:151], v[116:119]
	v_mfma_f32_16x16x32_bf16 v[112:115], v[188:191], v[148:151], v[112:115]
	v_mfma_f32_16x16x32_bf16 v[100:103], v[180:183], v[156:159], v[100:103]
	v_mfma_f32_16x16x32_bf16 v[96:99], v[188:191], v[156:159], v[96:99]
	v_mfma_f32_16x16x32_bf16 v[84:87], v[180:183], v[164:167], v[84:87]
	v_mfma_f32_16x16x32_bf16 v[80:83], v[188:191], v[164:167], v[80:83]
	v_mfma_f32_16x16x32_bf16 v[68:71], v[180:183], v[172:175], v[68:71]
	v_mfma_f32_16x16x32_bf16 v[64:67], v[188:191], v[172:175], v[64:67]
	s_barrier
	s_setprio 0
	s_mov_b32 m0, s38
	v_lshl_add_u64 v[196:197], s[30:31], 0, v[202:203]
	ds_read_b128 v[144:147], v238 offset:16384
	ds_read_b128 v[148:151], v238 offset:17408
	ds_read_b128 v[152:155], v238 offset:18432
	ds_read_b128 v[156:159], v238 offset:19456
	ds_read_b128 v[160:163], v238 offset:20480
	ds_read_b128 v[164:167], v238 offset:21504
	ds_read_b128 v[168:171], v238 offset:22528
	ds_read_b128 v[172:175], v238 offset:23552
	global_load_lds_dwordx4 v202, s[30:31]
	v_lshl_add_u64 v[198:199], s[30:31], 0, v[206:207]
	s_mov_b32 m0, s39
	s_nop 0
	global_load_lds_dwordx4 v206, s[30:31]
	s_setprio 1
	s_barrier
	s_waitcnt lgkmcnt(0)
	v_mfma_f32_16x16x32_bf16 v[60:63], v[128:131], v[144:147], v[60:63]
	v_mfma_f32_16x16x32_bf16 v[56:59], v[136:139], v[144:147], v[56:59]
	v_mfma_f32_16x16x32_bf16 v[44:47], v[128:131], v[152:155], v[44:47]
	v_mfma_f32_16x16x32_bf16 v[40:43], v[136:139], v[152:155], v[40:43]
	v_mfma_f32_16x16x32_bf16 v[28:31], v[128:131], v[160:163], v[28:31]
	v_mfma_f32_16x16x32_bf16 v[24:27], v[136:139], v[160:163], v[24:27]
	v_mfma_f32_16x16x32_bf16 v[12:15], v[128:131], v[168:171], v[12:15]
	v_mfma_f32_16x16x32_bf16 v[8:11], v[136:139], v[168:171], v[8:11]
	v_mfma_f32_16x16x32_bf16 v[60:63], v[132:135], v[148:151], v[60:63]
	v_mfma_f32_16x16x32_bf16 v[56:59], v[140:143], v[148:151], v[56:59]
	v_mfma_f32_16x16x32_bf16 v[44:47], v[132:135], v[156:159], v[44:47]
	v_mfma_f32_16x16x32_bf16 v[40:43], v[140:143], v[156:159], v[40:43]
	v_mfma_f32_16x16x32_bf16 v[28:31], v[132:135], v[164:167], v[28:31]
	v_mfma_f32_16x16x32_bf16 v[24:27], v[140:143], v[164:167], v[24:27]
	v_mfma_f32_16x16x32_bf16 v[12:15], v[132:135], v[172:175], v[12:15]
	v_mfma_f32_16x16x32_bf16 v[8:11], v[140:143], v[172:175], v[8:11]
	s_barrier
	s_setprio 0
	s_add_u32 s24, s28, 0x60000
	s_addc_u32 s25, s29, 0
	s_add_i32 s59, s51, s37
	s_mov_b32 m0, s59
	s_nop 0
	global_load_lds_dwordx4 v204, s[24:25]
	s_add_i32 m0, s59, 0x2000
	s_nop 0
	global_load_lds_dwordx4 v208, s[24:25]
	s_add_u32 s24, s30, 0x60000
	s_addc_u32 s25, s31, 0
	s_mov_b32 m0, s40
	s_nop 0
	global_load_lds_dwordx4 v202, s[24:25]
	s_mov_b32 m0, s41
	s_nop 0
	global_load_lds_dwordx4 v206, s[24:25]
	s_waitcnt vmcnt(10)
	s_setprio 1
	s_barrier
	v_mfma_f32_16x16x32_bf16 v[52:55], v[176:179], v[144:147], v[52:55]
	v_mfma_f32_16x16x32_bf16 v[48:51], v[184:187], v[144:147], v[48:51]
	v_mfma_f32_16x16x32_bf16 v[36:39], v[176:179], v[152:155], v[36:39]
	v_mfma_f32_16x16x32_bf16 v[32:35], v[184:187], v[152:155], v[32:35]
	v_mfma_f32_16x16x32_bf16 v[20:23], v[176:179], v[160:163], v[20:23]
	v_mfma_f32_16x16x32_bf16 v[16:19], v[184:187], v[160:163], v[16:19]
	v_mfma_f32_16x16x32_bf16 v[4:7], v[176:179], v[168:171], v[4:7]
	v_mfma_f32_16x16x32_bf16 v[0:3], v[184:187], v[168:171], v[0:3]
	v_mfma_f32_16x16x32_bf16 v[52:55], v[180:183], v[148:151], v[52:55]
	v_mfma_f32_16x16x32_bf16 v[48:51], v[188:191], v[148:151], v[48:51]
	v_mfma_f32_16x16x32_bf16 v[36:39], v[180:183], v[156:159], v[36:39]
	v_mfma_f32_16x16x32_bf16 v[32:35], v[188:191], v[156:159], v[32:35]
	v_mfma_f32_16x16x32_bf16 v[20:23], v[180:183], v[164:167], v[20:23]
	v_mfma_f32_16x16x32_bf16 v[16:19], v[188:191], v[164:167], v[16:19]
	v_mfma_f32_16x16x32_bf16 v[4:7], v[180:183], v[172:175], v[4:7]
	v_mfma_f32_16x16x32_bf16 v[0:3], v[188:191], v[172:175], v[0:3]
	s_barrier
	s_setprio 0
	s_add_i32 s59, 0, 0x18000
	ds_read_b128 v[128:131], v239 offset:16384
	ds_read_b128 v[132:135], v239 offset:17408
	ds_read_b128 v[136:139], v239 offset:18432
	ds_read_b128 v[140:143], v239 offset:19456
	ds_read_b128 v[144:147], v238 offset:32768
	ds_read_b128 v[148:151], v238 offset:33792
	ds_read_b128 v[152:155], v238 offset:34816
	ds_read_b128 v[156:159], v238 offset:35840
	ds_read_b128 v[160:163], v238 offset:36864
	ds_read_b128 v[164:167], v238 offset:37888
	ds_read_b128 v[168:171], v238 offset:38912
	ds_read_b128 v[172:175], v238 offset:39936
	s_waitcnt lgkmcnt(8)
	s_waitcnt vmcnt(8)
	s_setprio 1
	s_barrier
; #define PG8_STAGE(bufoff, gbase, voff) do { _Pragma("unroll") for (int _i = 0; _i < 2; ++_i) \
;         __builtin_amdgcn_global_load_lds((const unsigned*)((const char*)(gbase) + (voff)[_i]), (LAS unsigned*)(lds + (bufoff) + ldsw + _i * 8192), 16, 0, 0); } while (0)
; #define PG8_LDA(dst, b, h) do { _Pragma("unroll") for (int m = 0; m < 4; ++m) _Pragma("unroll") for (int k = 0; k < 2; ++k) dst[m][k] = *(const LAS bf16x8*)(lds + PG8_SA(b, h) + aoff + m * 2048 + k * 1024); } while (0)
; #define PG8_MMA(ai, bj, At, Bt) do { __builtin_amdgcn_s_setprio(1); _Pragma("unroll") for (int m = 0; m < 4; ++m) _Pragma("unroll") for (int n = 0; n < 2; ++n) _Pragma("unroll") for (int k = 0; k < 2; ++k) \
;         acc[ai][bj][m][n] = __builtin_amdgcn_mfma_f32_16x16x32_bf16(Bt[n][k], At[m][k], acc[ai][bj][m][n], 0, 0, 0); __builtin_amdgcn_s_setprio(0); } while (0)
; #define PG8_WAIT_V(n) asm volatile("s_waitcnt vmcnt(" #n ")" ::: "memory")
; #define PG8_WAIT_L(n) asm volatile("s_waitcnt lgkmcnt(" #n ")" ::: "memory")
; #define PG8_BAR __builtin_amdgcn_s_barrier()
; #define PG8_SCHED __builtin_amdgcn_sched_barrier(0)
; template <class Epi, class Sched>
; __device__ __forceinline__ void gemm_phase(LAS unsigned char* lds, const Gemm g, const Sched& S, const Epi& E) {
;     ...
;             PG8_LDA(At, 1, 1); PG8_STAGE(PG8_SA(1, 0), a3, voffA);
;             PG8_BAR; PG8_WAIT_L(0); PG8_MMA(1, 0, At, B0); PG8_BAR; PG8_SCHED;
;             PG8_STAGE(PG8_SB(1, 1), b3 + hstep, voffB);
;             PG8_WAIT_V(6); PG8_BAR; PG8_MMA(1, 1, At, B1); PG8_BAR;
	s_waitcnt lgkmcnt(0)
	v_mfma_f32_16x16x32_bf16 v[124:127], v[128:131], v[144:147], v[124:127]
	v_mfma_f32_16x16x32_bf16 v[120:123], v[136:139], v[144:147], v[120:123]
	v_mfma_f32_16x16x32_bf16 v[108:111], v[128:131], v[152:155], v[108:111]
	v_mfma_f32_16x16x32_bf16 v[104:107], v[136:139], v[152:155], v[104:107]
	v_mfma_f32_16x16x32_bf16 v[92:95], v[128:131], v[160:163], v[92:95]
	v_mfma_f32_16x16x32_bf16 v[88:91], v[136:139], v[160:163], v[88:91]
	v_mfma_f32_16x16x32_bf16 v[76:79], v[128:131], v[168:171], v[76:79]
	v_mfma_f32_16x16x32_bf16 v[72:75], v[136:139], v[168:171], v[72:75]
	v_mfma_f32_16x16x32_bf16 v[124:127], v[132:135], v[148:151], v[124:127]
	v_mfma_f32_16x16x32_bf16 v[120:123], v[140:143], v[148:151], v[120:123]
	v_mfma_f32_16x16x32_bf16 v[108:111], v[132:135], v[156:159], v[108:111]
	v_mfma_f32_16x16x32_bf16 v[104:107], v[140:143], v[156:159], v[104:107]
	v_mfma_f32_16x16x32_bf16 v[92:95], v[132:135], v[164:167], v[92:95]
	v_mfma_f32_16x16x32_bf16 v[88:91], v[140:143], v[164:167], v[88:91]
	v_mfma_f32_16x16x32_bf16 v[76:79], v[132:135], v[172:175], v[76:79]
	v_mfma_f32_16x16x32_bf16 v[72:75], v[140:143], v[172:175], v[72:75]
	s_barrier
	s_setprio 0
	s_add_i32 s30, 0, 0x1c000
	s_add_i32 s24, s59, s37
	v_add_u32_e32 v188, s30, v236
	s_add_u32 s0, s28, 0x80
	s_addc_u32 s1, s29, 0
	s_mov_b32 m0, s24
	ds_read_b128 v[176:179], v188
	ds_read_b128 v[180:183], v188 offset:1024
	ds_read_b128 v[184:187], v188 offset:2048
	ds_read_b128 v[188:191], v188 offset:3072
	global_load_lds_dwordx4 v204, s[0:1]
	s_add_i32 m0, s24, 0x2000
	s_nop 0
	global_load_lds_dwordx4 v208, s[0:1]
	s_waitcnt vmcnt(8)
	s_setprio 1
	s_barrier
	s_waitcnt lgkmcnt(0)
	v_mfma_f32_16x16x32_bf16 v[116:119], v[176:179], v[144:147], v[116:119]
	v_mfma_f32_16x16x32_bf16 v[112:115], v[184:187], v[144:147], v[112:115]
	v_mfma_f32_16x16x32_bf16 v[100:103], v[176:179], v[152:155], v[100:103]
	v_mfma_f32_16x16x32_bf16 v[96:99], v[184:187], v[152:155], v[96:99]
	v_mfma_f32_16x16x32_bf16 v[84:87], v[176:179], v[160:163], v[84:87]
	v_mfma_f32_16x16x32_bf16 v[80:83], v[184:187], v[160:163], v[80:83]
	v_mfma_f32_16x16x32_bf16 v[68:71], v[176:179], v[168:171], v[68:71]
	v_mfma_f32_16x16x32_bf16 v[64:67], v[184:187], v[168:171], v[64:67]
	v_mfma_f32_16x16x32_bf16 v[116:119], v[180:183], v[148:151], v[116:119]
	v_mfma_f32_16x16x32_bf16 v[112:115], v[188:191], v[148:151], v[112:115]
	v_mfma_f32_16x16x32_bf16 v[100:103], v[180:183], v[156:159], v[100:103]
	v_mfma_f32_16x16x32_bf16 v[96:99], v[188:191], v[156:159], v[96:99]
	v_mfma_f32_16x16x32_bf16 v[84:87], v[180:183], v[164:167], v[84:87]
	v_mfma_f32_16x16x32_bf16 v[80:83], v[188:191], v[164:167], v[80:83]
	v_mfma_f32_16x16x32_bf16 v[68:71], v[180:183], v[172:175], v[68:71]
	v_mfma_f32_16x16x32_bf16 v[64:67], v[188:191], v[172:175], v[64:67]
	s_barrier
	s_setprio 0
	s_mov_b32 m0, s47
	s_mov_b64 s[0:1], 0x80
	v_lshl_add_u64 v[192:193], v[196:197], 0, s[0:1]
	ds_read_b128 v[144:147], v238 offset:49152
	ds_read_b128 v[148:151], v238 offset:50176
	ds_read_b128 v[152:155], v238 offset:51200
	ds_read_b128 v[156:159], v238 offset:52224
	ds_read_b128 v[160:163], v238 offset:53248
	ds_read_b128 v[164:167], v238 offset:54272
	ds_read_b128 v[168:171], v238 offset:55296
	ds_read_b128 v[172:175], v238 offset:56320
	global_load_lds_dwordx4 v[192:193], off
	v_lshl_add_u64 v[192:193], v[198:199], 0, s[0:1]
	s_mov_b32 m0, s48
	s_nop 0
	global_load_lds_dwordx4 v[192:193], off
	s_setprio 1
	s_barrier
	s_waitcnt lgkmcnt(0)
	v_mfma_f32_16x16x32_bf16 v[60:63], v[128:131], v[144:147], v[60:63]
	v_mfma_f32_16x16x32_bf16 v[56:59], v[136:139], v[144:147], v[56:59]
	v_mfma_f32_16x16x32_bf16 v[44:47], v[128:131], v[152:155], v[44:47]
	v_mfma_f32_16x16x32_bf16 v[40:43], v[136:139], v[152:155], v[40:43]
	v_mfma_f32_16x16x32_bf16 v[28:31], v[128:131], v[160:163], v[28:31]
	v_mfma_f32_16x16x32_bf16 v[24:27], v[136:139], v[160:163], v[24:27]
	v_mfma_f32_16x16x32_bf16 v[12:15], v[128:131], v[168:171], v[12:15]
	v_mfma_f32_16x16x32_bf16 v[8:11], v[136:139], v[168:171], v[8:11]
	v_mfma_f32_16x16x32_bf16 v[60:63], v[132:135], v[148:151], v[60:63]
	v_mfma_f32_16x16x32_bf16 v[56:59], v[140:143], v[148:151], v[56:59]
	v_mfma_f32_16x16x32_bf16 v[44:47], v[132:135], v[156:159], v[44:47]
	v_mfma_f32_16x16x32_bf16 v[40:43], v[140:143], v[156:159], v[40:43]
	v_mfma_f32_16x16x32_bf16 v[28:31], v[132:135], v[164:167], v[28:31]
	v_mfma_f32_16x16x32_bf16 v[24:27], v[140:143], v[164:167], v[24:27]
	v_mfma_f32_16x16x32_bf16 v[12:15], v[132:135], v[172:175], v[12:15]
	v_mfma_f32_16x16x32_bf16 v[8:11], v[140:143], v[172:175], v[8:11]
	s_barrier
	s_setprio 0
	s_add_u32 s24, s28, 0x60080
	s_addc_u32 s25, s29, 0
	s_add_i32 s28, s30, s37
	s_mov_b32 m0, s28
	s_nop 0
	global_load_lds_dwordx4 v204, s[24:25]
	s_add_i32 m0, s28, 0x2000
	s_nop 0
	global_load_lds_dwordx4 v208, s[24:25]
	s_waitcnt vmcnt(8)
	s_setprio 1
	s_barrier
	v_mfma_f32_16x16x32_bf16 v[52:55], v[176:179], v[144:147], v[52:55]
	v_mfma_f32_16x16x32_bf16 v[48:51], v[184:187], v[144:147], v[48:51]
	v_mfma_f32_16x16x32_bf16 v[36:39], v[176:179], v[152:155], v[36:39]
	v_mfma_f32_16x16x32_bf16 v[32:35], v[184:187], v[152:155], v[32:35]
	v_mfma_f32_16x16x32_bf16 v[20:23], v[176:179], v[160:163], v[20:23]
	v_mfma_f32_16x16x32_bf16 v[16:19], v[184:187], v[160:163], v[16:19]
	v_mfma_f32_16x16x32_bf16 v[4:7], v[176:179], v[168:171], v[4:7]
	v_mfma_f32_16x16x32_bf16 v[0:3], v[184:187], v[168:171], v[0:3]
	v_mfma_f32_16x16x32_bf16 v[52:55], v[180:183], v[148:151], v[52:55]
	v_mfma_f32_16x16x32_bf16 v[48:51], v[188:191], v[148:151], v[48:51]
	v_mfma_f32_16x16x32_bf16 v[36:39], v[180:183], v[156:159], v[36:39]
	v_mfma_f32_16x16x32_bf16 v[32:35], v[188:191], v[156:159], v[32:35]
	v_mfma_f32_16x16x32_bf16 v[20:23], v[180:183], v[164:167], v[20:23]
	v_mfma_f32_16x16x32_bf16 v[16:19], v[188:191], v[164:167], v[16:19]
	v_mfma_f32_16x16x32_bf16 v[4:7], v[180:183], v[172:175], v[4:7]
	v_mfma_f32_16x16x32_bf16 v[0:3], v[188:191], v[172:175], v[0:3]
	s_barrier
; __device__ __forceinline__ unsigned cvt_pk_bf16(float lo, float hi) { unsigned r; asm volatile("v_cvt_pk_bf16_f32 %0, %1, %2" : "=v"(r) : "v"(lo), "v"(hi)); return r; }
; __device__ __forceinline__ float bf_lo(unsigned u) { return __uint_as_float(u << 16); }
; __device__ __forceinline__ float bf_hi(unsigned u) { return __uint_as_float(u & 0xffff0000u); }
;     __device__ __forceinline__ void operator()(const AccT& acc, const Unit& u, int wr, int wc, int fr, int fq) const {
;         asm volatile("" : "+v"(fr), "+v"(fq));
;         const int rowt = u.pm * 256; const int b = rowt >> 11;
;         const bf16_t* res = res_b + (size_t)rowt * DM; bf16_t* out = hb + (size_t)rowt * DM;
;         const int col0 = u.pn * 256 + wc * 32 + 8 * fq;
;         f32x4 gv[2][2];
; #pragma unroll
;         for (int bj = 0; bj < 2; ++bj)
; #pragma unroll
;             for (int n = 0; n < 2; ++n) gv[bj][n] = *(const f32x4*)(gate + (size_t)b * NMOD + col0 + bj * 128 + n * 4) * gs;
;         u32x4 r[2][4][2];
; #pragma unroll
;         for (int ai = 0; ai < 2; ++ai)
; #pragma unroll
;             for (int m = 0; m < 4; ++m)
; #pragma unroll
;                 for (int bj = 0; bj < 2; ++bj) r[ai][m][bj] = *(const u32x4*)(res + (size_t)(wr * 64 + fr + ai * 128 + m * 16) * DM + col0 + bj * 128);
; #pragma unroll
;         for (int ai = 0; ai < 2; ++ai)
; #pragma unroll
;             for (int m = 0; m < 4; ++m)
; #pragma unroll
;                 for (int bj = 0; bj < 2; ++bj) {
;                     const u32x4 q = r[ai][m][bj];
;                     const f32x4 r0 = {bf_lo(q.x), bf_hi(q.x), bf_lo(q.y), bf_hi(q.y)}, r1 = {bf_lo(q.z), bf_hi(q.z), bf_lo(q.w), bf_hi(q.w)};
;                     const f32x4 h0 = r0 + gv[bj][0] * acc[ai][bj][m][0], h1 = r1 + gv[bj][1] * acc[ai][bj][m][1];
;                     u32x4 w; w.x = cvt_pk_bf16(h0[0], h0[1]); w.y = cvt_pk_bf16(h0[2], h0[3]); w.z = cvt_pk_bf16(h1[0], h1[1]); w.w = cvt_pk_bf16(h1[2], h1[3]);
;                     *(u32x4*)(out + (size_t)(wr * 64 + fr + ai * 128 + m * 16) * DM + col0 + bj * 128) = w;
	s_setprio 0
	s_add_i32 s58, s58, 2
	s_add_u32 s56, s56, 0x100
	s_addc_u32 s57, s57, 0
	s_cmp_gt_u32 s58, 21
	s_mov_b64 s[24:25], s[26:27]
	s_cbranch_scc0 .LBB0_902
	s_lshl_b32 s27, s55, 8
	v_mov_b32_e32 v146, v235
	v_mov_b32_e32 v128, v234
	s_lshl_b32 s24, s54, 8
	s_ashr_i32 s26, s54, 3
	s_or_b32 s27, s27, s46
	s_ashr_i32 s25, s24, 31
	v_lshl_add_u32 v144, v128, 3, s27
	s_mul_hi_i32 s27, s26, 0x9000
	s_mul_i32 s26, s26, 0x9000
	s_add_u32 s26, s43, s26
	s_addc_u32 s27, s44, s27
	v_ashrrev_i32_e32 v145, 31, v144
	s_lshl_b64 s[24:25], s[24:25], 11
	v_lshl_add_u64 v[132:133], v[144:145], 2, s[26:27]
	s_add_u32 s26, s62, s24
	v_add_u32_e32 v146, s45, v146
	s_addc_u32 s27, s63, s25
	v_lshlrev_b64 v[222:223], 1, v[144:145]
	v_ashrrev_i32_e32 v147, 31, v146
	v_lshl_add_u64 v[144:145], s[26:27], 0, v[222:223]
	v_lshlrev_b64 v[248:249], 11, v[146:147]
	v_lshl_add_u64 v[146:147], v[144:145], 0, v[248:249]
	global_load_dwordx4 v[136:139], v[132:133], off offset:16
	global_load_dwordx4 v[140:143], v[132:133], off
	global_load_dwordx4 v[128:131], v[132:133], off offset:528
	s_nop 0
	global_load_dwordx4 v[132:135], v[132:133], off offset:512
	s_nop 0
	global_load_dwordx4 v[240:243], v[146:147], off
	global_load_dwordx4 v[244:247], v[146:147], off offset:256
	v_lshl_add_u64 v[232:233], v[248:249], 0, s[10:11]
	v_lshl_add_u64 v[146:147], v[144:145], 0, v[232:233]
	global_load_dwordx4 v[196:199], v[146:147], off
	global_load_dwordx4 v[192:195], v[146:147], off offset:256
	v_lshl_add_u64 v[230:231], v[248:249], 0, s[12:13]
	v_lshl_add_u64 v[146:147], v[144:145], 0, v[230:231]
	global_load_dwordx4 v[188:191], v[146:147], off
	global_load_dwordx4 v[184:187], v[146:147], off offset:256
	v_lshl_add_u64 v[228:229], v[248:249], 0, s[14:15]
	v_lshl_add_u64 v[146:147], v[144:145], 0, v[228:229]
	global_load_dwordx4 v[180:183], v[146:147], off
	global_load_dwordx4 v[176:179], v[146:147], off offset:256
	v_lshl_add_u64 v[226:227], v[248:249], 0, s[16:17]
	v_lshl_add_u64 v[146:147], v[144:145], 0, v[226:227]
	global_load_dwordx4 v[172:175], v[146:147], off
	global_load_dwordx4 v[168:171], v[146:147], off offset:256
	v_lshl_add_u64 v[224:225], v[248:249], 0, s[18:19]
	v_lshl_add_u64 v[146:147], v[144:145], 0, v[224:225]
	global_load_dwordx4 v[164:167], v[146:147], off
	global_load_dwordx4 v[160:163], v[146:147], off offset:256
	v_lshl_add_u64 v[220:221], v[248:249], 0, s[20:21]
	v_lshl_add_u64 v[146:147], v[144:145], 0, v[220:221]
	global_load_dwordx4 v[156:159], v[146:147], off
	global_load_dwordx4 v[152:155], v[146:147], off offset:256
	v_lshl_add_u64 v[218:219], v[248:249], 0, s[22:23]
	v_lshl_add_u64 v[144:145], v[144:145], 0, v[218:219]
	global_load_dwordx4 v[148:151], v[144:145], off
	s_nop 0
	global_load_dwordx4 v[144:147], v[144:145], off offset:256
	s_add_u32 s24, s80, s24
	s_addc_u32 s25, s81, s25
	v_lshl_add_u64 v[222:223], s[24:25], 0, v[222:223]
	v_lshl_add_u64 v[248:249], v[222:223], 0, v[248:249]
	s_and_b64 vcc, exec, s[2:3]
	s_mov_b32 s55, s52
	s_mov_b32 s54, s53
	s_mov_b64 s[26:27], s[6:7]
	s_mov_b64 s[24:25], s[4:5]
	s_waitcnt vmcnt(0)
	v_lshlrev_b32_e32 v250, 16, v240
	v_and_b32_e32 v251, 0xffff0000, v240
	v_lshlrev_b32_e32 v240, 16, v241
	v_and_b32_e32 v241, 0xffff0000, v241
	v_lshlrev_b32_e32 v252, 16, v242
	v_and_b32_e32 v253, 0xffff0000, v242
	v_lshlrev_b32_e32 v242, 16, v243
	v_and_b32_e32 v243, 0xffff0000, v243
	v_pk_fma_f32 v[126:127], v[126:127], v[142:143], v[240:241]
	v_pk_fma_f32 v[124:125], v[124:125], v[140:141], v[250:251]
	v_pk_fma_f32 v[240:241], v[122:123], v[138:139], v[242:243]
	v_pk_fma_f32 v[122:123], v[120:121], v[136:137], v[252:253]
	v_cvt_pk_bf16_f32 v120, v124, v125
	v_cvt_pk_bf16_f32 v121, v126, v127
	v_lshlrev_b32_e32 v124, 16, v246
	v_cvt_pk_bf16_f32 v122, v122, v123
	v_cvt_pk_bf16_f32 v123, v240, v241
	global_store_dwordx4 v[248:249], v[120:123], off
	v_and_b32_e32 v125, 0xffff0000, v246
	v_lshlrev_b32_e32 v126, 16, v247
	v_lshlrev_b32_e32 v120, 16, v244
	v_and_b32_e32 v121, 0xffff0000, v244
	v_and_b32_e32 v127, 0xffff0000, v247
	v_lshlrev_b32_e32 v122, 16, v245
	v_and_b32_e32 v123, 0xffff0000, v245
	v_pk_fma_f32 v[116:117], v[116:117], v[132:133], v[120:121]
	v_pk_fma_f32 v[120:121], v[114:115], v[130:131], v[126:127]
	v_pk_fma_f32 v[114:115], v[112:113], v[128:129], v[124:125]
	v_pk_fma_f32 v[118:119], v[118:119], v[134:135], v[122:123]
	v_cvt_pk_bf16_f32 v112, v116, v117
	v_lshlrev_b32_e32 v116, 16, v197
	v_cvt_pk_bf16_f32 v113, v118, v119
	v_cvt_pk_bf16_f32 v114, v114, v115
	v_cvt_pk_bf16_f32 v115, v120, v121
	global_store_dwordx4 v[248:249], v[112:115], off offset:256
	v_and_b32_e32 v117, 0xffff0000, v197
	v_lshlrev_b32_e32 v118, 16, v198
	v_lshlrev_b32_e32 v114, 16, v196
	v_and_b32_e32 v115, 0xffff0000, v196
	v_and_b32_e32 v119, 0xffff0000, v198
	v_lshlrev_b32_e32 v120, 16, v199
	v_and_b32_e32 v121, 0xffff0000, v199
	v_lshl_add_u64 v[112:113], v[222:223], 0, v[232:233]
	v_pk_fma_f32 v[110:111], v[110:111], v[142:143], v[116:117]
	v_pk_fma_f32 v[108:109], v[108:109], v[140:141], v[114:115]
	v_pk_fma_f32 v[114:115], v[106:107], v[138:139], v[120:121]
	v_pk_fma_f32 v[106:107], v[104:105], v[136:137], v[118:119]
	v_cvt_pk_bf16_f32 v104, v108, v109
	v_cvt_pk_bf16_f32 v105, v110, v111
	v_lshlrev_b32_e32 v108, 16, v194
	v_cvt_pk_bf16_f32 v106, v106, v107
	v_cvt_pk_bf16_f32 v107, v114, v115
	global_store_dwordx4 v[112:113], v[104:107], off
	v_and_b32_e32 v109, 0xffff0000, v194
	v_lshlrev_b32_e32 v110, 16, v195
	v_lshlrev_b32_e32 v104, 16, v192
	v_and_b32_e32 v105, 0xffff0000, v192
	v_and_b32_e32 v111, 0xffff0000, v195
	v_lshlrev_b32_e32 v106, 16, v193
	v_and_b32_e32 v107, 0xffff0000, v193
; __device__ __forceinline__ unsigned cvt_pk_bf16(float lo, float hi) { unsigned r; asm volatile("v_cvt_pk_bf16_f32 %0, %1, %2" : "=v"(r) : "v"(lo), "v"(hi)); return r; }
; __device__ __forceinline__ float bf_lo(unsigned u) { return __uint_as_float(u << 16); }
; __device__ __forceinline__ float bf_hi(unsigned u) { return __uint_as_float(u & 0xffff0000u); }
;     __device__ __forceinline__ void operator()(const AccT& acc, const Unit& u, int wr, int wc, int fr, int fq) const {
;     ...
;         for (int ai = 0; ai < 2; ++ai)
; #pragma unroll
;             for (int m = 0; m < 4; ++m)
; #pragma unroll
;                 for (int bj = 0; bj < 2; ++bj) {
;                     const u32x4 q = r[ai][m][bj];
;                     const f32x4 r0 = {bf_lo(q.x), bf_hi(q.x), bf_lo(q.y), bf_hi(q.y)}, r1 = {bf_lo(q.z), bf_hi(q.z), bf_lo(q.w), bf_hi(q.w)};
;                     const f32x4 h0 = r0 + gv[bj][0] * acc[ai][bj][m][0], h1 = r1 + gv[bj][1] * acc[ai][bj][m][1];
;                     u32x4 w; w.x = cvt_pk_bf16(h0[0], h0[1]); w.y = cvt_pk_bf16(h0[2], h0[3]); w.z = cvt_pk_bf16(h1[0], h1[1]); w.w = cvt_pk_bf16(h1[2], h1[3]);
;                     *(u32x4*)(out + (size_t)(wr * 64 + fr + ai * 128 + m * 16) * DM + col0 + bj * 128) = w;
	v_pk_fma_f32 v[100:101], v[100:101], v[132:133], v[104:105]
	v_pk_fma_f32 v[104:105], v[98:99], v[130:131], v[110:111]
	v_pk_fma_f32 v[98:99], v[96:97], v[128:129], v[108:109]
	v_pk_fma_f32 v[102:103], v[102:103], v[134:135], v[106:107]
	v_cvt_pk_bf16_f32 v96, v100, v101
	v_lshlrev_b32_e32 v100, 16, v189
	v_cvt_pk_bf16_f32 v97, v102, v103
	v_cvt_pk_bf16_f32 v98, v98, v99
	v_cvt_pk_bf16_f32 v99, v104, v105
	global_store_dwordx4 v[112:113], v[96:99], off offset:256
	v_and_b32_e32 v101, 0xffff0000, v189
	v_lshlrev_b32_e32 v102, 16, v190
	v_lshlrev_b32_e32 v98, 16, v188
	v_and_b32_e32 v99, 0xffff0000, v188
	v_and_b32_e32 v103, 0xffff0000, v190
	v_lshlrev_b32_e32 v104, 16, v191
	v_and_b32_e32 v105, 0xffff0000, v191
	v_lshl_add_u64 v[96:97], v[222:223], 0, v[230:231]
	v_pk_fma_f32 v[94:95], v[94:95], v[142:143], v[100:101]
	v_pk_fma_f32 v[92:93], v[92:93], v[140:141], v[98:99]
	v_pk_fma_f32 v[98:99], v[90:91], v[138:139], v[104:105]
	v_pk_fma_f32 v[90:91], v[88:89], v[136:137], v[102:103]
	v_cvt_pk_bf16_f32 v88, v92, v93
	v_cvt_pk_bf16_f32 v89, v94, v95
	v_lshlrev_b32_e32 v92, 16, v186
	v_cvt_pk_bf16_f32 v90, v90, v91
	v_cvt_pk_bf16_f32 v91, v98, v99
	global_store_dwordx4 v[96:97], v[88:91], off
	v_and_b32_e32 v93, 0xffff0000, v186
	v_lshlrev_b32_e32 v94, 16, v187
	v_lshlrev_b32_e32 v88, 16, v184
	v_and_b32_e32 v89, 0xffff0000, v184
	v_and_b32_e32 v95, 0xffff0000, v187
	v_lshlrev_b32_e32 v90, 16, v185
	v_and_b32_e32 v91, 0xffff0000, v185
	v_pk_fma_f32 v[84:85], v[84:85], v[132:133], v[88:89]
	v_pk_fma_f32 v[88:89], v[82:83], v[130:131], v[94:95]
	v_pk_fma_f32 v[82:83], v[80:81], v[128:129], v[92:93]
	v_pk_fma_f32 v[86:87], v[86:87], v[134:135], v[90:91]
	v_cvt_pk_bf16_f32 v80, v84, v85
	v_lshlrev_b32_e32 v84, 16, v181
	v_cvt_pk_bf16_f32 v81, v86, v87
	v_cvt_pk_bf16_f32 v82, v82, v83
	v_cvt_pk_bf16_f32 v83, v88, v89
	global_store_dwordx4 v[96:97], v[80:83], off offset:256
	v_and_b32_e32 v85, 0xffff0000, v181
	v_lshlrev_b32_e32 v86, 16, v182
	v_lshlrev_b32_e32 v82, 16, v180
	v_and_b32_e32 v83, 0xffff0000, v180
	v_and_b32_e32 v87, 0xffff0000, v182
	v_lshlrev_b32_e32 v88, 16, v183
	v_and_b32_e32 v89, 0xffff0000, v183
	v_lshl_add_u64 v[80:81], v[222:223], 0, v[228:229]
	v_pk_fma_f32 v[78:79], v[78:79], v[142:143], v[84:85]
	v_pk_fma_f32 v[76:77], v[76:77], v[140:141], v[82:83]
	v_pk_fma_f32 v[82:83], v[74:75], v[138:139], v[88:89]
	v_pk_fma_f32 v[74:75], v[72:73], v[136:137], v[86:87]
	v_cvt_pk_bf16_f32 v72, v76, v77
	v_cvt_pk_bf16_f32 v73, v78, v79
	v_lshlrev_b32_e32 v76, 16, v178
	v_cvt_pk_bf16_f32 v74, v74, v75
	v_cvt_pk_bf16_f32 v75, v82, v83
	global_store_dwordx4 v[80:81], v[72:75], off
	v_and_b32_e32 v77, 0xffff0000, v178
	v_lshlrev_b32_e32 v78, 16, v179
	v_lshlrev_b32_e32 v72, 16, v176
	v_and_b32_e32 v73, 0xffff0000, v176
	v_and_b32_e32 v79, 0xffff0000, v179
	v_lshlrev_b32_e32 v74, 16, v177
	v_and_b32_e32 v75, 0xffff0000, v177
	v_pk_fma_f32 v[68:69], v[68:69], v[132:133], v[72:73]
	v_pk_fma_f32 v[72:73], v[66:67], v[130:131], v[78:79]
	v_pk_fma_f32 v[66:67], v[64:65], v[128:129], v[76:77]
	v_pk_fma_f32 v[70:71], v[70:71], v[134:135], v[74:75]
	v_cvt_pk_bf16_f32 v64, v68, v69
	v_lshlrev_b32_e32 v68, 16, v173
	v_cvt_pk_bf16_f32 v65, v70, v71
	v_cvt_pk_bf16_f32 v66, v66, v67
	v_cvt_pk_bf16_f32 v67, v72, v73
	global_store_dwordx4 v[80:81], v[64:67], off offset:256
	v_and_b32_e32 v69, 0xffff0000, v173
	v_lshlrev_b32_e32 v70, 16, v174
	v_lshlrev_b32_e32 v66, 16, v172
	v_and_b32_e32 v67, 0xffff0000, v172
	v_and_b32_e32 v71, 0xffff0000, v174
	v_lshlrev_b32_e32 v72, 16, v175
	v_and_b32_e32 v73, 0xffff0000, v175
	v_lshl_add_u64 v[64:65], v[222:223], 0, v[226:227]
	v_pk_fma_f32 v[62:63], v[62:63], v[142:143], v[68:69]
	v_pk_fma_f32 v[60:61], v[60:61], v[140:141], v[66:67]
	v_pk_fma_f32 v[66:67], v[58:59], v[138:139], v[72:73]
	v_pk_fma_f32 v[58:59], v[56:57], v[136:137], v[70:71]
	v_cvt_pk_bf16_f32 v56, v60, v61
	v_cvt_pk_bf16_f32 v57, v62, v63
	v_lshlrev_b32_e32 v60, 16, v170
	v_cvt_pk_bf16_f32 v58, v58, v59
	v_cvt_pk_bf16_f32 v59, v66, v67
	global_store_dwordx4 v[64:65], v[56:59], off
	v_and_b32_e32 v61, 0xffff0000, v170
	v_lshlrev_b32_e32 v62, 16, v171
	v_lshlrev_b32_e32 v56, 16, v168
	v_and_b32_e32 v57, 0xffff0000, v168
	v_and_b32_e32 v63, 0xffff0000, v171
	v_lshlrev_b32_e32 v58, 16, v169
	v_and_b32_e32 v59, 0xffff0000, v169
	v_pk_fma_f32 v[52:53], v[52:53], v[132:133], v[56:57]
	v_pk_fma_f32 v[56:57], v[50:51], v[130:131], v[62:63]
	v_pk_fma_f32 v[50:51], v[48:49], v[128:129], v[60:61]
	v_pk_fma_f32 v[54:55], v[54:55], v[134:135], v[58:59]
; __device__ __forceinline__ unsigned cvt_pk_bf16(float lo, float hi) { unsigned r; asm volatile("v_cvt_pk_bf16_f32 %0, %1, %2" : "=v"(r) : "v"(lo), "v"(hi)); return r; }
; __device__ __forceinline__ float bf_lo(unsigned u) { return __uint_as_float(u << 16); }
; __device__ __forceinline__ float bf_hi(unsigned u) { return __uint_as_float(u & 0xffff0000u); }
; template <class Epi, class Sched>
; __device__ __forceinline__ void gemm_phase(LAS unsigned char* lds, const Gemm g, const Sched& S, const Epi& E) {
;     ...
;         E(acc, cur, wr, wc, fr, fq);
;         if (!has_next) break;
;     __device__ __forceinline__ void operator()(const AccT& acc, const Unit& u, int wr, int wc, int fr, int fq) const {
;     ...
;         for (int ai = 0; ai < 2; ++ai)
; #pragma unroll
;             for (int m = 0; m < 4; ++m)
; #pragma unroll
;                 for (int bj = 0; bj < 2; ++bj) {
;                     const u32x4 q = r[ai][m][bj];
;                     const f32x4 r0 = {bf_lo(q.x), bf_hi(q.x), bf_lo(q.y), bf_hi(q.y)}, r1 = {bf_lo(q.z), bf_hi(q.z), bf_lo(q.w), bf_hi(q.w)};
;                     const f32x4 h0 = r0 + gv[bj][0] * acc[ai][bj][m][0], h1 = r1 + gv[bj][1] * acc[ai][bj][m][1];
;                     u32x4 w; w.x = cvt_pk_bf16(h0[0], h0[1]); w.y = cvt_pk_bf16(h0[2], h0[3]); w.z = cvt_pk_bf16(h1[0], h1[1]); w.w = cvt_pk_bf16(h1[2], h1[3]);
;                     *(u32x4*)(out + (size_t)(wr * 64 + fr + ai * 128 + m * 16) * DM + col0 + bj * 128) = w;
	v_cvt_pk_bf16_f32 v48, v52, v53
	v_lshlrev_b32_e32 v52, 16, v165
	v_cvt_pk_bf16_f32 v49, v54, v55
	v_cvt_pk_bf16_f32 v50, v50, v51
	v_cvt_pk_bf16_f32 v51, v56, v57
	global_store_dwordx4 v[64:65], v[48:51], off offset:256
	v_and_b32_e32 v53, 0xffff0000, v165
	v_lshlrev_b32_e32 v54, 16, v166
	v_lshlrev_b32_e32 v50, 16, v164
	v_and_b32_e32 v51, 0xffff0000, v164
	v_and_b32_e32 v55, 0xffff0000, v166
	v_lshlrev_b32_e32 v56, 16, v167
	v_and_b32_e32 v57, 0xffff0000, v167
	v_lshl_add_u64 v[48:49], v[222:223], 0, v[224:225]
	v_pk_fma_f32 v[46:47], v[46:47], v[142:143], v[52:53]
	v_pk_fma_f32 v[44:45], v[44:45], v[140:141], v[50:51]
	v_pk_fma_f32 v[50:51], v[42:43], v[138:139], v[56:57]
	v_pk_fma_f32 v[42:43], v[40:41], v[136:137], v[54:55]
	v_cvt_pk_bf16_f32 v40, v44, v45
	v_cvt_pk_bf16_f32 v41, v46, v47
	v_lshlrev_b32_e32 v44, 16, v162
	v_cvt_pk_bf16_f32 v42, v42, v43
	v_cvt_pk_bf16_f32 v43, v50, v51
	global_store_dwordx4 v[48:49], v[40:43], off
	v_and_b32_e32 v45, 0xffff0000, v162
	v_lshlrev_b32_e32 v46, 16, v163
	v_lshlrev_b32_e32 v40, 16, v160
	v_and_b32_e32 v41, 0xffff0000, v160
	v_and_b32_e32 v47, 0xffff0000, v163
	v_lshlrev_b32_e32 v42, 16, v161
	v_and_b32_e32 v43, 0xffff0000, v161
	v_pk_fma_f32 v[36:37], v[36:37], v[132:133], v[40:41]
	v_pk_fma_f32 v[40:41], v[34:35], v[130:131], v[46:47]
	v_pk_fma_f32 v[34:35], v[32:33], v[128:129], v[44:45]
	v_pk_fma_f32 v[38:39], v[38:39], v[134:135], v[42:43]
	v_cvt_pk_bf16_f32 v32, v36, v37
	v_lshlrev_b32_e32 v36, 16, v157
	v_cvt_pk_bf16_f32 v33, v38, v39
	v_cvt_pk_bf16_f32 v34, v34, v35
	v_cvt_pk_bf16_f32 v35, v40, v41
	global_store_dwordx4 v[48:49], v[32:35], off offset:256
	v_and_b32_e32 v37, 0xffff0000, v157
	v_lshlrev_b32_e32 v38, 16, v158
	v_lshlrev_b32_e32 v34, 16, v156
	v_and_b32_e32 v35, 0xffff0000, v156
	v_and_b32_e32 v39, 0xffff0000, v158
	v_lshlrev_b32_e32 v40, 16, v159
	v_and_b32_e32 v41, 0xffff0000, v159
	v_lshl_add_u64 v[32:33], v[222:223], 0, v[220:221]
	v_pk_fma_f32 v[30:31], v[30:31], v[142:143], v[36:37]
	v_pk_fma_f32 v[28:29], v[28:29], v[140:141], v[34:35]
	v_pk_fma_f32 v[34:35], v[26:27], v[138:139], v[40:41]
	v_pk_fma_f32 v[26:27], v[24:25], v[136:137], v[38:39]
	v_cvt_pk_bf16_f32 v24, v28, v29
	v_cvt_pk_bf16_f32 v25, v30, v31
	v_lshlrev_b32_e32 v28, 16, v154
	v_cvt_pk_bf16_f32 v26, v26, v27
	v_cvt_pk_bf16_f32 v27, v34, v35
	global_store_dwordx4 v[32:33], v[24:27], off
	v_and_b32_e32 v29, 0xffff0000, v154
	v_lshlrev_b32_e32 v30, 16, v155
	v_lshlrev_b32_e32 v24, 16, v152
	v_and_b32_e32 v25, 0xffff0000, v152
	v_and_b32_e32 v31, 0xffff0000, v155
	v_lshlrev_b32_e32 v26, 16, v153
	v_and_b32_e32 v27, 0xffff0000, v153
	v_pk_fma_f32 v[20:21], v[20:21], v[132:133], v[24:25]
	v_pk_fma_f32 v[24:25], v[18:19], v[130:131], v[30:31]
	v_pk_fma_f32 v[18:19], v[16:17], v[128:129], v[28:29]
	v_pk_fma_f32 v[22:23], v[22:23], v[134:135], v[26:27]
	v_cvt_pk_bf16_f32 v16, v20, v21
	v_lshlrev_b32_e32 v20, 16, v149
	v_cvt_pk_bf16_f32 v17, v22, v23
	v_cvt_pk_bf16_f32 v18, v18, v19
	v_cvt_pk_bf16_f32 v19, v24, v25
	global_store_dwordx4 v[32:33], v[16:19], off offset:256
	v_and_b32_e32 v21, 0xffff0000, v149
	v_lshlrev_b32_e32 v22, 16, v150
	v_lshlrev_b32_e32 v18, 16, v148
	v_and_b32_e32 v19, 0xffff0000, v148
	v_and_b32_e32 v23, 0xffff0000, v150
	v_lshlrev_b32_e32 v24, 16, v151
	v_and_b32_e32 v25, 0xffff0000, v151
	v_lshl_add_u64 v[16:17], v[222:223], 0, v[218:219]
	v_pk_fma_f32 v[14:15], v[14:15], v[142:143], v[20:21]
	v_pk_fma_f32 v[12:13], v[12:13], v[140:141], v[18:19]
	v_pk_fma_f32 v[18:19], v[10:11], v[138:139], v[24:25]
	v_pk_fma_f32 v[10:11], v[8:9], v[136:137], v[22:23]
	v_cvt_pk_bf16_f32 v8, v12, v13
	v_cvt_pk_bf16_f32 v9, v14, v15
	v_lshlrev_b32_e32 v12, 16, v146
	v_cvt_pk_bf16_f32 v10, v10, v11
	v_cvt_pk_bf16_f32 v11, v18, v19
	global_store_dwordx4 v[16:17], v[8:11], off
	v_and_b32_e32 v13, 0xffff0000, v146
	v_lshlrev_b32_e32 v14, 16, v147
	v_lshlrev_b32_e32 v8, 16, v144
	v_and_b32_e32 v9, 0xffff0000, v144
	v_and_b32_e32 v15, 0xffff0000, v147
	v_lshlrev_b32_e32 v10, 16, v145
	v_and_b32_e32 v11, 0xffff0000, v145
	v_pk_fma_f32 v[4:5], v[4:5], v[132:133], v[8:9]
	v_pk_fma_f32 v[8:9], v[2:3], v[130:131], v[14:15]
	v_pk_fma_f32 v[2:3], v[0:1], v[128:129], v[12:13]
	v_pk_fma_f32 v[6:7], v[6:7], v[134:135], v[10:11]
	v_cvt_pk_bf16_f32 v0, v4, v5
	s_nop 0
	v_cvt_pk_bf16_f32 v1, v6, v7
	v_cvt_pk_bf16_f32 v2, v2, v3
	v_cvt_pk_bf16_f32 v3, v8, v9
	global_store_dwordx4 v[16:17], v[0:3], off offset:256
	s_cbranch_vccz .LBB0_891
	s_waitcnt vmcnt(0)
	s_cmpk_gt_u32 s33, 0xff
	s_cbranch_scc1 .LBB0_906
	s_barrier

; #define PG8_STAGE(bufoff, gbase, voff) do { _Pragma("unroll") for (int _i = 0; _i < 2; ++_i) \
;         __builtin_amdgcn_global_load_lds((const unsigned*)((const char*)(gbase) + (voff)[_i]), (LAS unsigned*)(lds + (bufoff) + ldsw + _i * 8192), 16, 0, 0); } while (0)
; #define PG8_LDA(dst, b, h) do { _Pragma("unroll") for (int m = 0; m < 4; ++m) _Pragma("unroll") for (int k = 0; k < 2; ++k) dst[m][k] = *(const LAS bf16x8*)(lds + PG8_SA(b, h) + aoff + m * 2048 + k * 1024); } while (0)
; #define PG8_LDB(dst, b, h) do { _Pragma("unroll") for (int n = 0; n < 2; ++n) _Pragma("unroll") for (int k = 0; k < 2; ++k) dst[n][k] = *(const LAS bf16x8*)(lds + PG8_SB(b, h) + boff + n * 2048 + k * 1024); } while (0)
; #define PG8_MMA(ai, bj, At, Bt) do { __builtin_amdgcn_s_setprio(1); _Pragma("unroll") for (int m = 0; m < 4; ++m) _Pragma("unroll") for (int n = 0; n < 2; ++n) _Pragma("unroll") for (int k = 0; k < 2; ++k) \
;         acc[ai][bj][m][n] = __builtin_amdgcn_mfma_f32_16x16x32_bf16(Bt[n][k], At[m][k], acc[ai][bj][m][n], 0, 0, 0); __builtin_amdgcn_s_setprio(0); } while (0)
; #define PG8_WAIT_L(n) asm volatile("s_waitcnt lgkmcnt(" #n ")" ::: "memory")
; template <class Epi, class Sched>
; __device__ __forceinline__ void gemm_phase(LAS unsigned char* lds, const Gemm g, const Sched& S, const Epi& E) {
;     ...
;         const bool has_next = S.next(ui + 1, nxt);
;         const char* nA = has_next ? (const char*)g.A + (size_t)nxt.pm * tstep : cA; const char* nB = has_next ? (const char*)g.Bt + (size_t)nxt.pn * tstep : cB;
;         for (int t = 0; t < nt; t += 2) {
;             const bool last = (t == nt - 2);
;             const char* a1 = cA + (size_t)(t + 1) * kstep;
;             const char* a2 = last ? nA : cA + (size_t)(t + 2) * kstep; const char* b2 = last ? nB : cB + (size_t)(t + 2) * kstep;
;             const char* a3 = a2 + kstep; const char* b3 = b2 + kstep;
;             PG8_LDB(B0, 0, 0); PG8_SCHED; PG8_LDA(At, 0, 0); PG8_STAGE(PG8_SA(1, 1), a1 + hstep, voffA);
;             PG8_WAIT_L(8); PG8_BAR; PG8_WAIT_L(0); PG8_MMA(0, 0, At, B0); PG8_BAR; PG8_SCHED;
;             PG8_LDB(B1, 0, 1); PG8_STAGE(PG8_SB(0, 0), b2, voffB);
;             PG8_BAR; PG8_WAIT_L(0); PG8_MMA(0, 1, At, B1); PG8_BAR;
;             PG8_LDA(At, 0, 1); PG8_STAGE(PG8_SA(0, 0), a2, voffA);
;             PG8_BAR; PG8_WAIT_L(0); PG8_MMA(1, 0, At, B0); PG8_BAR; PG8_SCHED;
.LBB0_1020:
	s_ashr_i32 s7, s6, 31
	v_cmp_lt_i64_e32 vcc, s[10:11], v[140:141]
	s_lshl_b64 s[10:11], s[6:7], 19
	s_add_u32 s10, s96, s10
	s_addc_u32 s11, s97, s11
	s_and_b64 s[12:13], vcc, exec
	s_cselect_b32 s7, s11, s17
	s_cselect_b32 s42, s10, s16
	s_ashr_i32 s5, s4, 31
	s_lshl_b64 s[12:13], s[4:5], 19
	s_add_u32 s12, s23, s12
	s_addc_u32 s13, s24, s13
	s_and_b64 s[20:21], vcc, exec
	s_cselect_b32 s5, s13, s19
	s_cselect_b32 s43, s12, s18
	s_add_u32 s16, s16, 0x40080
	s_addc_u32 s17, s17, 0
	s_add_u32 s44, s18, 0x100
	s_addc_u32 s45, s19, 0
	s_mov_b32 s46, -2
	ds_read_b128 v[150:153], v147
	ds_read_b128 v[154:157], v147 offset:1024
	ds_read_b128 v[158:161], v147 offset:2048
	ds_read_b128 v[162:165], v147 offset:3072
	s_add_u32 s18, s16, 0xfffc0080
	s_addc_u32 s19, s17, -1
	s_cmp_eq_u32 s46, 12
	s_cselect_b32 s21, s7, s19
	s_cselect_b32 s20, s42, s18
	s_cselect_b32 s19, s5, s45
	s_cselect_b32 s18, s43, s44
	s_add_i32 m0, s15, 0xc000
	ds_read_b128 v[166:169], v148
	ds_read_b128 v[170:173], v148 offset:1024
	ds_read_b128 v[174:177], v148 offset:2048
	ds_read_b128 v[178:181], v148 offset:3072
	ds_read_b128 v[182:185], v148 offset:4096
	ds_read_b128 v[186:189], v148 offset:5120
	ds_read_b128 v[190:193], v148 offset:6144
	ds_read_b128 v[194:197], v148 offset:7168
	global_load_lds_dwordx4 v136, s[16:17]
	s_add_i32 m0, s15, 0xe000
	s_nop 0
	global_load_lds_dwordx4 v138, s[16:17]
	s_waitcnt lgkmcnt(8)
	s_waitcnt vmcnt(8)
	s_setprio 1
	s_barrier
	s_waitcnt lgkmcnt(0)
	v_mfma_f32_16x16x32_bf16 v[124:127], v[150:153], v[166:169], 0
	v_mfma_f32_16x16x32_bf16 v[116:119], v[158:161], v[166:169], 0
	v_mfma_f32_16x16x32_bf16 v[108:111], v[150:153], v[174:177], 0
	v_mfma_f32_16x16x32_bf16 v[100:103], v[158:161], v[174:177], 0
	v_mfma_f32_16x16x32_bf16 v[92:95], v[150:153], v[182:185], 0
	v_mfma_f32_16x16x32_bf16 v[84:87], v[158:161], v[182:185], 0
	v_mfma_f32_16x16x32_bf16 v[76:79], v[150:153], v[190:193], 0
	v_mfma_f32_16x16x32_bf16 v[68:71], v[158:161], v[190:193], 0
	v_mfma_f32_16x16x32_bf16 v[124:127], v[154:157], v[170:173], v[124:127]
	v_mfma_f32_16x16x32_bf16 v[116:119], v[162:165], v[170:173], v[116:119]
	v_mfma_f32_16x16x32_bf16 v[108:111], v[154:157], v[178:181], v[108:111]
	v_mfma_f32_16x16x32_bf16 v[100:103], v[162:165], v[178:181], v[100:103]
	v_mfma_f32_16x16x32_bf16 v[92:95], v[154:157], v[186:189], v[92:95]
	v_mfma_f32_16x16x32_bf16 v[84:87], v[162:165], v[186:189], v[84:87]
	v_mfma_f32_16x16x32_bf16 v[76:79], v[154:157], v[194:197], v[76:79]
	v_mfma_f32_16x16x32_bf16 v[68:71], v[162:165], v[194:197], v[68:71]
	s_barrier
	s_setprio 0
	s_add_i32 s47, s38, s25
	s_mov_b32 m0, s47
	ds_read_b128 v[202:205], v149
	ds_read_b128 v[206:209], v149 offset:1024
	ds_read_b128 v[210:213], v149 offset:2048
	ds_read_b128 v[214:217], v149 offset:3072
	global_load_lds_dwordx4 v132, s[18:19]
	s_add_i32 m0, s47, 0x2000
	s_nop 0
	global_load_lds_dwordx4 v128, s[18:19]
	s_waitcnt vmcnt(8)
	s_setprio 1
	s_barrier
	s_waitcnt lgkmcnt(0)
	v_mfma_f32_16x16x32_bf16 v[120:123], v[202:205], v[166:169], 0
	v_mfma_f32_16x16x32_bf16 v[112:115], v[210:213], v[166:169], 0
	v_mfma_f32_16x16x32_bf16 v[104:107], v[202:205], v[174:177], 0
	v_mfma_f32_16x16x32_bf16 v[96:99], v[210:213], v[174:177], 0
	v_mfma_f32_16x16x32_bf16 v[88:91], v[202:205], v[182:185], 0
	v_mfma_f32_16x16x32_bf16 v[80:83], v[210:213], v[182:185], 0
	v_mfma_f32_16x16x32_bf16 v[72:75], v[202:205], v[190:193], 0
	v_mfma_f32_16x16x32_bf16 v[64:67], v[210:213], v[190:193], 0
	v_mfma_f32_16x16x32_bf16 v[120:123], v[206:209], v[170:173], v[120:123]
	v_mfma_f32_16x16x32_bf16 v[112:115], v[214:217], v[170:173], v[112:115]
	v_mfma_f32_16x16x32_bf16 v[104:107], v[206:209], v[178:181], v[104:107]
	v_mfma_f32_16x16x32_bf16 v[96:99], v[214:217], v[178:181], v[96:99]
	v_mfma_f32_16x16x32_bf16 v[88:91], v[206:209], v[186:189], v[88:91]
	v_mfma_f32_16x16x32_bf16 v[80:83], v[214:217], v[186:189], v[80:83]
	v_mfma_f32_16x16x32_bf16 v[72:75], v[206:209], v[194:197], v[72:75]
	v_mfma_f32_16x16x32_bf16 v[64:67], v[214:217], v[194:197], v[64:67]
	s_barrier
	s_setprio 0
	s_mov_b32 m0, s15
	v_lshl_add_u64 v[220:221], s[20:21], 0, v[134:135]
	ds_read_b128 v[166:169], v148 offset:16384
	ds_read_b128 v[170:173], v148 offset:17408
	ds_read_b128 v[174:177], v148 offset:18432
	ds_read_b128 v[178:181], v148 offset:19456
	ds_read_b128 v[182:185], v148 offset:20480
	ds_read_b128 v[186:189], v148 offset:21504
	ds_read_b128 v[190:193], v148 offset:22528
	ds_read_b128 v[194:197], v148 offset:23552
	global_load_lds_dwordx4 v134, s[20:21]
	v_lshl_add_u64 v[222:223], s[20:21], 0, v[130:131]
	s_mov_b32 m0, s28
	s_nop 0
	global_load_lds_dwordx4 v130, s[20:21]
	s_setprio 1
	s_barrier
	s_waitcnt lgkmcnt(0)
	v_mfma_f32_16x16x32_bf16 v[60:63], v[150:153], v[166:169], 0
	v_mfma_f32_16x16x32_bf16 v[56:59], v[158:161], v[166:169], 0
	v_mfma_f32_16x16x32_bf16 v[44:47], v[150:153], v[174:177], 0
	v_mfma_f32_16x16x32_bf16 v[40:43], v[158:161], v[174:177], 0
	v_mfma_f32_16x16x32_bf16 v[28:31], v[150:153], v[182:185], 0
	v_mfma_f32_16x16x32_bf16 v[24:27], v[158:161], v[182:185], 0
	v_mfma_f32_16x16x32_bf16 v[12:15], v[150:153], v[190:193], 0
	v_mfma_f32_16x16x32_bf16 v[8:11], v[158:161], v[190:193], 0
	v_mfma_f32_16x16x32_bf16 v[60:63], v[154:157], v[170:173], v[60:63]
	v_mfma_f32_16x16x32_bf16 v[56:59], v[162:165], v[170:173], v[56:59]
	v_mfma_f32_16x16x32_bf16 v[44:47], v[154:157], v[178:181], v[44:47]
	v_mfma_f32_16x16x32_bf16 v[40:43], v[162:165], v[178:181], v[40:43]
	v_mfma_f32_16x16x32_bf16 v[28:31], v[154:157], v[186:189], v[28:31]
	v_mfma_f32_16x16x32_bf16 v[24:27], v[162:165], v[186:189], v[24:27]
	v_mfma_f32_16x16x32_bf16 v[12:15], v[154:157], v[194:197], v[12:15]
	v_mfma_f32_16x16x32_bf16 v[8:11], v[162:165], v[194:197], v[8:11]
	s_barrier
; #define PG8_STAGE(bufoff, gbase, voff) do { _Pragma("unroll") for (int _i = 0; _i < 2; ++_i) \
;         __builtin_amdgcn_global_load_lds((const unsigned*)((const char*)(gbase) + (voff)[_i]), (LAS unsigned*)(lds + (bufoff) + ldsw + _i * 8192), 16, 0, 0); } while (0)
; #define PG8_LDA(dst, b, h) do { _Pragma("unroll") for (int m = 0; m < 4; ++m) _Pragma("unroll") for (int k = 0; k < 2; ++k) dst[m][k] = *(const LAS bf16x8*)(lds + PG8_SA(b, h) + aoff + m * 2048 + k * 1024); } while (0)
; #define PG8_LDB(dst, b, h) do { _Pragma("unroll") for (int n = 0; n < 2; ++n) _Pragma("unroll") for (int k = 0; k < 2; ++k) dst[n][k] = *(const LAS bf16x8*)(lds + PG8_SB(b, h) + boff + n * 2048 + k * 1024); } while (0)
; #define PG8_MMA(ai, bj, At, Bt) do { __builtin_amdgcn_s_setprio(1); _Pragma("unroll") for (int m = 0; m < 4; ++m) _Pragma("unroll") for (int n = 0; n < 2; ++n) _Pragma("unroll") for (int k = 0; k < 2; ++k) \
;         acc[ai][bj][m][n] = __builtin_amdgcn_mfma_f32_16x16x32_bf16(Bt[n][k], At[m][k], acc[ai][bj][m][n], 0, 0, 0); __builtin_amdgcn_s_setprio(0); } while (0)
; #define PG8_WAIT_V(n) asm volatile("s_waitcnt vmcnt(" #n ")" ::: "memory")
; #define PG8_WAIT_L(n) asm volatile("s_waitcnt lgkmcnt(" #n ")" ::: "memory")
; #define PG8_BAR __builtin_amdgcn_s_barrier()
; #define PG8_SCHED __builtin_amdgcn_sched_barrier(0)
; template <class Epi, class Sched>
; __device__ __forceinline__ void gemm_phase(LAS unsigned char* lds, const Gemm g, const Sched& S, const Epi& E) {
;     ...
;             PG8_STAGE(PG8_SB(0, 1), b2 + hstep, voffB);
;             PG8_WAIT_V(6); PG8_BAR; PG8_MMA(1, 1, At, B1); PG8_BAR;
;             PG8_LDB(B0, 1, 0); PG8_SCHED; PG8_LDA(At, 1, 0); PG8_STAGE(PG8_SA(0, 1), a2 + hstep, voffA);
;             PG8_WAIT_L(8); PG8_BAR; PG8_WAIT_L(0); PG8_MMA(0, 0, At, B0); PG8_BAR; PG8_SCHED;
;             PG8_LDB(B1, 1, 1); PG8_STAGE(PG8_SB(1, 0), b3, voffB);
;             PG8_BAR; PG8_WAIT_L(0); PG8_MMA(0, 1, At, B1); PG8_BAR;
;             PG8_LDA(At, 1, 1); PG8_STAGE(PG8_SA(1, 0), a3, voffA);
	s_setprio 0
	s_add_u32 s48, s18, 0x40000
	s_addc_u32 s49, s19, 0
	s_add_i32 s47, s39, s25
	s_mov_b32 m0, s47
	s_nop 0
	global_load_lds_dwordx4 v132, s[48:49]
	s_add_i32 m0, s47, 0x2000
	s_nop 0
	global_load_lds_dwordx4 v128, s[48:49]
	s_add_u32 s20, s20, 0x40000
	s_addc_u32 s21, s21, 0
	s_mov_b32 m0, s29
	s_nop 0
	global_load_lds_dwordx4 v134, s[20:21]
	s_mov_b32 m0, s30
	s_nop 0
	global_load_lds_dwordx4 v130, s[20:21]
	s_waitcnt vmcnt(10)
	s_setprio 1
	s_barrier
	v_mfma_f32_16x16x32_bf16 v[52:55], v[202:205], v[166:169], 0
	v_mfma_f32_16x16x32_bf16 v[48:51], v[210:213], v[166:169], 0
	v_mfma_f32_16x16x32_bf16 v[36:39], v[202:205], v[174:177], 0
	v_mfma_f32_16x16x32_bf16 v[32:35], v[210:213], v[174:177], 0
	v_mfma_f32_16x16x32_bf16 v[20:23], v[202:205], v[182:185], 0
	v_mfma_f32_16x16x32_bf16 v[16:19], v[210:213], v[182:185], 0
	v_mfma_f32_16x16x32_bf16 v[4:7], v[202:205], v[190:193], 0
	v_mfma_f32_16x16x32_bf16 v[0:3], v[210:213], v[190:193], 0
	v_mfma_f32_16x16x32_bf16 v[52:55], v[206:209], v[170:173], v[52:55]
	v_mfma_f32_16x16x32_bf16 v[48:51], v[214:217], v[170:173], v[48:51]
	v_mfma_f32_16x16x32_bf16 v[36:39], v[206:209], v[178:181], v[36:39]
	v_mfma_f32_16x16x32_bf16 v[32:35], v[214:217], v[178:181], v[32:35]
	v_mfma_f32_16x16x32_bf16 v[20:23], v[206:209], v[186:189], v[20:23]
	v_mfma_f32_16x16x32_bf16 v[16:19], v[214:217], v[186:189], v[16:19]
	v_mfma_f32_16x16x32_bf16 v[4:7], v[206:209], v[194:197], v[4:7]
	v_mfma_f32_16x16x32_bf16 v[0:3], v[214:217], v[194:197], v[0:3]
	s_barrier
	s_setprio 0
	s_add_i32 s47, 0, 0x18000
	ds_read_b128 v[150:153], v149 offset:16384
	ds_read_b128 v[154:157], v149 offset:17408
	ds_read_b128 v[158:161], v149 offset:18432
	ds_read_b128 v[162:165], v149 offset:19456
	ds_read_b128 v[166:169], v148 offset:32768
	ds_read_b128 v[170:173], v148 offset:33792
	ds_read_b128 v[174:177], v148 offset:34816
	ds_read_b128 v[178:181], v148 offset:35840
	ds_read_b128 v[182:185], v148 offset:36864
	ds_read_b128 v[186:189], v148 offset:37888
	ds_read_b128 v[190:193], v148 offset:38912
	ds_read_b128 v[194:197], v148 offset:39936
	s_waitcnt lgkmcnt(8)
	s_waitcnt vmcnt(8)
	s_setprio 1
	s_barrier
	s_waitcnt lgkmcnt(0)
	v_mfma_f32_16x16x32_bf16 v[124:127], v[150:153], v[166:169], v[124:127]
	v_mfma_f32_16x16x32_bf16 v[116:119], v[158:161], v[166:169], v[116:119]
	v_mfma_f32_16x16x32_bf16 v[108:111], v[150:153], v[174:177], v[108:111]
	v_mfma_f32_16x16x32_bf16 v[100:103], v[158:161], v[174:177], v[100:103]
	v_mfma_f32_16x16x32_bf16 v[92:95], v[150:153], v[182:185], v[92:95]
	v_mfma_f32_16x16x32_bf16 v[84:87], v[158:161], v[182:185], v[84:87]
	v_mfma_f32_16x16x32_bf16 v[76:79], v[150:153], v[190:193], v[76:79]
	v_mfma_f32_16x16x32_bf16 v[68:71], v[158:161], v[190:193], v[68:71]
	v_mfma_f32_16x16x32_bf16 v[124:127], v[154:157], v[170:173], v[124:127]
	v_mfma_f32_16x16x32_bf16 v[116:119], v[162:165], v[170:173], v[116:119]
	v_mfma_f32_16x16x32_bf16 v[108:111], v[154:157], v[178:181], v[108:111]
	v_mfma_f32_16x16x32_bf16 v[100:103], v[162:165], v[178:181], v[100:103]
	v_mfma_f32_16x16x32_bf16 v[92:95], v[154:157], v[186:189], v[92:95]
	v_mfma_f32_16x16x32_bf16 v[84:87], v[162:165], v[186:189], v[84:87]
	v_mfma_f32_16x16x32_bf16 v[76:79], v[154:157], v[194:197], v[76:79]
	v_mfma_f32_16x16x32_bf16 v[68:71], v[162:165], v[194:197], v[68:71]
	s_barrier
	s_setprio 0
	s_add_i32 s20, 0, 0x1c000
	s_add_i32 s21, s47, s25
	v_add_u32_e32 v214, s20, v146
	s_add_u32 s0, s18, 0x80
	s_addc_u32 s1, s19, 0
	s_mov_b32 m0, s21
	ds_read_b128 v[202:205], v214
	ds_read_b128 v[206:209], v214 offset:1024
	ds_read_b128 v[210:213], v214 offset:2048
	ds_read_b128 v[214:217], v214 offset:3072
	global_load_lds_dwordx4 v132, s[0:1]
	s_add_i32 m0, s21, 0x2000
	s_nop 0
	global_load_lds_dwordx4 v128, s[0:1]
	s_waitcnt vmcnt(8)
	s_setprio 1
	s_barrier
	s_waitcnt lgkmcnt(0)
	v_mfma_f32_16x16x32_bf16 v[120:123], v[202:205], v[166:169], v[120:123]
	v_mfma_f32_16x16x32_bf16 v[112:115], v[210:213], v[166:169], v[112:115]
	v_mfma_f32_16x16x32_bf16 v[104:107], v[202:205], v[174:177], v[104:107]
	v_mfma_f32_16x16x32_bf16 v[96:99], v[210:213], v[174:177], v[96:99]
	v_mfma_f32_16x16x32_bf16 v[88:91], v[202:205], v[182:185], v[88:91]
	v_mfma_f32_16x16x32_bf16 v[80:83], v[210:213], v[182:185], v[80:83]
	v_mfma_f32_16x16x32_bf16 v[72:75], v[202:205], v[190:193], v[72:75]
	v_mfma_f32_16x16x32_bf16 v[64:67], v[210:213], v[190:193], v[64:67]
	v_mfma_f32_16x16x32_bf16 v[120:123], v[206:209], v[170:173], v[120:123]
	v_mfma_f32_16x16x32_bf16 v[112:115], v[214:217], v[170:173], v[112:115]
	v_mfma_f32_16x16x32_bf16 v[104:107], v[206:209], v[178:181], v[104:107]
	v_mfma_f32_16x16x32_bf16 v[96:99], v[214:217], v[178:181], v[96:99]
	v_mfma_f32_16x16x32_bf16 v[88:91], v[206:209], v[186:189], v[88:91]
	v_mfma_f32_16x16x32_bf16 v[80:83], v[214:217], v[186:189], v[80:83]
	v_mfma_f32_16x16x32_bf16 v[72:75], v[206:209], v[194:197], v[72:75]
	v_mfma_f32_16x16x32_bf16 v[64:67], v[214:217], v[194:197], v[64:67]
	s_barrier
	s_setprio 0
	s_mov_b32 m0, s35
	s_mov_b64 s[0:1], 0x80
	v_lshl_add_u64 v[198:199], v[220:221], 0, s[0:1]
	ds_read_b128 v[166:169], v148 offset:49152
	ds_read_b128 v[170:173], v148 offset:50176
	ds_read_b128 v[174:177], v148 offset:51200
	ds_read_b128 v[178:181], v148 offset:52224
	ds_read_b128 v[182:185], v148 offset:53248
	ds_read_b128 v[186:189], v148 offset:54272
	ds_read_b128 v[190:193], v148 offset:55296
	ds_read_b128 v[194:197], v148 offset:56320
	global_load_lds_dwordx4 v[198:199], off
	v_lshl_add_u64 v[198:199], v[222:223], 0, s[0:1]
	s_mov_b32 m0, s36
	s_nop 0
	global_load_lds_dwordx4 v[198:199], off
	s_setprio 1
	s_barrier
; #define PG8_STAGE(bufoff, gbase, voff) do { _Pragma("unroll") for (int _i = 0; _i < 2; ++_i) \
;         __builtin_amdgcn_global_load_lds((const unsigned*)((const char*)(gbase) + (voff)[_i]), (LAS unsigned*)(lds + (bufoff) + ldsw + _i * 8192), 16, 0, 0); } while (0)
; #define PG8_LDA(dst, b, h) do { _Pragma("unroll") for (int m = 0; m < 4; ++m) _Pragma("unroll") for (int k = 0; k < 2; ++k) dst[m][k] = *(const LAS bf16x8*)(lds + PG8_SA(b, h) + aoff + m * 2048 + k * 1024); } while (0)
; #define PG8_LDB(dst, b, h) do { _Pragma("unroll") for (int n = 0; n < 2; ++n) _Pragma("unroll") for (int k = 0; k < 2; ++k) dst[n][k] = *(const LAS bf16x8*)(lds + PG8_SB(b, h) + boff + n * 2048 + k * 1024); } while (0)
; #define PG8_WAIT_V(n) asm volatile("s_waitcnt vmcnt(" #n ")" ::: "memory")
; #define PG8_WAIT_L(n) asm volatile("s_waitcnt lgkmcnt(" #n ")" ::: "memory")
; #define PG8_BAR __builtin_amdgcn_s_barrier()
; #define PG8_SCHED __builtin_amdgcn_sched_barrier(0)
; template <class Epi, class Sched>
; __device__ __forceinline__ void gemm_phase(LAS unsigned char* lds, const Gemm g, const Sched& S, const Epi& E) {
;     ...
;             PG8_LDB(B0, 0, 0); PG8_SCHED; PG8_LDA(At, 0, 0); PG8_STAGE(PG8_SA(1, 1), a1 + hstep, voffA);
;             PG8_WAIT_L(8); PG8_BAR; PG8_WAIT_L(0); PG8_MMA(0, 0, At, B0); PG8_BAR; PG8_SCHED;
;             PG8_LDB(B1, 0, 1); PG8_STAGE(PG8_SB(0, 0), b2, voffB);
;             PG8_BAR; PG8_WAIT_L(0); PG8_MMA(0, 1, At, B1); PG8_BAR;
;             PG8_LDA(At, 0, 1); PG8_STAGE(PG8_SA(0, 0), a2, voffA);
;             PG8_BAR; PG8_WAIT_L(0); PG8_MMA(1, 0, At, B0); PG8_BAR; PG8_SCHED;
;             PG8_STAGE(PG8_SB(0, 1), b2 + hstep, voffB);
;             PG8_WAIT_V(6); PG8_BAR; PG8_MMA(1, 1, At, B1); PG8_BAR;
;             PG8_LDB(B0, 1, 0); PG8_SCHED; PG8_LDA(At, 1, 0); PG8_STAGE(PG8_SA(0, 1), a2 + hstep, voffA);
;             PG8_WAIT_L(8); PG8_BAR; PG8_WAIT_L(0); PG8_MMA(0, 0, At, B0); PG8_BAR; PG8_SCHED;
;             PG8_LDB(B1, 1, 1); PG8_STAGE(PG8_SB(1, 0), b3, voffB);
;             PG8_BAR; PG8_WAIT_L(0); PG8_MMA(0, 1, At, B1); PG8_BAR;
;             PG8_LDA(At, 1, 1); PG8_STAGE(PG8_SA(1, 0), a3, voffA);
;             PG8_BAR; PG8_WAIT_L(0); PG8_MMA(1, 0, At, B0); PG8_BAR; PG8_SCHED;
;             PG8_STAGE(PG8_SB(1, 1), b3 + hstep, voffB);
;             PG8_WAIT_V(6); PG8_BAR; PG8_MMA(1, 1, At, B1); PG8_BAR;
	s_waitcnt lgkmcnt(0)
	v_mfma_f32_16x16x32_bf16 v[60:63], v[150:153], v[166:169], v[60:63]
	v_mfma_f32_16x16x32_bf16 v[56:59], v[158:161], v[166:169], v[56:59]
	v_mfma_f32_16x16x32_bf16 v[44:47], v[150:153], v[174:177], v[44:47]
	v_mfma_f32_16x16x32_bf16 v[40:43], v[158:161], v[174:177], v[40:43]
	v_mfma_f32_16x16x32_bf16 v[28:31], v[150:153], v[182:185], v[28:31]
	v_mfma_f32_16x16x32_bf16 v[24:27], v[158:161], v[182:185], v[24:27]
	v_mfma_f32_16x16x32_bf16 v[12:15], v[150:153], v[190:193], v[12:15]
	v_mfma_f32_16x16x32_bf16 v[8:11], v[158:161], v[190:193], v[8:11]
	v_mfma_f32_16x16x32_bf16 v[60:63], v[154:157], v[170:173], v[60:63]
	v_mfma_f32_16x16x32_bf16 v[56:59], v[162:165], v[170:173], v[56:59]
	v_mfma_f32_16x16x32_bf16 v[44:47], v[154:157], v[178:181], v[44:47]
	v_mfma_f32_16x16x32_bf16 v[40:43], v[162:165], v[178:181], v[40:43]
	v_mfma_f32_16x16x32_bf16 v[28:31], v[154:157], v[186:189], v[28:31]
	v_mfma_f32_16x16x32_bf16 v[24:27], v[162:165], v[186:189], v[24:27]
	v_mfma_f32_16x16x32_bf16 v[12:15], v[154:157], v[194:197], v[12:15]
	v_mfma_f32_16x16x32_bf16 v[8:11], v[162:165], v[194:197], v[8:11]
	s_barrier
	s_setprio 0
	s_add_u32 s18, s18, 0x40080
	s_addc_u32 s19, s19, 0
	s_add_i32 s20, s20, s25
	s_mov_b32 m0, s20
	s_nop 0
	global_load_lds_dwordx4 v132, s[18:19]
	s_add_i32 m0, s20, 0x2000
	s_nop 0
	global_load_lds_dwordx4 v128, s[18:19]
	s_waitcnt vmcnt(8)
	s_setprio 1
	s_barrier
	v_mfma_f32_16x16x32_bf16 v[52:55], v[202:205], v[166:169], v[52:55]
	v_mfma_f32_16x16x32_bf16 v[48:51], v[210:213], v[166:169], v[48:51]
	v_mfma_f32_16x16x32_bf16 v[36:39], v[202:205], v[174:177], v[36:39]
	v_mfma_f32_16x16x32_bf16 v[32:35], v[210:213], v[174:177], v[32:35]
	v_mfma_f32_16x16x32_bf16 v[20:23], v[202:205], v[182:185], v[20:23]
	v_mfma_f32_16x16x32_bf16 v[16:19], v[210:213], v[182:185], v[16:19]
	v_mfma_f32_16x16x32_bf16 v[4:7], v[202:205], v[190:193], v[4:7]
	v_mfma_f32_16x16x32_bf16 v[0:3], v[210:213], v[190:193], v[0:3]
	v_mfma_f32_16x16x32_bf16 v[52:55], v[206:209], v[170:173], v[52:55]
	v_mfma_f32_16x16x32_bf16 v[48:51], v[214:217], v[170:173], v[48:51]
	v_mfma_f32_16x16x32_bf16 v[36:39], v[206:209], v[178:181], v[36:39]
	v_mfma_f32_16x16x32_bf16 v[32:35], v[214:217], v[178:181], v[32:35]
	v_mfma_f32_16x16x32_bf16 v[20:23], v[206:209], v[186:189], v[20:23]
	v_mfma_f32_16x16x32_bf16 v[16:19], v[214:217], v[186:189], v[16:19]
	v_mfma_f32_16x16x32_bf16 v[4:7], v[206:209], v[194:197], v[4:7]
	v_mfma_f32_16x16x32_bf16 v[0:3], v[214:217], v[194:197], v[0:3]
	s_barrier
	s_setprio 0
	s_add_i32 s46, s46, 2
	s_add_u32 s16, s16, 0x100
	s_addc_u32 s17, s17, 0
	s_add_u32 s44, s44, 0x100
	s_addc_u32 s45, s45, 0
	s_cmp_gt_u32 s46, 13
.LBB0_1021:
	ds_read_b128 v[150:153], v147
	ds_read_b128 v[154:157], v147 offset:1024
	ds_read_b128 v[158:161], v147 offset:2048
	ds_read_b128 v[162:165], v147 offset:3072
	s_add_u32 s18, s16, 0xfffc0080
	s_addc_u32 s19, s17, -1
	s_cmp_eq_u32 s46, 12
	s_cselect_b32 s21, s7, s19
	s_cselect_b32 s20, s42, s18
	s_cselect_b32 s19, s5, s45
	s_cselect_b32 s18, s43, s44
	s_add_i32 m0, s15, 0xc000
	ds_read_b128 v[166:169], v148
	ds_read_b128 v[170:173], v148 offset:1024
	ds_read_b128 v[174:177], v148 offset:2048
	ds_read_b128 v[178:181], v148 offset:3072
	ds_read_b128 v[182:185], v148 offset:4096
	ds_read_b128 v[186:189], v148 offset:5120
	ds_read_b128 v[190:193], v148 offset:6144
	ds_read_b128 v[194:197], v148 offset:7168
	global_load_lds_dwordx4 v136, s[16:17]
	s_add_i32 m0, s15, 0xe000
	s_nop 0
	global_load_lds_dwordx4 v138, s[16:17]
	s_waitcnt lgkmcnt(8)
	s_waitcnt vmcnt(8)
	s_setprio 1
	s_barrier
	s_waitcnt lgkmcnt(0)
	v_mfma_f32_16x16x32_bf16 v[124:127], v[150:153], v[166:169], v[124:127]
	v_mfma_f32_16x16x32_bf16 v[116:119], v[158:161], v[166:169], v[116:119]
	v_mfma_f32_16x16x32_bf16 v[108:111], v[150:153], v[174:177], v[108:111]
	v_mfma_f32_16x16x32_bf16 v[100:103], v[158:161], v[174:177], v[100:103]
	v_mfma_f32_16x16x32_bf16 v[92:95], v[150:153], v[182:185], v[92:95]
	v_mfma_f32_16x16x32_bf16 v[84:87], v[158:161], v[182:185], v[84:87]
	v_mfma_f32_16x16x32_bf16 v[76:79], v[150:153], v[190:193], v[76:79]
	v_mfma_f32_16x16x32_bf16 v[68:71], v[158:161], v[190:193], v[68:71]
	v_mfma_f32_16x16x32_bf16 v[124:127], v[154:157], v[170:173], v[124:127]
	v_mfma_f32_16x16x32_bf16 v[116:119], v[162:165], v[170:173], v[116:119]
	v_mfma_f32_16x16x32_bf16 v[108:111], v[154:157], v[178:181], v[108:111]
	v_mfma_f32_16x16x32_bf16 v[100:103], v[162:165], v[178:181], v[100:103]
	v_mfma_f32_16x16x32_bf16 v[92:95], v[154:157], v[186:189], v[92:95]
	v_mfma_f32_16x16x32_bf16 v[84:87], v[162:165], v[186:189], v[84:87]
	v_mfma_f32_16x16x32_bf16 v[76:79], v[154:157], v[194:197], v[76:79]
	v_mfma_f32_16x16x32_bf16 v[68:71], v[162:165], v[194:197], v[68:71]
	s_barrier
	s_setprio 0
	s_add_i32 s47, s38, s25
	s_mov_b32 m0, s47
	ds_read_b128 v[202:205], v149
	ds_read_b128 v[206:209], v149 offset:1024
	ds_read_b128 v[210:213], v149 offset:2048
	ds_read_b128 v[214:217], v149 offset:3072
	global_load_lds_dwordx4 v132, s[18:19]
	s_add_i32 m0, s47, 0x2000
	s_nop 0
	global_load_lds_dwordx4 v128, s[18:19]
	s_waitcnt vmcnt(8)
	s_setprio 1
	s_barrier
; #define PG8_STAGE(bufoff, gbase, voff) do { _Pragma("unroll") for (int _i = 0; _i < 2; ++_i) \
;         __builtin_amdgcn_global_load_lds((const unsigned*)((const char*)(gbase) + (voff)[_i]), (LAS unsigned*)(lds + (bufoff) + ldsw + _i * 8192), 16, 0, 0); } while (0)
; #define PG8_LDA(dst, b, h) do { _Pragma("unroll") for (int m = 0; m < 4; ++m) _Pragma("unroll") for (int k = 0; k < 2; ++k) dst[m][k] = *(const LAS bf16x8*)(lds + PG8_SA(b, h) + aoff + m * 2048 + k * 1024); } while (0)
; #define PG8_LDB(dst, b, h) do { _Pragma("unroll") for (int n = 0; n < 2; ++n) _Pragma("unroll") for (int k = 0; k < 2; ++k) dst[n][k] = *(const LAS bf16x8*)(lds + PG8_SB(b, h) + boff + n * 2048 + k * 1024); } while (0)
; #define PG8_MMA(ai, bj, At, Bt) do { __builtin_amdgcn_s_setprio(1); _Pragma("unroll") for (int m = 0; m < 4; ++m) _Pragma("unroll") for (int n = 0; n < 2; ++n) _Pragma("unroll") for (int k = 0; k < 2; ++k) \
;         acc[ai][bj][m][n] = __builtin_amdgcn_mfma_f32_16x16x32_bf16(Bt[n][k], At[m][k], acc[ai][bj][m][n], 0, 0, 0); __builtin_amdgcn_s_setprio(0); } while (0)
; #define PG8_WAIT_V(n) asm volatile("s_waitcnt vmcnt(" #n ")" ::: "memory")
; #define PG8_WAIT_L(n) asm volatile("s_waitcnt lgkmcnt(" #n ")" ::: "memory")
; #define PG8_BAR __builtin_amdgcn_s_barrier()
; #define PG8_SCHED __builtin_amdgcn_sched_barrier(0)
; template <class Epi, class Sched>
; __device__ __forceinline__ void gemm_phase(LAS unsigned char* lds, const Gemm g, const Sched& S, const Epi& E) {
;     ...
;             PG8_BAR; PG8_WAIT_L(0); PG8_MMA(1, 0, At, B0); PG8_BAR; PG8_SCHED;
;             PG8_STAGE(PG8_SB(0, 1), b2 + hstep, voffB);
;             PG8_WAIT_V(6); PG8_BAR; PG8_MMA(1, 1, At, B1); PG8_BAR;
;             PG8_LDB(B0, 1, 0); PG8_SCHED; PG8_LDA(At, 1, 0); PG8_STAGE(PG8_SA(0, 1), a2 + hstep, voffA);
;             PG8_WAIT_L(8); PG8_BAR; PG8_WAIT_L(0); PG8_MMA(0, 0, At, B0); PG8_BAR; PG8_SCHED;
;             PG8_LDB(B1, 1, 1); PG8_STAGE(PG8_SB(1, 0), b3, voffB);
;             PG8_BAR; PG8_WAIT_L(0); PG8_MMA(0, 1, At, B1); PG8_BAR;
;             PG8_LDA(At, 1, 1); PG8_STAGE(PG8_SA(1, 0), a3, voffA);
	s_waitcnt lgkmcnt(0)
	v_mfma_f32_16x16x32_bf16 v[120:123], v[202:205], v[166:169], v[120:123]
	v_mfma_f32_16x16x32_bf16 v[112:115], v[210:213], v[166:169], v[112:115]
	v_mfma_f32_16x16x32_bf16 v[104:107], v[202:205], v[174:177], v[104:107]
	v_mfma_f32_16x16x32_bf16 v[96:99], v[210:213], v[174:177], v[96:99]
	v_mfma_f32_16x16x32_bf16 v[88:91], v[202:205], v[182:185], v[88:91]
	v_mfma_f32_16x16x32_bf16 v[80:83], v[210:213], v[182:185], v[80:83]
	v_mfma_f32_16x16x32_bf16 v[72:75], v[202:205], v[190:193], v[72:75]
	v_mfma_f32_16x16x32_bf16 v[64:67], v[210:213], v[190:193], v[64:67]
	v_mfma_f32_16x16x32_bf16 v[120:123], v[206:209], v[170:173], v[120:123]
	v_mfma_f32_16x16x32_bf16 v[112:115], v[214:217], v[170:173], v[112:115]
	v_mfma_f32_16x16x32_bf16 v[104:107], v[206:209], v[178:181], v[104:107]
	v_mfma_f32_16x16x32_bf16 v[96:99], v[214:217], v[178:181], v[96:99]
	v_mfma_f32_16x16x32_bf16 v[88:91], v[206:209], v[186:189], v[88:91]
	v_mfma_f32_16x16x32_bf16 v[80:83], v[214:217], v[186:189], v[80:83]
	v_mfma_f32_16x16x32_bf16 v[72:75], v[206:209], v[194:197], v[72:75]
	v_mfma_f32_16x16x32_bf16 v[64:67], v[214:217], v[194:197], v[64:67]
	s_barrier
	s_setprio 0
	s_mov_b32 m0, s15
	v_lshl_add_u64 v[220:221], s[20:21], 0, v[134:135]
	ds_read_b128 v[166:169], v148 offset:16384
	ds_read_b128 v[170:173], v148 offset:17408
	ds_read_b128 v[174:177], v148 offset:18432
	ds_read_b128 v[178:181], v148 offset:19456
	ds_read_b128 v[182:185], v148 offset:20480
	ds_read_b128 v[186:189], v148 offset:21504
	ds_read_b128 v[190:193], v148 offset:22528
	ds_read_b128 v[194:197], v148 offset:23552
	global_load_lds_dwordx4 v134, s[20:21]
	v_lshl_add_u64 v[222:223], s[20:21], 0, v[130:131]
	s_mov_b32 m0, s28
	s_nop 0
	global_load_lds_dwordx4 v130, s[20:21]
	s_setprio 1
	s_barrier
	s_waitcnt lgkmcnt(0)
	v_mfma_f32_16x16x32_bf16 v[60:63], v[150:153], v[166:169], v[60:63]
	v_mfma_f32_16x16x32_bf16 v[56:59], v[158:161], v[166:169], v[56:59]
	v_mfma_f32_16x16x32_bf16 v[44:47], v[150:153], v[174:177], v[44:47]
	v_mfma_f32_16x16x32_bf16 v[40:43], v[158:161], v[174:177], v[40:43]
	v_mfma_f32_16x16x32_bf16 v[28:31], v[150:153], v[182:185], v[28:31]
	v_mfma_f32_16x16x32_bf16 v[24:27], v[158:161], v[182:185], v[24:27]
	v_mfma_f32_16x16x32_bf16 v[12:15], v[150:153], v[190:193], v[12:15]
	v_mfma_f32_16x16x32_bf16 v[8:11], v[158:161], v[190:193], v[8:11]
	v_mfma_f32_16x16x32_bf16 v[60:63], v[154:157], v[170:173], v[60:63]
	v_mfma_f32_16x16x32_bf16 v[56:59], v[162:165], v[170:173], v[56:59]
	v_mfma_f32_16x16x32_bf16 v[44:47], v[154:157], v[178:181], v[44:47]
	v_mfma_f32_16x16x32_bf16 v[40:43], v[162:165], v[178:181], v[40:43]
	v_mfma_f32_16x16x32_bf16 v[28:31], v[154:157], v[186:189], v[28:31]
	v_mfma_f32_16x16x32_bf16 v[24:27], v[162:165], v[186:189], v[24:27]
	v_mfma_f32_16x16x32_bf16 v[12:15], v[154:157], v[194:197], v[12:15]
	v_mfma_f32_16x16x32_bf16 v[8:11], v[162:165], v[194:197], v[8:11]
	s_barrier
	s_setprio 0
	s_add_u32 s48, s18, 0x40000
	s_addc_u32 s49, s19, 0
	s_add_i32 s47, s39, s25
	s_mov_b32 m0, s47
	s_nop 0
	global_load_lds_dwordx4 v132, s[48:49]
	s_add_i32 m0, s47, 0x2000
	s_nop 0
	global_load_lds_dwordx4 v128, s[48:49]
	s_add_u32 s20, s20, 0x40000
	s_addc_u32 s21, s21, 0
	s_mov_b32 m0, s29
	s_nop 0
	global_load_lds_dwordx4 v134, s[20:21]
	s_mov_b32 m0, s30
	s_nop 0
	global_load_lds_dwordx4 v130, s[20:21]
	s_waitcnt vmcnt(10)
	s_setprio 1
	s_barrier
	v_mfma_f32_16x16x32_bf16 v[52:55], v[202:205], v[166:169], v[52:55]
	v_mfma_f32_16x16x32_bf16 v[48:51], v[210:213], v[166:169], v[48:51]
	v_mfma_f32_16x16x32_bf16 v[36:39], v[202:205], v[174:177], v[36:39]
	v_mfma_f32_16x16x32_bf16 v[32:35], v[210:213], v[174:177], v[32:35]
	v_mfma_f32_16x16x32_bf16 v[20:23], v[202:205], v[182:185], v[20:23]
	v_mfma_f32_16x16x32_bf16 v[16:19], v[210:213], v[182:185], v[16:19]
	v_mfma_f32_16x16x32_bf16 v[4:7], v[202:205], v[190:193], v[4:7]
	v_mfma_f32_16x16x32_bf16 v[0:3], v[210:213], v[190:193], v[0:3]
	v_mfma_f32_16x16x32_bf16 v[52:55], v[206:209], v[170:173], v[52:55]
	v_mfma_f32_16x16x32_bf16 v[48:51], v[214:217], v[170:173], v[48:51]
	v_mfma_f32_16x16x32_bf16 v[36:39], v[206:209], v[178:181], v[36:39]
	v_mfma_f32_16x16x32_bf16 v[32:35], v[214:217], v[178:181], v[32:35]
	v_mfma_f32_16x16x32_bf16 v[20:23], v[206:209], v[186:189], v[20:23]
	v_mfma_f32_16x16x32_bf16 v[16:19], v[214:217], v[186:189], v[16:19]
	v_mfma_f32_16x16x32_bf16 v[4:7], v[206:209], v[194:197], v[4:7]
	v_mfma_f32_16x16x32_bf16 v[0:3], v[214:217], v[194:197], v[0:3]
	s_barrier
	s_setprio 0
	s_add_i32 s47, 0, 0x18000
	ds_read_b128 v[150:153], v149 offset:16384
	ds_read_b128 v[154:157], v149 offset:17408
	ds_read_b128 v[158:161], v149 offset:18432
	ds_read_b128 v[162:165], v149 offset:19456
	ds_read_b128 v[166:169], v148 offset:32768
	ds_read_b128 v[170:173], v148 offset:33792
	ds_read_b128 v[174:177], v148 offset:34816
	ds_read_b128 v[178:181], v148 offset:35840
	ds_read_b128 v[182:185], v148 offset:36864
	ds_read_b128 v[186:189], v148 offset:37888
	ds_read_b128 v[190:193], v148 offset:38912
	ds_read_b128 v[194:197], v148 offset:39936
	s_waitcnt lgkmcnt(8)
	s_waitcnt vmcnt(8)
	s_setprio 1
	s_barrier
; #define PG8_STAGE(bufoff, gbase, voff) do { _Pragma("unroll") for (int _i = 0; _i < 2; ++_i) \
;         __builtin_amdgcn_global_load_lds((const unsigned*)((const char*)(gbase) + (voff)[_i]), (LAS unsigned*)(lds + (bufoff) + ldsw + _i * 8192), 16, 0, 0); } while (0)
; #define PG8_LDA(dst, b, h) do { _Pragma("unroll") for (int m = 0; m < 4; ++m) _Pragma("unroll") for (int k = 0; k < 2; ++k) dst[m][k] = *(const LAS bf16x8*)(lds + PG8_SA(b, h) + aoff + m * 2048 + k * 1024); } while (0)
; #define PG8_MMA(ai, bj, At, Bt) do { __builtin_amdgcn_s_setprio(1); _Pragma("unroll") for (int m = 0; m < 4; ++m) _Pragma("unroll") for (int n = 0; n < 2; ++n) _Pragma("unroll") for (int k = 0; k < 2; ++k) \
;         acc[ai][bj][m][n] = __builtin_amdgcn_mfma_f32_16x16x32_bf16(Bt[n][k], At[m][k], acc[ai][bj][m][n], 0, 0, 0); __builtin_amdgcn_s_setprio(0); } while (0)
; #define PG8_WAIT_V(n) asm volatile("s_waitcnt vmcnt(" #n ")" ::: "memory")
; #define PG8_WAIT_L(n) asm volatile("s_waitcnt lgkmcnt(" #n ")" ::: "memory")
; #define PG8_BAR __builtin_amdgcn_s_barrier()
; #define PG8_SCHED __builtin_amdgcn_sched_barrier(0)
; template <class Epi, class Sched>
; __device__ __forceinline__ void gemm_phase(LAS unsigned char* lds, const Gemm g, const Sched& S, const Epi& E) {
;     ...
;             PG8_LDA(At, 1, 1); PG8_STAGE(PG8_SA(1, 0), a3, voffA);
;             PG8_BAR; PG8_WAIT_L(0); PG8_MMA(1, 0, At, B0); PG8_BAR; PG8_SCHED;
;             PG8_STAGE(PG8_SB(1, 1), b3 + hstep, voffB);
;             PG8_WAIT_V(6); PG8_BAR; PG8_MMA(1, 1, At, B1); PG8_BAR;
	s_waitcnt lgkmcnt(0)
	v_mfma_f32_16x16x32_bf16 v[124:127], v[150:153], v[166:169], v[124:127]
	v_mfma_f32_16x16x32_bf16 v[116:119], v[158:161], v[166:169], v[116:119]
	v_mfma_f32_16x16x32_bf16 v[108:111], v[150:153], v[174:177], v[108:111]
	v_mfma_f32_16x16x32_bf16 v[100:103], v[158:161], v[174:177], v[100:103]
	v_mfma_f32_16x16x32_bf16 v[92:95], v[150:153], v[182:185], v[92:95]
	v_mfma_f32_16x16x32_bf16 v[84:87], v[158:161], v[182:185], v[84:87]
	v_mfma_f32_16x16x32_bf16 v[76:79], v[150:153], v[190:193], v[76:79]
	v_mfma_f32_16x16x32_bf16 v[68:71], v[158:161], v[190:193], v[68:71]
	v_mfma_f32_16x16x32_bf16 v[124:127], v[154:157], v[170:173], v[124:127]
	v_mfma_f32_16x16x32_bf16 v[116:119], v[162:165], v[170:173], v[116:119]
	v_mfma_f32_16x16x32_bf16 v[108:111], v[154:157], v[178:181], v[108:111]
	v_mfma_f32_16x16x32_bf16 v[100:103], v[162:165], v[178:181], v[100:103]
	v_mfma_f32_16x16x32_bf16 v[92:95], v[154:157], v[186:189], v[92:95]
	v_mfma_f32_16x16x32_bf16 v[84:87], v[162:165], v[186:189], v[84:87]
	v_mfma_f32_16x16x32_bf16 v[76:79], v[154:157], v[194:197], v[76:79]
	v_mfma_f32_16x16x32_bf16 v[68:71], v[162:165], v[194:197], v[68:71]
	s_barrier
	s_setprio 0
	s_add_i32 s20, 0, 0x1c000
	s_add_i32 s21, s47, s25
	v_add_u32_e32 v214, s20, v146
	s_add_u32 s0, s18, 0x80
	s_addc_u32 s1, s19, 0
	s_mov_b32 m0, s21
	ds_read_b128 v[202:205], v214
	ds_read_b128 v[206:209], v214 offset:1024
	ds_read_b128 v[210:213], v214 offset:2048
	ds_read_b128 v[214:217], v214 offset:3072
	global_load_lds_dwordx4 v132, s[0:1]
	s_add_i32 m0, s21, 0x2000
	s_nop 0
	global_load_lds_dwordx4 v128, s[0:1]
	s_waitcnt vmcnt(8)
	s_setprio 1
	s_barrier
	s_waitcnt lgkmcnt(0)
	v_mfma_f32_16x16x32_bf16 v[120:123], v[202:205], v[166:169], v[120:123]
	v_mfma_f32_16x16x32_bf16 v[112:115], v[210:213], v[166:169], v[112:115]
	v_mfma_f32_16x16x32_bf16 v[104:107], v[202:205], v[174:177], v[104:107]
	v_mfma_f32_16x16x32_bf16 v[96:99], v[210:213], v[174:177], v[96:99]
	v_mfma_f32_16x16x32_bf16 v[88:91], v[202:205], v[182:185], v[88:91]
	v_mfma_f32_16x16x32_bf16 v[80:83], v[210:213], v[182:185], v[80:83]
	v_mfma_f32_16x16x32_bf16 v[72:75], v[202:205], v[190:193], v[72:75]
	v_mfma_f32_16x16x32_bf16 v[64:67], v[210:213], v[190:193], v[64:67]
	v_mfma_f32_16x16x32_bf16 v[120:123], v[206:209], v[170:173], v[120:123]
	v_mfma_f32_16x16x32_bf16 v[112:115], v[214:217], v[170:173], v[112:115]
	v_mfma_f32_16x16x32_bf16 v[104:107], v[206:209], v[178:181], v[104:107]
	v_mfma_f32_16x16x32_bf16 v[96:99], v[214:217], v[178:181], v[96:99]
	v_mfma_f32_16x16x32_bf16 v[88:91], v[206:209], v[186:189], v[88:91]
	v_mfma_f32_16x16x32_bf16 v[80:83], v[214:217], v[186:189], v[80:83]
	v_mfma_f32_16x16x32_bf16 v[72:75], v[206:209], v[194:197], v[72:75]
	v_mfma_f32_16x16x32_bf16 v[64:67], v[214:217], v[194:197], v[64:67]
	s_barrier
	s_setprio 0
	s_mov_b32 m0, s35
	s_mov_b64 s[0:1], 0x80
	v_lshl_add_u64 v[198:199], v[220:221], 0, s[0:1]
	ds_read_b128 v[166:169], v148 offset:49152
	ds_read_b128 v[170:173], v148 offset:50176
	ds_read_b128 v[174:177], v148 offset:51200
	ds_read_b128 v[178:181], v148 offset:52224
	ds_read_b128 v[182:185], v148 offset:53248
	ds_read_b128 v[186:189], v148 offset:54272
	ds_read_b128 v[190:193], v148 offset:55296
	ds_read_b128 v[194:197], v148 offset:56320
	global_load_lds_dwordx4 v[198:199], off
	v_lshl_add_u64 v[198:199], v[222:223], 0, s[0:1]
	s_mov_b32 m0, s36
	s_nop 0
	global_load_lds_dwordx4 v[198:199], off
	s_setprio 1
	s_barrier
	s_waitcnt lgkmcnt(0)
	v_mfma_f32_16x16x32_bf16 v[60:63], v[150:153], v[166:169], v[60:63]
	v_mfma_f32_16x16x32_bf16 v[56:59], v[158:161], v[166:169], v[56:59]
	v_mfma_f32_16x16x32_bf16 v[44:47], v[150:153], v[174:177], v[44:47]
	v_mfma_f32_16x16x32_bf16 v[40:43], v[158:161], v[174:177], v[40:43]
	v_mfma_f32_16x16x32_bf16 v[28:31], v[150:153], v[182:185], v[28:31]
	v_mfma_f32_16x16x32_bf16 v[24:27], v[158:161], v[182:185], v[24:27]
	v_mfma_f32_16x16x32_bf16 v[12:15], v[150:153], v[190:193], v[12:15]
	v_mfma_f32_16x16x32_bf16 v[8:11], v[158:161], v[190:193], v[8:11]
	v_mfma_f32_16x16x32_bf16 v[60:63], v[154:157], v[170:173], v[60:63]
	v_mfma_f32_16x16x32_bf16 v[56:59], v[162:165], v[170:173], v[56:59]
	v_mfma_f32_16x16x32_bf16 v[44:47], v[154:157], v[178:181], v[44:47]
	v_mfma_f32_16x16x32_bf16 v[40:43], v[162:165], v[178:181], v[40:43]
	v_mfma_f32_16x16x32_bf16 v[28:31], v[154:157], v[186:189], v[28:31]
	v_mfma_f32_16x16x32_bf16 v[24:27], v[162:165], v[186:189], v[24:27]
	v_mfma_f32_16x16x32_bf16 v[12:15], v[154:157], v[194:197], v[12:15]
	v_mfma_f32_16x16x32_bf16 v[8:11], v[162:165], v[194:197], v[8:11]
	s_barrier
	s_setprio 0
	s_add_u32 s18, s18, 0x40080
	s_addc_u32 s19, s19, 0
	s_add_i32 s20, s20, s25
	s_mov_b32 m0, s20
	s_nop 0
	global_load_lds_dwordx4 v132, s[18:19]
	s_add_i32 m0, s20, 0x2000
	s_nop 0
	global_load_lds_dwordx4 v128, s[18:19]
	s_waitcnt vmcnt(8)
	s_setprio 1
	s_barrier
	v_mfma_f32_16x16x32_bf16 v[52:55], v[202:205], v[166:169], v[52:55]
	v_mfma_f32_16x16x32_bf16 v[48:51], v[210:213], v[166:169], v[48:51]
	v_mfma_f32_16x16x32_bf16 v[36:39], v[202:205], v[174:177], v[36:39]
	v_mfma_f32_16x16x32_bf16 v[32:35], v[210:213], v[174:177], v[32:35]
	v_mfma_f32_16x16x32_bf16 v[20:23], v[202:205], v[182:185], v[20:23]
	v_mfma_f32_16x16x32_bf16 v[16:19], v[210:213], v[182:185], v[16:19]
	v_mfma_f32_16x16x32_bf16 v[4:7], v[202:205], v[190:193], v[4:7]
	v_mfma_f32_16x16x32_bf16 v[0:3], v[210:213], v[190:193], v[0:3]
	v_mfma_f32_16x16x32_bf16 v[52:55], v[206:209], v[170:173], v[52:55]
	v_mfma_f32_16x16x32_bf16 v[48:51], v[214:217], v[170:173], v[48:51]
	v_mfma_f32_16x16x32_bf16 v[36:39], v[206:209], v[178:181], v[36:39]
	v_mfma_f32_16x16x32_bf16 v[32:35], v[214:217], v[178:181], v[32:35]
	v_mfma_f32_16x16x32_bf16 v[20:23], v[206:209], v[186:189], v[20:23]
	v_mfma_f32_16x16x32_bf16 v[16:19], v[214:217], v[186:189], v[16:19]
	v_mfma_f32_16x16x32_bf16 v[4:7], v[206:209], v[194:197], v[4:7]
	v_mfma_f32_16x16x32_bf16 v[0:3], v[214:217], v[194:197], v[0:3]
	s_setprio 0
	s_add_i32 s46, s46, 2
	s_add_u32 s16, s16, 0x100
	s_addc_u32 s17, s17, 0
	s_add_u32 s44, s44, 0x100
	s_addc_u32 s45, s45, 0
	s_cmp_gt_u32 s46, 13
	s_cbranch_scc1 .Lconc_last_g11
	s_barrier
	s_branch .LBB0_1021

; #define PG8_STAGE(bufoff, gbase, voff) do { _Pragma("unroll") for (int _i = 0; _i < 2; ++_i) \
;         __builtin_amdgcn_global_load_lds((const unsigned*)((const char*)(gbase) + (voff)[_i]), (LAS unsigned*)(lds + (bufoff) + ldsw + _i * 8192), 16, 0, 0); } while (0)
; #define PG8_LDA(dst, b, h) do { _Pragma("unroll") for (int m = 0; m < 4; ++m) _Pragma("unroll") for (int k = 0; k < 2; ++k) dst[m][k] = *(const LAS bf16x8*)(lds + PG8_SA(b, h) + aoff + m * 2048 + k * 1024); } while (0)
; #define PG8_LDB(dst, b, h) do { _Pragma("unroll") for (int n = 0; n < 2; ++n) _Pragma("unroll") for (int k = 0; k < 2; ++k) dst[n][k] = *(const LAS bf16x8*)(lds + PG8_SB(b, h) + boff + n * 2048 + k * 1024); } while (0)
; #define PG8_MMA(ai, bj, At, Bt) do { __builtin_amdgcn_s_setprio(1); _Pragma("unroll") for (int m = 0; m < 4; ++m) _Pragma("unroll") for (int n = 0; n < 2; ++n) _Pragma("unroll") for (int k = 0; k < 2; ++k) \
;         acc[ai][bj][m][n] = __builtin_amdgcn_mfma_f32_16x16x32_bf16(Bt[n][k], At[m][k], acc[ai][bj][m][n], 0, 0, 0); __builtin_amdgcn_s_setprio(0); } while (0)
; #define PG8_WAIT_L(n) asm volatile("s_waitcnt lgkmcnt(" #n ")" ::: "memory")
; template <class Epi, class Sched>
; __device__ __forceinline__ void gemm_phase(LAS unsigned char* lds, const Gemm g, const Sched& S, const Epi& E) {
;     ...
;         const bool has_next = S.next(ui + 1, nxt);
;         const char* nA = has_next ? (const char*)g.A + (size_t)nxt.pm * tstep : cA; const char* nB = has_next ? (const char*)g.Bt + (size_t)nxt.pn * tstep : cB;
;         for (int t = 0; t < nt; t += 2) {
;             const bool last = (t == nt - 2);
;             const char* a1 = cA + (size_t)(t + 1) * kstep;
;             const char* a2 = last ? nA : cA + (size_t)(t + 2) * kstep; const char* b2 = last ? nB : cB + (size_t)(t + 2) * kstep;
;             const char* a3 = a2 + kstep; const char* b3 = b2 + kstep;
;             PG8_LDB(B0, 0, 0); PG8_SCHED; PG8_LDA(At, 0, 0); PG8_STAGE(PG8_SA(1, 1), a1 + hstep, voffA);
;             PG8_WAIT_L(8); PG8_BAR; PG8_WAIT_L(0); PG8_MMA(0, 0, At, B0); PG8_BAR; PG8_SCHED;
;             PG8_LDB(B1, 0, 1); PG8_STAGE(PG8_SB(0, 0), b2, voffB);
;             PG8_BAR; PG8_WAIT_L(0); PG8_MMA(0, 1, At, B1); PG8_BAR;
;             PG8_LDA(At, 0, 1); PG8_STAGE(PG8_SA(0, 0), a2, voffA);
;             PG8_BAR; PG8_WAIT_L(0); PG8_MMA(1, 0, At, B0); PG8_BAR; PG8_SCHED;
.LBB0_1096:
	s_add_u32 s54, s24, 0x100
	s_addc_u32 s55, s25, 0
	s_mov_b32 s56, -2
	ds_read_b128 v[128:131], v241
	ds_read_b128 v[132:135], v241 offset:1024
	ds_read_b128 v[136:139], v241 offset:2048
	ds_read_b128 v[140:143], v241 offset:3072
	s_add_u32 s24, s22, 0x100
	s_addc_u32 s25, s23, 0
	s_cmp_eq_u32 s56, 40
	s_cselect_b32 s29, s5, s25
	s_cselect_b32 s28, s4, s24
	s_cselect_b32 s27, s7, s55
	s_cselect_b32 s26, s6, s54
	v_lshl_add_u64 v[176:177], s[22:23], 0, v[196:197]
	s_add_i32 m0, s35, 0xc000
	ds_read_b128 v[144:147], v242
	ds_read_b128 v[148:151], v242 offset:1024
	ds_read_b128 v[152:155], v242 offset:2048
	ds_read_b128 v[156:159], v242 offset:3072
	ds_read_b128 v[160:163], v242 offset:4096
	ds_read_b128 v[164:167], v242 offset:5120
	ds_read_b128 v[168:171], v242 offset:6144
	ds_read_b128 v[172:175], v242 offset:7168
	global_load_lds_dwordx4 v[176:177], off
	v_lshl_add_u64 v[176:177], s[22:23], 0, v[198:199]
	s_add_i32 m0, s35, 0xe000
	s_nop 0
	global_load_lds_dwordx4 v[176:177], off
	s_waitcnt lgkmcnt(8)
	s_waitcnt vmcnt(8)
	s_setprio 1
	s_barrier
	s_waitcnt lgkmcnt(0)
	v_mfma_f32_16x16x32_bf16 v[124:127], v[128:131], v[144:147], 0
	v_mfma_f32_16x16x32_bf16 v[120:123], v[136:139], v[144:147], 0
	v_mfma_f32_16x16x32_bf16 v[108:111], v[128:131], v[152:155], 0
	v_mfma_f32_16x16x32_bf16 v[104:107], v[136:139], v[152:155], 0
	v_mfma_f32_16x16x32_bf16 v[92:95], v[128:131], v[160:163], 0
	v_mfma_f32_16x16x32_bf16 v[88:91], v[136:139], v[160:163], 0
	v_mfma_f32_16x16x32_bf16 v[76:79], v[128:131], v[168:171], 0
	v_mfma_f32_16x16x32_bf16 v[72:75], v[136:139], v[168:171], 0
	v_mfma_f32_16x16x32_bf16 v[124:127], v[132:135], v[148:151], v[124:127]
	v_mfma_f32_16x16x32_bf16 v[120:123], v[140:143], v[148:151], v[120:123]
	v_mfma_f32_16x16x32_bf16 v[108:111], v[132:135], v[156:159], v[108:111]
	v_mfma_f32_16x16x32_bf16 v[104:107], v[140:143], v[156:159], v[104:107]
	v_mfma_f32_16x16x32_bf16 v[92:95], v[132:135], v[164:167], v[92:95]
	v_mfma_f32_16x16x32_bf16 v[88:91], v[140:143], v[164:167], v[88:91]
	v_mfma_f32_16x16x32_bf16 v[76:79], v[132:135], v[172:175], v[76:79]
	v_mfma_f32_16x16x32_bf16 v[72:75], v[140:143], v[172:175], v[72:75]
	s_barrier
	s_setprio 0
	s_add_i32 s22, s48, s34
	s_mov_b32 m0, s22
	ds_read_b128 v[176:179], v243
	ds_read_b128 v[180:183], v243 offset:1024
	ds_read_b128 v[184:187], v243 offset:2048
	ds_read_b128 v[206:209], v243 offset:3072
	global_load_lds_dwordx4 v190, s[26:27]
	s_add_i32 m0, s22, 0x2000
	s_nop 0
	global_load_lds_dwordx4 v194, s[26:27]
	s_waitcnt vmcnt(8)
	s_setprio 1
	s_barrier
	s_waitcnt lgkmcnt(0)
	v_mfma_f32_16x16x32_bf16 v[116:119], v[176:179], v[144:147], 0
	v_mfma_f32_16x16x32_bf16 v[112:115], v[184:187], v[144:147], 0
	v_mfma_f32_16x16x32_bf16 v[100:103], v[176:179], v[152:155], 0
	v_mfma_f32_16x16x32_bf16 v[96:99], v[184:187], v[152:155], 0
	v_mfma_f32_16x16x32_bf16 v[84:87], v[176:179], v[160:163], 0
	v_mfma_f32_16x16x32_bf16 v[80:83], v[184:187], v[160:163], 0
	v_mfma_f32_16x16x32_bf16 v[68:71], v[176:179], v[168:171], 0
	v_mfma_f32_16x16x32_bf16 v[64:67], v[184:187], v[168:171], 0
	v_mfma_f32_16x16x32_bf16 v[116:119], v[180:183], v[148:151], v[116:119]
	v_mfma_f32_16x16x32_bf16 v[112:115], v[206:209], v[148:151], v[112:115]
	v_mfma_f32_16x16x32_bf16 v[100:103], v[180:183], v[156:159], v[100:103]
	v_mfma_f32_16x16x32_bf16 v[96:99], v[206:209], v[156:159], v[96:99]
	v_mfma_f32_16x16x32_bf16 v[84:87], v[180:183], v[164:167], v[84:87]
	v_mfma_f32_16x16x32_bf16 v[80:83], v[206:209], v[164:167], v[80:83]
	v_mfma_f32_16x16x32_bf16 v[68:71], v[180:183], v[172:175], v[68:71]
	v_mfma_f32_16x16x32_bf16 v[64:67], v[206:209], v[172:175], v[64:67]
	s_barrier
	s_setprio 0
	s_mov_b32 m0, s35
	v_lshl_add_u64 v[214:215], s[28:29], 0, v[188:189]
	ds_read_b128 v[144:147], v242 offset:16384
	ds_read_b128 v[148:151], v242 offset:17408
	ds_read_b128 v[152:155], v242 offset:18432
	ds_read_b128 v[156:159], v242 offset:19456
	ds_read_b128 v[160:163], v242 offset:20480
	ds_read_b128 v[164:167], v242 offset:21504
	ds_read_b128 v[168:171], v242 offset:22528
	ds_read_b128 v[172:175], v242 offset:23552
	global_load_lds_dwordx4 v188, s[28:29]
	v_lshl_add_u64 v[216:217], s[28:29], 0, v[192:193]
	s_mov_b32 m0, s36
	s_nop 0
	global_load_lds_dwordx4 v192, s[28:29]
	s_setprio 1
	s_barrier
	s_waitcnt lgkmcnt(0)
	v_mfma_f32_16x16x32_bf16 v[60:63], v[128:131], v[144:147], 0
	v_mfma_f32_16x16x32_bf16 v[56:59], v[136:139], v[144:147], 0
	v_mfma_f32_16x16x32_bf16 v[44:47], v[128:131], v[152:155], 0
	v_mfma_f32_16x16x32_bf16 v[40:43], v[136:139], v[152:155], 0
	v_mfma_f32_16x16x32_bf16 v[28:31], v[128:131], v[160:163], 0
	v_mfma_f32_16x16x32_bf16 v[24:27], v[136:139], v[160:163], 0
	v_mfma_f32_16x16x32_bf16 v[12:15], v[128:131], v[168:171], 0
	v_mfma_f32_16x16x32_bf16 v[8:11], v[136:139], v[168:171], 0
	v_mfma_f32_16x16x32_bf16 v[60:63], v[132:135], v[148:151], v[60:63]
	v_mfma_f32_16x16x32_bf16 v[56:59], v[140:143], v[148:151], v[56:59]
	v_mfma_f32_16x16x32_bf16 v[44:47], v[132:135], v[156:159], v[44:47]
	v_mfma_f32_16x16x32_bf16 v[40:43], v[140:143], v[156:159], v[40:43]
	v_mfma_f32_16x16x32_bf16 v[28:31], v[132:135], v[164:167], v[28:31]
	v_mfma_f32_16x16x32_bf16 v[24:27], v[140:143], v[164:167], v[24:27]
	v_mfma_f32_16x16x32_bf16 v[12:15], v[132:135], v[172:175], v[12:15]
	v_mfma_f32_16x16x32_bf16 v[8:11], v[140:143], v[172:175], v[8:11]
	s_barrier
	s_setprio 0
	s_add_u32 s22, s26, 0xb0000
	s_addc_u32 s23, s27, 0
	s_add_i32 s57, s49, s34
	s_mov_b32 m0, s57
	s_nop 0
	global_load_lds_dwordx4 v190, s[22:23]
	s_add_i32 m0, s57, 0x2000
	s_nop 0
	global_load_lds_dwordx4 v194, s[22:23]
	s_add_u32 s22, s28, 0xb0000
	s_addc_u32 s23, s29, 0
	s_mov_b32 m0, s37
	s_nop 0
	global_load_lds_dwordx4 v188, s[22:23]
	s_mov_b32 m0, s38
	s_nop 0
	global_load_lds_dwordx4 v192, s[22:23]
	s_waitcnt vmcnt(10)
	s_setprio 1
	s_barrier
; #define PG8_STAGE(bufoff, gbase, voff) do { _Pragma("unroll") for (int _i = 0; _i < 2; ++_i) \
;         __builtin_amdgcn_global_load_lds((const unsigned*)((const char*)(gbase) + (voff)[_i]), (LAS unsigned*)(lds + (bufoff) + ldsw + _i * 8192), 16, 0, 0); } while (0)
; #define PG8_LDA(dst, b, h) do { _Pragma("unroll") for (int m = 0; m < 4; ++m) _Pragma("unroll") for (int k = 0; k < 2; ++k) dst[m][k] = *(const LAS bf16x8*)(lds + PG8_SA(b, h) + aoff + m * 2048 + k * 1024); } while (0)
; #define PG8_LDB(dst, b, h) do { _Pragma("unroll") for (int n = 0; n < 2; ++n) _Pragma("unroll") for (int k = 0; k < 2; ++k) dst[n][k] = *(const LAS bf16x8*)(lds + PG8_SB(b, h) + boff + n * 2048 + k * 1024); } while (0)
; #define PG8_MMA(ai, bj, At, Bt) do { __builtin_amdgcn_s_setprio(1); _Pragma("unroll") for (int m = 0; m < 4; ++m) _Pragma("unroll") for (int n = 0; n < 2; ++n) _Pragma("unroll") for (int k = 0; k < 2; ++k) \
;         acc[ai][bj][m][n] = __builtin_amdgcn_mfma_f32_16x16x32_bf16(Bt[n][k], At[m][k], acc[ai][bj][m][n], 0, 0, 0); __builtin_amdgcn_s_setprio(0); } while (0)
; #define PG8_WAIT_V(n) asm volatile("s_waitcnt vmcnt(" #n ")" ::: "memory")
; #define PG8_WAIT_L(n) asm volatile("s_waitcnt lgkmcnt(" #n ")" ::: "memory")
; #define PG8_BAR __builtin_amdgcn_s_barrier()
; #define PG8_SCHED __builtin_amdgcn_sched_barrier(0)
; template <class Epi, class Sched>
; __device__ __forceinline__ void gemm_phase(LAS unsigned char* lds, const Gemm g, const Sched& S, const Epi& E) {
;     ...
;             PG8_STAGE(PG8_SB(0, 1), b2 + hstep, voffB);
;             PG8_WAIT_V(6); PG8_BAR; PG8_MMA(1, 1, At, B1); PG8_BAR;
;             PG8_LDB(B0, 1, 0); PG8_SCHED; PG8_LDA(At, 1, 0); PG8_STAGE(PG8_SA(0, 1), a2 + hstep, voffA);
;             PG8_WAIT_L(8); PG8_BAR; PG8_WAIT_L(0); PG8_MMA(0, 0, At, B0); PG8_BAR; PG8_SCHED;
;             PG8_LDB(B1, 1, 1); PG8_STAGE(PG8_SB(1, 0), b3, voffB);
;             PG8_BAR; PG8_WAIT_L(0); PG8_MMA(0, 1, At, B1); PG8_BAR;
;             PG8_LDA(At, 1, 1); PG8_STAGE(PG8_SA(1, 0), a3, voffA);
	v_mfma_f32_16x16x32_bf16 v[52:55], v[176:179], v[144:147], 0
	v_mfma_f32_16x16x32_bf16 v[48:51], v[184:187], v[144:147], 0
	v_mfma_f32_16x16x32_bf16 v[36:39], v[176:179], v[152:155], 0
	v_mfma_f32_16x16x32_bf16 v[32:35], v[184:187], v[152:155], 0
	v_mfma_f32_16x16x32_bf16 v[20:23], v[176:179], v[160:163], 0
	v_mfma_f32_16x16x32_bf16 v[16:19], v[184:187], v[160:163], 0
	v_mfma_f32_16x16x32_bf16 v[4:7], v[176:179], v[168:171], 0
	v_mfma_f32_16x16x32_bf16 v[0:3], v[184:187], v[168:171], 0
	v_mfma_f32_16x16x32_bf16 v[52:55], v[180:183], v[148:151], v[52:55]
	v_mfma_f32_16x16x32_bf16 v[48:51], v[206:209], v[148:151], v[48:51]
	v_mfma_f32_16x16x32_bf16 v[36:39], v[180:183], v[156:159], v[36:39]
	v_mfma_f32_16x16x32_bf16 v[32:35], v[206:209], v[156:159], v[32:35]
	v_mfma_f32_16x16x32_bf16 v[20:23], v[180:183], v[164:167], v[20:23]
	v_mfma_f32_16x16x32_bf16 v[16:19], v[206:209], v[164:167], v[16:19]
	v_mfma_f32_16x16x32_bf16 v[4:7], v[180:183], v[172:175], v[4:7]
	v_mfma_f32_16x16x32_bf16 v[0:3], v[206:209], v[172:175], v[0:3]
	s_barrier
	s_setprio 0
	s_add_i32 s57, 0, 0x18000
	ds_read_b128 v[128:131], v243 offset:16384
	ds_read_b128 v[132:135], v243 offset:17408
	ds_read_b128 v[136:139], v243 offset:18432
	ds_read_b128 v[140:143], v243 offset:19456
	ds_read_b128 v[144:147], v242 offset:32768
	ds_read_b128 v[148:151], v242 offset:33792
	ds_read_b128 v[152:155], v242 offset:34816
	ds_read_b128 v[156:159], v242 offset:35840
	ds_read_b128 v[160:163], v242 offset:36864
	ds_read_b128 v[164:167], v242 offset:37888
	ds_read_b128 v[168:171], v242 offset:38912
	ds_read_b128 v[172:175], v242 offset:39936
	s_waitcnt lgkmcnt(8)
	s_waitcnt vmcnt(8)
	s_setprio 1
	s_barrier
	s_waitcnt lgkmcnt(0)
	v_mfma_f32_16x16x32_bf16 v[124:127], v[128:131], v[144:147], v[124:127]
	v_mfma_f32_16x16x32_bf16 v[120:123], v[136:139], v[144:147], v[120:123]
	v_mfma_f32_16x16x32_bf16 v[108:111], v[128:131], v[152:155], v[108:111]
	v_mfma_f32_16x16x32_bf16 v[104:107], v[136:139], v[152:155], v[104:107]
	v_mfma_f32_16x16x32_bf16 v[92:95], v[128:131], v[160:163], v[92:95]
	v_mfma_f32_16x16x32_bf16 v[88:91], v[136:139], v[160:163], v[88:91]
	v_mfma_f32_16x16x32_bf16 v[76:79], v[128:131], v[168:171], v[76:79]
	v_mfma_f32_16x16x32_bf16 v[72:75], v[136:139], v[168:171], v[72:75]
	v_mfma_f32_16x16x32_bf16 v[124:127], v[132:135], v[148:151], v[124:127]
	v_mfma_f32_16x16x32_bf16 v[120:123], v[140:143], v[148:151], v[120:123]
	v_mfma_f32_16x16x32_bf16 v[108:111], v[132:135], v[156:159], v[108:111]
	v_mfma_f32_16x16x32_bf16 v[104:107], v[140:143], v[156:159], v[104:107]
	v_mfma_f32_16x16x32_bf16 v[92:95], v[132:135], v[164:167], v[92:95]
	v_mfma_f32_16x16x32_bf16 v[88:91], v[140:143], v[164:167], v[88:91]
	v_mfma_f32_16x16x32_bf16 v[76:79], v[132:135], v[172:175], v[76:79]
	v_mfma_f32_16x16x32_bf16 v[72:75], v[140:143], v[172:175], v[72:75]
	s_barrier
	s_setprio 0
	s_add_i32 s28, 0, 0x1c000
	s_add_i32 s22, s57, s34
	v_add_u32_e32 v206, s28, v240
	s_add_u32 s0, s26, 0x80
	s_addc_u32 s1, s27, 0
	s_mov_b32 m0, s22
	ds_read_b128 v[176:179], v206
	ds_read_b128 v[180:183], v206 offset:1024
	ds_read_b128 v[184:187], v206 offset:2048
	ds_read_b128 v[206:209], v206 offset:3072
	global_load_lds_dwordx4 v190, s[0:1]
	s_add_i32 m0, s22, 0x2000
	s_nop 0
	global_load_lds_dwordx4 v194, s[0:1]
	s_waitcnt vmcnt(8)
	s_setprio 1
	s_barrier
	s_waitcnt lgkmcnt(0)
	v_mfma_f32_16x16x32_bf16 v[116:119], v[176:179], v[144:147], v[116:119]
	v_mfma_f32_16x16x32_bf16 v[112:115], v[184:187], v[144:147], v[112:115]
	v_mfma_f32_16x16x32_bf16 v[100:103], v[176:179], v[152:155], v[100:103]
	v_mfma_f32_16x16x32_bf16 v[96:99], v[184:187], v[152:155], v[96:99]
	v_mfma_f32_16x16x32_bf16 v[84:87], v[176:179], v[160:163], v[84:87]
	v_mfma_f32_16x16x32_bf16 v[80:83], v[184:187], v[160:163], v[80:83]
	v_mfma_f32_16x16x32_bf16 v[68:71], v[176:179], v[168:171], v[68:71]
	v_mfma_f32_16x16x32_bf16 v[64:67], v[184:187], v[168:171], v[64:67]
	v_mfma_f32_16x16x32_bf16 v[116:119], v[180:183], v[148:151], v[116:119]
	v_mfma_f32_16x16x32_bf16 v[112:115], v[206:209], v[148:151], v[112:115]
	v_mfma_f32_16x16x32_bf16 v[100:103], v[180:183], v[156:159], v[100:103]
	v_mfma_f32_16x16x32_bf16 v[96:99], v[206:209], v[156:159], v[96:99]
	v_mfma_f32_16x16x32_bf16 v[84:87], v[180:183], v[164:167], v[84:87]
	v_mfma_f32_16x16x32_bf16 v[80:83], v[206:209], v[164:167], v[80:83]
	v_mfma_f32_16x16x32_bf16 v[68:71], v[180:183], v[172:175], v[68:71]
	v_mfma_f32_16x16x32_bf16 v[64:67], v[206:209], v[172:175], v[64:67]
	s_barrier
	s_setprio 0
	s_mov_b32 m0, s44
	s_mov_b64 s[0:1], 0x80
	v_lshl_add_u64 v[210:211], v[214:215], 0, s[0:1]
	ds_read_b128 v[144:147], v242 offset:49152
	ds_read_b128 v[148:151], v242 offset:50176
	ds_read_b128 v[152:155], v242 offset:51200
	ds_read_b128 v[156:159], v242 offset:52224
	ds_read_b128 v[160:163], v242 offset:53248
	ds_read_b128 v[164:167], v242 offset:54272
	ds_read_b128 v[168:171], v242 offset:55296
	ds_read_b128 v[172:175], v242 offset:56320
	global_load_lds_dwordx4 v[210:211], off
	v_lshl_add_u64 v[210:211], v[216:217], 0, s[0:1]
	s_mov_b32 m0, s45
	s_nop 0
	global_load_lds_dwordx4 v[210:211], off
	s_setprio 1
	s_barrier
; #define PG8_STAGE(bufoff, gbase, voff) do { _Pragma("unroll") for (int _i = 0; _i < 2; ++_i) \
;         __builtin_amdgcn_global_load_lds((const unsigned*)((const char*)(gbase) + (voff)[_i]), (LAS unsigned*)(lds + (bufoff) + ldsw + _i * 8192), 16, 0, 0); } while (0)
; #define PG8_LDA(dst, b, h) do { _Pragma("unroll") for (int m = 0; m < 4; ++m) _Pragma("unroll") for (int k = 0; k < 2; ++k) dst[m][k] = *(const LAS bf16x8*)(lds + PG8_SA(b, h) + aoff + m * 2048 + k * 1024); } while (0)
; #define PG8_LDB(dst, b, h) do { _Pragma("unroll") for (int n = 0; n < 2; ++n) _Pragma("unroll") for (int k = 0; k < 2; ++k) dst[n][k] = *(const LAS bf16x8*)(lds + PG8_SB(b, h) + boff + n * 2048 + k * 1024); } while (0)
; #define PG8_WAIT_V(n) asm volatile("s_waitcnt vmcnt(" #n ")" ::: "memory")
; #define PG8_WAIT_L(n) asm volatile("s_waitcnt lgkmcnt(" #n ")" ::: "memory")
; #define PG8_BAR __builtin_amdgcn_s_barrier()
; #define PG8_SCHED __builtin_amdgcn_sched_barrier(0)
; template <class Epi, class Sched>
; __device__ __forceinline__ void gemm_phase(LAS unsigned char* lds, const Gemm g, const Sched& S, const Epi& E) {
;     ...
;             PG8_LDB(B0, 0, 0); PG8_SCHED; PG8_LDA(At, 0, 0); PG8_STAGE(PG8_SA(1, 1), a1 + hstep, voffA);
;             PG8_WAIT_L(8); PG8_BAR; PG8_WAIT_L(0); PG8_MMA(0, 0, At, B0); PG8_BAR; PG8_SCHED;
;             PG8_LDB(B1, 0, 1); PG8_STAGE(PG8_SB(0, 0), b2, voffB);
;             PG8_BAR; PG8_WAIT_L(0); PG8_MMA(0, 1, At, B1); PG8_BAR;
;             PG8_LDA(At, 0, 1); PG8_STAGE(PG8_SA(0, 0), a2, voffA);
;             PG8_BAR; PG8_WAIT_L(0); PG8_MMA(1, 0, At, B0); PG8_BAR; PG8_SCHED;
;             PG8_STAGE(PG8_SB(0, 1), b2 + hstep, voffB);
;             PG8_WAIT_V(6); PG8_BAR; PG8_MMA(1, 1, At, B1); PG8_BAR;
;             PG8_LDB(B0, 1, 0); PG8_SCHED; PG8_LDA(At, 1, 0); PG8_STAGE(PG8_SA(0, 1), a2 + hstep, voffA);
;             PG8_WAIT_L(8); PG8_BAR; PG8_WAIT_L(0); PG8_MMA(0, 0, At, B0); PG8_BAR; PG8_SCHED;
;             PG8_LDB(B1, 1, 1); PG8_STAGE(PG8_SB(1, 0), b3, voffB);
;             PG8_BAR; PG8_WAIT_L(0); PG8_MMA(0, 1, At, B1); PG8_BAR;
;             PG8_LDA(At, 1, 1); PG8_STAGE(PG8_SA(1, 0), a3, voffA);
;             PG8_BAR; PG8_WAIT_L(0); PG8_MMA(1, 0, At, B0); PG8_BAR; PG8_SCHED;
;             PG8_STAGE(PG8_SB(1, 1), b3 + hstep, voffB);
;             PG8_WAIT_V(6); PG8_BAR; PG8_MMA(1, 1, At, B1); PG8_BAR;
	s_waitcnt lgkmcnt(0)
	v_mfma_f32_16x16x32_bf16 v[60:63], v[128:131], v[144:147], v[60:63]
	v_mfma_f32_16x16x32_bf16 v[56:59], v[136:139], v[144:147], v[56:59]
	v_mfma_f32_16x16x32_bf16 v[44:47], v[128:131], v[152:155], v[44:47]
	v_mfma_f32_16x16x32_bf16 v[40:43], v[136:139], v[152:155], v[40:43]
	v_mfma_f32_16x16x32_bf16 v[28:31], v[128:131], v[160:163], v[28:31]
	v_mfma_f32_16x16x32_bf16 v[24:27], v[136:139], v[160:163], v[24:27]
	v_mfma_f32_16x16x32_bf16 v[12:15], v[128:131], v[168:171], v[12:15]
	v_mfma_f32_16x16x32_bf16 v[8:11], v[136:139], v[168:171], v[8:11]
	v_mfma_f32_16x16x32_bf16 v[60:63], v[132:135], v[148:151], v[60:63]
	v_mfma_f32_16x16x32_bf16 v[56:59], v[140:143], v[148:151], v[56:59]
	v_mfma_f32_16x16x32_bf16 v[44:47], v[132:135], v[156:159], v[44:47]
	v_mfma_f32_16x16x32_bf16 v[40:43], v[140:143], v[156:159], v[40:43]
	v_mfma_f32_16x16x32_bf16 v[28:31], v[132:135], v[164:167], v[28:31]
	v_mfma_f32_16x16x32_bf16 v[24:27], v[140:143], v[164:167], v[24:27]
	v_mfma_f32_16x16x32_bf16 v[12:15], v[132:135], v[172:175], v[12:15]
	v_mfma_f32_16x16x32_bf16 v[8:11], v[140:143], v[172:175], v[8:11]
	s_barrier
	s_setprio 0
	s_add_u32 s22, s26, 0xb0080
	s_addc_u32 s23, s27, 0
	s_add_i32 s26, s28, s34
	s_mov_b32 m0, s26
	s_nop 0
	global_load_lds_dwordx4 v190, s[22:23]
	s_add_i32 m0, s26, 0x2000
	s_nop 0
	global_load_lds_dwordx4 v194, s[22:23]
	s_waitcnt vmcnt(8)
	s_setprio 1
	s_barrier
	v_mfma_f32_16x16x32_bf16 v[52:55], v[176:179], v[144:147], v[52:55]
	v_mfma_f32_16x16x32_bf16 v[48:51], v[184:187], v[144:147], v[48:51]
	v_mfma_f32_16x16x32_bf16 v[36:39], v[176:179], v[152:155], v[36:39]
	v_mfma_f32_16x16x32_bf16 v[32:35], v[184:187], v[152:155], v[32:35]
	v_mfma_f32_16x16x32_bf16 v[20:23], v[176:179], v[160:163], v[20:23]
	v_mfma_f32_16x16x32_bf16 v[16:19], v[184:187], v[160:163], v[16:19]
	v_mfma_f32_16x16x32_bf16 v[4:7], v[176:179], v[168:171], v[4:7]
	v_mfma_f32_16x16x32_bf16 v[0:3], v[184:187], v[168:171], v[0:3]
	v_mfma_f32_16x16x32_bf16 v[52:55], v[180:183], v[148:151], v[52:55]
	v_mfma_f32_16x16x32_bf16 v[48:51], v[206:209], v[148:151], v[48:51]
	v_mfma_f32_16x16x32_bf16 v[36:39], v[180:183], v[156:159], v[36:39]
	v_mfma_f32_16x16x32_bf16 v[32:35], v[206:209], v[156:159], v[32:35]
	v_mfma_f32_16x16x32_bf16 v[20:23], v[180:183], v[164:167], v[20:23]
	v_mfma_f32_16x16x32_bf16 v[16:19], v[206:209], v[164:167], v[16:19]
	v_mfma_f32_16x16x32_bf16 v[4:7], v[180:183], v[172:175], v[4:7]
	v_mfma_f32_16x16x32_bf16 v[0:3], v[206:209], v[172:175], v[0:3]
	s_barrier
	s_setprio 0
	s_add_i32 s56, s56, 2
	s_add_u32 s54, s54, 0x100
	s_addc_u32 s55, s55, 0
	s_cmp_gt_u32 s56, 41
	s_mov_b64 s[22:23], s[24:25]
.LBB0_1097:
	ds_read_b128 v[128:131], v241
	ds_read_b128 v[132:135], v241 offset:1024
	ds_read_b128 v[136:139], v241 offset:2048
	ds_read_b128 v[140:143], v241 offset:3072
	s_add_u32 s24, s22, 0x100
	s_addc_u32 s25, s23, 0
	s_cmp_eq_u32 s56, 40
	s_cselect_b32 s29, s5, s25
	s_cselect_b32 s28, s4, s24
	s_cselect_b32 s27, s7, s55
	s_cselect_b32 s26, s6, s54
	v_lshl_add_u64 v[176:177], s[22:23], 0, v[196:197]
	s_add_i32 m0, s35, 0xc000
	ds_read_b128 v[144:147], v242
	ds_read_b128 v[148:151], v242 offset:1024
	ds_read_b128 v[152:155], v242 offset:2048
	ds_read_b128 v[156:159], v242 offset:3072
	ds_read_b128 v[160:163], v242 offset:4096
	ds_read_b128 v[164:167], v242 offset:5120
	ds_read_b128 v[168:171], v242 offset:6144
	ds_read_b128 v[172:175], v242 offset:7168
	global_load_lds_dwordx4 v[176:177], off
	v_lshl_add_u64 v[176:177], s[22:23], 0, v[198:199]
	s_add_i32 m0, s35, 0xe000
	s_nop 0
	global_load_lds_dwordx4 v[176:177], off
	s_waitcnt lgkmcnt(8)
	s_waitcnt vmcnt(8)
	s_setprio 1
	s_barrier
	s_waitcnt lgkmcnt(0)
	v_mfma_f32_16x16x32_bf16 v[124:127], v[128:131], v[144:147], v[124:127]
	v_mfma_f32_16x16x32_bf16 v[120:123], v[136:139], v[144:147], v[120:123]
	v_mfma_f32_16x16x32_bf16 v[108:111], v[128:131], v[152:155], v[108:111]
	v_mfma_f32_16x16x32_bf16 v[104:107], v[136:139], v[152:155], v[104:107]
	v_mfma_f32_16x16x32_bf16 v[92:95], v[128:131], v[160:163], v[92:95]
	v_mfma_f32_16x16x32_bf16 v[88:91], v[136:139], v[160:163], v[88:91]
	v_mfma_f32_16x16x32_bf16 v[76:79], v[128:131], v[168:171], v[76:79]
	v_mfma_f32_16x16x32_bf16 v[72:75], v[136:139], v[168:171], v[72:75]
	v_mfma_f32_16x16x32_bf16 v[124:127], v[132:135], v[148:151], v[124:127]
	v_mfma_f32_16x16x32_bf16 v[120:123], v[140:143], v[148:151], v[120:123]
	v_mfma_f32_16x16x32_bf16 v[108:111], v[132:135], v[156:159], v[108:111]
	v_mfma_f32_16x16x32_bf16 v[104:107], v[140:143], v[156:159], v[104:107]
	v_mfma_f32_16x16x32_bf16 v[92:95], v[132:135], v[164:167], v[92:95]
	v_mfma_f32_16x16x32_bf16 v[88:91], v[140:143], v[164:167], v[88:91]
	v_mfma_f32_16x16x32_bf16 v[76:79], v[132:135], v[172:175], v[76:79]
	v_mfma_f32_16x16x32_bf16 v[72:75], v[140:143], v[172:175], v[72:75]
	s_barrier
	s_setprio 0
	s_add_i32 s22, s48, s34
	s_mov_b32 m0, s22
	ds_read_b128 v[176:179], v243
	ds_read_b128 v[180:183], v243 offset:1024
	ds_read_b128 v[184:187], v243 offset:2048
	ds_read_b128 v[206:209], v243 offset:3072
	global_load_lds_dwordx4 v190, s[26:27]
	s_add_i32 m0, s22, 0x2000
	s_nop 0
	global_load_lds_dwordx4 v194, s[26:27]
	s_waitcnt vmcnt(8)
	s_setprio 1
	s_barrier
; #define PG8_STAGE(bufoff, gbase, voff) do { _Pragma("unroll") for (int _i = 0; _i < 2; ++_i) \
;         __builtin_amdgcn_global_load_lds((const unsigned*)((const char*)(gbase) + (voff)[_i]), (LAS unsigned*)(lds + (bufoff) + ldsw + _i * 8192), 16, 0, 0); } while (0)
; #define PG8_LDA(dst, b, h) do { _Pragma("unroll") for (int m = 0; m < 4; ++m) _Pragma("unroll") for (int k = 0; k < 2; ++k) dst[m][k] = *(const LAS bf16x8*)(lds + PG8_SA(b, h) + aoff + m * 2048 + k * 1024); } while (0)
; #define PG8_LDB(dst, b, h) do { _Pragma("unroll") for (int n = 0; n < 2; ++n) _Pragma("unroll") for (int k = 0; k < 2; ++k) dst[n][k] = *(const LAS bf16x8*)(lds + PG8_SB(b, h) + boff + n * 2048 + k * 1024); } while (0)
; #define PG8_MMA(ai, bj, At, Bt) do { __builtin_amdgcn_s_setprio(1); _Pragma("unroll") for (int m = 0; m < 4; ++m) _Pragma("unroll") for (int n = 0; n < 2; ++n) _Pragma("unroll") for (int k = 0; k < 2; ++k) \
;         acc[ai][bj][m][n] = __builtin_amdgcn_mfma_f32_16x16x32_bf16(Bt[n][k], At[m][k], acc[ai][bj][m][n], 0, 0, 0); __builtin_amdgcn_s_setprio(0); } while (0)
; #define PG8_WAIT_V(n) asm volatile("s_waitcnt vmcnt(" #n ")" ::: "memory")
; #define PG8_WAIT_L(n) asm volatile("s_waitcnt lgkmcnt(" #n ")" ::: "memory")
; #define PG8_BAR __builtin_amdgcn_s_barrier()
; #define PG8_SCHED __builtin_amdgcn_sched_barrier(0)
; template <class Epi, class Sched>
; __device__ __forceinline__ void gemm_phase(LAS unsigned char* lds, const Gemm g, const Sched& S, const Epi& E) {
;     ...
;             PG8_BAR; PG8_WAIT_L(0); PG8_MMA(0, 1, At, B1); PG8_BAR;
;             PG8_LDA(At, 0, 1); PG8_STAGE(PG8_SA(0, 0), a2, voffA);
;             PG8_BAR; PG8_WAIT_L(0); PG8_MMA(1, 0, At, B0); PG8_BAR; PG8_SCHED;
;             PG8_STAGE(PG8_SB(0, 1), b2 + hstep, voffB);
;             PG8_WAIT_V(6); PG8_BAR; PG8_MMA(1, 1, At, B1); PG8_BAR;
;             PG8_LDB(B0, 1, 0); PG8_SCHED; PG8_LDA(At, 1, 0); PG8_STAGE(PG8_SA(0, 1), a2 + hstep, voffA);
;             PG8_WAIT_L(8); PG8_BAR; PG8_WAIT_L(0); PG8_MMA(0, 0, At, B0); PG8_BAR; PG8_SCHED;
	s_waitcnt lgkmcnt(0)
	v_mfma_f32_16x16x32_bf16 v[116:119], v[176:179], v[144:147], v[116:119]
	v_mfma_f32_16x16x32_bf16 v[112:115], v[184:187], v[144:147], v[112:115]
	v_mfma_f32_16x16x32_bf16 v[100:103], v[176:179], v[152:155], v[100:103]
	v_mfma_f32_16x16x32_bf16 v[96:99], v[184:187], v[152:155], v[96:99]
	v_mfma_f32_16x16x32_bf16 v[84:87], v[176:179], v[160:163], v[84:87]
	v_mfma_f32_16x16x32_bf16 v[80:83], v[184:187], v[160:163], v[80:83]
	v_mfma_f32_16x16x32_bf16 v[68:71], v[176:179], v[168:171], v[68:71]
	v_mfma_f32_16x16x32_bf16 v[64:67], v[184:187], v[168:171], v[64:67]
	v_mfma_f32_16x16x32_bf16 v[116:119], v[180:183], v[148:151], v[116:119]
	v_mfma_f32_16x16x32_bf16 v[112:115], v[206:209], v[148:151], v[112:115]
	v_mfma_f32_16x16x32_bf16 v[100:103], v[180:183], v[156:159], v[100:103]
	v_mfma_f32_16x16x32_bf16 v[96:99], v[206:209], v[156:159], v[96:99]
	v_mfma_f32_16x16x32_bf16 v[84:87], v[180:183], v[164:167], v[84:87]
	v_mfma_f32_16x16x32_bf16 v[80:83], v[206:209], v[164:167], v[80:83]
	v_mfma_f32_16x16x32_bf16 v[68:71], v[180:183], v[172:175], v[68:71]
	v_mfma_f32_16x16x32_bf16 v[64:67], v[206:209], v[172:175], v[64:67]
	s_barrier
	s_setprio 0
	s_mov_b32 m0, s35
	v_lshl_add_u64 v[214:215], s[28:29], 0, v[188:189]
	ds_read_b128 v[144:147], v242 offset:16384
	ds_read_b128 v[148:151], v242 offset:17408
	ds_read_b128 v[152:155], v242 offset:18432
	ds_read_b128 v[156:159], v242 offset:19456
	ds_read_b128 v[160:163], v242 offset:20480
	ds_read_b128 v[164:167], v242 offset:21504
	ds_read_b128 v[168:171], v242 offset:22528
	ds_read_b128 v[172:175], v242 offset:23552
	global_load_lds_dwordx4 v188, s[28:29]
	v_lshl_add_u64 v[216:217], s[28:29], 0, v[192:193]
	s_mov_b32 m0, s36
	s_nop 0
	global_load_lds_dwordx4 v192, s[28:29]
	s_setprio 1
	s_barrier
	s_waitcnt lgkmcnt(0)
	v_mfma_f32_16x16x32_bf16 v[60:63], v[128:131], v[144:147], v[60:63]
	v_mfma_f32_16x16x32_bf16 v[56:59], v[136:139], v[144:147], v[56:59]
	v_mfma_f32_16x16x32_bf16 v[44:47], v[128:131], v[152:155], v[44:47]
	v_mfma_f32_16x16x32_bf16 v[40:43], v[136:139], v[152:155], v[40:43]
	v_mfma_f32_16x16x32_bf16 v[28:31], v[128:131], v[160:163], v[28:31]
	v_mfma_f32_16x16x32_bf16 v[24:27], v[136:139], v[160:163], v[24:27]
	v_mfma_f32_16x16x32_bf16 v[12:15], v[128:131], v[168:171], v[12:15]
	v_mfma_f32_16x16x32_bf16 v[8:11], v[136:139], v[168:171], v[8:11]
	v_mfma_f32_16x16x32_bf16 v[60:63], v[132:135], v[148:151], v[60:63]
	v_mfma_f32_16x16x32_bf16 v[56:59], v[140:143], v[148:151], v[56:59]
	v_mfma_f32_16x16x32_bf16 v[44:47], v[132:135], v[156:159], v[44:47]
	v_mfma_f32_16x16x32_bf16 v[40:43], v[140:143], v[156:159], v[40:43]
	v_mfma_f32_16x16x32_bf16 v[28:31], v[132:135], v[164:167], v[28:31]
	v_mfma_f32_16x16x32_bf16 v[24:27], v[140:143], v[164:167], v[24:27]
	v_mfma_f32_16x16x32_bf16 v[12:15], v[132:135], v[172:175], v[12:15]
	v_mfma_f32_16x16x32_bf16 v[8:11], v[140:143], v[172:175], v[8:11]
	s_barrier
	s_setprio 0
	s_add_u32 s22, s26, 0xb0000
	s_addc_u32 s23, s27, 0
	s_add_i32 s57, s49, s34
	s_mov_b32 m0, s57
	s_nop 0
	global_load_lds_dwordx4 v190, s[22:23]
	s_add_i32 m0, s57, 0x2000
	s_nop 0
	global_load_lds_dwordx4 v194, s[22:23]
	s_add_u32 s22, s28, 0xb0000
	s_addc_u32 s23, s29, 0
	s_mov_b32 m0, s37
	s_nop 0
	global_load_lds_dwordx4 v188, s[22:23]
	s_mov_b32 m0, s38
	s_nop 0
	global_load_lds_dwordx4 v192, s[22:23]
	s_waitcnt vmcnt(10)
	s_setprio 1
	s_barrier
	v_mfma_f32_16x16x32_bf16 v[52:55], v[176:179], v[144:147], v[52:55]
	v_mfma_f32_16x16x32_bf16 v[48:51], v[184:187], v[144:147], v[48:51]
	v_mfma_f32_16x16x32_bf16 v[36:39], v[176:179], v[152:155], v[36:39]
	v_mfma_f32_16x16x32_bf16 v[32:35], v[184:187], v[152:155], v[32:35]
	v_mfma_f32_16x16x32_bf16 v[20:23], v[176:179], v[160:163], v[20:23]
	v_mfma_f32_16x16x32_bf16 v[16:19], v[184:187], v[160:163], v[16:19]
	v_mfma_f32_16x16x32_bf16 v[4:7], v[176:179], v[168:171], v[4:7]
	v_mfma_f32_16x16x32_bf16 v[0:3], v[184:187], v[168:171], v[0:3]
	v_mfma_f32_16x16x32_bf16 v[52:55], v[180:183], v[148:151], v[52:55]
	v_mfma_f32_16x16x32_bf16 v[48:51], v[206:209], v[148:151], v[48:51]
	v_mfma_f32_16x16x32_bf16 v[36:39], v[180:183], v[156:159], v[36:39]
	v_mfma_f32_16x16x32_bf16 v[32:35], v[206:209], v[156:159], v[32:35]
	v_mfma_f32_16x16x32_bf16 v[20:23], v[180:183], v[164:167], v[20:23]
	v_mfma_f32_16x16x32_bf16 v[16:19], v[206:209], v[164:167], v[16:19]
	v_mfma_f32_16x16x32_bf16 v[4:7], v[180:183], v[172:175], v[4:7]
	v_mfma_f32_16x16x32_bf16 v[0:3], v[206:209], v[172:175], v[0:3]
	s_barrier
	s_setprio 0
	s_add_i32 s57, 0, 0x18000
	ds_read_b128 v[128:131], v243 offset:16384
	ds_read_b128 v[132:135], v243 offset:17408
	ds_read_b128 v[136:139], v243 offset:18432
	ds_read_b128 v[140:143], v243 offset:19456
	ds_read_b128 v[144:147], v242 offset:32768
	ds_read_b128 v[148:151], v242 offset:33792
	ds_read_b128 v[152:155], v242 offset:34816
	ds_read_b128 v[156:159], v242 offset:35840
	ds_read_b128 v[160:163], v242 offset:36864
	ds_read_b128 v[164:167], v242 offset:37888
	ds_read_b128 v[168:171], v242 offset:38912
	ds_read_b128 v[172:175], v242 offset:39936
	s_waitcnt lgkmcnt(8)
	s_waitcnt vmcnt(8)
	s_setprio 1
	s_barrier
; #define PG8_STAGE(bufoff, gbase, voff) do { _Pragma("unroll") for (int _i = 0; _i < 2; ++_i) \
;         __builtin_amdgcn_global_load_lds((const unsigned*)((const char*)(gbase) + (voff)[_i]), (LAS unsigned*)(lds + (bufoff) + ldsw + _i * 8192), 16, 0, 0); } while (0)
; #define PG8_LDA(dst, b, h) do { _Pragma("unroll") for (int m = 0; m < 4; ++m) _Pragma("unroll") for (int k = 0; k < 2; ++k) dst[m][k] = *(const LAS bf16x8*)(lds + PG8_SA(b, h) + aoff + m * 2048 + k * 1024); } while (0)
; #define PG8_LDB(dst, b, h) do { _Pragma("unroll") for (int n = 0; n < 2; ++n) _Pragma("unroll") for (int k = 0; k < 2; ++k) dst[n][k] = *(const LAS bf16x8*)(lds + PG8_SB(b, h) + boff + n * 2048 + k * 1024); } while (0)
; #define PG8_MMA(ai, bj, At, Bt) do { __builtin_amdgcn_s_setprio(1); _Pragma("unroll") for (int m = 0; m < 4; ++m) _Pragma("unroll") for (int n = 0; n < 2; ++n) _Pragma("unroll") for (int k = 0; k < 2; ++k) \
;         acc[ai][bj][m][n] = __builtin_amdgcn_mfma_f32_16x16x32_bf16(Bt[n][k], At[m][k], acc[ai][bj][m][n], 0, 0, 0); __builtin_amdgcn_s_setprio(0); } while (0)
; #define PG8_WAIT_V(n) asm volatile("s_waitcnt vmcnt(" #n ")" ::: "memory")
; #define PG8_WAIT_L(n) asm volatile("s_waitcnt lgkmcnt(" #n ")" ::: "memory")
; #define PG8_BAR __builtin_amdgcn_s_barrier()
; #define PG8_SCHED __builtin_amdgcn_sched_barrier(0)
; template <class Epi, class Sched>
; __device__ __forceinline__ void gemm_phase(LAS unsigned char* lds, const Gemm g, const Sched& S, const Epi& E) {
;     ...
;             PG8_WAIT_L(8); PG8_BAR; PG8_WAIT_L(0); PG8_MMA(0, 0, At, B0); PG8_BAR; PG8_SCHED;
;             PG8_LDB(B1, 1, 1); PG8_STAGE(PG8_SB(1, 0), b3, voffB);
;             PG8_BAR; PG8_WAIT_L(0); PG8_MMA(0, 1, At, B1); PG8_BAR;
;             PG8_LDA(At, 1, 1); PG8_STAGE(PG8_SA(1, 0), a3, voffA);
;             PG8_BAR; PG8_WAIT_L(0); PG8_MMA(1, 0, At, B0); PG8_BAR; PG8_SCHED;
;             PG8_STAGE(PG8_SB(1, 1), b3 + hstep, voffB);
;             PG8_WAIT_V(6); PG8_BAR; PG8_MMA(1, 1, At, B1); PG8_BAR;
	s_waitcnt lgkmcnt(0)
	v_mfma_f32_16x16x32_bf16 v[124:127], v[128:131], v[144:147], v[124:127]
	v_mfma_f32_16x16x32_bf16 v[120:123], v[136:139], v[144:147], v[120:123]
	v_mfma_f32_16x16x32_bf16 v[108:111], v[128:131], v[152:155], v[108:111]
	v_mfma_f32_16x16x32_bf16 v[104:107], v[136:139], v[152:155], v[104:107]
	v_mfma_f32_16x16x32_bf16 v[92:95], v[128:131], v[160:163], v[92:95]
	v_mfma_f32_16x16x32_bf16 v[88:91], v[136:139], v[160:163], v[88:91]
	v_mfma_f32_16x16x32_bf16 v[76:79], v[128:131], v[168:171], v[76:79]
	v_mfma_f32_16x16x32_bf16 v[72:75], v[136:139], v[168:171], v[72:75]
	v_mfma_f32_16x16x32_bf16 v[124:127], v[132:135], v[148:151], v[124:127]
	v_mfma_f32_16x16x32_bf16 v[120:123], v[140:143], v[148:151], v[120:123]
	v_mfma_f32_16x16x32_bf16 v[108:111], v[132:135], v[156:159], v[108:111]
	v_mfma_f32_16x16x32_bf16 v[104:107], v[140:143], v[156:159], v[104:107]
	v_mfma_f32_16x16x32_bf16 v[92:95], v[132:135], v[164:167], v[92:95]
	v_mfma_f32_16x16x32_bf16 v[88:91], v[140:143], v[164:167], v[88:91]
	v_mfma_f32_16x16x32_bf16 v[76:79], v[132:135], v[172:175], v[76:79]
	v_mfma_f32_16x16x32_bf16 v[72:75], v[140:143], v[172:175], v[72:75]
	s_barrier
	s_setprio 0
	s_add_i32 s28, 0, 0x1c000
	s_add_i32 s22, s57, s34
	v_add_u32_e32 v206, s28, v240
	s_add_u32 s0, s26, 0x80
	s_addc_u32 s1, s27, 0
	s_mov_b32 m0, s22
	ds_read_b128 v[176:179], v206
	ds_read_b128 v[180:183], v206 offset:1024
	ds_read_b128 v[184:187], v206 offset:2048
	ds_read_b128 v[206:209], v206 offset:3072
	global_load_lds_dwordx4 v190, s[0:1]
	s_add_i32 m0, s22, 0x2000
	s_nop 0
	global_load_lds_dwordx4 v194, s[0:1]
	s_waitcnt vmcnt(8)
	s_setprio 1
	s_barrier
	s_waitcnt lgkmcnt(0)
	v_mfma_f32_16x16x32_bf16 v[116:119], v[176:179], v[144:147], v[116:119]
	v_mfma_f32_16x16x32_bf16 v[112:115], v[184:187], v[144:147], v[112:115]
	v_mfma_f32_16x16x32_bf16 v[100:103], v[176:179], v[152:155], v[100:103]
	v_mfma_f32_16x16x32_bf16 v[96:99], v[184:187], v[152:155], v[96:99]
	v_mfma_f32_16x16x32_bf16 v[84:87], v[176:179], v[160:163], v[84:87]
	v_mfma_f32_16x16x32_bf16 v[80:83], v[184:187], v[160:163], v[80:83]
	v_mfma_f32_16x16x32_bf16 v[68:71], v[176:179], v[168:171], v[68:71]
	v_mfma_f32_16x16x32_bf16 v[64:67], v[184:187], v[168:171], v[64:67]
	v_mfma_f32_16x16x32_bf16 v[116:119], v[180:183], v[148:151], v[116:119]
	v_mfma_f32_16x16x32_bf16 v[112:115], v[206:209], v[148:151], v[112:115]
	v_mfma_f32_16x16x32_bf16 v[100:103], v[180:183], v[156:159], v[100:103]
	v_mfma_f32_16x16x32_bf16 v[96:99], v[206:209], v[156:159], v[96:99]
	v_mfma_f32_16x16x32_bf16 v[84:87], v[180:183], v[164:167], v[84:87]
	v_mfma_f32_16x16x32_bf16 v[80:83], v[206:209], v[164:167], v[80:83]
	v_mfma_f32_16x16x32_bf16 v[68:71], v[180:183], v[172:175], v[68:71]
	v_mfma_f32_16x16x32_bf16 v[64:67], v[206:209], v[172:175], v[64:67]
	s_barrier
	s_setprio 0
	s_mov_b32 m0, s44
	s_mov_b64 s[0:1], 0x80
	v_lshl_add_u64 v[210:211], v[214:215], 0, s[0:1]
	ds_read_b128 v[144:147], v242 offset:49152
	ds_read_b128 v[148:151], v242 offset:50176
	ds_read_b128 v[152:155], v242 offset:51200
	ds_read_b128 v[156:159], v242 offset:52224
	ds_read_b128 v[160:163], v242 offset:53248
	ds_read_b128 v[164:167], v242 offset:54272
	ds_read_b128 v[168:171], v242 offset:55296
	ds_read_b128 v[172:175], v242 offset:56320
	global_load_lds_dwordx4 v[210:211], off
	v_lshl_add_u64 v[210:211], v[216:217], 0, s[0:1]
	s_mov_b32 m0, s45
	s_nop 0
	global_load_lds_dwordx4 v[210:211], off
	s_setprio 1
	s_barrier
	s_waitcnt lgkmcnt(0)
	v_mfma_f32_16x16x32_bf16 v[60:63], v[128:131], v[144:147], v[60:63]
	v_mfma_f32_16x16x32_bf16 v[56:59], v[136:139], v[144:147], v[56:59]
	v_mfma_f32_16x16x32_bf16 v[44:47], v[128:131], v[152:155], v[44:47]
	v_mfma_f32_16x16x32_bf16 v[40:43], v[136:139], v[152:155], v[40:43]
	v_mfma_f32_16x16x32_bf16 v[28:31], v[128:131], v[160:163], v[28:31]
	v_mfma_f32_16x16x32_bf16 v[24:27], v[136:139], v[160:163], v[24:27]
	v_mfma_f32_16x16x32_bf16 v[12:15], v[128:131], v[168:171], v[12:15]
	v_mfma_f32_16x16x32_bf16 v[8:11], v[136:139], v[168:171], v[8:11]
	v_mfma_f32_16x16x32_bf16 v[60:63], v[132:135], v[148:151], v[60:63]
	v_mfma_f32_16x16x32_bf16 v[56:59], v[140:143], v[148:151], v[56:59]
	v_mfma_f32_16x16x32_bf16 v[44:47], v[132:135], v[156:159], v[44:47]
	v_mfma_f32_16x16x32_bf16 v[40:43], v[140:143], v[156:159], v[40:43]
	v_mfma_f32_16x16x32_bf16 v[28:31], v[132:135], v[164:167], v[28:31]
	v_mfma_f32_16x16x32_bf16 v[24:27], v[140:143], v[164:167], v[24:27]
	v_mfma_f32_16x16x32_bf16 v[12:15], v[132:135], v[172:175], v[12:15]
	v_mfma_f32_16x16x32_bf16 v[8:11], v[140:143], v[172:175], v[8:11]
	s_barrier
	s_setprio 0
	s_add_u32 s22, s26, 0xb0080
	s_addc_u32 s23, s27, 0
	s_add_i32 s26, s28, s34
	s_mov_b32 m0, s26
	s_nop 0
	global_load_lds_dwordx4 v190, s[22:23]
	s_add_i32 m0, s26, 0x2000
	s_nop 0
	global_load_lds_dwordx4 v194, s[22:23]
	s_waitcnt vmcnt(8)
	s_setprio 1
	s_barrier
	v_mfma_f32_16x16x32_bf16 v[52:55], v[176:179], v[144:147], v[52:55]
	v_mfma_f32_16x16x32_bf16 v[48:51], v[184:187], v[144:147], v[48:51]
	v_mfma_f32_16x16x32_bf16 v[36:39], v[176:179], v[152:155], v[36:39]
	v_mfma_f32_16x16x32_bf16 v[32:35], v[184:187], v[152:155], v[32:35]
	v_mfma_f32_16x16x32_bf16 v[20:23], v[176:179], v[160:163], v[20:23]
	v_mfma_f32_16x16x32_bf16 v[16:19], v[184:187], v[160:163], v[16:19]
	v_mfma_f32_16x16x32_bf16 v[4:7], v[176:179], v[168:171], v[4:7]
	v_mfma_f32_16x16x32_bf16 v[0:3], v[184:187], v[168:171], v[0:3]
	v_mfma_f32_16x16x32_bf16 v[52:55], v[180:183], v[148:151], v[52:55]
	v_mfma_f32_16x16x32_bf16 v[48:51], v[206:209], v[148:151], v[48:51]
	v_mfma_f32_16x16x32_bf16 v[36:39], v[180:183], v[156:159], v[36:39]
	v_mfma_f32_16x16x32_bf16 v[32:35], v[206:209], v[156:159], v[32:35]
	v_mfma_f32_16x16x32_bf16 v[20:23], v[180:183], v[164:167], v[20:23]
	v_mfma_f32_16x16x32_bf16 v[16:19], v[206:209], v[164:167], v[16:19]
	v_mfma_f32_16x16x32_bf16 v[4:7], v[180:183], v[172:175], v[4:7]
	v_mfma_f32_16x16x32_bf16 v[0:3], v[206:209], v[172:175], v[0:3]
	s_barrier
; __device__ __forceinline__ unsigned cvt_pk_bf16(float lo, float hi) { unsigned r; asm volatile("v_cvt_pk_bf16_f32 %0, %1, %2" : "=v"(r) : "v"(lo), "v"(hi)); return r; }
; __device__ __forceinline__ float bf_lo(unsigned u) { return __uint_as_float(u << 16); }
; __device__ __forceinline__ float bf_hi(unsigned u) { return __uint_as_float(u & 0xffff0000u); }
; template <class Epi, class Sched>
; __device__ __forceinline__ void gemm_phase(LAS unsigned char* lds, const Gemm g, const Sched& S, const Epi& E) {
;     ...
;             PG8_WAIT_V(6); PG8_BAR; PG8_MMA(1, 1, At, B1); PG8_BAR;
;         }
;         E(acc, cur, wr, wc, fr, fq);
;         if (!has_next) break;
;     __device__ __forceinline__ void operator()(const AccT& acc, const Unit& u, int wr, int wc, int fr, int fq) const {
;         asm volatile("" : "+v"(fr), "+v"(fq));
;         const int rowt = u.pm * 256; const int b = rowt >> 11;
;         const bf16_t* res = res_b + (size_t)rowt * DM; bf16_t* out = hb + (size_t)rowt * DM;
;         const int col0 = u.pn * 256 + wc * 32 + 8 * fq;
;         f32x4 gv[2][2];
; #pragma unroll
;         for (int bj = 0; bj < 2; ++bj)
; #pragma unroll
;             for (int n = 0; n < 2; ++n) gv[bj][n] = *(const f32x4*)(gate + (size_t)b * NMOD + col0 + bj * 128 + n * 4) * gs;
;         u32x4 r[2][4][2];
; #pragma unroll
;         for (int ai = 0; ai < 2; ++ai)
; #pragma unroll
;             for (int m = 0; m < 4; ++m)
; #pragma unroll
;                 for (int bj = 0; bj < 2; ++bj) r[ai][m][bj] = *(const u32x4*)(res + (size_t)(wr * 64 + fr + ai * 128 + m * 16) * DM + col0 + bj * 128);
; #pragma unroll
;         for (int ai = 0; ai < 2; ++ai)
; #pragma unroll
;             for (int m = 0; m < 4; ++m)
; #pragma unroll
;                 for (int bj = 0; bj < 2; ++bj) {
;                     const u32x4 q = r[ai][m][bj];
;                     const f32x4 r0 = {bf_lo(q.x), bf_hi(q.x), bf_lo(q.y), bf_hi(q.y)}, r1 = {bf_lo(q.z), bf_hi(q.z), bf_lo(q.w), bf_hi(q.w)};
;                     const f32x4 h0 = r0 + gv[bj][0] * acc[ai][bj][m][0], h1 = r1 + gv[bj][1] * acc[ai][bj][m][1];
;                     u32x4 w; w.x = cvt_pk_bf16(h0[0], h0[1]); w.y = cvt_pk_bf16(h0[2], h0[3]); w.z = cvt_pk_bf16(h1[0], h1[1]); w.w = cvt_pk_bf16(h1[2], h1[3]);
;                     *(u32x4*)(out + (size_t)(wr * 64 + fr + ai * 128 + m * 16) * DM + col0 + bj * 128) = w;
	s_setprio 0
	s_add_i32 s56, s56, 2
	s_add_u32 s54, s54, 0x100
	s_addc_u32 s55, s55, 0
	s_cmp_gt_u32 s56, 41
	s_mov_b64 s[22:23], s[24:25]
	s_cbranch_scc0 .LBB0_1097
	s_lshl_b32 s25, s52, 8
	v_mov_b32_e32 v140, v239
	v_mov_b32_e32 v128, v238
	s_lshl_b32 s22, s53, 8
	s_ashr_i32 s24, s53, 3
	s_or_b32 s25, s25, s43
	s_ashr_i32 s23, s22, 31
	v_lshl_add_u32 v136, v128, 3, s25
	s_mul_hi_i32 s25, s24, 0x9000
	s_mul_i32 s24, s24, 0x9000
	s_add_u32 s24, s40, s24
	s_addc_u32 s25, s41, s25
	v_ashrrev_i32_e32 v137, 31, v136
	v_lshl_add_u64 v[138:139], v[136:137], 2, s[24:25]
	global_load_dwordx4 v[128:131], v[138:139], off offset:16
	global_load_dwordx4 v[132:135], v[138:139], off
	s_lshl_b64 s[22:23], s[22:23], 11
	s_add_u32 s24, s80, s22
	s_addc_u32 s25, s81, s23
	v_lshlrev_b64 v[226:227], 1, v[136:137]
	s_add_u32 s22, s96, s22
	s_addc_u32 s23, s97, s23
	s_and_b64 vcc, exec, s[2:3]
	s_mov_b32 s52, s50
	s_mov_b32 s53, s51
	s_waitcnt vmcnt(0)
	v_pk_mul_f32 v[216:217], v[130:131], 0.5 op_sel_hi:[1,0]
	v_pk_mul_f32 v[220:221], v[134:135], 0.5 op_sel_hi:[1,0]
	v_pk_mul_f32 v[218:219], v[132:133], 0.5 op_sel_hi:[1,0]
	v_pk_mul_f32 v[214:215], v[128:129], 0.5 op_sel_hi:[1,0]
	global_load_dwordx4 v[128:131], v[138:139], off offset:528
	global_load_dwordx4 v[132:135], v[138:139], off offset:512
	s_waitcnt vmcnt(0)
	v_pk_mul_f32 v[206:207], v[128:129], 0.5 op_sel_hi:[1,0]
	v_add_u32_e32 v128, s42, v140
	v_ashrrev_i32_e32 v129, 31, v128
	v_pk_mul_f32 v[208:209], v[130:131], 0.5 op_sel_hi:[1,0]
	v_lshl_add_u64 v[130:131], s[24:25], 0, v[226:227]
	v_lshlrev_b64 v[248:249], 11, v[128:129]
	v_lshl_add_u64 v[128:129], v[130:131], 0, v[248:249]
	global_load_dwordx4 v[244:247], v[128:129], off
	global_load_dwordx4 v[184:187], v[128:129], off offset:256
	v_lshl_add_u64 v[236:237], v[248:249], 0, s[8:9]
	v_lshl_add_u64 v[128:129], v[130:131], 0, v[236:237]
	global_load_dwordx4 v[180:183], v[128:129], off
	global_load_dwordx4 v[176:179], v[128:129], off offset:256
	v_lshl_add_u64 v[234:235], v[248:249], 0, s[10:11]
	v_lshl_add_u64 v[128:129], v[130:131], 0, v[234:235]
	global_load_dwordx4 v[172:175], v[128:129], off
	global_load_dwordx4 v[168:171], v[128:129], off offset:256
	v_lshl_add_u64 v[232:233], v[248:249], 0, s[12:13]
	v_lshl_add_u64 v[128:129], v[130:131], 0, v[232:233]
	global_load_dwordx4 v[164:167], v[128:129], off
	global_load_dwordx4 v[160:163], v[128:129], off offset:256
	v_lshl_add_u64 v[230:231], v[248:249], 0, s[14:15]
	v_lshl_add_u64 v[128:129], v[130:131], 0, v[230:231]
	global_load_dwordx4 v[156:159], v[128:129], off
	global_load_dwordx4 v[152:155], v[128:129], off offset:256
	v_lshl_add_u64 v[228:229], v[248:249], 0, s[16:17]
	v_lshl_add_u64 v[128:129], v[130:131], 0, v[228:229]
	global_load_dwordx4 v[148:151], v[128:129], off
	global_load_dwordx4 v[144:147], v[128:129], off offset:256
	v_lshl_add_u64 v[224:225], v[248:249], 0, s[18:19]
	v_lshl_add_u64 v[128:129], v[130:131], 0, v[224:225]
	global_load_dwordx4 v[140:143], v[128:129], off
	global_load_dwordx4 v[136:139], v[128:129], off offset:256
	v_lshl_add_u64 v[222:223], v[248:249], 0, s[20:21]
	v_lshl_add_u64 v[128:129], v[130:131], 0, v[222:223]
	v_pk_mul_f32 v[212:213], v[134:135], 0.5 op_sel_hi:[1,0]
	v_pk_mul_f32 v[210:211], v[132:133], 0.5 op_sel_hi:[1,0]
	global_load_dwordx4 v[132:135], v[128:129], off
	s_nop 0
	global_load_dwordx4 v[128:131], v[128:129], off offset:256
	v_lshl_add_u64 v[226:227], s[22:23], 0, v[226:227]
	v_lshl_add_u64 v[248:249], v[226:227], 0, v[248:249]
	s_mov_b64 s[24:25], s[6:7]
	s_mov_b64 s[22:23], s[4:5]
	s_waitcnt vmcnt(0)
	v_lshlrev_b32_e32 v250, 16, v244
	v_and_b32_e32 v251, 0xffff0000, v244
	v_lshlrev_b32_e32 v244, 16, v245
	v_and_b32_e32 v245, 0xffff0000, v245
	v_lshlrev_b32_e32 v252, 16, v246
	v_and_b32_e32 v253, 0xffff0000, v246
	v_lshlrev_b32_e32 v246, 16, v247
	v_and_b32_e32 v247, 0xffff0000, v247
	v_pk_fma_f32 v[126:127], v[126:127], v[220:221], v[244:245]
	v_pk_fma_f32 v[124:125], v[124:125], v[218:219], v[250:251]
	v_pk_fma_f32 v[244:245], v[122:123], v[216:217], v[246:247]
	v_pk_fma_f32 v[122:123], v[120:121], v[214:215], v[252:253]
	v_cvt_pk_bf16_f32 v120, v124, v125
	v_cvt_pk_bf16_f32 v121, v126, v127
	v_lshlrev_b32_e32 v124, 16, v186
	v_cvt_pk_bf16_f32 v122, v122, v123
	v_cvt_pk_bf16_f32 v123, v244, v245
	global_store_dwordx4 v[248:249], v[120:123], off
	v_and_b32_e32 v125, 0xffff0000, v186
	v_lshlrev_b32_e32 v126, 16, v187
	v_lshlrev_b32_e32 v120, 16, v184
	v_and_b32_e32 v121, 0xffff0000, v184
	v_and_b32_e32 v127, 0xffff0000, v187
	v_lshlrev_b32_e32 v122, 16, v185
	v_and_b32_e32 v123, 0xffff0000, v185
	v_pk_fma_f32 v[116:117], v[116:117], v[210:211], v[120:121]
	v_pk_fma_f32 v[120:121], v[114:115], v[208:209], v[126:127]
	v_pk_fma_f32 v[114:115], v[112:113], v[206:207], v[124:125]
	v_pk_fma_f32 v[118:119], v[118:119], v[212:213], v[122:123]
	v_cvt_pk_bf16_f32 v112, v116, v117
	v_lshlrev_b32_e32 v116, 16, v181
	v_cvt_pk_bf16_f32 v113, v118, v119
	v_cvt_pk_bf16_f32 v114, v114, v115
	v_cvt_pk_bf16_f32 v115, v120, v121
	global_store_dwordx4 v[248:249], v[112:115], off offset:256
	v_and_b32_e32 v117, 0xffff0000, v181
	v_lshlrev_b32_e32 v118, 16, v182
	v_lshlrev_b32_e32 v114, 16, v180
	v_and_b32_e32 v115, 0xffff0000, v180
	v_and_b32_e32 v119, 0xffff0000, v182
	v_lshlrev_b32_e32 v120, 16, v183
	v_and_b32_e32 v121, 0xffff0000, v183
	v_lshl_add_u64 v[112:113], v[226:227], 0, v[236:237]
	v_pk_fma_f32 v[110:111], v[110:111], v[220:221], v[116:117]
	v_pk_fma_f32 v[108:109], v[108:109], v[218:219], v[114:115]
	v_pk_fma_f32 v[114:115], v[106:107], v[216:217], v[120:121]
	v_pk_fma_f32 v[106:107], v[104:105], v[214:215], v[118:119]
	v_cvt_pk_bf16_f32 v104, v108, v109
; __device__ __forceinline__ unsigned cvt_pk_bf16(float lo, float hi) { unsigned r; asm volatile("v_cvt_pk_bf16_f32 %0, %1, %2" : "=v"(r) : "v"(lo), "v"(hi)); return r; }
; __device__ __forceinline__ float bf_lo(unsigned u) { return __uint_as_float(u << 16); }
; __device__ __forceinline__ float bf_hi(unsigned u) { return __uint_as_float(u & 0xffff0000u); }
;     __device__ __forceinline__ void operator()(const AccT& acc, const Unit& u, int wr, int wc, int fr, int fq) const {
;     ...
;                 for (int bj = 0; bj < 2; ++bj) {
;                     const u32x4 q = r[ai][m][bj];
;                     const f32x4 r0 = {bf_lo(q.x), bf_hi(q.x), bf_lo(q.y), bf_hi(q.y)}, r1 = {bf_lo(q.z), bf_hi(q.z), bf_lo(q.w), bf_hi(q.w)};
;                     const f32x4 h0 = r0 + gv[bj][0] * acc[ai][bj][m][0], h1 = r1 + gv[bj][1] * acc[ai][bj][m][1];
;                     u32x4 w; w.x = cvt_pk_bf16(h0[0], h0[1]); w.y = cvt_pk_bf16(h0[2], h0[3]); w.z = cvt_pk_bf16(h1[0], h1[1]); w.w = cvt_pk_bf16(h1[2], h1[3]);
;                     *(u32x4*)(out + (size_t)(wr * 64 + fr + ai * 128 + m * 16) * DM + col0 + bj * 128) = w;
	v_cvt_pk_bf16_f32 v105, v110, v111
	v_lshlrev_b32_e32 v108, 16, v178
	v_cvt_pk_bf16_f32 v106, v106, v107
	v_cvt_pk_bf16_f32 v107, v114, v115
	global_store_dwordx4 v[112:113], v[104:107], off
	v_and_b32_e32 v109, 0xffff0000, v178
	v_lshlrev_b32_e32 v110, 16, v179
	v_lshlrev_b32_e32 v104, 16, v176
	v_and_b32_e32 v105, 0xffff0000, v176
	v_and_b32_e32 v111, 0xffff0000, v179
	v_lshlrev_b32_e32 v106, 16, v177
	v_and_b32_e32 v107, 0xffff0000, v177
	v_pk_fma_f32 v[100:101], v[100:101], v[210:211], v[104:105]
	v_pk_fma_f32 v[104:105], v[98:99], v[208:209], v[110:111]
	v_pk_fma_f32 v[98:99], v[96:97], v[206:207], v[108:109]
	v_pk_fma_f32 v[102:103], v[102:103], v[212:213], v[106:107]
	v_cvt_pk_bf16_f32 v96, v100, v101
	v_lshlrev_b32_e32 v100, 16, v173
	v_cvt_pk_bf16_f32 v97, v102, v103
	v_cvt_pk_bf16_f32 v98, v98, v99
	v_cvt_pk_bf16_f32 v99, v104, v105
	global_store_dwordx4 v[112:113], v[96:99], off offset:256
	v_and_b32_e32 v101, 0xffff0000, v173
	v_lshlrev_b32_e32 v102, 16, v174
	v_lshlrev_b32_e32 v98, 16, v172
	v_and_b32_e32 v99, 0xffff0000, v172
	v_and_b32_e32 v103, 0xffff0000, v174
	v_lshlrev_b32_e32 v104, 16, v175
	v_and_b32_e32 v105, 0xffff0000, v175
	v_lshl_add_u64 v[96:97], v[226:227], 0, v[234:235]
	v_pk_fma_f32 v[94:95], v[94:95], v[220:221], v[100:101]
	v_pk_fma_f32 v[92:93], v[92:93], v[218:219], v[98:99]
	v_pk_fma_f32 v[98:99], v[90:91], v[216:217], v[104:105]
	v_pk_fma_f32 v[90:91], v[88:89], v[214:215], v[102:103]
	v_cvt_pk_bf16_f32 v88, v92, v93
	v_cvt_pk_bf16_f32 v89, v94, v95
	v_lshlrev_b32_e32 v92, 16, v170
	v_cvt_pk_bf16_f32 v90, v90, v91
	v_cvt_pk_bf16_f32 v91, v98, v99
	global_store_dwordx4 v[96:97], v[88:91], off
	v_and_b32_e32 v93, 0xffff0000, v170
	v_lshlrev_b32_e32 v94, 16, v171
	v_lshlrev_b32_e32 v88, 16, v168
	v_and_b32_e32 v89, 0xffff0000, v168
	v_and_b32_e32 v95, 0xffff0000, v171
	v_lshlrev_b32_e32 v90, 16, v169
	v_and_b32_e32 v91, 0xffff0000, v169
	v_pk_fma_f32 v[84:85], v[84:85], v[210:211], v[88:89]
	v_pk_fma_f32 v[88:89], v[82:83], v[208:209], v[94:95]
	v_pk_fma_f32 v[82:83], v[80:81], v[206:207], v[92:93]
	v_pk_fma_f32 v[86:87], v[86:87], v[212:213], v[90:91]
	v_cvt_pk_bf16_f32 v80, v84, v85
	v_lshlrev_b32_e32 v84, 16, v165
	v_cvt_pk_bf16_f32 v81, v86, v87
	v_cvt_pk_bf16_f32 v82, v82, v83
	v_cvt_pk_bf16_f32 v83, v88, v89
	global_store_dwordx4 v[96:97], v[80:83], off offset:256
	v_and_b32_e32 v85, 0xffff0000, v165
	v_lshlrev_b32_e32 v86, 16, v166
	v_lshlrev_b32_e32 v82, 16, v164
	v_and_b32_e32 v83, 0xffff0000, v164
	v_and_b32_e32 v87, 0xffff0000, v166
	v_lshlrev_b32_e32 v88, 16, v167
	v_and_b32_e32 v89, 0xffff0000, v167
	v_lshl_add_u64 v[80:81], v[226:227], 0, v[232:233]
	v_pk_fma_f32 v[78:79], v[78:79], v[220:221], v[84:85]
	v_pk_fma_f32 v[76:77], v[76:77], v[218:219], v[82:83]
	v_pk_fma_f32 v[82:83], v[74:75], v[216:217], v[88:89]
	v_pk_fma_f32 v[74:75], v[72:73], v[214:215], v[86:87]
	v_cvt_pk_bf16_f32 v72, v76, v77
	v_cvt_pk_bf16_f32 v73, v78, v79
	v_lshlrev_b32_e32 v76, 16, v162
	v_cvt_pk_bf16_f32 v74, v74, v75
	v_cvt_pk_bf16_f32 v75, v82, v83
	global_store_dwordx4 v[80:81], v[72:75], off
	v_and_b32_e32 v77, 0xffff0000, v162
	v_lshlrev_b32_e32 v78, 16, v163
	v_lshlrev_b32_e32 v72, 16, v160
	v_and_b32_e32 v73, 0xffff0000, v160
	v_and_b32_e32 v79, 0xffff0000, v163
	v_lshlrev_b32_e32 v74, 16, v161
	v_and_b32_e32 v75, 0xffff0000, v161
	v_pk_fma_f32 v[68:69], v[68:69], v[210:211], v[72:73]
	v_pk_fma_f32 v[72:73], v[66:67], v[208:209], v[78:79]
	v_pk_fma_f32 v[66:67], v[64:65], v[206:207], v[76:77]
	v_pk_fma_f32 v[70:71], v[70:71], v[212:213], v[74:75]
	v_cvt_pk_bf16_f32 v64, v68, v69
	v_lshlrev_b32_e32 v68, 16, v157
	v_cvt_pk_bf16_f32 v65, v70, v71
	v_cvt_pk_bf16_f32 v66, v66, v67
	v_cvt_pk_bf16_f32 v67, v72, v73
	global_store_dwordx4 v[80:81], v[64:67], off offset:256
	v_and_b32_e32 v69, 0xffff0000, v157
	v_lshlrev_b32_e32 v70, 16, v158
	v_lshlrev_b32_e32 v66, 16, v156
	v_and_b32_e32 v67, 0xffff0000, v156
	v_and_b32_e32 v71, 0xffff0000, v158
	v_lshlrev_b32_e32 v72, 16, v159
	v_and_b32_e32 v73, 0xffff0000, v159
	v_lshl_add_u64 v[64:65], v[226:227], 0, v[230:231]
	v_pk_fma_f32 v[62:63], v[62:63], v[220:221], v[68:69]
	v_pk_fma_f32 v[60:61], v[60:61], v[218:219], v[66:67]
	v_pk_fma_f32 v[66:67], v[58:59], v[216:217], v[72:73]
	v_pk_fma_f32 v[58:59], v[56:57], v[214:215], v[70:71]
	v_cvt_pk_bf16_f32 v56, v60, v61
	v_cvt_pk_bf16_f32 v57, v62, v63
	v_lshlrev_b32_e32 v60, 16, v154
	v_cvt_pk_bf16_f32 v58, v58, v59
	v_cvt_pk_bf16_f32 v59, v66, v67
	global_store_dwordx4 v[64:65], v[56:59], off
	v_and_b32_e32 v61, 0xffff0000, v154
	v_lshlrev_b32_e32 v62, 16, v155
	v_lshlrev_b32_e32 v56, 16, v152
	v_and_b32_e32 v57, 0xffff0000, v152
	v_and_b32_e32 v63, 0xffff0000, v155
	v_lshlrev_b32_e32 v58, 16, v153
	v_and_b32_e32 v59, 0xffff0000, v153
; __device__ __forceinline__ unsigned cvt_pk_bf16(float lo, float hi) { unsigned r; asm volatile("v_cvt_pk_bf16_f32 %0, %1, %2" : "=v"(r) : "v"(lo), "v"(hi)); return r; }
; __device__ __forceinline__ float bf_lo(unsigned u) { return __uint_as_float(u << 16); }
; __device__ __forceinline__ float bf_hi(unsigned u) { return __uint_as_float(u & 0xffff0000u); }
; #define PG8_WAIT_V(n) asm volatile("s_waitcnt vmcnt(" #n ")" ::: "memory")
; #define PG8_BAR __builtin_amdgcn_s_barrier()
; template <class Epi, class Sched>
; __device__ __forceinline__ void gemm_phase(LAS unsigned char* lds, const Gemm g, const Sched& S, const Epi& E) {
;     ...
;         if (!has_next) break;
; #pragma unroll
;         for (int a = 0; a < 2; ++a)
; #pragma unroll
;             for (int b = 0; b < 2; ++b)
; #pragma unroll
;                 for (int m = 0; m < 4; ++m)
; #pragma unroll
;                     for (int n = 0; n < 2; ++n) acc[a][b][m][n] = (f32x4){0.f, 0.f, 0.f, 0.f};
;         cur = nxt; cA = nA; cB = nB; ++ui;
;     }
;     PG8_WAIT_V(0);
;     if (wr == 0) PG8_BAR;
;     PG8_BAR;
;     __device__ __forceinline__ void operator()(const AccT& acc, const Unit& u, int wr, int wc, int fr, int fq) const {
;     ...
;                 for (int bj = 0; bj < 2; ++bj) {
;                     const u32x4 q = r[ai][m][bj];
;                     const f32x4 r0 = {bf_lo(q.x), bf_hi(q.x), bf_lo(q.y), bf_hi(q.y)}, r1 = {bf_lo(q.z), bf_hi(q.z), bf_lo(q.w), bf_hi(q.w)};
;                     const f32x4 h0 = r0 + gv[bj][0] * acc[ai][bj][m][0], h1 = r1 + gv[bj][1] * acc[ai][bj][m][1];
;                     u32x4 w; w.x = cvt_pk_bf16(h0[0], h0[1]); w.y = cvt_pk_bf16(h0[2], h0[3]); w.z = cvt_pk_bf16(h1[0], h1[1]); w.w = cvt_pk_bf16(h1[2], h1[3]);
;                     *(u32x4*)(out + (size_t)(wr * 64 + fr + ai * 128 + m * 16) * DM + col0 + bj * 128) = w;
;                 }
	v_pk_fma_f32 v[52:53], v[52:53], v[210:211], v[56:57]
	v_pk_fma_f32 v[56:57], v[50:51], v[208:209], v[62:63]
	v_pk_fma_f32 v[50:51], v[48:49], v[206:207], v[60:61]
	v_pk_fma_f32 v[54:55], v[54:55], v[212:213], v[58:59]
	v_cvt_pk_bf16_f32 v48, v52, v53
	v_lshlrev_b32_e32 v52, 16, v149
	v_cvt_pk_bf16_f32 v49, v54, v55
	v_cvt_pk_bf16_f32 v50, v50, v51
	v_cvt_pk_bf16_f32 v51, v56, v57
	global_store_dwordx4 v[64:65], v[48:51], off offset:256
	v_and_b32_e32 v53, 0xffff0000, v149
	v_lshlrev_b32_e32 v54, 16, v150
	v_lshlrev_b32_e32 v50, 16, v148
	v_and_b32_e32 v51, 0xffff0000, v148
	v_and_b32_e32 v55, 0xffff0000, v150
	v_lshlrev_b32_e32 v56, 16, v151
	v_and_b32_e32 v57, 0xffff0000, v151
	v_lshl_add_u64 v[48:49], v[226:227], 0, v[228:229]
	v_pk_fma_f32 v[46:47], v[46:47], v[220:221], v[52:53]
	v_pk_fma_f32 v[44:45], v[44:45], v[218:219], v[50:51]
	v_pk_fma_f32 v[50:51], v[42:43], v[216:217], v[56:57]
	v_pk_fma_f32 v[42:43], v[40:41], v[214:215], v[54:55]
	v_cvt_pk_bf16_f32 v40, v44, v45
	v_cvt_pk_bf16_f32 v41, v46, v47
	v_lshlrev_b32_e32 v44, 16, v146
	v_cvt_pk_bf16_f32 v42, v42, v43
	v_cvt_pk_bf16_f32 v43, v50, v51
	global_store_dwordx4 v[48:49], v[40:43], off
	v_and_b32_e32 v45, 0xffff0000, v146
	v_lshlrev_b32_e32 v46, 16, v147
	v_lshlrev_b32_e32 v40, 16, v144
	v_and_b32_e32 v41, 0xffff0000, v144
	v_and_b32_e32 v47, 0xffff0000, v147
	v_lshlrev_b32_e32 v42, 16, v145
	v_and_b32_e32 v43, 0xffff0000, v145
	v_pk_fma_f32 v[36:37], v[36:37], v[210:211], v[40:41]
	v_pk_fma_f32 v[40:41], v[34:35], v[208:209], v[46:47]
	v_pk_fma_f32 v[34:35], v[32:33], v[206:207], v[44:45]
	v_pk_fma_f32 v[38:39], v[38:39], v[212:213], v[42:43]
	v_cvt_pk_bf16_f32 v32, v36, v37
	v_lshlrev_b32_e32 v36, 16, v141
	v_cvt_pk_bf16_f32 v33, v38, v39
	v_cvt_pk_bf16_f32 v34, v34, v35
	v_cvt_pk_bf16_f32 v35, v40, v41
	global_store_dwordx4 v[48:49], v[32:35], off offset:256
	v_and_b32_e32 v37, 0xffff0000, v141
	v_lshlrev_b32_e32 v38, 16, v142
	v_lshlrev_b32_e32 v34, 16, v140
	v_and_b32_e32 v35, 0xffff0000, v140
	v_and_b32_e32 v39, 0xffff0000, v142
	v_lshlrev_b32_e32 v40, 16, v143
	v_and_b32_e32 v41, 0xffff0000, v143
	v_lshl_add_u64 v[32:33], v[226:227], 0, v[224:225]
	v_pk_fma_f32 v[30:31], v[30:31], v[220:221], v[36:37]
	v_pk_fma_f32 v[28:29], v[28:29], v[218:219], v[34:35]
	v_pk_fma_f32 v[34:35], v[26:27], v[216:217], v[40:41]
	v_pk_fma_f32 v[26:27], v[24:25], v[214:215], v[38:39]
	v_cvt_pk_bf16_f32 v24, v28, v29
	v_cvt_pk_bf16_f32 v25, v30, v31
	v_lshlrev_b32_e32 v28, 16, v138
	v_cvt_pk_bf16_f32 v26, v26, v27
	v_cvt_pk_bf16_f32 v27, v34, v35
	global_store_dwordx4 v[32:33], v[24:27], off
	v_and_b32_e32 v29, 0xffff0000, v138
	v_lshlrev_b32_e32 v30, 16, v139
	v_lshlrev_b32_e32 v24, 16, v136
	v_and_b32_e32 v25, 0xffff0000, v136
	v_and_b32_e32 v31, 0xffff0000, v139
	v_lshlrev_b32_e32 v26, 16, v137
	v_and_b32_e32 v27, 0xffff0000, v137
	v_pk_fma_f32 v[20:21], v[20:21], v[210:211], v[24:25]
	v_pk_fma_f32 v[24:25], v[18:19], v[208:209], v[30:31]
	v_pk_fma_f32 v[18:19], v[16:17], v[206:207], v[28:29]
	v_pk_fma_f32 v[22:23], v[22:23], v[212:213], v[26:27]
	v_cvt_pk_bf16_f32 v16, v20, v21
	v_lshlrev_b32_e32 v20, 16, v133
	v_cvt_pk_bf16_f32 v17, v22, v23
	v_cvt_pk_bf16_f32 v18, v18, v19
	v_cvt_pk_bf16_f32 v19, v24, v25
	global_store_dwordx4 v[32:33], v[16:19], off offset:256
	v_and_b32_e32 v21, 0xffff0000, v133
	v_lshlrev_b32_e32 v22, 16, v134
	v_lshlrev_b32_e32 v18, 16, v132
	v_and_b32_e32 v19, 0xffff0000, v132
	v_and_b32_e32 v23, 0xffff0000, v134
	v_lshlrev_b32_e32 v24, 16, v135
	v_and_b32_e32 v25, 0xffff0000, v135
	v_lshl_add_u64 v[16:17], v[226:227], 0, v[222:223]
	v_pk_fma_f32 v[14:15], v[14:15], v[220:221], v[20:21]
	v_pk_fma_f32 v[12:13], v[12:13], v[218:219], v[18:19]
	v_pk_fma_f32 v[18:19], v[10:11], v[216:217], v[24:25]
	v_pk_fma_f32 v[10:11], v[8:9], v[214:215], v[22:23]
	v_cvt_pk_bf16_f32 v8, v12, v13
	v_cvt_pk_bf16_f32 v9, v14, v15
	v_lshlrev_b32_e32 v12, 16, v130
	v_cvt_pk_bf16_f32 v10, v10, v11
	v_cvt_pk_bf16_f32 v11, v18, v19
	global_store_dwordx4 v[16:17], v[8:11], off
	v_and_b32_e32 v13, 0xffff0000, v130
	v_lshlrev_b32_e32 v14, 16, v131
	v_lshlrev_b32_e32 v8, 16, v128
	v_and_b32_e32 v9, 0xffff0000, v128
	v_and_b32_e32 v15, 0xffff0000, v131
	v_lshlrev_b32_e32 v10, 16, v129
	v_and_b32_e32 v11, 0xffff0000, v129
	v_pk_fma_f32 v[4:5], v[4:5], v[210:211], v[8:9]
	v_pk_fma_f32 v[8:9], v[2:3], v[208:209], v[14:15]
	v_pk_fma_f32 v[2:3], v[0:1], v[206:207], v[12:13]
	v_pk_fma_f32 v[6:7], v[6:7], v[212:213], v[10:11]
	v_cvt_pk_bf16_f32 v0, v4, v5
	s_nop 0
	v_cvt_pk_bf16_f32 v1, v6, v7
	v_cvt_pk_bf16_f32 v2, v2, v3
	v_cvt_pk_bf16_f32 v3, v8, v9
	global_store_dwordx4 v[16:17], v[0:3], off offset:256
	s_cbranch_vccz .LBB0_1086
	s_waitcnt vmcnt(0)
	s_cmpk_gt_u32 s30, 0xff
	s_cbranch_scc1 .LBB0_1101
	s_barrier
